# gate/merge GEMM epilogues: the eight sigmoids per row group recomputed with packed f32 math (same op sequence, inactive div_scale steps dropped)
# speedup vs baseline: 1.0200x; 1.0077x over previous
; #define PG8_STAGE(bufoff, gbase, voff) do { _Pragma("unroll") for (int _i = 0; _i < 2; ++_i) \
;         __builtin_amdgcn_global_load_lds((const unsigned*)((const char*)(gbase) + (voff)[_i]), (LAS unsigned*)(lds + (bufoff) + ldsw + _i * 8192), 16, 0, 0); } while (0)
; #define PG8_LDA(dst, b, h) do { _Pragma("unroll") for (int m = 0; m < 4; ++m) _Pragma("unroll") for (int k = 0; k < 2; ++k) dst[m][k] = *(const LAS bf16x8*)(lds + PG8_SA(b, h) + aoff + m * 2048 + k * 1024); } while (0)
; #define PG8_LDB(dst, b, h) do { _Pragma("unroll") for (int n = 0; n < 2; ++n) _Pragma("unroll") for (int k = 0; k < 2; ++k) dst[n][k] = *(const LAS bf16x8*)(lds + PG8_SB(b, h) + boff + n * 2048 + k * 1024); } while (0)
; #define PG8_MMA(ai, bj, At, Bt) do { __builtin_amdgcn_s_setprio(1); _Pragma("unroll") for (int m = 0; m < 4; ++m) _Pragma("unroll") for (int n = 0; n < 2; ++n) _Pragma("unroll") for (int k = 0; k < 2; ++k) \
;         acc[ai][bj][m][n] = __builtin_amdgcn_mfma_f32_16x16x32_bf16(Bt[n][k], At[m][k], acc[ai][bj][m][n], 0, 0, 0); __builtin_amdgcn_s_setprio(0); } while (0)
; #define PG8_WAIT_L(n) asm volatile("s_waitcnt lgkmcnt(" #n ")" ::: "memory")
; #define PG8_BAR __builtin_amdgcn_s_barrier()
; #define PG8_SCHED __builtin_amdgcn_sched_barrier(0)
;     ...
;             PG8_LDB(B0, 0, 0); PG8_SCHED; PG8_LDA(At, 0, 0); PG8_STAGE(PG8_SA(1, 1), a1 + hA, voffA);
;             PG8_WAIT_L(8); PG8_BAR; PG8_WAIT_L(0); PG8_MMA(0, 0, At, B0); PG8_BAR; PG8_SCHED;
;             PG8_LDB(B1, 0, 1); PG8_STAGE(PG8_SB(0, 0), b2, voffB);
;             PG8_BAR; PG8_WAIT_L(0); PG8_MMA(0, 1, At, B1); PG8_BAR;
;             PG8_LDA(At, 0, 1); PG8_STAGE(PG8_SA(0, 0), a2, voffA);
;             PG8_BAR; PG8_WAIT_L(0); PG8_MMA(1, 0, At, B0); PG8_BAR; PG8_SCHED;
.LBB0_627:
	ds_read_b128 v[146:149], v157
	ds_read_b128 v[150:153], v157 offset:1024
	ds_read_b128 v[160:163], v157 offset:2048
	ds_read_b128 v[170:173], v157 offset:3072
	s_add_u32 s12, s14, 0x100
	s_addc_u32 s13, s15, 0
	s_cmp_eq_u32 s42, 4
	s_cselect_b32 s19, s31, s13
	s_cselect_b32 s18, s30, s12
	s_cselect_b32 s17, s8, s33
	s_cselect_b32 s16, s9, s29
	v_lshl_add_u64 v[164:165], s[14:15], 0, v[138:139]
	s_add_i32 m0, s39, 0xc000
	ds_read_b128 v[174:177], v158
	ds_read_b128 v[178:181], v158 offset:1024
	ds_read_b128 v[182:185], v158 offset:2048
	ds_read_b128 v[186:189], v158 offset:3072
	ds_read_b128 v[190:193], v158 offset:4096
	ds_read_b128 v[194:197], v158 offset:5120
	ds_read_b128 v[198:201], v158 offset:6144
	ds_read_b128 v[202:205], v158 offset:7168
	global_load_lds_dwordx4 v[164:165], off
	v_lshl_add_u64 v[164:165], s[14:15], 0, v[136:137]
	s_add_i32 m0, s39, 0xe000
	s_nop 0
	global_load_lds_dwordx4 v[164:165], off
	s_waitcnt lgkmcnt(8)
	s_barrier
	s_waitcnt lgkmcnt(0)
	s_setprio 1
	s_waitcnt lgkmcnt(0)
	v_mfma_f32_16x16x32_bf16 v[124:127], v[146:149], v[174:177], v[124:127]
	v_mfma_f32_16x16x32_bf16 v[120:123], v[160:163], v[174:177], v[120:123]
	v_mfma_f32_16x16x32_bf16 v[108:111], v[146:149], v[182:185], v[108:111]
	v_mfma_f32_16x16x32_bf16 v[104:107], v[160:163], v[182:185], v[104:107]
	v_mfma_f32_16x16x32_bf16 v[92:95], v[146:149], v[190:193], v[92:95]
	v_mfma_f32_16x16x32_bf16 v[88:91], v[160:163], v[190:193], v[88:91]
	v_mfma_f32_16x16x32_bf16 v[76:79], v[146:149], v[198:201], v[76:79]
	v_mfma_f32_16x16x32_bf16 v[72:75], v[160:163], v[198:201], v[72:75]
	v_mfma_f32_16x16x32_bf16 v[124:127], v[150:153], v[178:181], v[124:127]
	v_mfma_f32_16x16x32_bf16 v[120:123], v[170:173], v[178:181], v[120:123]
	v_mfma_f32_16x16x32_bf16 v[108:111], v[150:153], v[186:189], v[108:111]
	v_mfma_f32_16x16x32_bf16 v[104:107], v[170:173], v[186:189], v[104:107]
	v_mfma_f32_16x16x32_bf16 v[92:95], v[150:153], v[194:197], v[92:95]
	v_mfma_f32_16x16x32_bf16 v[88:91], v[170:173], v[194:197], v[88:91]
	v_mfma_f32_16x16x32_bf16 v[76:79], v[150:153], v[202:205], v[76:79]
	v_mfma_f32_16x16x32_bf16 v[72:75], v[170:173], v[202:205], v[72:75]
	s_setprio 0
	s_barrier
	s_add_i32 s14, s59, s37
	v_lshl_add_u64 v[164:165], s[16:17], 0, v[132:133]
	s_mov_b32 m0, s14
	ds_read_b128 v[206:209], v159
	ds_read_b128 v[210:213], v159 offset:1024
	ds_read_b128 v[214:217], v159 offset:2048
	ds_read_b128 v[218:221], v159 offset:3072
	global_load_lds_dwordx4 v[164:165], off
	v_lshl_add_u64 v[222:223], s[16:17], 0, v[128:129]
	s_add_i32 m0, s14, 0x2000
	s_nop 0
	global_load_lds_dwordx4 v[222:223], off
	s_barrier
	s_waitcnt lgkmcnt(0)
	s_setprio 1
	s_waitcnt lgkmcnt(0)
	v_mfma_f32_16x16x32_bf16 v[116:119], v[206:209], v[174:177], v[116:119]
	v_mfma_f32_16x16x32_bf16 v[112:115], v[214:217], v[174:177], v[112:115]
	v_mfma_f32_16x16x32_bf16 v[100:103], v[206:209], v[182:185], v[100:103]
	v_mfma_f32_16x16x32_bf16 v[96:99], v[214:217], v[182:185], v[96:99]
	v_mfma_f32_16x16x32_bf16 v[84:87], v[206:209], v[190:193], v[84:87]
	v_mfma_f32_16x16x32_bf16 v[80:83], v[214:217], v[190:193], v[80:83]
	v_mfma_f32_16x16x32_bf16 v[68:71], v[206:209], v[198:201], v[68:71]
	v_mfma_f32_16x16x32_bf16 v[64:67], v[214:217], v[198:201], v[64:67]
	v_mfma_f32_16x16x32_bf16 v[116:119], v[210:213], v[178:181], v[116:119]
	v_mfma_f32_16x16x32_bf16 v[112:115], v[218:221], v[178:181], v[112:115]
	v_mfma_f32_16x16x32_bf16 v[100:103], v[210:213], v[186:189], v[100:103]
	v_mfma_f32_16x16x32_bf16 v[96:99], v[218:221], v[186:189], v[96:99]
	v_mfma_f32_16x16x32_bf16 v[84:87], v[210:213], v[194:197], v[84:87]
	v_mfma_f32_16x16x32_bf16 v[80:83], v[218:221], v[194:197], v[80:83]
	v_mfma_f32_16x16x32_bf16 v[68:71], v[210:213], v[202:205], v[68:71]
	v_mfma_f32_16x16x32_bf16 v[64:67], v[218:221], v[202:205], v[64:67]
	s_setprio 0
	s_mov_b32 m0, s39
	v_lshl_add_u64 v[224:225], s[18:19], 0, v[134:135]
	s_barrier
	ds_read_b128 v[174:177], v158 offset:16384
	ds_read_b128 v[178:181], v158 offset:17408
	ds_read_b128 v[182:185], v158 offset:18432
	ds_read_b128 v[186:189], v158 offset:19456
	ds_read_b128 v[190:193], v158 offset:20480
	ds_read_b128 v[194:197], v158 offset:21504
	ds_read_b128 v[198:201], v158 offset:22528
	ds_read_b128 v[202:205], v158 offset:23552
	global_load_lds_dwordx4 v[224:225], off
	v_lshl_add_u64 v[226:227], s[18:19], 0, v[130:131]
	s_mov_b32 m0, s51
	s_nop 0
	global_load_lds_dwordx4 v[226:227], off
	s_barrier
	s_waitcnt lgkmcnt(0)
	s_setprio 1
	s_waitcnt lgkmcnt(0)
	v_mfma_f32_16x16x32_bf16 v[60:63], v[146:149], v[174:177], v[60:63]
	v_mfma_f32_16x16x32_bf16 v[56:59], v[160:163], v[174:177], v[56:59]
	v_mfma_f32_16x16x32_bf16 v[44:47], v[146:149], v[182:185], v[44:47]
	v_mfma_f32_16x16x32_bf16 v[40:43], v[160:163], v[182:185], v[40:43]
	v_mfma_f32_16x16x32_bf16 v[28:31], v[146:149], v[190:193], v[28:31]
	v_mfma_f32_16x16x32_bf16 v[24:27], v[160:163], v[190:193], v[24:27]
	v_mfma_f32_16x16x32_bf16 v[12:15], v[146:149], v[198:201], v[12:15]
	v_mfma_f32_16x16x32_bf16 v[8:11], v[160:163], v[198:201], v[8:11]
	v_mfma_f32_16x16x32_bf16 v[60:63], v[150:153], v[178:181], v[60:63]
	v_mfma_f32_16x16x32_bf16 v[56:59], v[170:173], v[178:181], v[56:59]
	v_mfma_f32_16x16x32_bf16 v[44:47], v[150:153], v[186:189], v[44:47]
	v_mfma_f32_16x16x32_bf16 v[40:43], v[170:173], v[186:189], v[40:43]
	v_mfma_f32_16x16x32_bf16 v[28:31], v[150:153], v[194:197], v[28:31]
	v_mfma_f32_16x16x32_bf16 v[24:27], v[170:173], v[194:197], v[24:27]
	v_mfma_f32_16x16x32_bf16 v[12:15], v[150:153], v[202:205], v[12:15]
	v_mfma_f32_16x16x32_bf16 v[8:11], v[170:173], v[202:205], v[8:11]
	s_setprio 0
	s_barrier
; #define PG8_STAGE(bufoff, gbase, voff) do { _Pragma("unroll") for (int _i = 0; _i < 2; ++_i) \
;         __builtin_amdgcn_global_load_lds((const unsigned*)((const char*)(gbase) + (voff)[_i]), (LAS unsigned*)(lds + (bufoff) + ldsw + _i * 8192), 16, 0, 0); } while (0)
; #define PG8_LDA(dst, b, h) do { _Pragma("unroll") for (int m = 0; m < 4; ++m) _Pragma("unroll") for (int k = 0; k < 2; ++k) dst[m][k] = *(const LAS bf16x8*)(lds + PG8_SA(b, h) + aoff + m * 2048 + k * 1024); } while (0)
; #define PG8_LDB(dst, b, h) do { _Pragma("unroll") for (int n = 0; n < 2; ++n) _Pragma("unroll") for (int k = 0; k < 2; ++k) dst[n][k] = *(const LAS bf16x8*)(lds + PG8_SB(b, h) + boff + n * 2048 + k * 1024); } while (0)
; #define PG8_MMA(ai, bj, At, Bt) do { __builtin_amdgcn_s_setprio(1); _Pragma("unroll") for (int m = 0; m < 4; ++m) _Pragma("unroll") for (int n = 0; n < 2; ++n) _Pragma("unroll") for (int k = 0; k < 2; ++k) \
;         acc[ai][bj][m][n] = __builtin_amdgcn_mfma_f32_16x16x32_bf16(Bt[n][k], At[m][k], acc[ai][bj][m][n], 0, 0, 0); __builtin_amdgcn_s_setprio(0); } while (0)
; #define PG8_WAIT_V(n) asm volatile("s_waitcnt vmcnt(" #n ")" ::: "memory")
; #define PG8_WAIT_L(n) asm volatile("s_waitcnt lgkmcnt(" #n ")" ::: "memory")
; #define PG8_BAR __builtin_amdgcn_s_barrier()
; #define PG8_SCHED __builtin_amdgcn_sched_barrier(0)
;     ...
;             PG8_STAGE(PG8_SB(0, 1), b2 + hB, voffB);
;             PG8_WAIT_V(6); PG8_BAR; PG8_MMA(1, 1, At, B1); PG8_BAR;
;             PG8_LDB(B0, 1, 0); PG8_SCHED; PG8_LDA(At, 1, 0); PG8_STAGE(PG8_SA(0, 1), a2 + hA, voffA);
;             PG8_WAIT_L(8); PG8_BAR; PG8_WAIT_L(0); PG8_MMA(0, 0, At, B0); PG8_BAR; PG8_SCHED;
;             PG8_LDB(B1, 1, 1); PG8_STAGE(PG8_SB(1, 0), b3, voffB);
;             PG8_BAR; PG8_WAIT_L(0); PG8_MMA(0, 1, At, B1); PG8_BAR;
;             PG8_LDA(At, 1, 1); PG8_STAGE(PG8_SA(1, 0), a3, voffA);
;             PG8_BAR; PG8_WAIT_L(0); PG8_MMA(1, 0, At, B0); PG8_BAR; PG8_SCHED;
	s_add_u32 s14, s16, 0x20000
	s_addc_u32 s15, s17, 0
	s_add_i32 s43, s60, s37
	v_lshl_add_u64 v[146:147], s[14:15], 0, v[132:133]
	s_mov_b32 m0, s43
	s_nop 0
	global_load_lds_dwordx4 v[146:147], off
	v_lshl_add_u64 v[146:147], s[14:15], 0, v[128:129]
	s_add_i32 m0, s43, 0x2000
	s_nop 0
	global_load_lds_dwordx4 v[146:147], off
	s_waitcnt vmcnt(6)
	s_barrier
	s_setprio 1
	v_mfma_f32_16x16x32_bf16 v[52:55], v[206:209], v[174:177], v[52:55]
	v_mfma_f32_16x16x32_bf16 v[48:51], v[214:217], v[174:177], v[48:51]
	v_mfma_f32_16x16x32_bf16 v[36:39], v[206:209], v[182:185], v[36:39]
	v_mfma_f32_16x16x32_bf16 v[32:35], v[214:217], v[182:185], v[32:35]
	v_mfma_f32_16x16x32_bf16 v[20:23], v[206:209], v[190:193], v[20:23]
	v_mfma_f32_16x16x32_bf16 v[16:19], v[214:217], v[190:193], v[16:19]
	v_mfma_f32_16x16x32_bf16 v[4:7], v[206:209], v[198:201], v[4:7]
	v_mfma_f32_16x16x32_bf16 v[0:3], v[214:217], v[198:201], v[0:3]
	v_mfma_f32_16x16x32_bf16 v[52:55], v[210:213], v[178:181], v[52:55]
	v_mfma_f32_16x16x32_bf16 v[48:51], v[218:221], v[178:181], v[48:51]
	v_mfma_f32_16x16x32_bf16 v[36:39], v[210:213], v[186:189], v[36:39]
	v_mfma_f32_16x16x32_bf16 v[32:35], v[218:221], v[186:189], v[32:35]
	v_mfma_f32_16x16x32_bf16 v[20:23], v[210:213], v[194:197], v[20:23]
	v_mfma_f32_16x16x32_bf16 v[16:19], v[218:221], v[194:197], v[16:19]
	v_mfma_f32_16x16x32_bf16 v[4:7], v[210:213], v[202:205], v[4:7]
	v_mfma_f32_16x16x32_bf16 v[0:3], v[218:221], v[202:205], v[0:3]
	s_setprio 0
	s_add_i32 s43, 0, 0x18000
	v_add_u32_e32 v170, s43, v155
	s_barrier
	ds_read_b128 v[146:149], v170
	ds_read_b128 v[150:153], v170 offset:1024
	ds_read_b128 v[160:163], v170 offset:2048
	ds_read_b128 v[170:173], v170 offset:3072
	s_add_u32 s14, s18, 0x110000
	s_addc_u32 s15, s19, 0
	s_mov_b32 m0, s53
	v_lshl_add_u64 v[206:207], s[14:15], 0, v[134:135]
	ds_read_b128 v[174:177], v158 offset:32768
	ds_read_b128 v[178:181], v158 offset:33792
	ds_read_b128 v[182:185], v158 offset:34816
	ds_read_b128 v[186:189], v158 offset:35840
	ds_read_b128 v[190:193], v158 offset:36864
	ds_read_b128 v[194:197], v158 offset:37888
	ds_read_b128 v[198:201], v158 offset:38912
	ds_read_b128 v[202:205], v158 offset:39936
	global_load_lds_dwordx4 v[206:207], off
	v_lshl_add_u64 v[206:207], s[14:15], 0, v[130:131]
	s_mov_b32 m0, s54
	s_nop 0
	global_load_lds_dwordx4 v[206:207], off
	s_waitcnt lgkmcnt(8)
	s_barrier
	s_waitcnt lgkmcnt(0)
	s_setprio 1
	s_waitcnt lgkmcnt(0)
	v_mfma_f32_16x16x32_bf16 v[124:127], v[146:149], v[174:177], v[124:127]
	v_mfma_f32_16x16x32_bf16 v[120:123], v[160:163], v[174:177], v[120:123]
	v_mfma_f32_16x16x32_bf16 v[108:111], v[146:149], v[182:185], v[108:111]
	v_mfma_f32_16x16x32_bf16 v[104:107], v[160:163], v[182:185], v[104:107]
	v_mfma_f32_16x16x32_bf16 v[92:95], v[146:149], v[190:193], v[92:95]
	v_mfma_f32_16x16x32_bf16 v[88:91], v[160:163], v[190:193], v[88:91]
	v_mfma_f32_16x16x32_bf16 v[76:79], v[146:149], v[198:201], v[76:79]
	v_mfma_f32_16x16x32_bf16 v[72:75], v[160:163], v[198:201], v[72:75]
	v_mfma_f32_16x16x32_bf16 v[124:127], v[150:153], v[178:181], v[124:127]
	v_mfma_f32_16x16x32_bf16 v[120:123], v[170:173], v[178:181], v[120:123]
	v_mfma_f32_16x16x32_bf16 v[108:111], v[150:153], v[186:189], v[108:111]
	v_mfma_f32_16x16x32_bf16 v[104:107], v[170:173], v[186:189], v[104:107]
	v_mfma_f32_16x16x32_bf16 v[92:95], v[150:153], v[194:197], v[92:95]
	v_mfma_f32_16x16x32_bf16 v[88:91], v[170:173], v[194:197], v[88:91]
	v_mfma_f32_16x16x32_bf16 v[76:79], v[150:153], v[202:205], v[76:79]
	v_mfma_f32_16x16x32_bf16 v[72:75], v[170:173], v[202:205], v[72:75]
	s_setprio 0
	s_barrier
	s_add_i32 s18, 0, 0x1c000
	s_add_i32 s14, s43, s37
	v_add_u32_e32 v218, s18, v155
	v_lshl_add_u64 v[164:165], v[164:165], 0, s[26:27]
	s_mov_b32 m0, s14
	ds_read_b128 v[206:209], v218
	ds_read_b128 v[210:213], v218 offset:1024
	ds_read_b128 v[214:217], v218 offset:2048
	ds_read_b128 v[218:221], v218 offset:3072
	global_load_lds_dwordx4 v[164:165], off
	v_lshl_add_u64 v[164:165], v[222:223], 0, s[26:27]
	s_add_i32 m0, s14, 0x2000
	s_nop 0
	global_load_lds_dwordx4 v[164:165], off
	s_barrier
	s_waitcnt lgkmcnt(0)
	s_setprio 1
	s_waitcnt lgkmcnt(0)
	v_mfma_f32_16x16x32_bf16 v[116:119], v[206:209], v[174:177], v[116:119]
	v_mfma_f32_16x16x32_bf16 v[112:115], v[214:217], v[174:177], v[112:115]
	v_mfma_f32_16x16x32_bf16 v[100:103], v[206:209], v[182:185], v[100:103]
	v_mfma_f32_16x16x32_bf16 v[96:99], v[214:217], v[182:185], v[96:99]
	v_mfma_f32_16x16x32_bf16 v[84:87], v[206:209], v[190:193], v[84:87]
	v_mfma_f32_16x16x32_bf16 v[80:83], v[214:217], v[190:193], v[80:83]
	v_mfma_f32_16x16x32_bf16 v[68:71], v[206:209], v[198:201], v[68:71]
	v_mfma_f32_16x16x32_bf16 v[64:67], v[214:217], v[198:201], v[64:67]
	v_mfma_f32_16x16x32_bf16 v[116:119], v[210:213], v[178:181], v[116:119]
	v_mfma_f32_16x16x32_bf16 v[112:115], v[218:221], v[178:181], v[112:115]
	v_mfma_f32_16x16x32_bf16 v[100:103], v[210:213], v[186:189], v[100:103]
	v_mfma_f32_16x16x32_bf16 v[96:99], v[218:221], v[186:189], v[96:99]
	v_mfma_f32_16x16x32_bf16 v[84:87], v[210:213], v[194:197], v[84:87]
	v_mfma_f32_16x16x32_bf16 v[80:83], v[218:221], v[194:197], v[80:83]
	v_mfma_f32_16x16x32_bf16 v[68:71], v[210:213], v[202:205], v[68:71]
	v_mfma_f32_16x16x32_bf16 v[64:67], v[218:221], v[202:205], v[64:67]
	s_setprio 0
	s_mov_b32 m0, s56
	v_lshl_add_u64 v[164:165], v[224:225], 0, s[26:27]
	s_barrier
	ds_read_b128 v[174:177], v158 offset:49152
	ds_read_b128 v[178:181], v158 offset:50176
	ds_read_b128 v[182:185], v158 offset:51200
	ds_read_b128 v[186:189], v158 offset:52224
	ds_read_b128 v[190:193], v158 offset:53248
	ds_read_b128 v[194:197], v158 offset:54272
	ds_read_b128 v[198:201], v158 offset:55296
	ds_read_b128 v[202:205], v158 offset:56320
	global_load_lds_dwordx4 v[164:165], off
	v_lshl_add_u64 v[164:165], v[226:227], 0, s[26:27]
	s_mov_b32 m0, s57
	s_nop 0
	global_load_lds_dwordx4 v[164:165], off
	s_barrier
; __device__ __forceinline__ float sigmoidf_(float x) { return 1.0f / (1.0f + __expf(-x)); }
; #define PG8_STAGE(bufoff, gbase, voff) do { _Pragma("unroll") for (int _i = 0; _i < 2; ++_i) \
;         __builtin_amdgcn_global_load_lds((const unsigned*)((const char*)(gbase) + (voff)[_i]), (LAS unsigned*)(lds + (bufoff) + ldsw + _i * 8192), 16, 0, 0); } while (0)
; #define PG8_MMA(ai, bj, At, Bt) do { __builtin_amdgcn_s_setprio(1); _Pragma("unroll") for (int m = 0; m < 4; ++m) _Pragma("unroll") for (int n = 0; n < 2; ++n) _Pragma("unroll") for (int k = 0; k < 2; ++k) \
;         acc[ai][bj][m][n] = __builtin_amdgcn_mfma_f32_16x16x32_bf16(Bt[n][k], At[m][k], acc[ai][bj][m][n], 0, 0, 0); __builtin_amdgcn_s_setprio(0); } while (0)
; #define PG8_WAIT_V(n) asm volatile("s_waitcnt vmcnt(" #n ")" ::: "memory")
; #define PG8_WAIT_L(n) asm volatile("s_waitcnt lgkmcnt(" #n ")" ::: "memory")
; #define PG8_BAR __builtin_amdgcn_s_barrier()
; #define PG8_SCHED __builtin_amdgcn_sched_barrier(0)
; __device__ __forceinline__ void unpack8(const u32x4 w, f32x4& v0, f32x4& v1) { v0 = (f32x4){bflo(w.x), bfhi(w.x), bflo(w.y), bfhi(w.y)}; v1 = (f32x4){bflo(w.z), bfhi(w.z), bflo(w.w), bfhi(w.w)}; }
;     ...
;             PG8_BAR; PG8_WAIT_L(0); PG8_MMA(1, 0, At, B0); PG8_BAR; PG8_SCHED;
;             PG8_STAGE(PG8_SB(1, 1), b3 + hB, voffB);
;             PG8_WAIT_V(6); PG8_BAR; PG8_MMA(1, 1, At, B1); PG8_BAR;
;         }
;         E(acc, cur, wr, wc, fr, fq);
;     __device__ __forceinline__ void operator()(const f32x4 (&acc)[2][2][4][2], const Unit& u, int wr, int wc, int fr, int fq) const {
;         const int row0 = u.pm * 256 + wr * 64 + fr, col0 = u.pn * 256 + wc * 32 + 8 * fq;
; #pragma unroll
;         for (int ai = 0; ai < 2; ++ai)
; #pragma unroll
;             for (int m = 0; m < 4; ++m) {
;                 bf16_t* rowp = z + (size_t)(row0 + ai * 128 + m * 16) * DIN + col0;
; #pragma unroll
;                 for (int bj = 0; bj < 2; ++bj) {
;                     const u32x4 gw = *(const u32x4*)(rowp + (MODE == 0 ? O_GB : O_GA) + bj * 128);
;                     f32x4 g0, g1; unpack8(gw, g0, g1);
;                     f32x4 v0, v1;
; #pragma unroll
;                     for (int j = 0; j < 4; ++j) { v0[j] = sigmoidf_(g0[j]) * acc[ai][bj][m][0][j]; v1[j] = sigmoidf_(g1[j]) * acc[ai][bj][m][1][j]; }
	s_waitcnt lgkmcnt(0)
	s_setprio 1
	s_waitcnt lgkmcnt(0)
	v_mfma_f32_16x16x32_bf16 v[60:63], v[146:149], v[174:177], v[60:63]
	v_mfma_f32_16x16x32_bf16 v[56:59], v[160:163], v[174:177], v[56:59]
	v_mfma_f32_16x16x32_bf16 v[44:47], v[146:149], v[182:185], v[44:47]
	v_mfma_f32_16x16x32_bf16 v[40:43], v[160:163], v[182:185], v[40:43]
	v_mfma_f32_16x16x32_bf16 v[28:31], v[146:149], v[190:193], v[28:31]
	v_mfma_f32_16x16x32_bf16 v[24:27], v[160:163], v[190:193], v[24:27]
	v_mfma_f32_16x16x32_bf16 v[12:15], v[146:149], v[198:201], v[12:15]
	v_mfma_f32_16x16x32_bf16 v[8:11], v[160:163], v[198:201], v[8:11]
	v_mfma_f32_16x16x32_bf16 v[60:63], v[150:153], v[178:181], v[60:63]
	v_mfma_f32_16x16x32_bf16 v[56:59], v[170:173], v[178:181], v[56:59]
	v_mfma_f32_16x16x32_bf16 v[44:47], v[150:153], v[186:189], v[44:47]
	v_mfma_f32_16x16x32_bf16 v[40:43], v[170:173], v[186:189], v[40:43]
	v_mfma_f32_16x16x32_bf16 v[28:31], v[150:153], v[194:197], v[28:31]
	v_mfma_f32_16x16x32_bf16 v[24:27], v[170:173], v[194:197], v[24:27]
	v_mfma_f32_16x16x32_bf16 v[12:15], v[150:153], v[202:205], v[12:15]
	v_mfma_f32_16x16x32_bf16 v[8:11], v[170:173], v[202:205], v[8:11]
	s_setprio 0
	s_barrier
	s_add_u32 s14, s16, 0x20080
	s_addc_u32 s15, s17, 0
	s_add_i32 s16, s18, s37
	v_lshl_add_u64 v[146:147], s[14:15], 0, v[132:133]
	s_mov_b32 m0, s16
	s_nop 0
	global_load_lds_dwordx4 v[146:147], off
	v_lshl_add_u64 v[146:147], s[14:15], 0, v[128:129]
	s_add_i32 m0, s16, 0x2000
	s_nop 0
	global_load_lds_dwordx4 v[146:147], off
	s_waitcnt vmcnt(6)
	s_barrier
	s_setprio 1
	v_mfma_f32_16x16x32_bf16 v[52:55], v[206:209], v[174:177], v[52:55]
	v_mfma_f32_16x16x32_bf16 v[48:51], v[214:217], v[174:177], v[48:51]
	v_mfma_f32_16x16x32_bf16 v[36:39], v[206:209], v[182:185], v[36:39]
	v_mfma_f32_16x16x32_bf16 v[32:35], v[214:217], v[182:185], v[32:35]
	v_mfma_f32_16x16x32_bf16 v[20:23], v[206:209], v[190:193], v[20:23]
	v_mfma_f32_16x16x32_bf16 v[16:19], v[214:217], v[190:193], v[16:19]
	v_mfma_f32_16x16x32_bf16 v[4:7], v[206:209], v[198:201], v[4:7]
	v_mfma_f32_16x16x32_bf16 v[0:3], v[214:217], v[198:201], v[0:3]
	v_mfma_f32_16x16x32_bf16 v[52:55], v[210:213], v[178:181], v[52:55]
	v_mfma_f32_16x16x32_bf16 v[48:51], v[218:221], v[178:181], v[48:51]
	v_mfma_f32_16x16x32_bf16 v[36:39], v[210:213], v[186:189], v[36:39]
	v_mfma_f32_16x16x32_bf16 v[32:35], v[218:221], v[186:189], v[32:35]
	v_mfma_f32_16x16x32_bf16 v[20:23], v[210:213], v[194:197], v[20:23]
	v_mfma_f32_16x16x32_bf16 v[16:19], v[218:221], v[194:197], v[16:19]
	v_mfma_f32_16x16x32_bf16 v[4:7], v[210:213], v[202:205], v[4:7]
	v_mfma_f32_16x16x32_bf16 v[0:3], v[218:221], v[202:205], v[0:3]
	s_setprio 0
	s_add_i32 s42, s42, 2
	s_add_u32 s29, s29, 0x100
	s_addc_u32 s33, s33, 0
	s_cmp_gt_u32 s42, 5
	s_mov_b64 s[14:15], s[12:13]
	s_barrier
	s_cbranch_scc0 .LBB0_627
	v_lshl_or_b32 v148, s7, 8, v156
	v_lshl_add_u32 v160, s6, 8, v154
	v_ashrrev_i32_e32 v149, 31, v148
	v_mov_b64_e32 v[146:147], s[24:25]
	v_mad_i64_i32 v[150:151], s[6:7], v160, s61, v[146:147]
	v_lshlrev_b64 v[148:149], 1, v[148:149]
	v_lshl_add_u64 v[150:151], v[150:151], 0, v[148:149]
	v_add_co_u32_e32 v152, vcc, 0x1000, v150
	s_nop 1
	v_addc_co_u32_e32 v153, vcc, 0, v151, vcc
	v_subrev_u32_e32 v198, s24, v150
	v_add_u32_e32 v199, 0x1a00, v198
	global_load_dwordx4 v[200:203], v199, s[24:25]
	v_add_u32_e32 v199, 0x1b00, v198
	global_load_dwordx4 v[204:207], v199, s[24:25]
	v_add_u32_e32 v199, 0x23a00, v198
	global_load_dwordx4 v[208:211], v199, s[24:25]
	v_add_u32_e32 v199, 0x23b00, v198
	global_load_dwordx4 v[212:215], v199, s[24:25]
	v_add_u32_e32 v199, 0x45a00, v198
	global_load_dwordx4 v[216:219], v199, s[24:25]
	v_add_u32_e32 v199, 0x45b00, v198
	global_load_dwordx4 v[232:235], v199, s[24:25]
	v_add_u32_e32 v199, 0x67a00, v198
	global_load_dwordx4 v[236:239], v199, s[24:25]
	s_waitcnt vmcnt(6)
	v_mov_b32_e32 v162, v200
	v_mov_b32_e32 v163, v201
	v_mov_b32_e32 v164, v202
	v_mov_b32_e32 v165, v203
	v_add_u32_e32 v199, 0x67b00, v198
	global_load_dwordx4 v[200:203], v199, s[24:25]
	s_mov_b32 s100, 0xbfb8aa3b
	v_lshlrev_b32_e32 v242, 16, v162
	v_and_b32_e32 v243, 0xffff0000, v162
	v_lshlrev_b32_e32 v244, 16, v164
	v_and_b32_e32 v245, 0xffff0000, v164
	v_lshlrev_b32_e32 v246, 16, v163
	v_and_b32_e32 v247, 0xffff0000, v163
	v_lshlrev_b32_e32 v248, 16, v165
	v_and_b32_e32 v249, 0xffff0000, v165
	v_pk_mul_f32 v[242:243], v[242:243], s[100:101] op_sel_hi:[1,0]
	v_pk_mul_f32 v[244:245], v[244:245], s[100:101] op_sel_hi:[1,0]
	v_pk_mul_f32 v[246:247], v[246:247], s[100:101] op_sel_hi:[1,0]
	v_pk_mul_f32 v[248:249], v[248:249], s[100:101] op_sel_hi:[1,0]
	v_exp_f32_e32 v242, v242
	v_exp_f32_e32 v243, v243
	v_exp_f32_e32 v244, v244
	v_exp_f32_e32 v245, v245
	v_exp_f32_e32 v246, v246
	v_exp_f32_e32 v247, v247
	v_exp_f32_e32 v248, v248
	v_exp_f32_e32 v249, v249
	s_nop 0
	v_pk_add_f32 v[242:243], v[242:243], 1.0 op_sel_hi:[1,0]
	v_pk_add_f32 v[244:245], v[244:245], 1.0 op_sel_hi:[1,0]
	v_pk_add_f32 v[246:247], v[246:247], 1.0 op_sel_hi:[1,0]
	v_pk_add_f32 v[248:249], v[248:249], 1.0 op_sel_hi:[1,0]
	v_rcp_f32_e32 v250, v242
	v_rcp_f32_e32 v251, v243
	s_nop 0
	v_pk_fma_f32 v[252:253], v[242:243], v[250:251], 1.0 op_sel_hi:[1,1,0] neg_lo:[1,0,0] neg_hi:[1,0,0]
	v_pk_fma_f32 v[250:251], v[252:253], v[250:251], v[250:251]
	v_pk_fma_f32 v[252:253], v[242:243], v[250:251], 1.0 op_sel_hi:[1,1,0] neg_lo:[1,0,0] neg_hi:[1,0,0]
	v_pk_fma_f32 v[254:255], v[252:253], v[250:251], v[250:251]
	v_pk_fma_f32 v[252:253], v[242:243], v[254:255], 1.0 op_sel_hi:[1,1,0] neg_lo:[1,0,0] neg_hi:[1,0,0]
	v_pk_fma_f32 v[254:255], v[252:253], v[250:251], v[254:255]
	v_div_fixup_f32 v242, v254, v242, 1.0
; __device__ __forceinline__ float sigmoidf_(float x) { return 1.0f / (1.0f + __expf(-x)); }
; __device__ __forceinline__ u32x4 pack8(const f32x4 v0, const f32x4 v1) { u32x4 w; w.x = pk2(v0[0], v0[1]); w.y = pk2(v0[2], v0[3]); w.z = pk2(v1[0], v1[1]); w.w = pk2(v1[2], v1[3]); return w; }
; __device__ __forceinline__ void unpack8(const u32x4 w, f32x4& v0, f32x4& v1) { v0 = (f32x4){bflo(w.x), bfhi(w.x), bflo(w.y), bfhi(w.y)}; v1 = (f32x4){bflo(w.z), bfhi(w.z), bflo(w.w), bfhi(w.w)}; }
;     __device__ __forceinline__ void operator()(const f32x4 (&acc)[2][2][4][2], const Unit& u, int wr, int wc, int fr, int fq) const {
;     ...
;         for (int ai = 0; ai < 2; ++ai)
; #pragma unroll
;             for (int m = 0; m < 4; ++m) {
;                 bf16_t* rowp = z + (size_t)(row0 + ai * 128 + m * 16) * DIN + col0;
; #pragma unroll
;                 for (int bj = 0; bj < 2; ++bj) {
;                     const u32x4 gw = *(const u32x4*)(rowp + (MODE == 0 ? O_GB : O_GA) + bj * 128);
;                     f32x4 g0, g1; unpack8(gw, g0, g1);
;                     f32x4 v0, v1;
; #pragma unroll
;                     for (int j = 0; j < 4; ++j) { v0[j] = sigmoidf_(g0[j]) * acc[ai][bj][m][0][j]; v1[j] = sigmoidf_(g1[j]) * acc[ai][bj][m][1][j]; }
;                     if (MODE == 1) { const u32x4 mw = *(const u32x4*)(rowp + bj * 128); f32x4 m0, m1; unpack8(mw, m0, m1); v0 += m0; v1 += m1; }
;                     *(u32x4*)(rowp + bj * 128) = pack8(v0, v1); }
	v_div_fixup_f32 v243, v255, v243, 1.0
	v_rcp_f32_e32 v250, v244
	v_rcp_f32_e32 v251, v245
	s_nop 0
	v_pk_fma_f32 v[252:253], v[244:245], v[250:251], 1.0 op_sel_hi:[1,1,0] neg_lo:[1,0,0] neg_hi:[1,0,0]
	v_pk_fma_f32 v[250:251], v[252:253], v[250:251], v[250:251]
	v_pk_fma_f32 v[252:253], v[244:245], v[250:251], 1.0 op_sel_hi:[1,1,0] neg_lo:[1,0,0] neg_hi:[1,0,0]
	v_pk_fma_f32 v[254:255], v[252:253], v[250:251], v[250:251]
	v_pk_fma_f32 v[252:253], v[244:245], v[254:255], 1.0 op_sel_hi:[1,1,0] neg_lo:[1,0,0] neg_hi:[1,0,0]
	v_pk_fma_f32 v[254:255], v[252:253], v[250:251], v[254:255]
	v_div_fixup_f32 v244, v254, v244, 1.0
	v_div_fixup_f32 v245, v255, v245, 1.0
	v_rcp_f32_e32 v250, v246
	v_rcp_f32_e32 v251, v247
	s_nop 0
	v_pk_fma_f32 v[252:253], v[246:247], v[250:251], 1.0 op_sel_hi:[1,1,0] neg_lo:[1,0,0] neg_hi:[1,0,0]
	v_pk_fma_f32 v[250:251], v[252:253], v[250:251], v[250:251]
	v_pk_fma_f32 v[252:253], v[246:247], v[250:251], 1.0 op_sel_hi:[1,1,0] neg_lo:[1,0,0] neg_hi:[1,0,0]
	v_pk_fma_f32 v[254:255], v[252:253], v[250:251], v[250:251]
	v_pk_fma_f32 v[252:253], v[246:247], v[254:255], 1.0 op_sel_hi:[1,1,0] neg_lo:[1,0,0] neg_hi:[1,0,0]
	v_pk_fma_f32 v[254:255], v[252:253], v[250:251], v[254:255]
	v_div_fixup_f32 v246, v254, v246, 1.0
	v_div_fixup_f32 v247, v255, v247, 1.0
	v_rcp_f32_e32 v250, v248
	v_rcp_f32_e32 v251, v249
	s_nop 0
	v_pk_fma_f32 v[252:253], v[248:249], v[250:251], 1.0 op_sel_hi:[1,1,0] neg_lo:[1,0,0] neg_hi:[1,0,0]
	v_pk_fma_f32 v[250:251], v[252:253], v[250:251], v[250:251]
	v_pk_fma_f32 v[252:253], v[248:249], v[250:251], 1.0 op_sel_hi:[1,1,0] neg_lo:[1,0,0] neg_hi:[1,0,0]
	v_pk_fma_f32 v[254:255], v[252:253], v[250:251], v[250:251]
	v_pk_fma_f32 v[252:253], v[248:249], v[254:255], 1.0 op_sel_hi:[1,1,0] neg_lo:[1,0,0] neg_hi:[1,0,0]
	v_pk_fma_f32 v[254:255], v[252:253], v[250:251], v[254:255]
	v_div_fixup_f32 v248, v254, v248, 1.0
	v_div_fixup_f32 v249, v255, v249, 1.0
	s_mov_b64 vcc, s[12:13]
	s_mov_b64 vcc, s[14:15]
	v_mul_f32_e32 v124, v124, v242
	s_mov_b64 vcc, s[16:17]
	v_mul_f32_e32 v161, v120, v244
	v_mul_f32_e32 v120, v125, v243
	v_mul_f32_e32 v125, v121, v245
	s_mov_b64 vcc, s[18:19]
	v_mul_f32_e32 v126, v126, v246
	v_mul_f32_e32 v162, v122, v248
	v_mul_f32_e32 v121, v127, v247
	v_mul_f32_e32 v123, v123, v249
	v_cvt_pk_bf16_f32 v120, v124, v120
	v_cvt_pk_bf16_f32 v121, v126, v121
	v_cvt_pk_bf16_f32 v122, v161, v125
	v_cvt_pk_bf16_f32 v123, v162, v123
	s_mov_b64 s[16:17], s[34:35]
	global_store_dwordx4 v[150:151], v[120:123], off
	s_mov_b64 s[14:15], s[30:31]
	s_waitcnt vmcnt(7)
	v_mov_b32_e32 v124, v204
	v_mov_b32_e32 v125, v205
	v_mov_b32_e32 v126, v206
	v_mov_b32_e32 v127, v207
	v_add_u32_e32 v199, 0x111a00, v198
	global_load_dwordx4 v[204:207], v199, s[24:25]
	s_mov_b32 s100, 0xbfb8aa3b
	v_lshlrev_b32_e32 v242, 16, v124
	v_and_b32_e32 v243, 0xffff0000, v124
	v_lshlrev_b32_e32 v244, 16, v126
	v_and_b32_e32 v245, 0xffff0000, v126
	v_lshlrev_b32_e32 v246, 16, v125
	v_and_b32_e32 v247, 0xffff0000, v125
	v_lshlrev_b32_e32 v248, 16, v127
	v_and_b32_e32 v249, 0xffff0000, v127
	v_pk_mul_f32 v[242:243], v[242:243], s[100:101] op_sel_hi:[1,0]
	v_pk_mul_f32 v[244:245], v[244:245], s[100:101] op_sel_hi:[1,0]
	v_pk_mul_f32 v[246:247], v[246:247], s[100:101] op_sel_hi:[1,0]
	v_pk_mul_f32 v[248:249], v[248:249], s[100:101] op_sel_hi:[1,0]
	v_exp_f32_e32 v242, v242
	v_exp_f32_e32 v243, v243
	v_exp_f32_e32 v244, v244
	v_exp_f32_e32 v245, v245
	v_exp_f32_e32 v246, v246
	v_exp_f32_e32 v247, v247
	v_exp_f32_e32 v248, v248
	v_exp_f32_e32 v249, v249
	s_nop 0
	v_pk_add_f32 v[242:243], v[242:243], 1.0 op_sel_hi:[1,0]
	v_pk_add_f32 v[244:245], v[244:245], 1.0 op_sel_hi:[1,0]
	v_pk_add_f32 v[246:247], v[246:247], 1.0 op_sel_hi:[1,0]
	v_pk_add_f32 v[248:249], v[248:249], 1.0 op_sel_hi:[1,0]
	v_rcp_f32_e32 v250, v242
	v_rcp_f32_e32 v251, v243
	s_nop 0
	v_pk_fma_f32 v[252:253], v[242:243], v[250:251], 1.0 op_sel_hi:[1,1,0] neg_lo:[1,0,0] neg_hi:[1,0,0]
	v_pk_fma_f32 v[250:251], v[252:253], v[250:251], v[250:251]
	v_pk_fma_f32 v[252:253], v[242:243], v[250:251], 1.0 op_sel_hi:[1,1,0] neg_lo:[1,0,0] neg_hi:[1,0,0]
	v_pk_fma_f32 v[254:255], v[252:253], v[250:251], v[250:251]
	v_pk_fma_f32 v[252:253], v[242:243], v[254:255], 1.0 op_sel_hi:[1,1,0] neg_lo:[1,0,0] neg_hi:[1,0,0]
	v_pk_fma_f32 v[254:255], v[252:253], v[250:251], v[254:255]
	v_div_fixup_f32 v242, v254, v242, 1.0
	v_div_fixup_f32 v243, v255, v243, 1.0
	v_rcp_f32_e32 v250, v244
	v_rcp_f32_e32 v251, v245
	s_nop 0
	v_pk_fma_f32 v[252:253], v[244:245], v[250:251], 1.0 op_sel_hi:[1,1,0] neg_lo:[1,0,0] neg_hi:[1,0,0]
	v_pk_fma_f32 v[250:251], v[252:253], v[250:251], v[250:251]
	v_pk_fma_f32 v[252:253], v[244:245], v[250:251], 1.0 op_sel_hi:[1,1,0] neg_lo:[1,0,0] neg_hi:[1,0,0]
	v_pk_fma_f32 v[254:255], v[252:253], v[250:251], v[250:251]
	v_pk_fma_f32 v[252:253], v[244:245], v[254:255], 1.0 op_sel_hi:[1,1,0] neg_lo:[1,0,0] neg_hi:[1,0,0]
	v_pk_fma_f32 v[254:255], v[252:253], v[250:251], v[254:255]
	v_div_fixup_f32 v244, v254, v244, 1.0
	v_div_fixup_f32 v245, v255, v245, 1.0
	v_rcp_f32_e32 v250, v246
	v_rcp_f32_e32 v251, v247
	s_nop 0
	v_pk_fma_f32 v[252:253], v[246:247], v[250:251], 1.0 op_sel_hi:[1,1,0] neg_lo:[1,0,0] neg_hi:[1,0,0]
	v_pk_fma_f32 v[250:251], v[252:253], v[250:251], v[250:251]
	v_pk_fma_f32 v[252:253], v[246:247], v[250:251], 1.0 op_sel_hi:[1,1,0] neg_lo:[1,0,0] neg_hi:[1,0,0]
	v_pk_fma_f32 v[254:255], v[252:253], v[250:251], v[250:251]
	v_pk_fma_f32 v[252:253], v[246:247], v[254:255], 1.0 op_sel_hi:[1,1,0] neg_lo:[1,0,0] neg_hi:[1,0,0]
	v_pk_fma_f32 v[254:255], v[252:253], v[250:251], v[254:255]
	v_div_fixup_f32 v246, v254, v246, 1.0
	v_div_fixup_f32 v247, v255, v247, 1.0
	v_rcp_f32_e32 v250, v248
	v_rcp_f32_e32 v251, v249
	s_nop 0
	v_pk_fma_f32 v[252:253], v[248:249], v[250:251], 1.0 op_sel_hi:[1,1,0] neg_lo:[1,0,0] neg_hi:[1,0,0]
	v_pk_fma_f32 v[250:251], v[252:253], v[250:251], v[250:251]
	v_pk_fma_f32 v[252:253], v[248:249], v[250:251], 1.0 op_sel_hi:[1,1,0] neg_lo:[1,0,0] neg_hi:[1,0,0]
	v_pk_fma_f32 v[254:255], v[252:253], v[250:251], v[250:251]
	v_pk_fma_f32 v[252:253], v[248:249], v[254:255], 1.0 op_sel_hi:[1,1,0] neg_lo:[1,0,0] neg_hi:[1,0,0]
	v_pk_fma_f32 v[254:255], v[252:253], v[250:251], v[254:255]
	v_div_fixup_f32 v248, v254, v248, 1.0
	v_div_fixup_f32 v249, v255, v249, 1.0
	s_mov_b64 vcc, s[12:13]
	v_pk_mul_f32 v[116:117], v[116:117], v[242:243]
	v_pk_mul_f32 v[112:113], v[112:113], v[244:245]
	v_pk_mul_f32 v[118:119], v[118:119], v[246:247]
	v_pk_mul_f32 v[120:121], v[114:115], v[248:249]
	v_cvt_pk_bf16_f32 v114, v116, v117
	v_cvt_pk_bf16_f32 v115, v118, v119
	v_cvt_pk_bf16_f32 v116, v112, v113
	v_or_b32_e32 v112, 16, v160
	v_mad_i64_i32 v[112:113], s[6:7], v112, s61, v[146:147]
	v_lshl_add_u64 v[112:113], v[112:113], 0, v[148:149]
	v_add_co_u32_e32 v122, vcc, s62, v112
	v_cvt_pk_bf16_f32 v117, v120, v121
	global_store_dwordx4 v[150:151], v[114:117], off offset:256
	s_nop 0
	v_addc_co_u32_e32 v123, vcc, 0, v113, vcc
	s_waitcnt vmcnt(8)
; __device__ __forceinline__ float sigmoidf_(float x) { return 1.0f / (1.0f + __expf(-x)); }
; __device__ __forceinline__ u32x4 pack8(const f32x4 v0, const f32x4 v1) { u32x4 w; w.x = pk2(v0[0], v0[1]); w.y = pk2(v0[2], v0[3]); w.z = pk2(v1[0], v1[1]); w.w = pk2(v1[2], v1[3]); return w; }
; __device__ __forceinline__ void unpack8(const u32x4 w, f32x4& v0, f32x4& v1) { v0 = (f32x4){bflo(w.x), bfhi(w.x), bflo(w.y), bfhi(w.y)}; v1 = (f32x4){bflo(w.z), bfhi(w.z), bflo(w.w), bfhi(w.w)}; }
;     __device__ __forceinline__ void operator()(const f32x4 (&acc)[2][2][4][2], const Unit& u, int wr, int wc, int fr, int fq) const {
;     ...
;         for (int ai = 0; ai < 2; ++ai)
; #pragma unroll
;             for (int m = 0; m < 4; ++m) {
;                 bf16_t* rowp = z + (size_t)(row0 + ai * 128 + m * 16) * DIN + col0;
; #pragma unroll
;                 for (int bj = 0; bj < 2; ++bj) {
;                     const u32x4 gw = *(const u32x4*)(rowp + (MODE == 0 ? O_GB : O_GA) + bj * 128);
;                     f32x4 g0, g1; unpack8(gw, g0, g1);
;                     f32x4 v0, v1;
; #pragma unroll
;                     for (int j = 0; j < 4; ++j) { v0[j] = sigmoidf_(g0[j]) * acc[ai][bj][m][0][j]; v1[j] = sigmoidf_(g1[j]) * acc[ai][bj][m][1][j]; }
;                     if (MODE == 1) { const u32x4 mw = *(const u32x4*)(rowp + bj * 128); f32x4 m0, m1; unpack8(mw, m0, m1); v0 += m0; v1 += m1; }
;                     *(u32x4*)(rowp + bj * 128) = pack8(v0, v1); }
	v_mov_b32_e32 v118, v208
	v_mov_b32_e32 v119, v209
	v_mov_b32_e32 v120, v210
	v_mov_b32_e32 v121, v211
	v_add_u32_e32 v199, 0x111b00, v198
	global_load_dwordx4 v[208:211], v199, s[24:25]
	s_mov_b32 s100, 0xbfb8aa3b
	v_lshlrev_b32_e32 v242, 16, v118
	v_and_b32_e32 v243, 0xffff0000, v118
	v_lshlrev_b32_e32 v244, 16, v120
	v_and_b32_e32 v245, 0xffff0000, v120
	v_lshlrev_b32_e32 v246, 16, v119
	v_and_b32_e32 v247, 0xffff0000, v119
	v_lshlrev_b32_e32 v248, 16, v121
	v_and_b32_e32 v249, 0xffff0000, v121
	v_pk_mul_f32 v[242:243], v[242:243], s[100:101] op_sel_hi:[1,0]
	v_pk_mul_f32 v[244:245], v[244:245], s[100:101] op_sel_hi:[1,0]
	v_pk_mul_f32 v[246:247], v[246:247], s[100:101] op_sel_hi:[1,0]
	v_pk_mul_f32 v[248:249], v[248:249], s[100:101] op_sel_hi:[1,0]
	v_exp_f32_e32 v242, v242
	v_exp_f32_e32 v243, v243
	v_exp_f32_e32 v244, v244
	v_exp_f32_e32 v245, v245
	v_exp_f32_e32 v246, v246
	v_exp_f32_e32 v247, v247
	v_exp_f32_e32 v248, v248
	v_exp_f32_e32 v249, v249
	s_nop 0
	v_pk_add_f32 v[242:243], v[242:243], 1.0 op_sel_hi:[1,0]
	v_pk_add_f32 v[244:245], v[244:245], 1.0 op_sel_hi:[1,0]
	v_pk_add_f32 v[246:247], v[246:247], 1.0 op_sel_hi:[1,0]
	v_pk_add_f32 v[248:249], v[248:249], 1.0 op_sel_hi:[1,0]
	v_rcp_f32_e32 v250, v242
	v_rcp_f32_e32 v251, v243
	s_nop 0
	v_pk_fma_f32 v[252:253], v[242:243], v[250:251], 1.0 op_sel_hi:[1,1,0] neg_lo:[1,0,0] neg_hi:[1,0,0]
	v_pk_fma_f32 v[250:251], v[252:253], v[250:251], v[250:251]
	v_pk_fma_f32 v[252:253], v[242:243], v[250:251], 1.0 op_sel_hi:[1,1,0] neg_lo:[1,0,0] neg_hi:[1,0,0]
	v_pk_fma_f32 v[254:255], v[252:253], v[250:251], v[250:251]
	v_pk_fma_f32 v[252:253], v[242:243], v[254:255], 1.0 op_sel_hi:[1,1,0] neg_lo:[1,0,0] neg_hi:[1,0,0]
	v_pk_fma_f32 v[254:255], v[252:253], v[250:251], v[254:255]
	v_div_fixup_f32 v242, v254, v242, 1.0
	v_div_fixup_f32 v243, v255, v243, 1.0
	v_rcp_f32_e32 v250, v244
	v_rcp_f32_e32 v251, v245
	s_nop 0
	v_pk_fma_f32 v[252:253], v[244:245], v[250:251], 1.0 op_sel_hi:[1,1,0] neg_lo:[1,0,0] neg_hi:[1,0,0]
	v_pk_fma_f32 v[250:251], v[252:253], v[250:251], v[250:251]
	v_pk_fma_f32 v[252:253], v[244:245], v[250:251], 1.0 op_sel_hi:[1,1,0] neg_lo:[1,0,0] neg_hi:[1,0,0]
	v_pk_fma_f32 v[254:255], v[252:253], v[250:251], v[250:251]
	v_pk_fma_f32 v[252:253], v[244:245], v[254:255], 1.0 op_sel_hi:[1,1,0] neg_lo:[1,0,0] neg_hi:[1,0,0]
	v_pk_fma_f32 v[254:255], v[252:253], v[250:251], v[254:255]
	v_div_fixup_f32 v244, v254, v244, 1.0
	v_div_fixup_f32 v245, v255, v245, 1.0
	v_rcp_f32_e32 v250, v246
	v_rcp_f32_e32 v251, v247
	s_nop 0
	v_pk_fma_f32 v[252:253], v[246:247], v[250:251], 1.0 op_sel_hi:[1,1,0] neg_lo:[1,0,0] neg_hi:[1,0,0]
	v_pk_fma_f32 v[250:251], v[252:253], v[250:251], v[250:251]
	v_pk_fma_f32 v[252:253], v[246:247], v[250:251], 1.0 op_sel_hi:[1,1,0] neg_lo:[1,0,0] neg_hi:[1,0,0]
	v_pk_fma_f32 v[254:255], v[252:253], v[250:251], v[250:251]
	v_pk_fma_f32 v[252:253], v[246:247], v[254:255], 1.0 op_sel_hi:[1,1,0] neg_lo:[1,0,0] neg_hi:[1,0,0]
	v_pk_fma_f32 v[254:255], v[252:253], v[250:251], v[254:255]
	v_div_fixup_f32 v246, v254, v246, 1.0
	v_div_fixup_f32 v247, v255, v247, 1.0
	v_rcp_f32_e32 v250, v248
	v_rcp_f32_e32 v251, v249
	s_nop 0
	v_pk_fma_f32 v[252:253], v[248:249], v[250:251], 1.0 op_sel_hi:[1,1,0] neg_lo:[1,0,0] neg_hi:[1,0,0]
	v_pk_fma_f32 v[250:251], v[252:253], v[250:251], v[250:251]
	v_pk_fma_f32 v[252:253], v[248:249], v[250:251], 1.0 op_sel_hi:[1,1,0] neg_lo:[1,0,0] neg_hi:[1,0,0]
	v_pk_fma_f32 v[254:255], v[252:253], v[250:251], v[250:251]
	v_pk_fma_f32 v[252:253], v[248:249], v[254:255], 1.0 op_sel_hi:[1,1,0] neg_lo:[1,0,0] neg_hi:[1,0,0]
	v_pk_fma_f32 v[254:255], v[252:253], v[250:251], v[254:255]
	v_div_fixup_f32 v248, v254, v248, 1.0
	v_div_fixup_f32 v249, v255, v249, 1.0
	v_mul_f32_e32 v108, v108, v242
	v_mul_f32_e32 v114, v104, v244
	v_mul_f32_e32 v104, v109, v243
	v_mul_f32_e32 v109, v105, v245
	v_mul_f32_e32 v105, v110, v246
	v_mul_f32_e32 v110, v106, v248
	v_mul_f32_e32 v106, v111, v247
	v_mul_f32_e32 v107, v107, v249
	v_cvt_pk_bf16_f32 v104, v108, v104
	v_cvt_pk_bf16_f32 v105, v105, v106
	v_cvt_pk_bf16_f32 v106, v114, v109
	v_cvt_pk_bf16_f32 v107, v110, v107
	s_waitcnt vmcnt(8)
	v_mov_b32_e32 v108, v212
	v_mov_b32_e32 v109, v213
	v_mov_b32_e32 v110, v214
	v_mov_b32_e32 v111, v215
	v_add_u32_e32 v199, 0x133a00, v198
	global_load_dwordx4 v[212:215], v199, s[24:25]
	s_mov_b32 s100, 0xbfb8aa3b
	v_lshlrev_b32_e32 v242, 16, v108
	v_and_b32_e32 v243, 0xffff0000, v108
	v_lshlrev_b32_e32 v244, 16, v110
	v_and_b32_e32 v245, 0xffff0000, v110
	v_lshlrev_b32_e32 v246, 16, v109
	v_and_b32_e32 v247, 0xffff0000, v109
	v_lshlrev_b32_e32 v248, 16, v111
	v_and_b32_e32 v249, 0xffff0000, v111
	v_pk_mul_f32 v[242:243], v[242:243], s[100:101] op_sel_hi:[1,0]
	v_pk_mul_f32 v[244:245], v[244:245], s[100:101] op_sel_hi:[1,0]
	v_pk_mul_f32 v[246:247], v[246:247], s[100:101] op_sel_hi:[1,0]
	v_pk_mul_f32 v[248:249], v[248:249], s[100:101] op_sel_hi:[1,0]
	v_exp_f32_e32 v242, v242
	v_exp_f32_e32 v243, v243
	v_exp_f32_e32 v244, v244
	v_exp_f32_e32 v245, v245
	v_exp_f32_e32 v246, v246
	v_exp_f32_e32 v247, v247
	v_exp_f32_e32 v248, v248
	v_exp_f32_e32 v249, v249
	s_nop 0
	v_pk_add_f32 v[242:243], v[242:243], 1.0 op_sel_hi:[1,0]
	v_pk_add_f32 v[244:245], v[244:245], 1.0 op_sel_hi:[1,0]
	v_pk_add_f32 v[246:247], v[246:247], 1.0 op_sel_hi:[1,0]
	v_pk_add_f32 v[248:249], v[248:249], 1.0 op_sel_hi:[1,0]
	v_rcp_f32_e32 v250, v242
	v_rcp_f32_e32 v251, v243
	s_nop 0
	v_pk_fma_f32 v[252:253], v[242:243], v[250:251], 1.0 op_sel_hi:[1,1,0] neg_lo:[1,0,0] neg_hi:[1,0,0]
	v_pk_fma_f32 v[250:251], v[252:253], v[250:251], v[250:251]
	v_pk_fma_f32 v[252:253], v[242:243], v[250:251], 1.0 op_sel_hi:[1,1,0] neg_lo:[1,0,0] neg_hi:[1,0,0]
; __device__ __forceinline__ float sigmoidf_(float x) { return 1.0f / (1.0f + __expf(-x)); }
; __device__ __forceinline__ u32x4 pack8(const f32x4 v0, const f32x4 v1) { u32x4 w; w.x = pk2(v0[0], v0[1]); w.y = pk2(v0[2], v0[3]); w.z = pk2(v1[0], v1[1]); w.w = pk2(v1[2], v1[3]); return w; }
; __device__ __forceinline__ void unpack8(const u32x4 w, f32x4& v0, f32x4& v1) { v0 = (f32x4){bflo(w.x), bfhi(w.x), bflo(w.y), bfhi(w.y)}; v1 = (f32x4){bflo(w.z), bfhi(w.z), bflo(w.w), bfhi(w.w)}; }
;     __device__ __forceinline__ void operator()(const f32x4 (&acc)[2][2][4][2], const Unit& u, int wr, int wc, int fr, int fq) const {
;     ...
;         for (int ai = 0; ai < 2; ++ai)
; #pragma unroll
;             for (int m = 0; m < 4; ++m) {
;                 bf16_t* rowp = z + (size_t)(row0 + ai * 128 + m * 16) * DIN + col0;
; #pragma unroll
;                 for (int bj = 0; bj < 2; ++bj) {
;                     const u32x4 gw = *(const u32x4*)(rowp + (MODE == 0 ? O_GB : O_GA) + bj * 128);
;                     f32x4 g0, g1; unpack8(gw, g0, g1);
;                     f32x4 v0, v1;
; #pragma unroll
;                     for (int j = 0; j < 4; ++j) { v0[j] = sigmoidf_(g0[j]) * acc[ai][bj][m][0][j]; v1[j] = sigmoidf_(g1[j]) * acc[ai][bj][m][1][j]; }
;                     if (MODE == 1) { const u32x4 mw = *(const u32x4*)(rowp + bj * 128); f32x4 m0, m1; unpack8(mw, m0, m1); v0 += m0; v1 += m1; }
;                     *(u32x4*)(rowp + bj * 128) = pack8(v0, v1); }
	v_pk_fma_f32 v[254:255], v[252:253], v[250:251], v[250:251]
	v_pk_fma_f32 v[252:253], v[242:243], v[254:255], 1.0 op_sel_hi:[1,1,0] neg_lo:[1,0,0] neg_hi:[1,0,0]
	v_pk_fma_f32 v[254:255], v[252:253], v[250:251], v[254:255]
	v_div_fixup_f32 v242, v254, v242, 1.0
	v_div_fixup_f32 v243, v255, v243, 1.0
	v_rcp_f32_e32 v250, v244
	v_rcp_f32_e32 v251, v245
	s_nop 0
	v_pk_fma_f32 v[252:253], v[244:245], v[250:251], 1.0 op_sel_hi:[1,1,0] neg_lo:[1,0,0] neg_hi:[1,0,0]
	v_pk_fma_f32 v[250:251], v[252:253], v[250:251], v[250:251]
	v_pk_fma_f32 v[252:253], v[244:245], v[250:251], 1.0 op_sel_hi:[1,1,0] neg_lo:[1,0,0] neg_hi:[1,0,0]
	v_pk_fma_f32 v[254:255], v[252:253], v[250:251], v[250:251]
	v_pk_fma_f32 v[252:253], v[244:245], v[254:255], 1.0 op_sel_hi:[1,1,0] neg_lo:[1,0,0] neg_hi:[1,0,0]
	v_pk_fma_f32 v[254:255], v[252:253], v[250:251], v[254:255]
	v_div_fixup_f32 v244, v254, v244, 1.0
	v_div_fixup_f32 v245, v255, v245, 1.0
	v_rcp_f32_e32 v250, v246
	v_rcp_f32_e32 v251, v247
	s_nop 0
	v_pk_fma_f32 v[252:253], v[246:247], v[250:251], 1.0 op_sel_hi:[1,1,0] neg_lo:[1,0,0] neg_hi:[1,0,0]
	v_pk_fma_f32 v[250:251], v[252:253], v[250:251], v[250:251]
	v_pk_fma_f32 v[252:253], v[246:247], v[250:251], 1.0 op_sel_hi:[1,1,0] neg_lo:[1,0,0] neg_hi:[1,0,0]
	v_pk_fma_f32 v[254:255], v[252:253], v[250:251], v[250:251]
	v_pk_fma_f32 v[252:253], v[246:247], v[254:255], 1.0 op_sel_hi:[1,1,0] neg_lo:[1,0,0] neg_hi:[1,0,0]
	v_pk_fma_f32 v[254:255], v[252:253], v[250:251], v[254:255]
	v_div_fixup_f32 v246, v254, v246, 1.0
	v_div_fixup_f32 v247, v255, v247, 1.0
	v_rcp_f32_e32 v250, v248
	v_rcp_f32_e32 v251, v249
	s_nop 0
	v_pk_fma_f32 v[252:253], v[248:249], v[250:251], 1.0 op_sel_hi:[1,1,0] neg_lo:[1,0,0] neg_hi:[1,0,0]
	v_pk_fma_f32 v[250:251], v[252:253], v[250:251], v[250:251]
	v_pk_fma_f32 v[252:253], v[248:249], v[250:251], 1.0 op_sel_hi:[1,1,0] neg_lo:[1,0,0] neg_hi:[1,0,0]
	v_pk_fma_f32 v[254:255], v[252:253], v[250:251], v[250:251]
	v_pk_fma_f32 v[252:253], v[248:249], v[254:255], 1.0 op_sel_hi:[1,1,0] neg_lo:[1,0,0] neg_hi:[1,0,0]
	v_pk_fma_f32 v[254:255], v[252:253], v[250:251], v[254:255]
	v_div_fixup_f32 v248, v254, v248, 1.0
	v_div_fixup_f32 v249, v255, v249, 1.0
	global_store_dwordx4 v[112:113], v[104:107], off
	s_nop 0
	v_pk_mul_f32 v[100:101], v[100:101], v[242:243]
	v_pk_mul_f32 v[96:97], v[96:97], v[244:245]
	v_pk_mul_f32 v[102:103], v[102:103], v[246:247]
	v_pk_mul_f32 v[104:105], v[98:99], v[248:249]
	v_cvt_pk_bf16_f32 v98, v100, v101
	v_cvt_pk_bf16_f32 v99, v102, v103
	v_cvt_pk_bf16_f32 v100, v96, v97
	v_or_b32_e32 v96, 32, v160
	v_mad_i64_i32 v[96:97], s[6:7], v96, s61, v[146:147]
	v_lshl_add_u64 v[96:97], v[96:97], 0, v[148:149]
	v_add_co_u32_e32 v106, vcc, s62, v96
	v_cvt_pk_bf16_f32 v101, v104, v105
	global_store_dwordx4 v[112:113], v[98:101], off offset:256
	s_nop 0
	v_addc_co_u32_e32 v107, vcc, 0, v97, vcc
	s_waitcnt vmcnt(10)
	v_mov_b32_e32 v102, v216
	v_mov_b32_e32 v103, v217
	v_mov_b32_e32 v104, v218
	v_mov_b32_e32 v105, v219
	v_add_u32_e32 v199, 0x133b00, v198
	global_load_dwordx4 v[216:219], v199, s[24:25]
	s_mov_b32 s100, 0xbfb8aa3b
	v_lshlrev_b32_e32 v242, 16, v102
	v_and_b32_e32 v243, 0xffff0000, v102
	v_lshlrev_b32_e32 v244, 16, v104
	v_and_b32_e32 v245, 0xffff0000, v104
	v_lshlrev_b32_e32 v246, 16, v103
	v_and_b32_e32 v247, 0xffff0000, v103
	v_lshlrev_b32_e32 v248, 16, v105
	v_and_b32_e32 v249, 0xffff0000, v105
	v_pk_mul_f32 v[242:243], v[242:243], s[100:101] op_sel_hi:[1,0]
	v_pk_mul_f32 v[244:245], v[244:245], s[100:101] op_sel_hi:[1,0]
	v_pk_mul_f32 v[246:247], v[246:247], s[100:101] op_sel_hi:[1,0]
	v_pk_mul_f32 v[248:249], v[248:249], s[100:101] op_sel_hi:[1,0]
	v_exp_f32_e32 v242, v242
	v_exp_f32_e32 v243, v243
	v_exp_f32_e32 v244, v244
	v_exp_f32_e32 v245, v245
	v_exp_f32_e32 v246, v246
	v_exp_f32_e32 v247, v247
	v_exp_f32_e32 v248, v248
	v_exp_f32_e32 v249, v249
	s_nop 0
	v_pk_add_f32 v[242:243], v[242:243], 1.0 op_sel_hi:[1,0]
	v_pk_add_f32 v[244:245], v[244:245], 1.0 op_sel_hi:[1,0]
	v_pk_add_f32 v[246:247], v[246:247], 1.0 op_sel_hi:[1,0]
	v_pk_add_f32 v[248:249], v[248:249], 1.0 op_sel_hi:[1,0]
	v_rcp_f32_e32 v250, v242
	v_rcp_f32_e32 v251, v243
	s_nop 0
	v_pk_fma_f32 v[252:253], v[242:243], v[250:251], 1.0 op_sel_hi:[1,1,0] neg_lo:[1,0,0] neg_hi:[1,0,0]
	v_pk_fma_f32 v[250:251], v[252:253], v[250:251], v[250:251]
	v_pk_fma_f32 v[252:253], v[242:243], v[250:251], 1.0 op_sel_hi:[1,1,0] neg_lo:[1,0,0] neg_hi:[1,0,0]
	v_pk_fma_f32 v[254:255], v[252:253], v[250:251], v[250:251]
	v_pk_fma_f32 v[252:253], v[242:243], v[254:255], 1.0 op_sel_hi:[1,1,0] neg_lo:[1,0,0] neg_hi:[1,0,0]
	v_pk_fma_f32 v[254:255], v[252:253], v[250:251], v[254:255]
	v_div_fixup_f32 v242, v254, v242, 1.0
	v_div_fixup_f32 v243, v255, v243, 1.0
	v_rcp_f32_e32 v250, v244
	v_rcp_f32_e32 v251, v245
	s_nop 0
	v_pk_fma_f32 v[252:253], v[244:245], v[250:251], 1.0 op_sel_hi:[1,1,0] neg_lo:[1,0,0] neg_hi:[1,0,0]
	v_pk_fma_f32 v[250:251], v[252:253], v[250:251], v[250:251]
	v_pk_fma_f32 v[252:253], v[244:245], v[250:251], 1.0 op_sel_hi:[1,1,0] neg_lo:[1,0,0] neg_hi:[1,0,0]
	v_pk_fma_f32 v[254:255], v[252:253], v[250:251], v[250:251]
	v_pk_fma_f32 v[252:253], v[244:245], v[254:255], 1.0 op_sel_hi:[1,1,0] neg_lo:[1,0,0] neg_hi:[1,0,0]
	v_pk_fma_f32 v[254:255], v[252:253], v[250:251], v[254:255]
	v_div_fixup_f32 v244, v254, v244, 1.0
	v_div_fixup_f32 v245, v255, v245, 1.0
	v_rcp_f32_e32 v250, v246
	v_rcp_f32_e32 v251, v247
	s_nop 0
	v_pk_fma_f32 v[252:253], v[246:247], v[250:251], 1.0 op_sel_hi:[1,1,0] neg_lo:[1,0,0] neg_hi:[1,0,0]
	v_pk_fma_f32 v[250:251], v[252:253], v[250:251], v[250:251]
	v_pk_fma_f32 v[252:253], v[246:247], v[250:251], 1.0 op_sel_hi:[1,1,0] neg_lo:[1,0,0] neg_hi:[1,0,0]
	v_pk_fma_f32 v[254:255], v[252:253], v[250:251], v[250:251]
	v_pk_fma_f32 v[252:253], v[246:247], v[254:255], 1.0 op_sel_hi:[1,1,0] neg_lo:[1,0,0] neg_hi:[1,0,0]
	v_pk_fma_f32 v[254:255], v[252:253], v[250:251], v[254:255]
	v_div_fixup_f32 v246, v254, v246, 1.0
	v_div_fixup_f32 v247, v255, v247, 1.0
	v_rcp_f32_e32 v250, v248
	v_rcp_f32_e32 v251, v249
	s_nop 0
	v_pk_fma_f32 v[252:253], v[248:249], v[250:251], 1.0 op_sel_hi:[1,1,0] neg_lo:[1,0,0] neg_hi:[1,0,0]
	v_pk_fma_f32 v[250:251], v[252:253], v[250:251], v[250:251]
	v_pk_fma_f32 v[252:253], v[248:249], v[250:251], 1.0 op_sel_hi:[1,1,0] neg_lo:[1,0,0] neg_hi:[1,0,0]
	v_pk_fma_f32 v[254:255], v[252:253], v[250:251], v[250:251]
	v_pk_fma_f32 v[252:253], v[248:249], v[254:255], 1.0 op_sel_hi:[1,1,0] neg_lo:[1,0,0] neg_hi:[1,0,0]
	v_pk_fma_f32 v[254:255], v[252:253], v[250:251], v[254:255]
	v_div_fixup_f32 v248, v254, v248, 1.0
	v_div_fixup_f32 v249, v255, v249, 1.0
	v_mul_f32_e32 v92, v92, v242
	v_mul_f32_e32 v98, v88, v244
	v_mul_f32_e32 v88, v93, v243
	v_mul_f32_e32 v93, v89, v245
	v_mul_f32_e32 v89, v94, v246
	v_mul_f32_e32 v94, v90, v248
	v_mul_f32_e32 v90, v95, v247
	v_mul_f32_e32 v91, v91, v249
	v_cvt_pk_bf16_f32 v88, v92, v88
	v_cvt_pk_bf16_f32 v89, v89, v90
	v_cvt_pk_bf16_f32 v90, v98, v93
	v_cvt_pk_bf16_f32 v91, v94, v91
	s_waitcnt vmcnt(10)
; __device__ __forceinline__ float sigmoidf_(float x) { return 1.0f / (1.0f + __expf(-x)); }
; __device__ __forceinline__ u32x4 pack8(const f32x4 v0, const f32x4 v1) { u32x4 w; w.x = pk2(v0[0], v0[1]); w.y = pk2(v0[2], v0[3]); w.z = pk2(v1[0], v1[1]); w.w = pk2(v1[2], v1[3]); return w; }
; __device__ __forceinline__ void unpack8(const u32x4 w, f32x4& v0, f32x4& v1) { v0 = (f32x4){bflo(w.x), bfhi(w.x), bflo(w.y), bfhi(w.y)}; v1 = (f32x4){bflo(w.z), bfhi(w.z), bflo(w.w), bfhi(w.w)}; }
;     __device__ __forceinline__ void operator()(const f32x4 (&acc)[2][2][4][2], const Unit& u, int wr, int wc, int fr, int fq) const {
;     ...
;         for (int ai = 0; ai < 2; ++ai)
; #pragma unroll
;             for (int m = 0; m < 4; ++m) {
;                 bf16_t* rowp = z + (size_t)(row0 + ai * 128 + m * 16) * DIN + col0;
; #pragma unroll
;                 for (int bj = 0; bj < 2; ++bj) {
;                     const u32x4 gw = *(const u32x4*)(rowp + (MODE == 0 ? O_GB : O_GA) + bj * 128);
;                     f32x4 g0, g1; unpack8(gw, g0, g1);
;                     f32x4 v0, v1;
; #pragma unroll
;                     for (int j = 0; j < 4; ++j) { v0[j] = sigmoidf_(g0[j]) * acc[ai][bj][m][0][j]; v1[j] = sigmoidf_(g1[j]) * acc[ai][bj][m][1][j]; }
;                     if (MODE == 1) { const u32x4 mw = *(const u32x4*)(rowp + bj * 128); f32x4 m0, m1; unpack8(mw, m0, m1); v0 += m0; v1 += m1; }
;                     *(u32x4*)(rowp + bj * 128) = pack8(v0, v1); }
	v_mov_b32_e32 v92, v232
	v_mov_b32_e32 v93, v233
	v_mov_b32_e32 v94, v234
	v_mov_b32_e32 v95, v235
	v_add_u32_e32 v199, 0x155a00, v198
	global_load_dwordx4 v[232:235], v199, s[24:25]
	s_mov_b32 s100, 0xbfb8aa3b
	v_lshlrev_b32_e32 v242, 16, v92
	v_and_b32_e32 v243, 0xffff0000, v92
	v_lshlrev_b32_e32 v244, 16, v94
	v_and_b32_e32 v245, 0xffff0000, v94
	v_lshlrev_b32_e32 v246, 16, v93
	v_and_b32_e32 v247, 0xffff0000, v93
	v_lshlrev_b32_e32 v248, 16, v95
	v_and_b32_e32 v249, 0xffff0000, v95
	v_pk_mul_f32 v[242:243], v[242:243], s[100:101] op_sel_hi:[1,0]
	v_pk_mul_f32 v[244:245], v[244:245], s[100:101] op_sel_hi:[1,0]
	v_pk_mul_f32 v[246:247], v[246:247], s[100:101] op_sel_hi:[1,0]
	v_pk_mul_f32 v[248:249], v[248:249], s[100:101] op_sel_hi:[1,0]
	v_exp_f32_e32 v242, v242
	v_exp_f32_e32 v243, v243
	v_exp_f32_e32 v244, v244
	v_exp_f32_e32 v245, v245
	v_exp_f32_e32 v246, v246
	v_exp_f32_e32 v247, v247
	v_exp_f32_e32 v248, v248
	v_exp_f32_e32 v249, v249
	s_nop 0
	v_pk_add_f32 v[242:243], v[242:243], 1.0 op_sel_hi:[1,0]
	v_pk_add_f32 v[244:245], v[244:245], 1.0 op_sel_hi:[1,0]
	v_pk_add_f32 v[246:247], v[246:247], 1.0 op_sel_hi:[1,0]
	v_pk_add_f32 v[248:249], v[248:249], 1.0 op_sel_hi:[1,0]
	v_rcp_f32_e32 v250, v242
	v_rcp_f32_e32 v251, v243
	s_nop 0
	v_pk_fma_f32 v[252:253], v[242:243], v[250:251], 1.0 op_sel_hi:[1,1,0] neg_lo:[1,0,0] neg_hi:[1,0,0]
	v_pk_fma_f32 v[250:251], v[252:253], v[250:251], v[250:251]
	v_pk_fma_f32 v[252:253], v[242:243], v[250:251], 1.0 op_sel_hi:[1,1,0] neg_lo:[1,0,0] neg_hi:[1,0,0]
	v_pk_fma_f32 v[254:255], v[252:253], v[250:251], v[250:251]
	v_pk_fma_f32 v[252:253], v[242:243], v[254:255], 1.0 op_sel_hi:[1,1,0] neg_lo:[1,0,0] neg_hi:[1,0,0]
	v_pk_fma_f32 v[254:255], v[252:253], v[250:251], v[254:255]
	v_div_fixup_f32 v242, v254, v242, 1.0
	v_div_fixup_f32 v243, v255, v243, 1.0
	v_rcp_f32_e32 v250, v244
	v_rcp_f32_e32 v251, v245
	s_nop 0
	v_pk_fma_f32 v[252:253], v[244:245], v[250:251], 1.0 op_sel_hi:[1,1,0] neg_lo:[1,0,0] neg_hi:[1,0,0]
	v_pk_fma_f32 v[250:251], v[252:253], v[250:251], v[250:251]
	v_pk_fma_f32 v[252:253], v[244:245], v[250:251], 1.0 op_sel_hi:[1,1,0] neg_lo:[1,0,0] neg_hi:[1,0,0]
	v_pk_fma_f32 v[254:255], v[252:253], v[250:251], v[250:251]
	v_pk_fma_f32 v[252:253], v[244:245], v[254:255], 1.0 op_sel_hi:[1,1,0] neg_lo:[1,0,0] neg_hi:[1,0,0]
	v_pk_fma_f32 v[254:255], v[252:253], v[250:251], v[254:255]
	v_div_fixup_f32 v244, v254, v244, 1.0
	v_div_fixup_f32 v245, v255, v245, 1.0
	v_rcp_f32_e32 v250, v246
	v_rcp_f32_e32 v251, v247
	s_nop 0
	v_pk_fma_f32 v[252:253], v[246:247], v[250:251], 1.0 op_sel_hi:[1,1,0] neg_lo:[1,0,0] neg_hi:[1,0,0]
	v_pk_fma_f32 v[250:251], v[252:253], v[250:251], v[250:251]
	v_pk_fma_f32 v[252:253], v[246:247], v[250:251], 1.0 op_sel_hi:[1,1,0] neg_lo:[1,0,0] neg_hi:[1,0,0]
	v_pk_fma_f32 v[254:255], v[252:253], v[250:251], v[250:251]
	v_pk_fma_f32 v[252:253], v[246:247], v[254:255], 1.0 op_sel_hi:[1,1,0] neg_lo:[1,0,0] neg_hi:[1,0,0]
	v_pk_fma_f32 v[254:255], v[252:253], v[250:251], v[254:255]
	v_div_fixup_f32 v246, v254, v246, 1.0
	v_div_fixup_f32 v247, v255, v247, 1.0
	v_rcp_f32_e32 v250, v248
	v_rcp_f32_e32 v251, v249
	s_nop 0
	v_pk_fma_f32 v[252:253], v[248:249], v[250:251], 1.0 op_sel_hi:[1,1,0] neg_lo:[1,0,0] neg_hi:[1,0,0]
	v_pk_fma_f32 v[250:251], v[252:253], v[250:251], v[250:251]
	v_pk_fma_f32 v[252:253], v[248:249], v[250:251], 1.0 op_sel_hi:[1,1,0] neg_lo:[1,0,0] neg_hi:[1,0,0]
	v_pk_fma_f32 v[254:255], v[252:253], v[250:251], v[250:251]
	v_pk_fma_f32 v[252:253], v[248:249], v[254:255], 1.0 op_sel_hi:[1,1,0] neg_lo:[1,0,0] neg_hi:[1,0,0]
	v_pk_fma_f32 v[254:255], v[252:253], v[250:251], v[254:255]
	v_div_fixup_f32 v248, v254, v248, 1.0
	v_div_fixup_f32 v249, v255, v249, 1.0
	global_store_dwordx4 v[96:97], v[88:91], off
	s_nop 0
	v_pk_mul_f32 v[84:85], v[84:85], v[242:243]
	v_pk_mul_f32 v[80:81], v[80:81], v[244:245]
	v_pk_mul_f32 v[86:87], v[86:87], v[246:247]
	v_pk_mul_f32 v[88:89], v[82:83], v[248:249]
	v_cvt_pk_bf16_f32 v82, v84, v85
	v_cvt_pk_bf16_f32 v83, v86, v87
	v_cvt_pk_bf16_f32 v84, v80, v81
	v_or_b32_e32 v80, 48, v160
	v_mad_i64_i32 v[80:81], s[6:7], v80, s61, v[146:147]
	v_lshl_add_u64 v[80:81], v[80:81], 0, v[148:149]
	v_add_co_u32_e32 v90, vcc, s62, v80
	v_cvt_pk_bf16_f32 v85, v88, v89
	global_store_dwordx4 v[96:97], v[82:85], off offset:256
	s_nop 0
	v_addc_co_u32_e32 v91, vcc, 0, v81, vcc
	s_waitcnt vmcnt(12)
; __device__ __forceinline__ float sigmoidf_(float x) { return 1.0f / (1.0f + __expf(-x)); }
; __device__ __forceinline__ u32x4 pack8(const f32x4 v0, const f32x4 v1) { u32x4 w; w.x = pk2(v0[0], v0[1]); w.y = pk2(v0[2], v0[3]); w.z = pk2(v1[0], v1[1]); w.w = pk2(v1[2], v1[3]); return w; }
; __device__ __forceinline__ void unpack8(const u32x4 w, f32x4& v0, f32x4& v1) { v0 = (f32x4){bflo(w.x), bfhi(w.x), bflo(w.y), bfhi(w.y)}; v1 = (f32x4){bflo(w.z), bfhi(w.z), bflo(w.w), bfhi(w.w)}; }
;     __device__ __forceinline__ void operator()(const f32x4 (&acc)[2][2][4][2], const Unit& u, int wr, int wc, int fr, int fq) const {
;     ...
;         for (int ai = 0; ai < 2; ++ai)
; #pragma unroll
;             for (int m = 0; m < 4; ++m) {
;                 bf16_t* rowp = z + (size_t)(row0 + ai * 128 + m * 16) * DIN + col0;
; #pragma unroll
;                 for (int bj = 0; bj < 2; ++bj) {
;                     const u32x4 gw = *(const u32x4*)(rowp + (MODE == 0 ? O_GB : O_GA) + bj * 128);
;                     f32x4 g0, g1; unpack8(gw, g0, g1);
;                     f32x4 v0, v1;
; #pragma unroll
;                     for (int j = 0; j < 4; ++j) { v0[j] = sigmoidf_(g0[j]) * acc[ai][bj][m][0][j]; v1[j] = sigmoidf_(g1[j]) * acc[ai][bj][m][1][j]; }
;                     if (MODE == 1) { const u32x4 mw = *(const u32x4*)(rowp + bj * 128); f32x4 m0, m1; unpack8(mw, m0, m1); v0 += m0; v1 += m1; }
;                     *(u32x4*)(rowp + bj * 128) = pack8(v0, v1); }
	v_mov_b32_e32 v86, v236
	v_mov_b32_e32 v87, v237
	v_mov_b32_e32 v88, v238
	v_mov_b32_e32 v89, v239
	v_add_u32_e32 v199, 0x155b00, v198
	global_load_dwordx4 v[236:239], v199, s[24:25]
	s_mov_b32 s100, 0xbfb8aa3b
	v_lshlrev_b32_e32 v242, 16, v86
	v_and_b32_e32 v243, 0xffff0000, v86
	v_lshlrev_b32_e32 v244, 16, v88
	v_and_b32_e32 v245, 0xffff0000, v88
	v_lshlrev_b32_e32 v246, 16, v87
	v_and_b32_e32 v247, 0xffff0000, v87
	v_lshlrev_b32_e32 v248, 16, v89
	v_and_b32_e32 v249, 0xffff0000, v89
	v_pk_mul_f32 v[242:243], v[242:243], s[100:101] op_sel_hi:[1,0]
	v_pk_mul_f32 v[244:245], v[244:245], s[100:101] op_sel_hi:[1,0]
	v_pk_mul_f32 v[246:247], v[246:247], s[100:101] op_sel_hi:[1,0]
	v_pk_mul_f32 v[248:249], v[248:249], s[100:101] op_sel_hi:[1,0]
	v_exp_f32_e32 v242, v242
	v_exp_f32_e32 v243, v243
	v_exp_f32_e32 v244, v244
	v_exp_f32_e32 v245, v245
	v_exp_f32_e32 v246, v246
	v_exp_f32_e32 v247, v247
	v_exp_f32_e32 v248, v248
	v_exp_f32_e32 v249, v249
	s_nop 0
	v_pk_add_f32 v[242:243], v[242:243], 1.0 op_sel_hi:[1,0]
	v_pk_add_f32 v[244:245], v[244:245], 1.0 op_sel_hi:[1,0]
	v_pk_add_f32 v[246:247], v[246:247], 1.0 op_sel_hi:[1,0]
	v_pk_add_f32 v[248:249], v[248:249], 1.0 op_sel_hi:[1,0]
	v_rcp_f32_e32 v250, v242
	v_rcp_f32_e32 v251, v243
	s_nop 0
	v_pk_fma_f32 v[252:253], v[242:243], v[250:251], 1.0 op_sel_hi:[1,1,0] neg_lo:[1,0,0] neg_hi:[1,0,0]
	v_pk_fma_f32 v[250:251], v[252:253], v[250:251], v[250:251]
	v_pk_fma_f32 v[252:253], v[242:243], v[250:251], 1.0 op_sel_hi:[1,1,0] neg_lo:[1,0,0] neg_hi:[1,0,0]
	v_pk_fma_f32 v[254:255], v[252:253], v[250:251], v[250:251]
	v_pk_fma_f32 v[252:253], v[242:243], v[254:255], 1.0 op_sel_hi:[1,1,0] neg_lo:[1,0,0] neg_hi:[1,0,0]
	v_pk_fma_f32 v[254:255], v[252:253], v[250:251], v[254:255]
	v_div_fixup_f32 v242, v254, v242, 1.0
	v_div_fixup_f32 v243, v255, v243, 1.0
	v_rcp_f32_e32 v250, v244
	v_rcp_f32_e32 v251, v245
	s_nop 0
	v_pk_fma_f32 v[252:253], v[244:245], v[250:251], 1.0 op_sel_hi:[1,1,0] neg_lo:[1,0,0] neg_hi:[1,0,0]
	v_pk_fma_f32 v[250:251], v[252:253], v[250:251], v[250:251]
	v_pk_fma_f32 v[252:253], v[244:245], v[250:251], 1.0 op_sel_hi:[1,1,0] neg_lo:[1,0,0] neg_hi:[1,0,0]
	v_pk_fma_f32 v[254:255], v[252:253], v[250:251], v[250:251]
	v_pk_fma_f32 v[252:253], v[244:245], v[254:255], 1.0 op_sel_hi:[1,1,0] neg_lo:[1,0,0] neg_hi:[1,0,0]
	v_pk_fma_f32 v[254:255], v[252:253], v[250:251], v[254:255]
	v_div_fixup_f32 v244, v254, v244, 1.0
	v_div_fixup_f32 v245, v255, v245, 1.0
	v_rcp_f32_e32 v250, v246
	v_rcp_f32_e32 v251, v247
	s_nop 0
	v_pk_fma_f32 v[252:253], v[246:247], v[250:251], 1.0 op_sel_hi:[1,1,0] neg_lo:[1,0,0] neg_hi:[1,0,0]
	v_pk_fma_f32 v[250:251], v[252:253], v[250:251], v[250:251]
	v_pk_fma_f32 v[252:253], v[246:247], v[250:251], 1.0 op_sel_hi:[1,1,0] neg_lo:[1,0,0] neg_hi:[1,0,0]
	v_pk_fma_f32 v[254:255], v[252:253], v[250:251], v[250:251]
	v_pk_fma_f32 v[252:253], v[246:247], v[254:255], 1.0 op_sel_hi:[1,1,0] neg_lo:[1,0,0] neg_hi:[1,0,0]
	v_pk_fma_f32 v[254:255], v[252:253], v[250:251], v[254:255]
	v_div_fixup_f32 v246, v254, v246, 1.0
	v_div_fixup_f32 v247, v255, v247, 1.0
	v_rcp_f32_e32 v250, v248
	v_rcp_f32_e32 v251, v249
	s_nop 0
	v_pk_fma_f32 v[252:253], v[248:249], v[250:251], 1.0 op_sel_hi:[1,1,0] neg_lo:[1,0,0] neg_hi:[1,0,0]
	v_pk_fma_f32 v[250:251], v[252:253], v[250:251], v[250:251]
	v_pk_fma_f32 v[252:253], v[248:249], v[250:251], 1.0 op_sel_hi:[1,1,0] neg_lo:[1,0,0] neg_hi:[1,0,0]
	v_pk_fma_f32 v[254:255], v[252:253], v[250:251], v[250:251]
	v_pk_fma_f32 v[252:253], v[248:249], v[254:255], 1.0 op_sel_hi:[1,1,0] neg_lo:[1,0,0] neg_hi:[1,0,0]
	v_pk_fma_f32 v[254:255], v[252:253], v[250:251], v[254:255]
	v_div_fixup_f32 v248, v254, v248, 1.0
	v_div_fixup_f32 v249, v255, v249, 1.0
	v_mul_f32_e32 v76, v76, v242
	v_mul_f32_e32 v82, v72, v244
	v_mul_f32_e32 v72, v77, v243
	v_mul_f32_e32 v77, v73, v245
	v_mul_f32_e32 v73, v78, v246
	v_mul_f32_e32 v78, v74, v248
	v_mul_f32_e32 v74, v79, v247
	v_mul_f32_e32 v75, v75, v249
	v_cvt_pk_bf16_f32 v72, v76, v72
	v_cvt_pk_bf16_f32 v73, v73, v74
	v_cvt_pk_bf16_f32 v74, v82, v77
	v_cvt_pk_bf16_f32 v75, v78, v75
	s_waitcnt vmcnt(12)
	v_mov_b32_e32 v76, v200
	v_mov_b32_e32 v77, v201
	v_mov_b32_e32 v78, v202
	v_mov_b32_e32 v79, v203
	v_add_u32_e32 v199, 0x177a00, v198
	global_load_dwordx4 v[200:203], v199, s[24:25]
	s_mov_b32 s100, 0xbfb8aa3b
	v_lshlrev_b32_e32 v242, 16, v76
	v_and_b32_e32 v243, 0xffff0000, v76
	v_lshlrev_b32_e32 v244, 16, v78
	v_and_b32_e32 v245, 0xffff0000, v78
	v_lshlrev_b32_e32 v246, 16, v77
	v_and_b32_e32 v247, 0xffff0000, v77
	v_lshlrev_b32_e32 v248, 16, v79
	v_and_b32_e32 v249, 0xffff0000, v79
	v_pk_mul_f32 v[242:243], v[242:243], s[100:101] op_sel_hi:[1,0]
	v_pk_mul_f32 v[244:245], v[244:245], s[100:101] op_sel_hi:[1,0]
	v_pk_mul_f32 v[246:247], v[246:247], s[100:101] op_sel_hi:[1,0]
	v_pk_mul_f32 v[248:249], v[248:249], s[100:101] op_sel_hi:[1,0]
	v_exp_f32_e32 v242, v242
	v_exp_f32_e32 v243, v243
	v_exp_f32_e32 v244, v244
	v_exp_f32_e32 v245, v245
	v_exp_f32_e32 v246, v246
	v_exp_f32_e32 v247, v247
	v_exp_f32_e32 v248, v248
	v_exp_f32_e32 v249, v249
	s_nop 0
	v_pk_add_f32 v[242:243], v[242:243], 1.0 op_sel_hi:[1,0]
	v_pk_add_f32 v[244:245], v[244:245], 1.0 op_sel_hi:[1,0]
	v_pk_add_f32 v[246:247], v[246:247], 1.0 op_sel_hi:[1,0]
	v_pk_add_f32 v[248:249], v[248:249], 1.0 op_sel_hi:[1,0]
	v_rcp_f32_e32 v250, v242
	v_rcp_f32_e32 v251, v243
	s_nop 0
	v_pk_fma_f32 v[252:253], v[242:243], v[250:251], 1.0 op_sel_hi:[1,1,0] neg_lo:[1,0,0] neg_hi:[1,0,0]
	v_pk_fma_f32 v[250:251], v[252:253], v[250:251], v[250:251]
	v_pk_fma_f32 v[252:253], v[242:243], v[250:251], 1.0 op_sel_hi:[1,1,0] neg_lo:[1,0,0] neg_hi:[1,0,0]
; __device__ __forceinline__ float sigmoidf_(float x) { return 1.0f / (1.0f + __expf(-x)); }
; __device__ __forceinline__ u32x4 pack8(const f32x4 v0, const f32x4 v1) { u32x4 w; w.x = pk2(v0[0], v0[1]); w.y = pk2(v0[2], v0[3]); w.z = pk2(v1[0], v1[1]); w.w = pk2(v1[2], v1[3]); return w; }
; __device__ __forceinline__ void unpack8(const u32x4 w, f32x4& v0, f32x4& v1) { v0 = (f32x4){bflo(w.x), bfhi(w.x), bflo(w.y), bfhi(w.y)}; v1 = (f32x4){bflo(w.z), bfhi(w.z), bflo(w.w), bfhi(w.w)}; }
;     __device__ __forceinline__ void operator()(const f32x4 (&acc)[2][2][4][2], const Unit& u, int wr, int wc, int fr, int fq) const {
;     ...
;         for (int ai = 0; ai < 2; ++ai)
; #pragma unroll
;             for (int m = 0; m < 4; ++m) {
;                 bf16_t* rowp = z + (size_t)(row0 + ai * 128 + m * 16) * DIN + col0;
; #pragma unroll
;                 for (int bj = 0; bj < 2; ++bj) {
;                     const u32x4 gw = *(const u32x4*)(rowp + (MODE == 0 ? O_GB : O_GA) + bj * 128);
;                     f32x4 g0, g1; unpack8(gw, g0, g1);
;                     f32x4 v0, v1;
; #pragma unroll
;                     for (int j = 0; j < 4; ++j) { v0[j] = sigmoidf_(g0[j]) * acc[ai][bj][m][0][j]; v1[j] = sigmoidf_(g1[j]) * acc[ai][bj][m][1][j]; }
;                     if (MODE == 1) { const u32x4 mw = *(const u32x4*)(rowp + bj * 128); f32x4 m0, m1; unpack8(mw, m0, m1); v0 += m0; v1 += m1; }
;                     *(u32x4*)(rowp + bj * 128) = pack8(v0, v1); }
	v_pk_fma_f32 v[254:255], v[252:253], v[250:251], v[250:251]
	v_pk_fma_f32 v[252:253], v[242:243], v[254:255], 1.0 op_sel_hi:[1,1,0] neg_lo:[1,0,0] neg_hi:[1,0,0]
	v_pk_fma_f32 v[254:255], v[252:253], v[250:251], v[254:255]
	v_div_fixup_f32 v242, v254, v242, 1.0
	v_div_fixup_f32 v243, v255, v243, 1.0
	v_rcp_f32_e32 v250, v244
	v_rcp_f32_e32 v251, v245
	s_nop 0
	v_pk_fma_f32 v[252:253], v[244:245], v[250:251], 1.0 op_sel_hi:[1,1,0] neg_lo:[1,0,0] neg_hi:[1,0,0]
	v_pk_fma_f32 v[250:251], v[252:253], v[250:251], v[250:251]
	v_pk_fma_f32 v[252:253], v[244:245], v[250:251], 1.0 op_sel_hi:[1,1,0] neg_lo:[1,0,0] neg_hi:[1,0,0]
	v_pk_fma_f32 v[254:255], v[252:253], v[250:251], v[250:251]
	v_pk_fma_f32 v[252:253], v[244:245], v[254:255], 1.0 op_sel_hi:[1,1,0] neg_lo:[1,0,0] neg_hi:[1,0,0]
	v_pk_fma_f32 v[254:255], v[252:253], v[250:251], v[254:255]
	v_div_fixup_f32 v244, v254, v244, 1.0
	v_div_fixup_f32 v245, v255, v245, 1.0
	v_rcp_f32_e32 v250, v246
	v_rcp_f32_e32 v251, v247
	s_nop 0
	v_pk_fma_f32 v[252:253], v[246:247], v[250:251], 1.0 op_sel_hi:[1,1,0] neg_lo:[1,0,0] neg_hi:[1,0,0]
	v_pk_fma_f32 v[250:251], v[252:253], v[250:251], v[250:251]
	v_pk_fma_f32 v[252:253], v[246:247], v[250:251], 1.0 op_sel_hi:[1,1,0] neg_lo:[1,0,0] neg_hi:[1,0,0]
	v_pk_fma_f32 v[254:255], v[252:253], v[250:251], v[250:251]
	v_pk_fma_f32 v[252:253], v[246:247], v[254:255], 1.0 op_sel_hi:[1,1,0] neg_lo:[1,0,0] neg_hi:[1,0,0]
	v_pk_fma_f32 v[254:255], v[252:253], v[250:251], v[254:255]
	v_div_fixup_f32 v246, v254, v246, 1.0
	v_div_fixup_f32 v247, v255, v247, 1.0
	v_rcp_f32_e32 v250, v248
	v_rcp_f32_e32 v251, v249
	s_nop 0
	v_pk_fma_f32 v[252:253], v[248:249], v[250:251], 1.0 op_sel_hi:[1,1,0] neg_lo:[1,0,0] neg_hi:[1,0,0]
	v_pk_fma_f32 v[250:251], v[252:253], v[250:251], v[250:251]
	v_pk_fma_f32 v[252:253], v[248:249], v[250:251], 1.0 op_sel_hi:[1,1,0] neg_lo:[1,0,0] neg_hi:[1,0,0]
	v_pk_fma_f32 v[254:255], v[252:253], v[250:251], v[250:251]
	v_pk_fma_f32 v[252:253], v[248:249], v[254:255], 1.0 op_sel_hi:[1,1,0] neg_lo:[1,0,0] neg_hi:[1,0,0]
	v_pk_fma_f32 v[254:255], v[252:253], v[250:251], v[254:255]
	v_div_fixup_f32 v248, v254, v248, 1.0
	v_div_fixup_f32 v249, v255, v249, 1.0
	global_store_dwordx4 v[80:81], v[72:75], off
	s_nop 0
	v_pk_mul_f32 v[68:69], v[68:69], v[242:243]
	v_pk_mul_f32 v[64:65], v[64:65], v[244:245]
	v_pk_mul_f32 v[70:71], v[70:71], v[246:247]
	v_pk_mul_f32 v[72:73], v[66:67], v[248:249]
	v_cvt_pk_bf16_f32 v66, v68, v69
	v_cvt_pk_bf16_f32 v67, v70, v71
	v_cvt_pk_bf16_f32 v68, v64, v65
	v_add_u32_e32 v64, 0x80, v160
	v_mad_i64_i32 v[64:65], s[6:7], v64, s61, v[146:147]
	v_lshl_add_u64 v[64:65], v[64:65], 0, v[148:149]
	v_add_co_u32_e32 v74, vcc, s62, v64
	v_cvt_pk_bf16_f32 v69, v72, v73
	global_store_dwordx4 v[80:81], v[66:69], off offset:256
	s_nop 0
	v_addc_co_u32_e32 v75, vcc, 0, v65, vcc
	s_waitcnt vmcnt(13)
	v_mov_b32_e32 v70, v204
	v_mov_b32_e32 v71, v205
	v_mov_b32_e32 v72, v206
	v_mov_b32_e32 v73, v207
	v_add_u32_e32 v199, 0x177b00, v198
	global_load_dwordx4 v[204:207], v199, s[24:25]
	s_mov_b32 s100, 0xbfb8aa3b
	v_lshlrev_b32_e32 v242, 16, v70
	v_and_b32_e32 v243, 0xffff0000, v70
	v_lshlrev_b32_e32 v244, 16, v72
	v_and_b32_e32 v245, 0xffff0000, v72
	v_lshlrev_b32_e32 v246, 16, v71
	v_and_b32_e32 v247, 0xffff0000, v71
	v_lshlrev_b32_e32 v248, 16, v73
	v_and_b32_e32 v249, 0xffff0000, v73
	v_pk_mul_f32 v[242:243], v[242:243], s[100:101] op_sel_hi:[1,0]
	v_pk_mul_f32 v[244:245], v[244:245], s[100:101] op_sel_hi:[1,0]
	v_pk_mul_f32 v[246:247], v[246:247], s[100:101] op_sel_hi:[1,0]
	v_pk_mul_f32 v[248:249], v[248:249], s[100:101] op_sel_hi:[1,0]
	v_exp_f32_e32 v242, v242
	v_exp_f32_e32 v243, v243
	v_exp_f32_e32 v244, v244
	v_exp_f32_e32 v245, v245
	v_exp_f32_e32 v246, v246
	v_exp_f32_e32 v247, v247
	v_exp_f32_e32 v248, v248
	v_exp_f32_e32 v249, v249
	s_nop 0
	v_pk_add_f32 v[242:243], v[242:243], 1.0 op_sel_hi:[1,0]
	v_pk_add_f32 v[244:245], v[244:245], 1.0 op_sel_hi:[1,0]
	v_pk_add_f32 v[246:247], v[246:247], 1.0 op_sel_hi:[1,0]
	v_pk_add_f32 v[248:249], v[248:249], 1.0 op_sel_hi:[1,0]
	v_rcp_f32_e32 v250, v242
	v_rcp_f32_e32 v251, v243
	s_nop 0
	v_pk_fma_f32 v[252:253], v[242:243], v[250:251], 1.0 op_sel_hi:[1,1,0] neg_lo:[1,0,0] neg_hi:[1,0,0]
	v_pk_fma_f32 v[250:251], v[252:253], v[250:251], v[250:251]
	v_pk_fma_f32 v[252:253], v[242:243], v[250:251], 1.0 op_sel_hi:[1,1,0] neg_lo:[1,0,0] neg_hi:[1,0,0]
	v_pk_fma_f32 v[254:255], v[252:253], v[250:251], v[250:251]
	v_pk_fma_f32 v[252:253], v[242:243], v[254:255], 1.0 op_sel_hi:[1,1,0] neg_lo:[1,0,0] neg_hi:[1,0,0]
	v_pk_fma_f32 v[254:255], v[252:253], v[250:251], v[254:255]
	v_div_fixup_f32 v242, v254, v242, 1.0
	v_div_fixup_f32 v243, v255, v243, 1.0
	v_rcp_f32_e32 v250, v244
	v_rcp_f32_e32 v251, v245
	s_nop 0
	v_pk_fma_f32 v[252:253], v[244:245], v[250:251], 1.0 op_sel_hi:[1,1,0] neg_lo:[1,0,0] neg_hi:[1,0,0]
	v_pk_fma_f32 v[250:251], v[252:253], v[250:251], v[250:251]
	v_pk_fma_f32 v[252:253], v[244:245], v[250:251], 1.0 op_sel_hi:[1,1,0] neg_lo:[1,0,0] neg_hi:[1,0,0]
	v_pk_fma_f32 v[254:255], v[252:253], v[250:251], v[250:251]
	v_pk_fma_f32 v[252:253], v[244:245], v[254:255], 1.0 op_sel_hi:[1,1,0] neg_lo:[1,0,0] neg_hi:[1,0,0]
	v_pk_fma_f32 v[254:255], v[252:253], v[250:251], v[254:255]
	v_div_fixup_f32 v244, v254, v244, 1.0
	v_div_fixup_f32 v245, v255, v245, 1.0
	v_rcp_f32_e32 v250, v246
	v_rcp_f32_e32 v251, v247
	s_nop 0
	v_pk_fma_f32 v[252:253], v[246:247], v[250:251], 1.0 op_sel_hi:[1,1,0] neg_lo:[1,0,0] neg_hi:[1,0,0]
	v_pk_fma_f32 v[250:251], v[252:253], v[250:251], v[250:251]
	v_pk_fma_f32 v[252:253], v[246:247], v[250:251], 1.0 op_sel_hi:[1,1,0] neg_lo:[1,0,0] neg_hi:[1,0,0]
	v_pk_fma_f32 v[254:255], v[252:253], v[250:251], v[250:251]
	v_pk_fma_f32 v[252:253], v[246:247], v[254:255], 1.0 op_sel_hi:[1,1,0] neg_lo:[1,0,0] neg_hi:[1,0,0]
	v_pk_fma_f32 v[254:255], v[252:253], v[250:251], v[254:255]
	v_div_fixup_f32 v246, v254, v246, 1.0
	v_div_fixup_f32 v247, v255, v247, 1.0
	v_rcp_f32_e32 v250, v248
	v_rcp_f32_e32 v251, v249
	s_nop 0
	v_pk_fma_f32 v[252:253], v[248:249], v[250:251], 1.0 op_sel_hi:[1,1,0] neg_lo:[1,0,0] neg_hi:[1,0,0]
	v_pk_fma_f32 v[250:251], v[252:253], v[250:251], v[250:251]
	v_pk_fma_f32 v[252:253], v[248:249], v[250:251], 1.0 op_sel_hi:[1,1,0] neg_lo:[1,0,0] neg_hi:[1,0,0]
	v_pk_fma_f32 v[254:255], v[252:253], v[250:251], v[250:251]
	v_pk_fma_f32 v[252:253], v[248:249], v[254:255], 1.0 op_sel_hi:[1,1,0] neg_lo:[1,0,0] neg_hi:[1,0,0]
	v_pk_fma_f32 v[254:255], v[252:253], v[250:251], v[254:255]
	v_div_fixup_f32 v248, v254, v248, 1.0
	v_div_fixup_f32 v249, v255, v249, 1.0
	v_mul_f32_e32 v60, v60, v242
	v_mul_f32_e32 v66, v56, v244
	v_mul_f32_e32 v56, v61, v243
	v_mul_f32_e32 v61, v57, v245
	v_mul_f32_e32 v57, v62, v246
	v_mul_f32_e32 v62, v58, v248
	v_mul_f32_e32 v58, v63, v247
	v_mul_f32_e32 v59, v59, v249
	v_cvt_pk_bf16_f32 v56, v60, v56
	v_cvt_pk_bf16_f32 v57, v57, v58
	v_cvt_pk_bf16_f32 v58, v66, v61
	v_cvt_pk_bf16_f32 v59, v62, v59
	s_waitcnt vmcnt(12)
; __device__ __forceinline__ float sigmoidf_(float x) { return 1.0f / (1.0f + __expf(-x)); }
; __device__ __forceinline__ u32x4 pack8(const f32x4 v0, const f32x4 v1) { u32x4 w; w.x = pk2(v0[0], v0[1]); w.y = pk2(v0[2], v0[3]); w.z = pk2(v1[0], v1[1]); w.w = pk2(v1[2], v1[3]); return w; }
; __device__ __forceinline__ void unpack8(const u32x4 w, f32x4& v0, f32x4& v1) { v0 = (f32x4){bflo(w.x), bfhi(w.x), bflo(w.y), bfhi(w.y)}; v1 = (f32x4){bflo(w.z), bfhi(w.z), bflo(w.w), bfhi(w.w)}; }
;     __device__ __forceinline__ void operator()(const f32x4 (&acc)[2][2][4][2], const Unit& u, int wr, int wc, int fr, int fq) const {
;     ...
;         for (int ai = 0; ai < 2; ++ai)
; #pragma unroll
;             for (int m = 0; m < 4; ++m) {
;                 bf16_t* rowp = z + (size_t)(row0 + ai * 128 + m * 16) * DIN + col0;
; #pragma unroll
;                 for (int bj = 0; bj < 2; ++bj) {
;                     const u32x4 gw = *(const u32x4*)(rowp + (MODE == 0 ? O_GB : O_GA) + bj * 128);
;                     f32x4 g0, g1; unpack8(gw, g0, g1);
;                     f32x4 v0, v1;
; #pragma unroll
;                     for (int j = 0; j < 4; ++j) { v0[j] = sigmoidf_(g0[j]) * acc[ai][bj][m][0][j]; v1[j] = sigmoidf_(g1[j]) * acc[ai][bj][m][1][j]; }
;                     if (MODE == 1) { const u32x4 mw = *(const u32x4*)(rowp + bj * 128); f32x4 m0, m1; unpack8(mw, m0, m1); v0 += m0; v1 += m1; }
;                     *(u32x4*)(rowp + bj * 128) = pack8(v0, v1); }
	v_mov_b32_e32 v60, v208
	v_mov_b32_e32 v61, v209
	v_mov_b32_e32 v62, v210
	v_mov_b32_e32 v63, v211
	s_mov_b32 s100, 0xbfb8aa3b
	v_lshlrev_b32_e32 v242, 16, v60
	v_and_b32_e32 v243, 0xffff0000, v60
	v_lshlrev_b32_e32 v244, 16, v62
	v_and_b32_e32 v245, 0xffff0000, v62
	v_lshlrev_b32_e32 v246, 16, v61
	v_and_b32_e32 v247, 0xffff0000, v61
	v_lshlrev_b32_e32 v248, 16, v63
	v_and_b32_e32 v249, 0xffff0000, v63
	v_pk_mul_f32 v[242:243], v[242:243], s[100:101] op_sel_hi:[1,0]
	v_pk_mul_f32 v[244:245], v[244:245], s[100:101] op_sel_hi:[1,0]
	v_pk_mul_f32 v[246:247], v[246:247], s[100:101] op_sel_hi:[1,0]
	v_pk_mul_f32 v[248:249], v[248:249], s[100:101] op_sel_hi:[1,0]
	v_exp_f32_e32 v242, v242
	v_exp_f32_e32 v243, v243
	v_exp_f32_e32 v244, v244
	v_exp_f32_e32 v245, v245
	v_exp_f32_e32 v246, v246
	v_exp_f32_e32 v247, v247
	v_exp_f32_e32 v248, v248
	v_exp_f32_e32 v249, v249
	s_nop 0
	v_pk_add_f32 v[242:243], v[242:243], 1.0 op_sel_hi:[1,0]
	v_pk_add_f32 v[244:245], v[244:245], 1.0 op_sel_hi:[1,0]
	v_pk_add_f32 v[246:247], v[246:247], 1.0 op_sel_hi:[1,0]
	v_pk_add_f32 v[248:249], v[248:249], 1.0 op_sel_hi:[1,0]
	v_rcp_f32_e32 v250, v242
	v_rcp_f32_e32 v251, v243
	s_nop 0
	v_pk_fma_f32 v[252:253], v[242:243], v[250:251], 1.0 op_sel_hi:[1,1,0] neg_lo:[1,0,0] neg_hi:[1,0,0]
	v_pk_fma_f32 v[250:251], v[252:253], v[250:251], v[250:251]
	v_pk_fma_f32 v[252:253], v[242:243], v[250:251], 1.0 op_sel_hi:[1,1,0] neg_lo:[1,0,0] neg_hi:[1,0,0]
	v_pk_fma_f32 v[254:255], v[252:253], v[250:251], v[250:251]
	v_pk_fma_f32 v[252:253], v[242:243], v[254:255], 1.0 op_sel_hi:[1,1,0] neg_lo:[1,0,0] neg_hi:[1,0,0]
	v_pk_fma_f32 v[254:255], v[252:253], v[250:251], v[254:255]
	v_div_fixup_f32 v242, v254, v242, 1.0
	v_div_fixup_f32 v243, v255, v243, 1.0
	v_rcp_f32_e32 v250, v244
	v_rcp_f32_e32 v251, v245
	s_nop 0
	v_pk_fma_f32 v[252:253], v[244:245], v[250:251], 1.0 op_sel_hi:[1,1,0] neg_lo:[1,0,0] neg_hi:[1,0,0]
	v_pk_fma_f32 v[250:251], v[252:253], v[250:251], v[250:251]
	v_pk_fma_f32 v[252:253], v[244:245], v[250:251], 1.0 op_sel_hi:[1,1,0] neg_lo:[1,0,0] neg_hi:[1,0,0]
	v_pk_fma_f32 v[254:255], v[252:253], v[250:251], v[250:251]
	v_pk_fma_f32 v[252:253], v[244:245], v[254:255], 1.0 op_sel_hi:[1,1,0] neg_lo:[1,0,0] neg_hi:[1,0,0]
	v_pk_fma_f32 v[254:255], v[252:253], v[250:251], v[254:255]
	v_div_fixup_f32 v244, v254, v244, 1.0
	v_div_fixup_f32 v245, v255, v245, 1.0
	v_rcp_f32_e32 v250, v246
	v_rcp_f32_e32 v251, v247
	s_nop 0
	v_pk_fma_f32 v[252:253], v[246:247], v[250:251], 1.0 op_sel_hi:[1,1,0] neg_lo:[1,0,0] neg_hi:[1,0,0]
	v_pk_fma_f32 v[250:251], v[252:253], v[250:251], v[250:251]
	v_pk_fma_f32 v[252:253], v[246:247], v[250:251], 1.0 op_sel_hi:[1,1,0] neg_lo:[1,0,0] neg_hi:[1,0,0]
	v_pk_fma_f32 v[254:255], v[252:253], v[250:251], v[250:251]
	v_pk_fma_f32 v[252:253], v[246:247], v[254:255], 1.0 op_sel_hi:[1,1,0] neg_lo:[1,0,0] neg_hi:[1,0,0]
	v_pk_fma_f32 v[254:255], v[252:253], v[250:251], v[254:255]
	v_div_fixup_f32 v246, v254, v246, 1.0
	v_div_fixup_f32 v247, v255, v247, 1.0
	v_rcp_f32_e32 v250, v248
	v_rcp_f32_e32 v251, v249
	s_nop 0
	v_pk_fma_f32 v[252:253], v[248:249], v[250:251], 1.0 op_sel_hi:[1,1,0] neg_lo:[1,0,0] neg_hi:[1,0,0]
	v_pk_fma_f32 v[250:251], v[252:253], v[250:251], v[250:251]
	v_pk_fma_f32 v[252:253], v[248:249], v[250:251], 1.0 op_sel_hi:[1,1,0] neg_lo:[1,0,0] neg_hi:[1,0,0]
	v_pk_fma_f32 v[254:255], v[252:253], v[250:251], v[250:251]
	v_pk_fma_f32 v[252:253], v[248:249], v[254:255], 1.0 op_sel_hi:[1,1,0] neg_lo:[1,0,0] neg_hi:[1,0,0]
	v_pk_fma_f32 v[254:255], v[252:253], v[250:251], v[254:255]
	v_div_fixup_f32 v248, v254, v248, 1.0
	v_div_fixup_f32 v249, v255, v249, 1.0
	global_store_dwordx4 v[64:65], v[56:59], off
	s_nop 0
	v_pk_mul_f32 v[52:53], v[52:53], v[242:243]
	v_pk_mul_f32 v[48:49], v[48:49], v[244:245]
	v_pk_mul_f32 v[54:55], v[54:55], v[246:247]
	v_pk_mul_f32 v[56:57], v[50:51], v[248:249]
	v_cvt_pk_bf16_f32 v50, v52, v53
	v_cvt_pk_bf16_f32 v51, v54, v55
	v_cvt_pk_bf16_f32 v52, v48, v49
	v_add_u32_e32 v48, 0x90, v160
	v_mad_i64_i32 v[48:49], s[6:7], v48, s61, v[146:147]
	v_lshl_add_u64 v[48:49], v[48:49], 0, v[148:149]
	v_add_co_u32_e32 v58, vcc, s62, v48
	v_cvt_pk_bf16_f32 v53, v56, v57
	global_store_dwordx4 v[64:65], v[50:53], off offset:256
	s_nop 0
	v_addc_co_u32_e32 v59, vcc, 0, v49, vcc
	s_waitcnt vmcnt(13)
; __device__ __forceinline__ float sigmoidf_(float x) { return 1.0f / (1.0f + __expf(-x)); }
; __device__ __forceinline__ u32x4 pack8(const f32x4 v0, const f32x4 v1) { u32x4 w; w.x = pk2(v0[0], v0[1]); w.y = pk2(v0[2], v0[3]); w.z = pk2(v1[0], v1[1]); w.w = pk2(v1[2], v1[3]); return w; }
; __device__ __forceinline__ void unpack8(const u32x4 w, f32x4& v0, f32x4& v1) { v0 = (f32x4){bflo(w.x), bfhi(w.x), bflo(w.y), bfhi(w.y)}; v1 = (f32x4){bflo(w.z), bfhi(w.z), bflo(w.w), bfhi(w.w)}; }
;     __device__ __forceinline__ void operator()(const f32x4 (&acc)[2][2][4][2], const Unit& u, int wr, int wc, int fr, int fq) const {
;     ...
;         for (int ai = 0; ai < 2; ++ai)
; #pragma unroll
;             for (int m = 0; m < 4; ++m) {
;                 bf16_t* rowp = z + (size_t)(row0 + ai * 128 + m * 16) * DIN + col0;
; #pragma unroll
;                 for (int bj = 0; bj < 2; ++bj) {
;                     const u32x4 gw = *(const u32x4*)(rowp + (MODE == 0 ? O_GB : O_GA) + bj * 128);
;                     f32x4 g0, g1; unpack8(gw, g0, g1);
;                     f32x4 v0, v1;
; #pragma unroll
;                     for (int j = 0; j < 4; ++j) { v0[j] = sigmoidf_(g0[j]) * acc[ai][bj][m][0][j]; v1[j] = sigmoidf_(g1[j]) * acc[ai][bj][m][1][j]; }
;                     if (MODE == 1) { const u32x4 mw = *(const u32x4*)(rowp + bj * 128); f32x4 m0, m1; unpack8(mw, m0, m1); v0 += m0; v1 += m1; }
;                     *(u32x4*)(rowp + bj * 128) = pack8(v0, v1); }
	v_mov_b32_e32 v54, v212
	v_mov_b32_e32 v55, v213
	v_mov_b32_e32 v56, v214
	v_mov_b32_e32 v57, v215
	s_mov_b32 s100, 0xbfb8aa3b
	v_lshlrev_b32_e32 v242, 16, v54
	v_and_b32_e32 v243, 0xffff0000, v54
	v_lshlrev_b32_e32 v244, 16, v56
	v_and_b32_e32 v245, 0xffff0000, v56
	v_lshlrev_b32_e32 v246, 16, v55
	v_and_b32_e32 v247, 0xffff0000, v55
	v_lshlrev_b32_e32 v248, 16, v57
	v_and_b32_e32 v249, 0xffff0000, v57
	v_pk_mul_f32 v[242:243], v[242:243], s[100:101] op_sel_hi:[1,0]
	v_pk_mul_f32 v[244:245], v[244:245], s[100:101] op_sel_hi:[1,0]
	v_pk_mul_f32 v[246:247], v[246:247], s[100:101] op_sel_hi:[1,0]
	v_pk_mul_f32 v[248:249], v[248:249], s[100:101] op_sel_hi:[1,0]
	v_exp_f32_e32 v242, v242
	v_exp_f32_e32 v243, v243
	v_exp_f32_e32 v244, v244
	v_exp_f32_e32 v245, v245
	v_exp_f32_e32 v246, v246
	v_exp_f32_e32 v247, v247
	v_exp_f32_e32 v248, v248
	v_exp_f32_e32 v249, v249
	s_nop 0
	v_pk_add_f32 v[242:243], v[242:243], 1.0 op_sel_hi:[1,0]
	v_pk_add_f32 v[244:245], v[244:245], 1.0 op_sel_hi:[1,0]
	v_pk_add_f32 v[246:247], v[246:247], 1.0 op_sel_hi:[1,0]
	v_pk_add_f32 v[248:249], v[248:249], 1.0 op_sel_hi:[1,0]
	v_rcp_f32_e32 v250, v242
	v_rcp_f32_e32 v251, v243
	s_nop 0
	v_pk_fma_f32 v[252:253], v[242:243], v[250:251], 1.0 op_sel_hi:[1,1,0] neg_lo:[1,0,0] neg_hi:[1,0,0]
	v_pk_fma_f32 v[250:251], v[252:253], v[250:251], v[250:251]
	v_pk_fma_f32 v[252:253], v[242:243], v[250:251], 1.0 op_sel_hi:[1,1,0] neg_lo:[1,0,0] neg_hi:[1,0,0]
	v_pk_fma_f32 v[254:255], v[252:253], v[250:251], v[250:251]
	v_pk_fma_f32 v[252:253], v[242:243], v[254:255], 1.0 op_sel_hi:[1,1,0] neg_lo:[1,0,0] neg_hi:[1,0,0]
	v_pk_fma_f32 v[254:255], v[252:253], v[250:251], v[254:255]
	v_div_fixup_f32 v242, v254, v242, 1.0
	v_div_fixup_f32 v243, v255, v243, 1.0
	v_rcp_f32_e32 v250, v244
	v_rcp_f32_e32 v251, v245
	s_nop 0
	v_pk_fma_f32 v[252:253], v[244:245], v[250:251], 1.0 op_sel_hi:[1,1,0] neg_lo:[1,0,0] neg_hi:[1,0,0]
	v_pk_fma_f32 v[250:251], v[252:253], v[250:251], v[250:251]
	v_pk_fma_f32 v[252:253], v[244:245], v[250:251], 1.0 op_sel_hi:[1,1,0] neg_lo:[1,0,0] neg_hi:[1,0,0]
	v_pk_fma_f32 v[254:255], v[252:253], v[250:251], v[250:251]
	v_pk_fma_f32 v[252:253], v[244:245], v[254:255], 1.0 op_sel_hi:[1,1,0] neg_lo:[1,0,0] neg_hi:[1,0,0]
	v_pk_fma_f32 v[254:255], v[252:253], v[250:251], v[254:255]
	v_div_fixup_f32 v244, v254, v244, 1.0
	v_div_fixup_f32 v245, v255, v245, 1.0
	v_rcp_f32_e32 v250, v246
	v_rcp_f32_e32 v251, v247
	s_nop 0
	v_pk_fma_f32 v[252:253], v[246:247], v[250:251], 1.0 op_sel_hi:[1,1,0] neg_lo:[1,0,0] neg_hi:[1,0,0]
	v_pk_fma_f32 v[250:251], v[252:253], v[250:251], v[250:251]
	v_pk_fma_f32 v[252:253], v[246:247], v[250:251], 1.0 op_sel_hi:[1,1,0] neg_lo:[1,0,0] neg_hi:[1,0,0]
	v_pk_fma_f32 v[254:255], v[252:253], v[250:251], v[250:251]
	v_pk_fma_f32 v[252:253], v[246:247], v[254:255], 1.0 op_sel_hi:[1,1,0] neg_lo:[1,0,0] neg_hi:[1,0,0]
	v_pk_fma_f32 v[254:255], v[252:253], v[250:251], v[254:255]
	v_div_fixup_f32 v246, v254, v246, 1.0
	v_div_fixup_f32 v247, v255, v247, 1.0
	v_rcp_f32_e32 v250, v248
	v_rcp_f32_e32 v251, v249
	s_nop 0
	v_pk_fma_f32 v[252:253], v[248:249], v[250:251], 1.0 op_sel_hi:[1,1,0] neg_lo:[1,0,0] neg_hi:[1,0,0]
	v_pk_fma_f32 v[250:251], v[252:253], v[250:251], v[250:251]
	v_pk_fma_f32 v[252:253], v[248:249], v[250:251], 1.0 op_sel_hi:[1,1,0] neg_lo:[1,0,0] neg_hi:[1,0,0]
	v_pk_fma_f32 v[254:255], v[252:253], v[250:251], v[250:251]
	v_pk_fma_f32 v[252:253], v[248:249], v[254:255], 1.0 op_sel_hi:[1,1,0] neg_lo:[1,0,0] neg_hi:[1,0,0]
	v_pk_fma_f32 v[254:255], v[252:253], v[250:251], v[254:255]
	v_div_fixup_f32 v248, v254, v248, 1.0
	v_div_fixup_f32 v249, v255, v249, 1.0
	v_mul_f32_e32 v44, v44, v242
	v_mul_f32_e32 v50, v40, v244
	v_mul_f32_e32 v40, v45, v243
	v_mul_f32_e32 v45, v41, v245
	v_mul_f32_e32 v41, v46, v246
	v_mul_f32_e32 v46, v42, v248
	v_mul_f32_e32 v42, v47, v247
	v_mul_f32_e32 v43, v43, v249
	v_cvt_pk_bf16_f32 v40, v44, v40
	v_cvt_pk_bf16_f32 v41, v41, v42
	v_cvt_pk_bf16_f32 v42, v50, v45
	v_cvt_pk_bf16_f32 v43, v46, v43
	s_waitcnt vmcnt(10)
	v_mov_b32_e32 v44, v216
	v_mov_b32_e32 v45, v217
	v_mov_b32_e32 v46, v218
	v_mov_b32_e32 v47, v219
	s_mov_b32 s100, 0xbfb8aa3b
	v_lshlrev_b32_e32 v242, 16, v44
	v_and_b32_e32 v243, 0xffff0000, v44
	v_lshlrev_b32_e32 v244, 16, v46
	v_and_b32_e32 v245, 0xffff0000, v46
	v_lshlrev_b32_e32 v246, 16, v45
	v_and_b32_e32 v247, 0xffff0000, v45
	v_lshlrev_b32_e32 v248, 16, v47
	v_and_b32_e32 v249, 0xffff0000, v47
	v_pk_mul_f32 v[242:243], v[242:243], s[100:101] op_sel_hi:[1,0]
	v_pk_mul_f32 v[244:245], v[244:245], s[100:101] op_sel_hi:[1,0]
	v_pk_mul_f32 v[246:247], v[246:247], s[100:101] op_sel_hi:[1,0]
	v_pk_mul_f32 v[248:249], v[248:249], s[100:101] op_sel_hi:[1,0]
	v_exp_f32_e32 v242, v242
	v_exp_f32_e32 v243, v243
	v_exp_f32_e32 v244, v244
	v_exp_f32_e32 v245, v245
	v_exp_f32_e32 v246, v246
	v_exp_f32_e32 v247, v247
	v_exp_f32_e32 v248, v248
	v_exp_f32_e32 v249, v249
	s_nop 0
	v_pk_add_f32 v[242:243], v[242:243], 1.0 op_sel_hi:[1,0]
	v_pk_add_f32 v[244:245], v[244:245], 1.0 op_sel_hi:[1,0]
	v_pk_add_f32 v[246:247], v[246:247], 1.0 op_sel_hi:[1,0]
	v_pk_add_f32 v[248:249], v[248:249], 1.0 op_sel_hi:[1,0]
	v_rcp_f32_e32 v250, v242
	v_rcp_f32_e32 v251, v243
	s_nop 0
	v_pk_fma_f32 v[252:253], v[242:243], v[250:251], 1.0 op_sel_hi:[1,1,0] neg_lo:[1,0,0] neg_hi:[1,0,0]
	v_pk_fma_f32 v[250:251], v[252:253], v[250:251], v[250:251]
	v_pk_fma_f32 v[252:253], v[242:243], v[250:251], 1.0 op_sel_hi:[1,1,0] neg_lo:[1,0,0] neg_hi:[1,0,0]
	v_pk_fma_f32 v[254:255], v[252:253], v[250:251], v[250:251]
	v_pk_fma_f32 v[252:253], v[242:243], v[254:255], 1.0 op_sel_hi:[1,1,0] neg_lo:[1,0,0] neg_hi:[1,0,0]
; __device__ __forceinline__ float sigmoidf_(float x) { return 1.0f / (1.0f + __expf(-x)); }
; __device__ __forceinline__ u32x4 pack8(const f32x4 v0, const f32x4 v1) { u32x4 w; w.x = pk2(v0[0], v0[1]); w.y = pk2(v0[2], v0[3]); w.z = pk2(v1[0], v1[1]); w.w = pk2(v1[2], v1[3]); return w; }
; __device__ __forceinline__ void unpack8(const u32x4 w, f32x4& v0, f32x4& v1) { v0 = (f32x4){bflo(w.x), bfhi(w.x), bflo(w.y), bfhi(w.y)}; v1 = (f32x4){bflo(w.z), bfhi(w.z), bflo(w.w), bfhi(w.w)}; }
;     __device__ __forceinline__ void operator()(const f32x4 (&acc)[2][2][4][2], const Unit& u, int wr, int wc, int fr, int fq) const {
;     ...
;         for (int ai = 0; ai < 2; ++ai)
; #pragma unroll
;             for (int m = 0; m < 4; ++m) {
;                 bf16_t* rowp = z + (size_t)(row0 + ai * 128 + m * 16) * DIN + col0;
; #pragma unroll
;                 for (int bj = 0; bj < 2; ++bj) {
;                     const u32x4 gw = *(const u32x4*)(rowp + (MODE == 0 ? O_GB : O_GA) + bj * 128);
;                     f32x4 g0, g1; unpack8(gw, g0, g1);
;                     f32x4 v0, v1;
; #pragma unroll
;                     for (int j = 0; j < 4; ++j) { v0[j] = sigmoidf_(g0[j]) * acc[ai][bj][m][0][j]; v1[j] = sigmoidf_(g1[j]) * acc[ai][bj][m][1][j]; }
;                     if (MODE == 1) { const u32x4 mw = *(const u32x4*)(rowp + bj * 128); f32x4 m0, m1; unpack8(mw, m0, m1); v0 += m0; v1 += m1; }
;                     *(u32x4*)(rowp + bj * 128) = pack8(v0, v1); }
	v_pk_fma_f32 v[254:255], v[252:253], v[250:251], v[254:255]
	v_div_fixup_f32 v242, v254, v242, 1.0
	v_div_fixup_f32 v243, v255, v243, 1.0
	v_rcp_f32_e32 v250, v244
	v_rcp_f32_e32 v251, v245
	s_nop 0
	v_pk_fma_f32 v[252:253], v[244:245], v[250:251], 1.0 op_sel_hi:[1,1,0] neg_lo:[1,0,0] neg_hi:[1,0,0]
	v_pk_fma_f32 v[250:251], v[252:253], v[250:251], v[250:251]
	v_pk_fma_f32 v[252:253], v[244:245], v[250:251], 1.0 op_sel_hi:[1,1,0] neg_lo:[1,0,0] neg_hi:[1,0,0]
	v_pk_fma_f32 v[254:255], v[252:253], v[250:251], v[250:251]
	v_pk_fma_f32 v[252:253], v[244:245], v[254:255], 1.0 op_sel_hi:[1,1,0] neg_lo:[1,0,0] neg_hi:[1,0,0]
	v_pk_fma_f32 v[254:255], v[252:253], v[250:251], v[254:255]
	v_div_fixup_f32 v244, v254, v244, 1.0
	v_div_fixup_f32 v245, v255, v245, 1.0
	v_rcp_f32_e32 v250, v246
	v_rcp_f32_e32 v251, v247
	s_nop 0
	v_pk_fma_f32 v[252:253], v[246:247], v[250:251], 1.0 op_sel_hi:[1,1,0] neg_lo:[1,0,0] neg_hi:[1,0,0]
	v_pk_fma_f32 v[250:251], v[252:253], v[250:251], v[250:251]
	v_pk_fma_f32 v[252:253], v[246:247], v[250:251], 1.0 op_sel_hi:[1,1,0] neg_lo:[1,0,0] neg_hi:[1,0,0]
	v_pk_fma_f32 v[254:255], v[252:253], v[250:251], v[250:251]
	v_pk_fma_f32 v[252:253], v[246:247], v[254:255], 1.0 op_sel_hi:[1,1,0] neg_lo:[1,0,0] neg_hi:[1,0,0]
	v_pk_fma_f32 v[254:255], v[252:253], v[250:251], v[254:255]
	v_div_fixup_f32 v246, v254, v246, 1.0
	v_div_fixup_f32 v247, v255, v247, 1.0
	v_rcp_f32_e32 v250, v248
	v_rcp_f32_e32 v251, v249
	s_nop 0
	v_pk_fma_f32 v[252:253], v[248:249], v[250:251], 1.0 op_sel_hi:[1,1,0] neg_lo:[1,0,0] neg_hi:[1,0,0]
	v_pk_fma_f32 v[250:251], v[252:253], v[250:251], v[250:251]
	v_pk_fma_f32 v[252:253], v[248:249], v[250:251], 1.0 op_sel_hi:[1,1,0] neg_lo:[1,0,0] neg_hi:[1,0,0]
	v_pk_fma_f32 v[254:255], v[252:253], v[250:251], v[250:251]
	v_pk_fma_f32 v[252:253], v[248:249], v[254:255], 1.0 op_sel_hi:[1,1,0] neg_lo:[1,0,0] neg_hi:[1,0,0]
	v_pk_fma_f32 v[254:255], v[252:253], v[250:251], v[254:255]
	v_div_fixup_f32 v248, v254, v248, 1.0
	v_div_fixup_f32 v249, v255, v249, 1.0
	global_store_dwordx4 v[48:49], v[40:43], off
	s_nop 0
	v_pk_mul_f32 v[36:37], v[36:37], v[242:243]
	v_pk_mul_f32 v[32:33], v[32:33], v[244:245]
	v_pk_mul_f32 v[38:39], v[38:39], v[246:247]
	v_pk_mul_f32 v[40:41], v[34:35], v[248:249]
	v_cvt_pk_bf16_f32 v34, v36, v37
	v_cvt_pk_bf16_f32 v35, v38, v39
	v_cvt_pk_bf16_f32 v36, v32, v33
	v_add_u32_e32 v32, 0xa0, v160
	v_mad_i64_i32 v[32:33], s[6:7], v32, s61, v[146:147]
	v_lshl_add_u64 v[32:33], v[32:33], 0, v[148:149]
	v_add_co_u32_e32 v42, vcc, s62, v32
	v_cvt_pk_bf16_f32 v37, v40, v41
	global_store_dwordx4 v[48:49], v[34:37], off offset:256
	s_nop 0
	v_addc_co_u32_e32 v43, vcc, 0, v33, vcc
	s_waitcnt vmcnt(11)
	v_mov_b32_e32 v38, v232
	v_mov_b32_e32 v39, v233
	v_mov_b32_e32 v40, v234
	v_mov_b32_e32 v41, v235
	s_mov_b32 s100, 0xbfb8aa3b
	v_lshlrev_b32_e32 v242, 16, v38
	v_and_b32_e32 v243, 0xffff0000, v38
	v_lshlrev_b32_e32 v244, 16, v40
	v_and_b32_e32 v245, 0xffff0000, v40
	v_lshlrev_b32_e32 v246, 16, v39
	v_and_b32_e32 v247, 0xffff0000, v39
	v_lshlrev_b32_e32 v248, 16, v41
	v_and_b32_e32 v249, 0xffff0000, v41
	v_pk_mul_f32 v[242:243], v[242:243], s[100:101] op_sel_hi:[1,0]
	v_pk_mul_f32 v[244:245], v[244:245], s[100:101] op_sel_hi:[1,0]
	v_pk_mul_f32 v[246:247], v[246:247], s[100:101] op_sel_hi:[1,0]
	v_pk_mul_f32 v[248:249], v[248:249], s[100:101] op_sel_hi:[1,0]
	v_exp_f32_e32 v242, v242
	v_exp_f32_e32 v243, v243
	v_exp_f32_e32 v244, v244
	v_exp_f32_e32 v245, v245
	v_exp_f32_e32 v246, v246
	v_exp_f32_e32 v247, v247
	v_exp_f32_e32 v248, v248
	v_exp_f32_e32 v249, v249
	s_nop 0
	v_pk_add_f32 v[242:243], v[242:243], 1.0 op_sel_hi:[1,0]
	v_pk_add_f32 v[244:245], v[244:245], 1.0 op_sel_hi:[1,0]
	v_pk_add_f32 v[246:247], v[246:247], 1.0 op_sel_hi:[1,0]
	v_pk_add_f32 v[248:249], v[248:249], 1.0 op_sel_hi:[1,0]
	v_rcp_f32_e32 v250, v242
	v_rcp_f32_e32 v251, v243
	s_nop 0
	v_pk_fma_f32 v[252:253], v[242:243], v[250:251], 1.0 op_sel_hi:[1,1,0] neg_lo:[1,0,0] neg_hi:[1,0,0]
	v_pk_fma_f32 v[250:251], v[252:253], v[250:251], v[250:251]
	v_pk_fma_f32 v[252:253], v[242:243], v[250:251], 1.0 op_sel_hi:[1,1,0] neg_lo:[1,0,0] neg_hi:[1,0,0]
	v_pk_fma_f32 v[254:255], v[252:253], v[250:251], v[250:251]
	v_pk_fma_f32 v[252:253], v[242:243], v[254:255], 1.0 op_sel_hi:[1,1,0] neg_lo:[1,0,0] neg_hi:[1,0,0]
	v_pk_fma_f32 v[254:255], v[252:253], v[250:251], v[254:255]
	v_div_fixup_f32 v242, v254, v242, 1.0
	v_div_fixup_f32 v243, v255, v243, 1.0
	v_rcp_f32_e32 v250, v244
	v_rcp_f32_e32 v251, v245
	s_nop 0
	v_pk_fma_f32 v[252:253], v[244:245], v[250:251], 1.0 op_sel_hi:[1,1,0] neg_lo:[1,0,0] neg_hi:[1,0,0]
	v_pk_fma_f32 v[250:251], v[252:253], v[250:251], v[250:251]
	v_pk_fma_f32 v[252:253], v[244:245], v[250:251], 1.0 op_sel_hi:[1,1,0] neg_lo:[1,0,0] neg_hi:[1,0,0]
	v_pk_fma_f32 v[254:255], v[252:253], v[250:251], v[250:251]
	v_pk_fma_f32 v[252:253], v[244:245], v[254:255], 1.0 op_sel_hi:[1,1,0] neg_lo:[1,0,0] neg_hi:[1,0,0]
	v_pk_fma_f32 v[254:255], v[252:253], v[250:251], v[254:255]
	v_div_fixup_f32 v244, v254, v244, 1.0
	v_div_fixup_f32 v245, v255, v245, 1.0
	v_rcp_f32_e32 v250, v246
	v_rcp_f32_e32 v251, v247
	s_nop 0
	v_pk_fma_f32 v[252:253], v[246:247], v[250:251], 1.0 op_sel_hi:[1,1,0] neg_lo:[1,0,0] neg_hi:[1,0,0]
	v_pk_fma_f32 v[250:251], v[252:253], v[250:251], v[250:251]
	v_pk_fma_f32 v[252:253], v[246:247], v[250:251], 1.0 op_sel_hi:[1,1,0] neg_lo:[1,0,0] neg_hi:[1,0,0]
	v_pk_fma_f32 v[254:255], v[252:253], v[250:251], v[250:251]
	v_pk_fma_f32 v[252:253], v[246:247], v[254:255], 1.0 op_sel_hi:[1,1,0] neg_lo:[1,0,0] neg_hi:[1,0,0]
	v_pk_fma_f32 v[254:255], v[252:253], v[250:251], v[254:255]
	v_div_fixup_f32 v246, v254, v246, 1.0
	v_div_fixup_f32 v247, v255, v247, 1.0
	v_rcp_f32_e32 v250, v248
	v_rcp_f32_e32 v251, v249
	s_nop 0
	v_pk_fma_f32 v[252:253], v[248:249], v[250:251], 1.0 op_sel_hi:[1,1,0] neg_lo:[1,0,0] neg_hi:[1,0,0]
	v_pk_fma_f32 v[250:251], v[252:253], v[250:251], v[250:251]
	v_pk_fma_f32 v[252:253], v[248:249], v[250:251], 1.0 op_sel_hi:[1,1,0] neg_lo:[1,0,0] neg_hi:[1,0,0]
	v_pk_fma_f32 v[254:255], v[252:253], v[250:251], v[250:251]
	v_pk_fma_f32 v[252:253], v[248:249], v[254:255], 1.0 op_sel_hi:[1,1,0] neg_lo:[1,0,0] neg_hi:[1,0,0]
	v_pk_fma_f32 v[254:255], v[252:253], v[250:251], v[254:255]
	v_div_fixup_f32 v248, v254, v248, 1.0
	v_div_fixup_f32 v249, v255, v249, 1.0
	v_mul_f32_e32 v28, v28, v242
	v_mul_f32_e32 v34, v24, v244
	v_mul_f32_e32 v24, v29, v243
	v_mul_f32_e32 v29, v25, v245
	v_mul_f32_e32 v25, v30, v246
	v_mul_f32_e32 v30, v26, v248
	v_mul_f32_e32 v26, v31, v247
	v_mul_f32_e32 v27, v27, v249
	v_cvt_pk_bf16_f32 v24, v28, v24
	v_cvt_pk_bf16_f32 v25, v25, v26
	v_cvt_pk_bf16_f32 v26, v34, v29
	v_cvt_pk_bf16_f32 v27, v30, v27
	s_waitcnt vmcnt(8)
; __device__ __forceinline__ float sigmoidf_(float x) { return 1.0f / (1.0f + __expf(-x)); }
; __device__ __forceinline__ u32x4 pack8(const f32x4 v0, const f32x4 v1) { u32x4 w; w.x = pk2(v0[0], v0[1]); w.y = pk2(v0[2], v0[3]); w.z = pk2(v1[0], v1[1]); w.w = pk2(v1[2], v1[3]); return w; }
; __device__ __forceinline__ void unpack8(const u32x4 w, f32x4& v0, f32x4& v1) { v0 = (f32x4){bflo(w.x), bfhi(w.x), bflo(w.y), bfhi(w.y)}; v1 = (f32x4){bflo(w.z), bfhi(w.z), bflo(w.w), bfhi(w.w)}; }
;     __device__ __forceinline__ void operator()(const f32x4 (&acc)[2][2][4][2], const Unit& u, int wr, int wc, int fr, int fq) const {
;     ...
;         for (int ai = 0; ai < 2; ++ai)
; #pragma unroll
;             for (int m = 0; m < 4; ++m) {
;                 bf16_t* rowp = z + (size_t)(row0 + ai * 128 + m * 16) * DIN + col0;
; #pragma unroll
;                 for (int bj = 0; bj < 2; ++bj) {
;                     const u32x4 gw = *(const u32x4*)(rowp + (MODE == 0 ? O_GB : O_GA) + bj * 128);
;                     f32x4 g0, g1; unpack8(gw, g0, g1);
;                     f32x4 v0, v1;
; #pragma unroll
;                     for (int j = 0; j < 4; ++j) { v0[j] = sigmoidf_(g0[j]) * acc[ai][bj][m][0][j]; v1[j] = sigmoidf_(g1[j]) * acc[ai][bj][m][1][j]; }
;                     if (MODE == 1) { const u32x4 mw = *(const u32x4*)(rowp + bj * 128); f32x4 m0, m1; unpack8(mw, m0, m1); v0 += m0; v1 += m1; }
;                     *(u32x4*)(rowp + bj * 128) = pack8(v0, v1); }
	v_mov_b32_e32 v28, v236
	v_mov_b32_e32 v29, v237
	v_mov_b32_e32 v30, v238
	v_mov_b32_e32 v31, v239
	s_mov_b32 s100, 0xbfb8aa3b
	v_lshlrev_b32_e32 v242, 16, v28
	v_and_b32_e32 v243, 0xffff0000, v28
	v_lshlrev_b32_e32 v244, 16, v30
	v_and_b32_e32 v245, 0xffff0000, v30
	v_lshlrev_b32_e32 v246, 16, v29
	v_and_b32_e32 v247, 0xffff0000, v29
	v_lshlrev_b32_e32 v248, 16, v31
	v_and_b32_e32 v249, 0xffff0000, v31
	v_pk_mul_f32 v[242:243], v[242:243], s[100:101] op_sel_hi:[1,0]
	v_pk_mul_f32 v[244:245], v[244:245], s[100:101] op_sel_hi:[1,0]
	v_pk_mul_f32 v[246:247], v[246:247], s[100:101] op_sel_hi:[1,0]
	v_pk_mul_f32 v[248:249], v[248:249], s[100:101] op_sel_hi:[1,0]
	v_exp_f32_e32 v242, v242
	v_exp_f32_e32 v243, v243
	v_exp_f32_e32 v244, v244
	v_exp_f32_e32 v245, v245
	v_exp_f32_e32 v246, v246
	v_exp_f32_e32 v247, v247
	v_exp_f32_e32 v248, v248
	v_exp_f32_e32 v249, v249
	s_nop 0
	v_pk_add_f32 v[242:243], v[242:243], 1.0 op_sel_hi:[1,0]
	v_pk_add_f32 v[244:245], v[244:245], 1.0 op_sel_hi:[1,0]
	v_pk_add_f32 v[246:247], v[246:247], 1.0 op_sel_hi:[1,0]
	v_pk_add_f32 v[248:249], v[248:249], 1.0 op_sel_hi:[1,0]
	v_rcp_f32_e32 v250, v242
	v_rcp_f32_e32 v251, v243
	s_nop 0
	v_pk_fma_f32 v[252:253], v[242:243], v[250:251], 1.0 op_sel_hi:[1,1,0] neg_lo:[1,0,0] neg_hi:[1,0,0]
	v_pk_fma_f32 v[250:251], v[252:253], v[250:251], v[250:251]
	v_pk_fma_f32 v[252:253], v[242:243], v[250:251], 1.0 op_sel_hi:[1,1,0] neg_lo:[1,0,0] neg_hi:[1,0,0]
	v_pk_fma_f32 v[254:255], v[252:253], v[250:251], v[250:251]
	v_pk_fma_f32 v[252:253], v[242:243], v[254:255], 1.0 op_sel_hi:[1,1,0] neg_lo:[1,0,0] neg_hi:[1,0,0]
	v_pk_fma_f32 v[254:255], v[252:253], v[250:251], v[254:255]
	v_div_fixup_f32 v242, v254, v242, 1.0
	v_div_fixup_f32 v243, v255, v243, 1.0
	v_rcp_f32_e32 v250, v244
	v_rcp_f32_e32 v251, v245
	s_nop 0
	v_pk_fma_f32 v[252:253], v[244:245], v[250:251], 1.0 op_sel_hi:[1,1,0] neg_lo:[1,0,0] neg_hi:[1,0,0]
	v_pk_fma_f32 v[250:251], v[252:253], v[250:251], v[250:251]
	v_pk_fma_f32 v[252:253], v[244:245], v[250:251], 1.0 op_sel_hi:[1,1,0] neg_lo:[1,0,0] neg_hi:[1,0,0]
	v_pk_fma_f32 v[254:255], v[252:253], v[250:251], v[250:251]
	v_pk_fma_f32 v[252:253], v[244:245], v[254:255], 1.0 op_sel_hi:[1,1,0] neg_lo:[1,0,0] neg_hi:[1,0,0]
	v_pk_fma_f32 v[254:255], v[252:253], v[250:251], v[254:255]
	v_div_fixup_f32 v244, v254, v244, 1.0
	v_div_fixup_f32 v245, v255, v245, 1.0
	v_rcp_f32_e32 v250, v246
	v_rcp_f32_e32 v251, v247
	s_nop 0
	v_pk_fma_f32 v[252:253], v[246:247], v[250:251], 1.0 op_sel_hi:[1,1,0] neg_lo:[1,0,0] neg_hi:[1,0,0]
	v_pk_fma_f32 v[250:251], v[252:253], v[250:251], v[250:251]
	v_pk_fma_f32 v[252:253], v[246:247], v[250:251], 1.0 op_sel_hi:[1,1,0] neg_lo:[1,0,0] neg_hi:[1,0,0]
	v_pk_fma_f32 v[254:255], v[252:253], v[250:251], v[250:251]
	v_pk_fma_f32 v[252:253], v[246:247], v[254:255], 1.0 op_sel_hi:[1,1,0] neg_lo:[1,0,0] neg_hi:[1,0,0]
	v_pk_fma_f32 v[254:255], v[252:253], v[250:251], v[254:255]
	v_div_fixup_f32 v246, v254, v246, 1.0
	v_div_fixup_f32 v247, v255, v247, 1.0
	v_rcp_f32_e32 v250, v248
	v_rcp_f32_e32 v251, v249
	s_nop 0
	v_pk_fma_f32 v[252:253], v[248:249], v[250:251], 1.0 op_sel_hi:[1,1,0] neg_lo:[1,0,0] neg_hi:[1,0,0]
	v_pk_fma_f32 v[250:251], v[252:253], v[250:251], v[250:251]
	v_pk_fma_f32 v[252:253], v[248:249], v[250:251], 1.0 op_sel_hi:[1,1,0] neg_lo:[1,0,0] neg_hi:[1,0,0]
	v_pk_fma_f32 v[254:255], v[252:253], v[250:251], v[250:251]
	v_pk_fma_f32 v[252:253], v[248:249], v[254:255], 1.0 op_sel_hi:[1,1,0] neg_lo:[1,0,0] neg_hi:[1,0,0]
	v_pk_fma_f32 v[254:255], v[252:253], v[250:251], v[254:255]
	v_div_fixup_f32 v248, v254, v248, 1.0
	v_div_fixup_f32 v249, v255, v249, 1.0
	global_store_dwordx4 v[32:33], v[24:27], off
	s_nop 0
	v_pk_mul_f32 v[20:21], v[20:21], v[242:243]
	v_pk_mul_f32 v[16:17], v[16:17], v[244:245]
	v_pk_mul_f32 v[22:23], v[22:23], v[246:247]
	v_pk_mul_f32 v[24:25], v[18:19], v[248:249]
	v_cvt_pk_bf16_f32 v18, v20, v21
	v_cvt_pk_bf16_f32 v19, v22, v23
	v_cvt_pk_bf16_f32 v20, v16, v17
	v_add_u32_e32 v16, 0xb0, v160
	v_mad_i64_i32 v[16:17], s[6:7], v16, s61, v[146:147]
	v_lshl_add_u64 v[16:17], v[16:17], 0, v[148:149]
	v_add_co_u32_e32 v26, vcc, s62, v16
	v_cvt_pk_bf16_f32 v21, v24, v25
	global_store_dwordx4 v[32:33], v[18:21], off offset:256
	s_nop 0
	v_addc_co_u32_e32 v27, vcc, 0, v17, vcc
	s_waitcnt vmcnt(9)
; __device__ __forceinline__ float sigmoidf_(float x) { return 1.0f / (1.0f + __expf(-x)); }
; __device__ __forceinline__ u32x4 pack8(const f32x4 v0, const f32x4 v1) { u32x4 w; w.x = pk2(v0[0], v0[1]); w.y = pk2(v0[2], v0[3]); w.z = pk2(v1[0], v1[1]); w.w = pk2(v1[2], v1[3]); return w; }
; __device__ __forceinline__ void unpack8(const u32x4 w, f32x4& v0, f32x4& v1) { v0 = (f32x4){bflo(w.x), bfhi(w.x), bflo(w.y), bfhi(w.y)}; v1 = (f32x4){bflo(w.z), bfhi(w.z), bflo(w.w), bfhi(w.w)}; }
;     __device__ __forceinline__ void operator()(const f32x4 (&acc)[2][2][4][2], const Unit& u, int wr, int wc, int fr, int fq) const {
;     ...
;         for (int ai = 0; ai < 2; ++ai)
; #pragma unroll
;             for (int m = 0; m < 4; ++m) {
;                 bf16_t* rowp = z + (size_t)(row0 + ai * 128 + m * 16) * DIN + col0;
; #pragma unroll
;                 for (int bj = 0; bj < 2; ++bj) {
;                     const u32x4 gw = *(const u32x4*)(rowp + (MODE == 0 ? O_GB : O_GA) + bj * 128);
;                     f32x4 g0, g1; unpack8(gw, g0, g1);
;                     f32x4 v0, v1;
; #pragma unroll
;                     for (int j = 0; j < 4; ++j) { v0[j] = sigmoidf_(g0[j]) * acc[ai][bj][m][0][j]; v1[j] = sigmoidf_(g1[j]) * acc[ai][bj][m][1][j]; }
;                     if (MODE == 1) { const u32x4 mw = *(const u32x4*)(rowp + bj * 128); f32x4 m0, m1; unpack8(mw, m0, m1); v0 += m0; v1 += m1; }
;                     *(u32x4*)(rowp + bj * 128) = pack8(v0, v1); }
	v_mov_b32_e32 v22, v200
	v_mov_b32_e32 v23, v201
	v_mov_b32_e32 v24, v202
	v_mov_b32_e32 v25, v203
	s_mov_b32 s100, 0xbfb8aa3b
	v_lshlrev_b32_e32 v242, 16, v22
	v_and_b32_e32 v243, 0xffff0000, v22
	v_lshlrev_b32_e32 v244, 16, v24
	v_and_b32_e32 v245, 0xffff0000, v24
	v_lshlrev_b32_e32 v246, 16, v23
	v_and_b32_e32 v247, 0xffff0000, v23
	v_lshlrev_b32_e32 v248, 16, v25
	v_and_b32_e32 v249, 0xffff0000, v25
	v_pk_mul_f32 v[242:243], v[242:243], s[100:101] op_sel_hi:[1,0]
	v_pk_mul_f32 v[244:245], v[244:245], s[100:101] op_sel_hi:[1,0]
	v_pk_mul_f32 v[246:247], v[246:247], s[100:101] op_sel_hi:[1,0]
	v_pk_mul_f32 v[248:249], v[248:249], s[100:101] op_sel_hi:[1,0]
	v_exp_f32_e32 v242, v242
	v_exp_f32_e32 v243, v243
	v_exp_f32_e32 v244, v244
	v_exp_f32_e32 v245, v245
	v_exp_f32_e32 v246, v246
	v_exp_f32_e32 v247, v247
	v_exp_f32_e32 v248, v248
	v_exp_f32_e32 v249, v249
	s_nop 0
	v_pk_add_f32 v[242:243], v[242:243], 1.0 op_sel_hi:[1,0]
	v_pk_add_f32 v[244:245], v[244:245], 1.0 op_sel_hi:[1,0]
	v_pk_add_f32 v[246:247], v[246:247], 1.0 op_sel_hi:[1,0]
	v_pk_add_f32 v[248:249], v[248:249], 1.0 op_sel_hi:[1,0]
	v_rcp_f32_e32 v250, v242
	v_rcp_f32_e32 v251, v243
	s_nop 0
	v_pk_fma_f32 v[252:253], v[242:243], v[250:251], 1.0 op_sel_hi:[1,1,0] neg_lo:[1,0,0] neg_hi:[1,0,0]
	v_pk_fma_f32 v[250:251], v[252:253], v[250:251], v[250:251]
	v_pk_fma_f32 v[252:253], v[242:243], v[250:251], 1.0 op_sel_hi:[1,1,0] neg_lo:[1,0,0] neg_hi:[1,0,0]
	v_pk_fma_f32 v[254:255], v[252:253], v[250:251], v[250:251]
	v_pk_fma_f32 v[252:253], v[242:243], v[254:255], 1.0 op_sel_hi:[1,1,0] neg_lo:[1,0,0] neg_hi:[1,0,0]
	v_pk_fma_f32 v[254:255], v[252:253], v[250:251], v[254:255]
	v_div_fixup_f32 v242, v254, v242, 1.0
	v_div_fixup_f32 v243, v255, v243, 1.0
	v_rcp_f32_e32 v250, v244
	v_rcp_f32_e32 v251, v245
	s_nop 0
	v_pk_fma_f32 v[252:253], v[244:245], v[250:251], 1.0 op_sel_hi:[1,1,0] neg_lo:[1,0,0] neg_hi:[1,0,0]
	v_pk_fma_f32 v[250:251], v[252:253], v[250:251], v[250:251]
	v_pk_fma_f32 v[252:253], v[244:245], v[250:251], 1.0 op_sel_hi:[1,1,0] neg_lo:[1,0,0] neg_hi:[1,0,0]
	v_pk_fma_f32 v[254:255], v[252:253], v[250:251], v[250:251]
	v_pk_fma_f32 v[252:253], v[244:245], v[254:255], 1.0 op_sel_hi:[1,1,0] neg_lo:[1,0,0] neg_hi:[1,0,0]
	v_pk_fma_f32 v[254:255], v[252:253], v[250:251], v[254:255]
	v_div_fixup_f32 v244, v254, v244, 1.0
	v_div_fixup_f32 v245, v255, v245, 1.0
	v_rcp_f32_e32 v250, v246
	v_rcp_f32_e32 v251, v247
	s_nop 0
	v_pk_fma_f32 v[252:253], v[246:247], v[250:251], 1.0 op_sel_hi:[1,1,0] neg_lo:[1,0,0] neg_hi:[1,0,0]
	v_pk_fma_f32 v[250:251], v[252:253], v[250:251], v[250:251]
	v_pk_fma_f32 v[252:253], v[246:247], v[250:251], 1.0 op_sel_hi:[1,1,0] neg_lo:[1,0,0] neg_hi:[1,0,0]
	v_pk_fma_f32 v[254:255], v[252:253], v[250:251], v[250:251]
	v_pk_fma_f32 v[252:253], v[246:247], v[254:255], 1.0 op_sel_hi:[1,1,0] neg_lo:[1,0,0] neg_hi:[1,0,0]
	v_pk_fma_f32 v[254:255], v[252:253], v[250:251], v[254:255]
	v_div_fixup_f32 v246, v254, v246, 1.0
	v_div_fixup_f32 v247, v255, v247, 1.0
	v_rcp_f32_e32 v250, v248
	v_rcp_f32_e32 v251, v249
	s_nop 0
	v_pk_fma_f32 v[252:253], v[248:249], v[250:251], 1.0 op_sel_hi:[1,1,0] neg_lo:[1,0,0] neg_hi:[1,0,0]
	v_pk_fma_f32 v[250:251], v[252:253], v[250:251], v[250:251]
	v_pk_fma_f32 v[252:253], v[248:249], v[250:251], 1.0 op_sel_hi:[1,1,0] neg_lo:[1,0,0] neg_hi:[1,0,0]
	v_pk_fma_f32 v[254:255], v[252:253], v[250:251], v[250:251]
	v_pk_fma_f32 v[252:253], v[248:249], v[254:255], 1.0 op_sel_hi:[1,1,0] neg_lo:[1,0,0] neg_hi:[1,0,0]
	v_pk_fma_f32 v[254:255], v[252:253], v[250:251], v[254:255]
	v_div_fixup_f32 v248, v254, v248, 1.0
	v_div_fixup_f32 v249, v255, v249, 1.0
	v_mul_f32_e32 v12, v12, v242
	v_mul_f32_e32 v18, v8, v244
	v_mul_f32_e32 v8, v13, v243
	v_mul_f32_e32 v13, v9, v245
	v_mul_f32_e32 v9, v14, v246
	v_mul_f32_e32 v14, v10, v248
	v_mul_f32_e32 v10, v15, v247
	v_mul_f32_e32 v11, v11, v249
	v_cvt_pk_bf16_f32 v8, v12, v8
	v_cvt_pk_bf16_f32 v9, v9, v10
	v_cvt_pk_bf16_f32 v10, v18, v13
	v_cvt_pk_bf16_f32 v11, v14, v11
	s_waitcnt vmcnt(6)
; __device__ __forceinline__ float sigmoidf_(float x) { return 1.0f / (1.0f + __expf(-x)); }
; __device__ __forceinline__ u32x4 pack8(const f32x4 v0, const f32x4 v1) { u32x4 w; w.x = pk2(v0[0], v0[1]); w.y = pk2(v0[2], v0[3]); w.z = pk2(v1[0], v1[1]); w.w = pk2(v1[2], v1[3]); return w; }
; __device__ __forceinline__ void unpack8(const u32x4 w, f32x4& v0, f32x4& v1) { v0 = (f32x4){bflo(w.x), bfhi(w.x), bflo(w.y), bfhi(w.y)}; v1 = (f32x4){bflo(w.z), bfhi(w.z), bflo(w.w), bfhi(w.w)}; }
;     __device__ __forceinline__ void operator()(const f32x4 (&acc)[2][2][4][2], const Unit& u, int wr, int wc, int fr, int fq) const {
;     ...
;         for (int ai = 0; ai < 2; ++ai)
; #pragma unroll
;             for (int m = 0; m < 4; ++m) {
;                 bf16_t* rowp = z + (size_t)(row0 + ai * 128 + m * 16) * DIN + col0;
; #pragma unroll
;                 for (int bj = 0; bj < 2; ++bj) {
;                     const u32x4 gw = *(const u32x4*)(rowp + (MODE == 0 ? O_GB : O_GA) + bj * 128);
;                     f32x4 g0, g1; unpack8(gw, g0, g1);
;                     f32x4 v0, v1;
; #pragma unroll
;                     for (int j = 0; j < 4; ++j) { v0[j] = sigmoidf_(g0[j]) * acc[ai][bj][m][0][j]; v1[j] = sigmoidf_(g1[j]) * acc[ai][bj][m][1][j]; }
;                     if (MODE == 1) { const u32x4 mw = *(const u32x4*)(rowp + bj * 128); f32x4 m0, m1; unpack8(mw, m0, m1); v0 += m0; v1 += m1; }
;                     *(u32x4*)(rowp + bj * 128) = pack8(v0, v1); }
	v_mov_b32_e32 v12, v204
	v_mov_b32_e32 v13, v205
	v_mov_b32_e32 v14, v206
	v_mov_b32_e32 v15, v207
	s_mov_b32 s100, 0xbfb8aa3b
	v_lshlrev_b32_e32 v242, 16, v12
	v_and_b32_e32 v243, 0xffff0000, v12
	v_lshlrev_b32_e32 v244, 16, v14
	v_and_b32_e32 v245, 0xffff0000, v14
	v_lshlrev_b32_e32 v246, 16, v13
	v_and_b32_e32 v247, 0xffff0000, v13
	v_lshlrev_b32_e32 v248, 16, v15
	v_and_b32_e32 v249, 0xffff0000, v15
	v_pk_mul_f32 v[242:243], v[242:243], s[100:101] op_sel_hi:[1,0]
	v_pk_mul_f32 v[244:245], v[244:245], s[100:101] op_sel_hi:[1,0]
	v_pk_mul_f32 v[246:247], v[246:247], s[100:101] op_sel_hi:[1,0]
	v_pk_mul_f32 v[248:249], v[248:249], s[100:101] op_sel_hi:[1,0]
	v_exp_f32_e32 v242, v242
	v_exp_f32_e32 v243, v243
	v_exp_f32_e32 v244, v244
	v_exp_f32_e32 v245, v245
	v_exp_f32_e32 v246, v246
	v_exp_f32_e32 v247, v247
	v_exp_f32_e32 v248, v248
	v_exp_f32_e32 v249, v249
	s_nop 0
	v_pk_add_f32 v[242:243], v[242:243], 1.0 op_sel_hi:[1,0]
	v_pk_add_f32 v[244:245], v[244:245], 1.0 op_sel_hi:[1,0]
	v_pk_add_f32 v[246:247], v[246:247], 1.0 op_sel_hi:[1,0]
	v_pk_add_f32 v[248:249], v[248:249], 1.0 op_sel_hi:[1,0]
	v_rcp_f32_e32 v250, v242
	v_rcp_f32_e32 v251, v243
	s_nop 0
	v_pk_fma_f32 v[252:253], v[242:243], v[250:251], 1.0 op_sel_hi:[1,1,0] neg_lo:[1,0,0] neg_hi:[1,0,0]
	v_pk_fma_f32 v[250:251], v[252:253], v[250:251], v[250:251]
	v_pk_fma_f32 v[252:253], v[242:243], v[250:251], 1.0 op_sel_hi:[1,1,0] neg_lo:[1,0,0] neg_hi:[1,0,0]
	v_pk_fma_f32 v[254:255], v[252:253], v[250:251], v[250:251]
	v_pk_fma_f32 v[252:253], v[242:243], v[254:255], 1.0 op_sel_hi:[1,1,0] neg_lo:[1,0,0] neg_hi:[1,0,0]
	v_pk_fma_f32 v[254:255], v[252:253], v[250:251], v[254:255]
	v_div_fixup_f32 v242, v254, v242, 1.0
	v_div_fixup_f32 v243, v255, v243, 1.0
	v_rcp_f32_e32 v250, v244
	v_rcp_f32_e32 v251, v245
	s_nop 0
	v_pk_fma_f32 v[252:253], v[244:245], v[250:251], 1.0 op_sel_hi:[1,1,0] neg_lo:[1,0,0] neg_hi:[1,0,0]
	v_pk_fma_f32 v[250:251], v[252:253], v[250:251], v[250:251]
	v_pk_fma_f32 v[252:253], v[244:245], v[250:251], 1.0 op_sel_hi:[1,1,0] neg_lo:[1,0,0] neg_hi:[1,0,0]
	v_pk_fma_f32 v[254:255], v[252:253], v[250:251], v[250:251]
	v_pk_fma_f32 v[252:253], v[244:245], v[254:255], 1.0 op_sel_hi:[1,1,0] neg_lo:[1,0,0] neg_hi:[1,0,0]
	v_pk_fma_f32 v[254:255], v[252:253], v[250:251], v[254:255]
	v_div_fixup_f32 v244, v254, v244, 1.0
	v_div_fixup_f32 v245, v255, v245, 1.0
	v_rcp_f32_e32 v250, v246
	v_rcp_f32_e32 v251, v247
	s_nop 0
	v_pk_fma_f32 v[252:253], v[246:247], v[250:251], 1.0 op_sel_hi:[1,1,0] neg_lo:[1,0,0] neg_hi:[1,0,0]
	v_pk_fma_f32 v[250:251], v[252:253], v[250:251], v[250:251]
	v_pk_fma_f32 v[252:253], v[246:247], v[250:251], 1.0 op_sel_hi:[1,1,0] neg_lo:[1,0,0] neg_hi:[1,0,0]
	v_pk_fma_f32 v[254:255], v[252:253], v[250:251], v[250:251]
	v_pk_fma_f32 v[252:253], v[246:247], v[254:255], 1.0 op_sel_hi:[1,1,0] neg_lo:[1,0,0] neg_hi:[1,0,0]
	v_pk_fma_f32 v[254:255], v[252:253], v[250:251], v[254:255]
	v_div_fixup_f32 v246, v254, v246, 1.0
	v_div_fixup_f32 v247, v255, v247, 1.0
	v_rcp_f32_e32 v250, v248
	v_rcp_f32_e32 v251, v249
	s_nop 0
	v_pk_fma_f32 v[252:253], v[248:249], v[250:251], 1.0 op_sel_hi:[1,1,0] neg_lo:[1,0,0] neg_hi:[1,0,0]
	v_pk_fma_f32 v[250:251], v[252:253], v[250:251], v[250:251]
	v_pk_fma_f32 v[252:253], v[248:249], v[250:251], 1.0 op_sel_hi:[1,1,0] neg_lo:[1,0,0] neg_hi:[1,0,0]
	v_pk_fma_f32 v[254:255], v[252:253], v[250:251], v[250:251]
	v_pk_fma_f32 v[252:253], v[248:249], v[254:255], 1.0 op_sel_hi:[1,1,0] neg_lo:[1,0,0] neg_hi:[1,0,0]
	v_pk_fma_f32 v[254:255], v[252:253], v[250:251], v[254:255]
	v_div_fixup_f32 v248, v254, v248, 1.0
	v_div_fixup_f32 v249, v255, v249, 1.0
	global_store_dwordx4 v[16:17], v[8:11], off
	s_nop 0
	v_mul_f32_e32 v4, v4, v242
	v_mul_f32_e32 v8, v0, v244
	v_mul_f32_e32 v0, v5, v243
	v_mul_f32_e32 v5, v1, v245
	v_mul_f32_e32 v1, v6, v246
	v_mul_f32_e32 v6, v2, v248
	v_mul_f32_e32 v2, v7, v247
	v_mul_f32_e32 v3, v3, v249
	s_and_b64 vcc, exec, s[10:11]
	s_mov_b32 s7, s28
	s_mov_b32 s6, s63
	v_cvt_pk_bf16_f32 v0, v4, v0
	v_cvt_pk_bf16_f32 v1, v1, v2
	v_cvt_pk_bf16_f32 v2, v8, v5
	v_cvt_pk_bf16_f32 v3, v6, v3
	global_store_dwordx4 v[16:17], v[0:3], off offset:256
	s_cbranch_vccz .LBB0_622
	s_waitcnt vmcnt(0)
	s_cmpk_gt_u32 s36, 0xff
	s_cbranch_scc1 .LBB0_631
	s_barrier

; #define PG8_STAGE(bufoff, gbase, voff) do { _Pragma("unroll") for (int _i = 0; _i < 2; ++_i) \
;         __builtin_amdgcn_global_load_lds((const unsigned*)((const char*)(gbase) + (voff)[_i]), (LAS unsigned*)(lds + (bufoff) + ldsw + _i * 8192), 16, 0, 0); } while (0)
; #define PG8_LDA(dst, b, h) do { _Pragma("unroll") for (int m = 0; m < 4; ++m) _Pragma("unroll") for (int k = 0; k < 2; ++k) dst[m][k] = *(const LAS bf16x8*)(lds + PG8_SA(b, h) + aoff + m * 2048 + k * 1024); } while (0)
; #define PG8_LDB(dst, b, h) do { _Pragma("unroll") for (int n = 0; n < 2; ++n) _Pragma("unroll") for (int k = 0; k < 2; ++k) dst[n][k] = *(const LAS bf16x8*)(lds + PG8_SB(b, h) + boff + n * 2048 + k * 1024); } while (0)
; #define PG8_MMA(ai, bj, At, Bt) do { __builtin_amdgcn_s_setprio(1); _Pragma("unroll") for (int m = 0; m < 4; ++m) _Pragma("unroll") for (int n = 0; n < 2; ++n) _Pragma("unroll") for (int k = 0; k < 2; ++k) \
;         acc[ai][bj][m][n] = __builtin_amdgcn_mfma_f32_16x16x32_bf16(Bt[n][k], At[m][k], acc[ai][bj][m][n], 0, 0, 0); __builtin_amdgcn_s_setprio(0); } while (0)
; #define PG8_WAIT_L(n) asm volatile("s_waitcnt lgkmcnt(" #n ")" ::: "memory")
; #define PG8_BAR __builtin_amdgcn_s_barrier()
; #define PG8_SCHED __builtin_amdgcn_sched_barrier(0)
;     ...
;             PG8_LDB(B0, 0, 0); PG8_SCHED; PG8_LDA(At, 0, 0); PG8_STAGE(PG8_SA(1, 1), a1 + hA, voffA);
;             PG8_WAIT_L(8); PG8_BAR; PG8_WAIT_L(0); PG8_MMA(0, 0, At, B0); PG8_BAR; PG8_SCHED;
;             PG8_LDB(B1, 0, 1); PG8_STAGE(PG8_SB(0, 0), b2, voffB);
;             PG8_BAR; PG8_WAIT_L(0); PG8_MMA(0, 1, At, B1); PG8_BAR;
;             PG8_LDA(At, 0, 1); PG8_STAGE(PG8_SA(0, 0), a2, voffA);
;             PG8_BAR; PG8_WAIT_L(0); PG8_MMA(1, 0, At, B0); PG8_BAR; PG8_SCHED;
.LBB0_700:
	ds_read_b128 v[146:149], v159
	ds_read_b128 v[150:153], v159 offset:1024
	ds_read_b128 v[162:165], v159 offset:2048
	ds_read_b128 v[170:173], v159 offset:3072
	s_add_u32 s16, s14, 0xfffe0080
	s_addc_u32 s17, s15, -1
	s_cmp_eq_u32 s41, 4
	s_cselect_b32 s19, s7, s17
	s_cselect_b32 s18, s8, s16
	s_cselect_b32 s17, s9, s33
	s_cselect_b32 s16, s20, s21
	v_lshl_add_u64 v[154:155], s[14:15], 0, v[138:139]
	s_add_i32 m0, s67, 0xc000
	ds_read_b128 v[174:177], v160
	ds_read_b128 v[178:181], v160 offset:1024
	ds_read_b128 v[182:185], v160 offset:2048
	ds_read_b128 v[186:189], v160 offset:3072
	ds_read_b128 v[190:193], v160 offset:4096
	ds_read_b128 v[194:197], v160 offset:5120
	ds_read_b128 v[198:201], v160 offset:6144
	ds_read_b128 v[202:205], v160 offset:7168
	global_load_lds_dwordx4 v[154:155], off
	v_lshl_add_u64 v[154:155], s[14:15], 0, v[136:137]
	s_add_i32 m0, s67, 0xe000
	s_nop 0
	global_load_lds_dwordx4 v[154:155], off
	s_waitcnt lgkmcnt(8)
	s_barrier
	s_waitcnt lgkmcnt(0)
	s_setprio 1
	s_waitcnt lgkmcnt(0)
	v_mfma_f32_16x16x32_bf16 v[124:127], v[146:149], v[174:177], v[124:127]
	v_mfma_f32_16x16x32_bf16 v[120:123], v[162:165], v[174:177], v[120:123]
	v_mfma_f32_16x16x32_bf16 v[108:111], v[146:149], v[182:185], v[108:111]
	v_mfma_f32_16x16x32_bf16 v[104:107], v[162:165], v[182:185], v[104:107]
	v_mfma_f32_16x16x32_bf16 v[92:95], v[146:149], v[190:193], v[92:95]
	v_mfma_f32_16x16x32_bf16 v[88:91], v[162:165], v[190:193], v[88:91]
	v_mfma_f32_16x16x32_bf16 v[76:79], v[146:149], v[198:201], v[76:79]
	v_mfma_f32_16x16x32_bf16 v[72:75], v[162:165], v[198:201], v[72:75]
	v_mfma_f32_16x16x32_bf16 v[124:127], v[150:153], v[178:181], v[124:127]
	v_mfma_f32_16x16x32_bf16 v[120:123], v[170:173], v[178:181], v[120:123]
	v_mfma_f32_16x16x32_bf16 v[108:111], v[150:153], v[186:189], v[108:111]
	v_mfma_f32_16x16x32_bf16 v[104:107], v[170:173], v[186:189], v[104:107]
	v_mfma_f32_16x16x32_bf16 v[92:95], v[150:153], v[194:197], v[92:95]
	v_mfma_f32_16x16x32_bf16 v[88:91], v[170:173], v[194:197], v[88:91]
	v_mfma_f32_16x16x32_bf16 v[76:79], v[150:153], v[202:205], v[76:79]
	v_mfma_f32_16x16x32_bf16 v[72:75], v[170:173], v[202:205], v[72:75]
	s_setprio 0
	s_barrier
	s_add_i32 s42, s75, s66
	v_lshl_add_u64 v[154:155], s[16:17], 0, v[130:131]
	s_mov_b32 m0, s42
	ds_read_b128 v[206:209], v161
	ds_read_b128 v[210:213], v161 offset:1024
	ds_read_b128 v[214:217], v161 offset:2048
	ds_read_b128 v[218:221], v161 offset:3072
	global_load_lds_dwordx4 v[154:155], off
	v_lshl_add_u64 v[222:223], s[16:17], 0, v[134:135]
	s_add_i32 m0, s42, 0x2000
	s_nop 0
	global_load_lds_dwordx4 v[222:223], off
	s_barrier
	s_waitcnt lgkmcnt(0)
	s_setprio 1
	s_waitcnt lgkmcnt(0)
	v_mfma_f32_16x16x32_bf16 v[116:119], v[206:209], v[174:177], v[116:119]
	v_mfma_f32_16x16x32_bf16 v[112:115], v[214:217], v[174:177], v[112:115]
	v_mfma_f32_16x16x32_bf16 v[100:103], v[206:209], v[182:185], v[100:103]
	v_mfma_f32_16x16x32_bf16 v[96:99], v[214:217], v[182:185], v[96:99]
	v_mfma_f32_16x16x32_bf16 v[84:87], v[206:209], v[190:193], v[84:87]
	v_mfma_f32_16x16x32_bf16 v[80:83], v[214:217], v[190:193], v[80:83]
	v_mfma_f32_16x16x32_bf16 v[68:71], v[206:209], v[198:201], v[68:71]
	v_mfma_f32_16x16x32_bf16 v[64:67], v[214:217], v[198:201], v[64:67]
	v_mfma_f32_16x16x32_bf16 v[116:119], v[210:213], v[178:181], v[116:119]
	v_mfma_f32_16x16x32_bf16 v[112:115], v[218:221], v[178:181], v[112:115]
	v_mfma_f32_16x16x32_bf16 v[100:103], v[210:213], v[186:189], v[100:103]
	v_mfma_f32_16x16x32_bf16 v[96:99], v[218:221], v[186:189], v[96:99]
	v_mfma_f32_16x16x32_bf16 v[84:87], v[210:213], v[194:197], v[84:87]
	v_mfma_f32_16x16x32_bf16 v[80:83], v[218:221], v[194:197], v[80:83]
	v_mfma_f32_16x16x32_bf16 v[68:71], v[210:213], v[202:205], v[68:71]
	v_mfma_f32_16x16x32_bf16 v[64:67], v[218:221], v[202:205], v[64:67]
	s_setprio 0
	s_mov_b32 m0, s67
	v_lshl_add_u64 v[224:225], s[18:19], 0, v[128:129]
	s_barrier
	ds_read_b128 v[174:177], v160 offset:16384
	ds_read_b128 v[178:181], v160 offset:17408
	ds_read_b128 v[182:185], v160 offset:18432
	ds_read_b128 v[186:189], v160 offset:19456
	ds_read_b128 v[190:193], v160 offset:20480
	ds_read_b128 v[194:197], v160 offset:21504
	ds_read_b128 v[198:201], v160 offset:22528
	ds_read_b128 v[202:205], v160 offset:23552
	global_load_lds_dwordx4 v[224:225], off
	v_lshl_add_u64 v[226:227], s[18:19], 0, v[132:133]
	s_mov_b32 m0, s68
	s_nop 0
	global_load_lds_dwordx4 v[226:227], off
	s_barrier
	s_waitcnt lgkmcnt(0)
	s_setprio 1
	s_waitcnt lgkmcnt(0)
	v_mfma_f32_16x16x32_bf16 v[60:63], v[146:149], v[174:177], v[60:63]
	v_mfma_f32_16x16x32_bf16 v[56:59], v[162:165], v[174:177], v[56:59]
	v_mfma_f32_16x16x32_bf16 v[44:47], v[146:149], v[182:185], v[44:47]
	v_mfma_f32_16x16x32_bf16 v[40:43], v[162:165], v[182:185], v[40:43]
	v_mfma_f32_16x16x32_bf16 v[28:31], v[146:149], v[190:193], v[28:31]
	v_mfma_f32_16x16x32_bf16 v[24:27], v[162:165], v[190:193], v[24:27]
	v_mfma_f32_16x16x32_bf16 v[12:15], v[146:149], v[198:201], v[12:15]
	v_mfma_f32_16x16x32_bf16 v[8:11], v[162:165], v[198:201], v[8:11]
	v_mfma_f32_16x16x32_bf16 v[60:63], v[150:153], v[178:181], v[60:63]
	v_mfma_f32_16x16x32_bf16 v[56:59], v[170:173], v[178:181], v[56:59]
	v_mfma_f32_16x16x32_bf16 v[44:47], v[150:153], v[186:189], v[44:47]
	v_mfma_f32_16x16x32_bf16 v[40:43], v[170:173], v[186:189], v[40:43]
	v_mfma_f32_16x16x32_bf16 v[28:31], v[150:153], v[194:197], v[28:31]
	v_mfma_f32_16x16x32_bf16 v[24:27], v[170:173], v[194:197], v[24:27]
	v_mfma_f32_16x16x32_bf16 v[12:15], v[150:153], v[202:205], v[12:15]
	v_mfma_f32_16x16x32_bf16 v[8:11], v[170:173], v[202:205], v[8:11]
	s_setprio 0
	s_barrier
; #define PG8_STAGE(bufoff, gbase, voff) do { _Pragma("unroll") for (int _i = 0; _i < 2; ++_i) \
;         __builtin_amdgcn_global_load_lds((const unsigned*)((const char*)(gbase) + (voff)[_i]), (LAS unsigned*)(lds + (bufoff) + ldsw + _i * 8192), 16, 0, 0); } while (0)
; #define PG8_LDA(dst, b, h) do { _Pragma("unroll") for (int m = 0; m < 4; ++m) _Pragma("unroll") for (int k = 0; k < 2; ++k) dst[m][k] = *(const LAS bf16x8*)(lds + PG8_SA(b, h) + aoff + m * 2048 + k * 1024); } while (0)
; #define PG8_LDB(dst, b, h) do { _Pragma("unroll") for (int n = 0; n < 2; ++n) _Pragma("unroll") for (int k = 0; k < 2; ++k) dst[n][k] = *(const LAS bf16x8*)(lds + PG8_SB(b, h) + boff + n * 2048 + k * 1024); } while (0)
; #define PG8_MMA(ai, bj, At, Bt) do { __builtin_amdgcn_s_setprio(1); _Pragma("unroll") for (int m = 0; m < 4; ++m) _Pragma("unroll") for (int n = 0; n < 2; ++n) _Pragma("unroll") for (int k = 0; k < 2; ++k) \
;         acc[ai][bj][m][n] = __builtin_amdgcn_mfma_f32_16x16x32_bf16(Bt[n][k], At[m][k], acc[ai][bj][m][n], 0, 0, 0); __builtin_amdgcn_s_setprio(0); } while (0)
; #define PG8_WAIT_V(n) asm volatile("s_waitcnt vmcnt(" #n ")" ::: "memory")
; #define PG8_WAIT_L(n) asm volatile("s_waitcnt lgkmcnt(" #n ")" ::: "memory")
; #define PG8_BAR __builtin_amdgcn_s_barrier()
; #define PG8_SCHED __builtin_amdgcn_sched_barrier(0)
;     ...
;             PG8_STAGE(PG8_SB(0, 1), b2 + hB, voffB);
;             PG8_WAIT_V(6); PG8_BAR; PG8_MMA(1, 1, At, B1); PG8_BAR;
;             PG8_LDB(B0, 1, 0); PG8_SCHED; PG8_LDA(At, 1, 0); PG8_STAGE(PG8_SA(0, 1), a2 + hA, voffA);
;             PG8_WAIT_L(8); PG8_BAR; PG8_WAIT_L(0); PG8_MMA(0, 0, At, B0); PG8_BAR; PG8_SCHED;
;             PG8_LDB(B1, 1, 1); PG8_STAGE(PG8_SB(1, 0), b3, voffB);
;             PG8_BAR; PG8_WAIT_L(0); PG8_MMA(0, 1, At, B1); PG8_BAR;
;             PG8_LDA(At, 1, 1); PG8_STAGE(PG8_SA(1, 0), a3, voffA);
;             PG8_BAR; PG8_WAIT_L(0); PG8_MMA(1, 0, At, B0); PG8_BAR; PG8_SCHED;
	s_add_u32 s42, s16, 0x20000
	s_addc_u32 s43, s17, 0
	s_add_i32 s44, s76, s66
	v_lshl_add_u64 v[146:147], s[42:43], 0, v[130:131]
	s_mov_b32 m0, s44
	s_nop 0
	global_load_lds_dwordx4 v[146:147], off
	v_lshl_add_u64 v[146:147], s[42:43], 0, v[134:135]
	s_add_i32 m0, s44, 0x2000
	s_nop 0
	global_load_lds_dwordx4 v[146:147], off
	s_waitcnt vmcnt(6)
	s_barrier
	s_setprio 1
	v_mfma_f32_16x16x32_bf16 v[52:55], v[206:209], v[174:177], v[52:55]
	v_mfma_f32_16x16x32_bf16 v[48:51], v[214:217], v[174:177], v[48:51]
	v_mfma_f32_16x16x32_bf16 v[36:39], v[206:209], v[182:185], v[36:39]
	v_mfma_f32_16x16x32_bf16 v[32:35], v[214:217], v[182:185], v[32:35]
	v_mfma_f32_16x16x32_bf16 v[20:23], v[206:209], v[190:193], v[20:23]
	v_mfma_f32_16x16x32_bf16 v[16:19], v[214:217], v[190:193], v[16:19]
	v_mfma_f32_16x16x32_bf16 v[4:7], v[206:209], v[198:201], v[4:7]
	v_mfma_f32_16x16x32_bf16 v[0:3], v[214:217], v[198:201], v[0:3]
	v_mfma_f32_16x16x32_bf16 v[52:55], v[210:213], v[178:181], v[52:55]
	v_mfma_f32_16x16x32_bf16 v[48:51], v[218:221], v[178:181], v[48:51]
	v_mfma_f32_16x16x32_bf16 v[36:39], v[210:213], v[186:189], v[36:39]
	v_mfma_f32_16x16x32_bf16 v[32:35], v[218:221], v[186:189], v[32:35]
	v_mfma_f32_16x16x32_bf16 v[20:23], v[210:213], v[194:197], v[20:23]
	v_mfma_f32_16x16x32_bf16 v[16:19], v[218:221], v[194:197], v[16:19]
	v_mfma_f32_16x16x32_bf16 v[4:7], v[210:213], v[202:205], v[4:7]
	v_mfma_f32_16x16x32_bf16 v[0:3], v[218:221], v[202:205], v[0:3]
	s_setprio 0
	s_add_i32 s42, 0, 0x18000
	v_add_u32_e32 v170, s42, v157
	s_barrier
	ds_read_b128 v[146:149], v170
	ds_read_b128 v[150:153], v170 offset:1024
	ds_read_b128 v[162:165], v170 offset:2048
	ds_read_b128 v[170:173], v170 offset:3072
	s_add_u32 s18, s18, 0x20000
	s_addc_u32 s19, s19, 0
	s_mov_b32 m0, s69
	v_lshl_add_u64 v[206:207], s[18:19], 0, v[128:129]
	ds_read_b128 v[174:177], v160 offset:32768
	ds_read_b128 v[178:181], v160 offset:33792
	ds_read_b128 v[182:185], v160 offset:34816
	ds_read_b128 v[186:189], v160 offset:35840
	ds_read_b128 v[190:193], v160 offset:36864
	ds_read_b128 v[194:197], v160 offset:37888
	ds_read_b128 v[198:201], v160 offset:38912
	ds_read_b128 v[202:205], v160 offset:39936
	global_load_lds_dwordx4 v[206:207], off
	v_lshl_add_u64 v[206:207], s[18:19], 0, v[132:133]
	s_mov_b32 m0, s70
	s_nop 0
	global_load_lds_dwordx4 v[206:207], off
	s_waitcnt lgkmcnt(8)
	s_barrier
	s_waitcnt lgkmcnt(0)
	s_setprio 1
	s_waitcnt lgkmcnt(0)
	v_mfma_f32_16x16x32_bf16 v[124:127], v[146:149], v[174:177], v[124:127]
	v_mfma_f32_16x16x32_bf16 v[120:123], v[162:165], v[174:177], v[120:123]
	v_mfma_f32_16x16x32_bf16 v[108:111], v[146:149], v[182:185], v[108:111]
	v_mfma_f32_16x16x32_bf16 v[104:107], v[162:165], v[182:185], v[104:107]
	v_mfma_f32_16x16x32_bf16 v[92:95], v[146:149], v[190:193], v[92:95]
	v_mfma_f32_16x16x32_bf16 v[88:91], v[162:165], v[190:193], v[88:91]
	v_mfma_f32_16x16x32_bf16 v[76:79], v[146:149], v[198:201], v[76:79]
	v_mfma_f32_16x16x32_bf16 v[72:75], v[162:165], v[198:201], v[72:75]
	v_mfma_f32_16x16x32_bf16 v[124:127], v[150:153], v[178:181], v[124:127]
	v_mfma_f32_16x16x32_bf16 v[120:123], v[170:173], v[178:181], v[120:123]
	v_mfma_f32_16x16x32_bf16 v[108:111], v[150:153], v[186:189], v[108:111]
	v_mfma_f32_16x16x32_bf16 v[104:107], v[170:173], v[186:189], v[104:107]
	v_mfma_f32_16x16x32_bf16 v[92:95], v[150:153], v[194:197], v[92:95]
	v_mfma_f32_16x16x32_bf16 v[88:91], v[170:173], v[194:197], v[88:91]
	v_mfma_f32_16x16x32_bf16 v[76:79], v[150:153], v[202:205], v[76:79]
	v_mfma_f32_16x16x32_bf16 v[72:75], v[170:173], v[202:205], v[72:75]
	s_setprio 0
	s_barrier
	s_add_i32 s18, 0, 0x1c000
	s_add_i32 s19, s42, s66
	v_add_u32_e32 v218, s18, v157
	v_lshl_add_u64 v[154:155], v[154:155], 0, s[54:55]
	s_mov_b32 m0, s19
	ds_read_b128 v[206:209], v218
	ds_read_b128 v[210:213], v218 offset:1024
	ds_read_b128 v[214:217], v218 offset:2048
	ds_read_b128 v[218:221], v218 offset:3072
	global_load_lds_dwordx4 v[154:155], off
	v_lshl_add_u64 v[154:155], v[222:223], 0, s[54:55]
	s_add_i32 m0, s19, 0x2000
	s_nop 0
	global_load_lds_dwordx4 v[154:155], off
	s_barrier
	s_waitcnt lgkmcnt(0)
	s_setprio 1
	s_waitcnt lgkmcnt(0)
	v_mfma_f32_16x16x32_bf16 v[116:119], v[206:209], v[174:177], v[116:119]
	v_mfma_f32_16x16x32_bf16 v[112:115], v[214:217], v[174:177], v[112:115]
	v_mfma_f32_16x16x32_bf16 v[100:103], v[206:209], v[182:185], v[100:103]
	v_mfma_f32_16x16x32_bf16 v[96:99], v[214:217], v[182:185], v[96:99]
	v_mfma_f32_16x16x32_bf16 v[84:87], v[206:209], v[190:193], v[84:87]
	v_mfma_f32_16x16x32_bf16 v[80:83], v[214:217], v[190:193], v[80:83]
	v_mfma_f32_16x16x32_bf16 v[68:71], v[206:209], v[198:201], v[68:71]
	v_mfma_f32_16x16x32_bf16 v[64:67], v[214:217], v[198:201], v[64:67]
	v_mfma_f32_16x16x32_bf16 v[116:119], v[210:213], v[178:181], v[116:119]
	v_mfma_f32_16x16x32_bf16 v[112:115], v[218:221], v[178:181], v[112:115]
	v_mfma_f32_16x16x32_bf16 v[100:103], v[210:213], v[186:189], v[100:103]
	v_mfma_f32_16x16x32_bf16 v[96:99], v[218:221], v[186:189], v[96:99]
	v_mfma_f32_16x16x32_bf16 v[84:87], v[210:213], v[194:197], v[84:87]
	v_mfma_f32_16x16x32_bf16 v[80:83], v[218:221], v[194:197], v[80:83]
	v_mfma_f32_16x16x32_bf16 v[68:71], v[210:213], v[202:205], v[68:71]
	v_mfma_f32_16x16x32_bf16 v[64:67], v[218:221], v[202:205], v[64:67]
	s_setprio 0
	s_mov_b32 m0, s72
	v_lshl_add_u64 v[154:155], v[224:225], 0, s[54:55]
	s_barrier
	ds_read_b128 v[174:177], v160 offset:49152
	ds_read_b128 v[178:181], v160 offset:50176
	ds_read_b128 v[182:185], v160 offset:51200
	ds_read_b128 v[186:189], v160 offset:52224
	ds_read_b128 v[190:193], v160 offset:53248
	ds_read_b128 v[194:197], v160 offset:54272
	ds_read_b128 v[198:201], v160 offset:55296
	ds_read_b128 v[202:205], v160 offset:56320
	global_load_lds_dwordx4 v[154:155], off
	v_lshl_add_u64 v[154:155], v[226:227], 0, s[54:55]
	s_mov_b32 m0, s73
	s_nop 0
	global_load_lds_dwordx4 v[154:155], off
	s_barrier
; __device__ __forceinline__ float sigmoidf_(float x) { return 1.0f / (1.0f + __expf(-x)); }
; #define PG8_STAGE(bufoff, gbase, voff) do { _Pragma("unroll") for (int _i = 0; _i < 2; ++_i) \
;         __builtin_amdgcn_global_load_lds((const unsigned*)((const char*)(gbase) + (voff)[_i]), (LAS unsigned*)(lds + (bufoff) + ldsw + _i * 8192), 16, 0, 0); } while (0)
; #define PG8_MMA(ai, bj, At, Bt) do { __builtin_amdgcn_s_setprio(1); _Pragma("unroll") for (int m = 0; m < 4; ++m) _Pragma("unroll") for (int n = 0; n < 2; ++n) _Pragma("unroll") for (int k = 0; k < 2; ++k) \
;         acc[ai][bj][m][n] = __builtin_amdgcn_mfma_f32_16x16x32_bf16(Bt[n][k], At[m][k], acc[ai][bj][m][n], 0, 0, 0); __builtin_amdgcn_s_setprio(0); } while (0)
; #define PG8_WAIT_V(n) asm volatile("s_waitcnt vmcnt(" #n ")" ::: "memory")
; #define PG8_WAIT_L(n) asm volatile("s_waitcnt lgkmcnt(" #n ")" ::: "memory")
; #define PG8_BAR __builtin_amdgcn_s_barrier()
; #define PG8_SCHED __builtin_amdgcn_sched_barrier(0)
;     ...
;             PG8_BAR; PG8_WAIT_L(0); PG8_MMA(1, 0, At, B0); PG8_BAR; PG8_SCHED;
;             PG8_STAGE(PG8_SB(1, 1), b3 + hB, voffB);
;             PG8_WAIT_V(6); PG8_BAR; PG8_MMA(1, 1, At, B1); PG8_BAR;
;         }
;         E(acc, cur, wr, wc, fr, fq);
;     __device__ __forceinline__ void operator()(const f32x4 (&acc)[2][2][4][2], const Unit& u, int wr, int wc, int fr, int fq) const {
;         const __amdgpu_buffer_rsrc_t rsrc = __builtin_amdgcn_make_buffer_rsrc((void*)z, 0, T_ALL * DIN * 2, 0x00020000);
;         const int row0 = row_off + u.pm * 256 + wr * 64 + fr, col0 = u.pn * 256 + wc * 32 + 8 * fq;
; #pragma unroll
;         for (int ai = 0; ai < 2; ++ai)
; #pragma unroll
;             for (int m = 0; m < 4; ++m) {
;                 const int row = row0 + ai * 128 + m * 16;
;                 const bf16_t* rowp = z + (size_t)row * DIN + col0;
; #pragma unroll
;                 for (int bj = 0; bj < 2; ++bj) {
;                     const u32x4 gw = *(const u32x4*)(rowp + O_GA + bj * 128);
;                     f32x4 g0, g1; unpack8(gw, g0, g1);
;                     f32x4 v0, v1;
; #pragma unroll
;                     for (int j = 0; j < 4; ++j) { v0[j] = sigmoidf_(g0[j]) * acc[ai][bj][m][0][j]; v1[j] = sigmoidf_(g1[j]) * acc[ai][bj][m][1][j]; }
;                     const u32x4 mw = *(const u32x4*)(rowp + bj * 128); f32x4 m0, m1; unpack8(mw, m0, m1); v0 += m0; v1 += m1;
	s_waitcnt lgkmcnt(0)
	s_setprio 1
	s_waitcnt lgkmcnt(0)
	v_mfma_f32_16x16x32_bf16 v[60:63], v[146:149], v[174:177], v[60:63]
	v_mfma_f32_16x16x32_bf16 v[56:59], v[162:165], v[174:177], v[56:59]
	v_mfma_f32_16x16x32_bf16 v[44:47], v[146:149], v[182:185], v[44:47]
	v_mfma_f32_16x16x32_bf16 v[40:43], v[162:165], v[182:185], v[40:43]
	v_mfma_f32_16x16x32_bf16 v[28:31], v[146:149], v[190:193], v[28:31]
	v_mfma_f32_16x16x32_bf16 v[24:27], v[162:165], v[190:193], v[24:27]
	v_mfma_f32_16x16x32_bf16 v[12:15], v[146:149], v[198:201], v[12:15]
	v_mfma_f32_16x16x32_bf16 v[8:11], v[162:165], v[198:201], v[8:11]
	v_mfma_f32_16x16x32_bf16 v[60:63], v[150:153], v[178:181], v[60:63]
	v_mfma_f32_16x16x32_bf16 v[56:59], v[170:173], v[178:181], v[56:59]
	v_mfma_f32_16x16x32_bf16 v[44:47], v[150:153], v[186:189], v[44:47]
	v_mfma_f32_16x16x32_bf16 v[40:43], v[170:173], v[186:189], v[40:43]
	v_mfma_f32_16x16x32_bf16 v[28:31], v[150:153], v[194:197], v[28:31]
	v_mfma_f32_16x16x32_bf16 v[24:27], v[170:173], v[194:197], v[24:27]
	v_mfma_f32_16x16x32_bf16 v[12:15], v[150:153], v[202:205], v[12:15]
	v_mfma_f32_16x16x32_bf16 v[8:11], v[170:173], v[202:205], v[8:11]
	s_setprio 0
	s_barrier
	s_add_u32 s16, s16, 0x20080
	s_addc_u32 s17, s17, 0
	s_add_i32 s18, s18, s66
	v_lshl_add_u64 v[146:147], s[16:17], 0, v[130:131]
	s_mov_b32 m0, s18
	s_nop 0
	global_load_lds_dwordx4 v[146:147], off
	v_lshl_add_u64 v[146:147], s[16:17], 0, v[134:135]
	s_add_i32 m0, s18, 0x2000
	s_nop 0
	global_load_lds_dwordx4 v[146:147], off
	s_waitcnt vmcnt(6)
	s_barrier
	s_setprio 1
	v_mfma_f32_16x16x32_bf16 v[52:55], v[206:209], v[174:177], v[52:55]
	v_mfma_f32_16x16x32_bf16 v[48:51], v[214:217], v[174:177], v[48:51]
	v_mfma_f32_16x16x32_bf16 v[36:39], v[206:209], v[182:185], v[36:39]
	v_mfma_f32_16x16x32_bf16 v[32:35], v[214:217], v[182:185], v[32:35]
	v_mfma_f32_16x16x32_bf16 v[20:23], v[206:209], v[190:193], v[20:23]
	v_mfma_f32_16x16x32_bf16 v[16:19], v[214:217], v[190:193], v[16:19]
	v_mfma_f32_16x16x32_bf16 v[4:7], v[206:209], v[198:201], v[4:7]
	v_mfma_f32_16x16x32_bf16 v[0:3], v[214:217], v[198:201], v[0:3]
	v_mfma_f32_16x16x32_bf16 v[52:55], v[210:213], v[178:181], v[52:55]
	v_mfma_f32_16x16x32_bf16 v[48:51], v[218:221], v[178:181], v[48:51]
	v_mfma_f32_16x16x32_bf16 v[36:39], v[210:213], v[186:189], v[36:39]
	v_mfma_f32_16x16x32_bf16 v[32:35], v[218:221], v[186:189], v[32:35]
	v_mfma_f32_16x16x32_bf16 v[20:23], v[210:213], v[194:197], v[20:23]
	v_mfma_f32_16x16x32_bf16 v[16:19], v[218:221], v[194:197], v[16:19]
	v_mfma_f32_16x16x32_bf16 v[4:7], v[210:213], v[202:205], v[4:7]
	v_mfma_f32_16x16x32_bf16 v[0:3], v[218:221], v[202:205], v[0:3]
	s_setprio 0
	s_add_i32 s41, s41, 2
	s_add_u32 s21, s21, 0x100
	s_addc_u32 s33, s33, 0
	s_add_u32 s14, s14, 0x100
	s_addc_u32 s15, s15, 0
	s_cmp_gt_u32 s41, 5
	s_barrier
	s_cbranch_scc0 .LBB0_700
	v_lshl_or_b32 v146, s6, 8, v158
	v_lshl_add_u32 v162, s79, 8, v156
	v_ashrrev_i32_e32 v147, 31, v146
	v_mad_i64_i32 v[154:155], s[6:7], v162, s77, 0
	v_lshl_add_u64 v[150:151], v[154:155], 1, s[38:39]
	v_lshlrev_b64 v[148:149], 1, v[146:147]
	v_lshl_add_u64 v[150:151], v[150:151], 0, v[148:149]
	v_add_co_u32_e32 v152, vcc, 0x1000, v150
	s_nop 1
	v_addc_co_u32_e32 v153, vcc, 0, v151, vcc
	v_subrev_u32_e32 v202, s38, v150
	v_add_u32_e32 v203, 0x1200, v202
	global_load_dwordx4 v[204:207], v203, s[38:39]
	v_add_u32_e32 v203, 0x0, v202
	global_load_dwordx4 v[208:211], v203, s[38:39]
	v_add_u32_e32 v203, 0x1300, v202
	global_load_dwordx4 v[212:215], v203, s[38:39]
	v_add_u32_e32 v203, 0x100, v202
	global_load_dwordx4 v[216:219], v203, s[38:39]
	v_add_u32_e32 v203, 0x23200, v202
	global_load_dwordx4 v[232:235], v203, s[38:39]
	v_add_u32_e32 v203, 0x22000, v202
	global_load_dwordx4 v[236:239], v203, s[38:39]
	s_waitcnt vmcnt(4)
	v_mov_b32_e32 v170, v204
	v_mov_b32_e32 v171, v205
	v_mov_b32_e32 v172, v206
	v_mov_b32_e32 v173, v207
	v_mov_b32_e32 v174, v208
	v_mov_b32_e32 v175, v209
	v_mov_b32_e32 v176, v210
	v_mov_b32_e32 v177, v211
	v_add_u32_e32 v203, 0x23300, v202
	global_load_dwordx4 v[204:207], v203, s[38:39]
	v_add_u32_e32 v203, 0x22100, v202
	global_load_dwordx4 v[208:211], v203, s[38:39]
	s_mov_b32 s100, 0xbfb8aa3b
	v_lshlrev_b32_e32 v242, 16, v170
	v_and_b32_e32 v243, 0xffff0000, v170
	v_lshlrev_b32_e32 v244, 16, v172
	v_and_b32_e32 v245, 0xffff0000, v172
	v_lshlrev_b32_e32 v246, 16, v171
	v_and_b32_e32 v247, 0xffff0000, v171
	v_lshlrev_b32_e32 v248, 16, v173
	v_and_b32_e32 v249, 0xffff0000, v173
	v_pk_mul_f32 v[242:243], v[242:243], s[100:101] op_sel_hi:[1,0]
	v_pk_mul_f32 v[244:245], v[244:245], s[100:101] op_sel_hi:[1,0]
	v_pk_mul_f32 v[246:247], v[246:247], s[100:101] op_sel_hi:[1,0]
	v_pk_mul_f32 v[248:249], v[248:249], s[100:101] op_sel_hi:[1,0]
	v_exp_f32_e32 v242, v242
	v_exp_f32_e32 v243, v243
	v_exp_f32_e32 v244, v244
	v_exp_f32_e32 v245, v245
	v_exp_f32_e32 v246, v246
	v_exp_f32_e32 v247, v247
	v_exp_f32_e32 v248, v248
	v_exp_f32_e32 v249, v249
	s_nop 0
	v_pk_add_f32 v[242:243], v[242:243], 1.0 op_sel_hi:[1,0]
	v_pk_add_f32 v[244:245], v[244:245], 1.0 op_sel_hi:[1,0]
	v_pk_add_f32 v[246:247], v[246:247], 1.0 op_sel_hi:[1,0]
	v_pk_add_f32 v[248:249], v[248:249], 1.0 op_sel_hi:[1,0]
	v_rcp_f32_e32 v250, v242
	v_rcp_f32_e32 v251, v243
	s_nop 0
	v_pk_fma_f32 v[252:253], v[242:243], v[250:251], 1.0 op_sel_hi:[1,1,0] neg_lo:[1,0,0] neg_hi:[1,0,0]
	v_pk_fma_f32 v[250:251], v[252:253], v[250:251], v[250:251]
	v_pk_fma_f32 v[252:253], v[242:243], v[250:251], 1.0 op_sel_hi:[1,1,0] neg_lo:[1,0,0] neg_hi:[1,0,0]
	v_pk_fma_f32 v[254:255], v[252:253], v[250:251], v[250:251]
	v_pk_fma_f32 v[252:253], v[242:243], v[254:255], 1.0 op_sel_hi:[1,1,0] neg_lo:[1,0,0] neg_hi:[1,0,0]
; __device__ __forceinline__ float sigmoidf_(float x) { return 1.0f / (1.0f + __expf(-x)); }
; __device__ __forceinline__ u32x4 pack8(const f32x4 v0, const f32x4 v1) { u32x4 w; w.x = pk2(v0[0], v0[1]); w.y = pk2(v0[2], v0[3]); w.z = pk2(v1[0], v1[1]); w.w = pk2(v1[2], v1[3]); return w; }
; __device__ __forceinline__ void unpack8(const u32x4 w, f32x4& v0, f32x4& v1) { v0 = (f32x4){bflo(w.x), bfhi(w.x), bflo(w.y), bfhi(w.y)}; v1 = (f32x4){bflo(w.z), bfhi(w.z), bflo(w.w), bfhi(w.w)}; }
;     __device__ __forceinline__ void operator()(const f32x4 (&acc)[2][2][4][2], const Unit& u, int wr, int wc, int fr, int fq) const {
;     ...
;         for (int ai = 0; ai < 2; ++ai)
; #pragma unroll
;             for (int m = 0; m < 4; ++m) {
;                 const int row = row0 + ai * 128 + m * 16;
;                 const bf16_t* rowp = z + (size_t)row * DIN + col0;
; #pragma unroll
;                 for (int bj = 0; bj < 2; ++bj) {
;                     const u32x4 gw = *(const u32x4*)(rowp + O_GA + bj * 128);
;                     f32x4 g0, g1; unpack8(gw, g0, g1);
;                     f32x4 v0, v1;
; #pragma unroll
;                     for (int j = 0; j < 4; ++j) { v0[j] = sigmoidf_(g0[j]) * acc[ai][bj][m][0][j]; v1[j] = sigmoidf_(g1[j]) * acc[ai][bj][m][1][j]; }
;                     const u32x4 mw = *(const u32x4*)(rowp + bj * 128); f32x4 m0, m1; unpack8(mw, m0, m1); v0 += m0; v1 += m1;
;                     __builtin_amdgcn_raw_buffer_store_b128(pack8(v0, v1), rsrc, (unsigned)(((size_t)row * DIN + col0 + bj * 128) * 2), 0, 16  ); }
	v_pk_fma_f32 v[254:255], v[252:253], v[250:251], v[254:255]
	v_div_fixup_f32 v242, v254, v242, 1.0
	v_div_fixup_f32 v243, v255, v243, 1.0
	v_rcp_f32_e32 v250, v244
	v_rcp_f32_e32 v251, v245
	s_nop 0
	v_pk_fma_f32 v[252:253], v[244:245], v[250:251], 1.0 op_sel_hi:[1,1,0] neg_lo:[1,0,0] neg_hi:[1,0,0]
	v_pk_fma_f32 v[250:251], v[252:253], v[250:251], v[250:251]
	v_pk_fma_f32 v[252:253], v[244:245], v[250:251], 1.0 op_sel_hi:[1,1,0] neg_lo:[1,0,0] neg_hi:[1,0,0]
	v_pk_fma_f32 v[254:255], v[252:253], v[250:251], v[250:251]
	v_pk_fma_f32 v[252:253], v[244:245], v[254:255], 1.0 op_sel_hi:[1,1,0] neg_lo:[1,0,0] neg_hi:[1,0,0]
	v_pk_fma_f32 v[254:255], v[252:253], v[250:251], v[254:255]
	v_div_fixup_f32 v244, v254, v244, 1.0
	v_div_fixup_f32 v245, v255, v245, 1.0
	v_rcp_f32_e32 v250, v246
	v_rcp_f32_e32 v251, v247
	s_nop 0
	v_pk_fma_f32 v[252:253], v[246:247], v[250:251], 1.0 op_sel_hi:[1,1,0] neg_lo:[1,0,0] neg_hi:[1,0,0]
	v_pk_fma_f32 v[250:251], v[252:253], v[250:251], v[250:251]
	v_pk_fma_f32 v[252:253], v[246:247], v[250:251], 1.0 op_sel_hi:[1,1,0] neg_lo:[1,0,0] neg_hi:[1,0,0]
	v_pk_fma_f32 v[254:255], v[252:253], v[250:251], v[250:251]
	v_pk_fma_f32 v[252:253], v[246:247], v[254:255], 1.0 op_sel_hi:[1,1,0] neg_lo:[1,0,0] neg_hi:[1,0,0]
	v_pk_fma_f32 v[254:255], v[252:253], v[250:251], v[254:255]
	v_div_fixup_f32 v246, v254, v246, 1.0
	v_div_fixup_f32 v247, v255, v247, 1.0
	v_rcp_f32_e32 v250, v248
	v_rcp_f32_e32 v251, v249
	s_nop 0
	v_pk_fma_f32 v[252:253], v[248:249], v[250:251], 1.0 op_sel_hi:[1,1,0] neg_lo:[1,0,0] neg_hi:[1,0,0]
	v_pk_fma_f32 v[250:251], v[252:253], v[250:251], v[250:251]
	v_pk_fma_f32 v[252:253], v[248:249], v[250:251], 1.0 op_sel_hi:[1,1,0] neg_lo:[1,0,0] neg_hi:[1,0,0]
	v_pk_fma_f32 v[254:255], v[252:253], v[250:251], v[250:251]
	v_pk_fma_f32 v[252:253], v[248:249], v[254:255], 1.0 op_sel_hi:[1,1,0] neg_lo:[1,0,0] neg_hi:[1,0,0]
	v_pk_fma_f32 v[254:255], v[252:253], v[250:251], v[254:255]
	v_div_fixup_f32 v248, v254, v248, 1.0
	v_div_fixup_f32 v249, v255, v249, 1.0
	s_mov_b64 vcc, s[14:15]
	s_mov_b64 vcc, s[16:17]
	s_mov_b64 vcc, s[18:19]
	s_mov_b64 vcc, s[20:21]
	v_lshlrev_b32_e32 v182, 16, v176
	v_and_b32_e32 v183, 0xffff0000, v176
	v_lshlrev_b32_e32 v180, 16, v174
	v_and_b32_e32 v181, 0xffff0000, v174
	v_lshlrev_b32_e32 v176, 16, v177
	v_and_b32_e32 v177, 0xffff0000, v177
	v_lshlrev_b32_e32 v174, 16, v175
	v_and_b32_e32 v175, 0xffff0000, v175
	v_pk_fma_f32 v[124:125], v[124:125], v[242:243], v[180:181]
	v_pk_fma_f32 v[164:165], v[122:123], v[248:249], v[176:177]
	v_pk_fma_f32 v[122:123], v[120:121], v[244:245], v[182:183]
	v_add_lshl_u32 v147, v146, v154, 1
	v_pk_fma_f32 v[126:127], v[126:127], v[246:247], v[174:175]
	v_cvt_pk_bf16_f32 v120, v124, v125
	s_nop 0
	v_cvt_pk_bf16_f32 v121, v126, v127
	v_cvt_pk_bf16_f32 v122, v122, v123
	v_cvt_pk_bf16_f32 v123, v164, v165
	buffer_store_dwordx4 v[120:123], v147, s[24:27], 0 offen sc1
	s_nop 0
	s_waitcnt vmcnt(5)
	v_mov_b32_e32 v120, v212
	v_mov_b32_e32 v121, v213
	v_mov_b32_e32 v122, v214
	v_mov_b32_e32 v123, v215
	v_mov_b32_e32 v124, v216
	v_mov_b32_e32 v125, v217
	v_mov_b32_e32 v126, v218
	v_mov_b32_e32 v127, v219
	v_add_u32_e32 v203, 0x45200, v202
	global_load_dwordx4 v[212:215], v203, s[38:39]
	v_add_u32_e32 v203, 0x44000, v202
	global_load_dwordx4 v[216:219], v203, s[38:39]
	s_mov_b32 s100, 0xbfb8aa3b
	v_lshlrev_b32_e32 v242, 16, v120
	v_and_b32_e32 v243, 0xffff0000, v120
	v_lshlrev_b32_e32 v244, 16, v122
	v_and_b32_e32 v245, 0xffff0000, v122
	v_lshlrev_b32_e32 v246, 16, v121
	v_and_b32_e32 v247, 0xffff0000, v121
	v_lshlrev_b32_e32 v248, 16, v123
	v_and_b32_e32 v249, 0xffff0000, v123
	v_pk_mul_f32 v[242:243], v[242:243], s[100:101] op_sel_hi:[1,0]
	v_pk_mul_f32 v[244:245], v[244:245], s[100:101] op_sel_hi:[1,0]
	v_pk_mul_f32 v[246:247], v[246:247], s[100:101] op_sel_hi:[1,0]
	v_pk_mul_f32 v[248:249], v[248:249], s[100:101] op_sel_hi:[1,0]
	v_exp_f32_e32 v242, v242
	v_exp_f32_e32 v243, v243
	v_exp_f32_e32 v244, v244
	v_exp_f32_e32 v245, v245
	v_exp_f32_e32 v246, v246
	v_exp_f32_e32 v247, v247
	v_exp_f32_e32 v248, v248
	v_exp_f32_e32 v249, v249
	s_nop 0
	v_pk_add_f32 v[242:243], v[242:243], 1.0 op_sel_hi:[1,0]
	v_pk_add_f32 v[244:245], v[244:245], 1.0 op_sel_hi:[1,0]
	v_pk_add_f32 v[246:247], v[246:247], 1.0 op_sel_hi:[1,0]
	v_pk_add_f32 v[248:249], v[248:249], 1.0 op_sel_hi:[1,0]
	v_rcp_f32_e32 v250, v242
	v_rcp_f32_e32 v251, v243
	s_nop 0
	v_pk_fma_f32 v[252:253], v[242:243], v[250:251], 1.0 op_sel_hi:[1,1,0] neg_lo:[1,0,0] neg_hi:[1,0,0]
	v_pk_fma_f32 v[250:251], v[252:253], v[250:251], v[250:251]
	v_pk_fma_f32 v[252:253], v[242:243], v[250:251], 1.0 op_sel_hi:[1,1,0] neg_lo:[1,0,0] neg_hi:[1,0,0]
	v_pk_fma_f32 v[254:255], v[252:253], v[250:251], v[250:251]
	v_pk_fma_f32 v[252:253], v[242:243], v[254:255], 1.0 op_sel_hi:[1,1,0] neg_lo:[1,0,0] neg_hi:[1,0,0]
	v_pk_fma_f32 v[254:255], v[252:253], v[250:251], v[254:255]
	v_div_fixup_f32 v242, v254, v242, 1.0
	v_div_fixup_f32 v243, v255, v243, 1.0
	v_rcp_f32_e32 v250, v244
	v_rcp_f32_e32 v251, v245
	s_nop 0
	v_pk_fma_f32 v[252:253], v[244:245], v[250:251], 1.0 op_sel_hi:[1,1,0] neg_lo:[1,0,0] neg_hi:[1,0,0]
	v_pk_fma_f32 v[250:251], v[252:253], v[250:251], v[250:251]
	v_pk_fma_f32 v[252:253], v[244:245], v[250:251], 1.0 op_sel_hi:[1,1,0] neg_lo:[1,0,0] neg_hi:[1,0,0]
	v_pk_fma_f32 v[254:255], v[252:253], v[250:251], v[250:251]
	v_pk_fma_f32 v[252:253], v[244:245], v[254:255], 1.0 op_sel_hi:[1,1,0] neg_lo:[1,0,0] neg_hi:[1,0,0]
	v_pk_fma_f32 v[254:255], v[252:253], v[250:251], v[254:255]
	v_div_fixup_f32 v244, v254, v244, 1.0
	v_div_fixup_f32 v245, v255, v245, 1.0
	v_rcp_f32_e32 v250, v246
	v_rcp_f32_e32 v251, v247
; __device__ __forceinline__ u32x4 pack8(const f32x4 v0, const f32x4 v1) { u32x4 w; w.x = pk2(v0[0], v0[1]); w.y = pk2(v0[2], v0[3]); w.z = pk2(v1[0], v1[1]); w.w = pk2(v1[2], v1[3]); return w; }
; __device__ __forceinline__ void unpack8(const u32x4 w, f32x4& v0, f32x4& v1) { v0 = (f32x4){bflo(w.x), bfhi(w.x), bflo(w.y), bfhi(w.y)}; v1 = (f32x4){bflo(w.z), bfhi(w.z), bflo(w.w), bfhi(w.w)}; }
; __device__ __forceinline__ float sigmoidf_(float x) { return 1.0f / (1.0f + __expf(-x)); }
;     __device__ __forceinline__ void operator()(const f32x4 (&acc)[2][2][4][2], const Unit& u, int wr, int wc, int fr, int fq) const {
;     ...
;                 const int row = row0 + ai * 128 + m * 16;
;                 const bf16_t* rowp = z + (size_t)row * DIN + col0;
; #pragma unroll
;                 for (int bj = 0; bj < 2; ++bj) {
;                     const u32x4 gw = *(const u32x4*)(rowp + O_GA + bj * 128);
;                     f32x4 g0, g1; unpack8(gw, g0, g1);
;                     f32x4 v0, v1;
; #pragma unroll
;                     for (int j = 0; j < 4; ++j) { v0[j] = sigmoidf_(g0[j]) * acc[ai][bj][m][0][j]; v1[j] = sigmoidf_(g1[j]) * acc[ai][bj][m][1][j]; }
;                     const u32x4 mw = *(const u32x4*)(rowp + bj * 128); f32x4 m0, m1; unpack8(mw, m0, m1); v0 += m0; v1 += m1;
;                     __builtin_amdgcn_raw_buffer_store_b128(pack8(v0, v1), rsrc, (unsigned)(((size_t)row * DIN + col0 + bj * 128) * 2), 0, 16  ); }
	s_nop 0
	v_pk_fma_f32 v[252:253], v[246:247], v[250:251], 1.0 op_sel_hi:[1,1,0] neg_lo:[1,0,0] neg_hi:[1,0,0]
	v_pk_fma_f32 v[250:251], v[252:253], v[250:251], v[250:251]
	v_pk_fma_f32 v[252:253], v[246:247], v[250:251], 1.0 op_sel_hi:[1,1,0] neg_lo:[1,0,0] neg_hi:[1,0,0]
	v_pk_fma_f32 v[254:255], v[252:253], v[250:251], v[250:251]
	v_pk_fma_f32 v[252:253], v[246:247], v[254:255], 1.0 op_sel_hi:[1,1,0] neg_lo:[1,0,0] neg_hi:[1,0,0]
	v_pk_fma_f32 v[254:255], v[252:253], v[250:251], v[254:255]
	v_div_fixup_f32 v246, v254, v246, 1.0
	v_div_fixup_f32 v247, v255, v247, 1.0
	v_rcp_f32_e32 v250, v248
	v_rcp_f32_e32 v251, v249
	s_nop 0
	v_pk_fma_f32 v[252:253], v[248:249], v[250:251], 1.0 op_sel_hi:[1,1,0] neg_lo:[1,0,0] neg_hi:[1,0,0]
	v_pk_fma_f32 v[250:251], v[252:253], v[250:251], v[250:251]
	v_pk_fma_f32 v[252:253], v[248:249], v[250:251], 1.0 op_sel_hi:[1,1,0] neg_lo:[1,0,0] neg_hi:[1,0,0]
	v_pk_fma_f32 v[254:255], v[252:253], v[250:251], v[250:251]
	v_pk_fma_f32 v[252:253], v[248:249], v[254:255], 1.0 op_sel_hi:[1,1,0] neg_lo:[1,0,0] neg_hi:[1,0,0]
	v_pk_fma_f32 v[254:255], v[252:253], v[250:251], v[254:255]
	v_div_fixup_f32 v248, v254, v248, 1.0
	v_div_fixup_f32 v249, v255, v249, 1.0
	v_lshlrev_b32_e32 v154, 16, v124
	v_and_b32_e32 v155, 0xffff0000, v124
	v_lshlrev_b32_e32 v164, 16, v126
	v_and_b32_e32 v165, 0xffff0000, v126
	v_lshlrev_b32_e32 v126, 16, v127
	v_and_b32_e32 v127, 0xffff0000, v127
	v_lshlrev_b32_e32 v124, 16, v125
	v_and_b32_e32 v125, 0xffff0000, v125
	v_pk_fma_f32 v[116:117], v[116:117], v[242:243], v[154:155]
	v_pk_fma_f32 v[120:121], v[114:115], v[248:249], v[126:127]
	v_pk_fma_f32 v[114:115], v[112:113], v[244:245], v[164:165]
	v_cvt_pk_bf16_f32 v112, v116, v117
	v_pk_fma_f32 v[118:119], v[118:119], v[246:247], v[124:125]
	s_nop 0
	v_cvt_pk_bf16_f32 v113, v118, v119
	v_cvt_pk_bf16_f32 v114, v114, v115
	v_cvt_pk_bf16_f32 v115, v120, v121
	buffer_store_dwordx4 v[112:115], v147, s[24:27], 0 offen offset:256 sc1
	s_nop 1
	v_or_b32_e32 v112, 16, v162
	v_mad_i64_i32 v[114:115], s[6:7], v112, s77, 0
	v_lshl_add_u64 v[112:113], v[114:115], 1, s[38:39]
	v_lshl_add_u64 v[112:113], v[112:113], 0, v[148:149]
	v_add_co_u32_e32 v116, vcc, s78, v112
	s_nop 1
	v_addc_co_u32_e32 v117, vcc, 0, v113, vcc
	s_waitcnt vmcnt(6)
	v_mov_b32_e32 v118, v232
	v_mov_b32_e32 v119, v233
	v_mov_b32_e32 v120, v234
	v_mov_b32_e32 v121, v235
	v_mov_b32_e32 v122, v236
	v_mov_b32_e32 v123, v237
	v_mov_b32_e32 v124, v238
	v_mov_b32_e32 v125, v239
	v_add_u32_e32 v203, 0x45300, v202
	global_load_dwordx4 v[232:235], v203, s[38:39]
	v_add_u32_e32 v203, 0x44100, v202
	global_load_dwordx4 v[236:239], v203, s[38:39]
	s_mov_b32 s100, 0xbfb8aa3b
	v_lshlrev_b32_e32 v242, 16, v118
	v_and_b32_e32 v243, 0xffff0000, v118
	v_lshlrev_b32_e32 v244, 16, v120
	v_and_b32_e32 v245, 0xffff0000, v120
	v_lshlrev_b32_e32 v246, 16, v119
	v_and_b32_e32 v247, 0xffff0000, v119
	v_lshlrev_b32_e32 v248, 16, v121
	v_and_b32_e32 v249, 0xffff0000, v121
	v_pk_mul_f32 v[242:243], v[242:243], s[100:101] op_sel_hi:[1,0]
	v_pk_mul_f32 v[244:245], v[244:245], s[100:101] op_sel_hi:[1,0]
	v_pk_mul_f32 v[246:247], v[246:247], s[100:101] op_sel_hi:[1,0]
	v_pk_mul_f32 v[248:249], v[248:249], s[100:101] op_sel_hi:[1,0]
	v_exp_f32_e32 v242, v242
	v_exp_f32_e32 v243, v243
	v_exp_f32_e32 v244, v244
	v_exp_f32_e32 v245, v245
	v_exp_f32_e32 v246, v246
	v_exp_f32_e32 v247, v247
	v_exp_f32_e32 v248, v248
	v_exp_f32_e32 v249, v249
	s_nop 0
	v_pk_add_f32 v[242:243], v[242:243], 1.0 op_sel_hi:[1,0]
	v_pk_add_f32 v[244:245], v[244:245], 1.0 op_sel_hi:[1,0]
	v_pk_add_f32 v[246:247], v[246:247], 1.0 op_sel_hi:[1,0]
	v_pk_add_f32 v[248:249], v[248:249], 1.0 op_sel_hi:[1,0]
	v_rcp_f32_e32 v250, v242
	v_rcp_f32_e32 v251, v243
	s_nop 0
	v_pk_fma_f32 v[252:253], v[242:243], v[250:251], 1.0 op_sel_hi:[1,1,0] neg_lo:[1,0,0] neg_hi:[1,0,0]
	v_pk_fma_f32 v[250:251], v[252:253], v[250:251], v[250:251]
	v_pk_fma_f32 v[252:253], v[242:243], v[250:251], 1.0 op_sel_hi:[1,1,0] neg_lo:[1,0,0] neg_hi:[1,0,0]
	v_pk_fma_f32 v[254:255], v[252:253], v[250:251], v[250:251]
	v_pk_fma_f32 v[252:253], v[242:243], v[254:255], 1.0 op_sel_hi:[1,1,0] neg_lo:[1,0,0] neg_hi:[1,0,0]
	v_pk_fma_f32 v[254:255], v[252:253], v[250:251], v[254:255]
	v_div_fixup_f32 v242, v254, v242, 1.0
	v_div_fixup_f32 v243, v255, v243, 1.0
	v_rcp_f32_e32 v250, v244
	v_rcp_f32_e32 v251, v245
	s_nop 0
	v_pk_fma_f32 v[252:253], v[244:245], v[250:251], 1.0 op_sel_hi:[1,1,0] neg_lo:[1,0,0] neg_hi:[1,0,0]
	v_pk_fma_f32 v[250:251], v[252:253], v[250:251], v[250:251]
	v_pk_fma_f32 v[252:253], v[244:245], v[250:251], 1.0 op_sel_hi:[1,1,0] neg_lo:[1,0,0] neg_hi:[1,0,0]
	v_pk_fma_f32 v[254:255], v[252:253], v[250:251], v[250:251]
	v_pk_fma_f32 v[252:253], v[244:245], v[254:255], 1.0 op_sel_hi:[1,1,0] neg_lo:[1,0,0] neg_hi:[1,0,0]
	v_pk_fma_f32 v[254:255], v[252:253], v[250:251], v[254:255]
	v_div_fixup_f32 v244, v254, v244, 1.0
	v_div_fixup_f32 v245, v255, v245, 1.0
	v_rcp_f32_e32 v250, v246
	v_rcp_f32_e32 v251, v247
	s_nop 0
	v_pk_fma_f32 v[252:253], v[246:247], v[250:251], 1.0 op_sel_hi:[1,1,0] neg_lo:[1,0,0] neg_hi:[1,0,0]
	v_pk_fma_f32 v[250:251], v[252:253], v[250:251], v[250:251]
	v_pk_fma_f32 v[252:253], v[246:247], v[250:251], 1.0 op_sel_hi:[1,1,0] neg_lo:[1,0,0] neg_hi:[1,0,0]
	v_pk_fma_f32 v[254:255], v[252:253], v[250:251], v[250:251]
	v_pk_fma_f32 v[252:253], v[246:247], v[254:255], 1.0 op_sel_hi:[1,1,0] neg_lo:[1,0,0] neg_hi:[1,0,0]
	v_pk_fma_f32 v[254:255], v[252:253], v[250:251], v[254:255]
	v_div_fixup_f32 v246, v254, v246, 1.0
	v_div_fixup_f32 v247, v255, v247, 1.0
	v_rcp_f32_e32 v250, v248
	v_rcp_f32_e32 v251, v249
	s_nop 0
	v_pk_fma_f32 v[252:253], v[248:249], v[250:251], 1.0 op_sel_hi:[1,1,0] neg_lo:[1,0,0] neg_hi:[1,0,0]
	v_pk_fma_f32 v[250:251], v[252:253], v[250:251], v[250:251]
	v_pk_fma_f32 v[252:253], v[248:249], v[250:251], 1.0 op_sel_hi:[1,1,0] neg_lo:[1,0,0] neg_hi:[1,0,0]
	v_pk_fma_f32 v[254:255], v[252:253], v[250:251], v[250:251]
	v_pk_fma_f32 v[252:253], v[248:249], v[254:255], 1.0 op_sel_hi:[1,1,0] neg_lo:[1,0,0] neg_hi:[1,0,0]
	v_pk_fma_f32 v[254:255], v[252:253], v[250:251], v[254:255]
	v_div_fixup_f32 v248, v254, v248, 1.0
	v_div_fixup_f32 v249, v255, v249, 1.0
	v_and_b32_e32 v155, 0xffff0000, v124
	v_lshlrev_b32_e32 v152, 16, v122
	v_and_b32_e32 v153, 0xffff0000, v122
	v_lshlrev_b32_e32 v154, 16, v124
	v_lshlrev_b32_e32 v124, 16, v125
	v_and_b32_e32 v125, 0xffff0000, v125
	v_lshlrev_b32_e32 v122, 16, v123
	v_and_b32_e32 v123, 0xffff0000, v123
	v_pk_fma_f32 v[108:109], v[108:109], v[242:243], v[152:153]
	v_pk_fma_f32 v[118:119], v[106:107], v[248:249], v[124:125]
	v_pk_fma_f32 v[106:107], v[104:105], v[244:245], v[154:155]
	v_add_lshl_u32 v120, v146, v114, 1
	v_pk_fma_f32 v[110:111], v[110:111], v[246:247], v[122:123]
	v_cvt_pk_bf16_f32 v104, v108, v109
	s_nop 0
	v_cvt_pk_bf16_f32 v105, v110, v111
	v_cvt_pk_bf16_f32 v106, v106, v107
	v_cvt_pk_bf16_f32 v107, v118, v119
	buffer_store_dwordx4 v[104:107], v120, s[24:27], 0 offen sc1
	s_nop 0
	s_waitcnt vmcnt(7)
; __device__ __forceinline__ u32x4 pack8(const f32x4 v0, const f32x4 v1) { u32x4 w; w.x = pk2(v0[0], v0[1]); w.y = pk2(v0[2], v0[3]); w.z = pk2(v1[0], v1[1]); w.w = pk2(v1[2], v1[3]); return w; }
; __device__ __forceinline__ void unpack8(const u32x4 w, f32x4& v0, f32x4& v1) { v0 = (f32x4){bflo(w.x), bfhi(w.x), bflo(w.y), bfhi(w.y)}; v1 = (f32x4){bflo(w.z), bfhi(w.z), bflo(w.w), bfhi(w.w)}; }
; __device__ __forceinline__ float sigmoidf_(float x) { return 1.0f / (1.0f + __expf(-x)); }
;     __device__ __forceinline__ void operator()(const f32x4 (&acc)[2][2][4][2], const Unit& u, int wr, int wc, int fr, int fq) const {
;     ...
;                 const int row = row0 + ai * 128 + m * 16;
;                 const bf16_t* rowp = z + (size_t)row * DIN + col0;
; #pragma unroll
;                 for (int bj = 0; bj < 2; ++bj) {
;                     const u32x4 gw = *(const u32x4*)(rowp + O_GA + bj * 128);
;                     f32x4 g0, g1; unpack8(gw, g0, g1);
;                     f32x4 v0, v1;
; #pragma unroll
;                     for (int j = 0; j < 4; ++j) { v0[j] = sigmoidf_(g0[j]) * acc[ai][bj][m][0][j]; v1[j] = sigmoidf_(g1[j]) * acc[ai][bj][m][1][j]; }
;                     const u32x4 mw = *(const u32x4*)(rowp + bj * 128); f32x4 m0, m1; unpack8(mw, m0, m1); v0 += m0; v1 += m1;
;                     __builtin_amdgcn_raw_buffer_store_b128(pack8(v0, v1), rsrc, (unsigned)(((size_t)row * DIN + col0 + bj * 128) * 2), 0, 16  ); }
	v_mov_b32_e32 v104, v204
	v_mov_b32_e32 v105, v205
	v_mov_b32_e32 v106, v206
	v_mov_b32_e32 v107, v207
	v_mov_b32_e32 v108, v208
	v_mov_b32_e32 v109, v209
	v_mov_b32_e32 v110, v210
	v_mov_b32_e32 v111, v211
	v_add_u32_e32 v203, 0x67200, v202
	global_load_dwordx4 v[204:207], v203, s[38:39]
	v_add_u32_e32 v203, 0x66000, v202
	global_load_dwordx4 v[208:211], v203, s[38:39]
	s_mov_b32 s100, 0xbfb8aa3b
	v_lshlrev_b32_e32 v242, 16, v106
	v_and_b32_e32 v243, 0xffff0000, v106
	v_lshlrev_b32_e32 v244, 16, v104
	v_and_b32_e32 v245, 0xffff0000, v104
	v_lshlrev_b32_e32 v246, 16, v105
	v_and_b32_e32 v247, 0xffff0000, v105
	v_lshlrev_b32_e32 v248, 16, v107
	v_and_b32_e32 v249, 0xffff0000, v107
	v_pk_mul_f32 v[242:243], v[242:243], s[100:101] op_sel_hi:[1,0]
	v_pk_mul_f32 v[244:245], v[244:245], s[100:101] op_sel_hi:[1,0]
	v_pk_mul_f32 v[246:247], v[246:247], s[100:101] op_sel_hi:[1,0]
	v_pk_mul_f32 v[248:249], v[248:249], s[100:101] op_sel_hi:[1,0]
	v_exp_f32_e32 v242, v242
	v_exp_f32_e32 v243, v243
	v_exp_f32_e32 v244, v244
	v_exp_f32_e32 v245, v245
	v_exp_f32_e32 v246, v246
	v_exp_f32_e32 v247, v247
	v_exp_f32_e32 v248, v248
	v_exp_f32_e32 v249, v249
	s_nop 0
	v_pk_add_f32 v[242:243], v[242:243], 1.0 op_sel_hi:[1,0]
	v_pk_add_f32 v[244:245], v[244:245], 1.0 op_sel_hi:[1,0]
	v_pk_add_f32 v[246:247], v[246:247], 1.0 op_sel_hi:[1,0]
	v_pk_add_f32 v[248:249], v[248:249], 1.0 op_sel_hi:[1,0]
	v_rcp_f32_e32 v250, v242
	v_rcp_f32_e32 v251, v243
	s_nop 0
	v_pk_fma_f32 v[252:253], v[242:243], v[250:251], 1.0 op_sel_hi:[1,1,0] neg_lo:[1,0,0] neg_hi:[1,0,0]
	v_pk_fma_f32 v[250:251], v[252:253], v[250:251], v[250:251]
	v_pk_fma_f32 v[252:253], v[242:243], v[250:251], 1.0 op_sel_hi:[1,1,0] neg_lo:[1,0,0] neg_hi:[1,0,0]
	v_pk_fma_f32 v[254:255], v[252:253], v[250:251], v[250:251]
	v_pk_fma_f32 v[252:253], v[242:243], v[254:255], 1.0 op_sel_hi:[1,1,0] neg_lo:[1,0,0] neg_hi:[1,0,0]
	v_pk_fma_f32 v[254:255], v[252:253], v[250:251], v[254:255]
	v_div_fixup_f32 v242, v254, v242, 1.0
	v_div_fixup_f32 v243, v255, v243, 1.0
	v_rcp_f32_e32 v250, v244
	v_rcp_f32_e32 v251, v245
	s_nop 0
	v_pk_fma_f32 v[252:253], v[244:245], v[250:251], 1.0 op_sel_hi:[1,1,0] neg_lo:[1,0,0] neg_hi:[1,0,0]
	v_pk_fma_f32 v[250:251], v[252:253], v[250:251], v[250:251]
	v_pk_fma_f32 v[252:253], v[244:245], v[250:251], 1.0 op_sel_hi:[1,1,0] neg_lo:[1,0,0] neg_hi:[1,0,0]
	v_pk_fma_f32 v[254:255], v[252:253], v[250:251], v[250:251]
	v_pk_fma_f32 v[252:253], v[244:245], v[254:255], 1.0 op_sel_hi:[1,1,0] neg_lo:[1,0,0] neg_hi:[1,0,0]
	v_pk_fma_f32 v[254:255], v[252:253], v[250:251], v[254:255]
	v_div_fixup_f32 v244, v254, v244, 1.0
	v_div_fixup_f32 v245, v255, v245, 1.0
	v_rcp_f32_e32 v250, v246
	v_rcp_f32_e32 v251, v247
	s_nop 0
	v_pk_fma_f32 v[252:253], v[246:247], v[250:251], 1.0 op_sel_hi:[1,1,0] neg_lo:[1,0,0] neg_hi:[1,0,0]
	v_pk_fma_f32 v[250:251], v[252:253], v[250:251], v[250:251]
	v_pk_fma_f32 v[252:253], v[246:247], v[250:251], 1.0 op_sel_hi:[1,1,0] neg_lo:[1,0,0] neg_hi:[1,0,0]
	v_pk_fma_f32 v[254:255], v[252:253], v[250:251], v[250:251]
	v_pk_fma_f32 v[252:253], v[246:247], v[254:255], 1.0 op_sel_hi:[1,1,0] neg_lo:[1,0,0] neg_hi:[1,0,0]
	v_pk_fma_f32 v[254:255], v[252:253], v[250:251], v[254:255]
	v_div_fixup_f32 v246, v254, v246, 1.0
	v_div_fixup_f32 v247, v255, v247, 1.0
	v_rcp_f32_e32 v250, v248
	v_rcp_f32_e32 v251, v249
	s_nop 0
	v_pk_fma_f32 v[252:253], v[248:249], v[250:251], 1.0 op_sel_hi:[1,1,0] neg_lo:[1,0,0] neg_hi:[1,0,0]
	v_pk_fma_f32 v[250:251], v[252:253], v[250:251], v[250:251]
	v_pk_fma_f32 v[252:253], v[248:249], v[250:251], 1.0 op_sel_hi:[1,1,0] neg_lo:[1,0,0] neg_hi:[1,0,0]
	v_pk_fma_f32 v[254:255], v[252:253], v[250:251], v[250:251]
	v_pk_fma_f32 v[252:253], v[248:249], v[254:255], 1.0 op_sel_hi:[1,1,0] neg_lo:[1,0,0] neg_hi:[1,0,0]
	v_pk_fma_f32 v[254:255], v[252:253], v[250:251], v[254:255]
	v_div_fixup_f32 v248, v254, v248, 1.0
	v_div_fixup_f32 v249, v255, v249, 1.0
	v_lshlrev_b32_e32 v116, 16, v108
	v_and_b32_e32 v117, 0xffff0000, v108
	v_lshlrev_b32_e32 v118, 16, v110
	v_and_b32_e32 v119, 0xffff0000, v110
	v_lshlrev_b32_e32 v110, 16, v111
	v_and_b32_e32 v111, 0xffff0000, v111
	v_lshlrev_b32_e32 v108, 16, v109
	v_and_b32_e32 v109, 0xffff0000, v109
	v_pk_fma_f32 v[100:101], v[100:101], v[244:245], v[116:117]
	v_pk_fma_f32 v[104:105], v[98:99], v[248:249], v[110:111]
	v_pk_fma_f32 v[98:99], v[96:97], v[242:243], v[118:119]
	v_cvt_pk_bf16_f32 v96, v100, v101
	v_pk_fma_f32 v[102:103], v[102:103], v[246:247], v[108:109]
	s_nop 0
	v_cvt_pk_bf16_f32 v97, v102, v103
	v_cvt_pk_bf16_f32 v98, v98, v99
	v_cvt_pk_bf16_f32 v99, v104, v105
	buffer_store_dwordx4 v[96:99], v120, s[24:27], 0 offen offset:256 sc1
	s_nop 1
	v_or_b32_e32 v96, 32, v162
	v_mad_i64_i32 v[98:99], s[6:7], v96, s77, 0
	v_lshl_add_u64 v[96:97], v[98:99], 1, s[38:39]
	v_lshl_add_u64 v[96:97], v[96:97], 0, v[148:149]
	v_add_co_u32_e32 v100, vcc, s78, v96
	s_nop 1
	v_addc_co_u32_e32 v101, vcc, 0, v97, vcc
	s_waitcnt vmcnt(7)
; __device__ __forceinline__ u32x4 pack8(const f32x4 v0, const f32x4 v1) { u32x4 w; w.x = pk2(v0[0], v0[1]); w.y = pk2(v0[2], v0[3]); w.z = pk2(v1[0], v1[1]); w.w = pk2(v1[2], v1[3]); return w; }
; __device__ __forceinline__ void unpack8(const u32x4 w, f32x4& v0, f32x4& v1) { v0 = (f32x4){bflo(w.x), bfhi(w.x), bflo(w.y), bfhi(w.y)}; v1 = (f32x4){bflo(w.z), bfhi(w.z), bflo(w.w), bfhi(w.w)}; }
; __device__ __forceinline__ float sigmoidf_(float x) { return 1.0f / (1.0f + __expf(-x)); }
;     __device__ __forceinline__ void operator()(const f32x4 (&acc)[2][2][4][2], const Unit& u, int wr, int wc, int fr, int fq) const {
;     ...
;                 const int row = row0 + ai * 128 + m * 16;
;                 const bf16_t* rowp = z + (size_t)row * DIN + col0;
; #pragma unroll
;                 for (int bj = 0; bj < 2; ++bj) {
;                     const u32x4 gw = *(const u32x4*)(rowp + O_GA + bj * 128);
;                     f32x4 g0, g1; unpack8(gw, g0, g1);
;                     f32x4 v0, v1;
; #pragma unroll
;                     for (int j = 0; j < 4; ++j) { v0[j] = sigmoidf_(g0[j]) * acc[ai][bj][m][0][j]; v1[j] = sigmoidf_(g1[j]) * acc[ai][bj][m][1][j]; }
;                     const u32x4 mw = *(const u32x4*)(rowp + bj * 128); f32x4 m0, m1; unpack8(mw, m0, m1); v0 += m0; v1 += m1;
;                     __builtin_amdgcn_raw_buffer_store_b128(pack8(v0, v1), rsrc, (unsigned)(((size_t)row * DIN + col0 + bj * 128) * 2), 0, 16  ); }
	v_mov_b32_e32 v102, v212
	v_mov_b32_e32 v103, v213
	v_mov_b32_e32 v104, v214
	v_mov_b32_e32 v105, v215
	v_mov_b32_e32 v106, v216
	v_mov_b32_e32 v107, v217
	v_mov_b32_e32 v108, v218
	v_mov_b32_e32 v109, v219
	v_add_u32_e32 v203, 0x67300, v202
	global_load_dwordx4 v[212:215], v203, s[38:39]
	v_add_u32_e32 v203, 0x66100, v202
	global_load_dwordx4 v[216:219], v203, s[38:39]
	s_mov_b32 s100, 0xbfb8aa3b
	v_lshlrev_b32_e32 v242, 16, v102
	v_and_b32_e32 v243, 0xffff0000, v102
	v_lshlrev_b32_e32 v244, 16, v104
	v_and_b32_e32 v245, 0xffff0000, v104
	v_lshlrev_b32_e32 v246, 16, v103
	v_and_b32_e32 v247, 0xffff0000, v103
	v_lshlrev_b32_e32 v248, 16, v105
	v_and_b32_e32 v249, 0xffff0000, v105
	v_pk_mul_f32 v[242:243], v[242:243], s[100:101] op_sel_hi:[1,0]
	v_pk_mul_f32 v[244:245], v[244:245], s[100:101] op_sel_hi:[1,0]
	v_pk_mul_f32 v[246:247], v[246:247], s[100:101] op_sel_hi:[1,0]
	v_pk_mul_f32 v[248:249], v[248:249], s[100:101] op_sel_hi:[1,0]
	v_exp_f32_e32 v242, v242
	v_exp_f32_e32 v243, v243
	v_exp_f32_e32 v244, v244
	v_exp_f32_e32 v245, v245
	v_exp_f32_e32 v246, v246
	v_exp_f32_e32 v247, v247
	v_exp_f32_e32 v248, v248
	v_exp_f32_e32 v249, v249
	s_nop 0
	v_pk_add_f32 v[242:243], v[242:243], 1.0 op_sel_hi:[1,0]
	v_pk_add_f32 v[244:245], v[244:245], 1.0 op_sel_hi:[1,0]
	v_pk_add_f32 v[246:247], v[246:247], 1.0 op_sel_hi:[1,0]
	v_pk_add_f32 v[248:249], v[248:249], 1.0 op_sel_hi:[1,0]
	v_rcp_f32_e32 v250, v242
	v_rcp_f32_e32 v251, v243
	s_nop 0
	v_pk_fma_f32 v[252:253], v[242:243], v[250:251], 1.0 op_sel_hi:[1,1,0] neg_lo:[1,0,0] neg_hi:[1,0,0]
	v_pk_fma_f32 v[250:251], v[252:253], v[250:251], v[250:251]
	v_pk_fma_f32 v[252:253], v[242:243], v[250:251], 1.0 op_sel_hi:[1,1,0] neg_lo:[1,0,0] neg_hi:[1,0,0]
	v_pk_fma_f32 v[254:255], v[252:253], v[250:251], v[250:251]
	v_pk_fma_f32 v[252:253], v[242:243], v[254:255], 1.0 op_sel_hi:[1,1,0] neg_lo:[1,0,0] neg_hi:[1,0,0]
	v_pk_fma_f32 v[254:255], v[252:253], v[250:251], v[254:255]
	v_div_fixup_f32 v242, v254, v242, 1.0
	v_div_fixup_f32 v243, v255, v243, 1.0
	v_rcp_f32_e32 v250, v244
	v_rcp_f32_e32 v251, v245
	s_nop 0
	v_pk_fma_f32 v[252:253], v[244:245], v[250:251], 1.0 op_sel_hi:[1,1,0] neg_lo:[1,0,0] neg_hi:[1,0,0]
	v_pk_fma_f32 v[250:251], v[252:253], v[250:251], v[250:251]
	v_pk_fma_f32 v[252:253], v[244:245], v[250:251], 1.0 op_sel_hi:[1,1,0] neg_lo:[1,0,0] neg_hi:[1,0,0]
	v_pk_fma_f32 v[254:255], v[252:253], v[250:251], v[250:251]
	v_pk_fma_f32 v[252:253], v[244:245], v[254:255], 1.0 op_sel_hi:[1,1,0] neg_lo:[1,0,0] neg_hi:[1,0,0]
	v_pk_fma_f32 v[254:255], v[252:253], v[250:251], v[254:255]
	v_div_fixup_f32 v244, v254, v244, 1.0
	v_div_fixup_f32 v245, v255, v245, 1.0
	v_rcp_f32_e32 v250, v246
	v_rcp_f32_e32 v251, v247
	s_nop 0
	v_pk_fma_f32 v[252:253], v[246:247], v[250:251], 1.0 op_sel_hi:[1,1,0] neg_lo:[1,0,0] neg_hi:[1,0,0]
	v_pk_fma_f32 v[250:251], v[252:253], v[250:251], v[250:251]
	v_pk_fma_f32 v[252:253], v[246:247], v[250:251], 1.0 op_sel_hi:[1,1,0] neg_lo:[1,0,0] neg_hi:[1,0,0]
	v_pk_fma_f32 v[254:255], v[252:253], v[250:251], v[250:251]
	v_pk_fma_f32 v[252:253], v[246:247], v[254:255], 1.0 op_sel_hi:[1,1,0] neg_lo:[1,0,0] neg_hi:[1,0,0]
	v_pk_fma_f32 v[254:255], v[252:253], v[250:251], v[254:255]
	v_div_fixup_f32 v246, v254, v246, 1.0
	v_div_fixup_f32 v247, v255, v247, 1.0
	v_rcp_f32_e32 v250, v248
	v_rcp_f32_e32 v251, v249
	s_nop 0
	v_pk_fma_f32 v[252:253], v[248:249], v[250:251], 1.0 op_sel_hi:[1,1,0] neg_lo:[1,0,0] neg_hi:[1,0,0]
	v_pk_fma_f32 v[250:251], v[252:253], v[250:251], v[250:251]
	v_pk_fma_f32 v[252:253], v[248:249], v[250:251], 1.0 op_sel_hi:[1,1,0] neg_lo:[1,0,0] neg_hi:[1,0,0]
	v_pk_fma_f32 v[254:255], v[252:253], v[250:251], v[250:251]
	v_pk_fma_f32 v[252:253], v[248:249], v[254:255], 1.0 op_sel_hi:[1,1,0] neg_lo:[1,0,0] neg_hi:[1,0,0]
	v_pk_fma_f32 v[254:255], v[252:253], v[250:251], v[254:255]
	v_div_fixup_f32 v248, v254, v248, 1.0
	v_div_fixup_f32 v249, v255, v249, 1.0
	v_lshlrev_b32_e32 v114, 16, v106
	v_and_b32_e32 v115, 0xffff0000, v106
	v_lshlrev_b32_e32 v116, 16, v108
	v_and_b32_e32 v117, 0xffff0000, v108
	v_lshlrev_b32_e32 v108, 16, v109
	v_and_b32_e32 v109, 0xffff0000, v109
	v_lshlrev_b32_e32 v106, 16, v107
	v_and_b32_e32 v107, 0xffff0000, v107
	v_pk_fma_f32 v[92:93], v[92:93], v[242:243], v[114:115]
	v_pk_fma_f32 v[102:103], v[90:91], v[248:249], v[108:109]
	v_pk_fma_f32 v[90:91], v[88:89], v[244:245], v[116:117]
	v_add_lshl_u32 v104, v146, v98, 1
	v_pk_fma_f32 v[94:95], v[94:95], v[246:247], v[106:107]
	v_cvt_pk_bf16_f32 v88, v92, v93
	s_nop 0
	v_cvt_pk_bf16_f32 v89, v94, v95
	v_cvt_pk_bf16_f32 v90, v90, v91
	v_cvt_pk_bf16_f32 v91, v102, v103
	buffer_store_dwordx4 v[88:91], v104, s[24:27], 0 offen sc1
	s_nop 0
	s_waitcnt vmcnt(7)
; __device__ __forceinline__ u32x4 pack8(const f32x4 v0, const f32x4 v1) { u32x4 w; w.x = pk2(v0[0], v0[1]); w.y = pk2(v0[2], v0[3]); w.z = pk2(v1[0], v1[1]); w.w = pk2(v1[2], v1[3]); return w; }
; __device__ __forceinline__ void unpack8(const u32x4 w, f32x4& v0, f32x4& v1) { v0 = (f32x4){bflo(w.x), bfhi(w.x), bflo(w.y), bfhi(w.y)}; v1 = (f32x4){bflo(w.z), bfhi(w.z), bflo(w.w), bfhi(w.w)}; }
; __device__ __forceinline__ float sigmoidf_(float x) { return 1.0f / (1.0f + __expf(-x)); }
;     __device__ __forceinline__ void operator()(const f32x4 (&acc)[2][2][4][2], const Unit& u, int wr, int wc, int fr, int fq) const {
;     ...
;                 const int row = row0 + ai * 128 + m * 16;
;                 const bf16_t* rowp = z + (size_t)row * DIN + col0;
; #pragma unroll
;                 for (int bj = 0; bj < 2; ++bj) {
;                     const u32x4 gw = *(const u32x4*)(rowp + O_GA + bj * 128);
;                     f32x4 g0, g1; unpack8(gw, g0, g1);
;                     f32x4 v0, v1;
; #pragma unroll
;                     for (int j = 0; j < 4; ++j) { v0[j] = sigmoidf_(g0[j]) * acc[ai][bj][m][0][j]; v1[j] = sigmoidf_(g1[j]) * acc[ai][bj][m][1][j]; }
;                     const u32x4 mw = *(const u32x4*)(rowp + bj * 128); f32x4 m0, m1; unpack8(mw, m0, m1); v0 += m0; v1 += m1;
;                     __builtin_amdgcn_raw_buffer_store_b128(pack8(v0, v1), rsrc, (unsigned)(((size_t)row * DIN + col0 + bj * 128) * 2), 0, 16  ); }
	v_mov_b32_e32 v88, v232
	v_mov_b32_e32 v89, v233
	v_mov_b32_e32 v90, v234
	v_mov_b32_e32 v91, v235
	v_mov_b32_e32 v92, v236
	v_mov_b32_e32 v93, v237
	v_mov_b32_e32 v94, v238
	v_mov_b32_e32 v95, v239
	v_add_u32_e32 v203, 0x111200, v202
	global_load_dwordx4 v[232:235], v203, s[38:39]
	v_add_u32_e32 v203, 0x110000, v202
	global_load_dwordx4 v[236:239], v203, s[38:39]
	s_mov_b32 s100, 0xbfb8aa3b
	v_lshlrev_b32_e32 v242, 16, v90
	v_and_b32_e32 v243, 0xffff0000, v90
	v_lshlrev_b32_e32 v244, 16, v88
	v_and_b32_e32 v245, 0xffff0000, v88
	v_lshlrev_b32_e32 v246, 16, v89
	v_and_b32_e32 v247, 0xffff0000, v89
	v_lshlrev_b32_e32 v248, 16, v91
	v_and_b32_e32 v249, 0xffff0000, v91
	v_pk_mul_f32 v[242:243], v[242:243], s[100:101] op_sel_hi:[1,0]
	v_pk_mul_f32 v[244:245], v[244:245], s[100:101] op_sel_hi:[1,0]
	v_pk_mul_f32 v[246:247], v[246:247], s[100:101] op_sel_hi:[1,0]
	v_pk_mul_f32 v[248:249], v[248:249], s[100:101] op_sel_hi:[1,0]
	v_exp_f32_e32 v242, v242
	v_exp_f32_e32 v243, v243
	v_exp_f32_e32 v244, v244
	v_exp_f32_e32 v245, v245
	v_exp_f32_e32 v246, v246
	v_exp_f32_e32 v247, v247
	v_exp_f32_e32 v248, v248
	v_exp_f32_e32 v249, v249
	s_nop 0
	v_pk_add_f32 v[242:243], v[242:243], 1.0 op_sel_hi:[1,0]
	v_pk_add_f32 v[244:245], v[244:245], 1.0 op_sel_hi:[1,0]
	v_pk_add_f32 v[246:247], v[246:247], 1.0 op_sel_hi:[1,0]
	v_pk_add_f32 v[248:249], v[248:249], 1.0 op_sel_hi:[1,0]
	v_rcp_f32_e32 v250, v242
	v_rcp_f32_e32 v251, v243
	s_nop 0
	v_pk_fma_f32 v[252:253], v[242:243], v[250:251], 1.0 op_sel_hi:[1,1,0] neg_lo:[1,0,0] neg_hi:[1,0,0]
	v_pk_fma_f32 v[250:251], v[252:253], v[250:251], v[250:251]
	v_pk_fma_f32 v[252:253], v[242:243], v[250:251], 1.0 op_sel_hi:[1,1,0] neg_lo:[1,0,0] neg_hi:[1,0,0]
	v_pk_fma_f32 v[254:255], v[252:253], v[250:251], v[250:251]
	v_pk_fma_f32 v[252:253], v[242:243], v[254:255], 1.0 op_sel_hi:[1,1,0] neg_lo:[1,0,0] neg_hi:[1,0,0]
	v_pk_fma_f32 v[254:255], v[252:253], v[250:251], v[254:255]
	v_div_fixup_f32 v242, v254, v242, 1.0
	v_div_fixup_f32 v243, v255, v243, 1.0
	v_rcp_f32_e32 v250, v244
	v_rcp_f32_e32 v251, v245
	s_nop 0
	v_pk_fma_f32 v[252:253], v[244:245], v[250:251], 1.0 op_sel_hi:[1,1,0] neg_lo:[1,0,0] neg_hi:[1,0,0]
	v_pk_fma_f32 v[250:251], v[252:253], v[250:251], v[250:251]
	v_pk_fma_f32 v[252:253], v[244:245], v[250:251], 1.0 op_sel_hi:[1,1,0] neg_lo:[1,0,0] neg_hi:[1,0,0]
	v_pk_fma_f32 v[254:255], v[252:253], v[250:251], v[250:251]
	v_pk_fma_f32 v[252:253], v[244:245], v[254:255], 1.0 op_sel_hi:[1,1,0] neg_lo:[1,0,0] neg_hi:[1,0,0]
	v_pk_fma_f32 v[254:255], v[252:253], v[250:251], v[254:255]
	v_div_fixup_f32 v244, v254, v244, 1.0
	v_div_fixup_f32 v245, v255, v245, 1.0
	v_rcp_f32_e32 v250, v246
	v_rcp_f32_e32 v251, v247
	s_nop 0
	v_pk_fma_f32 v[252:253], v[246:247], v[250:251], 1.0 op_sel_hi:[1,1,0] neg_lo:[1,0,0] neg_hi:[1,0,0]
	v_pk_fma_f32 v[250:251], v[252:253], v[250:251], v[250:251]
	v_pk_fma_f32 v[252:253], v[246:247], v[250:251], 1.0 op_sel_hi:[1,1,0] neg_lo:[1,0,0] neg_hi:[1,0,0]
	v_pk_fma_f32 v[254:255], v[252:253], v[250:251], v[250:251]
	v_pk_fma_f32 v[252:253], v[246:247], v[254:255], 1.0 op_sel_hi:[1,1,0] neg_lo:[1,0,0] neg_hi:[1,0,0]
	v_pk_fma_f32 v[254:255], v[252:253], v[250:251], v[254:255]
	v_div_fixup_f32 v246, v254, v246, 1.0
	v_div_fixup_f32 v247, v255, v247, 1.0
	v_rcp_f32_e32 v250, v248
	v_rcp_f32_e32 v251, v249
	s_nop 0
	v_pk_fma_f32 v[252:253], v[248:249], v[250:251], 1.0 op_sel_hi:[1,1,0] neg_lo:[1,0,0] neg_hi:[1,0,0]
	v_pk_fma_f32 v[250:251], v[252:253], v[250:251], v[250:251]
	v_pk_fma_f32 v[252:253], v[248:249], v[250:251], 1.0 op_sel_hi:[1,1,0] neg_lo:[1,0,0] neg_hi:[1,0,0]
	v_pk_fma_f32 v[254:255], v[252:253], v[250:251], v[250:251]
	v_pk_fma_f32 v[252:253], v[248:249], v[254:255], 1.0 op_sel_hi:[1,1,0] neg_lo:[1,0,0] neg_hi:[1,0,0]
	v_pk_fma_f32 v[254:255], v[252:253], v[250:251], v[254:255]
	v_div_fixup_f32 v248, v254, v248, 1.0
	v_div_fixup_f32 v249, v255, v249, 1.0
	v_lshlrev_b32_e32 v100, 16, v92
	v_and_b32_e32 v101, 0xffff0000, v92
	v_lshlrev_b32_e32 v102, 16, v94
	v_and_b32_e32 v103, 0xffff0000, v94
	v_lshlrev_b32_e32 v94, 16, v95
	v_and_b32_e32 v95, 0xffff0000, v95
	v_lshlrev_b32_e32 v92, 16, v93
	v_and_b32_e32 v93, 0xffff0000, v93
	v_pk_fma_f32 v[84:85], v[84:85], v[244:245], v[100:101]
	v_pk_fma_f32 v[88:89], v[82:83], v[248:249], v[94:95]
	v_pk_fma_f32 v[82:83], v[80:81], v[242:243], v[102:103]
	v_cvt_pk_bf16_f32 v80, v84, v85
	v_pk_fma_f32 v[86:87], v[86:87], v[246:247], v[92:93]
	s_nop 0
	v_cvt_pk_bf16_f32 v81, v86, v87
	v_cvt_pk_bf16_f32 v82, v82, v83
	v_cvt_pk_bf16_f32 v83, v88, v89
	buffer_store_dwordx4 v[80:83], v104, s[24:27], 0 offen offset:256 sc1
	s_nop 1
	v_or_b32_e32 v80, 48, v162
	v_mad_i64_i32 v[82:83], s[6:7], v80, s77, 0
	v_lshl_add_u64 v[80:81], v[82:83], 1, s[38:39]
	v_lshl_add_u64 v[80:81], v[80:81], 0, v[148:149]
	v_add_co_u32_e32 v84, vcc, s78, v80
	s_nop 1
	v_addc_co_u32_e32 v85, vcc, 0, v81, vcc
	s_waitcnt vmcnt(7)
; __device__ __forceinline__ u32x4 pack8(const f32x4 v0, const f32x4 v1) { u32x4 w; w.x = pk2(v0[0], v0[1]); w.y = pk2(v0[2], v0[3]); w.z = pk2(v1[0], v1[1]); w.w = pk2(v1[2], v1[3]); return w; }
; __device__ __forceinline__ void unpack8(const u32x4 w, f32x4& v0, f32x4& v1) { v0 = (f32x4){bflo(w.x), bfhi(w.x), bflo(w.y), bfhi(w.y)}; v1 = (f32x4){bflo(w.z), bfhi(w.z), bflo(w.w), bfhi(w.w)}; }
; __device__ __forceinline__ float sigmoidf_(float x) { return 1.0f / (1.0f + __expf(-x)); }
;     __device__ __forceinline__ void operator()(const f32x4 (&acc)[2][2][4][2], const Unit& u, int wr, int wc, int fr, int fq) const {
;     ...
;                 const int row = row0 + ai * 128 + m * 16;
;                 const bf16_t* rowp = z + (size_t)row * DIN + col0;
; #pragma unroll
;                 for (int bj = 0; bj < 2; ++bj) {
;                     const u32x4 gw = *(const u32x4*)(rowp + O_GA + bj * 128);
;                     f32x4 g0, g1; unpack8(gw, g0, g1);
;                     f32x4 v0, v1;
; #pragma unroll
;                     for (int j = 0; j < 4; ++j) { v0[j] = sigmoidf_(g0[j]) * acc[ai][bj][m][0][j]; v1[j] = sigmoidf_(g1[j]) * acc[ai][bj][m][1][j]; }
;                     const u32x4 mw = *(const u32x4*)(rowp + bj * 128); f32x4 m0, m1; unpack8(mw, m0, m1); v0 += m0; v1 += m1;
;                     __builtin_amdgcn_raw_buffer_store_b128(pack8(v0, v1), rsrc, (unsigned)(((size_t)row * DIN + col0 + bj * 128) * 2), 0, 16  ); }
	v_mov_b32_e32 v86, v204
	v_mov_b32_e32 v87, v205
	v_mov_b32_e32 v88, v206
	v_mov_b32_e32 v89, v207
	v_mov_b32_e32 v90, v208
	v_mov_b32_e32 v91, v209
	v_mov_b32_e32 v92, v210
	v_mov_b32_e32 v93, v211
	v_add_u32_e32 v203, 0x111300, v202
	global_load_dwordx4 v[204:207], v203, s[38:39]
	v_add_u32_e32 v203, 0x110100, v202
	global_load_dwordx4 v[208:211], v203, s[38:39]
	s_mov_b32 s100, 0xbfb8aa3b
	v_lshlrev_b32_e32 v242, 16, v86
	v_and_b32_e32 v243, 0xffff0000, v86
	v_lshlrev_b32_e32 v244, 16, v88
	v_and_b32_e32 v245, 0xffff0000, v88
	v_lshlrev_b32_e32 v246, 16, v87
	v_and_b32_e32 v247, 0xffff0000, v87
	v_lshlrev_b32_e32 v248, 16, v89
	v_and_b32_e32 v249, 0xffff0000, v89
	v_pk_mul_f32 v[242:243], v[242:243], s[100:101] op_sel_hi:[1,0]
	v_pk_mul_f32 v[244:245], v[244:245], s[100:101] op_sel_hi:[1,0]
	v_pk_mul_f32 v[246:247], v[246:247], s[100:101] op_sel_hi:[1,0]
	v_pk_mul_f32 v[248:249], v[248:249], s[100:101] op_sel_hi:[1,0]
	v_exp_f32_e32 v242, v242
	v_exp_f32_e32 v243, v243
	v_exp_f32_e32 v244, v244
	v_exp_f32_e32 v245, v245
	v_exp_f32_e32 v246, v246
	v_exp_f32_e32 v247, v247
	v_exp_f32_e32 v248, v248
	v_exp_f32_e32 v249, v249
	s_nop 0
	v_pk_add_f32 v[242:243], v[242:243], 1.0 op_sel_hi:[1,0]
	v_pk_add_f32 v[244:245], v[244:245], 1.0 op_sel_hi:[1,0]
	v_pk_add_f32 v[246:247], v[246:247], 1.0 op_sel_hi:[1,0]
	v_pk_add_f32 v[248:249], v[248:249], 1.0 op_sel_hi:[1,0]
	v_rcp_f32_e32 v250, v242
	v_rcp_f32_e32 v251, v243
	s_nop 0
	v_pk_fma_f32 v[252:253], v[242:243], v[250:251], 1.0 op_sel_hi:[1,1,0] neg_lo:[1,0,0] neg_hi:[1,0,0]
	v_pk_fma_f32 v[250:251], v[252:253], v[250:251], v[250:251]
	v_pk_fma_f32 v[252:253], v[242:243], v[250:251], 1.0 op_sel_hi:[1,1,0] neg_lo:[1,0,0] neg_hi:[1,0,0]
	v_pk_fma_f32 v[254:255], v[252:253], v[250:251], v[250:251]
	v_pk_fma_f32 v[252:253], v[242:243], v[254:255], 1.0 op_sel_hi:[1,1,0] neg_lo:[1,0,0] neg_hi:[1,0,0]
	v_pk_fma_f32 v[254:255], v[252:253], v[250:251], v[254:255]
	v_div_fixup_f32 v242, v254, v242, 1.0
	v_div_fixup_f32 v243, v255, v243, 1.0
	v_rcp_f32_e32 v250, v244
	v_rcp_f32_e32 v251, v245
	s_nop 0
	v_pk_fma_f32 v[252:253], v[244:245], v[250:251], 1.0 op_sel_hi:[1,1,0] neg_lo:[1,0,0] neg_hi:[1,0,0]
	v_pk_fma_f32 v[250:251], v[252:253], v[250:251], v[250:251]
	v_pk_fma_f32 v[252:253], v[244:245], v[250:251], 1.0 op_sel_hi:[1,1,0] neg_lo:[1,0,0] neg_hi:[1,0,0]
	v_pk_fma_f32 v[254:255], v[252:253], v[250:251], v[250:251]
	v_pk_fma_f32 v[252:253], v[244:245], v[254:255], 1.0 op_sel_hi:[1,1,0] neg_lo:[1,0,0] neg_hi:[1,0,0]
	v_pk_fma_f32 v[254:255], v[252:253], v[250:251], v[254:255]
	v_div_fixup_f32 v244, v254, v244, 1.0
	v_div_fixup_f32 v245, v255, v245, 1.0
	v_rcp_f32_e32 v250, v246
	v_rcp_f32_e32 v251, v247
	s_nop 0
	v_pk_fma_f32 v[252:253], v[246:247], v[250:251], 1.0 op_sel_hi:[1,1,0] neg_lo:[1,0,0] neg_hi:[1,0,0]
	v_pk_fma_f32 v[250:251], v[252:253], v[250:251], v[250:251]
	v_pk_fma_f32 v[252:253], v[246:247], v[250:251], 1.0 op_sel_hi:[1,1,0] neg_lo:[1,0,0] neg_hi:[1,0,0]
	v_pk_fma_f32 v[254:255], v[252:253], v[250:251], v[250:251]
	v_pk_fma_f32 v[252:253], v[246:247], v[254:255], 1.0 op_sel_hi:[1,1,0] neg_lo:[1,0,0] neg_hi:[1,0,0]
	v_pk_fma_f32 v[254:255], v[252:253], v[250:251], v[254:255]
	v_div_fixup_f32 v246, v254, v246, 1.0
	v_div_fixup_f32 v247, v255, v247, 1.0
	v_rcp_f32_e32 v250, v248
	v_rcp_f32_e32 v251, v249
	s_nop 0
	v_pk_fma_f32 v[252:253], v[248:249], v[250:251], 1.0 op_sel_hi:[1,1,0] neg_lo:[1,0,0] neg_hi:[1,0,0]
	v_pk_fma_f32 v[250:251], v[252:253], v[250:251], v[250:251]
	v_pk_fma_f32 v[252:253], v[248:249], v[250:251], 1.0 op_sel_hi:[1,1,0] neg_lo:[1,0,0] neg_hi:[1,0,0]
	v_pk_fma_f32 v[254:255], v[252:253], v[250:251], v[250:251]
	v_pk_fma_f32 v[252:253], v[248:249], v[254:255], 1.0 op_sel_hi:[1,1,0] neg_lo:[1,0,0] neg_hi:[1,0,0]
	v_pk_fma_f32 v[254:255], v[252:253], v[250:251], v[254:255]
	v_div_fixup_f32 v248, v254, v248, 1.0
	v_div_fixup_f32 v249, v255, v249, 1.0
	v_lshlrev_b32_e32 v98, 16, v90
	v_and_b32_e32 v99, 0xffff0000, v90
	v_lshlrev_b32_e32 v100, 16, v92
	v_and_b32_e32 v101, 0xffff0000, v92
	v_lshlrev_b32_e32 v92, 16, v93
	v_and_b32_e32 v93, 0xffff0000, v93
	v_lshlrev_b32_e32 v90, 16, v91
	v_and_b32_e32 v91, 0xffff0000, v91
	v_pk_fma_f32 v[76:77], v[76:77], v[242:243], v[98:99]
	v_pk_fma_f32 v[86:87], v[74:75], v[248:249], v[92:93]
	v_pk_fma_f32 v[74:75], v[72:73], v[244:245], v[100:101]
	v_add_lshl_u32 v88, v146, v82, 1
	v_pk_fma_f32 v[78:79], v[78:79], v[246:247], v[90:91]
	v_cvt_pk_bf16_f32 v72, v76, v77
	s_nop 0
	v_cvt_pk_bf16_f32 v73, v78, v79
	v_cvt_pk_bf16_f32 v74, v74, v75
	v_cvt_pk_bf16_f32 v75, v86, v87
	buffer_store_dwordx4 v[72:75], v88, s[24:27], 0 offen sc1
	s_nop 0
	s_waitcnt vmcnt(7)
; __device__ __forceinline__ u32x4 pack8(const f32x4 v0, const f32x4 v1) { u32x4 w; w.x = pk2(v0[0], v0[1]); w.y = pk2(v0[2], v0[3]); w.z = pk2(v1[0], v1[1]); w.w = pk2(v1[2], v1[3]); return w; }
; __device__ __forceinline__ void unpack8(const u32x4 w, f32x4& v0, f32x4& v1) { v0 = (f32x4){bflo(w.x), bfhi(w.x), bflo(w.y), bfhi(w.y)}; v1 = (f32x4){bflo(w.z), bfhi(w.z), bflo(w.w), bfhi(w.w)}; }
; __device__ __forceinline__ float sigmoidf_(float x) { return 1.0f / (1.0f + __expf(-x)); }
;     __device__ __forceinline__ void operator()(const f32x4 (&acc)[2][2][4][2], const Unit& u, int wr, int wc, int fr, int fq) const {
;     ...
;                 const int row = row0 + ai * 128 + m * 16;
;                 const bf16_t* rowp = z + (size_t)row * DIN + col0;
; #pragma unroll
;                 for (int bj = 0; bj < 2; ++bj) {
;                     const u32x4 gw = *(const u32x4*)(rowp + O_GA + bj * 128);
;                     f32x4 g0, g1; unpack8(gw, g0, g1);
;                     f32x4 v0, v1;
; #pragma unroll
;                     for (int j = 0; j < 4; ++j) { v0[j] = sigmoidf_(g0[j]) * acc[ai][bj][m][0][j]; v1[j] = sigmoidf_(g1[j]) * acc[ai][bj][m][1][j]; }
;                     const u32x4 mw = *(const u32x4*)(rowp + bj * 128); f32x4 m0, m1; unpack8(mw, m0, m1); v0 += m0; v1 += m1;
;                     __builtin_amdgcn_raw_buffer_store_b128(pack8(v0, v1), rsrc, (unsigned)(((size_t)row * DIN + col0 + bj * 128) * 2), 0, 16  ); }
	v_mov_b32_e32 v72, v212
	v_mov_b32_e32 v73, v213
	v_mov_b32_e32 v74, v214
	v_mov_b32_e32 v75, v215
	v_mov_b32_e32 v76, v216
	v_mov_b32_e32 v77, v217
	v_mov_b32_e32 v78, v218
	v_mov_b32_e32 v79, v219
	v_add_u32_e32 v203, 0x133200, v202
	global_load_dwordx4 v[212:215], v203, s[38:39]
	v_add_u32_e32 v203, 0x132000, v202
	global_load_dwordx4 v[216:219], v203, s[38:39]
	s_mov_b32 s100, 0xbfb8aa3b
	v_lshlrev_b32_e32 v242, 16, v74
	v_and_b32_e32 v243, 0xffff0000, v74
	v_lshlrev_b32_e32 v244, 16, v72
	v_and_b32_e32 v245, 0xffff0000, v72
	v_lshlrev_b32_e32 v246, 16, v73
	v_and_b32_e32 v247, 0xffff0000, v73
	v_lshlrev_b32_e32 v248, 16, v75
	v_and_b32_e32 v249, 0xffff0000, v75
	v_pk_mul_f32 v[242:243], v[242:243], s[100:101] op_sel_hi:[1,0]
	v_pk_mul_f32 v[244:245], v[244:245], s[100:101] op_sel_hi:[1,0]
	v_pk_mul_f32 v[246:247], v[246:247], s[100:101] op_sel_hi:[1,0]
	v_pk_mul_f32 v[248:249], v[248:249], s[100:101] op_sel_hi:[1,0]
	v_exp_f32_e32 v242, v242
	v_exp_f32_e32 v243, v243
	v_exp_f32_e32 v244, v244
	v_exp_f32_e32 v245, v245
	v_exp_f32_e32 v246, v246
	v_exp_f32_e32 v247, v247
	v_exp_f32_e32 v248, v248
	v_exp_f32_e32 v249, v249
	s_nop 0
	v_pk_add_f32 v[242:243], v[242:243], 1.0 op_sel_hi:[1,0]
	v_pk_add_f32 v[244:245], v[244:245], 1.0 op_sel_hi:[1,0]
	v_pk_add_f32 v[246:247], v[246:247], 1.0 op_sel_hi:[1,0]
	v_pk_add_f32 v[248:249], v[248:249], 1.0 op_sel_hi:[1,0]
	v_rcp_f32_e32 v250, v242
	v_rcp_f32_e32 v251, v243
	s_nop 0
	v_pk_fma_f32 v[252:253], v[242:243], v[250:251], 1.0 op_sel_hi:[1,1,0] neg_lo:[1,0,0] neg_hi:[1,0,0]
	v_pk_fma_f32 v[250:251], v[252:253], v[250:251], v[250:251]
	v_pk_fma_f32 v[252:253], v[242:243], v[250:251], 1.0 op_sel_hi:[1,1,0] neg_lo:[1,0,0] neg_hi:[1,0,0]
	v_pk_fma_f32 v[254:255], v[252:253], v[250:251], v[250:251]
	v_pk_fma_f32 v[252:253], v[242:243], v[254:255], 1.0 op_sel_hi:[1,1,0] neg_lo:[1,0,0] neg_hi:[1,0,0]
	v_pk_fma_f32 v[254:255], v[252:253], v[250:251], v[254:255]
	v_div_fixup_f32 v242, v254, v242, 1.0
	v_div_fixup_f32 v243, v255, v243, 1.0
	v_rcp_f32_e32 v250, v244
	v_rcp_f32_e32 v251, v245
	s_nop 0
	v_pk_fma_f32 v[252:253], v[244:245], v[250:251], 1.0 op_sel_hi:[1,1,0] neg_lo:[1,0,0] neg_hi:[1,0,0]
	v_pk_fma_f32 v[250:251], v[252:253], v[250:251], v[250:251]
	v_pk_fma_f32 v[252:253], v[244:245], v[250:251], 1.0 op_sel_hi:[1,1,0] neg_lo:[1,0,0] neg_hi:[1,0,0]
	v_pk_fma_f32 v[254:255], v[252:253], v[250:251], v[250:251]
	v_pk_fma_f32 v[252:253], v[244:245], v[254:255], 1.0 op_sel_hi:[1,1,0] neg_lo:[1,0,0] neg_hi:[1,0,0]
	v_pk_fma_f32 v[254:255], v[252:253], v[250:251], v[254:255]
	v_div_fixup_f32 v244, v254, v244, 1.0
	v_div_fixup_f32 v245, v255, v245, 1.0
	v_rcp_f32_e32 v250, v246
	v_rcp_f32_e32 v251, v247
	s_nop 0
	v_pk_fma_f32 v[252:253], v[246:247], v[250:251], 1.0 op_sel_hi:[1,1,0] neg_lo:[1,0,0] neg_hi:[1,0,0]
	v_pk_fma_f32 v[250:251], v[252:253], v[250:251], v[250:251]
	v_pk_fma_f32 v[252:253], v[246:247], v[250:251], 1.0 op_sel_hi:[1,1,0] neg_lo:[1,0,0] neg_hi:[1,0,0]
	v_pk_fma_f32 v[254:255], v[252:253], v[250:251], v[250:251]
	v_pk_fma_f32 v[252:253], v[246:247], v[254:255], 1.0 op_sel_hi:[1,1,0] neg_lo:[1,0,0] neg_hi:[1,0,0]
	v_pk_fma_f32 v[254:255], v[252:253], v[250:251], v[254:255]
	v_div_fixup_f32 v246, v254, v246, 1.0
	v_div_fixup_f32 v247, v255, v247, 1.0
	v_rcp_f32_e32 v250, v248
	v_rcp_f32_e32 v251, v249
	s_nop 0
	v_pk_fma_f32 v[252:253], v[248:249], v[250:251], 1.0 op_sel_hi:[1,1,0] neg_lo:[1,0,0] neg_hi:[1,0,0]
	v_pk_fma_f32 v[250:251], v[252:253], v[250:251], v[250:251]
	v_pk_fma_f32 v[252:253], v[248:249], v[250:251], 1.0 op_sel_hi:[1,1,0] neg_lo:[1,0,0] neg_hi:[1,0,0]
	v_pk_fma_f32 v[254:255], v[252:253], v[250:251], v[250:251]
	v_pk_fma_f32 v[252:253], v[248:249], v[254:255], 1.0 op_sel_hi:[1,1,0] neg_lo:[1,0,0] neg_hi:[1,0,0]
	v_pk_fma_f32 v[254:255], v[252:253], v[250:251], v[254:255]
	v_div_fixup_f32 v248, v254, v248, 1.0
	v_div_fixup_f32 v249, v255, v249, 1.0
	v_lshlrev_b32_e32 v84, 16, v76
	v_and_b32_e32 v85, 0xffff0000, v76
	v_lshlrev_b32_e32 v86, 16, v78
	v_and_b32_e32 v87, 0xffff0000, v78
	v_lshlrev_b32_e32 v78, 16, v79
	v_and_b32_e32 v79, 0xffff0000, v79
	v_lshlrev_b32_e32 v76, 16, v77
	v_and_b32_e32 v77, 0xffff0000, v77
	v_pk_fma_f32 v[68:69], v[68:69], v[244:245], v[84:85]
	v_pk_fma_f32 v[72:73], v[66:67], v[248:249], v[78:79]
	v_pk_fma_f32 v[66:67], v[64:65], v[242:243], v[86:87]
	v_cvt_pk_bf16_f32 v64, v68, v69
	v_pk_fma_f32 v[70:71], v[70:71], v[246:247], v[76:77]
	s_nop 0
	v_cvt_pk_bf16_f32 v65, v70, v71
	v_cvt_pk_bf16_f32 v66, v66, v67
	v_cvt_pk_bf16_f32 v67, v72, v73
	buffer_store_dwordx4 v[64:67], v88, s[24:27], 0 offen offset:256 sc1
	s_nop 1
	v_add_u32_e32 v64, 0x80, v162
	v_mad_i64_i32 v[66:67], s[6:7], v64, s77, 0
	v_lshl_add_u64 v[64:65], v[66:67], 1, s[38:39]
	v_lshl_add_u64 v[64:65], v[64:65], 0, v[148:149]
	v_add_co_u32_e32 v68, vcc, s78, v64
	s_nop 1
	v_addc_co_u32_e32 v69, vcc, 0, v65, vcc
	s_waitcnt vmcnt(7)
; __device__ __forceinline__ u32x4 pack8(const f32x4 v0, const f32x4 v1) { u32x4 w; w.x = pk2(v0[0], v0[1]); w.y = pk2(v0[2], v0[3]); w.z = pk2(v1[0], v1[1]); w.w = pk2(v1[2], v1[3]); return w; }
; __device__ __forceinline__ void unpack8(const u32x4 w, f32x4& v0, f32x4& v1) { v0 = (f32x4){bflo(w.x), bfhi(w.x), bflo(w.y), bfhi(w.y)}; v1 = (f32x4){bflo(w.z), bfhi(w.z), bflo(w.w), bfhi(w.w)}; }
; __device__ __forceinline__ float sigmoidf_(float x) { return 1.0f / (1.0f + __expf(-x)); }
;     __device__ __forceinline__ void operator()(const f32x4 (&acc)[2][2][4][2], const Unit& u, int wr, int wc, int fr, int fq) const {
;     ...
;                 const int row = row0 + ai * 128 + m * 16;
;                 const bf16_t* rowp = z + (size_t)row * DIN + col0;
; #pragma unroll
;                 for (int bj = 0; bj < 2; ++bj) {
;                     const u32x4 gw = *(const u32x4*)(rowp + O_GA + bj * 128);
;                     f32x4 g0, g1; unpack8(gw, g0, g1);
;                     f32x4 v0, v1;
; #pragma unroll
;                     for (int j = 0; j < 4; ++j) { v0[j] = sigmoidf_(g0[j]) * acc[ai][bj][m][0][j]; v1[j] = sigmoidf_(g1[j]) * acc[ai][bj][m][1][j]; }
;                     const u32x4 mw = *(const u32x4*)(rowp + bj * 128); f32x4 m0, m1; unpack8(mw, m0, m1); v0 += m0; v1 += m1;
;                     __builtin_amdgcn_raw_buffer_store_b128(pack8(v0, v1), rsrc, (unsigned)(((size_t)row * DIN + col0 + bj * 128) * 2), 0, 16  ); }
	v_mov_b32_e32 v70, v232
	v_mov_b32_e32 v71, v233
	v_mov_b32_e32 v72, v234
	v_mov_b32_e32 v73, v235
	v_mov_b32_e32 v74, v236
	v_mov_b32_e32 v75, v237
	v_mov_b32_e32 v76, v238
	v_mov_b32_e32 v77, v239
	v_add_u32_e32 v203, 0x133300, v202
	global_load_dwordx4 v[232:235], v203, s[38:39]
	v_add_u32_e32 v203, 0x132100, v202
	global_load_dwordx4 v[236:239], v203, s[38:39]
	s_mov_b32 s100, 0xbfb8aa3b
	v_lshlrev_b32_e32 v242, 16, v70
	v_and_b32_e32 v243, 0xffff0000, v70
	v_lshlrev_b32_e32 v244, 16, v72
	v_and_b32_e32 v245, 0xffff0000, v72
	v_lshlrev_b32_e32 v246, 16, v71
	v_and_b32_e32 v247, 0xffff0000, v71
	v_lshlrev_b32_e32 v248, 16, v73
	v_and_b32_e32 v249, 0xffff0000, v73
	v_pk_mul_f32 v[242:243], v[242:243], s[100:101] op_sel_hi:[1,0]
	v_pk_mul_f32 v[244:245], v[244:245], s[100:101] op_sel_hi:[1,0]
	v_pk_mul_f32 v[246:247], v[246:247], s[100:101] op_sel_hi:[1,0]
	v_pk_mul_f32 v[248:249], v[248:249], s[100:101] op_sel_hi:[1,0]
	v_exp_f32_e32 v242, v242
	v_exp_f32_e32 v243, v243
	v_exp_f32_e32 v244, v244
	v_exp_f32_e32 v245, v245
	v_exp_f32_e32 v246, v246
	v_exp_f32_e32 v247, v247
	v_exp_f32_e32 v248, v248
	v_exp_f32_e32 v249, v249
	s_nop 0
	v_pk_add_f32 v[242:243], v[242:243], 1.0 op_sel_hi:[1,0]
	v_pk_add_f32 v[244:245], v[244:245], 1.0 op_sel_hi:[1,0]
	v_pk_add_f32 v[246:247], v[246:247], 1.0 op_sel_hi:[1,0]
	v_pk_add_f32 v[248:249], v[248:249], 1.0 op_sel_hi:[1,0]
	v_rcp_f32_e32 v250, v242
	v_rcp_f32_e32 v251, v243
	s_nop 0
	v_pk_fma_f32 v[252:253], v[242:243], v[250:251], 1.0 op_sel_hi:[1,1,0] neg_lo:[1,0,0] neg_hi:[1,0,0]
	v_pk_fma_f32 v[250:251], v[252:253], v[250:251], v[250:251]
	v_pk_fma_f32 v[252:253], v[242:243], v[250:251], 1.0 op_sel_hi:[1,1,0] neg_lo:[1,0,0] neg_hi:[1,0,0]
	v_pk_fma_f32 v[254:255], v[252:253], v[250:251], v[250:251]
	v_pk_fma_f32 v[252:253], v[242:243], v[254:255], 1.0 op_sel_hi:[1,1,0] neg_lo:[1,0,0] neg_hi:[1,0,0]
	v_pk_fma_f32 v[254:255], v[252:253], v[250:251], v[254:255]
	v_div_fixup_f32 v242, v254, v242, 1.0
	v_div_fixup_f32 v243, v255, v243, 1.0
	v_rcp_f32_e32 v250, v244
	v_rcp_f32_e32 v251, v245
	s_nop 0
	v_pk_fma_f32 v[252:253], v[244:245], v[250:251], 1.0 op_sel_hi:[1,1,0] neg_lo:[1,0,0] neg_hi:[1,0,0]
	v_pk_fma_f32 v[250:251], v[252:253], v[250:251], v[250:251]
	v_pk_fma_f32 v[252:253], v[244:245], v[250:251], 1.0 op_sel_hi:[1,1,0] neg_lo:[1,0,0] neg_hi:[1,0,0]
	v_pk_fma_f32 v[254:255], v[252:253], v[250:251], v[250:251]
	v_pk_fma_f32 v[252:253], v[244:245], v[254:255], 1.0 op_sel_hi:[1,1,0] neg_lo:[1,0,0] neg_hi:[1,0,0]
	v_pk_fma_f32 v[254:255], v[252:253], v[250:251], v[254:255]
	v_div_fixup_f32 v244, v254, v244, 1.0
	v_div_fixup_f32 v245, v255, v245, 1.0
	v_rcp_f32_e32 v250, v246
	v_rcp_f32_e32 v251, v247
	s_nop 0
	v_pk_fma_f32 v[252:253], v[246:247], v[250:251], 1.0 op_sel_hi:[1,1,0] neg_lo:[1,0,0] neg_hi:[1,0,0]
	v_pk_fma_f32 v[250:251], v[252:253], v[250:251], v[250:251]
	v_pk_fma_f32 v[252:253], v[246:247], v[250:251], 1.0 op_sel_hi:[1,1,0] neg_lo:[1,0,0] neg_hi:[1,0,0]
	v_pk_fma_f32 v[254:255], v[252:253], v[250:251], v[250:251]
	v_pk_fma_f32 v[252:253], v[246:247], v[254:255], 1.0 op_sel_hi:[1,1,0] neg_lo:[1,0,0] neg_hi:[1,0,0]
	v_pk_fma_f32 v[254:255], v[252:253], v[250:251], v[254:255]
	v_div_fixup_f32 v246, v254, v246, 1.0
	v_div_fixup_f32 v247, v255, v247, 1.0
	v_rcp_f32_e32 v250, v248
	v_rcp_f32_e32 v251, v249
	s_nop 0
	v_pk_fma_f32 v[252:253], v[248:249], v[250:251], 1.0 op_sel_hi:[1,1,0] neg_lo:[1,0,0] neg_hi:[1,0,0]
	v_pk_fma_f32 v[250:251], v[252:253], v[250:251], v[250:251]
	v_pk_fma_f32 v[252:253], v[248:249], v[250:251], 1.0 op_sel_hi:[1,1,0] neg_lo:[1,0,0] neg_hi:[1,0,0]
	v_pk_fma_f32 v[254:255], v[252:253], v[250:251], v[250:251]
	v_pk_fma_f32 v[252:253], v[248:249], v[254:255], 1.0 op_sel_hi:[1,1,0] neg_lo:[1,0,0] neg_hi:[1,0,0]
	v_pk_fma_f32 v[254:255], v[252:253], v[250:251], v[254:255]
	v_div_fixup_f32 v248, v254, v248, 1.0
	v_div_fixup_f32 v249, v255, v249, 1.0
	v_lshlrev_b32_e32 v82, 16, v74
	v_and_b32_e32 v83, 0xffff0000, v74
	v_lshlrev_b32_e32 v84, 16, v76
	v_and_b32_e32 v85, 0xffff0000, v76
	v_lshlrev_b32_e32 v76, 16, v77
	v_and_b32_e32 v77, 0xffff0000, v77
	v_lshlrev_b32_e32 v74, 16, v75
	v_and_b32_e32 v75, 0xffff0000, v75
	v_pk_fma_f32 v[60:61], v[60:61], v[242:243], v[82:83]
	v_pk_fma_f32 v[70:71], v[58:59], v[248:249], v[76:77]
	v_pk_fma_f32 v[58:59], v[56:57], v[244:245], v[84:85]
	v_add_lshl_u32 v72, v146, v66, 1
	v_pk_fma_f32 v[62:63], v[62:63], v[246:247], v[74:75]
	v_cvt_pk_bf16_f32 v56, v60, v61
	s_nop 0
	v_cvt_pk_bf16_f32 v57, v62, v63
	v_cvt_pk_bf16_f32 v58, v58, v59
	v_cvt_pk_bf16_f32 v59, v70, v71
	buffer_store_dwordx4 v[56:59], v72, s[24:27], 0 offen sc1
	s_nop 0
	s_waitcnt vmcnt(7)
; __device__ __forceinline__ u32x4 pack8(const f32x4 v0, const f32x4 v1) { u32x4 w; w.x = pk2(v0[0], v0[1]); w.y = pk2(v0[2], v0[3]); w.z = pk2(v1[0], v1[1]); w.w = pk2(v1[2], v1[3]); return w; }
; __device__ __forceinline__ void unpack8(const u32x4 w, f32x4& v0, f32x4& v1) { v0 = (f32x4){bflo(w.x), bfhi(w.x), bflo(w.y), bfhi(w.y)}; v1 = (f32x4){bflo(w.z), bfhi(w.z), bflo(w.w), bfhi(w.w)}; }
; __device__ __forceinline__ float sigmoidf_(float x) { return 1.0f / (1.0f + __expf(-x)); }
;     __device__ __forceinline__ void operator()(const f32x4 (&acc)[2][2][4][2], const Unit& u, int wr, int wc, int fr, int fq) const {
;     ...
;                 const int row = row0 + ai * 128 + m * 16;
;                 const bf16_t* rowp = z + (size_t)row * DIN + col0;
; #pragma unroll
;                 for (int bj = 0; bj < 2; ++bj) {
;                     const u32x4 gw = *(const u32x4*)(rowp + O_GA + bj * 128);
;                     f32x4 g0, g1; unpack8(gw, g0, g1);
;                     f32x4 v0, v1;
; #pragma unroll
;                     for (int j = 0; j < 4; ++j) { v0[j] = sigmoidf_(g0[j]) * acc[ai][bj][m][0][j]; v1[j] = sigmoidf_(g1[j]) * acc[ai][bj][m][1][j]; }
;                     const u32x4 mw = *(const u32x4*)(rowp + bj * 128); f32x4 m0, m1; unpack8(mw, m0, m1); v0 += m0; v1 += m1;
;                     __builtin_amdgcn_raw_buffer_store_b128(pack8(v0, v1), rsrc, (unsigned)(((size_t)row * DIN + col0 + bj * 128) * 2), 0, 16  ); }
	v_mov_b32_e32 v56, v204
	v_mov_b32_e32 v57, v205
	v_mov_b32_e32 v58, v206
	v_mov_b32_e32 v59, v207
	v_mov_b32_e32 v60, v208
	v_mov_b32_e32 v61, v209
	v_mov_b32_e32 v62, v210
	v_mov_b32_e32 v63, v211
	v_add_u32_e32 v203, 0x155200, v202
	global_load_dwordx4 v[204:207], v203, s[38:39]
	v_add_u32_e32 v203, 0x154000, v202
	global_load_dwordx4 v[208:211], v203, s[38:39]
	s_mov_b32 s100, 0xbfb8aa3b
	v_lshlrev_b32_e32 v242, 16, v58
	v_and_b32_e32 v243, 0xffff0000, v58
	v_lshlrev_b32_e32 v244, 16, v56
	v_and_b32_e32 v245, 0xffff0000, v56
	v_lshlrev_b32_e32 v246, 16, v57
	v_and_b32_e32 v247, 0xffff0000, v57
	v_lshlrev_b32_e32 v248, 16, v59
	v_and_b32_e32 v249, 0xffff0000, v59
	v_pk_mul_f32 v[242:243], v[242:243], s[100:101] op_sel_hi:[1,0]
	v_pk_mul_f32 v[244:245], v[244:245], s[100:101] op_sel_hi:[1,0]
	v_pk_mul_f32 v[246:247], v[246:247], s[100:101] op_sel_hi:[1,0]
	v_pk_mul_f32 v[248:249], v[248:249], s[100:101] op_sel_hi:[1,0]
	v_exp_f32_e32 v242, v242
	v_exp_f32_e32 v243, v243
	v_exp_f32_e32 v244, v244
	v_exp_f32_e32 v245, v245
	v_exp_f32_e32 v246, v246
	v_exp_f32_e32 v247, v247
	v_exp_f32_e32 v248, v248
	v_exp_f32_e32 v249, v249
	s_nop 0
	v_pk_add_f32 v[242:243], v[242:243], 1.0 op_sel_hi:[1,0]
	v_pk_add_f32 v[244:245], v[244:245], 1.0 op_sel_hi:[1,0]
	v_pk_add_f32 v[246:247], v[246:247], 1.0 op_sel_hi:[1,0]
	v_pk_add_f32 v[248:249], v[248:249], 1.0 op_sel_hi:[1,0]
	v_rcp_f32_e32 v250, v242
	v_rcp_f32_e32 v251, v243
	s_nop 0
	v_pk_fma_f32 v[252:253], v[242:243], v[250:251], 1.0 op_sel_hi:[1,1,0] neg_lo:[1,0,0] neg_hi:[1,0,0]
	v_pk_fma_f32 v[250:251], v[252:253], v[250:251], v[250:251]
	v_pk_fma_f32 v[252:253], v[242:243], v[250:251], 1.0 op_sel_hi:[1,1,0] neg_lo:[1,0,0] neg_hi:[1,0,0]
	v_pk_fma_f32 v[254:255], v[252:253], v[250:251], v[250:251]
	v_pk_fma_f32 v[252:253], v[242:243], v[254:255], 1.0 op_sel_hi:[1,1,0] neg_lo:[1,0,0] neg_hi:[1,0,0]
	v_pk_fma_f32 v[254:255], v[252:253], v[250:251], v[254:255]
	v_div_fixup_f32 v242, v254, v242, 1.0
	v_div_fixup_f32 v243, v255, v243, 1.0
	v_rcp_f32_e32 v250, v244
	v_rcp_f32_e32 v251, v245
	s_nop 0
	v_pk_fma_f32 v[252:253], v[244:245], v[250:251], 1.0 op_sel_hi:[1,1,0] neg_lo:[1,0,0] neg_hi:[1,0,0]
	v_pk_fma_f32 v[250:251], v[252:253], v[250:251], v[250:251]
	v_pk_fma_f32 v[252:253], v[244:245], v[250:251], 1.0 op_sel_hi:[1,1,0] neg_lo:[1,0,0] neg_hi:[1,0,0]
	v_pk_fma_f32 v[254:255], v[252:253], v[250:251], v[250:251]
	v_pk_fma_f32 v[252:253], v[244:245], v[254:255], 1.0 op_sel_hi:[1,1,0] neg_lo:[1,0,0] neg_hi:[1,0,0]
	v_pk_fma_f32 v[254:255], v[252:253], v[250:251], v[254:255]
	v_div_fixup_f32 v244, v254, v244, 1.0
	v_div_fixup_f32 v245, v255, v245, 1.0
	v_rcp_f32_e32 v250, v246
	v_rcp_f32_e32 v251, v247
	s_nop 0
	v_pk_fma_f32 v[252:253], v[246:247], v[250:251], 1.0 op_sel_hi:[1,1,0] neg_lo:[1,0,0] neg_hi:[1,0,0]
	v_pk_fma_f32 v[250:251], v[252:253], v[250:251], v[250:251]
	v_pk_fma_f32 v[252:253], v[246:247], v[250:251], 1.0 op_sel_hi:[1,1,0] neg_lo:[1,0,0] neg_hi:[1,0,0]
	v_pk_fma_f32 v[254:255], v[252:253], v[250:251], v[250:251]
	v_pk_fma_f32 v[252:253], v[246:247], v[254:255], 1.0 op_sel_hi:[1,1,0] neg_lo:[1,0,0] neg_hi:[1,0,0]
	v_pk_fma_f32 v[254:255], v[252:253], v[250:251], v[254:255]
	v_div_fixup_f32 v246, v254, v246, 1.0
	v_div_fixup_f32 v247, v255, v247, 1.0
	v_rcp_f32_e32 v250, v248
	v_rcp_f32_e32 v251, v249
	s_nop 0
	v_pk_fma_f32 v[252:253], v[248:249], v[250:251], 1.0 op_sel_hi:[1,1,0] neg_lo:[1,0,0] neg_hi:[1,0,0]
	v_pk_fma_f32 v[250:251], v[252:253], v[250:251], v[250:251]
	v_pk_fma_f32 v[252:253], v[248:249], v[250:251], 1.0 op_sel_hi:[1,1,0] neg_lo:[1,0,0] neg_hi:[1,0,0]
	v_pk_fma_f32 v[254:255], v[252:253], v[250:251], v[250:251]
	v_pk_fma_f32 v[252:253], v[248:249], v[254:255], 1.0 op_sel_hi:[1,1,0] neg_lo:[1,0,0] neg_hi:[1,0,0]
	v_pk_fma_f32 v[254:255], v[252:253], v[250:251], v[254:255]
	v_div_fixup_f32 v248, v254, v248, 1.0
	v_div_fixup_f32 v249, v255, v249, 1.0
	v_lshlrev_b32_e32 v68, 16, v60
	v_and_b32_e32 v69, 0xffff0000, v60
	v_lshlrev_b32_e32 v70, 16, v62
	v_and_b32_e32 v71, 0xffff0000, v62
	v_lshlrev_b32_e32 v62, 16, v63
	v_and_b32_e32 v63, 0xffff0000, v63
	v_lshlrev_b32_e32 v60, 16, v61
	v_and_b32_e32 v61, 0xffff0000, v61
	v_pk_fma_f32 v[52:53], v[52:53], v[244:245], v[68:69]
	v_pk_fma_f32 v[56:57], v[50:51], v[248:249], v[62:63]
	v_pk_fma_f32 v[50:51], v[48:49], v[242:243], v[70:71]
	v_cvt_pk_bf16_f32 v48, v52, v53
	v_pk_fma_f32 v[54:55], v[54:55], v[246:247], v[60:61]
	s_nop 0
	v_cvt_pk_bf16_f32 v49, v54, v55
	v_cvt_pk_bf16_f32 v50, v50, v51
	v_cvt_pk_bf16_f32 v51, v56, v57
	buffer_store_dwordx4 v[48:51], v72, s[24:27], 0 offen offset:256 sc1
	s_nop 1
	v_add_u32_e32 v48, 0x90, v162
	v_mad_i64_i32 v[50:51], s[6:7], v48, s77, 0
	v_lshl_add_u64 v[48:49], v[50:51], 1, s[38:39]
	v_lshl_add_u64 v[48:49], v[48:49], 0, v[148:149]
	v_add_co_u32_e32 v52, vcc, s78, v48
	s_nop 1
	v_addc_co_u32_e32 v53, vcc, 0, v49, vcc
	s_waitcnt vmcnt(7)
; __device__ __forceinline__ u32x4 pack8(const f32x4 v0, const f32x4 v1) { u32x4 w; w.x = pk2(v0[0], v0[1]); w.y = pk2(v0[2], v0[3]); w.z = pk2(v1[0], v1[1]); w.w = pk2(v1[2], v1[3]); return w; }
; __device__ __forceinline__ void unpack8(const u32x4 w, f32x4& v0, f32x4& v1) { v0 = (f32x4){bflo(w.x), bfhi(w.x), bflo(w.y), bfhi(w.y)}; v1 = (f32x4){bflo(w.z), bfhi(w.z), bflo(w.w), bfhi(w.w)}; }
; __device__ __forceinline__ float sigmoidf_(float x) { return 1.0f / (1.0f + __expf(-x)); }
;     __device__ __forceinline__ void operator()(const f32x4 (&acc)[2][2][4][2], const Unit& u, int wr, int wc, int fr, int fq) const {
;     ...
;                 const int row = row0 + ai * 128 + m * 16;
;                 const bf16_t* rowp = z + (size_t)row * DIN + col0;
; #pragma unroll
;                 for (int bj = 0; bj < 2; ++bj) {
;                     const u32x4 gw = *(const u32x4*)(rowp + O_GA + bj * 128);
;                     f32x4 g0, g1; unpack8(gw, g0, g1);
;                     f32x4 v0, v1;
; #pragma unroll
;                     for (int j = 0; j < 4; ++j) { v0[j] = sigmoidf_(g0[j]) * acc[ai][bj][m][0][j]; v1[j] = sigmoidf_(g1[j]) * acc[ai][bj][m][1][j]; }
;                     const u32x4 mw = *(const u32x4*)(rowp + bj * 128); f32x4 m0, m1; unpack8(mw, m0, m1); v0 += m0; v1 += m1;
;                     __builtin_amdgcn_raw_buffer_store_b128(pack8(v0, v1), rsrc, (unsigned)(((size_t)row * DIN + col0 + bj * 128) * 2), 0, 16  ); }
	v_mov_b32_e32 v54, v212
	v_mov_b32_e32 v55, v213
	v_mov_b32_e32 v56, v214
	v_mov_b32_e32 v57, v215
	v_mov_b32_e32 v58, v216
	v_mov_b32_e32 v59, v217
	v_mov_b32_e32 v60, v218
	v_mov_b32_e32 v61, v219
	v_add_u32_e32 v203, 0x155300, v202
	global_load_dwordx4 v[212:215], v203, s[38:39]
	v_add_u32_e32 v203, 0x154100, v202
	global_load_dwordx4 v[216:219], v203, s[38:39]
	s_mov_b32 s100, 0xbfb8aa3b
	v_lshlrev_b32_e32 v242, 16, v54
	v_and_b32_e32 v243, 0xffff0000, v54
	v_lshlrev_b32_e32 v244, 16, v56
	v_and_b32_e32 v245, 0xffff0000, v56
	v_lshlrev_b32_e32 v246, 16, v55
	v_and_b32_e32 v247, 0xffff0000, v55
	v_lshlrev_b32_e32 v248, 16, v57
	v_and_b32_e32 v249, 0xffff0000, v57
	v_pk_mul_f32 v[242:243], v[242:243], s[100:101] op_sel_hi:[1,0]
	v_pk_mul_f32 v[244:245], v[244:245], s[100:101] op_sel_hi:[1,0]
	v_pk_mul_f32 v[246:247], v[246:247], s[100:101] op_sel_hi:[1,0]
	v_pk_mul_f32 v[248:249], v[248:249], s[100:101] op_sel_hi:[1,0]
	v_exp_f32_e32 v242, v242
	v_exp_f32_e32 v243, v243
	v_exp_f32_e32 v244, v244
	v_exp_f32_e32 v245, v245
	v_exp_f32_e32 v246, v246
	v_exp_f32_e32 v247, v247
	v_exp_f32_e32 v248, v248
	v_exp_f32_e32 v249, v249
	s_nop 0
	v_pk_add_f32 v[242:243], v[242:243], 1.0 op_sel_hi:[1,0]
	v_pk_add_f32 v[244:245], v[244:245], 1.0 op_sel_hi:[1,0]
	v_pk_add_f32 v[246:247], v[246:247], 1.0 op_sel_hi:[1,0]
	v_pk_add_f32 v[248:249], v[248:249], 1.0 op_sel_hi:[1,0]
	v_rcp_f32_e32 v250, v242
	v_rcp_f32_e32 v251, v243
	s_nop 0
	v_pk_fma_f32 v[252:253], v[242:243], v[250:251], 1.0 op_sel_hi:[1,1,0] neg_lo:[1,0,0] neg_hi:[1,0,0]
	v_pk_fma_f32 v[250:251], v[252:253], v[250:251], v[250:251]
	v_pk_fma_f32 v[252:253], v[242:243], v[250:251], 1.0 op_sel_hi:[1,1,0] neg_lo:[1,0,0] neg_hi:[1,0,0]
	v_pk_fma_f32 v[254:255], v[252:253], v[250:251], v[250:251]
	v_pk_fma_f32 v[252:253], v[242:243], v[254:255], 1.0 op_sel_hi:[1,1,0] neg_lo:[1,0,0] neg_hi:[1,0,0]
	v_pk_fma_f32 v[254:255], v[252:253], v[250:251], v[254:255]
	v_div_fixup_f32 v242, v254, v242, 1.0
	v_div_fixup_f32 v243, v255, v243, 1.0
	v_rcp_f32_e32 v250, v244
	v_rcp_f32_e32 v251, v245
	s_nop 0
	v_pk_fma_f32 v[252:253], v[244:245], v[250:251], 1.0 op_sel_hi:[1,1,0] neg_lo:[1,0,0] neg_hi:[1,0,0]
	v_pk_fma_f32 v[250:251], v[252:253], v[250:251], v[250:251]
	v_pk_fma_f32 v[252:253], v[244:245], v[250:251], 1.0 op_sel_hi:[1,1,0] neg_lo:[1,0,0] neg_hi:[1,0,0]
	v_pk_fma_f32 v[254:255], v[252:253], v[250:251], v[250:251]
	v_pk_fma_f32 v[252:253], v[244:245], v[254:255], 1.0 op_sel_hi:[1,1,0] neg_lo:[1,0,0] neg_hi:[1,0,0]
	v_pk_fma_f32 v[254:255], v[252:253], v[250:251], v[254:255]
	v_div_fixup_f32 v244, v254, v244, 1.0
	v_div_fixup_f32 v245, v255, v245, 1.0
	v_rcp_f32_e32 v250, v246
	v_rcp_f32_e32 v251, v247
	s_nop 0
	v_pk_fma_f32 v[252:253], v[246:247], v[250:251], 1.0 op_sel_hi:[1,1,0] neg_lo:[1,0,0] neg_hi:[1,0,0]
	v_pk_fma_f32 v[250:251], v[252:253], v[250:251], v[250:251]
	v_pk_fma_f32 v[252:253], v[246:247], v[250:251], 1.0 op_sel_hi:[1,1,0] neg_lo:[1,0,0] neg_hi:[1,0,0]
	v_pk_fma_f32 v[254:255], v[252:253], v[250:251], v[250:251]
	v_pk_fma_f32 v[252:253], v[246:247], v[254:255], 1.0 op_sel_hi:[1,1,0] neg_lo:[1,0,0] neg_hi:[1,0,0]
	v_pk_fma_f32 v[254:255], v[252:253], v[250:251], v[254:255]
	v_div_fixup_f32 v246, v254, v246, 1.0
	v_div_fixup_f32 v247, v255, v247, 1.0
	v_rcp_f32_e32 v250, v248
	v_rcp_f32_e32 v251, v249
	s_nop 0
	v_pk_fma_f32 v[252:253], v[248:249], v[250:251], 1.0 op_sel_hi:[1,1,0] neg_lo:[1,0,0] neg_hi:[1,0,0]
	v_pk_fma_f32 v[250:251], v[252:253], v[250:251], v[250:251]
	v_pk_fma_f32 v[252:253], v[248:249], v[250:251], 1.0 op_sel_hi:[1,1,0] neg_lo:[1,0,0] neg_hi:[1,0,0]
	v_pk_fma_f32 v[254:255], v[252:253], v[250:251], v[250:251]
	v_pk_fma_f32 v[252:253], v[248:249], v[254:255], 1.0 op_sel_hi:[1,1,0] neg_lo:[1,0,0] neg_hi:[1,0,0]
	v_pk_fma_f32 v[254:255], v[252:253], v[250:251], v[254:255]
	v_div_fixup_f32 v248, v254, v248, 1.0
	v_div_fixup_f32 v249, v255, v249, 1.0
	v_lshlrev_b32_e32 v66, 16, v58
	v_and_b32_e32 v67, 0xffff0000, v58
	v_lshlrev_b32_e32 v68, 16, v60
	v_and_b32_e32 v69, 0xffff0000, v60
	v_lshlrev_b32_e32 v60, 16, v61
	v_and_b32_e32 v61, 0xffff0000, v61
	v_lshlrev_b32_e32 v58, 16, v59
	v_and_b32_e32 v59, 0xffff0000, v59
	v_pk_fma_f32 v[44:45], v[44:45], v[242:243], v[66:67]
	v_pk_fma_f32 v[54:55], v[42:43], v[248:249], v[60:61]
	v_pk_fma_f32 v[42:43], v[40:41], v[244:245], v[68:69]
	v_add_lshl_u32 v56, v146, v50, 1
	v_pk_fma_f32 v[46:47], v[46:47], v[246:247], v[58:59]
	v_cvt_pk_bf16_f32 v40, v44, v45
	s_nop 0
	v_cvt_pk_bf16_f32 v41, v46, v47
	v_cvt_pk_bf16_f32 v42, v42, v43
	v_cvt_pk_bf16_f32 v43, v54, v55
	buffer_store_dwordx4 v[40:43], v56, s[24:27], 0 offen sc1
	s_nop 0
	s_waitcnt vmcnt(7)
; __device__ __forceinline__ u32x4 pack8(const f32x4 v0, const f32x4 v1) { u32x4 w; w.x = pk2(v0[0], v0[1]); w.y = pk2(v0[2], v0[3]); w.z = pk2(v1[0], v1[1]); w.w = pk2(v1[2], v1[3]); return w; }
; __device__ __forceinline__ void unpack8(const u32x4 w, f32x4& v0, f32x4& v1) { v0 = (f32x4){bflo(w.x), bfhi(w.x), bflo(w.y), bfhi(w.y)}; v1 = (f32x4){bflo(w.z), bfhi(w.z), bflo(w.w), bfhi(w.w)}; }
; __device__ __forceinline__ float sigmoidf_(float x) { return 1.0f / (1.0f + __expf(-x)); }
;     __device__ __forceinline__ void operator()(const f32x4 (&acc)[2][2][4][2], const Unit& u, int wr, int wc, int fr, int fq) const {
;     ...
;                 const int row = row0 + ai * 128 + m * 16;
;                 const bf16_t* rowp = z + (size_t)row * DIN + col0;
; #pragma unroll
;                 for (int bj = 0; bj < 2; ++bj) {
;                     const u32x4 gw = *(const u32x4*)(rowp + O_GA + bj * 128);
;                     f32x4 g0, g1; unpack8(gw, g0, g1);
;                     f32x4 v0, v1;
; #pragma unroll
;                     for (int j = 0; j < 4; ++j) { v0[j] = sigmoidf_(g0[j]) * acc[ai][bj][m][0][j]; v1[j] = sigmoidf_(g1[j]) * acc[ai][bj][m][1][j]; }
;                     const u32x4 mw = *(const u32x4*)(rowp + bj * 128); f32x4 m0, m1; unpack8(mw, m0, m1); v0 += m0; v1 += m1;
;                     __builtin_amdgcn_raw_buffer_store_b128(pack8(v0, v1), rsrc, (unsigned)(((size_t)row * DIN + col0 + bj * 128) * 2), 0, 16  ); }
	v_mov_b32_e32 v40, v232
	v_mov_b32_e32 v41, v233
	v_mov_b32_e32 v42, v234
	v_mov_b32_e32 v43, v235
	v_mov_b32_e32 v44, v236
	v_mov_b32_e32 v45, v237
	v_mov_b32_e32 v46, v238
	v_mov_b32_e32 v47, v239
	v_add_u32_e32 v203, 0x177200, v202
	global_load_dwordx4 v[232:235], v203, s[38:39]
	v_add_u32_e32 v203, 0x176000, v202
	global_load_dwordx4 v[236:239], v203, s[38:39]
	s_mov_b32 s100, 0xbfb8aa3b
	v_lshlrev_b32_e32 v242, 16, v42
	v_and_b32_e32 v243, 0xffff0000, v42
	v_lshlrev_b32_e32 v244, 16, v40
	v_and_b32_e32 v245, 0xffff0000, v40
	v_lshlrev_b32_e32 v246, 16, v41
	v_and_b32_e32 v247, 0xffff0000, v41
	v_lshlrev_b32_e32 v248, 16, v43
	v_and_b32_e32 v249, 0xffff0000, v43
	v_pk_mul_f32 v[242:243], v[242:243], s[100:101] op_sel_hi:[1,0]
	v_pk_mul_f32 v[244:245], v[244:245], s[100:101] op_sel_hi:[1,0]
	v_pk_mul_f32 v[246:247], v[246:247], s[100:101] op_sel_hi:[1,0]
	v_pk_mul_f32 v[248:249], v[248:249], s[100:101] op_sel_hi:[1,0]
	v_exp_f32_e32 v242, v242
	v_exp_f32_e32 v243, v243
	v_exp_f32_e32 v244, v244
	v_exp_f32_e32 v245, v245
	v_exp_f32_e32 v246, v246
	v_exp_f32_e32 v247, v247
	v_exp_f32_e32 v248, v248
	v_exp_f32_e32 v249, v249
	s_nop 0
	v_pk_add_f32 v[242:243], v[242:243], 1.0 op_sel_hi:[1,0]
	v_pk_add_f32 v[244:245], v[244:245], 1.0 op_sel_hi:[1,0]
	v_pk_add_f32 v[246:247], v[246:247], 1.0 op_sel_hi:[1,0]
	v_pk_add_f32 v[248:249], v[248:249], 1.0 op_sel_hi:[1,0]
	v_rcp_f32_e32 v250, v242
	v_rcp_f32_e32 v251, v243
	s_nop 0
	v_pk_fma_f32 v[252:253], v[242:243], v[250:251], 1.0 op_sel_hi:[1,1,0] neg_lo:[1,0,0] neg_hi:[1,0,0]
	v_pk_fma_f32 v[250:251], v[252:253], v[250:251], v[250:251]
	v_pk_fma_f32 v[252:253], v[242:243], v[250:251], 1.0 op_sel_hi:[1,1,0] neg_lo:[1,0,0] neg_hi:[1,0,0]
	v_pk_fma_f32 v[254:255], v[252:253], v[250:251], v[250:251]
	v_pk_fma_f32 v[252:253], v[242:243], v[254:255], 1.0 op_sel_hi:[1,1,0] neg_lo:[1,0,0] neg_hi:[1,0,0]
	v_pk_fma_f32 v[254:255], v[252:253], v[250:251], v[254:255]
	v_div_fixup_f32 v242, v254, v242, 1.0
	v_div_fixup_f32 v243, v255, v243, 1.0
	v_rcp_f32_e32 v250, v244
	v_rcp_f32_e32 v251, v245
	s_nop 0
	v_pk_fma_f32 v[252:253], v[244:245], v[250:251], 1.0 op_sel_hi:[1,1,0] neg_lo:[1,0,0] neg_hi:[1,0,0]
	v_pk_fma_f32 v[250:251], v[252:253], v[250:251], v[250:251]
	v_pk_fma_f32 v[252:253], v[244:245], v[250:251], 1.0 op_sel_hi:[1,1,0] neg_lo:[1,0,0] neg_hi:[1,0,0]
	v_pk_fma_f32 v[254:255], v[252:253], v[250:251], v[250:251]
	v_pk_fma_f32 v[252:253], v[244:245], v[254:255], 1.0 op_sel_hi:[1,1,0] neg_lo:[1,0,0] neg_hi:[1,0,0]
	v_pk_fma_f32 v[254:255], v[252:253], v[250:251], v[254:255]
	v_div_fixup_f32 v244, v254, v244, 1.0
	v_div_fixup_f32 v245, v255, v245, 1.0
	v_rcp_f32_e32 v250, v246
	v_rcp_f32_e32 v251, v247
	s_nop 0
	v_pk_fma_f32 v[252:253], v[246:247], v[250:251], 1.0 op_sel_hi:[1,1,0] neg_lo:[1,0,0] neg_hi:[1,0,0]
	v_pk_fma_f32 v[250:251], v[252:253], v[250:251], v[250:251]
	v_pk_fma_f32 v[252:253], v[246:247], v[250:251], 1.0 op_sel_hi:[1,1,0] neg_lo:[1,0,0] neg_hi:[1,0,0]
	v_pk_fma_f32 v[254:255], v[252:253], v[250:251], v[250:251]
	v_pk_fma_f32 v[252:253], v[246:247], v[254:255], 1.0 op_sel_hi:[1,1,0] neg_lo:[1,0,0] neg_hi:[1,0,0]
	v_pk_fma_f32 v[254:255], v[252:253], v[250:251], v[254:255]
	v_div_fixup_f32 v246, v254, v246, 1.0
	v_div_fixup_f32 v247, v255, v247, 1.0
	v_rcp_f32_e32 v250, v248
	v_rcp_f32_e32 v251, v249
	s_nop 0
	v_pk_fma_f32 v[252:253], v[248:249], v[250:251], 1.0 op_sel_hi:[1,1,0] neg_lo:[1,0,0] neg_hi:[1,0,0]
	v_pk_fma_f32 v[250:251], v[252:253], v[250:251], v[250:251]
	v_pk_fma_f32 v[252:253], v[248:249], v[250:251], 1.0 op_sel_hi:[1,1,0] neg_lo:[1,0,0] neg_hi:[1,0,0]
	v_pk_fma_f32 v[254:255], v[252:253], v[250:251], v[250:251]
	v_pk_fma_f32 v[252:253], v[248:249], v[254:255], 1.0 op_sel_hi:[1,1,0] neg_lo:[1,0,0] neg_hi:[1,0,0]
	v_pk_fma_f32 v[254:255], v[252:253], v[250:251], v[254:255]
	v_div_fixup_f32 v248, v254, v248, 1.0
	v_div_fixup_f32 v249, v255, v249, 1.0
	v_lshlrev_b32_e32 v52, 16, v44
	v_and_b32_e32 v53, 0xffff0000, v44
	v_lshlrev_b32_e32 v54, 16, v46
	v_and_b32_e32 v55, 0xffff0000, v46
	v_lshlrev_b32_e32 v46, 16, v47
	v_and_b32_e32 v47, 0xffff0000, v47
	v_lshlrev_b32_e32 v44, 16, v45
	v_and_b32_e32 v45, 0xffff0000, v45
	v_pk_fma_f32 v[36:37], v[36:37], v[244:245], v[52:53]
	v_pk_fma_f32 v[40:41], v[34:35], v[248:249], v[46:47]
	v_pk_fma_f32 v[34:35], v[32:33], v[242:243], v[54:55]
	v_cvt_pk_bf16_f32 v32, v36, v37
	v_pk_fma_f32 v[38:39], v[38:39], v[246:247], v[44:45]
	s_nop 0
	v_cvt_pk_bf16_f32 v33, v38, v39
	v_cvt_pk_bf16_f32 v34, v34, v35
	v_cvt_pk_bf16_f32 v35, v40, v41
	buffer_store_dwordx4 v[32:35], v56, s[24:27], 0 offen offset:256 sc1
	s_nop 1
	v_add_u32_e32 v32, 0xa0, v162
	v_mad_i64_i32 v[34:35], s[6:7], v32, s77, 0
	v_lshl_add_u64 v[32:33], v[34:35], 1, s[38:39]
	v_lshl_add_u64 v[32:33], v[32:33], 0, v[148:149]
	v_add_co_u32_e32 v36, vcc, s78, v32
	s_nop 1
	v_addc_co_u32_e32 v37, vcc, 0, v33, vcc
	s_waitcnt vmcnt(7)
; __device__ __forceinline__ u32x4 pack8(const f32x4 v0, const f32x4 v1) { u32x4 w; w.x = pk2(v0[0], v0[1]); w.y = pk2(v0[2], v0[3]); w.z = pk2(v1[0], v1[1]); w.w = pk2(v1[2], v1[3]); return w; }
; __device__ __forceinline__ void unpack8(const u32x4 w, f32x4& v0, f32x4& v1) { v0 = (f32x4){bflo(w.x), bfhi(w.x), bflo(w.y), bfhi(w.y)}; v1 = (f32x4){bflo(w.z), bfhi(w.z), bflo(w.w), bfhi(w.w)}; }
; __device__ __forceinline__ float sigmoidf_(float x) { return 1.0f / (1.0f + __expf(-x)); }
;     __device__ __forceinline__ void operator()(const f32x4 (&acc)[2][2][4][2], const Unit& u, int wr, int wc, int fr, int fq) const {
;     ...
;                 const int row = row0 + ai * 128 + m * 16;
;                 const bf16_t* rowp = z + (size_t)row * DIN + col0;
; #pragma unroll
;                 for (int bj = 0; bj < 2; ++bj) {
;                     const u32x4 gw = *(const u32x4*)(rowp + O_GA + bj * 128);
;                     f32x4 g0, g1; unpack8(gw, g0, g1);
;                     f32x4 v0, v1;
; #pragma unroll
;                     for (int j = 0; j < 4; ++j) { v0[j] = sigmoidf_(g0[j]) * acc[ai][bj][m][0][j]; v1[j] = sigmoidf_(g1[j]) * acc[ai][bj][m][1][j]; }
;                     const u32x4 mw = *(const u32x4*)(rowp + bj * 128); f32x4 m0, m1; unpack8(mw, m0, m1); v0 += m0; v1 += m1;
;                     __builtin_amdgcn_raw_buffer_store_b128(pack8(v0, v1), rsrc, (unsigned)(((size_t)row * DIN + col0 + bj * 128) * 2), 0, 16  ); }
	v_mov_b32_e32 v38, v204
	v_mov_b32_e32 v39, v205
	v_mov_b32_e32 v40, v206
	v_mov_b32_e32 v41, v207
	v_mov_b32_e32 v42, v208
	v_mov_b32_e32 v43, v209
	v_mov_b32_e32 v44, v210
	v_mov_b32_e32 v45, v211
	v_add_u32_e32 v203, 0x177300, v202
	global_load_dwordx4 v[204:207], v203, s[38:39]
	v_add_u32_e32 v203, 0x176100, v202
	global_load_dwordx4 v[208:211], v203, s[38:39]
	s_mov_b32 s100, 0xbfb8aa3b
	v_lshlrev_b32_e32 v242, 16, v38
	v_and_b32_e32 v243, 0xffff0000, v38
	v_lshlrev_b32_e32 v244, 16, v40
	v_and_b32_e32 v245, 0xffff0000, v40
	v_lshlrev_b32_e32 v246, 16, v39
	v_and_b32_e32 v247, 0xffff0000, v39
	v_lshlrev_b32_e32 v248, 16, v41
	v_and_b32_e32 v249, 0xffff0000, v41
	v_pk_mul_f32 v[242:243], v[242:243], s[100:101] op_sel_hi:[1,0]
	v_pk_mul_f32 v[244:245], v[244:245], s[100:101] op_sel_hi:[1,0]
	v_pk_mul_f32 v[246:247], v[246:247], s[100:101] op_sel_hi:[1,0]
	v_pk_mul_f32 v[248:249], v[248:249], s[100:101] op_sel_hi:[1,0]
	v_exp_f32_e32 v242, v242
	v_exp_f32_e32 v243, v243
	v_exp_f32_e32 v244, v244
	v_exp_f32_e32 v245, v245
	v_exp_f32_e32 v246, v246
	v_exp_f32_e32 v247, v247
	v_exp_f32_e32 v248, v248
	v_exp_f32_e32 v249, v249
	s_nop 0
	v_pk_add_f32 v[242:243], v[242:243], 1.0 op_sel_hi:[1,0]
	v_pk_add_f32 v[244:245], v[244:245], 1.0 op_sel_hi:[1,0]
	v_pk_add_f32 v[246:247], v[246:247], 1.0 op_sel_hi:[1,0]
	v_pk_add_f32 v[248:249], v[248:249], 1.0 op_sel_hi:[1,0]
	v_rcp_f32_e32 v250, v242
	v_rcp_f32_e32 v251, v243
	s_nop 0
	v_pk_fma_f32 v[252:253], v[242:243], v[250:251], 1.0 op_sel_hi:[1,1,0] neg_lo:[1,0,0] neg_hi:[1,0,0]
	v_pk_fma_f32 v[250:251], v[252:253], v[250:251], v[250:251]
	v_pk_fma_f32 v[252:253], v[242:243], v[250:251], 1.0 op_sel_hi:[1,1,0] neg_lo:[1,0,0] neg_hi:[1,0,0]
	v_pk_fma_f32 v[254:255], v[252:253], v[250:251], v[250:251]
	v_pk_fma_f32 v[252:253], v[242:243], v[254:255], 1.0 op_sel_hi:[1,1,0] neg_lo:[1,0,0] neg_hi:[1,0,0]
	v_pk_fma_f32 v[254:255], v[252:253], v[250:251], v[254:255]
	v_div_fixup_f32 v242, v254, v242, 1.0
	v_div_fixup_f32 v243, v255, v243, 1.0
	v_rcp_f32_e32 v250, v244
	v_rcp_f32_e32 v251, v245
	s_nop 0
	v_pk_fma_f32 v[252:253], v[244:245], v[250:251], 1.0 op_sel_hi:[1,1,0] neg_lo:[1,0,0] neg_hi:[1,0,0]
	v_pk_fma_f32 v[250:251], v[252:253], v[250:251], v[250:251]
	v_pk_fma_f32 v[252:253], v[244:245], v[250:251], 1.0 op_sel_hi:[1,1,0] neg_lo:[1,0,0] neg_hi:[1,0,0]
	v_pk_fma_f32 v[254:255], v[252:253], v[250:251], v[250:251]
	v_pk_fma_f32 v[252:253], v[244:245], v[254:255], 1.0 op_sel_hi:[1,1,0] neg_lo:[1,0,0] neg_hi:[1,0,0]
	v_pk_fma_f32 v[254:255], v[252:253], v[250:251], v[254:255]
	v_div_fixup_f32 v244, v254, v244, 1.0
	v_div_fixup_f32 v245, v255, v245, 1.0
	v_rcp_f32_e32 v250, v246
	v_rcp_f32_e32 v251, v247
	s_nop 0
	v_pk_fma_f32 v[252:253], v[246:247], v[250:251], 1.0 op_sel_hi:[1,1,0] neg_lo:[1,0,0] neg_hi:[1,0,0]
	v_pk_fma_f32 v[250:251], v[252:253], v[250:251], v[250:251]
	v_pk_fma_f32 v[252:253], v[246:247], v[250:251], 1.0 op_sel_hi:[1,1,0] neg_lo:[1,0,0] neg_hi:[1,0,0]
	v_pk_fma_f32 v[254:255], v[252:253], v[250:251], v[250:251]
	v_pk_fma_f32 v[252:253], v[246:247], v[254:255], 1.0 op_sel_hi:[1,1,0] neg_lo:[1,0,0] neg_hi:[1,0,0]
	v_pk_fma_f32 v[254:255], v[252:253], v[250:251], v[254:255]
	v_div_fixup_f32 v246, v254, v246, 1.0
	v_div_fixup_f32 v247, v255, v247, 1.0
	v_rcp_f32_e32 v250, v248
	v_rcp_f32_e32 v251, v249
	s_nop 0
	v_pk_fma_f32 v[252:253], v[248:249], v[250:251], 1.0 op_sel_hi:[1,1,0] neg_lo:[1,0,0] neg_hi:[1,0,0]
	v_pk_fma_f32 v[250:251], v[252:253], v[250:251], v[250:251]
	v_pk_fma_f32 v[252:253], v[248:249], v[250:251], 1.0 op_sel_hi:[1,1,0] neg_lo:[1,0,0] neg_hi:[1,0,0]
	v_pk_fma_f32 v[254:255], v[252:253], v[250:251], v[250:251]
	v_pk_fma_f32 v[252:253], v[248:249], v[254:255], 1.0 op_sel_hi:[1,1,0] neg_lo:[1,0,0] neg_hi:[1,0,0]
	v_pk_fma_f32 v[254:255], v[252:253], v[250:251], v[254:255]
	v_div_fixup_f32 v248, v254, v248, 1.0
	v_div_fixup_f32 v249, v255, v249, 1.0
	v_lshlrev_b32_e32 v50, 16, v42
	v_and_b32_e32 v51, 0xffff0000, v42
	v_lshlrev_b32_e32 v52, 16, v44
	v_and_b32_e32 v53, 0xffff0000, v44
	v_lshlrev_b32_e32 v44, 16, v45
	v_and_b32_e32 v45, 0xffff0000, v45
	v_lshlrev_b32_e32 v42, 16, v43
	v_and_b32_e32 v43, 0xffff0000, v43
	v_pk_fma_f32 v[28:29], v[28:29], v[242:243], v[50:51]
	v_pk_fma_f32 v[38:39], v[26:27], v[248:249], v[44:45]
	v_pk_fma_f32 v[26:27], v[24:25], v[244:245], v[52:53]
	v_add_lshl_u32 v40, v146, v34, 1
	v_pk_fma_f32 v[30:31], v[30:31], v[246:247], v[42:43]
	v_cvt_pk_bf16_f32 v24, v28, v29
	s_nop 0
	v_cvt_pk_bf16_f32 v25, v30, v31
	v_cvt_pk_bf16_f32 v26, v26, v27
	v_cvt_pk_bf16_f32 v27, v38, v39
	buffer_store_dwordx4 v[24:27], v40, s[24:27], 0 offen sc1
	s_nop 0
	s_waitcnt vmcnt(7)
; __device__ __forceinline__ u32x4 pack8(const f32x4 v0, const f32x4 v1) { u32x4 w; w.x = pk2(v0[0], v0[1]); w.y = pk2(v0[2], v0[3]); w.z = pk2(v1[0], v1[1]); w.w = pk2(v1[2], v1[3]); return w; }
; __device__ __forceinline__ void unpack8(const u32x4 w, f32x4& v0, f32x4& v1) { v0 = (f32x4){bflo(w.x), bfhi(w.x), bflo(w.y), bfhi(w.y)}; v1 = (f32x4){bflo(w.z), bfhi(w.z), bflo(w.w), bfhi(w.w)}; }
; __device__ __forceinline__ float sigmoidf_(float x) { return 1.0f / (1.0f + __expf(-x)); }
;     __device__ __forceinline__ void operator()(const f32x4 (&acc)[2][2][4][2], const Unit& u, int wr, int wc, int fr, int fq) const {
;     ...
;                 const int row = row0 + ai * 128 + m * 16;
;                 const bf16_t* rowp = z + (size_t)row * DIN + col0;
; #pragma unroll
;                 for (int bj = 0; bj < 2; ++bj) {
;                     const u32x4 gw = *(const u32x4*)(rowp + O_GA + bj * 128);
;                     f32x4 g0, g1; unpack8(gw, g0, g1);
;                     f32x4 v0, v1;
; #pragma unroll
;                     for (int j = 0; j < 4; ++j) { v0[j] = sigmoidf_(g0[j]) * acc[ai][bj][m][0][j]; v1[j] = sigmoidf_(g1[j]) * acc[ai][bj][m][1][j]; }
;                     const u32x4 mw = *(const u32x4*)(rowp + bj * 128); f32x4 m0, m1; unpack8(mw, m0, m1); v0 += m0; v1 += m1;
;                     __builtin_amdgcn_raw_buffer_store_b128(pack8(v0, v1), rsrc, (unsigned)(((size_t)row * DIN + col0 + bj * 128) * 2), 0, 16  ); }
	v_mov_b32_e32 v24, v212
	v_mov_b32_e32 v25, v213
	v_mov_b32_e32 v26, v214
	v_mov_b32_e32 v27, v215
	v_mov_b32_e32 v28, v216
	v_mov_b32_e32 v29, v217
	v_mov_b32_e32 v30, v218
	v_mov_b32_e32 v31, v219
	s_mov_b32 s100, 0xbfb8aa3b
	v_lshlrev_b32_e32 v242, 16, v26
	v_and_b32_e32 v243, 0xffff0000, v26
	v_lshlrev_b32_e32 v244, 16, v24
	v_and_b32_e32 v245, 0xffff0000, v24
	v_lshlrev_b32_e32 v246, 16, v25
	v_and_b32_e32 v247, 0xffff0000, v25
	v_lshlrev_b32_e32 v248, 16, v27
	v_and_b32_e32 v249, 0xffff0000, v27
	v_pk_mul_f32 v[242:243], v[242:243], s[100:101] op_sel_hi:[1,0]
	v_pk_mul_f32 v[244:245], v[244:245], s[100:101] op_sel_hi:[1,0]
	v_pk_mul_f32 v[246:247], v[246:247], s[100:101] op_sel_hi:[1,0]
	v_pk_mul_f32 v[248:249], v[248:249], s[100:101] op_sel_hi:[1,0]
	v_exp_f32_e32 v242, v242
	v_exp_f32_e32 v243, v243
	v_exp_f32_e32 v244, v244
	v_exp_f32_e32 v245, v245
	v_exp_f32_e32 v246, v246
	v_exp_f32_e32 v247, v247
	v_exp_f32_e32 v248, v248
	v_exp_f32_e32 v249, v249
	s_nop 0
	v_pk_add_f32 v[242:243], v[242:243], 1.0 op_sel_hi:[1,0]
	v_pk_add_f32 v[244:245], v[244:245], 1.0 op_sel_hi:[1,0]
	v_pk_add_f32 v[246:247], v[246:247], 1.0 op_sel_hi:[1,0]
	v_pk_add_f32 v[248:249], v[248:249], 1.0 op_sel_hi:[1,0]
	v_rcp_f32_e32 v250, v242
	v_rcp_f32_e32 v251, v243
	s_nop 0
	v_pk_fma_f32 v[252:253], v[242:243], v[250:251], 1.0 op_sel_hi:[1,1,0] neg_lo:[1,0,0] neg_hi:[1,0,0]
	v_pk_fma_f32 v[250:251], v[252:253], v[250:251], v[250:251]
	v_pk_fma_f32 v[252:253], v[242:243], v[250:251], 1.0 op_sel_hi:[1,1,0] neg_lo:[1,0,0] neg_hi:[1,0,0]
	v_pk_fma_f32 v[254:255], v[252:253], v[250:251], v[250:251]
	v_pk_fma_f32 v[252:253], v[242:243], v[254:255], 1.0 op_sel_hi:[1,1,0] neg_lo:[1,0,0] neg_hi:[1,0,0]
	v_pk_fma_f32 v[254:255], v[252:253], v[250:251], v[254:255]
	v_div_fixup_f32 v242, v254, v242, 1.0
	v_div_fixup_f32 v243, v255, v243, 1.0
	v_rcp_f32_e32 v250, v244
	v_rcp_f32_e32 v251, v245
	s_nop 0
	v_pk_fma_f32 v[252:253], v[244:245], v[250:251], 1.0 op_sel_hi:[1,1,0] neg_lo:[1,0,0] neg_hi:[1,0,0]
	v_pk_fma_f32 v[250:251], v[252:253], v[250:251], v[250:251]
	v_pk_fma_f32 v[252:253], v[244:245], v[250:251], 1.0 op_sel_hi:[1,1,0] neg_lo:[1,0,0] neg_hi:[1,0,0]
	v_pk_fma_f32 v[254:255], v[252:253], v[250:251], v[250:251]
	v_pk_fma_f32 v[252:253], v[244:245], v[254:255], 1.0 op_sel_hi:[1,1,0] neg_lo:[1,0,0] neg_hi:[1,0,0]
	v_pk_fma_f32 v[254:255], v[252:253], v[250:251], v[254:255]
	v_div_fixup_f32 v244, v254, v244, 1.0
	v_div_fixup_f32 v245, v255, v245, 1.0
	v_rcp_f32_e32 v250, v246
	v_rcp_f32_e32 v251, v247
	s_nop 0
	v_pk_fma_f32 v[252:253], v[246:247], v[250:251], 1.0 op_sel_hi:[1,1,0] neg_lo:[1,0,0] neg_hi:[1,0,0]
	v_pk_fma_f32 v[250:251], v[252:253], v[250:251], v[250:251]
	v_pk_fma_f32 v[252:253], v[246:247], v[250:251], 1.0 op_sel_hi:[1,1,0] neg_lo:[1,0,0] neg_hi:[1,0,0]
	v_pk_fma_f32 v[254:255], v[252:253], v[250:251], v[250:251]
	v_pk_fma_f32 v[252:253], v[246:247], v[254:255], 1.0 op_sel_hi:[1,1,0] neg_lo:[1,0,0] neg_hi:[1,0,0]
	v_pk_fma_f32 v[254:255], v[252:253], v[250:251], v[254:255]
	v_div_fixup_f32 v246, v254, v246, 1.0
	v_div_fixup_f32 v247, v255, v247, 1.0
	v_rcp_f32_e32 v250, v248
	v_rcp_f32_e32 v251, v249
	s_nop 0
	v_pk_fma_f32 v[252:253], v[248:249], v[250:251], 1.0 op_sel_hi:[1,1,0] neg_lo:[1,0,0] neg_hi:[1,0,0]
	v_pk_fma_f32 v[250:251], v[252:253], v[250:251], v[250:251]
	v_pk_fma_f32 v[252:253], v[248:249], v[250:251], 1.0 op_sel_hi:[1,1,0] neg_lo:[1,0,0] neg_hi:[1,0,0]
	v_pk_fma_f32 v[254:255], v[252:253], v[250:251], v[250:251]
	v_pk_fma_f32 v[252:253], v[248:249], v[254:255], 1.0 op_sel_hi:[1,1,0] neg_lo:[1,0,0] neg_hi:[1,0,0]
	v_pk_fma_f32 v[254:255], v[252:253], v[250:251], v[254:255]
	v_div_fixup_f32 v248, v254, v248, 1.0
	v_div_fixup_f32 v249, v255, v249, 1.0
	v_lshlrev_b32_e32 v36, 16, v28
	v_and_b32_e32 v37, 0xffff0000, v28
	v_lshlrev_b32_e32 v38, 16, v30
	v_and_b32_e32 v39, 0xffff0000, v30
	v_lshlrev_b32_e32 v30, 16, v31
	v_and_b32_e32 v31, 0xffff0000, v31
	v_lshlrev_b32_e32 v28, 16, v29
	v_and_b32_e32 v29, 0xffff0000, v29
	v_pk_fma_f32 v[20:21], v[20:21], v[244:245], v[36:37]
	v_pk_fma_f32 v[24:25], v[18:19], v[248:249], v[30:31]
	v_pk_fma_f32 v[18:19], v[16:17], v[242:243], v[38:39]
	v_cvt_pk_bf16_f32 v16, v20, v21
	v_pk_fma_f32 v[22:23], v[22:23], v[246:247], v[28:29]
	s_nop 0
	v_cvt_pk_bf16_f32 v17, v22, v23
	v_cvt_pk_bf16_f32 v18, v18, v19
	v_cvt_pk_bf16_f32 v19, v24, v25
	buffer_store_dwordx4 v[16:19], v40, s[24:27], 0 offen offset:256 sc1
	s_nop 1
	v_add_u32_e32 v16, 0xb0, v162
	v_mad_i64_i32 v[18:19], s[6:7], v16, s77, 0
	v_lshl_add_u64 v[16:17], v[18:19], 1, s[38:39]
	v_lshl_add_u64 v[16:17], v[16:17], 0, v[148:149]
	v_add_co_u32_e32 v20, vcc, s78, v16
	s_nop 1
	v_addc_co_u32_e32 v21, vcc, 0, v17, vcc
	s_waitcnt vmcnt(5)
; __device__ __forceinline__ u32x4 pack8(const f32x4 v0, const f32x4 v1) { u32x4 w; w.x = pk2(v0[0], v0[1]); w.y = pk2(v0[2], v0[3]); w.z = pk2(v1[0], v1[1]); w.w = pk2(v1[2], v1[3]); return w; }
; __device__ __forceinline__ void unpack8(const u32x4 w, f32x4& v0, f32x4& v1) { v0 = (f32x4){bflo(w.x), bfhi(w.x), bflo(w.y), bfhi(w.y)}; v1 = (f32x4){bflo(w.z), bfhi(w.z), bflo(w.w), bfhi(w.w)}; }
; __device__ __forceinline__ float sigmoidf_(float x) { return 1.0f / (1.0f + __expf(-x)); }
;     __device__ __forceinline__ void operator()(const f32x4 (&acc)[2][2][4][2], const Unit& u, int wr, int wc, int fr, int fq) const {
;     ...
;                 const int row = row0 + ai * 128 + m * 16;
;                 const bf16_t* rowp = z + (size_t)row * DIN + col0;
; #pragma unroll
;                 for (int bj = 0; bj < 2; ++bj) {
;                     const u32x4 gw = *(const u32x4*)(rowp + O_GA + bj * 128);
;                     f32x4 g0, g1; unpack8(gw, g0, g1);
;                     f32x4 v0, v1;
; #pragma unroll
;                     for (int j = 0; j < 4; ++j) { v0[j] = sigmoidf_(g0[j]) * acc[ai][bj][m][0][j]; v1[j] = sigmoidf_(g1[j]) * acc[ai][bj][m][1][j]; }
;                     const u32x4 mw = *(const u32x4*)(rowp + bj * 128); f32x4 m0, m1; unpack8(mw, m0, m1); v0 += m0; v1 += m1;
;                     __builtin_amdgcn_raw_buffer_store_b128(pack8(v0, v1), rsrc, (unsigned)(((size_t)row * DIN + col0 + bj * 128) * 2), 0, 16  ); }
	v_mov_b32_e32 v22, v232
	v_mov_b32_e32 v23, v233
	v_mov_b32_e32 v24, v234
	v_mov_b32_e32 v25, v235
	v_mov_b32_e32 v26, v236
	v_mov_b32_e32 v27, v237
	v_mov_b32_e32 v28, v238
	v_mov_b32_e32 v29, v239
	s_mov_b32 s100, 0xbfb8aa3b
	v_lshlrev_b32_e32 v242, 16, v22
	v_and_b32_e32 v243, 0xffff0000, v22
	v_lshlrev_b32_e32 v244, 16, v24
	v_and_b32_e32 v245, 0xffff0000, v24
	v_lshlrev_b32_e32 v246, 16, v23
	v_and_b32_e32 v247, 0xffff0000, v23
	v_lshlrev_b32_e32 v248, 16, v25
	v_and_b32_e32 v249, 0xffff0000, v25
	v_pk_mul_f32 v[242:243], v[242:243], s[100:101] op_sel_hi:[1,0]
	v_pk_mul_f32 v[244:245], v[244:245], s[100:101] op_sel_hi:[1,0]
	v_pk_mul_f32 v[246:247], v[246:247], s[100:101] op_sel_hi:[1,0]
	v_pk_mul_f32 v[248:249], v[248:249], s[100:101] op_sel_hi:[1,0]
	v_exp_f32_e32 v242, v242
	v_exp_f32_e32 v243, v243
	v_exp_f32_e32 v244, v244
	v_exp_f32_e32 v245, v245
	v_exp_f32_e32 v246, v246
	v_exp_f32_e32 v247, v247
	v_exp_f32_e32 v248, v248
	v_exp_f32_e32 v249, v249
	s_nop 0
	v_pk_add_f32 v[242:243], v[242:243], 1.0 op_sel_hi:[1,0]
	v_pk_add_f32 v[244:245], v[244:245], 1.0 op_sel_hi:[1,0]
	v_pk_add_f32 v[246:247], v[246:247], 1.0 op_sel_hi:[1,0]
	v_pk_add_f32 v[248:249], v[248:249], 1.0 op_sel_hi:[1,0]
	v_rcp_f32_e32 v250, v242
	v_rcp_f32_e32 v251, v243
	s_nop 0
	v_pk_fma_f32 v[252:253], v[242:243], v[250:251], 1.0 op_sel_hi:[1,1,0] neg_lo:[1,0,0] neg_hi:[1,0,0]
	v_pk_fma_f32 v[250:251], v[252:253], v[250:251], v[250:251]
	v_pk_fma_f32 v[252:253], v[242:243], v[250:251], 1.0 op_sel_hi:[1,1,0] neg_lo:[1,0,0] neg_hi:[1,0,0]
	v_pk_fma_f32 v[254:255], v[252:253], v[250:251], v[250:251]
	v_pk_fma_f32 v[252:253], v[242:243], v[254:255], 1.0 op_sel_hi:[1,1,0] neg_lo:[1,0,0] neg_hi:[1,0,0]
	v_pk_fma_f32 v[254:255], v[252:253], v[250:251], v[254:255]
	v_div_fixup_f32 v242, v254, v242, 1.0
	v_div_fixup_f32 v243, v255, v243, 1.0
	v_rcp_f32_e32 v250, v244
	v_rcp_f32_e32 v251, v245
	s_nop 0
	v_pk_fma_f32 v[252:253], v[244:245], v[250:251], 1.0 op_sel_hi:[1,1,0] neg_lo:[1,0,0] neg_hi:[1,0,0]
	v_pk_fma_f32 v[250:251], v[252:253], v[250:251], v[250:251]
	v_pk_fma_f32 v[252:253], v[244:245], v[250:251], 1.0 op_sel_hi:[1,1,0] neg_lo:[1,0,0] neg_hi:[1,0,0]
	v_pk_fma_f32 v[254:255], v[252:253], v[250:251], v[250:251]
	v_pk_fma_f32 v[252:253], v[244:245], v[254:255], 1.0 op_sel_hi:[1,1,0] neg_lo:[1,0,0] neg_hi:[1,0,0]
	v_pk_fma_f32 v[254:255], v[252:253], v[250:251], v[254:255]
	v_div_fixup_f32 v244, v254, v244, 1.0
	v_div_fixup_f32 v245, v255, v245, 1.0
	v_rcp_f32_e32 v250, v246
	v_rcp_f32_e32 v251, v247
	s_nop 0
	v_pk_fma_f32 v[252:253], v[246:247], v[250:251], 1.0 op_sel_hi:[1,1,0] neg_lo:[1,0,0] neg_hi:[1,0,0]
	v_pk_fma_f32 v[250:251], v[252:253], v[250:251], v[250:251]
	v_pk_fma_f32 v[252:253], v[246:247], v[250:251], 1.0 op_sel_hi:[1,1,0] neg_lo:[1,0,0] neg_hi:[1,0,0]
	v_pk_fma_f32 v[254:255], v[252:253], v[250:251], v[250:251]
	v_pk_fma_f32 v[252:253], v[246:247], v[254:255], 1.0 op_sel_hi:[1,1,0] neg_lo:[1,0,0] neg_hi:[1,0,0]
	v_pk_fma_f32 v[254:255], v[252:253], v[250:251], v[254:255]
	v_div_fixup_f32 v246, v254, v246, 1.0
	v_div_fixup_f32 v247, v255, v247, 1.0
	v_rcp_f32_e32 v250, v248
	v_rcp_f32_e32 v251, v249
	s_nop 0
	v_pk_fma_f32 v[252:253], v[248:249], v[250:251], 1.0 op_sel_hi:[1,1,0] neg_lo:[1,0,0] neg_hi:[1,0,0]
	v_pk_fma_f32 v[250:251], v[252:253], v[250:251], v[250:251]
	v_pk_fma_f32 v[252:253], v[248:249], v[250:251], 1.0 op_sel_hi:[1,1,0] neg_lo:[1,0,0] neg_hi:[1,0,0]
	v_pk_fma_f32 v[254:255], v[252:253], v[250:251], v[250:251]
	v_pk_fma_f32 v[252:253], v[248:249], v[254:255], 1.0 op_sel_hi:[1,1,0] neg_lo:[1,0,0] neg_hi:[1,0,0]
	v_pk_fma_f32 v[254:255], v[252:253], v[250:251], v[254:255]
	v_div_fixup_f32 v248, v254, v248, 1.0
	v_div_fixup_f32 v249, v255, v249, 1.0
	v_lshlrev_b32_e32 v34, 16, v26
	v_and_b32_e32 v35, 0xffff0000, v26
	v_lshlrev_b32_e32 v36, 16, v28
	v_and_b32_e32 v37, 0xffff0000, v28
	v_lshlrev_b32_e32 v28, 16, v29
	v_and_b32_e32 v29, 0xffff0000, v29
	v_lshlrev_b32_e32 v26, 16, v27
	v_and_b32_e32 v27, 0xffff0000, v27
	v_pk_fma_f32 v[12:13], v[12:13], v[242:243], v[34:35]
	v_pk_fma_f32 v[22:23], v[10:11], v[248:249], v[28:29]
	v_pk_fma_f32 v[10:11], v[8:9], v[244:245], v[36:37]
	v_add_lshl_u32 v24, v146, v18, 1
	v_pk_fma_f32 v[14:15], v[14:15], v[246:247], v[26:27]
	v_cvt_pk_bf16_f32 v8, v12, v13
	s_nop 0
	v_cvt_pk_bf16_f32 v9, v14, v15
	v_cvt_pk_bf16_f32 v10, v10, v11
	v_cvt_pk_bf16_f32 v11, v22, v23
	buffer_store_dwordx4 v[8:11], v24, s[24:27], 0 offen sc1
	s_nop 0
	s_waitcnt vmcnt(3)
; __device__ __forceinline__ u32x4 pack8(const f32x4 v0, const f32x4 v1) { u32x4 w; w.x = pk2(v0[0], v0[1]); w.y = pk2(v0[2], v0[3]); w.z = pk2(v1[0], v1[1]); w.w = pk2(v1[2], v1[3]); return w; }
; __device__ __forceinline__ void unpack8(const u32x4 w, f32x4& v0, f32x4& v1) { v0 = (f32x4){bflo(w.x), bfhi(w.x), bflo(w.y), bfhi(w.y)}; v1 = (f32x4){bflo(w.z), bfhi(w.z), bflo(w.w), bfhi(w.w)}; }
; __device__ __forceinline__ float sigmoidf_(float x) { return 1.0f / (1.0f + __expf(-x)); }
;     __device__ __forceinline__ void operator()(const f32x4 (&acc)[2][2][4][2], const Unit& u, int wr, int wc, int fr, int fq) const {
;     ...
;                 const int row = row0 + ai * 128 + m * 16;
;                 const bf16_t* rowp = z + (size_t)row * DIN + col0;
; #pragma unroll
;                 for (int bj = 0; bj < 2; ++bj) {
;                     const u32x4 gw = *(const u32x4*)(rowp + O_GA + bj * 128);
;                     f32x4 g0, g1; unpack8(gw, g0, g1);
;                     f32x4 v0, v1;
; #pragma unroll
;                     for (int j = 0; j < 4; ++j) { v0[j] = sigmoidf_(g0[j]) * acc[ai][bj][m][0][j]; v1[j] = sigmoidf_(g1[j]) * acc[ai][bj][m][1][j]; }
;                     const u32x4 mw = *(const u32x4*)(rowp + bj * 128); f32x4 m0, m1; unpack8(mw, m0, m1); v0 += m0; v1 += m1;
;                     __builtin_amdgcn_raw_buffer_store_b128(pack8(v0, v1), rsrc, (unsigned)(((size_t)row * DIN + col0 + bj * 128) * 2), 0, 16  ); }
;             }
;         asm volatile("s_waitcnt vmcnt(0)" ::: "memory");
;         if (fr == 0 && fq == 0) (void)__hip_atomic_fetch_add(ready + 64 * (pm_off + u.pm), 1u, __ATOMIC_RELAXED, __HIP_MEMORY_SCOPE_AGENT);
	v_mov_b32_e32 v8, v204
	v_mov_b32_e32 v9, v205
	v_mov_b32_e32 v10, v206
	v_mov_b32_e32 v11, v207
	v_mov_b32_e32 v12, v208
	v_mov_b32_e32 v13, v209
	v_mov_b32_e32 v14, v210
	v_mov_b32_e32 v15, v211
	s_mov_b32 s100, 0xbfb8aa3b
	v_lshlrev_b32_e32 v242, 16, v10
	v_and_b32_e32 v243, 0xffff0000, v10
	v_lshlrev_b32_e32 v244, 16, v8
	v_and_b32_e32 v245, 0xffff0000, v8
	v_lshlrev_b32_e32 v246, 16, v9
	v_and_b32_e32 v247, 0xffff0000, v9
	v_lshlrev_b32_e32 v248, 16, v11
	v_and_b32_e32 v249, 0xffff0000, v11
	v_pk_mul_f32 v[242:243], v[242:243], s[100:101] op_sel_hi:[1,0]
	v_pk_mul_f32 v[244:245], v[244:245], s[100:101] op_sel_hi:[1,0]
	v_pk_mul_f32 v[246:247], v[246:247], s[100:101] op_sel_hi:[1,0]
	v_pk_mul_f32 v[248:249], v[248:249], s[100:101] op_sel_hi:[1,0]
	v_exp_f32_e32 v242, v242
	v_exp_f32_e32 v243, v243
	v_exp_f32_e32 v244, v244
	v_exp_f32_e32 v245, v245
	v_exp_f32_e32 v246, v246
	v_exp_f32_e32 v247, v247
	v_exp_f32_e32 v248, v248
	v_exp_f32_e32 v249, v249
	s_nop 0
	v_pk_add_f32 v[242:243], v[242:243], 1.0 op_sel_hi:[1,0]
	v_pk_add_f32 v[244:245], v[244:245], 1.0 op_sel_hi:[1,0]
	v_pk_add_f32 v[246:247], v[246:247], 1.0 op_sel_hi:[1,0]
	v_pk_add_f32 v[248:249], v[248:249], 1.0 op_sel_hi:[1,0]
	v_rcp_f32_e32 v250, v242
	v_rcp_f32_e32 v251, v243
	s_nop 0
	v_pk_fma_f32 v[252:253], v[242:243], v[250:251], 1.0 op_sel_hi:[1,1,0] neg_lo:[1,0,0] neg_hi:[1,0,0]
	v_pk_fma_f32 v[250:251], v[252:253], v[250:251], v[250:251]
	v_pk_fma_f32 v[252:253], v[242:243], v[250:251], 1.0 op_sel_hi:[1,1,0] neg_lo:[1,0,0] neg_hi:[1,0,0]
	v_pk_fma_f32 v[254:255], v[252:253], v[250:251], v[250:251]
	v_pk_fma_f32 v[252:253], v[242:243], v[254:255], 1.0 op_sel_hi:[1,1,0] neg_lo:[1,0,0] neg_hi:[1,0,0]
	v_pk_fma_f32 v[254:255], v[252:253], v[250:251], v[254:255]
	v_div_fixup_f32 v242, v254, v242, 1.0
	v_div_fixup_f32 v243, v255, v243, 1.0
	v_rcp_f32_e32 v250, v244
	v_rcp_f32_e32 v251, v245
	s_nop 0
	v_pk_fma_f32 v[252:253], v[244:245], v[250:251], 1.0 op_sel_hi:[1,1,0] neg_lo:[1,0,0] neg_hi:[1,0,0]
	v_pk_fma_f32 v[250:251], v[252:253], v[250:251], v[250:251]
	v_pk_fma_f32 v[252:253], v[244:245], v[250:251], 1.0 op_sel_hi:[1,1,0] neg_lo:[1,0,0] neg_hi:[1,0,0]
	v_pk_fma_f32 v[254:255], v[252:253], v[250:251], v[250:251]
	v_pk_fma_f32 v[252:253], v[244:245], v[254:255], 1.0 op_sel_hi:[1,1,0] neg_lo:[1,0,0] neg_hi:[1,0,0]
	v_pk_fma_f32 v[254:255], v[252:253], v[250:251], v[254:255]
	v_div_fixup_f32 v244, v254, v244, 1.0
	v_div_fixup_f32 v245, v255, v245, 1.0
	v_rcp_f32_e32 v250, v246
	v_rcp_f32_e32 v251, v247
	s_nop 0
	v_pk_fma_f32 v[252:253], v[246:247], v[250:251], 1.0 op_sel_hi:[1,1,0] neg_lo:[1,0,0] neg_hi:[1,0,0]
	v_pk_fma_f32 v[250:251], v[252:253], v[250:251], v[250:251]
	v_pk_fma_f32 v[252:253], v[246:247], v[250:251], 1.0 op_sel_hi:[1,1,0] neg_lo:[1,0,0] neg_hi:[1,0,0]
	v_pk_fma_f32 v[254:255], v[252:253], v[250:251], v[250:251]
	v_pk_fma_f32 v[252:253], v[246:247], v[254:255], 1.0 op_sel_hi:[1,1,0] neg_lo:[1,0,0] neg_hi:[1,0,0]
	v_pk_fma_f32 v[254:255], v[252:253], v[250:251], v[254:255]
	v_div_fixup_f32 v246, v254, v246, 1.0
	v_div_fixup_f32 v247, v255, v247, 1.0
	v_rcp_f32_e32 v250, v248
	v_rcp_f32_e32 v251, v249
	s_nop 0
	v_pk_fma_f32 v[252:253], v[248:249], v[250:251], 1.0 op_sel_hi:[1,1,0] neg_lo:[1,0,0] neg_hi:[1,0,0]
	v_pk_fma_f32 v[250:251], v[252:253], v[250:251], v[250:251]
	v_pk_fma_f32 v[252:253], v[248:249], v[250:251], 1.0 op_sel_hi:[1,1,0] neg_lo:[1,0,0] neg_hi:[1,0,0]
	v_pk_fma_f32 v[254:255], v[252:253], v[250:251], v[250:251]
	v_pk_fma_f32 v[252:253], v[248:249], v[254:255], 1.0 op_sel_hi:[1,1,0] neg_lo:[1,0,0] neg_hi:[1,0,0]
	v_pk_fma_f32 v[254:255], v[252:253], v[250:251], v[254:255]
	v_div_fixup_f32 v248, v254, v248, 1.0
	v_div_fixup_f32 v249, v255, v249, 1.0
	v_lshlrev_b32_e32 v20, 16, v12
	v_and_b32_e32 v21, 0xffff0000, v12
	v_lshlrev_b32_e32 v22, 16, v14
	v_and_b32_e32 v23, 0xffff0000, v14
	v_lshlrev_b32_e32 v14, 16, v15
	v_and_b32_e32 v15, 0xffff0000, v15
	v_lshlrev_b32_e32 v12, 16, v13
	v_and_b32_e32 v13, 0xffff0000, v13
	v_pk_fma_f32 v[4:5], v[4:5], v[244:245], v[20:21]
	v_pk_fma_f32 v[8:9], v[2:3], v[248:249], v[14:15]
	v_pk_fma_f32 v[2:3], v[0:1], v[242:243], v[22:23]
	v_pk_fma_f32 v[6:7], v[6:7], v[246:247], v[12:13]
	v_cvt_pk_bf16_f32 v0, v4, v5
	s_nop 0
	v_cvt_pk_bf16_f32 v1, v6, v7
	v_cvt_pk_bf16_f32 v2, v2, v3
	v_cvt_pk_bf16_f32 v3, v8, v9
	buffer_store_dwordx4 v[0:3], v24, s[24:27], 0 offen offset:256 sc1
	s_waitcnt vmcnt(0)
	s_and_saveexec_b64 s[14:15], s[10:11]
	s_cbranch_execz .LBB0_692
	s_mov_b64 s[16:17], exec
	v_mbcnt_lo_u32_b32 v0, s16, 0
	v_mbcnt_hi_u32_b32 v0, s17, v0
	v_cmp_eq_u32_e32 vcc, 0, v0
	s_and_b64 s[6:7], exec, vcc
	s_mov_b64 exec, s[6:7]
	s_cbranch_execz .LBB0_692
	s_lshl_b32 s6, s79, 6
	s_ashr_i32 s7, s6, 31
	s_lshl_b64 s[6:7], s[6:7], 2
	s_add_u32 s6, s34, s6
	s_addc_u32 s7, s35, s7
	s_bcnt1_i32_b64 s8, s[16:17]
	v_mov_b32_e32 v0, s8
	global_atomic_add v131, v0, s[6:7]
	s_branch .LBB0_692

; #define PG8_STAGE(bufoff, gbase, voff) do { _Pragma("unroll") for (int _i = 0; _i < 2; ++_i) \
;         __builtin_amdgcn_global_load_lds((const unsigned*)((const char*)(gbase) + (voff)[_i]), (LAS unsigned*)(lds + (bufoff) + ldsw + _i * 8192), 16, 0, 0); } while (0)
; #define PG8_LDA(dst, b, h) do { _Pragma("unroll") for (int m = 0; m < 4; ++m) _Pragma("unroll") for (int k = 0; k < 2; ++k) dst[m][k] = *(const LAS bf16x8*)(lds + PG8_SA(b, h) + aoff + m * 2048 + k * 1024); } while (0)
; #define PG8_LDB(dst, b, h) do { _Pragma("unroll") for (int n = 0; n < 2; ++n) _Pragma("unroll") for (int k = 0; k < 2; ++k) dst[n][k] = *(const LAS bf16x8*)(lds + PG8_SB(b, h) + boff + n * 2048 + k * 1024); } while (0)
; #define PG8_MMA(ai, bj, At, Bt) do { __builtin_amdgcn_s_setprio(1); _Pragma("unroll") for (int m = 0; m < 4; ++m) _Pragma("unroll") for (int n = 0; n < 2; ++n) _Pragma("unroll") for (int k = 0; k < 2; ++k) \
;         acc[ai][bj][m][n] = __builtin_amdgcn_mfma_f32_16x16x32_bf16(Bt[n][k], At[m][k], acc[ai][bj][m][n], 0, 0, 0); __builtin_amdgcn_s_setprio(0); } while (0)
; #define PG8_WAIT_V(n) asm volatile("s_waitcnt vmcnt(" #n ")" ::: "memory")
; #define PG8_WAIT_L(n) asm volatile("s_waitcnt lgkmcnt(" #n ")" ::: "memory")
; #define PG8_BAR __builtin_amdgcn_s_barrier()
; #define PG8_SCHED __builtin_amdgcn_sched_barrier(0)
;     ...
;             PG8_LDB(B0, 0, 0); PG8_SCHED; PG8_LDA(At, 0, 0); PG8_STAGE(PG8_SA(1, 1), a1 + hA, voffA);
;             PG8_WAIT_L(8); PG8_BAR; PG8_WAIT_L(0); PG8_MMA(0, 0, At, B0); PG8_BAR; PG8_SCHED;
;             PG8_LDB(B1, 0, 1); PG8_STAGE(PG8_SB(0, 0), b2, voffB);
;             PG8_BAR; PG8_WAIT_L(0); PG8_MMA(0, 1, At, B1); PG8_BAR;
;             PG8_LDA(At, 0, 1); PG8_STAGE(PG8_SA(0, 0), a2, voffA);
;             PG8_BAR; PG8_WAIT_L(0); PG8_MMA(1, 0, At, B0); PG8_BAR; PG8_SCHED;
;             PG8_STAGE(PG8_SB(0, 1), b2 + hB, voffB);
;             PG8_WAIT_V(6); PG8_BAR; PG8_MMA(1, 1, At, B1); PG8_BAR;
.LBB0_723:
	ds_read_b128 v[140:143], v155
	ds_read_b128 v[146:149], v155 offset:1024
	ds_read_b128 v[158:161], v155 offset:2048
	ds_read_b128 v[162:165], v155 offset:3072
	s_add_u32 s14, s12, 0xfffe0080
	s_addc_u32 s15, s13, -1
	s_cmp_eq_u32 s39, 4
	s_cselect_b32 s17, s7, s15
	s_cselect_b32 s16, s8, s14
	s_cselect_b32 s15, s9, s33
	s_cselect_b32 s14, s18, s19
	v_lshl_add_u64 v[150:151], s[12:13], 0, v[138:139]
	s_add_i32 m0, s67, 0xc000
	ds_read_b128 v[170:173], v156
	ds_read_b128 v[174:177], v156 offset:1024
	ds_read_b128 v[178:181], v156 offset:2048
	ds_read_b128 v[182:185], v156 offset:3072
	ds_read_b128 v[186:189], v156 offset:4096
	ds_read_b128 v[190:193], v156 offset:5120
	ds_read_b128 v[194:197], v156 offset:6144
	ds_read_b128 v[198:201], v156 offset:7168
	global_load_lds_dwordx4 v[150:151], off
	v_lshl_add_u64 v[150:151], s[12:13], 0, v[136:137]
	s_add_i32 m0, s67, 0xe000
	s_nop 0
	global_load_lds_dwordx4 v[150:151], off
	s_waitcnt lgkmcnt(8)
	s_barrier
	s_waitcnt lgkmcnt(0)
	s_setprio 1
	s_waitcnt lgkmcnt(0)
	v_mfma_f32_16x16x32_bf16 v[124:127], v[140:143], v[170:173], v[124:127]
	v_mfma_f32_16x16x32_bf16 v[120:123], v[158:161], v[170:173], v[120:123]
	v_mfma_f32_16x16x32_bf16 v[108:111], v[140:143], v[178:181], v[108:111]
	v_mfma_f32_16x16x32_bf16 v[104:107], v[158:161], v[178:181], v[104:107]
	v_mfma_f32_16x16x32_bf16 v[92:95], v[140:143], v[186:189], v[92:95]
	v_mfma_f32_16x16x32_bf16 v[88:91], v[158:161], v[186:189], v[88:91]
	v_mfma_f32_16x16x32_bf16 v[76:79], v[140:143], v[194:197], v[76:79]
	v_mfma_f32_16x16x32_bf16 v[72:75], v[158:161], v[194:197], v[72:75]
	v_mfma_f32_16x16x32_bf16 v[124:127], v[146:149], v[174:177], v[124:127]
	v_mfma_f32_16x16x32_bf16 v[120:123], v[162:165], v[174:177], v[120:123]
	v_mfma_f32_16x16x32_bf16 v[108:111], v[146:149], v[182:185], v[108:111]
	v_mfma_f32_16x16x32_bf16 v[104:107], v[162:165], v[182:185], v[104:107]
	v_mfma_f32_16x16x32_bf16 v[92:95], v[146:149], v[190:193], v[92:95]
	v_mfma_f32_16x16x32_bf16 v[88:91], v[162:165], v[190:193], v[88:91]
	v_mfma_f32_16x16x32_bf16 v[76:79], v[146:149], v[198:201], v[76:79]
	v_mfma_f32_16x16x32_bf16 v[72:75], v[162:165], v[198:201], v[72:75]
	s_setprio 0
	s_barrier
	s_add_i32 s42, s75, s66
	v_lshl_add_u64 v[150:151], s[14:15], 0, v[130:131]
	s_mov_b32 m0, s42
	ds_read_b128 v[202:205], v157
	ds_read_b128 v[206:209], v157 offset:1024
	ds_read_b128 v[210:213], v157 offset:2048
	ds_read_b128 v[214:217], v157 offset:3072
	global_load_lds_dwordx4 v[150:151], off
	v_lshl_add_u64 v[218:219], s[14:15], 0, v[134:135]
	s_add_i32 m0, s42, 0x2000
	s_nop 0
	global_load_lds_dwordx4 v[218:219], off
	s_barrier
	s_waitcnt lgkmcnt(0)
	s_setprio 1
	s_waitcnt lgkmcnt(0)
	v_mfma_f32_16x16x32_bf16 v[116:119], v[202:205], v[170:173], v[116:119]
	v_mfma_f32_16x16x32_bf16 v[112:115], v[210:213], v[170:173], v[112:115]
	v_mfma_f32_16x16x32_bf16 v[100:103], v[202:205], v[178:181], v[100:103]
	v_mfma_f32_16x16x32_bf16 v[96:99], v[210:213], v[178:181], v[96:99]
	v_mfma_f32_16x16x32_bf16 v[84:87], v[202:205], v[186:189], v[84:87]
	v_mfma_f32_16x16x32_bf16 v[80:83], v[210:213], v[186:189], v[80:83]
	v_mfma_f32_16x16x32_bf16 v[68:71], v[202:205], v[194:197], v[68:71]
	v_mfma_f32_16x16x32_bf16 v[64:67], v[210:213], v[194:197], v[64:67]
	v_mfma_f32_16x16x32_bf16 v[116:119], v[206:209], v[174:177], v[116:119]
	v_mfma_f32_16x16x32_bf16 v[112:115], v[214:217], v[174:177], v[112:115]
	v_mfma_f32_16x16x32_bf16 v[100:103], v[206:209], v[182:185], v[100:103]
	v_mfma_f32_16x16x32_bf16 v[96:99], v[214:217], v[182:185], v[96:99]
	v_mfma_f32_16x16x32_bf16 v[84:87], v[206:209], v[190:193], v[84:87]
	v_mfma_f32_16x16x32_bf16 v[80:83], v[214:217], v[190:193], v[80:83]
	v_mfma_f32_16x16x32_bf16 v[68:71], v[206:209], v[198:201], v[68:71]
	v_mfma_f32_16x16x32_bf16 v[64:67], v[214:217], v[198:201], v[64:67]
	s_setprio 0
	s_mov_b32 m0, s67
	v_lshl_add_u64 v[220:221], s[16:17], 0, v[128:129]
	s_barrier
	ds_read_b128 v[170:173], v156 offset:16384
	ds_read_b128 v[174:177], v156 offset:17408
	ds_read_b128 v[178:181], v156 offset:18432
	ds_read_b128 v[182:185], v156 offset:19456
	ds_read_b128 v[186:189], v156 offset:20480
	ds_read_b128 v[190:193], v156 offset:21504
	ds_read_b128 v[194:197], v156 offset:22528
	ds_read_b128 v[198:201], v156 offset:23552
	global_load_lds_dwordx4 v[220:221], off
	v_lshl_add_u64 v[222:223], s[16:17], 0, v[132:133]
	s_mov_b32 m0, s68
	s_nop 0
	global_load_lds_dwordx4 v[222:223], off
	s_barrier
	s_waitcnt lgkmcnt(0)
	s_setprio 1
	s_waitcnt lgkmcnt(0)
	v_mfma_f32_16x16x32_bf16 v[60:63], v[140:143], v[170:173], v[60:63]
	v_mfma_f32_16x16x32_bf16 v[56:59], v[158:161], v[170:173], v[56:59]
	v_mfma_f32_16x16x32_bf16 v[44:47], v[140:143], v[178:181], v[44:47]
	v_mfma_f32_16x16x32_bf16 v[40:43], v[158:161], v[178:181], v[40:43]
	v_mfma_f32_16x16x32_bf16 v[28:31], v[140:143], v[186:189], v[28:31]
	v_mfma_f32_16x16x32_bf16 v[24:27], v[158:161], v[186:189], v[24:27]
	v_mfma_f32_16x16x32_bf16 v[12:15], v[140:143], v[194:197], v[12:15]
	v_mfma_f32_16x16x32_bf16 v[8:11], v[158:161], v[194:197], v[8:11]
	v_mfma_f32_16x16x32_bf16 v[60:63], v[146:149], v[174:177], v[60:63]
	v_mfma_f32_16x16x32_bf16 v[56:59], v[162:165], v[174:177], v[56:59]
	v_mfma_f32_16x16x32_bf16 v[44:47], v[146:149], v[182:185], v[44:47]
	v_mfma_f32_16x16x32_bf16 v[40:43], v[162:165], v[182:185], v[40:43]
	v_mfma_f32_16x16x32_bf16 v[28:31], v[146:149], v[190:193], v[28:31]
	v_mfma_f32_16x16x32_bf16 v[24:27], v[162:165], v[190:193], v[24:27]
	v_mfma_f32_16x16x32_bf16 v[12:15], v[146:149], v[198:201], v[12:15]
	v_mfma_f32_16x16x32_bf16 v[8:11], v[162:165], v[198:201], v[8:11]
	s_setprio 0
	s_barrier
; #define PG8_STAGE(bufoff, gbase, voff) do { _Pragma("unroll") for (int _i = 0; _i < 2; ++_i) \
;         __builtin_amdgcn_global_load_lds((const unsigned*)((const char*)(gbase) + (voff)[_i]), (LAS unsigned*)(lds + (bufoff) + ldsw + _i * 8192), 16, 0, 0); } while (0)
; #define PG8_LDA(dst, b, h) do { _Pragma("unroll") for (int m = 0; m < 4; ++m) _Pragma("unroll") for (int k = 0; k < 2; ++k) dst[m][k] = *(const LAS bf16x8*)(lds + PG8_SA(b, h) + aoff + m * 2048 + k * 1024); } while (0)
; #define PG8_LDB(dst, b, h) do { _Pragma("unroll") for (int n = 0; n < 2; ++n) _Pragma("unroll") for (int k = 0; k < 2; ++k) dst[n][k] = *(const LAS bf16x8*)(lds + PG8_SB(b, h) + boff + n * 2048 + k * 1024); } while (0)
; #define PG8_MMA(ai, bj, At, Bt) do { __builtin_amdgcn_s_setprio(1); _Pragma("unroll") for (int m = 0; m < 4; ++m) _Pragma("unroll") for (int n = 0; n < 2; ++n) _Pragma("unroll") for (int k = 0; k < 2; ++k) \
;         acc[ai][bj][m][n] = __builtin_amdgcn_mfma_f32_16x16x32_bf16(Bt[n][k], At[m][k], acc[ai][bj][m][n], 0, 0, 0); __builtin_amdgcn_s_setprio(0); } while (0)
; #define PG8_WAIT_V(n) asm volatile("s_waitcnt vmcnt(" #n ")" ::: "memory")
; #define PG8_WAIT_L(n) asm volatile("s_waitcnt lgkmcnt(" #n ")" ::: "memory")
; #define PG8_BAR __builtin_amdgcn_s_barrier()
; #define PG8_SCHED __builtin_amdgcn_sched_barrier(0)
;     ...
;             PG8_WAIT_V(6); PG8_BAR; PG8_MMA(1, 1, At, B1); PG8_BAR;
;             PG8_LDB(B0, 1, 0); PG8_SCHED; PG8_LDA(At, 1, 0); PG8_STAGE(PG8_SA(0, 1), a2 + hA, voffA);
;             PG8_WAIT_L(8); PG8_BAR; PG8_WAIT_L(0); PG8_MMA(0, 0, At, B0); PG8_BAR; PG8_SCHED;
;             PG8_LDB(B1, 1, 1); PG8_STAGE(PG8_SB(1, 0), b3, voffB);
;             PG8_BAR; PG8_WAIT_L(0); PG8_MMA(0, 1, At, B1); PG8_BAR;
;             PG8_LDA(At, 1, 1); PG8_STAGE(PG8_SA(1, 0), a3, voffA);
;             PG8_BAR; PG8_WAIT_L(0); PG8_MMA(1, 0, At, B0); PG8_BAR; PG8_SCHED;
	s_add_u32 s42, s14, 0x20000
	s_addc_u32 s43, s15, 0
	s_add_i32 s44, s76, s66
	v_lshl_add_u64 v[140:141], s[42:43], 0, v[130:131]
	s_mov_b32 m0, s44
	s_nop 0
	global_load_lds_dwordx4 v[140:141], off
	v_lshl_add_u64 v[140:141], s[42:43], 0, v[134:135]
	s_add_i32 m0, s44, 0x2000
	s_nop 0
	global_load_lds_dwordx4 v[140:141], off
	s_waitcnt vmcnt(6)
	s_barrier
	s_setprio 1
	v_mfma_f32_16x16x32_bf16 v[52:55], v[202:205], v[170:173], v[52:55]
	v_mfma_f32_16x16x32_bf16 v[48:51], v[210:213], v[170:173], v[48:51]
	v_mfma_f32_16x16x32_bf16 v[36:39], v[202:205], v[178:181], v[36:39]
	v_mfma_f32_16x16x32_bf16 v[32:35], v[210:213], v[178:181], v[32:35]
	v_mfma_f32_16x16x32_bf16 v[20:23], v[202:205], v[186:189], v[20:23]
	v_mfma_f32_16x16x32_bf16 v[16:19], v[210:213], v[186:189], v[16:19]
	v_mfma_f32_16x16x32_bf16 v[4:7], v[202:205], v[194:197], v[4:7]
	v_mfma_f32_16x16x32_bf16 v[0:3], v[210:213], v[194:197], v[0:3]
	v_mfma_f32_16x16x32_bf16 v[52:55], v[206:209], v[174:177], v[52:55]
	v_mfma_f32_16x16x32_bf16 v[48:51], v[214:217], v[174:177], v[48:51]
	v_mfma_f32_16x16x32_bf16 v[36:39], v[206:209], v[182:185], v[36:39]
	v_mfma_f32_16x16x32_bf16 v[32:35], v[214:217], v[182:185], v[32:35]
	v_mfma_f32_16x16x32_bf16 v[20:23], v[206:209], v[190:193], v[20:23]
	v_mfma_f32_16x16x32_bf16 v[16:19], v[214:217], v[190:193], v[16:19]
	v_mfma_f32_16x16x32_bf16 v[4:7], v[206:209], v[198:201], v[4:7]
	v_mfma_f32_16x16x32_bf16 v[0:3], v[214:217], v[198:201], v[0:3]
	s_setprio 0
	s_add_i32 s42, 0, 0x18000
	v_add_u32_e32 v162, s42, v153
	s_barrier
	ds_read_b128 v[140:143], v162
	ds_read_b128 v[146:149], v162 offset:1024
	ds_read_b128 v[158:161], v162 offset:2048
	ds_read_b128 v[162:165], v162 offset:3072
	s_add_u32 s16, s16, 0x20000
	s_addc_u32 s17, s17, 0
	s_mov_b32 m0, s69
	v_lshl_add_u64 v[202:203], s[16:17], 0, v[128:129]
	ds_read_b128 v[170:173], v156 offset:32768
	ds_read_b128 v[174:177], v156 offset:33792
	ds_read_b128 v[178:181], v156 offset:34816
	ds_read_b128 v[182:185], v156 offset:35840
	ds_read_b128 v[186:189], v156 offset:36864
	ds_read_b128 v[190:193], v156 offset:37888
	ds_read_b128 v[194:197], v156 offset:38912
	ds_read_b128 v[198:201], v156 offset:39936
	global_load_lds_dwordx4 v[202:203], off
	v_lshl_add_u64 v[202:203], s[16:17], 0, v[132:133]
	s_mov_b32 m0, s70
	s_nop 0
	global_load_lds_dwordx4 v[202:203], off
	s_waitcnt lgkmcnt(8)
	s_barrier
	s_waitcnt lgkmcnt(0)
	s_setprio 1
	s_waitcnt lgkmcnt(0)
	v_mfma_f32_16x16x32_bf16 v[124:127], v[140:143], v[170:173], v[124:127]
	v_mfma_f32_16x16x32_bf16 v[120:123], v[158:161], v[170:173], v[120:123]
	v_mfma_f32_16x16x32_bf16 v[108:111], v[140:143], v[178:181], v[108:111]
	v_mfma_f32_16x16x32_bf16 v[104:107], v[158:161], v[178:181], v[104:107]
	v_mfma_f32_16x16x32_bf16 v[92:95], v[140:143], v[186:189], v[92:95]
	v_mfma_f32_16x16x32_bf16 v[88:91], v[158:161], v[186:189], v[88:91]
	v_mfma_f32_16x16x32_bf16 v[76:79], v[140:143], v[194:197], v[76:79]
	v_mfma_f32_16x16x32_bf16 v[72:75], v[158:161], v[194:197], v[72:75]
	v_mfma_f32_16x16x32_bf16 v[124:127], v[146:149], v[174:177], v[124:127]
	v_mfma_f32_16x16x32_bf16 v[120:123], v[162:165], v[174:177], v[120:123]
	v_mfma_f32_16x16x32_bf16 v[108:111], v[146:149], v[182:185], v[108:111]
	v_mfma_f32_16x16x32_bf16 v[104:107], v[162:165], v[182:185], v[104:107]
	v_mfma_f32_16x16x32_bf16 v[92:95], v[146:149], v[190:193], v[92:95]
	v_mfma_f32_16x16x32_bf16 v[88:91], v[162:165], v[190:193], v[88:91]
	v_mfma_f32_16x16x32_bf16 v[76:79], v[146:149], v[198:201], v[76:79]
	v_mfma_f32_16x16x32_bf16 v[72:75], v[162:165], v[198:201], v[72:75]
	s_setprio 0
	s_barrier
	s_add_i32 s16, 0, 0x1c000
	s_add_i32 s17, s42, s66
	v_add_u32_e32 v214, s16, v153
	v_lshl_add_u64 v[150:151], v[150:151], 0, s[40:41]
	s_mov_b32 m0, s17
	ds_read_b128 v[202:205], v214
	ds_read_b128 v[206:209], v214 offset:1024
	ds_read_b128 v[210:213], v214 offset:2048
	ds_read_b128 v[214:217], v214 offset:3072
	global_load_lds_dwordx4 v[150:151], off
	v_lshl_add_u64 v[150:151], v[218:219], 0, s[40:41]
	s_add_i32 m0, s17, 0x2000
	s_nop 0
	global_load_lds_dwordx4 v[150:151], off
	s_barrier
	s_waitcnt lgkmcnt(0)
	s_setprio 1
	s_waitcnt lgkmcnt(0)
	v_mfma_f32_16x16x32_bf16 v[116:119], v[202:205], v[170:173], v[116:119]
	v_mfma_f32_16x16x32_bf16 v[112:115], v[210:213], v[170:173], v[112:115]
	v_mfma_f32_16x16x32_bf16 v[100:103], v[202:205], v[178:181], v[100:103]
	v_mfma_f32_16x16x32_bf16 v[96:99], v[210:213], v[178:181], v[96:99]
	v_mfma_f32_16x16x32_bf16 v[84:87], v[202:205], v[186:189], v[84:87]
	v_mfma_f32_16x16x32_bf16 v[80:83], v[210:213], v[186:189], v[80:83]
	v_mfma_f32_16x16x32_bf16 v[68:71], v[202:205], v[194:197], v[68:71]
	v_mfma_f32_16x16x32_bf16 v[64:67], v[210:213], v[194:197], v[64:67]
	v_mfma_f32_16x16x32_bf16 v[116:119], v[206:209], v[174:177], v[116:119]
	v_mfma_f32_16x16x32_bf16 v[112:115], v[214:217], v[174:177], v[112:115]
	v_mfma_f32_16x16x32_bf16 v[100:103], v[206:209], v[182:185], v[100:103]
	v_mfma_f32_16x16x32_bf16 v[96:99], v[214:217], v[182:185], v[96:99]
	v_mfma_f32_16x16x32_bf16 v[84:87], v[206:209], v[190:193], v[84:87]
	v_mfma_f32_16x16x32_bf16 v[80:83], v[214:217], v[190:193], v[80:83]
	v_mfma_f32_16x16x32_bf16 v[68:71], v[206:209], v[198:201], v[68:71]
	v_mfma_f32_16x16x32_bf16 v[64:67], v[214:217], v[198:201], v[64:67]
	s_setprio 0
	s_mov_b32 m0, s72
	v_lshl_add_u64 v[150:151], v[220:221], 0, s[40:41]
	s_barrier
	ds_read_b128 v[170:173], v156 offset:49152
	ds_read_b128 v[174:177], v156 offset:50176
	ds_read_b128 v[178:181], v156 offset:51200
	ds_read_b128 v[182:185], v156 offset:52224
	ds_read_b128 v[186:189], v156 offset:53248
	ds_read_b128 v[190:193], v156 offset:54272
	ds_read_b128 v[194:197], v156 offset:55296
	ds_read_b128 v[198:201], v156 offset:56320
	global_load_lds_dwordx4 v[150:151], off
	v_lshl_add_u64 v[150:151], v[222:223], 0, s[40:41]
	s_mov_b32 m0, s73
	s_nop 0
	global_load_lds_dwordx4 v[150:151], off
	s_barrier
; __device__ __forceinline__ float sigmoidf_(float x) { return 1.0f / (1.0f + __expf(-x)); }
; #define PG8_STAGE(bufoff, gbase, voff) do { _Pragma("unroll") for (int _i = 0; _i < 2; ++_i) \
;         __builtin_amdgcn_global_load_lds((const unsigned*)((const char*)(gbase) + (voff)[_i]), (LAS unsigned*)(lds + (bufoff) + ldsw + _i * 8192), 16, 0, 0); } while (0)
; #define PG8_LDA(dst, b, h) do { _Pragma("unroll") for (int m = 0; m < 4; ++m) _Pragma("unroll") for (int k = 0; k < 2; ++k) dst[m][k] = *(const LAS bf16x8*)(lds + PG8_SA(b, h) + aoff + m * 2048 + k * 1024); } while (0)
; #define PG8_LDB(dst, b, h) do { _Pragma("unroll") for (int n = 0; n < 2; ++n) _Pragma("unroll") for (int k = 0; k < 2; ++k) dst[n][k] = *(const LAS bf16x8*)(lds + PG8_SB(b, h) + boff + n * 2048 + k * 1024); } while (0)
; #define PG8_WAIT_V(n) asm volatile("s_waitcnt vmcnt(" #n ")" ::: "memory")
;     ...
;             PG8_WAIT_L(8); PG8_BAR; PG8_WAIT_L(0); PG8_MMA(0, 0, At, B0); PG8_BAR; PG8_SCHED;
;             PG8_LDB(B1, 1, 1); PG8_STAGE(PG8_SB(1, 0), b3, voffB);
;             PG8_BAR; PG8_WAIT_L(0); PG8_MMA(0, 1, At, B1); PG8_BAR;
;             PG8_LDA(At, 1, 1); PG8_STAGE(PG8_SA(1, 0), a3, voffA);
;             PG8_BAR; PG8_WAIT_L(0); PG8_MMA(1, 0, At, B0); PG8_BAR; PG8_SCHED;
;             PG8_STAGE(PG8_SB(1, 1), b3 + hB, voffB);
;             PG8_WAIT_V(6); PG8_BAR; PG8_MMA(1, 1, At, B1); PG8_BAR;
;         }
;     __device__ __forceinline__ void operator()(const f32x4 (&acc)[2][2][4][2], const Unit& u, int wr, int wc, int fr, int fq) const {
;     ...
;                 const int row = row0 + ai * 128 + m * 16;
;                 const bf16_t* rowp = z + (size_t)row * DIN + col0;
; #pragma unroll
;                 for (int bj = 0; bj < 2; ++bj) {
;                     const u32x4 gw = *(const u32x4*)(rowp + O_GA + bj * 128);
;                     f32x4 g0, g1; unpack8(gw, g0, g1);
;                     f32x4 v0, v1;
; #pragma unroll
;                     for (int j = 0; j < 4; ++j) { v0[j] = sigmoidf_(g0[j]) * acc[ai][bj][m][0][j]; v1[j] = sigmoidf_(g1[j]) * acc[ai][bj][m][1][j]; }
;                     const u32x4 mw = *(const u32x4*)(rowp + bj * 128); f32x4 m0, m1; unpack8(mw, m0, m1); v0 += m0; v1 += m1;
;                     __builtin_amdgcn_raw_buffer_store_b128(pack8(v0, v1), rsrc, (unsigned)(((size_t)row * DIN + col0 + bj * 128) * 2), 0, 16  ); }
	s_waitcnt lgkmcnt(0)
	s_setprio 1
	s_waitcnt lgkmcnt(0)
	v_mfma_f32_16x16x32_bf16 v[60:63], v[140:143], v[170:173], v[60:63]
	v_mfma_f32_16x16x32_bf16 v[56:59], v[158:161], v[170:173], v[56:59]
	v_mfma_f32_16x16x32_bf16 v[44:47], v[140:143], v[178:181], v[44:47]
	v_mfma_f32_16x16x32_bf16 v[40:43], v[158:161], v[178:181], v[40:43]
	v_mfma_f32_16x16x32_bf16 v[28:31], v[140:143], v[186:189], v[28:31]
	v_mfma_f32_16x16x32_bf16 v[24:27], v[158:161], v[186:189], v[24:27]
	v_mfma_f32_16x16x32_bf16 v[12:15], v[140:143], v[194:197], v[12:15]
	v_mfma_f32_16x16x32_bf16 v[8:11], v[158:161], v[194:197], v[8:11]
	v_mfma_f32_16x16x32_bf16 v[60:63], v[146:149], v[174:177], v[60:63]
	v_mfma_f32_16x16x32_bf16 v[56:59], v[162:165], v[174:177], v[56:59]
	v_mfma_f32_16x16x32_bf16 v[44:47], v[146:149], v[182:185], v[44:47]
	v_mfma_f32_16x16x32_bf16 v[40:43], v[162:165], v[182:185], v[40:43]
	v_mfma_f32_16x16x32_bf16 v[28:31], v[146:149], v[190:193], v[28:31]
	v_mfma_f32_16x16x32_bf16 v[24:27], v[162:165], v[190:193], v[24:27]
	v_mfma_f32_16x16x32_bf16 v[12:15], v[146:149], v[198:201], v[12:15]
	v_mfma_f32_16x16x32_bf16 v[8:11], v[162:165], v[198:201], v[8:11]
	s_setprio 0
	s_barrier
	s_add_u32 s14, s14, 0x20080
	s_addc_u32 s15, s15, 0
	s_add_i32 s16, s16, s66
	v_lshl_add_u64 v[140:141], s[14:15], 0, v[130:131]
	s_mov_b32 m0, s16
	s_nop 0
	global_load_lds_dwordx4 v[140:141], off
	v_lshl_add_u64 v[140:141], s[14:15], 0, v[134:135]
	s_add_i32 m0, s16, 0x2000
	s_nop 0
	global_load_lds_dwordx4 v[140:141], off
	s_waitcnt vmcnt(6)
	s_barrier
	s_setprio 1
	v_mfma_f32_16x16x32_bf16 v[52:55], v[202:205], v[170:173], v[52:55]
	v_mfma_f32_16x16x32_bf16 v[48:51], v[210:213], v[170:173], v[48:51]
	v_mfma_f32_16x16x32_bf16 v[36:39], v[202:205], v[178:181], v[36:39]
	v_mfma_f32_16x16x32_bf16 v[32:35], v[210:213], v[178:181], v[32:35]
	v_mfma_f32_16x16x32_bf16 v[20:23], v[202:205], v[186:189], v[20:23]
	v_mfma_f32_16x16x32_bf16 v[16:19], v[210:213], v[186:189], v[16:19]
	v_mfma_f32_16x16x32_bf16 v[4:7], v[202:205], v[194:197], v[4:7]
	v_mfma_f32_16x16x32_bf16 v[0:3], v[210:213], v[194:197], v[0:3]
	v_mfma_f32_16x16x32_bf16 v[52:55], v[206:209], v[174:177], v[52:55]
	v_mfma_f32_16x16x32_bf16 v[48:51], v[214:217], v[174:177], v[48:51]
	v_mfma_f32_16x16x32_bf16 v[36:39], v[206:209], v[182:185], v[36:39]
	v_mfma_f32_16x16x32_bf16 v[32:35], v[214:217], v[182:185], v[32:35]
	v_mfma_f32_16x16x32_bf16 v[20:23], v[206:209], v[190:193], v[20:23]
	v_mfma_f32_16x16x32_bf16 v[16:19], v[214:217], v[190:193], v[16:19]
	v_mfma_f32_16x16x32_bf16 v[4:7], v[206:209], v[198:201], v[4:7]
	v_mfma_f32_16x16x32_bf16 v[0:3], v[214:217], v[198:201], v[0:3]
	s_setprio 0
	s_add_i32 s39, s39, 2
	s_add_u32 s19, s19, 0x100
	s_addc_u32 s33, s33, 0
	s_add_u32 s12, s12, 0x100
	s_addc_u32 s13, s13, 0
	s_cmp_gt_u32 s39, 5
	s_barrier
	s_cbranch_scc0 .LBB0_723
	v_lshl_add_u32 v158, s79, 8, v152
	v_lshl_or_b32 v140, s6, 8, v154
	v_add_u32_e32 v142, 0x4000, v158
	v_ashrrev_i32_e32 v141, 31, v140
	v_mad_i64_i32 v[150:151], s[6:7], v142, s77, 0
	v_lshl_add_u64 v[146:147], v[150:151], 1, s[26:27]
	v_lshlrev_b64 v[142:143], 1, v[140:141]
	v_lshl_add_u64 v[146:147], v[146:147], 0, v[142:143]
	v_add_co_u32_e32 v148, vcc, 0x1000, v146
	s_nop 1
	v_addc_co_u32_e32 v149, vcc, 0, v147, vcc
	v_subrev_u32_e32 v198, s26, v146
	v_add_u32_e32 v199, 0x1200, v198
	global_load_dwordx4 v[200:203], v199, s[26:27]
	v_add_u32_e32 v199, 0x0, v198
	global_load_dwordx4 v[204:207], v199, s[26:27]
	v_add_u32_e32 v199, 0x1300, v198
	global_load_dwordx4 v[208:211], v199, s[26:27]
	v_add_u32_e32 v199, 0x100, v198
	global_load_dwordx4 v[212:215], v199, s[26:27]
	v_add_u32_e32 v199, 0x23200, v198
	global_load_dwordx4 v[232:235], v199, s[26:27]
	v_add_u32_e32 v199, 0x22000, v198
	global_load_dwordx4 v[236:239], v199, s[26:27]
	s_waitcnt vmcnt(4)
	v_mov_b32_e32 v160, v200
	v_mov_b32_e32 v161, v201
	v_mov_b32_e32 v162, v202
	v_mov_b32_e32 v163, v203
	v_mov_b32_e32 v170, v204
	v_mov_b32_e32 v171, v205
	v_mov_b32_e32 v172, v206
	v_mov_b32_e32 v173, v207
	v_add_u32_e32 v199, 0x23300, v198
	global_load_dwordx4 v[200:203], v199, s[26:27]
	v_add_u32_e32 v199, 0x22100, v198
	global_load_dwordx4 v[204:207], v199, s[26:27]
	s_mov_b32 s100, 0xbfb8aa3b
	v_lshlrev_b32_e32 v242, 16, v160
	v_and_b32_e32 v243, 0xffff0000, v160
	v_lshlrev_b32_e32 v244, 16, v162
	v_and_b32_e32 v245, 0xffff0000, v162
	v_lshlrev_b32_e32 v246, 16, v161
	v_and_b32_e32 v247, 0xffff0000, v161
	v_lshlrev_b32_e32 v248, 16, v163
	v_and_b32_e32 v249, 0xffff0000, v163
	v_pk_mul_f32 v[242:243], v[242:243], s[100:101] op_sel_hi:[1,0]
	v_pk_mul_f32 v[244:245], v[244:245], s[100:101] op_sel_hi:[1,0]
	v_pk_mul_f32 v[246:247], v[246:247], s[100:101] op_sel_hi:[1,0]
	v_pk_mul_f32 v[248:249], v[248:249], s[100:101] op_sel_hi:[1,0]
	v_exp_f32_e32 v242, v242
	v_exp_f32_e32 v243, v243
	v_exp_f32_e32 v244, v244
	v_exp_f32_e32 v245, v245
	v_exp_f32_e32 v246, v246
	v_exp_f32_e32 v247, v247
	v_exp_f32_e32 v248, v248
	v_exp_f32_e32 v249, v249
	s_nop 0
	v_pk_add_f32 v[242:243], v[242:243], 1.0 op_sel_hi:[1,0]
	v_pk_add_f32 v[244:245], v[244:245], 1.0 op_sel_hi:[1,0]
	v_pk_add_f32 v[246:247], v[246:247], 1.0 op_sel_hi:[1,0]
	v_pk_add_f32 v[248:249], v[248:249], 1.0 op_sel_hi:[1,0]
	v_rcp_f32_e32 v250, v242
	v_rcp_f32_e32 v251, v243
	s_nop 0
	v_pk_fma_f32 v[252:253], v[242:243], v[250:251], 1.0 op_sel_hi:[1,1,0] neg_lo:[1,0,0] neg_hi:[1,0,0]
	v_pk_fma_f32 v[250:251], v[252:253], v[250:251], v[250:251]
	v_pk_fma_f32 v[252:253], v[242:243], v[250:251], 1.0 op_sel_hi:[1,1,0] neg_lo:[1,0,0] neg_hi:[1,0,0]
	v_pk_fma_f32 v[254:255], v[252:253], v[250:251], v[250:251]
; __device__ __forceinline__ u32x4 pack8(const f32x4 v0, const f32x4 v1) { u32x4 w; w.x = pk2(v0[0], v0[1]); w.y = pk2(v0[2], v0[3]); w.z = pk2(v1[0], v1[1]); w.w = pk2(v1[2], v1[3]); return w; }
; __device__ __forceinline__ void unpack8(const u32x4 w, f32x4& v0, f32x4& v1) { v0 = (f32x4){bflo(w.x), bfhi(w.x), bflo(w.y), bfhi(w.y)}; v1 = (f32x4){bflo(w.z), bfhi(w.z), bflo(w.w), bfhi(w.w)}; }
; __device__ __forceinline__ float sigmoidf_(float x) { return 1.0f / (1.0f + __expf(-x)); }
;     __device__ __forceinline__ void operator()(const f32x4 (&acc)[2][2][4][2], const Unit& u, int wr, int wc, int fr, int fq) const {
;     ...
;                 const int row = row0 + ai * 128 + m * 16;
;                 const bf16_t* rowp = z + (size_t)row * DIN + col0;
; #pragma unroll
;                 for (int bj = 0; bj < 2; ++bj) {
;                     const u32x4 gw = *(const u32x4*)(rowp + O_GA + bj * 128);
;                     f32x4 g0, g1; unpack8(gw, g0, g1);
;                     f32x4 v0, v1;
; #pragma unroll
;                     for (int j = 0; j < 4; ++j) { v0[j] = sigmoidf_(g0[j]) * acc[ai][bj][m][0][j]; v1[j] = sigmoidf_(g1[j]) * acc[ai][bj][m][1][j]; }
;                     const u32x4 mw = *(const u32x4*)(rowp + bj * 128); f32x4 m0, m1; unpack8(mw, m0, m1); v0 += m0; v1 += m1;
;                     __builtin_amdgcn_raw_buffer_store_b128(pack8(v0, v1), rsrc, (unsigned)(((size_t)row * DIN + col0 + bj * 128) * 2), 0, 16  ); }
	v_pk_fma_f32 v[252:253], v[242:243], v[254:255], 1.0 op_sel_hi:[1,1,0] neg_lo:[1,0,0] neg_hi:[1,0,0]
	v_pk_fma_f32 v[254:255], v[252:253], v[250:251], v[254:255]
	v_div_fixup_f32 v242, v254, v242, 1.0
	v_div_fixup_f32 v243, v255, v243, 1.0
	v_rcp_f32_e32 v250, v244
	v_rcp_f32_e32 v251, v245
	s_nop 0
	v_pk_fma_f32 v[252:253], v[244:245], v[250:251], 1.0 op_sel_hi:[1,1,0] neg_lo:[1,0,0] neg_hi:[1,0,0]
	v_pk_fma_f32 v[250:251], v[252:253], v[250:251], v[250:251]
	v_pk_fma_f32 v[252:253], v[244:245], v[250:251], 1.0 op_sel_hi:[1,1,0] neg_lo:[1,0,0] neg_hi:[1,0,0]
	v_pk_fma_f32 v[254:255], v[252:253], v[250:251], v[250:251]
	v_pk_fma_f32 v[252:253], v[244:245], v[254:255], 1.0 op_sel_hi:[1,1,0] neg_lo:[1,0,0] neg_hi:[1,0,0]
	v_pk_fma_f32 v[254:255], v[252:253], v[250:251], v[254:255]
	v_div_fixup_f32 v244, v254, v244, 1.0
	v_div_fixup_f32 v245, v255, v245, 1.0
	v_rcp_f32_e32 v250, v246
	v_rcp_f32_e32 v251, v247
	s_nop 0
	v_pk_fma_f32 v[252:253], v[246:247], v[250:251], 1.0 op_sel_hi:[1,1,0] neg_lo:[1,0,0] neg_hi:[1,0,0]
	v_pk_fma_f32 v[250:251], v[252:253], v[250:251], v[250:251]
	v_pk_fma_f32 v[252:253], v[246:247], v[250:251], 1.0 op_sel_hi:[1,1,0] neg_lo:[1,0,0] neg_hi:[1,0,0]
	v_pk_fma_f32 v[254:255], v[252:253], v[250:251], v[250:251]
	v_pk_fma_f32 v[252:253], v[246:247], v[254:255], 1.0 op_sel_hi:[1,1,0] neg_lo:[1,0,0] neg_hi:[1,0,0]
	v_pk_fma_f32 v[254:255], v[252:253], v[250:251], v[254:255]
	v_div_fixup_f32 v246, v254, v246, 1.0
	v_div_fixup_f32 v247, v255, v247, 1.0
	v_rcp_f32_e32 v250, v248
	v_rcp_f32_e32 v251, v249
	s_nop 0
	v_pk_fma_f32 v[252:253], v[248:249], v[250:251], 1.0 op_sel_hi:[1,1,0] neg_lo:[1,0,0] neg_hi:[1,0,0]
	v_pk_fma_f32 v[250:251], v[252:253], v[250:251], v[250:251]
	v_pk_fma_f32 v[252:253], v[248:249], v[250:251], 1.0 op_sel_hi:[1,1,0] neg_lo:[1,0,0] neg_hi:[1,0,0]
	v_pk_fma_f32 v[254:255], v[252:253], v[250:251], v[250:251]
	v_pk_fma_f32 v[252:253], v[248:249], v[254:255], 1.0 op_sel_hi:[1,1,0] neg_lo:[1,0,0] neg_hi:[1,0,0]
	v_pk_fma_f32 v[254:255], v[252:253], v[250:251], v[254:255]
	v_div_fixup_f32 v248, v254, v248, 1.0
	v_div_fixup_f32 v249, v255, v249, 1.0
	s_mov_b64 vcc, s[12:13]
	s_mov_b64 vcc, s[14:15]
	s_mov_b64 vcc, s[16:17]
	s_mov_b64 vcc, s[18:19]
	v_lshlrev_b32_e32 v178, 16, v172
	v_and_b32_e32 v179, 0xffff0000, v172
	v_lshlrev_b32_e32 v176, 16, v170
	v_and_b32_e32 v177, 0xffff0000, v170
	v_lshlrev_b32_e32 v172, 16, v173
	v_and_b32_e32 v173, 0xffff0000, v173
	v_lshlrev_b32_e32 v170, 16, v171
	v_and_b32_e32 v171, 0xffff0000, v171
	v_pk_fma_f32 v[124:125], v[124:125], v[242:243], v[176:177]
	v_pk_fma_f32 v[160:161], v[122:123], v[248:249], v[172:173]
	v_pk_fma_f32 v[122:123], v[120:121], v[244:245], v[178:179]
	v_add_lshl_u32 v141, v140, v150, 1
	v_pk_fma_f32 v[126:127], v[126:127], v[246:247], v[170:171]
	v_cvt_pk_bf16_f32 v120, v124, v125
	s_nop 0
	v_cvt_pk_bf16_f32 v121, v126, v127
	v_cvt_pk_bf16_f32 v122, v122, v123
	v_cvt_pk_bf16_f32 v123, v160, v161
	buffer_store_dwordx4 v[120:123], v141, s[20:23], 0 offen sc1
	s_nop 0
	s_waitcnt vmcnt(5)
	v_mov_b32_e32 v120, v208
	v_mov_b32_e32 v121, v209
	v_mov_b32_e32 v122, v210
	v_mov_b32_e32 v123, v211
	v_mov_b32_e32 v124, v212
	v_mov_b32_e32 v125, v213
	v_mov_b32_e32 v126, v214
	v_mov_b32_e32 v127, v215
	v_add_u32_e32 v199, 0x45200, v198
	global_load_dwordx4 v[208:211], v199, s[26:27]
	v_add_u32_e32 v199, 0x44000, v198
	global_load_dwordx4 v[212:215], v199, s[26:27]
	s_mov_b32 s100, 0xbfb8aa3b
	v_lshlrev_b32_e32 v242, 16, v120
	v_and_b32_e32 v243, 0xffff0000, v120
	v_lshlrev_b32_e32 v244, 16, v122
	v_and_b32_e32 v245, 0xffff0000, v122
	v_lshlrev_b32_e32 v246, 16, v121
	v_and_b32_e32 v247, 0xffff0000, v121
	v_lshlrev_b32_e32 v248, 16, v123
	v_and_b32_e32 v249, 0xffff0000, v123
	v_pk_mul_f32 v[242:243], v[242:243], s[100:101] op_sel_hi:[1,0]
	v_pk_mul_f32 v[244:245], v[244:245], s[100:101] op_sel_hi:[1,0]
	v_pk_mul_f32 v[246:247], v[246:247], s[100:101] op_sel_hi:[1,0]
	v_pk_mul_f32 v[248:249], v[248:249], s[100:101] op_sel_hi:[1,0]
	v_exp_f32_e32 v242, v242
	v_exp_f32_e32 v243, v243
	v_exp_f32_e32 v244, v244
	v_exp_f32_e32 v245, v245
	v_exp_f32_e32 v246, v246
	v_exp_f32_e32 v247, v247
	v_exp_f32_e32 v248, v248
	v_exp_f32_e32 v249, v249
	s_nop 0
	v_pk_add_f32 v[242:243], v[242:243], 1.0 op_sel_hi:[1,0]
	v_pk_add_f32 v[244:245], v[244:245], 1.0 op_sel_hi:[1,0]
	v_pk_add_f32 v[246:247], v[246:247], 1.0 op_sel_hi:[1,0]
	v_pk_add_f32 v[248:249], v[248:249], 1.0 op_sel_hi:[1,0]
	v_rcp_f32_e32 v250, v242
	v_rcp_f32_e32 v251, v243
	s_nop 0
	v_pk_fma_f32 v[252:253], v[242:243], v[250:251], 1.0 op_sel_hi:[1,1,0] neg_lo:[1,0,0] neg_hi:[1,0,0]
	v_pk_fma_f32 v[250:251], v[252:253], v[250:251], v[250:251]
	v_pk_fma_f32 v[252:253], v[242:243], v[250:251], 1.0 op_sel_hi:[1,1,0] neg_lo:[1,0,0] neg_hi:[1,0,0]
	v_pk_fma_f32 v[254:255], v[252:253], v[250:251], v[250:251]
	v_pk_fma_f32 v[252:253], v[242:243], v[254:255], 1.0 op_sel_hi:[1,1,0] neg_lo:[1,0,0] neg_hi:[1,0,0]
	v_pk_fma_f32 v[254:255], v[252:253], v[250:251], v[254:255]
	v_div_fixup_f32 v242, v254, v242, 1.0
	v_div_fixup_f32 v243, v255, v243, 1.0
	v_rcp_f32_e32 v250, v244
	v_rcp_f32_e32 v251, v245
	s_nop 0
	v_pk_fma_f32 v[252:253], v[244:245], v[250:251], 1.0 op_sel_hi:[1,1,0] neg_lo:[1,0,0] neg_hi:[1,0,0]
	v_pk_fma_f32 v[250:251], v[252:253], v[250:251], v[250:251]
	v_pk_fma_f32 v[252:253], v[244:245], v[250:251], 1.0 op_sel_hi:[1,1,0] neg_lo:[1,0,0] neg_hi:[1,0,0]
	v_pk_fma_f32 v[254:255], v[252:253], v[250:251], v[250:251]
	v_pk_fma_f32 v[252:253], v[244:245], v[254:255], 1.0 op_sel_hi:[1,1,0] neg_lo:[1,0,0] neg_hi:[1,0,0]
	v_pk_fma_f32 v[254:255], v[252:253], v[250:251], v[254:255]
	v_div_fixup_f32 v244, v254, v244, 1.0
; __device__ __forceinline__ u32x4 pack8(const f32x4 v0, const f32x4 v1) { u32x4 w; w.x = pk2(v0[0], v0[1]); w.y = pk2(v0[2], v0[3]); w.z = pk2(v1[0], v1[1]); w.w = pk2(v1[2], v1[3]); return w; }
; __device__ __forceinline__ void unpack8(const u32x4 w, f32x4& v0, f32x4& v1) { v0 = (f32x4){bflo(w.x), bfhi(w.x), bflo(w.y), bfhi(w.y)}; v1 = (f32x4){bflo(w.z), bfhi(w.z), bflo(w.w), bfhi(w.w)}; }
; __device__ __forceinline__ float sigmoidf_(float x) { return 1.0f / (1.0f + __expf(-x)); }
;     __device__ __forceinline__ void operator()(const f32x4 (&acc)[2][2][4][2], const Unit& u, int wr, int wc, int fr, int fq) const {
;     ...
;                 const int row = row0 + ai * 128 + m * 16;
;                 const bf16_t* rowp = z + (size_t)row * DIN + col0;
; #pragma unroll
;                 for (int bj = 0; bj < 2; ++bj) {
;                     const u32x4 gw = *(const u32x4*)(rowp + O_GA + bj * 128);
;                     f32x4 g0, g1; unpack8(gw, g0, g1);
;                     f32x4 v0, v1;
; #pragma unroll
;                     for (int j = 0; j < 4; ++j) { v0[j] = sigmoidf_(g0[j]) * acc[ai][bj][m][0][j]; v1[j] = sigmoidf_(g1[j]) * acc[ai][bj][m][1][j]; }
;                     const u32x4 mw = *(const u32x4*)(rowp + bj * 128); f32x4 m0, m1; unpack8(mw, m0, m1); v0 += m0; v1 += m1;
;                     __builtin_amdgcn_raw_buffer_store_b128(pack8(v0, v1), rsrc, (unsigned)(((size_t)row * DIN + col0 + bj * 128) * 2), 0, 16  ); }
	v_div_fixup_f32 v245, v255, v245, 1.0
	v_rcp_f32_e32 v250, v246
	v_rcp_f32_e32 v251, v247
	s_nop 0
	v_pk_fma_f32 v[252:253], v[246:247], v[250:251], 1.0 op_sel_hi:[1,1,0] neg_lo:[1,0,0] neg_hi:[1,0,0]
	v_pk_fma_f32 v[250:251], v[252:253], v[250:251], v[250:251]
	v_pk_fma_f32 v[252:253], v[246:247], v[250:251], 1.0 op_sel_hi:[1,1,0] neg_lo:[1,0,0] neg_hi:[1,0,0]
	v_pk_fma_f32 v[254:255], v[252:253], v[250:251], v[250:251]
	v_pk_fma_f32 v[252:253], v[246:247], v[254:255], 1.0 op_sel_hi:[1,1,0] neg_lo:[1,0,0] neg_hi:[1,0,0]
	v_pk_fma_f32 v[254:255], v[252:253], v[250:251], v[254:255]
	v_div_fixup_f32 v246, v254, v246, 1.0
	v_div_fixup_f32 v247, v255, v247, 1.0
	v_rcp_f32_e32 v250, v248
	v_rcp_f32_e32 v251, v249
	s_nop 0
	v_pk_fma_f32 v[252:253], v[248:249], v[250:251], 1.0 op_sel_hi:[1,1,0] neg_lo:[1,0,0] neg_hi:[1,0,0]
	v_pk_fma_f32 v[250:251], v[252:253], v[250:251], v[250:251]
	v_pk_fma_f32 v[252:253], v[248:249], v[250:251], 1.0 op_sel_hi:[1,1,0] neg_lo:[1,0,0] neg_hi:[1,0,0]
	v_pk_fma_f32 v[254:255], v[252:253], v[250:251], v[250:251]
	v_pk_fma_f32 v[252:253], v[248:249], v[254:255], 1.0 op_sel_hi:[1,1,0] neg_lo:[1,0,0] neg_hi:[1,0,0]
	v_pk_fma_f32 v[254:255], v[252:253], v[250:251], v[254:255]
	v_div_fixup_f32 v248, v254, v248, 1.0
	v_div_fixup_f32 v249, v255, v249, 1.0
	v_lshlrev_b32_e32 v150, 16, v124
	v_and_b32_e32 v151, 0xffff0000, v124
	v_lshlrev_b32_e32 v160, 16, v126
	v_and_b32_e32 v161, 0xffff0000, v126
	v_lshlrev_b32_e32 v126, 16, v127
	v_and_b32_e32 v127, 0xffff0000, v127
	v_lshlrev_b32_e32 v124, 16, v125
	v_and_b32_e32 v125, 0xffff0000, v125
	v_pk_fma_f32 v[116:117], v[116:117], v[242:243], v[150:151]
	v_pk_fma_f32 v[120:121], v[114:115], v[248:249], v[126:127]
	v_pk_fma_f32 v[114:115], v[112:113], v[244:245], v[160:161]
	v_cvt_pk_bf16_f32 v112, v116, v117
	v_pk_fma_f32 v[118:119], v[118:119], v[246:247], v[124:125]
	s_nop 0
	v_cvt_pk_bf16_f32 v113, v118, v119
	v_cvt_pk_bf16_f32 v114, v114, v115
	v_cvt_pk_bf16_f32 v115, v120, v121
	buffer_store_dwordx4 v[112:115], v141, s[20:23], 0 offen offset:256 sc1
	s_nop 1
	v_add_u32_e32 v112, 0x4010, v158
	v_mad_i64_i32 v[114:115], s[6:7], v112, s77, 0
	v_lshl_add_u64 v[112:113], v[114:115], 1, s[26:27]
	v_lshl_add_u64 v[112:113], v[112:113], 0, v[142:143]
	v_add_co_u32_e32 v116, vcc, s78, v112
	s_nop 1
	v_addc_co_u32_e32 v117, vcc, 0, v113, vcc
	s_waitcnt vmcnt(6)
	v_mov_b32_e32 v118, v232
	v_mov_b32_e32 v119, v233
	v_mov_b32_e32 v120, v234
	v_mov_b32_e32 v121, v235
	v_mov_b32_e32 v122, v236
	v_mov_b32_e32 v123, v237
	v_mov_b32_e32 v124, v238
	v_mov_b32_e32 v125, v239
	v_add_u32_e32 v199, 0x45300, v198
	global_load_dwordx4 v[232:235], v199, s[26:27]
	v_add_u32_e32 v199, 0x44100, v198
	global_load_dwordx4 v[236:239], v199, s[26:27]
	s_mov_b32 s100, 0xbfb8aa3b
	v_lshlrev_b32_e32 v242, 16, v118
	v_and_b32_e32 v243, 0xffff0000, v118
	v_lshlrev_b32_e32 v244, 16, v120
	v_and_b32_e32 v245, 0xffff0000, v120
	v_lshlrev_b32_e32 v246, 16, v119
	v_and_b32_e32 v247, 0xffff0000, v119
	v_lshlrev_b32_e32 v248, 16, v121
	v_and_b32_e32 v249, 0xffff0000, v121
	v_pk_mul_f32 v[242:243], v[242:243], s[100:101] op_sel_hi:[1,0]
	v_pk_mul_f32 v[244:245], v[244:245], s[100:101] op_sel_hi:[1,0]
	v_pk_mul_f32 v[246:247], v[246:247], s[100:101] op_sel_hi:[1,0]
	v_pk_mul_f32 v[248:249], v[248:249], s[100:101] op_sel_hi:[1,0]
	v_exp_f32_e32 v242, v242
	v_exp_f32_e32 v243, v243
	v_exp_f32_e32 v244, v244
	v_exp_f32_e32 v245, v245
	v_exp_f32_e32 v246, v246
	v_exp_f32_e32 v247, v247
	v_exp_f32_e32 v248, v248
	v_exp_f32_e32 v249, v249
	s_nop 0
	v_pk_add_f32 v[242:243], v[242:243], 1.0 op_sel_hi:[1,0]
	v_pk_add_f32 v[244:245], v[244:245], 1.0 op_sel_hi:[1,0]
	v_pk_add_f32 v[246:247], v[246:247], 1.0 op_sel_hi:[1,0]
	v_pk_add_f32 v[248:249], v[248:249], 1.0 op_sel_hi:[1,0]
	v_rcp_f32_e32 v250, v242
	v_rcp_f32_e32 v251, v243
	s_nop 0
	v_pk_fma_f32 v[252:253], v[242:243], v[250:251], 1.0 op_sel_hi:[1,1,0] neg_lo:[1,0,0] neg_hi:[1,0,0]
	v_pk_fma_f32 v[250:251], v[252:253], v[250:251], v[250:251]
	v_pk_fma_f32 v[252:253], v[242:243], v[250:251], 1.0 op_sel_hi:[1,1,0] neg_lo:[1,0,0] neg_hi:[1,0,0]
	v_pk_fma_f32 v[254:255], v[252:253], v[250:251], v[250:251]
	v_pk_fma_f32 v[252:253], v[242:243], v[254:255], 1.0 op_sel_hi:[1,1,0] neg_lo:[1,0,0] neg_hi:[1,0,0]
	v_pk_fma_f32 v[254:255], v[252:253], v[250:251], v[254:255]
	v_div_fixup_f32 v242, v254, v242, 1.0
	v_div_fixup_f32 v243, v255, v243, 1.0
	v_rcp_f32_e32 v250, v244
	v_rcp_f32_e32 v251, v245
	s_nop 0
	v_pk_fma_f32 v[252:253], v[244:245], v[250:251], 1.0 op_sel_hi:[1,1,0] neg_lo:[1,0,0] neg_hi:[1,0,0]
	v_pk_fma_f32 v[250:251], v[252:253], v[250:251], v[250:251]
	v_pk_fma_f32 v[252:253], v[244:245], v[250:251], 1.0 op_sel_hi:[1,1,0] neg_lo:[1,0,0] neg_hi:[1,0,0]
	v_pk_fma_f32 v[254:255], v[252:253], v[250:251], v[250:251]
	v_pk_fma_f32 v[252:253], v[244:245], v[254:255], 1.0 op_sel_hi:[1,1,0] neg_lo:[1,0,0] neg_hi:[1,0,0]
	v_pk_fma_f32 v[254:255], v[252:253], v[250:251], v[254:255]
	v_div_fixup_f32 v244, v254, v244, 1.0
	v_div_fixup_f32 v245, v255, v245, 1.0
	v_rcp_f32_e32 v250, v246
	v_rcp_f32_e32 v251, v247
	s_nop 0
	v_pk_fma_f32 v[252:253], v[246:247], v[250:251], 1.0 op_sel_hi:[1,1,0] neg_lo:[1,0,0] neg_hi:[1,0,0]
	v_pk_fma_f32 v[250:251], v[252:253], v[250:251], v[250:251]
	v_pk_fma_f32 v[252:253], v[246:247], v[250:251], 1.0 op_sel_hi:[1,1,0] neg_lo:[1,0,0] neg_hi:[1,0,0]
	v_pk_fma_f32 v[254:255], v[252:253], v[250:251], v[250:251]
	v_pk_fma_f32 v[252:253], v[246:247], v[254:255], 1.0 op_sel_hi:[1,1,0] neg_lo:[1,0,0] neg_hi:[1,0,0]
	v_pk_fma_f32 v[254:255], v[252:253], v[250:251], v[254:255]
	v_div_fixup_f32 v246, v254, v246, 1.0
	v_div_fixup_f32 v247, v255, v247, 1.0
; __device__ __forceinline__ u32x4 pack8(const f32x4 v0, const f32x4 v1) { u32x4 w; w.x = pk2(v0[0], v0[1]); w.y = pk2(v0[2], v0[3]); w.z = pk2(v1[0], v1[1]); w.w = pk2(v1[2], v1[3]); return w; }
; __device__ __forceinline__ void unpack8(const u32x4 w, f32x4& v0, f32x4& v1) { v0 = (f32x4){bflo(w.x), bfhi(w.x), bflo(w.y), bfhi(w.y)}; v1 = (f32x4){bflo(w.z), bfhi(w.z), bflo(w.w), bfhi(w.w)}; }
; __device__ __forceinline__ float sigmoidf_(float x) { return 1.0f / (1.0f + __expf(-x)); }
;     __device__ __forceinline__ void operator()(const f32x4 (&acc)[2][2][4][2], const Unit& u, int wr, int wc, int fr, int fq) const {
;     ...
;                 for (int bj = 0; bj < 2; ++bj) {
;                     const u32x4 gw = *(const u32x4*)(rowp + O_GA + bj * 128);
;                     f32x4 g0, g1; unpack8(gw, g0, g1);
;                     f32x4 v0, v1;
; #pragma unroll
;                     for (int j = 0; j < 4; ++j) { v0[j] = sigmoidf_(g0[j]) * acc[ai][bj][m][0][j]; v1[j] = sigmoidf_(g1[j]) * acc[ai][bj][m][1][j]; }
;                     const u32x4 mw = *(const u32x4*)(rowp + bj * 128); f32x4 m0, m1; unpack8(mw, m0, m1); v0 += m0; v1 += m1;
;                     __builtin_amdgcn_raw_buffer_store_b128(pack8(v0, v1), rsrc, (unsigned)(((size_t)row * DIN + col0 + bj * 128) * 2), 0, 16  ); }
	v_rcp_f32_e32 v250, v248
	v_rcp_f32_e32 v251, v249
	s_nop 0
	v_pk_fma_f32 v[252:253], v[248:249], v[250:251], 1.0 op_sel_hi:[1,1,0] neg_lo:[1,0,0] neg_hi:[1,0,0]
	v_pk_fma_f32 v[250:251], v[252:253], v[250:251], v[250:251]
	v_pk_fma_f32 v[252:253], v[248:249], v[250:251], 1.0 op_sel_hi:[1,1,0] neg_lo:[1,0,0] neg_hi:[1,0,0]
	v_pk_fma_f32 v[254:255], v[252:253], v[250:251], v[250:251]
	v_pk_fma_f32 v[252:253], v[248:249], v[254:255], 1.0 op_sel_hi:[1,1,0] neg_lo:[1,0,0] neg_hi:[1,0,0]
	v_pk_fma_f32 v[254:255], v[252:253], v[250:251], v[254:255]
	v_div_fixup_f32 v248, v254, v248, 1.0
	v_div_fixup_f32 v249, v255, v249, 1.0
	v_and_b32_e32 v151, 0xffff0000, v124
	v_lshlrev_b32_e32 v148, 16, v122
	v_and_b32_e32 v149, 0xffff0000, v122
	v_lshlrev_b32_e32 v150, 16, v124
	v_lshlrev_b32_e32 v124, 16, v125
	v_and_b32_e32 v125, 0xffff0000, v125
	v_lshlrev_b32_e32 v122, 16, v123
	v_and_b32_e32 v123, 0xffff0000, v123
	v_pk_fma_f32 v[108:109], v[108:109], v[242:243], v[148:149]
	v_pk_fma_f32 v[118:119], v[106:107], v[248:249], v[124:125]
	v_pk_fma_f32 v[106:107], v[104:105], v[244:245], v[150:151]
	v_add_lshl_u32 v120, v140, v114, 1
	v_pk_fma_f32 v[110:111], v[110:111], v[246:247], v[122:123]
	v_cvt_pk_bf16_f32 v104, v108, v109
	s_nop 0
	v_cvt_pk_bf16_f32 v105, v110, v111
	v_cvt_pk_bf16_f32 v106, v106, v107
	v_cvt_pk_bf16_f32 v107, v118, v119
	buffer_store_dwordx4 v[104:107], v120, s[20:23], 0 offen sc1
	s_nop 0
	s_waitcnt vmcnt(7)
	v_mov_b32_e32 v104, v200
	v_mov_b32_e32 v105, v201
	v_mov_b32_e32 v106, v202
	v_mov_b32_e32 v107, v203
	v_mov_b32_e32 v108, v204
	v_mov_b32_e32 v109, v205
	v_mov_b32_e32 v110, v206
	v_mov_b32_e32 v111, v207
	v_add_u32_e32 v199, 0x67200, v198
	global_load_dwordx4 v[200:203], v199, s[26:27]
	v_add_u32_e32 v199, 0x66000, v198
	global_load_dwordx4 v[204:207], v199, s[26:27]
	s_mov_b32 s100, 0xbfb8aa3b
	v_lshlrev_b32_e32 v242, 16, v106
	v_and_b32_e32 v243, 0xffff0000, v106
	v_lshlrev_b32_e32 v244, 16, v104
	v_and_b32_e32 v245, 0xffff0000, v104
	v_lshlrev_b32_e32 v246, 16, v105
	v_and_b32_e32 v247, 0xffff0000, v105
	v_lshlrev_b32_e32 v248, 16, v107
	v_and_b32_e32 v249, 0xffff0000, v107
	v_pk_mul_f32 v[242:243], v[242:243], s[100:101] op_sel_hi:[1,0]
	v_pk_mul_f32 v[244:245], v[244:245], s[100:101] op_sel_hi:[1,0]
	v_pk_mul_f32 v[246:247], v[246:247], s[100:101] op_sel_hi:[1,0]
	v_pk_mul_f32 v[248:249], v[248:249], s[100:101] op_sel_hi:[1,0]
	v_exp_f32_e32 v242, v242
	v_exp_f32_e32 v243, v243
	v_exp_f32_e32 v244, v244
	v_exp_f32_e32 v245, v245
	v_exp_f32_e32 v246, v246
	v_exp_f32_e32 v247, v247
	v_exp_f32_e32 v248, v248
	v_exp_f32_e32 v249, v249
	s_nop 0
	v_pk_add_f32 v[242:243], v[242:243], 1.0 op_sel_hi:[1,0]
	v_pk_add_f32 v[244:245], v[244:245], 1.0 op_sel_hi:[1,0]
	v_pk_add_f32 v[246:247], v[246:247], 1.0 op_sel_hi:[1,0]
	v_pk_add_f32 v[248:249], v[248:249], 1.0 op_sel_hi:[1,0]
	v_rcp_f32_e32 v250, v242
	v_rcp_f32_e32 v251, v243
	s_nop 0
	v_pk_fma_f32 v[252:253], v[242:243], v[250:251], 1.0 op_sel_hi:[1,1,0] neg_lo:[1,0,0] neg_hi:[1,0,0]
	v_pk_fma_f32 v[250:251], v[252:253], v[250:251], v[250:251]
	v_pk_fma_f32 v[252:253], v[242:243], v[250:251], 1.0 op_sel_hi:[1,1,0] neg_lo:[1,0,0] neg_hi:[1,0,0]
	v_pk_fma_f32 v[254:255], v[252:253], v[250:251], v[250:251]
	v_pk_fma_f32 v[252:253], v[242:243], v[254:255], 1.0 op_sel_hi:[1,1,0] neg_lo:[1,0,0] neg_hi:[1,0,0]
	v_pk_fma_f32 v[254:255], v[252:253], v[250:251], v[254:255]
	v_div_fixup_f32 v242, v254, v242, 1.0
	v_div_fixup_f32 v243, v255, v243, 1.0
	v_rcp_f32_e32 v250, v244
	v_rcp_f32_e32 v251, v245
	s_nop 0
	v_pk_fma_f32 v[252:253], v[244:245], v[250:251], 1.0 op_sel_hi:[1,1,0] neg_lo:[1,0,0] neg_hi:[1,0,0]
	v_pk_fma_f32 v[250:251], v[252:253], v[250:251], v[250:251]
	v_pk_fma_f32 v[252:253], v[244:245], v[250:251], 1.0 op_sel_hi:[1,1,0] neg_lo:[1,0,0] neg_hi:[1,0,0]
	v_pk_fma_f32 v[254:255], v[252:253], v[250:251], v[250:251]
	v_pk_fma_f32 v[252:253], v[244:245], v[254:255], 1.0 op_sel_hi:[1,1,0] neg_lo:[1,0,0] neg_hi:[1,0,0]
	v_pk_fma_f32 v[254:255], v[252:253], v[250:251], v[254:255]
	v_div_fixup_f32 v244, v254, v244, 1.0
	v_div_fixup_f32 v245, v255, v245, 1.0
	v_rcp_f32_e32 v250, v246
	v_rcp_f32_e32 v251, v247
	s_nop 0
	v_pk_fma_f32 v[252:253], v[246:247], v[250:251], 1.0 op_sel_hi:[1,1,0] neg_lo:[1,0,0] neg_hi:[1,0,0]
	v_pk_fma_f32 v[250:251], v[252:253], v[250:251], v[250:251]
	v_pk_fma_f32 v[252:253], v[246:247], v[250:251], 1.0 op_sel_hi:[1,1,0] neg_lo:[1,0,0] neg_hi:[1,0,0]
	v_pk_fma_f32 v[254:255], v[252:253], v[250:251], v[250:251]
	v_pk_fma_f32 v[252:253], v[246:247], v[254:255], 1.0 op_sel_hi:[1,1,0] neg_lo:[1,0,0] neg_hi:[1,0,0]
	v_pk_fma_f32 v[254:255], v[252:253], v[250:251], v[254:255]
	v_div_fixup_f32 v246, v254, v246, 1.0
	v_div_fixup_f32 v247, v255, v247, 1.0
	v_rcp_f32_e32 v250, v248
	v_rcp_f32_e32 v251, v249
	s_nop 0
	v_pk_fma_f32 v[252:253], v[248:249], v[250:251], 1.0 op_sel_hi:[1,1,0] neg_lo:[1,0,0] neg_hi:[1,0,0]
	v_pk_fma_f32 v[250:251], v[252:253], v[250:251], v[250:251]
	v_pk_fma_f32 v[252:253], v[248:249], v[250:251], 1.0 op_sel_hi:[1,1,0] neg_lo:[1,0,0] neg_hi:[1,0,0]
	v_pk_fma_f32 v[254:255], v[252:253], v[250:251], v[250:251]
	v_pk_fma_f32 v[252:253], v[248:249], v[254:255], 1.0 op_sel_hi:[1,1,0] neg_lo:[1,0,0] neg_hi:[1,0,0]
	v_pk_fma_f32 v[254:255], v[252:253], v[250:251], v[254:255]
	v_div_fixup_f32 v248, v254, v248, 1.0
	v_div_fixup_f32 v249, v255, v249, 1.0
	v_lshlrev_b32_e32 v116, 16, v108
	v_and_b32_e32 v117, 0xffff0000, v108
	v_lshlrev_b32_e32 v118, 16, v110
	v_and_b32_e32 v119, 0xffff0000, v110
	v_lshlrev_b32_e32 v110, 16, v111
	v_and_b32_e32 v111, 0xffff0000, v111
	v_lshlrev_b32_e32 v108, 16, v109
	v_and_b32_e32 v109, 0xffff0000, v109
	v_pk_fma_f32 v[100:101], v[100:101], v[244:245], v[116:117]
	v_pk_fma_f32 v[104:105], v[98:99], v[248:249], v[110:111]
	v_pk_fma_f32 v[98:99], v[96:97], v[242:243], v[118:119]
	v_cvt_pk_bf16_f32 v96, v100, v101
	v_pk_fma_f32 v[102:103], v[102:103], v[246:247], v[108:109]
	s_nop 0
	v_cvt_pk_bf16_f32 v97, v102, v103
	v_cvt_pk_bf16_f32 v98, v98, v99
	v_cvt_pk_bf16_f32 v99, v104, v105
	buffer_store_dwordx4 v[96:99], v120, s[20:23], 0 offen offset:256 sc1
	s_nop 1
	v_add_u32_e32 v96, 0x4020, v158
	v_mad_i64_i32 v[98:99], s[6:7], v96, s77, 0
	v_lshl_add_u64 v[96:97], v[98:99], 1, s[26:27]
	v_lshl_add_u64 v[96:97], v[96:97], 0, v[142:143]
	v_add_co_u32_e32 v100, vcc, s78, v96
	s_nop 1
	v_addc_co_u32_e32 v101, vcc, 0, v97, vcc
	s_waitcnt vmcnt(7)
; __device__ __forceinline__ u32x4 pack8(const f32x4 v0, const f32x4 v1) { u32x4 w; w.x = pk2(v0[0], v0[1]); w.y = pk2(v0[2], v0[3]); w.z = pk2(v1[0], v1[1]); w.w = pk2(v1[2], v1[3]); return w; }
; __device__ __forceinline__ void unpack8(const u32x4 w, f32x4& v0, f32x4& v1) { v0 = (f32x4){bflo(w.x), bfhi(w.x), bflo(w.y), bfhi(w.y)}; v1 = (f32x4){bflo(w.z), bfhi(w.z), bflo(w.w), bfhi(w.w)}; }
; __device__ __forceinline__ float sigmoidf_(float x) { return 1.0f / (1.0f + __expf(-x)); }
;     __device__ __forceinline__ void operator()(const f32x4 (&acc)[2][2][4][2], const Unit& u, int wr, int wc, int fr, int fq) const {
;     ...
;                 for (int bj = 0; bj < 2; ++bj) {
;                     const u32x4 gw = *(const u32x4*)(rowp + O_GA + bj * 128);
;                     f32x4 g0, g1; unpack8(gw, g0, g1);
;                     f32x4 v0, v1;
; #pragma unroll
;                     for (int j = 0; j < 4; ++j) { v0[j] = sigmoidf_(g0[j]) * acc[ai][bj][m][0][j]; v1[j] = sigmoidf_(g1[j]) * acc[ai][bj][m][1][j]; }
;                     const u32x4 mw = *(const u32x4*)(rowp + bj * 128); f32x4 m0, m1; unpack8(mw, m0, m1); v0 += m0; v1 += m1;
;                     __builtin_amdgcn_raw_buffer_store_b128(pack8(v0, v1), rsrc, (unsigned)(((size_t)row * DIN + col0 + bj * 128) * 2), 0, 16  ); }
	v_mov_b32_e32 v102, v208
	v_mov_b32_e32 v103, v209
	v_mov_b32_e32 v104, v210
	v_mov_b32_e32 v105, v211
	v_mov_b32_e32 v106, v212
	v_mov_b32_e32 v107, v213
	v_mov_b32_e32 v108, v214
	v_mov_b32_e32 v109, v215
	v_add_u32_e32 v199, 0x67300, v198
	global_load_dwordx4 v[208:211], v199, s[26:27]
	v_add_u32_e32 v199, 0x66100, v198
	global_load_dwordx4 v[212:215], v199, s[26:27]
	s_mov_b32 s100, 0xbfb8aa3b
	v_lshlrev_b32_e32 v242, 16, v102
	v_and_b32_e32 v243, 0xffff0000, v102
	v_lshlrev_b32_e32 v244, 16, v104
	v_and_b32_e32 v245, 0xffff0000, v104
	v_lshlrev_b32_e32 v246, 16, v103
	v_and_b32_e32 v247, 0xffff0000, v103
	v_lshlrev_b32_e32 v248, 16, v105
	v_and_b32_e32 v249, 0xffff0000, v105
	v_pk_mul_f32 v[242:243], v[242:243], s[100:101] op_sel_hi:[1,0]
	v_pk_mul_f32 v[244:245], v[244:245], s[100:101] op_sel_hi:[1,0]
	v_pk_mul_f32 v[246:247], v[246:247], s[100:101] op_sel_hi:[1,0]
	v_pk_mul_f32 v[248:249], v[248:249], s[100:101] op_sel_hi:[1,0]
	v_exp_f32_e32 v242, v242
	v_exp_f32_e32 v243, v243
	v_exp_f32_e32 v244, v244
	v_exp_f32_e32 v245, v245
	v_exp_f32_e32 v246, v246
	v_exp_f32_e32 v247, v247
	v_exp_f32_e32 v248, v248
	v_exp_f32_e32 v249, v249
	s_nop 0
	v_pk_add_f32 v[242:243], v[242:243], 1.0 op_sel_hi:[1,0]
	v_pk_add_f32 v[244:245], v[244:245], 1.0 op_sel_hi:[1,0]
	v_pk_add_f32 v[246:247], v[246:247], 1.0 op_sel_hi:[1,0]
	v_pk_add_f32 v[248:249], v[248:249], 1.0 op_sel_hi:[1,0]
	v_rcp_f32_e32 v250, v242
	v_rcp_f32_e32 v251, v243
	s_nop 0
	v_pk_fma_f32 v[252:253], v[242:243], v[250:251], 1.0 op_sel_hi:[1,1,0] neg_lo:[1,0,0] neg_hi:[1,0,0]
	v_pk_fma_f32 v[250:251], v[252:253], v[250:251], v[250:251]
	v_pk_fma_f32 v[252:253], v[242:243], v[250:251], 1.0 op_sel_hi:[1,1,0] neg_lo:[1,0,0] neg_hi:[1,0,0]
	v_pk_fma_f32 v[254:255], v[252:253], v[250:251], v[250:251]
	v_pk_fma_f32 v[252:253], v[242:243], v[254:255], 1.0 op_sel_hi:[1,1,0] neg_lo:[1,0,0] neg_hi:[1,0,0]
	v_pk_fma_f32 v[254:255], v[252:253], v[250:251], v[254:255]
	v_div_fixup_f32 v242, v254, v242, 1.0
	v_div_fixup_f32 v243, v255, v243, 1.0
	v_rcp_f32_e32 v250, v244
	v_rcp_f32_e32 v251, v245
	s_nop 0
	v_pk_fma_f32 v[252:253], v[244:245], v[250:251], 1.0 op_sel_hi:[1,1,0] neg_lo:[1,0,0] neg_hi:[1,0,0]
	v_pk_fma_f32 v[250:251], v[252:253], v[250:251], v[250:251]
	v_pk_fma_f32 v[252:253], v[244:245], v[250:251], 1.0 op_sel_hi:[1,1,0] neg_lo:[1,0,0] neg_hi:[1,0,0]
	v_pk_fma_f32 v[254:255], v[252:253], v[250:251], v[250:251]
	v_pk_fma_f32 v[252:253], v[244:245], v[254:255], 1.0 op_sel_hi:[1,1,0] neg_lo:[1,0,0] neg_hi:[1,0,0]
	v_pk_fma_f32 v[254:255], v[252:253], v[250:251], v[254:255]
	v_div_fixup_f32 v244, v254, v244, 1.0
	v_div_fixup_f32 v245, v255, v245, 1.0
	v_rcp_f32_e32 v250, v246
	v_rcp_f32_e32 v251, v247
	s_nop 0
	v_pk_fma_f32 v[252:253], v[246:247], v[250:251], 1.0 op_sel_hi:[1,1,0] neg_lo:[1,0,0] neg_hi:[1,0,0]
	v_pk_fma_f32 v[250:251], v[252:253], v[250:251], v[250:251]
	v_pk_fma_f32 v[252:253], v[246:247], v[250:251], 1.0 op_sel_hi:[1,1,0] neg_lo:[1,0,0] neg_hi:[1,0,0]
	v_pk_fma_f32 v[254:255], v[252:253], v[250:251], v[250:251]
	v_pk_fma_f32 v[252:253], v[246:247], v[254:255], 1.0 op_sel_hi:[1,1,0] neg_lo:[1,0,0] neg_hi:[1,0,0]
	v_pk_fma_f32 v[254:255], v[252:253], v[250:251], v[254:255]
	v_div_fixup_f32 v246, v254, v246, 1.0
	v_div_fixup_f32 v247, v255, v247, 1.0
	v_rcp_f32_e32 v250, v248
	v_rcp_f32_e32 v251, v249
	s_nop 0
	v_pk_fma_f32 v[252:253], v[248:249], v[250:251], 1.0 op_sel_hi:[1,1,0] neg_lo:[1,0,0] neg_hi:[1,0,0]
	v_pk_fma_f32 v[250:251], v[252:253], v[250:251], v[250:251]
	v_pk_fma_f32 v[252:253], v[248:249], v[250:251], 1.0 op_sel_hi:[1,1,0] neg_lo:[1,0,0] neg_hi:[1,0,0]
	v_pk_fma_f32 v[254:255], v[252:253], v[250:251], v[250:251]
	v_pk_fma_f32 v[252:253], v[248:249], v[254:255], 1.0 op_sel_hi:[1,1,0] neg_lo:[1,0,0] neg_hi:[1,0,0]
	v_pk_fma_f32 v[254:255], v[252:253], v[250:251], v[254:255]
	v_div_fixup_f32 v248, v254, v248, 1.0
	v_div_fixup_f32 v249, v255, v249, 1.0
	v_lshlrev_b32_e32 v114, 16, v106
	v_and_b32_e32 v115, 0xffff0000, v106
	v_lshlrev_b32_e32 v116, 16, v108
	v_and_b32_e32 v117, 0xffff0000, v108
	v_lshlrev_b32_e32 v108, 16, v109
	v_and_b32_e32 v109, 0xffff0000, v109
	v_lshlrev_b32_e32 v106, 16, v107
	v_and_b32_e32 v107, 0xffff0000, v107
	v_pk_fma_f32 v[92:93], v[92:93], v[242:243], v[114:115]
	v_pk_fma_f32 v[102:103], v[90:91], v[248:249], v[108:109]
	v_pk_fma_f32 v[90:91], v[88:89], v[244:245], v[116:117]
	v_add_lshl_u32 v104, v140, v98, 1
	v_pk_fma_f32 v[94:95], v[94:95], v[246:247], v[106:107]
	v_cvt_pk_bf16_f32 v88, v92, v93
	s_nop 0
	v_cvt_pk_bf16_f32 v89, v94, v95
	v_cvt_pk_bf16_f32 v90, v90, v91
	v_cvt_pk_bf16_f32 v91, v102, v103
	buffer_store_dwordx4 v[88:91], v104, s[20:23], 0 offen sc1
	s_nop 0
	s_waitcnt vmcnt(7)
; __device__ __forceinline__ u32x4 pack8(const f32x4 v0, const f32x4 v1) { u32x4 w; w.x = pk2(v0[0], v0[1]); w.y = pk2(v0[2], v0[3]); w.z = pk2(v1[0], v1[1]); w.w = pk2(v1[2], v1[3]); return w; }
; __device__ __forceinline__ void unpack8(const u32x4 w, f32x4& v0, f32x4& v1) { v0 = (f32x4){bflo(w.x), bfhi(w.x), bflo(w.y), bfhi(w.y)}; v1 = (f32x4){bflo(w.z), bfhi(w.z), bflo(w.w), bfhi(w.w)}; }
; __device__ __forceinline__ float sigmoidf_(float x) { return 1.0f / (1.0f + __expf(-x)); }
;     __device__ __forceinline__ void operator()(const f32x4 (&acc)[2][2][4][2], const Unit& u, int wr, int wc, int fr, int fq) const {
;     ...
;                 for (int bj = 0; bj < 2; ++bj) {
;                     const u32x4 gw = *(const u32x4*)(rowp + O_GA + bj * 128);
;                     f32x4 g0, g1; unpack8(gw, g0, g1);
;                     f32x4 v0, v1;
; #pragma unroll
;                     for (int j = 0; j < 4; ++j) { v0[j] = sigmoidf_(g0[j]) * acc[ai][bj][m][0][j]; v1[j] = sigmoidf_(g1[j]) * acc[ai][bj][m][1][j]; }
;                     const u32x4 mw = *(const u32x4*)(rowp + bj * 128); f32x4 m0, m1; unpack8(mw, m0, m1); v0 += m0; v1 += m1;
;                     __builtin_amdgcn_raw_buffer_store_b128(pack8(v0, v1), rsrc, (unsigned)(((size_t)row * DIN + col0 + bj * 128) * 2), 0, 16  ); }
	v_mov_b32_e32 v88, v232
	v_mov_b32_e32 v89, v233
	v_mov_b32_e32 v90, v234
	v_mov_b32_e32 v91, v235
	v_mov_b32_e32 v92, v236
	v_mov_b32_e32 v93, v237
	v_mov_b32_e32 v94, v238
	v_mov_b32_e32 v95, v239
	v_add_u32_e32 v199, 0x111200, v198
	global_load_dwordx4 v[232:235], v199, s[26:27]
	v_add_u32_e32 v199, 0x110000, v198
	global_load_dwordx4 v[236:239], v199, s[26:27]
	s_mov_b32 s100, 0xbfb8aa3b
	v_lshlrev_b32_e32 v242, 16, v90
	v_and_b32_e32 v243, 0xffff0000, v90
	v_lshlrev_b32_e32 v244, 16, v88
	v_and_b32_e32 v245, 0xffff0000, v88
	v_lshlrev_b32_e32 v246, 16, v89
	v_and_b32_e32 v247, 0xffff0000, v89
	v_lshlrev_b32_e32 v248, 16, v91
	v_and_b32_e32 v249, 0xffff0000, v91
	v_pk_mul_f32 v[242:243], v[242:243], s[100:101] op_sel_hi:[1,0]
	v_pk_mul_f32 v[244:245], v[244:245], s[100:101] op_sel_hi:[1,0]
	v_pk_mul_f32 v[246:247], v[246:247], s[100:101] op_sel_hi:[1,0]
	v_pk_mul_f32 v[248:249], v[248:249], s[100:101] op_sel_hi:[1,0]
	v_exp_f32_e32 v242, v242
	v_exp_f32_e32 v243, v243
	v_exp_f32_e32 v244, v244
	v_exp_f32_e32 v245, v245
	v_exp_f32_e32 v246, v246
	v_exp_f32_e32 v247, v247
	v_exp_f32_e32 v248, v248
	v_exp_f32_e32 v249, v249
	s_nop 0
	v_pk_add_f32 v[242:243], v[242:243], 1.0 op_sel_hi:[1,0]
	v_pk_add_f32 v[244:245], v[244:245], 1.0 op_sel_hi:[1,0]
	v_pk_add_f32 v[246:247], v[246:247], 1.0 op_sel_hi:[1,0]
	v_pk_add_f32 v[248:249], v[248:249], 1.0 op_sel_hi:[1,0]
	v_rcp_f32_e32 v250, v242
	v_rcp_f32_e32 v251, v243
	s_nop 0
	v_pk_fma_f32 v[252:253], v[242:243], v[250:251], 1.0 op_sel_hi:[1,1,0] neg_lo:[1,0,0] neg_hi:[1,0,0]
	v_pk_fma_f32 v[250:251], v[252:253], v[250:251], v[250:251]
	v_pk_fma_f32 v[252:253], v[242:243], v[250:251], 1.0 op_sel_hi:[1,1,0] neg_lo:[1,0,0] neg_hi:[1,0,0]
	v_pk_fma_f32 v[254:255], v[252:253], v[250:251], v[250:251]
	v_pk_fma_f32 v[252:253], v[242:243], v[254:255], 1.0 op_sel_hi:[1,1,0] neg_lo:[1,0,0] neg_hi:[1,0,0]
	v_pk_fma_f32 v[254:255], v[252:253], v[250:251], v[254:255]
	v_div_fixup_f32 v242, v254, v242, 1.0
	v_div_fixup_f32 v243, v255, v243, 1.0
	v_rcp_f32_e32 v250, v244
	v_rcp_f32_e32 v251, v245
	s_nop 0
	v_pk_fma_f32 v[252:253], v[244:245], v[250:251], 1.0 op_sel_hi:[1,1,0] neg_lo:[1,0,0] neg_hi:[1,0,0]
	v_pk_fma_f32 v[250:251], v[252:253], v[250:251], v[250:251]
	v_pk_fma_f32 v[252:253], v[244:245], v[250:251], 1.0 op_sel_hi:[1,1,0] neg_lo:[1,0,0] neg_hi:[1,0,0]
	v_pk_fma_f32 v[254:255], v[252:253], v[250:251], v[250:251]
	v_pk_fma_f32 v[252:253], v[244:245], v[254:255], 1.0 op_sel_hi:[1,1,0] neg_lo:[1,0,0] neg_hi:[1,0,0]
	v_pk_fma_f32 v[254:255], v[252:253], v[250:251], v[254:255]
	v_div_fixup_f32 v244, v254, v244, 1.0
	v_div_fixup_f32 v245, v255, v245, 1.0
	v_rcp_f32_e32 v250, v246
	v_rcp_f32_e32 v251, v247
	s_nop 0
	v_pk_fma_f32 v[252:253], v[246:247], v[250:251], 1.0 op_sel_hi:[1,1,0] neg_lo:[1,0,0] neg_hi:[1,0,0]
	v_pk_fma_f32 v[250:251], v[252:253], v[250:251], v[250:251]
	v_pk_fma_f32 v[252:253], v[246:247], v[250:251], 1.0 op_sel_hi:[1,1,0] neg_lo:[1,0,0] neg_hi:[1,0,0]
	v_pk_fma_f32 v[254:255], v[252:253], v[250:251], v[250:251]
	v_pk_fma_f32 v[252:253], v[246:247], v[254:255], 1.0 op_sel_hi:[1,1,0] neg_lo:[1,0,0] neg_hi:[1,0,0]
	v_pk_fma_f32 v[254:255], v[252:253], v[250:251], v[254:255]
	v_div_fixup_f32 v246, v254, v246, 1.0
	v_div_fixup_f32 v247, v255, v247, 1.0
	v_rcp_f32_e32 v250, v248
	v_rcp_f32_e32 v251, v249
	s_nop 0
	v_pk_fma_f32 v[252:253], v[248:249], v[250:251], 1.0 op_sel_hi:[1,1,0] neg_lo:[1,0,0] neg_hi:[1,0,0]
	v_pk_fma_f32 v[250:251], v[252:253], v[250:251], v[250:251]
	v_pk_fma_f32 v[252:253], v[248:249], v[250:251], 1.0 op_sel_hi:[1,1,0] neg_lo:[1,0,0] neg_hi:[1,0,0]
	v_pk_fma_f32 v[254:255], v[252:253], v[250:251], v[250:251]
	v_pk_fma_f32 v[252:253], v[248:249], v[254:255], 1.0 op_sel_hi:[1,1,0] neg_lo:[1,0,0] neg_hi:[1,0,0]
	v_pk_fma_f32 v[254:255], v[252:253], v[250:251], v[254:255]
	v_div_fixup_f32 v248, v254, v248, 1.0
	v_div_fixup_f32 v249, v255, v249, 1.0
	v_lshlrev_b32_e32 v100, 16, v92
	v_and_b32_e32 v101, 0xffff0000, v92
	v_lshlrev_b32_e32 v102, 16, v94
	v_and_b32_e32 v103, 0xffff0000, v94
	v_lshlrev_b32_e32 v94, 16, v95
	v_and_b32_e32 v95, 0xffff0000, v95
	v_lshlrev_b32_e32 v92, 16, v93
	v_and_b32_e32 v93, 0xffff0000, v93
	v_pk_fma_f32 v[84:85], v[84:85], v[244:245], v[100:101]
	v_pk_fma_f32 v[88:89], v[82:83], v[248:249], v[94:95]
	v_pk_fma_f32 v[82:83], v[80:81], v[242:243], v[102:103]
	v_cvt_pk_bf16_f32 v80, v84, v85
	v_pk_fma_f32 v[86:87], v[86:87], v[246:247], v[92:93]
	s_nop 0
	v_cvt_pk_bf16_f32 v81, v86, v87
	v_cvt_pk_bf16_f32 v82, v82, v83
	v_cvt_pk_bf16_f32 v83, v88, v89
	buffer_store_dwordx4 v[80:83], v104, s[20:23], 0 offen offset:256 sc1
	s_nop 1
	v_add_u32_e32 v80, 0x4030, v158
	v_mad_i64_i32 v[82:83], s[6:7], v80, s77, 0
	v_lshl_add_u64 v[80:81], v[82:83], 1, s[26:27]
	v_lshl_add_u64 v[80:81], v[80:81], 0, v[142:143]
	v_add_co_u32_e32 v84, vcc, s78, v80
	s_nop 1
	v_addc_co_u32_e32 v85, vcc, 0, v81, vcc
	s_waitcnt vmcnt(7)
; __device__ __forceinline__ u32x4 pack8(const f32x4 v0, const f32x4 v1) { u32x4 w; w.x = pk2(v0[0], v0[1]); w.y = pk2(v0[2], v0[3]); w.z = pk2(v1[0], v1[1]); w.w = pk2(v1[2], v1[3]); return w; }
; __device__ __forceinline__ void unpack8(const u32x4 w, f32x4& v0, f32x4& v1) { v0 = (f32x4){bflo(w.x), bfhi(w.x), bflo(w.y), bfhi(w.y)}; v1 = (f32x4){bflo(w.z), bfhi(w.z), bflo(w.w), bfhi(w.w)}; }
; __device__ __forceinline__ float sigmoidf_(float x) { return 1.0f / (1.0f + __expf(-x)); }
;     __device__ __forceinline__ void operator()(const f32x4 (&acc)[2][2][4][2], const Unit& u, int wr, int wc, int fr, int fq) const {
;     ...
;                 for (int bj = 0; bj < 2; ++bj) {
;                     const u32x4 gw = *(const u32x4*)(rowp + O_GA + bj * 128);
;                     f32x4 g0, g1; unpack8(gw, g0, g1);
;                     f32x4 v0, v1;
; #pragma unroll
;                     for (int j = 0; j < 4; ++j) { v0[j] = sigmoidf_(g0[j]) * acc[ai][bj][m][0][j]; v1[j] = sigmoidf_(g1[j]) * acc[ai][bj][m][1][j]; }
;                     const u32x4 mw = *(const u32x4*)(rowp + bj * 128); f32x4 m0, m1; unpack8(mw, m0, m1); v0 += m0; v1 += m1;
;                     __builtin_amdgcn_raw_buffer_store_b128(pack8(v0, v1), rsrc, (unsigned)(((size_t)row * DIN + col0 + bj * 128) * 2), 0, 16  ); }
	v_mov_b32_e32 v86, v200
	v_mov_b32_e32 v87, v201
	v_mov_b32_e32 v88, v202
	v_mov_b32_e32 v89, v203
	v_mov_b32_e32 v90, v204
	v_mov_b32_e32 v91, v205
	v_mov_b32_e32 v92, v206
	v_mov_b32_e32 v93, v207
	v_add_u32_e32 v199, 0x111300, v198
	global_load_dwordx4 v[200:203], v199, s[26:27]
	v_add_u32_e32 v199, 0x110100, v198
	global_load_dwordx4 v[204:207], v199, s[26:27]
	s_mov_b32 s100, 0xbfb8aa3b
	v_lshlrev_b32_e32 v242, 16, v86
	v_and_b32_e32 v243, 0xffff0000, v86
	v_lshlrev_b32_e32 v244, 16, v88
	v_and_b32_e32 v245, 0xffff0000, v88
	v_lshlrev_b32_e32 v246, 16, v87
	v_and_b32_e32 v247, 0xffff0000, v87
	v_lshlrev_b32_e32 v248, 16, v89
	v_and_b32_e32 v249, 0xffff0000, v89
	v_pk_mul_f32 v[242:243], v[242:243], s[100:101] op_sel_hi:[1,0]
	v_pk_mul_f32 v[244:245], v[244:245], s[100:101] op_sel_hi:[1,0]
	v_pk_mul_f32 v[246:247], v[246:247], s[100:101] op_sel_hi:[1,0]
	v_pk_mul_f32 v[248:249], v[248:249], s[100:101] op_sel_hi:[1,0]
	v_exp_f32_e32 v242, v242
	v_exp_f32_e32 v243, v243
	v_exp_f32_e32 v244, v244
	v_exp_f32_e32 v245, v245
	v_exp_f32_e32 v246, v246
	v_exp_f32_e32 v247, v247
	v_exp_f32_e32 v248, v248
	v_exp_f32_e32 v249, v249
	s_nop 0
	v_pk_add_f32 v[242:243], v[242:243], 1.0 op_sel_hi:[1,0]
	v_pk_add_f32 v[244:245], v[244:245], 1.0 op_sel_hi:[1,0]
	v_pk_add_f32 v[246:247], v[246:247], 1.0 op_sel_hi:[1,0]
	v_pk_add_f32 v[248:249], v[248:249], 1.0 op_sel_hi:[1,0]
	v_rcp_f32_e32 v250, v242
	v_rcp_f32_e32 v251, v243
	s_nop 0
	v_pk_fma_f32 v[252:253], v[242:243], v[250:251], 1.0 op_sel_hi:[1,1,0] neg_lo:[1,0,0] neg_hi:[1,0,0]
	v_pk_fma_f32 v[250:251], v[252:253], v[250:251], v[250:251]
	v_pk_fma_f32 v[252:253], v[242:243], v[250:251], 1.0 op_sel_hi:[1,1,0] neg_lo:[1,0,0] neg_hi:[1,0,0]
	v_pk_fma_f32 v[254:255], v[252:253], v[250:251], v[250:251]
	v_pk_fma_f32 v[252:253], v[242:243], v[254:255], 1.0 op_sel_hi:[1,1,0] neg_lo:[1,0,0] neg_hi:[1,0,0]
	v_pk_fma_f32 v[254:255], v[252:253], v[250:251], v[254:255]
	v_div_fixup_f32 v242, v254, v242, 1.0
	v_div_fixup_f32 v243, v255, v243, 1.0
	v_rcp_f32_e32 v250, v244
	v_rcp_f32_e32 v251, v245
	s_nop 0
	v_pk_fma_f32 v[252:253], v[244:245], v[250:251], 1.0 op_sel_hi:[1,1,0] neg_lo:[1,0,0] neg_hi:[1,0,0]
	v_pk_fma_f32 v[250:251], v[252:253], v[250:251], v[250:251]
	v_pk_fma_f32 v[252:253], v[244:245], v[250:251], 1.0 op_sel_hi:[1,1,0] neg_lo:[1,0,0] neg_hi:[1,0,0]
	v_pk_fma_f32 v[254:255], v[252:253], v[250:251], v[250:251]
	v_pk_fma_f32 v[252:253], v[244:245], v[254:255], 1.0 op_sel_hi:[1,1,0] neg_lo:[1,0,0] neg_hi:[1,0,0]
	v_pk_fma_f32 v[254:255], v[252:253], v[250:251], v[254:255]
	v_div_fixup_f32 v244, v254, v244, 1.0
	v_div_fixup_f32 v245, v255, v245, 1.0
	v_rcp_f32_e32 v250, v246
	v_rcp_f32_e32 v251, v247
	s_nop 0
	v_pk_fma_f32 v[252:253], v[246:247], v[250:251], 1.0 op_sel_hi:[1,1,0] neg_lo:[1,0,0] neg_hi:[1,0,0]
	v_pk_fma_f32 v[250:251], v[252:253], v[250:251], v[250:251]
	v_pk_fma_f32 v[252:253], v[246:247], v[250:251], 1.0 op_sel_hi:[1,1,0] neg_lo:[1,0,0] neg_hi:[1,0,0]
	v_pk_fma_f32 v[254:255], v[252:253], v[250:251], v[250:251]
	v_pk_fma_f32 v[252:253], v[246:247], v[254:255], 1.0 op_sel_hi:[1,1,0] neg_lo:[1,0,0] neg_hi:[1,0,0]
	v_pk_fma_f32 v[254:255], v[252:253], v[250:251], v[254:255]
	v_div_fixup_f32 v246, v254, v246, 1.0
	v_div_fixup_f32 v247, v255, v247, 1.0
	v_rcp_f32_e32 v250, v248
	v_rcp_f32_e32 v251, v249
	s_nop 0
	v_pk_fma_f32 v[252:253], v[248:249], v[250:251], 1.0 op_sel_hi:[1,1,0] neg_lo:[1,0,0] neg_hi:[1,0,0]
	v_pk_fma_f32 v[250:251], v[252:253], v[250:251], v[250:251]
	v_pk_fma_f32 v[252:253], v[248:249], v[250:251], 1.0 op_sel_hi:[1,1,0] neg_lo:[1,0,0] neg_hi:[1,0,0]
	v_pk_fma_f32 v[254:255], v[252:253], v[250:251], v[250:251]
	v_pk_fma_f32 v[252:253], v[248:249], v[254:255], 1.0 op_sel_hi:[1,1,0] neg_lo:[1,0,0] neg_hi:[1,0,0]
	v_pk_fma_f32 v[254:255], v[252:253], v[250:251], v[254:255]
	v_div_fixup_f32 v248, v254, v248, 1.0
	v_div_fixup_f32 v249, v255, v249, 1.0
	v_lshlrev_b32_e32 v98, 16, v90
	v_and_b32_e32 v99, 0xffff0000, v90
	v_lshlrev_b32_e32 v100, 16, v92
	v_and_b32_e32 v101, 0xffff0000, v92
	v_lshlrev_b32_e32 v92, 16, v93
	v_and_b32_e32 v93, 0xffff0000, v93
	v_lshlrev_b32_e32 v90, 16, v91
	v_and_b32_e32 v91, 0xffff0000, v91
	v_pk_fma_f32 v[76:77], v[76:77], v[242:243], v[98:99]
	v_pk_fma_f32 v[86:87], v[74:75], v[248:249], v[92:93]
	v_pk_fma_f32 v[74:75], v[72:73], v[244:245], v[100:101]
	v_add_lshl_u32 v88, v140, v82, 1
	v_pk_fma_f32 v[78:79], v[78:79], v[246:247], v[90:91]
	v_cvt_pk_bf16_f32 v72, v76, v77
	s_nop 0
	v_cvt_pk_bf16_f32 v73, v78, v79
	v_cvt_pk_bf16_f32 v74, v74, v75
	v_cvt_pk_bf16_f32 v75, v86, v87
	buffer_store_dwordx4 v[72:75], v88, s[20:23], 0 offen sc1
	s_nop 0
	s_waitcnt vmcnt(7)
; __device__ __forceinline__ u32x4 pack8(const f32x4 v0, const f32x4 v1) { u32x4 w; w.x = pk2(v0[0], v0[1]); w.y = pk2(v0[2], v0[3]); w.z = pk2(v1[0], v1[1]); w.w = pk2(v1[2], v1[3]); return w; }
; __device__ __forceinline__ void unpack8(const u32x4 w, f32x4& v0, f32x4& v1) { v0 = (f32x4){bflo(w.x), bfhi(w.x), bflo(w.y), bfhi(w.y)}; v1 = (f32x4){bflo(w.z), bfhi(w.z), bflo(w.w), bfhi(w.w)}; }
; __device__ __forceinline__ float sigmoidf_(float x) { return 1.0f / (1.0f + __expf(-x)); }
;     __device__ __forceinline__ void operator()(const f32x4 (&acc)[2][2][4][2], const Unit& u, int wr, int wc, int fr, int fq) const {
;     ...
;                 for (int bj = 0; bj < 2; ++bj) {
;                     const u32x4 gw = *(const u32x4*)(rowp + O_GA + bj * 128);
;                     f32x4 g0, g1; unpack8(gw, g0, g1);
;                     f32x4 v0, v1;
; #pragma unroll
;                     for (int j = 0; j < 4; ++j) { v0[j] = sigmoidf_(g0[j]) * acc[ai][bj][m][0][j]; v1[j] = sigmoidf_(g1[j]) * acc[ai][bj][m][1][j]; }
;                     const u32x4 mw = *(const u32x4*)(rowp + bj * 128); f32x4 m0, m1; unpack8(mw, m0, m1); v0 += m0; v1 += m1;
;                     __builtin_amdgcn_raw_buffer_store_b128(pack8(v0, v1), rsrc, (unsigned)(((size_t)row * DIN + col0 + bj * 128) * 2), 0, 16  ); }
	v_mov_b32_e32 v72, v208
	v_mov_b32_e32 v73, v209
	v_mov_b32_e32 v74, v210
	v_mov_b32_e32 v75, v211
	v_mov_b32_e32 v76, v212
	v_mov_b32_e32 v77, v213
	v_mov_b32_e32 v78, v214
	v_mov_b32_e32 v79, v215
	v_add_u32_e32 v199, 0x133200, v198
	global_load_dwordx4 v[208:211], v199, s[26:27]
	v_add_u32_e32 v199, 0x132000, v198
	global_load_dwordx4 v[212:215], v199, s[26:27]
	s_mov_b32 s100, 0xbfb8aa3b
	v_lshlrev_b32_e32 v242, 16, v74
	v_and_b32_e32 v243, 0xffff0000, v74
	v_lshlrev_b32_e32 v244, 16, v72
	v_and_b32_e32 v245, 0xffff0000, v72
	v_lshlrev_b32_e32 v246, 16, v73
	v_and_b32_e32 v247, 0xffff0000, v73
	v_lshlrev_b32_e32 v248, 16, v75
	v_and_b32_e32 v249, 0xffff0000, v75
	v_pk_mul_f32 v[242:243], v[242:243], s[100:101] op_sel_hi:[1,0]
	v_pk_mul_f32 v[244:245], v[244:245], s[100:101] op_sel_hi:[1,0]
	v_pk_mul_f32 v[246:247], v[246:247], s[100:101] op_sel_hi:[1,0]
	v_pk_mul_f32 v[248:249], v[248:249], s[100:101] op_sel_hi:[1,0]
	v_exp_f32_e32 v242, v242
	v_exp_f32_e32 v243, v243
	v_exp_f32_e32 v244, v244
	v_exp_f32_e32 v245, v245
	v_exp_f32_e32 v246, v246
	v_exp_f32_e32 v247, v247
	v_exp_f32_e32 v248, v248
	v_exp_f32_e32 v249, v249
	s_nop 0
	v_pk_add_f32 v[242:243], v[242:243], 1.0 op_sel_hi:[1,0]
	v_pk_add_f32 v[244:245], v[244:245], 1.0 op_sel_hi:[1,0]
	v_pk_add_f32 v[246:247], v[246:247], 1.0 op_sel_hi:[1,0]
	v_pk_add_f32 v[248:249], v[248:249], 1.0 op_sel_hi:[1,0]
	v_rcp_f32_e32 v250, v242
	v_rcp_f32_e32 v251, v243
	s_nop 0
	v_pk_fma_f32 v[252:253], v[242:243], v[250:251], 1.0 op_sel_hi:[1,1,0] neg_lo:[1,0,0] neg_hi:[1,0,0]
	v_pk_fma_f32 v[250:251], v[252:253], v[250:251], v[250:251]
	v_pk_fma_f32 v[252:253], v[242:243], v[250:251], 1.0 op_sel_hi:[1,1,0] neg_lo:[1,0,0] neg_hi:[1,0,0]
	v_pk_fma_f32 v[254:255], v[252:253], v[250:251], v[250:251]
	v_pk_fma_f32 v[252:253], v[242:243], v[254:255], 1.0 op_sel_hi:[1,1,0] neg_lo:[1,0,0] neg_hi:[1,0,0]
	v_pk_fma_f32 v[254:255], v[252:253], v[250:251], v[254:255]
	v_div_fixup_f32 v242, v254, v242, 1.0
	v_div_fixup_f32 v243, v255, v243, 1.0
	v_rcp_f32_e32 v250, v244
	v_rcp_f32_e32 v251, v245
	s_nop 0
	v_pk_fma_f32 v[252:253], v[244:245], v[250:251], 1.0 op_sel_hi:[1,1,0] neg_lo:[1,0,0] neg_hi:[1,0,0]
	v_pk_fma_f32 v[250:251], v[252:253], v[250:251], v[250:251]
	v_pk_fma_f32 v[252:253], v[244:245], v[250:251], 1.0 op_sel_hi:[1,1,0] neg_lo:[1,0,0] neg_hi:[1,0,0]
	v_pk_fma_f32 v[254:255], v[252:253], v[250:251], v[250:251]
	v_pk_fma_f32 v[252:253], v[244:245], v[254:255], 1.0 op_sel_hi:[1,1,0] neg_lo:[1,0,0] neg_hi:[1,0,0]
	v_pk_fma_f32 v[254:255], v[252:253], v[250:251], v[254:255]
	v_div_fixup_f32 v244, v254, v244, 1.0
	v_div_fixup_f32 v245, v255, v245, 1.0
	v_rcp_f32_e32 v250, v246
	v_rcp_f32_e32 v251, v247
	s_nop 0
	v_pk_fma_f32 v[252:253], v[246:247], v[250:251], 1.0 op_sel_hi:[1,1,0] neg_lo:[1,0,0] neg_hi:[1,0,0]
	v_pk_fma_f32 v[250:251], v[252:253], v[250:251], v[250:251]
	v_pk_fma_f32 v[252:253], v[246:247], v[250:251], 1.0 op_sel_hi:[1,1,0] neg_lo:[1,0,0] neg_hi:[1,0,0]
	v_pk_fma_f32 v[254:255], v[252:253], v[250:251], v[250:251]
	v_pk_fma_f32 v[252:253], v[246:247], v[254:255], 1.0 op_sel_hi:[1,1,0] neg_lo:[1,0,0] neg_hi:[1,0,0]
	v_pk_fma_f32 v[254:255], v[252:253], v[250:251], v[254:255]
	v_div_fixup_f32 v246, v254, v246, 1.0
	v_div_fixup_f32 v247, v255, v247, 1.0
	v_rcp_f32_e32 v250, v248
	v_rcp_f32_e32 v251, v249
	s_nop 0
	v_pk_fma_f32 v[252:253], v[248:249], v[250:251], 1.0 op_sel_hi:[1,1,0] neg_lo:[1,0,0] neg_hi:[1,0,0]
	v_pk_fma_f32 v[250:251], v[252:253], v[250:251], v[250:251]
	v_pk_fma_f32 v[252:253], v[248:249], v[250:251], 1.0 op_sel_hi:[1,1,0] neg_lo:[1,0,0] neg_hi:[1,0,0]
	v_pk_fma_f32 v[254:255], v[252:253], v[250:251], v[250:251]
	v_pk_fma_f32 v[252:253], v[248:249], v[254:255], 1.0 op_sel_hi:[1,1,0] neg_lo:[1,0,0] neg_hi:[1,0,0]
	v_pk_fma_f32 v[254:255], v[252:253], v[250:251], v[254:255]
	v_div_fixup_f32 v248, v254, v248, 1.0
	v_div_fixup_f32 v249, v255, v249, 1.0
	v_lshlrev_b32_e32 v84, 16, v76
	v_and_b32_e32 v85, 0xffff0000, v76
	v_lshlrev_b32_e32 v86, 16, v78
	v_and_b32_e32 v87, 0xffff0000, v78
	v_lshlrev_b32_e32 v78, 16, v79
	v_and_b32_e32 v79, 0xffff0000, v79
	v_lshlrev_b32_e32 v76, 16, v77
	v_and_b32_e32 v77, 0xffff0000, v77
	v_pk_fma_f32 v[68:69], v[68:69], v[244:245], v[84:85]
	v_pk_fma_f32 v[72:73], v[66:67], v[248:249], v[78:79]
	v_pk_fma_f32 v[66:67], v[64:65], v[242:243], v[86:87]
	v_cvt_pk_bf16_f32 v64, v68, v69
	v_pk_fma_f32 v[70:71], v[70:71], v[246:247], v[76:77]
	s_nop 0
	v_cvt_pk_bf16_f32 v65, v70, v71
	v_cvt_pk_bf16_f32 v66, v66, v67
	v_cvt_pk_bf16_f32 v67, v72, v73
	buffer_store_dwordx4 v[64:67], v88, s[20:23], 0 offen offset:256 sc1
	s_nop 1
	v_add_u32_e32 v64, 0x4080, v158
	v_mad_i64_i32 v[66:67], s[6:7], v64, s77, 0
	v_lshl_add_u64 v[64:65], v[66:67], 1, s[26:27]
	v_lshl_add_u64 v[64:65], v[64:65], 0, v[142:143]
	v_add_co_u32_e32 v68, vcc, s78, v64
	s_nop 1
	v_addc_co_u32_e32 v69, vcc, 0, v65, vcc
	s_waitcnt vmcnt(7)
; __device__ __forceinline__ u32x4 pack8(const f32x4 v0, const f32x4 v1) { u32x4 w; w.x = pk2(v0[0], v0[1]); w.y = pk2(v0[2], v0[3]); w.z = pk2(v1[0], v1[1]); w.w = pk2(v1[2], v1[3]); return w; }
; __device__ __forceinline__ void unpack8(const u32x4 w, f32x4& v0, f32x4& v1) { v0 = (f32x4){bflo(w.x), bfhi(w.x), bflo(w.y), bfhi(w.y)}; v1 = (f32x4){bflo(w.z), bfhi(w.z), bflo(w.w), bfhi(w.w)}; }
; __device__ __forceinline__ float sigmoidf_(float x) { return 1.0f / (1.0f + __expf(-x)); }
;     __device__ __forceinline__ void operator()(const f32x4 (&acc)[2][2][4][2], const Unit& u, int wr, int wc, int fr, int fq) const {
;     ...
;                 for (int bj = 0; bj < 2; ++bj) {
;                     const u32x4 gw = *(const u32x4*)(rowp + O_GA + bj * 128);
;                     f32x4 g0, g1; unpack8(gw, g0, g1);
;                     f32x4 v0, v1;
; #pragma unroll
;                     for (int j = 0; j < 4; ++j) { v0[j] = sigmoidf_(g0[j]) * acc[ai][bj][m][0][j]; v1[j] = sigmoidf_(g1[j]) * acc[ai][bj][m][1][j]; }
;                     const u32x4 mw = *(const u32x4*)(rowp + bj * 128); f32x4 m0, m1; unpack8(mw, m0, m1); v0 += m0; v1 += m1;
;                     __builtin_amdgcn_raw_buffer_store_b128(pack8(v0, v1), rsrc, (unsigned)(((size_t)row * DIN + col0 + bj * 128) * 2), 0, 16  ); }
	v_mov_b32_e32 v70, v232
	v_mov_b32_e32 v71, v233
	v_mov_b32_e32 v72, v234
	v_mov_b32_e32 v73, v235
	v_mov_b32_e32 v74, v236
	v_mov_b32_e32 v75, v237
	v_mov_b32_e32 v76, v238
	v_mov_b32_e32 v77, v239
	v_add_u32_e32 v199, 0x133300, v198
	global_load_dwordx4 v[232:235], v199, s[26:27]
	v_add_u32_e32 v199, 0x132100, v198
	global_load_dwordx4 v[236:239], v199, s[26:27]
	s_mov_b32 s100, 0xbfb8aa3b
	v_lshlrev_b32_e32 v242, 16, v70
	v_and_b32_e32 v243, 0xffff0000, v70
	v_lshlrev_b32_e32 v244, 16, v72
	v_and_b32_e32 v245, 0xffff0000, v72
	v_lshlrev_b32_e32 v246, 16, v71
	v_and_b32_e32 v247, 0xffff0000, v71
	v_lshlrev_b32_e32 v248, 16, v73
	v_and_b32_e32 v249, 0xffff0000, v73
	v_pk_mul_f32 v[242:243], v[242:243], s[100:101] op_sel_hi:[1,0]
	v_pk_mul_f32 v[244:245], v[244:245], s[100:101] op_sel_hi:[1,0]
	v_pk_mul_f32 v[246:247], v[246:247], s[100:101] op_sel_hi:[1,0]
	v_pk_mul_f32 v[248:249], v[248:249], s[100:101] op_sel_hi:[1,0]
	v_exp_f32_e32 v242, v242
	v_exp_f32_e32 v243, v243
	v_exp_f32_e32 v244, v244
	v_exp_f32_e32 v245, v245
	v_exp_f32_e32 v246, v246
	v_exp_f32_e32 v247, v247
	v_exp_f32_e32 v248, v248
	v_exp_f32_e32 v249, v249
	s_nop 0
	v_pk_add_f32 v[242:243], v[242:243], 1.0 op_sel_hi:[1,0]
	v_pk_add_f32 v[244:245], v[244:245], 1.0 op_sel_hi:[1,0]
	v_pk_add_f32 v[246:247], v[246:247], 1.0 op_sel_hi:[1,0]
	v_pk_add_f32 v[248:249], v[248:249], 1.0 op_sel_hi:[1,0]
	v_rcp_f32_e32 v250, v242
	v_rcp_f32_e32 v251, v243
	s_nop 0
	v_pk_fma_f32 v[252:253], v[242:243], v[250:251], 1.0 op_sel_hi:[1,1,0] neg_lo:[1,0,0] neg_hi:[1,0,0]
	v_pk_fma_f32 v[250:251], v[252:253], v[250:251], v[250:251]
	v_pk_fma_f32 v[252:253], v[242:243], v[250:251], 1.0 op_sel_hi:[1,1,0] neg_lo:[1,0,0] neg_hi:[1,0,0]
	v_pk_fma_f32 v[254:255], v[252:253], v[250:251], v[250:251]
	v_pk_fma_f32 v[252:253], v[242:243], v[254:255], 1.0 op_sel_hi:[1,1,0] neg_lo:[1,0,0] neg_hi:[1,0,0]
	v_pk_fma_f32 v[254:255], v[252:253], v[250:251], v[254:255]
	v_div_fixup_f32 v242, v254, v242, 1.0
	v_div_fixup_f32 v243, v255, v243, 1.0
	v_rcp_f32_e32 v250, v244
	v_rcp_f32_e32 v251, v245
	s_nop 0
	v_pk_fma_f32 v[252:253], v[244:245], v[250:251], 1.0 op_sel_hi:[1,1,0] neg_lo:[1,0,0] neg_hi:[1,0,0]
	v_pk_fma_f32 v[250:251], v[252:253], v[250:251], v[250:251]
	v_pk_fma_f32 v[252:253], v[244:245], v[250:251], 1.0 op_sel_hi:[1,1,0] neg_lo:[1,0,0] neg_hi:[1,0,0]
	v_pk_fma_f32 v[254:255], v[252:253], v[250:251], v[250:251]
	v_pk_fma_f32 v[252:253], v[244:245], v[254:255], 1.0 op_sel_hi:[1,1,0] neg_lo:[1,0,0] neg_hi:[1,0,0]
	v_pk_fma_f32 v[254:255], v[252:253], v[250:251], v[254:255]
	v_div_fixup_f32 v244, v254, v244, 1.0
	v_div_fixup_f32 v245, v255, v245, 1.0
	v_rcp_f32_e32 v250, v246
	v_rcp_f32_e32 v251, v247
	s_nop 0
	v_pk_fma_f32 v[252:253], v[246:247], v[250:251], 1.0 op_sel_hi:[1,1,0] neg_lo:[1,0,0] neg_hi:[1,0,0]
	v_pk_fma_f32 v[250:251], v[252:253], v[250:251], v[250:251]
	v_pk_fma_f32 v[252:253], v[246:247], v[250:251], 1.0 op_sel_hi:[1,1,0] neg_lo:[1,0,0] neg_hi:[1,0,0]
	v_pk_fma_f32 v[254:255], v[252:253], v[250:251], v[250:251]
	v_pk_fma_f32 v[252:253], v[246:247], v[254:255], 1.0 op_sel_hi:[1,1,0] neg_lo:[1,0,0] neg_hi:[1,0,0]
	v_pk_fma_f32 v[254:255], v[252:253], v[250:251], v[254:255]
	v_div_fixup_f32 v246, v254, v246, 1.0
	v_div_fixup_f32 v247, v255, v247, 1.0
	v_rcp_f32_e32 v250, v248
	v_rcp_f32_e32 v251, v249
	s_nop 0
	v_pk_fma_f32 v[252:253], v[248:249], v[250:251], 1.0 op_sel_hi:[1,1,0] neg_lo:[1,0,0] neg_hi:[1,0,0]
	v_pk_fma_f32 v[250:251], v[252:253], v[250:251], v[250:251]
	v_pk_fma_f32 v[252:253], v[248:249], v[250:251], 1.0 op_sel_hi:[1,1,0] neg_lo:[1,0,0] neg_hi:[1,0,0]
	v_pk_fma_f32 v[254:255], v[252:253], v[250:251], v[250:251]
	v_pk_fma_f32 v[252:253], v[248:249], v[254:255], 1.0 op_sel_hi:[1,1,0] neg_lo:[1,0,0] neg_hi:[1,0,0]
	v_pk_fma_f32 v[254:255], v[252:253], v[250:251], v[254:255]
	v_div_fixup_f32 v248, v254, v248, 1.0
	v_div_fixup_f32 v249, v255, v249, 1.0
	v_lshlrev_b32_e32 v82, 16, v74
	v_and_b32_e32 v83, 0xffff0000, v74
	v_lshlrev_b32_e32 v84, 16, v76
	v_and_b32_e32 v85, 0xffff0000, v76
	v_lshlrev_b32_e32 v76, 16, v77
	v_and_b32_e32 v77, 0xffff0000, v77
	v_lshlrev_b32_e32 v74, 16, v75
	v_and_b32_e32 v75, 0xffff0000, v75
	v_pk_fma_f32 v[60:61], v[60:61], v[242:243], v[82:83]
	v_pk_fma_f32 v[70:71], v[58:59], v[248:249], v[76:77]
	v_pk_fma_f32 v[58:59], v[56:57], v[244:245], v[84:85]
	v_add_lshl_u32 v72, v140, v66, 1
	v_pk_fma_f32 v[62:63], v[62:63], v[246:247], v[74:75]
	v_cvt_pk_bf16_f32 v56, v60, v61
	s_nop 0
	v_cvt_pk_bf16_f32 v57, v62, v63
	v_cvt_pk_bf16_f32 v58, v58, v59
	v_cvt_pk_bf16_f32 v59, v70, v71
	buffer_store_dwordx4 v[56:59], v72, s[20:23], 0 offen sc1
	s_nop 0
	s_waitcnt vmcnt(7)
; __device__ __forceinline__ u32x4 pack8(const f32x4 v0, const f32x4 v1) { u32x4 w; w.x = pk2(v0[0], v0[1]); w.y = pk2(v0[2], v0[3]); w.z = pk2(v1[0], v1[1]); w.w = pk2(v1[2], v1[3]); return w; }
; __device__ __forceinline__ void unpack8(const u32x4 w, f32x4& v0, f32x4& v1) { v0 = (f32x4){bflo(w.x), bfhi(w.x), bflo(w.y), bfhi(w.y)}; v1 = (f32x4){bflo(w.z), bfhi(w.z), bflo(w.w), bfhi(w.w)}; }
; __device__ __forceinline__ float sigmoidf_(float x) { return 1.0f / (1.0f + __expf(-x)); }
;     __device__ __forceinline__ void operator()(const f32x4 (&acc)[2][2][4][2], const Unit& u, int wr, int wc, int fr, int fq) const {
;     ...
;                 for (int bj = 0; bj < 2; ++bj) {
;                     const u32x4 gw = *(const u32x4*)(rowp + O_GA + bj * 128);
;                     f32x4 g0, g1; unpack8(gw, g0, g1);
;                     f32x4 v0, v1;
; #pragma unroll
;                     for (int j = 0; j < 4; ++j) { v0[j] = sigmoidf_(g0[j]) * acc[ai][bj][m][0][j]; v1[j] = sigmoidf_(g1[j]) * acc[ai][bj][m][1][j]; }
;                     const u32x4 mw = *(const u32x4*)(rowp + bj * 128); f32x4 m0, m1; unpack8(mw, m0, m1); v0 += m0; v1 += m1;
;                     __builtin_amdgcn_raw_buffer_store_b128(pack8(v0, v1), rsrc, (unsigned)(((size_t)row * DIN + col0 + bj * 128) * 2), 0, 16  ); }
	v_mov_b32_e32 v56, v200
	v_mov_b32_e32 v57, v201
	v_mov_b32_e32 v58, v202
	v_mov_b32_e32 v59, v203
	v_mov_b32_e32 v60, v204
	v_mov_b32_e32 v61, v205
	v_mov_b32_e32 v62, v206
	v_mov_b32_e32 v63, v207
	v_add_u32_e32 v199, 0x155200, v198
	global_load_dwordx4 v[200:203], v199, s[26:27]
	v_add_u32_e32 v199, 0x154000, v198
	global_load_dwordx4 v[204:207], v199, s[26:27]
	s_mov_b32 s100, 0xbfb8aa3b
	v_lshlrev_b32_e32 v242, 16, v58
	v_and_b32_e32 v243, 0xffff0000, v58
	v_lshlrev_b32_e32 v244, 16, v56
	v_and_b32_e32 v245, 0xffff0000, v56
	v_lshlrev_b32_e32 v246, 16, v57
	v_and_b32_e32 v247, 0xffff0000, v57
	v_lshlrev_b32_e32 v248, 16, v59
	v_and_b32_e32 v249, 0xffff0000, v59
	v_pk_mul_f32 v[242:243], v[242:243], s[100:101] op_sel_hi:[1,0]
	v_pk_mul_f32 v[244:245], v[244:245], s[100:101] op_sel_hi:[1,0]
	v_pk_mul_f32 v[246:247], v[246:247], s[100:101] op_sel_hi:[1,0]
	v_pk_mul_f32 v[248:249], v[248:249], s[100:101] op_sel_hi:[1,0]
	v_exp_f32_e32 v242, v242
	v_exp_f32_e32 v243, v243
	v_exp_f32_e32 v244, v244
	v_exp_f32_e32 v245, v245
	v_exp_f32_e32 v246, v246
	v_exp_f32_e32 v247, v247
	v_exp_f32_e32 v248, v248
	v_exp_f32_e32 v249, v249
	s_nop 0
	v_pk_add_f32 v[242:243], v[242:243], 1.0 op_sel_hi:[1,0]
	v_pk_add_f32 v[244:245], v[244:245], 1.0 op_sel_hi:[1,0]
	v_pk_add_f32 v[246:247], v[246:247], 1.0 op_sel_hi:[1,0]
	v_pk_add_f32 v[248:249], v[248:249], 1.0 op_sel_hi:[1,0]
	v_rcp_f32_e32 v250, v242
	v_rcp_f32_e32 v251, v243
	s_nop 0
	v_pk_fma_f32 v[252:253], v[242:243], v[250:251], 1.0 op_sel_hi:[1,1,0] neg_lo:[1,0,0] neg_hi:[1,0,0]
	v_pk_fma_f32 v[250:251], v[252:253], v[250:251], v[250:251]
	v_pk_fma_f32 v[252:253], v[242:243], v[250:251], 1.0 op_sel_hi:[1,1,0] neg_lo:[1,0,0] neg_hi:[1,0,0]
	v_pk_fma_f32 v[254:255], v[252:253], v[250:251], v[250:251]
	v_pk_fma_f32 v[252:253], v[242:243], v[254:255], 1.0 op_sel_hi:[1,1,0] neg_lo:[1,0,0] neg_hi:[1,0,0]
	v_pk_fma_f32 v[254:255], v[252:253], v[250:251], v[254:255]
	v_div_fixup_f32 v242, v254, v242, 1.0
	v_div_fixup_f32 v243, v255, v243, 1.0
	v_rcp_f32_e32 v250, v244
	v_rcp_f32_e32 v251, v245
	s_nop 0
	v_pk_fma_f32 v[252:253], v[244:245], v[250:251], 1.0 op_sel_hi:[1,1,0] neg_lo:[1,0,0] neg_hi:[1,0,0]
	v_pk_fma_f32 v[250:251], v[252:253], v[250:251], v[250:251]
	v_pk_fma_f32 v[252:253], v[244:245], v[250:251], 1.0 op_sel_hi:[1,1,0] neg_lo:[1,0,0] neg_hi:[1,0,0]
	v_pk_fma_f32 v[254:255], v[252:253], v[250:251], v[250:251]
	v_pk_fma_f32 v[252:253], v[244:245], v[254:255], 1.0 op_sel_hi:[1,1,0] neg_lo:[1,0,0] neg_hi:[1,0,0]
	v_pk_fma_f32 v[254:255], v[252:253], v[250:251], v[254:255]
	v_div_fixup_f32 v244, v254, v244, 1.0
	v_div_fixup_f32 v245, v255, v245, 1.0
	v_rcp_f32_e32 v250, v246
	v_rcp_f32_e32 v251, v247
	s_nop 0
	v_pk_fma_f32 v[252:253], v[246:247], v[250:251], 1.0 op_sel_hi:[1,1,0] neg_lo:[1,0,0] neg_hi:[1,0,0]
	v_pk_fma_f32 v[250:251], v[252:253], v[250:251], v[250:251]
	v_pk_fma_f32 v[252:253], v[246:247], v[250:251], 1.0 op_sel_hi:[1,1,0] neg_lo:[1,0,0] neg_hi:[1,0,0]
	v_pk_fma_f32 v[254:255], v[252:253], v[250:251], v[250:251]
	v_pk_fma_f32 v[252:253], v[246:247], v[254:255], 1.0 op_sel_hi:[1,1,0] neg_lo:[1,0,0] neg_hi:[1,0,0]
	v_pk_fma_f32 v[254:255], v[252:253], v[250:251], v[254:255]
	v_div_fixup_f32 v246, v254, v246, 1.0
	v_div_fixup_f32 v247, v255, v247, 1.0
	v_rcp_f32_e32 v250, v248
	v_rcp_f32_e32 v251, v249
	s_nop 0
	v_pk_fma_f32 v[252:253], v[248:249], v[250:251], 1.0 op_sel_hi:[1,1,0] neg_lo:[1,0,0] neg_hi:[1,0,0]
	v_pk_fma_f32 v[250:251], v[252:253], v[250:251], v[250:251]
	v_pk_fma_f32 v[252:253], v[248:249], v[250:251], 1.0 op_sel_hi:[1,1,0] neg_lo:[1,0,0] neg_hi:[1,0,0]
	v_pk_fma_f32 v[254:255], v[252:253], v[250:251], v[250:251]
	v_pk_fma_f32 v[252:253], v[248:249], v[254:255], 1.0 op_sel_hi:[1,1,0] neg_lo:[1,0,0] neg_hi:[1,0,0]
	v_pk_fma_f32 v[254:255], v[252:253], v[250:251], v[254:255]
	v_div_fixup_f32 v248, v254, v248, 1.0
	v_div_fixup_f32 v249, v255, v249, 1.0
	v_lshlrev_b32_e32 v68, 16, v60
	v_and_b32_e32 v69, 0xffff0000, v60
	v_lshlrev_b32_e32 v70, 16, v62
	v_and_b32_e32 v71, 0xffff0000, v62
	v_lshlrev_b32_e32 v62, 16, v63
	v_and_b32_e32 v63, 0xffff0000, v63
	v_lshlrev_b32_e32 v60, 16, v61
	v_and_b32_e32 v61, 0xffff0000, v61
	v_pk_fma_f32 v[52:53], v[52:53], v[244:245], v[68:69]
	v_pk_fma_f32 v[56:57], v[50:51], v[248:249], v[62:63]
	v_pk_fma_f32 v[50:51], v[48:49], v[242:243], v[70:71]
	v_cvt_pk_bf16_f32 v48, v52, v53
	v_pk_fma_f32 v[54:55], v[54:55], v[246:247], v[60:61]
	s_nop 0
	v_cvt_pk_bf16_f32 v49, v54, v55
	v_cvt_pk_bf16_f32 v50, v50, v51
	v_cvt_pk_bf16_f32 v51, v56, v57
	buffer_store_dwordx4 v[48:51], v72, s[20:23], 0 offen offset:256 sc1
	s_nop 1
	v_add_u32_e32 v48, 0x4090, v158
	v_mad_i64_i32 v[50:51], s[6:7], v48, s77, 0
	v_lshl_add_u64 v[48:49], v[50:51], 1, s[26:27]
	v_lshl_add_u64 v[48:49], v[48:49], 0, v[142:143]
	v_add_co_u32_e32 v52, vcc, s78, v48
	s_nop 1
	v_addc_co_u32_e32 v53, vcc, 0, v49, vcc
	s_waitcnt vmcnt(7)
; __device__ __forceinline__ u32x4 pack8(const f32x4 v0, const f32x4 v1) { u32x4 w; w.x = pk2(v0[0], v0[1]); w.y = pk2(v0[2], v0[3]); w.z = pk2(v1[0], v1[1]); w.w = pk2(v1[2], v1[3]); return w; }
; __device__ __forceinline__ void unpack8(const u32x4 w, f32x4& v0, f32x4& v1) { v0 = (f32x4){bflo(w.x), bfhi(w.x), bflo(w.y), bfhi(w.y)}; v1 = (f32x4){bflo(w.z), bfhi(w.z), bflo(w.w), bfhi(w.w)}; }
; __device__ __forceinline__ float sigmoidf_(float x) { return 1.0f / (1.0f + __expf(-x)); }
;     __device__ __forceinline__ void operator()(const f32x4 (&acc)[2][2][4][2], const Unit& u, int wr, int wc, int fr, int fq) const {
;     ...
;                 for (int bj = 0; bj < 2; ++bj) {
;                     const u32x4 gw = *(const u32x4*)(rowp + O_GA + bj * 128);
;                     f32x4 g0, g1; unpack8(gw, g0, g1);
;                     f32x4 v0, v1;
; #pragma unroll
;                     for (int j = 0; j < 4; ++j) { v0[j] = sigmoidf_(g0[j]) * acc[ai][bj][m][0][j]; v1[j] = sigmoidf_(g1[j]) * acc[ai][bj][m][1][j]; }
;                     const u32x4 mw = *(const u32x4*)(rowp + bj * 128); f32x4 m0, m1; unpack8(mw, m0, m1); v0 += m0; v1 += m1;
;                     __builtin_amdgcn_raw_buffer_store_b128(pack8(v0, v1), rsrc, (unsigned)(((size_t)row * DIN + col0 + bj * 128) * 2), 0, 16  ); }
	v_mov_b32_e32 v54, v208
	v_mov_b32_e32 v55, v209
	v_mov_b32_e32 v56, v210
	v_mov_b32_e32 v57, v211
	v_mov_b32_e32 v58, v212
	v_mov_b32_e32 v59, v213
	v_mov_b32_e32 v60, v214
	v_mov_b32_e32 v61, v215
	v_add_u32_e32 v199, 0x155300, v198
	global_load_dwordx4 v[208:211], v199, s[26:27]
	v_add_u32_e32 v199, 0x154100, v198
	global_load_dwordx4 v[212:215], v199, s[26:27]
	s_mov_b32 s100, 0xbfb8aa3b
	v_lshlrev_b32_e32 v242, 16, v54
	v_and_b32_e32 v243, 0xffff0000, v54
	v_lshlrev_b32_e32 v244, 16, v56
	v_and_b32_e32 v245, 0xffff0000, v56
	v_lshlrev_b32_e32 v246, 16, v55
	v_and_b32_e32 v247, 0xffff0000, v55
	v_lshlrev_b32_e32 v248, 16, v57
	v_and_b32_e32 v249, 0xffff0000, v57
	v_pk_mul_f32 v[242:243], v[242:243], s[100:101] op_sel_hi:[1,0]
	v_pk_mul_f32 v[244:245], v[244:245], s[100:101] op_sel_hi:[1,0]
	v_pk_mul_f32 v[246:247], v[246:247], s[100:101] op_sel_hi:[1,0]
	v_pk_mul_f32 v[248:249], v[248:249], s[100:101] op_sel_hi:[1,0]
	v_exp_f32_e32 v242, v242
	v_exp_f32_e32 v243, v243
	v_exp_f32_e32 v244, v244
	v_exp_f32_e32 v245, v245
	v_exp_f32_e32 v246, v246
	v_exp_f32_e32 v247, v247
	v_exp_f32_e32 v248, v248
	v_exp_f32_e32 v249, v249
	s_nop 0
	v_pk_add_f32 v[242:243], v[242:243], 1.0 op_sel_hi:[1,0]
	v_pk_add_f32 v[244:245], v[244:245], 1.0 op_sel_hi:[1,0]
	v_pk_add_f32 v[246:247], v[246:247], 1.0 op_sel_hi:[1,0]
	v_pk_add_f32 v[248:249], v[248:249], 1.0 op_sel_hi:[1,0]
	v_rcp_f32_e32 v250, v242
	v_rcp_f32_e32 v251, v243
	s_nop 0
	v_pk_fma_f32 v[252:253], v[242:243], v[250:251], 1.0 op_sel_hi:[1,1,0] neg_lo:[1,0,0] neg_hi:[1,0,0]
	v_pk_fma_f32 v[250:251], v[252:253], v[250:251], v[250:251]
	v_pk_fma_f32 v[252:253], v[242:243], v[250:251], 1.0 op_sel_hi:[1,1,0] neg_lo:[1,0,0] neg_hi:[1,0,0]
	v_pk_fma_f32 v[254:255], v[252:253], v[250:251], v[250:251]
	v_pk_fma_f32 v[252:253], v[242:243], v[254:255], 1.0 op_sel_hi:[1,1,0] neg_lo:[1,0,0] neg_hi:[1,0,0]
	v_pk_fma_f32 v[254:255], v[252:253], v[250:251], v[254:255]
	v_div_fixup_f32 v242, v254, v242, 1.0
	v_div_fixup_f32 v243, v255, v243, 1.0
	v_rcp_f32_e32 v250, v244
	v_rcp_f32_e32 v251, v245
	s_nop 0
	v_pk_fma_f32 v[252:253], v[244:245], v[250:251], 1.0 op_sel_hi:[1,1,0] neg_lo:[1,0,0] neg_hi:[1,0,0]
	v_pk_fma_f32 v[250:251], v[252:253], v[250:251], v[250:251]
	v_pk_fma_f32 v[252:253], v[244:245], v[250:251], 1.0 op_sel_hi:[1,1,0] neg_lo:[1,0,0] neg_hi:[1,0,0]
	v_pk_fma_f32 v[254:255], v[252:253], v[250:251], v[250:251]
	v_pk_fma_f32 v[252:253], v[244:245], v[254:255], 1.0 op_sel_hi:[1,1,0] neg_lo:[1,0,0] neg_hi:[1,0,0]
	v_pk_fma_f32 v[254:255], v[252:253], v[250:251], v[254:255]
	v_div_fixup_f32 v244, v254, v244, 1.0
	v_div_fixup_f32 v245, v255, v245, 1.0
	v_rcp_f32_e32 v250, v246
	v_rcp_f32_e32 v251, v247
	s_nop 0
	v_pk_fma_f32 v[252:253], v[246:247], v[250:251], 1.0 op_sel_hi:[1,1,0] neg_lo:[1,0,0] neg_hi:[1,0,0]
	v_pk_fma_f32 v[250:251], v[252:253], v[250:251], v[250:251]
	v_pk_fma_f32 v[252:253], v[246:247], v[250:251], 1.0 op_sel_hi:[1,1,0] neg_lo:[1,0,0] neg_hi:[1,0,0]
	v_pk_fma_f32 v[254:255], v[252:253], v[250:251], v[250:251]
	v_pk_fma_f32 v[252:253], v[246:247], v[254:255], 1.0 op_sel_hi:[1,1,0] neg_lo:[1,0,0] neg_hi:[1,0,0]
	v_pk_fma_f32 v[254:255], v[252:253], v[250:251], v[254:255]
	v_div_fixup_f32 v246, v254, v246, 1.0
	v_div_fixup_f32 v247, v255, v247, 1.0
	v_rcp_f32_e32 v250, v248
	v_rcp_f32_e32 v251, v249
	s_nop 0
	v_pk_fma_f32 v[252:253], v[248:249], v[250:251], 1.0 op_sel_hi:[1,1,0] neg_lo:[1,0,0] neg_hi:[1,0,0]
	v_pk_fma_f32 v[250:251], v[252:253], v[250:251], v[250:251]
	v_pk_fma_f32 v[252:253], v[248:249], v[250:251], 1.0 op_sel_hi:[1,1,0] neg_lo:[1,0,0] neg_hi:[1,0,0]
	v_pk_fma_f32 v[254:255], v[252:253], v[250:251], v[250:251]
	v_pk_fma_f32 v[252:253], v[248:249], v[254:255], 1.0 op_sel_hi:[1,1,0] neg_lo:[1,0,0] neg_hi:[1,0,0]
	v_pk_fma_f32 v[254:255], v[252:253], v[250:251], v[254:255]
	v_div_fixup_f32 v248, v254, v248, 1.0
	v_div_fixup_f32 v249, v255, v249, 1.0
	v_lshlrev_b32_e32 v66, 16, v58
	v_and_b32_e32 v67, 0xffff0000, v58
	v_lshlrev_b32_e32 v68, 16, v60
	v_and_b32_e32 v69, 0xffff0000, v60
	v_lshlrev_b32_e32 v60, 16, v61
	v_and_b32_e32 v61, 0xffff0000, v61
	v_lshlrev_b32_e32 v58, 16, v59
	v_and_b32_e32 v59, 0xffff0000, v59
	v_pk_fma_f32 v[44:45], v[44:45], v[242:243], v[66:67]
	v_pk_fma_f32 v[54:55], v[42:43], v[248:249], v[60:61]
	v_pk_fma_f32 v[42:43], v[40:41], v[244:245], v[68:69]
	v_add_lshl_u32 v56, v140, v50, 1
	v_pk_fma_f32 v[46:47], v[46:47], v[246:247], v[58:59]
	v_cvt_pk_bf16_f32 v40, v44, v45
	s_nop 0
	v_cvt_pk_bf16_f32 v41, v46, v47
	v_cvt_pk_bf16_f32 v42, v42, v43
	v_cvt_pk_bf16_f32 v43, v54, v55
	buffer_store_dwordx4 v[40:43], v56, s[20:23], 0 offen sc1
	s_nop 0
	s_waitcnt vmcnt(7)
; __device__ __forceinline__ u32x4 pack8(const f32x4 v0, const f32x4 v1) { u32x4 w; w.x = pk2(v0[0], v0[1]); w.y = pk2(v0[2], v0[3]); w.z = pk2(v1[0], v1[1]); w.w = pk2(v1[2], v1[3]); return w; }
; __device__ __forceinline__ void unpack8(const u32x4 w, f32x4& v0, f32x4& v1) { v0 = (f32x4){bflo(w.x), bfhi(w.x), bflo(w.y), bfhi(w.y)}; v1 = (f32x4){bflo(w.z), bfhi(w.z), bflo(w.w), bfhi(w.w)}; }
; __device__ __forceinline__ float sigmoidf_(float x) { return 1.0f / (1.0f + __expf(-x)); }
;     __device__ __forceinline__ void operator()(const f32x4 (&acc)[2][2][4][2], const Unit& u, int wr, int wc, int fr, int fq) const {
;     ...
;                 for (int bj = 0; bj < 2; ++bj) {
;                     const u32x4 gw = *(const u32x4*)(rowp + O_GA + bj * 128);
;                     f32x4 g0, g1; unpack8(gw, g0, g1);
;                     f32x4 v0, v1;
; #pragma unroll
;                     for (int j = 0; j < 4; ++j) { v0[j] = sigmoidf_(g0[j]) * acc[ai][bj][m][0][j]; v1[j] = sigmoidf_(g1[j]) * acc[ai][bj][m][1][j]; }
;                     const u32x4 mw = *(const u32x4*)(rowp + bj * 128); f32x4 m0, m1; unpack8(mw, m0, m1); v0 += m0; v1 += m1;
;                     __builtin_amdgcn_raw_buffer_store_b128(pack8(v0, v1), rsrc, (unsigned)(((size_t)row * DIN + col0 + bj * 128) * 2), 0, 16  ); }
	v_mov_b32_e32 v40, v232
	v_mov_b32_e32 v41, v233
	v_mov_b32_e32 v42, v234
	v_mov_b32_e32 v43, v235
	v_mov_b32_e32 v44, v236
	v_mov_b32_e32 v45, v237
	v_mov_b32_e32 v46, v238
	v_mov_b32_e32 v47, v239
	v_add_u32_e32 v199, 0x177200, v198
	global_load_dwordx4 v[232:235], v199, s[26:27]
	v_add_u32_e32 v199, 0x176000, v198
	global_load_dwordx4 v[236:239], v199, s[26:27]
	s_mov_b32 s100, 0xbfb8aa3b
	v_lshlrev_b32_e32 v242, 16, v42
	v_and_b32_e32 v243, 0xffff0000, v42
	v_lshlrev_b32_e32 v244, 16, v40
	v_and_b32_e32 v245, 0xffff0000, v40
	v_lshlrev_b32_e32 v246, 16, v41
	v_and_b32_e32 v247, 0xffff0000, v41
	v_lshlrev_b32_e32 v248, 16, v43
	v_and_b32_e32 v249, 0xffff0000, v43
	v_pk_mul_f32 v[242:243], v[242:243], s[100:101] op_sel_hi:[1,0]
	v_pk_mul_f32 v[244:245], v[244:245], s[100:101] op_sel_hi:[1,0]
	v_pk_mul_f32 v[246:247], v[246:247], s[100:101] op_sel_hi:[1,0]
	v_pk_mul_f32 v[248:249], v[248:249], s[100:101] op_sel_hi:[1,0]
	v_exp_f32_e32 v242, v242
	v_exp_f32_e32 v243, v243
	v_exp_f32_e32 v244, v244
	v_exp_f32_e32 v245, v245
	v_exp_f32_e32 v246, v246
	v_exp_f32_e32 v247, v247
	v_exp_f32_e32 v248, v248
	v_exp_f32_e32 v249, v249
	s_nop 0
	v_pk_add_f32 v[242:243], v[242:243], 1.0 op_sel_hi:[1,0]
	v_pk_add_f32 v[244:245], v[244:245], 1.0 op_sel_hi:[1,0]
	v_pk_add_f32 v[246:247], v[246:247], 1.0 op_sel_hi:[1,0]
	v_pk_add_f32 v[248:249], v[248:249], 1.0 op_sel_hi:[1,0]
	v_rcp_f32_e32 v250, v242
	v_rcp_f32_e32 v251, v243
	s_nop 0
	v_pk_fma_f32 v[252:253], v[242:243], v[250:251], 1.0 op_sel_hi:[1,1,0] neg_lo:[1,0,0] neg_hi:[1,0,0]
	v_pk_fma_f32 v[250:251], v[252:253], v[250:251], v[250:251]
	v_pk_fma_f32 v[252:253], v[242:243], v[250:251], 1.0 op_sel_hi:[1,1,0] neg_lo:[1,0,0] neg_hi:[1,0,0]
	v_pk_fma_f32 v[254:255], v[252:253], v[250:251], v[250:251]
	v_pk_fma_f32 v[252:253], v[242:243], v[254:255], 1.0 op_sel_hi:[1,1,0] neg_lo:[1,0,0] neg_hi:[1,0,0]
	v_pk_fma_f32 v[254:255], v[252:253], v[250:251], v[254:255]
	v_div_fixup_f32 v242, v254, v242, 1.0
	v_div_fixup_f32 v243, v255, v243, 1.0
	v_rcp_f32_e32 v250, v244
	v_rcp_f32_e32 v251, v245
	s_nop 0
	v_pk_fma_f32 v[252:253], v[244:245], v[250:251], 1.0 op_sel_hi:[1,1,0] neg_lo:[1,0,0] neg_hi:[1,0,0]
	v_pk_fma_f32 v[250:251], v[252:253], v[250:251], v[250:251]
	v_pk_fma_f32 v[252:253], v[244:245], v[250:251], 1.0 op_sel_hi:[1,1,0] neg_lo:[1,0,0] neg_hi:[1,0,0]
	v_pk_fma_f32 v[254:255], v[252:253], v[250:251], v[250:251]
	v_pk_fma_f32 v[252:253], v[244:245], v[254:255], 1.0 op_sel_hi:[1,1,0] neg_lo:[1,0,0] neg_hi:[1,0,0]
	v_pk_fma_f32 v[254:255], v[252:253], v[250:251], v[254:255]
	v_div_fixup_f32 v244, v254, v244, 1.0
	v_div_fixup_f32 v245, v255, v245, 1.0
	v_rcp_f32_e32 v250, v246
	v_rcp_f32_e32 v251, v247
	s_nop 0
	v_pk_fma_f32 v[252:253], v[246:247], v[250:251], 1.0 op_sel_hi:[1,1,0] neg_lo:[1,0,0] neg_hi:[1,0,0]
	v_pk_fma_f32 v[250:251], v[252:253], v[250:251], v[250:251]
	v_pk_fma_f32 v[252:253], v[246:247], v[250:251], 1.0 op_sel_hi:[1,1,0] neg_lo:[1,0,0] neg_hi:[1,0,0]
	v_pk_fma_f32 v[254:255], v[252:253], v[250:251], v[250:251]
	v_pk_fma_f32 v[252:253], v[246:247], v[254:255], 1.0 op_sel_hi:[1,1,0] neg_lo:[1,0,0] neg_hi:[1,0,0]
	v_pk_fma_f32 v[254:255], v[252:253], v[250:251], v[254:255]
	v_div_fixup_f32 v246, v254, v246, 1.0
	v_div_fixup_f32 v247, v255, v247, 1.0
	v_rcp_f32_e32 v250, v248
	v_rcp_f32_e32 v251, v249
	s_nop 0
	v_pk_fma_f32 v[252:253], v[248:249], v[250:251], 1.0 op_sel_hi:[1,1,0] neg_lo:[1,0,0] neg_hi:[1,0,0]
	v_pk_fma_f32 v[250:251], v[252:253], v[250:251], v[250:251]
	v_pk_fma_f32 v[252:253], v[248:249], v[250:251], 1.0 op_sel_hi:[1,1,0] neg_lo:[1,0,0] neg_hi:[1,0,0]
	v_pk_fma_f32 v[254:255], v[252:253], v[250:251], v[250:251]
	v_pk_fma_f32 v[252:253], v[248:249], v[254:255], 1.0 op_sel_hi:[1,1,0] neg_lo:[1,0,0] neg_hi:[1,0,0]
	v_pk_fma_f32 v[254:255], v[252:253], v[250:251], v[254:255]
	v_div_fixup_f32 v248, v254, v248, 1.0
	v_div_fixup_f32 v249, v255, v249, 1.0
	v_lshlrev_b32_e32 v52, 16, v44
	v_and_b32_e32 v53, 0xffff0000, v44
	v_lshlrev_b32_e32 v54, 16, v46
	v_and_b32_e32 v55, 0xffff0000, v46
	v_lshlrev_b32_e32 v46, 16, v47
	v_and_b32_e32 v47, 0xffff0000, v47
	v_lshlrev_b32_e32 v44, 16, v45
	v_and_b32_e32 v45, 0xffff0000, v45
	v_pk_fma_f32 v[36:37], v[36:37], v[244:245], v[52:53]
	v_pk_fma_f32 v[40:41], v[34:35], v[248:249], v[46:47]
	v_pk_fma_f32 v[34:35], v[32:33], v[242:243], v[54:55]
	v_cvt_pk_bf16_f32 v32, v36, v37
	v_pk_fma_f32 v[38:39], v[38:39], v[246:247], v[44:45]
	s_nop 0
	v_cvt_pk_bf16_f32 v33, v38, v39
	v_cvt_pk_bf16_f32 v34, v34, v35
	v_cvt_pk_bf16_f32 v35, v40, v41
	buffer_store_dwordx4 v[32:35], v56, s[20:23], 0 offen offset:256 sc1
	s_nop 1
	v_add_u32_e32 v32, 0x40a0, v158
	v_mad_i64_i32 v[34:35], s[6:7], v32, s77, 0
	v_lshl_add_u64 v[32:33], v[34:35], 1, s[26:27]
	v_lshl_add_u64 v[32:33], v[32:33], 0, v[142:143]
	v_add_co_u32_e32 v36, vcc, s78, v32
	s_nop 1
	v_addc_co_u32_e32 v37, vcc, 0, v33, vcc
	s_waitcnt vmcnt(7)
; __device__ __forceinline__ u32x4 pack8(const f32x4 v0, const f32x4 v1) { u32x4 w; w.x = pk2(v0[0], v0[1]); w.y = pk2(v0[2], v0[3]); w.z = pk2(v1[0], v1[1]); w.w = pk2(v1[2], v1[3]); return w; }
; __device__ __forceinline__ void unpack8(const u32x4 w, f32x4& v0, f32x4& v1) { v0 = (f32x4){bflo(w.x), bfhi(w.x), bflo(w.y), bfhi(w.y)}; v1 = (f32x4){bflo(w.z), bfhi(w.z), bflo(w.w), bfhi(w.w)}; }
; __device__ __forceinline__ float sigmoidf_(float x) { return 1.0f / (1.0f + __expf(-x)); }
;     __device__ __forceinline__ void operator()(const f32x4 (&acc)[2][2][4][2], const Unit& u, int wr, int wc, int fr, int fq) const {
;     ...
;                 for (int bj = 0; bj < 2; ++bj) {
;                     const u32x4 gw = *(const u32x4*)(rowp + O_GA + bj * 128);
;                     f32x4 g0, g1; unpack8(gw, g0, g1);
;                     f32x4 v0, v1;
; #pragma unroll
;                     for (int j = 0; j < 4; ++j) { v0[j] = sigmoidf_(g0[j]) * acc[ai][bj][m][0][j]; v1[j] = sigmoidf_(g1[j]) * acc[ai][bj][m][1][j]; }
;                     const u32x4 mw = *(const u32x4*)(rowp + bj * 128); f32x4 m0, m1; unpack8(mw, m0, m1); v0 += m0; v1 += m1;
;                     __builtin_amdgcn_raw_buffer_store_b128(pack8(v0, v1), rsrc, (unsigned)(((size_t)row * DIN + col0 + bj * 128) * 2), 0, 16  ); }
	v_mov_b32_e32 v38, v200
	v_mov_b32_e32 v39, v201
	v_mov_b32_e32 v40, v202
	v_mov_b32_e32 v41, v203
	v_mov_b32_e32 v42, v204
	v_mov_b32_e32 v43, v205
	v_mov_b32_e32 v44, v206
	v_mov_b32_e32 v45, v207
	v_add_u32_e32 v199, 0x177300, v198
	global_load_dwordx4 v[200:203], v199, s[26:27]
	v_add_u32_e32 v199, 0x176100, v198
	global_load_dwordx4 v[204:207], v199, s[26:27]
	s_mov_b32 s100, 0xbfb8aa3b
	v_lshlrev_b32_e32 v242, 16, v38
	v_and_b32_e32 v243, 0xffff0000, v38
	v_lshlrev_b32_e32 v244, 16, v40
	v_and_b32_e32 v245, 0xffff0000, v40
	v_lshlrev_b32_e32 v246, 16, v39
	v_and_b32_e32 v247, 0xffff0000, v39
	v_lshlrev_b32_e32 v248, 16, v41
	v_and_b32_e32 v249, 0xffff0000, v41
	v_pk_mul_f32 v[242:243], v[242:243], s[100:101] op_sel_hi:[1,0]
	v_pk_mul_f32 v[244:245], v[244:245], s[100:101] op_sel_hi:[1,0]
	v_pk_mul_f32 v[246:247], v[246:247], s[100:101] op_sel_hi:[1,0]
	v_pk_mul_f32 v[248:249], v[248:249], s[100:101] op_sel_hi:[1,0]
	v_exp_f32_e32 v242, v242
	v_exp_f32_e32 v243, v243
	v_exp_f32_e32 v244, v244
	v_exp_f32_e32 v245, v245
	v_exp_f32_e32 v246, v246
	v_exp_f32_e32 v247, v247
	v_exp_f32_e32 v248, v248
	v_exp_f32_e32 v249, v249
	s_nop 0
	v_pk_add_f32 v[242:243], v[242:243], 1.0 op_sel_hi:[1,0]
	v_pk_add_f32 v[244:245], v[244:245], 1.0 op_sel_hi:[1,0]
	v_pk_add_f32 v[246:247], v[246:247], 1.0 op_sel_hi:[1,0]
	v_pk_add_f32 v[248:249], v[248:249], 1.0 op_sel_hi:[1,0]
	v_rcp_f32_e32 v250, v242
	v_rcp_f32_e32 v251, v243
	s_nop 0
	v_pk_fma_f32 v[252:253], v[242:243], v[250:251], 1.0 op_sel_hi:[1,1,0] neg_lo:[1,0,0] neg_hi:[1,0,0]
	v_pk_fma_f32 v[250:251], v[252:253], v[250:251], v[250:251]
	v_pk_fma_f32 v[252:253], v[242:243], v[250:251], 1.0 op_sel_hi:[1,1,0] neg_lo:[1,0,0] neg_hi:[1,0,0]
	v_pk_fma_f32 v[254:255], v[252:253], v[250:251], v[250:251]
	v_pk_fma_f32 v[252:253], v[242:243], v[254:255], 1.0 op_sel_hi:[1,1,0] neg_lo:[1,0,0] neg_hi:[1,0,0]
	v_pk_fma_f32 v[254:255], v[252:253], v[250:251], v[254:255]
	v_div_fixup_f32 v242, v254, v242, 1.0
	v_div_fixup_f32 v243, v255, v243, 1.0
	v_rcp_f32_e32 v250, v244
	v_rcp_f32_e32 v251, v245
	s_nop 0
	v_pk_fma_f32 v[252:253], v[244:245], v[250:251], 1.0 op_sel_hi:[1,1,0] neg_lo:[1,0,0] neg_hi:[1,0,0]
	v_pk_fma_f32 v[250:251], v[252:253], v[250:251], v[250:251]
	v_pk_fma_f32 v[252:253], v[244:245], v[250:251], 1.0 op_sel_hi:[1,1,0] neg_lo:[1,0,0] neg_hi:[1,0,0]
	v_pk_fma_f32 v[254:255], v[252:253], v[250:251], v[250:251]
	v_pk_fma_f32 v[252:253], v[244:245], v[254:255], 1.0 op_sel_hi:[1,1,0] neg_lo:[1,0,0] neg_hi:[1,0,0]
	v_pk_fma_f32 v[254:255], v[252:253], v[250:251], v[254:255]
	v_div_fixup_f32 v244, v254, v244, 1.0
	v_div_fixup_f32 v245, v255, v245, 1.0
	v_rcp_f32_e32 v250, v246
	v_rcp_f32_e32 v251, v247
	s_nop 0
	v_pk_fma_f32 v[252:253], v[246:247], v[250:251], 1.0 op_sel_hi:[1,1,0] neg_lo:[1,0,0] neg_hi:[1,0,0]
	v_pk_fma_f32 v[250:251], v[252:253], v[250:251], v[250:251]
	v_pk_fma_f32 v[252:253], v[246:247], v[250:251], 1.0 op_sel_hi:[1,1,0] neg_lo:[1,0,0] neg_hi:[1,0,0]
	v_pk_fma_f32 v[254:255], v[252:253], v[250:251], v[250:251]
	v_pk_fma_f32 v[252:253], v[246:247], v[254:255], 1.0 op_sel_hi:[1,1,0] neg_lo:[1,0,0] neg_hi:[1,0,0]
	v_pk_fma_f32 v[254:255], v[252:253], v[250:251], v[254:255]
	v_div_fixup_f32 v246, v254, v246, 1.0
	v_div_fixup_f32 v247, v255, v247, 1.0
	v_rcp_f32_e32 v250, v248
	v_rcp_f32_e32 v251, v249
	s_nop 0
	v_pk_fma_f32 v[252:253], v[248:249], v[250:251], 1.0 op_sel_hi:[1,1,0] neg_lo:[1,0,0] neg_hi:[1,0,0]
	v_pk_fma_f32 v[250:251], v[252:253], v[250:251], v[250:251]
	v_pk_fma_f32 v[252:253], v[248:249], v[250:251], 1.0 op_sel_hi:[1,1,0] neg_lo:[1,0,0] neg_hi:[1,0,0]
	v_pk_fma_f32 v[254:255], v[252:253], v[250:251], v[250:251]
	v_pk_fma_f32 v[252:253], v[248:249], v[254:255], 1.0 op_sel_hi:[1,1,0] neg_lo:[1,0,0] neg_hi:[1,0,0]
	v_pk_fma_f32 v[254:255], v[252:253], v[250:251], v[254:255]
	v_div_fixup_f32 v248, v254, v248, 1.0
	v_div_fixup_f32 v249, v255, v249, 1.0
	v_lshlrev_b32_e32 v50, 16, v42
	v_and_b32_e32 v51, 0xffff0000, v42
	v_lshlrev_b32_e32 v52, 16, v44
	v_and_b32_e32 v53, 0xffff0000, v44
	v_lshlrev_b32_e32 v44, 16, v45
	v_and_b32_e32 v45, 0xffff0000, v45
	v_lshlrev_b32_e32 v42, 16, v43
	v_and_b32_e32 v43, 0xffff0000, v43
	v_pk_fma_f32 v[28:29], v[28:29], v[242:243], v[50:51]
	v_pk_fma_f32 v[38:39], v[26:27], v[248:249], v[44:45]
	v_pk_fma_f32 v[26:27], v[24:25], v[244:245], v[52:53]
	v_add_lshl_u32 v40, v140, v34, 1
	v_pk_fma_f32 v[30:31], v[30:31], v[246:247], v[42:43]
	v_cvt_pk_bf16_f32 v24, v28, v29
	s_nop 0
	v_cvt_pk_bf16_f32 v25, v30, v31
	v_cvt_pk_bf16_f32 v26, v26, v27
	v_cvt_pk_bf16_f32 v27, v38, v39
	buffer_store_dwordx4 v[24:27], v40, s[20:23], 0 offen sc1
	s_nop 0
	s_waitcnt vmcnt(7)
; __device__ __forceinline__ u32x4 pack8(const f32x4 v0, const f32x4 v1) { u32x4 w; w.x = pk2(v0[0], v0[1]); w.y = pk2(v0[2], v0[3]); w.z = pk2(v1[0], v1[1]); w.w = pk2(v1[2], v1[3]); return w; }
; __device__ __forceinline__ void unpack8(const u32x4 w, f32x4& v0, f32x4& v1) { v0 = (f32x4){bflo(w.x), bfhi(w.x), bflo(w.y), bfhi(w.y)}; v1 = (f32x4){bflo(w.z), bfhi(w.z), bflo(w.w), bfhi(w.w)}; }
; __device__ __forceinline__ float sigmoidf_(float x) { return 1.0f / (1.0f + __expf(-x)); }
;     __device__ __forceinline__ void operator()(const f32x4 (&acc)[2][2][4][2], const Unit& u, int wr, int wc, int fr, int fq) const {
;     ...
;                 for (int bj = 0; bj < 2; ++bj) {
;                     const u32x4 gw = *(const u32x4*)(rowp + O_GA + bj * 128);
;                     f32x4 g0, g1; unpack8(gw, g0, g1);
;                     f32x4 v0, v1;
; #pragma unroll
;                     for (int j = 0; j < 4; ++j) { v0[j] = sigmoidf_(g0[j]) * acc[ai][bj][m][0][j]; v1[j] = sigmoidf_(g1[j]) * acc[ai][bj][m][1][j]; }
;                     const u32x4 mw = *(const u32x4*)(rowp + bj * 128); f32x4 m0, m1; unpack8(mw, m0, m1); v0 += m0; v1 += m1;
;                     __builtin_amdgcn_raw_buffer_store_b128(pack8(v0, v1), rsrc, (unsigned)(((size_t)row * DIN + col0 + bj * 128) * 2), 0, 16  ); }
	v_mov_b32_e32 v24, v208
	v_mov_b32_e32 v25, v209
	v_mov_b32_e32 v26, v210
	v_mov_b32_e32 v27, v211
	v_mov_b32_e32 v28, v212
	v_mov_b32_e32 v29, v213
	v_mov_b32_e32 v30, v214
	v_mov_b32_e32 v31, v215
	s_mov_b32 s100, 0xbfb8aa3b
	v_lshlrev_b32_e32 v242, 16, v26
	v_and_b32_e32 v243, 0xffff0000, v26
	v_lshlrev_b32_e32 v244, 16, v24
	v_and_b32_e32 v245, 0xffff0000, v24
	v_lshlrev_b32_e32 v246, 16, v25
	v_and_b32_e32 v247, 0xffff0000, v25
	v_lshlrev_b32_e32 v248, 16, v27
	v_and_b32_e32 v249, 0xffff0000, v27
	v_pk_mul_f32 v[242:243], v[242:243], s[100:101] op_sel_hi:[1,0]
	v_pk_mul_f32 v[244:245], v[244:245], s[100:101] op_sel_hi:[1,0]
	v_pk_mul_f32 v[246:247], v[246:247], s[100:101] op_sel_hi:[1,0]
	v_pk_mul_f32 v[248:249], v[248:249], s[100:101] op_sel_hi:[1,0]
	v_exp_f32_e32 v242, v242
	v_exp_f32_e32 v243, v243
	v_exp_f32_e32 v244, v244
	v_exp_f32_e32 v245, v245
	v_exp_f32_e32 v246, v246
	v_exp_f32_e32 v247, v247
	v_exp_f32_e32 v248, v248
	v_exp_f32_e32 v249, v249
	s_nop 0
	v_pk_add_f32 v[242:243], v[242:243], 1.0 op_sel_hi:[1,0]
	v_pk_add_f32 v[244:245], v[244:245], 1.0 op_sel_hi:[1,0]
	v_pk_add_f32 v[246:247], v[246:247], 1.0 op_sel_hi:[1,0]
	v_pk_add_f32 v[248:249], v[248:249], 1.0 op_sel_hi:[1,0]
	v_rcp_f32_e32 v250, v242
	v_rcp_f32_e32 v251, v243
	s_nop 0
	v_pk_fma_f32 v[252:253], v[242:243], v[250:251], 1.0 op_sel_hi:[1,1,0] neg_lo:[1,0,0] neg_hi:[1,0,0]
	v_pk_fma_f32 v[250:251], v[252:253], v[250:251], v[250:251]
	v_pk_fma_f32 v[252:253], v[242:243], v[250:251], 1.0 op_sel_hi:[1,1,0] neg_lo:[1,0,0] neg_hi:[1,0,0]
	v_pk_fma_f32 v[254:255], v[252:253], v[250:251], v[250:251]
	v_pk_fma_f32 v[252:253], v[242:243], v[254:255], 1.0 op_sel_hi:[1,1,0] neg_lo:[1,0,0] neg_hi:[1,0,0]
	v_pk_fma_f32 v[254:255], v[252:253], v[250:251], v[254:255]
	v_div_fixup_f32 v242, v254, v242, 1.0
	v_div_fixup_f32 v243, v255, v243, 1.0
	v_rcp_f32_e32 v250, v244
	v_rcp_f32_e32 v251, v245
	s_nop 0
	v_pk_fma_f32 v[252:253], v[244:245], v[250:251], 1.0 op_sel_hi:[1,1,0] neg_lo:[1,0,0] neg_hi:[1,0,0]
	v_pk_fma_f32 v[250:251], v[252:253], v[250:251], v[250:251]
	v_pk_fma_f32 v[252:253], v[244:245], v[250:251], 1.0 op_sel_hi:[1,1,0] neg_lo:[1,0,0] neg_hi:[1,0,0]
	v_pk_fma_f32 v[254:255], v[252:253], v[250:251], v[250:251]
	v_pk_fma_f32 v[252:253], v[244:245], v[254:255], 1.0 op_sel_hi:[1,1,0] neg_lo:[1,0,0] neg_hi:[1,0,0]
	v_pk_fma_f32 v[254:255], v[252:253], v[250:251], v[254:255]
	v_div_fixup_f32 v244, v254, v244, 1.0
	v_div_fixup_f32 v245, v255, v245, 1.0
	v_rcp_f32_e32 v250, v246
	v_rcp_f32_e32 v251, v247
	s_nop 0
	v_pk_fma_f32 v[252:253], v[246:247], v[250:251], 1.0 op_sel_hi:[1,1,0] neg_lo:[1,0,0] neg_hi:[1,0,0]
	v_pk_fma_f32 v[250:251], v[252:253], v[250:251], v[250:251]
	v_pk_fma_f32 v[252:253], v[246:247], v[250:251], 1.0 op_sel_hi:[1,1,0] neg_lo:[1,0,0] neg_hi:[1,0,0]
	v_pk_fma_f32 v[254:255], v[252:253], v[250:251], v[250:251]
	v_pk_fma_f32 v[252:253], v[246:247], v[254:255], 1.0 op_sel_hi:[1,1,0] neg_lo:[1,0,0] neg_hi:[1,0,0]
	v_pk_fma_f32 v[254:255], v[252:253], v[250:251], v[254:255]
	v_div_fixup_f32 v246, v254, v246, 1.0
	v_div_fixup_f32 v247, v255, v247, 1.0
	v_rcp_f32_e32 v250, v248
	v_rcp_f32_e32 v251, v249
	s_nop 0
	v_pk_fma_f32 v[252:253], v[248:249], v[250:251], 1.0 op_sel_hi:[1,1,0] neg_lo:[1,0,0] neg_hi:[1,0,0]
	v_pk_fma_f32 v[250:251], v[252:253], v[250:251], v[250:251]
	v_pk_fma_f32 v[252:253], v[248:249], v[250:251], 1.0 op_sel_hi:[1,1,0] neg_lo:[1,0,0] neg_hi:[1,0,0]
	v_pk_fma_f32 v[254:255], v[252:253], v[250:251], v[250:251]
	v_pk_fma_f32 v[252:253], v[248:249], v[254:255], 1.0 op_sel_hi:[1,1,0] neg_lo:[1,0,0] neg_hi:[1,0,0]
	v_pk_fma_f32 v[254:255], v[252:253], v[250:251], v[254:255]
	v_div_fixup_f32 v248, v254, v248, 1.0
	v_div_fixup_f32 v249, v255, v249, 1.0
	v_lshlrev_b32_e32 v36, 16, v28
	v_and_b32_e32 v37, 0xffff0000, v28
	v_lshlrev_b32_e32 v38, 16, v30
	v_and_b32_e32 v39, 0xffff0000, v30
	v_lshlrev_b32_e32 v30, 16, v31
	v_and_b32_e32 v31, 0xffff0000, v31
	v_lshlrev_b32_e32 v28, 16, v29
	v_and_b32_e32 v29, 0xffff0000, v29
	v_pk_fma_f32 v[20:21], v[20:21], v[244:245], v[36:37]
	v_pk_fma_f32 v[24:25], v[18:19], v[248:249], v[30:31]
	v_pk_fma_f32 v[18:19], v[16:17], v[242:243], v[38:39]
	v_cvt_pk_bf16_f32 v16, v20, v21
	v_pk_fma_f32 v[22:23], v[22:23], v[246:247], v[28:29]
	s_nop 0
	v_cvt_pk_bf16_f32 v17, v22, v23
	v_cvt_pk_bf16_f32 v18, v18, v19
	v_cvt_pk_bf16_f32 v19, v24, v25
	buffer_store_dwordx4 v[16:19], v40, s[20:23], 0 offen offset:256 sc1
	s_nop 1
	v_add_u32_e32 v16, 0x40b0, v158
	v_mad_i64_i32 v[18:19], s[6:7], v16, s77, 0
	v_lshl_add_u64 v[16:17], v[18:19], 1, s[26:27]
	v_lshl_add_u64 v[16:17], v[16:17], 0, v[142:143]
	v_add_co_u32_e32 v20, vcc, s78, v16
	s_nop 1
	v_addc_co_u32_e32 v21, vcc, 0, v17, vcc
	s_waitcnt vmcnt(5)
; __device__ __forceinline__ u32x4 pack8(const f32x4 v0, const f32x4 v1) { u32x4 w; w.x = pk2(v0[0], v0[1]); w.y = pk2(v0[2], v0[3]); w.z = pk2(v1[0], v1[1]); w.w = pk2(v1[2], v1[3]); return w; }
; __device__ __forceinline__ void unpack8(const u32x4 w, f32x4& v0, f32x4& v1) { v0 = (f32x4){bflo(w.x), bfhi(w.x), bflo(w.y), bfhi(w.y)}; v1 = (f32x4){bflo(w.z), bfhi(w.z), bflo(w.w), bfhi(w.w)}; }
; __device__ __forceinline__ float sigmoidf_(float x) { return 1.0f / (1.0f + __expf(-x)); }
;     __device__ __forceinline__ void operator()(const f32x4 (&acc)[2][2][4][2], const Unit& u, int wr, int wc, int fr, int fq) const {
;     ...
;                 for (int bj = 0; bj < 2; ++bj) {
;                     const u32x4 gw = *(const u32x4*)(rowp + O_GA + bj * 128);
;                     f32x4 g0, g1; unpack8(gw, g0, g1);
;                     f32x4 v0, v1;
; #pragma unroll
;                     for (int j = 0; j < 4; ++j) { v0[j] = sigmoidf_(g0[j]) * acc[ai][bj][m][0][j]; v1[j] = sigmoidf_(g1[j]) * acc[ai][bj][m][1][j]; }
;                     const u32x4 mw = *(const u32x4*)(rowp + bj * 128); f32x4 m0, m1; unpack8(mw, m0, m1); v0 += m0; v1 += m1;
;                     __builtin_amdgcn_raw_buffer_store_b128(pack8(v0, v1), rsrc, (unsigned)(((size_t)row * DIN + col0 + bj * 128) * 2), 0, 16  ); }
	v_mov_b32_e32 v22, v232
	v_mov_b32_e32 v23, v233
	v_mov_b32_e32 v24, v234
	v_mov_b32_e32 v25, v235
	v_mov_b32_e32 v26, v236
	v_mov_b32_e32 v27, v237
	v_mov_b32_e32 v28, v238
	v_mov_b32_e32 v29, v239
	s_mov_b32 s100, 0xbfb8aa3b
	v_lshlrev_b32_e32 v242, 16, v22
	v_and_b32_e32 v243, 0xffff0000, v22
	v_lshlrev_b32_e32 v244, 16, v24
	v_and_b32_e32 v245, 0xffff0000, v24
	v_lshlrev_b32_e32 v246, 16, v23
	v_and_b32_e32 v247, 0xffff0000, v23
	v_lshlrev_b32_e32 v248, 16, v25
	v_and_b32_e32 v249, 0xffff0000, v25
	v_pk_mul_f32 v[242:243], v[242:243], s[100:101] op_sel_hi:[1,0]
	v_pk_mul_f32 v[244:245], v[244:245], s[100:101] op_sel_hi:[1,0]
	v_pk_mul_f32 v[246:247], v[246:247], s[100:101] op_sel_hi:[1,0]
	v_pk_mul_f32 v[248:249], v[248:249], s[100:101] op_sel_hi:[1,0]
	v_exp_f32_e32 v242, v242
	v_exp_f32_e32 v243, v243
	v_exp_f32_e32 v244, v244
	v_exp_f32_e32 v245, v245
	v_exp_f32_e32 v246, v246
	v_exp_f32_e32 v247, v247
	v_exp_f32_e32 v248, v248
	v_exp_f32_e32 v249, v249
	s_nop 0
	v_pk_add_f32 v[242:243], v[242:243], 1.0 op_sel_hi:[1,0]
	v_pk_add_f32 v[244:245], v[244:245], 1.0 op_sel_hi:[1,0]
	v_pk_add_f32 v[246:247], v[246:247], 1.0 op_sel_hi:[1,0]
	v_pk_add_f32 v[248:249], v[248:249], 1.0 op_sel_hi:[1,0]
	v_rcp_f32_e32 v250, v242
	v_rcp_f32_e32 v251, v243
	s_nop 0
	v_pk_fma_f32 v[252:253], v[242:243], v[250:251], 1.0 op_sel_hi:[1,1,0] neg_lo:[1,0,0] neg_hi:[1,0,0]
	v_pk_fma_f32 v[250:251], v[252:253], v[250:251], v[250:251]
	v_pk_fma_f32 v[252:253], v[242:243], v[250:251], 1.0 op_sel_hi:[1,1,0] neg_lo:[1,0,0] neg_hi:[1,0,0]
	v_pk_fma_f32 v[254:255], v[252:253], v[250:251], v[250:251]
	v_pk_fma_f32 v[252:253], v[242:243], v[254:255], 1.0 op_sel_hi:[1,1,0] neg_lo:[1,0,0] neg_hi:[1,0,0]
	v_pk_fma_f32 v[254:255], v[252:253], v[250:251], v[254:255]
	v_div_fixup_f32 v242, v254, v242, 1.0
	v_div_fixup_f32 v243, v255, v243, 1.0
	v_rcp_f32_e32 v250, v244
	v_rcp_f32_e32 v251, v245
	s_nop 0
	v_pk_fma_f32 v[252:253], v[244:245], v[250:251], 1.0 op_sel_hi:[1,1,0] neg_lo:[1,0,0] neg_hi:[1,0,0]
	v_pk_fma_f32 v[250:251], v[252:253], v[250:251], v[250:251]
	v_pk_fma_f32 v[252:253], v[244:245], v[250:251], 1.0 op_sel_hi:[1,1,0] neg_lo:[1,0,0] neg_hi:[1,0,0]
	v_pk_fma_f32 v[254:255], v[252:253], v[250:251], v[250:251]
	v_pk_fma_f32 v[252:253], v[244:245], v[254:255], 1.0 op_sel_hi:[1,1,0] neg_lo:[1,0,0] neg_hi:[1,0,0]
	v_pk_fma_f32 v[254:255], v[252:253], v[250:251], v[254:255]
	v_div_fixup_f32 v244, v254, v244, 1.0
	v_div_fixup_f32 v245, v255, v245, 1.0
	v_rcp_f32_e32 v250, v246
	v_rcp_f32_e32 v251, v247
	s_nop 0
	v_pk_fma_f32 v[252:253], v[246:247], v[250:251], 1.0 op_sel_hi:[1,1,0] neg_lo:[1,0,0] neg_hi:[1,0,0]
	v_pk_fma_f32 v[250:251], v[252:253], v[250:251], v[250:251]
	v_pk_fma_f32 v[252:253], v[246:247], v[250:251], 1.0 op_sel_hi:[1,1,0] neg_lo:[1,0,0] neg_hi:[1,0,0]
	v_pk_fma_f32 v[254:255], v[252:253], v[250:251], v[250:251]
	v_pk_fma_f32 v[252:253], v[246:247], v[254:255], 1.0 op_sel_hi:[1,1,0] neg_lo:[1,0,0] neg_hi:[1,0,0]
	v_pk_fma_f32 v[254:255], v[252:253], v[250:251], v[254:255]
	v_div_fixup_f32 v246, v254, v246, 1.0
	v_div_fixup_f32 v247, v255, v247, 1.0
	v_rcp_f32_e32 v250, v248
	v_rcp_f32_e32 v251, v249
	s_nop 0
	v_pk_fma_f32 v[252:253], v[248:249], v[250:251], 1.0 op_sel_hi:[1,1,0] neg_lo:[1,0,0] neg_hi:[1,0,0]
	v_pk_fma_f32 v[250:251], v[252:253], v[250:251], v[250:251]
	v_pk_fma_f32 v[252:253], v[248:249], v[250:251], 1.0 op_sel_hi:[1,1,0] neg_lo:[1,0,0] neg_hi:[1,0,0]
	v_pk_fma_f32 v[254:255], v[252:253], v[250:251], v[250:251]
	v_pk_fma_f32 v[252:253], v[248:249], v[254:255], 1.0 op_sel_hi:[1,1,0] neg_lo:[1,0,0] neg_hi:[1,0,0]
	v_pk_fma_f32 v[254:255], v[252:253], v[250:251], v[254:255]
	v_div_fixup_f32 v248, v254, v248, 1.0
	v_div_fixup_f32 v249, v255, v249, 1.0
	v_lshlrev_b32_e32 v34, 16, v26
	v_and_b32_e32 v35, 0xffff0000, v26
	v_lshlrev_b32_e32 v36, 16, v28
	v_and_b32_e32 v37, 0xffff0000, v28
	v_lshlrev_b32_e32 v28, 16, v29
	v_and_b32_e32 v29, 0xffff0000, v29
	v_lshlrev_b32_e32 v26, 16, v27
	v_and_b32_e32 v27, 0xffff0000, v27
	v_pk_fma_f32 v[12:13], v[12:13], v[242:243], v[34:35]
	v_pk_fma_f32 v[22:23], v[10:11], v[248:249], v[28:29]
	v_pk_fma_f32 v[10:11], v[8:9], v[244:245], v[36:37]
	v_add_lshl_u32 v24, v140, v18, 1
	v_pk_fma_f32 v[14:15], v[14:15], v[246:247], v[26:27]
	v_cvt_pk_bf16_f32 v8, v12, v13
	s_nop 0
	v_cvt_pk_bf16_f32 v9, v14, v15
	v_cvt_pk_bf16_f32 v10, v10, v11
	v_cvt_pk_bf16_f32 v11, v22, v23
	buffer_store_dwordx4 v[8:11], v24, s[20:23], 0 offen sc1
	s_nop 0
	s_waitcnt vmcnt(3)
; __device__ __forceinline__ u32x4 pack8(const f32x4 v0, const f32x4 v1) { u32x4 w; w.x = pk2(v0[0], v0[1]); w.y = pk2(v0[2], v0[3]); w.z = pk2(v1[0], v1[1]); w.w = pk2(v1[2], v1[3]); return w; }
; __device__ __forceinline__ void unpack8(const u32x4 w, f32x4& v0, f32x4& v1) { v0 = (f32x4){bflo(w.x), bfhi(w.x), bflo(w.y), bfhi(w.y)}; v1 = (f32x4){bflo(w.z), bfhi(w.z), bflo(w.w), bfhi(w.w)}; }
; __device__ __forceinline__ float sigmoidf_(float x) { return 1.0f / (1.0f + __expf(-x)); }
;     __device__ __forceinline__ void operator()(const f32x4 (&acc)[2][2][4][2], const Unit& u, int wr, int wc, int fr, int fq) const {
;     ...
;                 for (int bj = 0; bj < 2; ++bj) {
;                     const u32x4 gw = *(const u32x4*)(rowp + O_GA + bj * 128);
;                     f32x4 g0, g1; unpack8(gw, g0, g1);
;                     f32x4 v0, v1;
; #pragma unroll
;                     for (int j = 0; j < 4; ++j) { v0[j] = sigmoidf_(g0[j]) * acc[ai][bj][m][0][j]; v1[j] = sigmoidf_(g1[j]) * acc[ai][bj][m][1][j]; }
;                     const u32x4 mw = *(const u32x4*)(rowp + bj * 128); f32x4 m0, m1; unpack8(mw, m0, m1); v0 += m0; v1 += m1;
;                     __builtin_amdgcn_raw_buffer_store_b128(pack8(v0, v1), rsrc, (unsigned)(((size_t)row * DIN + col0 + bj * 128) * 2), 0, 16  ); }
;             }
;         asm volatile("s_waitcnt vmcnt(0)" ::: "memory");
;         if (fr == 0 && fq == 0) (void)__hip_atomic_fetch_add(ready + 64 * (pm_off + u.pm), 1u, __ATOMIC_RELAXED, __HIP_MEMORY_SCOPE_AGENT);
	v_mov_b32_e32 v8, v200
	v_mov_b32_e32 v9, v201
	v_mov_b32_e32 v10, v202
	v_mov_b32_e32 v11, v203
	v_mov_b32_e32 v12, v204
	v_mov_b32_e32 v13, v205
	v_mov_b32_e32 v14, v206
	v_mov_b32_e32 v15, v207
	s_mov_b32 s100, 0xbfb8aa3b
	v_lshlrev_b32_e32 v242, 16, v10
	v_and_b32_e32 v243, 0xffff0000, v10
	v_lshlrev_b32_e32 v244, 16, v8
	v_and_b32_e32 v245, 0xffff0000, v8
	v_lshlrev_b32_e32 v246, 16, v9
	v_and_b32_e32 v247, 0xffff0000, v9
	v_lshlrev_b32_e32 v248, 16, v11
	v_and_b32_e32 v249, 0xffff0000, v11
	v_pk_mul_f32 v[242:243], v[242:243], s[100:101] op_sel_hi:[1,0]
	v_pk_mul_f32 v[244:245], v[244:245], s[100:101] op_sel_hi:[1,0]
	v_pk_mul_f32 v[246:247], v[246:247], s[100:101] op_sel_hi:[1,0]
	v_pk_mul_f32 v[248:249], v[248:249], s[100:101] op_sel_hi:[1,0]
	v_exp_f32_e32 v242, v242
	v_exp_f32_e32 v243, v243
	v_exp_f32_e32 v244, v244
	v_exp_f32_e32 v245, v245
	v_exp_f32_e32 v246, v246
	v_exp_f32_e32 v247, v247
	v_exp_f32_e32 v248, v248
	v_exp_f32_e32 v249, v249
	s_nop 0
	v_pk_add_f32 v[242:243], v[242:243], 1.0 op_sel_hi:[1,0]
	v_pk_add_f32 v[244:245], v[244:245], 1.0 op_sel_hi:[1,0]
	v_pk_add_f32 v[246:247], v[246:247], 1.0 op_sel_hi:[1,0]
	v_pk_add_f32 v[248:249], v[248:249], 1.0 op_sel_hi:[1,0]
	v_rcp_f32_e32 v250, v242
	v_rcp_f32_e32 v251, v243
	s_nop 0
	v_pk_fma_f32 v[252:253], v[242:243], v[250:251], 1.0 op_sel_hi:[1,1,0] neg_lo:[1,0,0] neg_hi:[1,0,0]
	v_pk_fma_f32 v[250:251], v[252:253], v[250:251], v[250:251]
	v_pk_fma_f32 v[252:253], v[242:243], v[250:251], 1.0 op_sel_hi:[1,1,0] neg_lo:[1,0,0] neg_hi:[1,0,0]
	v_pk_fma_f32 v[254:255], v[252:253], v[250:251], v[250:251]
	v_pk_fma_f32 v[252:253], v[242:243], v[254:255], 1.0 op_sel_hi:[1,1,0] neg_lo:[1,0,0] neg_hi:[1,0,0]
	v_pk_fma_f32 v[254:255], v[252:253], v[250:251], v[254:255]
	v_div_fixup_f32 v242, v254, v242, 1.0
	v_div_fixup_f32 v243, v255, v243, 1.0
	v_rcp_f32_e32 v250, v244
	v_rcp_f32_e32 v251, v245
	s_nop 0
	v_pk_fma_f32 v[252:253], v[244:245], v[250:251], 1.0 op_sel_hi:[1,1,0] neg_lo:[1,0,0] neg_hi:[1,0,0]
	v_pk_fma_f32 v[250:251], v[252:253], v[250:251], v[250:251]
	v_pk_fma_f32 v[252:253], v[244:245], v[250:251], 1.0 op_sel_hi:[1,1,0] neg_lo:[1,0,0] neg_hi:[1,0,0]
	v_pk_fma_f32 v[254:255], v[252:253], v[250:251], v[250:251]
	v_pk_fma_f32 v[252:253], v[244:245], v[254:255], 1.0 op_sel_hi:[1,1,0] neg_lo:[1,0,0] neg_hi:[1,0,0]
	v_pk_fma_f32 v[254:255], v[252:253], v[250:251], v[254:255]
	v_div_fixup_f32 v244, v254, v244, 1.0
	v_div_fixup_f32 v245, v255, v245, 1.0
	v_rcp_f32_e32 v250, v246
	v_rcp_f32_e32 v251, v247
	s_nop 0
	v_pk_fma_f32 v[252:253], v[246:247], v[250:251], 1.0 op_sel_hi:[1,1,0] neg_lo:[1,0,0] neg_hi:[1,0,0]
	v_pk_fma_f32 v[250:251], v[252:253], v[250:251], v[250:251]
	v_pk_fma_f32 v[252:253], v[246:247], v[250:251], 1.0 op_sel_hi:[1,1,0] neg_lo:[1,0,0] neg_hi:[1,0,0]
	v_pk_fma_f32 v[254:255], v[252:253], v[250:251], v[250:251]
	v_pk_fma_f32 v[252:253], v[246:247], v[254:255], 1.0 op_sel_hi:[1,1,0] neg_lo:[1,0,0] neg_hi:[1,0,0]
	v_pk_fma_f32 v[254:255], v[252:253], v[250:251], v[254:255]
	v_div_fixup_f32 v246, v254, v246, 1.0
	v_div_fixup_f32 v247, v255, v247, 1.0
	v_rcp_f32_e32 v250, v248
	v_rcp_f32_e32 v251, v249
	s_nop 0
	v_pk_fma_f32 v[252:253], v[248:249], v[250:251], 1.0 op_sel_hi:[1,1,0] neg_lo:[1,0,0] neg_hi:[1,0,0]
	v_pk_fma_f32 v[250:251], v[252:253], v[250:251], v[250:251]
	v_pk_fma_f32 v[252:253], v[248:249], v[250:251], 1.0 op_sel_hi:[1,1,0] neg_lo:[1,0,0] neg_hi:[1,0,0]
	v_pk_fma_f32 v[254:255], v[252:253], v[250:251], v[250:251]
	v_pk_fma_f32 v[252:253], v[248:249], v[254:255], 1.0 op_sel_hi:[1,1,0] neg_lo:[1,0,0] neg_hi:[1,0,0]
	v_pk_fma_f32 v[254:255], v[252:253], v[250:251], v[254:255]
	v_div_fixup_f32 v248, v254, v248, 1.0
	v_div_fixup_f32 v249, v255, v249, 1.0
	v_lshlrev_b32_e32 v20, 16, v12
	v_and_b32_e32 v21, 0xffff0000, v12
	v_lshlrev_b32_e32 v22, 16, v14
	v_and_b32_e32 v23, 0xffff0000, v14
	v_lshlrev_b32_e32 v14, 16, v15
	v_and_b32_e32 v15, 0xffff0000, v15
	v_lshlrev_b32_e32 v12, 16, v13
	v_and_b32_e32 v13, 0xffff0000, v13
	v_pk_fma_f32 v[4:5], v[4:5], v[244:245], v[20:21]
	v_pk_fma_f32 v[8:9], v[2:3], v[248:249], v[14:15]
	v_pk_fma_f32 v[2:3], v[0:1], v[242:243], v[22:23]
	v_pk_fma_f32 v[6:7], v[6:7], v[246:247], v[12:13]
	v_cvt_pk_bf16_f32 v0, v4, v5
	s_nop 0
	v_cvt_pk_bf16_f32 v1, v6, v7
	v_cvt_pk_bf16_f32 v2, v2, v3
	v_cvt_pk_bf16_f32 v3, v8, v9
	buffer_store_dwordx4 v[0:3], v24, s[20:23], 0 offen offset:256 sc1
	s_waitcnt vmcnt(0)
	s_and_saveexec_b64 s[12:13], s[10:11]
	s_cbranch_execz .LBB0_715
	s_mov_b64 s[14:15], exec
	v_mbcnt_lo_u32_b32 v0, s14, 0
	v_mbcnt_hi_u32_b32 v0, s15, v0
	v_cmp_eq_u32_e32 vcc, 0, v0
	s_and_b64 s[6:7], exec, vcc
	s_mov_b64 exec, s[6:7]
	s_cbranch_execz .LBB0_715
	s_lshl_b32 s6, s79, 6
	s_addk_i32 s6, 0x1000
	s_ashr_i32 s7, s6, 31
	s_lshl_b64 s[6:7], s[6:7], 2
	s_add_u32 s6, s34, s6
	s_addc_u32 s7, s35, s7
	s_bcnt1_i32_b64 s8, s[14:15]
	v_mov_b32_e32 v0, s8
	global_atomic_add v131, v0, s[6:7]
	s_branch .LBB0_715

; #define PG8_STAGE(bufoff, gbase, voff) do { _Pragma("unroll") for (int _i = 0; _i < 2; ++_i) \
;         __builtin_amdgcn_global_load_lds((const unsigned*)((const char*)(gbase) + (voff)[_i]), (LAS unsigned*)(lds + (bufoff) + ldsw + _i * 8192), 16, 0, 0); } while (0)
; #define PG8_LDA(dst, b, h) do { _Pragma("unroll") for (int m = 0; m < 4; ++m) _Pragma("unroll") for (int k = 0; k < 2; ++k) dst[m][k] = *(const LAS bf16x8*)(lds + PG8_SA(b, h) + aoff + m * 2048 + k * 1024); } while (0)
; #define PG8_LDB(dst, b, h) do { _Pragma("unroll") for (int n = 0; n < 2; ++n) _Pragma("unroll") for (int k = 0; k < 2; ++k) dst[n][k] = *(const LAS bf16x8*)(lds + PG8_SB(b, h) + boff + n * 2048 + k * 1024); } while (0)
; #define PG8_MMA(ai, bj, At, Bt) do { __builtin_amdgcn_s_setprio(1); _Pragma("unroll") for (int m = 0; m < 4; ++m) _Pragma("unroll") for (int n = 0; n < 2; ++n) _Pragma("unroll") for (int k = 0; k < 2; ++k) \
;         acc[ai][bj][m][n] = __builtin_amdgcn_mfma_f32_16x16x32_bf16(Bt[n][k], At[m][k], acc[ai][bj][m][n], 0, 0, 0); __builtin_amdgcn_s_setprio(0); } while (0)
; #define PG8_WAIT_L(n) asm volatile("s_waitcnt lgkmcnt(" #n ")" ::: "memory")
; #define PG8_BAR __builtin_amdgcn_s_barrier()
; #define PG8_SCHED __builtin_amdgcn_sched_barrier(0)
;     ...
;             PG8_LDB(B0, 0, 0); PG8_SCHED; PG8_LDA(At, 0, 0); PG8_STAGE(PG8_SA(1, 1), a1 + hA, voffA);
;             PG8_WAIT_L(8); PG8_BAR; PG8_WAIT_L(0); PG8_MMA(0, 0, At, B0); PG8_BAR; PG8_SCHED;
;             PG8_LDB(B1, 0, 1); PG8_STAGE(PG8_SB(0, 0), b2, voffB);
;             PG8_BAR; PG8_WAIT_L(0); PG8_MMA(0, 1, At, B1); PG8_BAR;
;             PG8_LDA(At, 0, 1); PG8_STAGE(PG8_SA(0, 0), a2, voffA);
;             PG8_BAR; PG8_WAIT_L(0); PG8_MMA(1, 0, At, B0); PG8_BAR; PG8_SCHED;
.LBB0_1768:
	ds_read_b128 v[146:149], v157
	ds_read_b128 v[150:153], v157 offset:1024
	ds_read_b128 v[160:163], v157 offset:2048
	ds_read_b128 v[170:173], v157 offset:3072
	s_add_u32 s10, s12, 0x100
	s_addc_u32 s11, s13, 0
	s_cmp_eq_u32 s60, 4
	s_cselect_b32 s17, s29, s11
	s_cselect_b32 s16, s28, s10
	s_cselect_b32 s15, s27, s45
	s_cselect_b32 s14, s33, s44
	v_lshl_add_u64 v[164:165], s[12:13], 0, v[138:139]
	s_add_i32 m0, s37, 0xc000
	ds_read_b128 v[174:177], v158
	ds_read_b128 v[178:181], v158 offset:1024
	ds_read_b128 v[182:185], v158 offset:2048
	ds_read_b128 v[186:189], v158 offset:3072
	ds_read_b128 v[190:193], v158 offset:4096
	ds_read_b128 v[194:197], v158 offset:5120
	ds_read_b128 v[198:201], v158 offset:6144
	ds_read_b128 v[202:205], v158 offset:7168
	global_load_lds_dwordx4 v[164:165], off
	v_lshl_add_u64 v[164:165], s[12:13], 0, v[136:137]
	s_add_i32 m0, s37, 0xe000
	s_nop 0
	global_load_lds_dwordx4 v[164:165], off
	s_waitcnt lgkmcnt(8)
	s_barrier
	s_waitcnt lgkmcnt(0)
	s_setprio 1
	s_waitcnt lgkmcnt(0)
	v_mfma_f32_16x16x32_bf16 v[124:127], v[146:149], v[174:177], v[124:127]
	v_mfma_f32_16x16x32_bf16 v[120:123], v[160:163], v[174:177], v[120:123]
	v_mfma_f32_16x16x32_bf16 v[108:111], v[146:149], v[182:185], v[108:111]
	v_mfma_f32_16x16x32_bf16 v[104:107], v[160:163], v[182:185], v[104:107]
	v_mfma_f32_16x16x32_bf16 v[92:95], v[146:149], v[190:193], v[92:95]
	v_mfma_f32_16x16x32_bf16 v[88:91], v[160:163], v[190:193], v[88:91]
	v_mfma_f32_16x16x32_bf16 v[76:79], v[146:149], v[198:201], v[76:79]
	v_mfma_f32_16x16x32_bf16 v[72:75], v[160:163], v[198:201], v[72:75]
	v_mfma_f32_16x16x32_bf16 v[124:127], v[150:153], v[178:181], v[124:127]
	v_mfma_f32_16x16x32_bf16 v[120:123], v[170:173], v[178:181], v[120:123]
	v_mfma_f32_16x16x32_bf16 v[108:111], v[150:153], v[186:189], v[108:111]
	v_mfma_f32_16x16x32_bf16 v[104:107], v[170:173], v[186:189], v[104:107]
	v_mfma_f32_16x16x32_bf16 v[92:95], v[150:153], v[194:197], v[92:95]
	v_mfma_f32_16x16x32_bf16 v[88:91], v[170:173], v[194:197], v[88:91]
	v_mfma_f32_16x16x32_bf16 v[76:79], v[150:153], v[202:205], v[76:79]
	v_mfma_f32_16x16x32_bf16 v[72:75], v[170:173], v[202:205], v[72:75]
	s_setprio 0
	s_barrier
	s_add_i32 s12, s55, s35
	v_lshl_add_u64 v[164:165], s[14:15], 0, v[132:133]
	s_mov_b32 m0, s12
	ds_read_b128 v[206:209], v159
	ds_read_b128 v[210:213], v159 offset:1024
	ds_read_b128 v[214:217], v159 offset:2048
	ds_read_b128 v[218:221], v159 offset:3072
	global_load_lds_dwordx4 v[164:165], off
	v_lshl_add_u64 v[222:223], s[14:15], 0, v[128:129]
	s_add_i32 m0, s12, 0x2000
	s_nop 0
	global_load_lds_dwordx4 v[222:223], off
	s_barrier
	s_waitcnt lgkmcnt(0)
	s_setprio 1
	s_waitcnt lgkmcnt(0)
	v_mfma_f32_16x16x32_bf16 v[116:119], v[206:209], v[174:177], v[116:119]
	v_mfma_f32_16x16x32_bf16 v[112:115], v[214:217], v[174:177], v[112:115]
	v_mfma_f32_16x16x32_bf16 v[100:103], v[206:209], v[182:185], v[100:103]
	v_mfma_f32_16x16x32_bf16 v[96:99], v[214:217], v[182:185], v[96:99]
	v_mfma_f32_16x16x32_bf16 v[84:87], v[206:209], v[190:193], v[84:87]
	v_mfma_f32_16x16x32_bf16 v[80:83], v[214:217], v[190:193], v[80:83]
	v_mfma_f32_16x16x32_bf16 v[68:71], v[206:209], v[198:201], v[68:71]
	v_mfma_f32_16x16x32_bf16 v[64:67], v[214:217], v[198:201], v[64:67]
	v_mfma_f32_16x16x32_bf16 v[116:119], v[210:213], v[178:181], v[116:119]
	v_mfma_f32_16x16x32_bf16 v[112:115], v[218:221], v[178:181], v[112:115]
	v_mfma_f32_16x16x32_bf16 v[100:103], v[210:213], v[186:189], v[100:103]
	v_mfma_f32_16x16x32_bf16 v[96:99], v[218:221], v[186:189], v[96:99]
	v_mfma_f32_16x16x32_bf16 v[84:87], v[210:213], v[194:197], v[84:87]
	v_mfma_f32_16x16x32_bf16 v[80:83], v[218:221], v[194:197], v[80:83]
	v_mfma_f32_16x16x32_bf16 v[68:71], v[210:213], v[202:205], v[68:71]
	v_mfma_f32_16x16x32_bf16 v[64:67], v[218:221], v[202:205], v[64:67]
	s_setprio 0
	s_mov_b32 m0, s37
	v_lshl_add_u64 v[224:225], s[16:17], 0, v[134:135]
	s_barrier
	ds_read_b128 v[174:177], v158 offset:16384
	ds_read_b128 v[178:181], v158 offset:17408
	ds_read_b128 v[182:185], v158 offset:18432
	ds_read_b128 v[186:189], v158 offset:19456
	ds_read_b128 v[190:193], v158 offset:20480
	ds_read_b128 v[194:197], v158 offset:21504
	ds_read_b128 v[198:201], v158 offset:22528
	ds_read_b128 v[202:205], v158 offset:23552
	global_load_lds_dwordx4 v[224:225], off
	v_lshl_add_u64 v[226:227], s[16:17], 0, v[130:131]
	s_mov_b32 m0, s40
	s_nop 0
	global_load_lds_dwordx4 v[226:227], off
	s_barrier
	s_waitcnt lgkmcnt(0)
	s_setprio 1
	s_waitcnt lgkmcnt(0)
	v_mfma_f32_16x16x32_bf16 v[60:63], v[146:149], v[174:177], v[60:63]
	v_mfma_f32_16x16x32_bf16 v[56:59], v[160:163], v[174:177], v[56:59]
	v_mfma_f32_16x16x32_bf16 v[44:47], v[146:149], v[182:185], v[44:47]
	v_mfma_f32_16x16x32_bf16 v[40:43], v[160:163], v[182:185], v[40:43]
	v_mfma_f32_16x16x32_bf16 v[28:31], v[146:149], v[190:193], v[28:31]
	v_mfma_f32_16x16x32_bf16 v[24:27], v[160:163], v[190:193], v[24:27]
	v_mfma_f32_16x16x32_bf16 v[12:15], v[146:149], v[198:201], v[12:15]
	v_mfma_f32_16x16x32_bf16 v[8:11], v[160:163], v[198:201], v[8:11]
	v_mfma_f32_16x16x32_bf16 v[60:63], v[150:153], v[178:181], v[60:63]
	v_mfma_f32_16x16x32_bf16 v[56:59], v[170:173], v[178:181], v[56:59]
	v_mfma_f32_16x16x32_bf16 v[44:47], v[150:153], v[186:189], v[44:47]
	v_mfma_f32_16x16x32_bf16 v[40:43], v[170:173], v[186:189], v[40:43]
	v_mfma_f32_16x16x32_bf16 v[28:31], v[150:153], v[194:197], v[28:31]
	v_mfma_f32_16x16x32_bf16 v[24:27], v[170:173], v[194:197], v[24:27]
	v_mfma_f32_16x16x32_bf16 v[12:15], v[150:153], v[202:205], v[12:15]
	v_mfma_f32_16x16x32_bf16 v[8:11], v[170:173], v[202:205], v[8:11]
	s_setprio 0
	s_barrier
; #define PG8_STAGE(bufoff, gbase, voff) do { _Pragma("unroll") for (int _i = 0; _i < 2; ++_i) \
;         __builtin_amdgcn_global_load_lds((const unsigned*)((const char*)(gbase) + (voff)[_i]), (LAS unsigned*)(lds + (bufoff) + ldsw + _i * 8192), 16, 0, 0); } while (0)
; #define PG8_LDA(dst, b, h) do { _Pragma("unroll") for (int m = 0; m < 4; ++m) _Pragma("unroll") for (int k = 0; k < 2; ++k) dst[m][k] = *(const LAS bf16x8*)(lds + PG8_SA(b, h) + aoff + m * 2048 + k * 1024); } while (0)
; #define PG8_LDB(dst, b, h) do { _Pragma("unroll") for (int n = 0; n < 2; ++n) _Pragma("unroll") for (int k = 0; k < 2; ++k) dst[n][k] = *(const LAS bf16x8*)(lds + PG8_SB(b, h) + boff + n * 2048 + k * 1024); } while (0)
; #define PG8_MMA(ai, bj, At, Bt) do { __builtin_amdgcn_s_setprio(1); _Pragma("unroll") for (int m = 0; m < 4; ++m) _Pragma("unroll") for (int n = 0; n < 2; ++n) _Pragma("unroll") for (int k = 0; k < 2; ++k) \
;         acc[ai][bj][m][n] = __builtin_amdgcn_mfma_f32_16x16x32_bf16(Bt[n][k], At[m][k], acc[ai][bj][m][n], 0, 0, 0); __builtin_amdgcn_s_setprio(0); } while (0)
; #define PG8_WAIT_V(n) asm volatile("s_waitcnt vmcnt(" #n ")" ::: "memory")
; #define PG8_WAIT_L(n) asm volatile("s_waitcnt lgkmcnt(" #n ")" ::: "memory")
; #define PG8_BAR __builtin_amdgcn_s_barrier()
; #define PG8_SCHED __builtin_amdgcn_sched_barrier(0)
;     ...
;             PG8_STAGE(PG8_SB(0, 1), b2 + hB, voffB);
;             PG8_WAIT_V(6); PG8_BAR; PG8_MMA(1, 1, At, B1); PG8_BAR;
;             PG8_LDB(B0, 1, 0); PG8_SCHED; PG8_LDA(At, 1, 0); PG8_STAGE(PG8_SA(0, 1), a2 + hA, voffA);
;             PG8_WAIT_L(8); PG8_BAR; PG8_WAIT_L(0); PG8_MMA(0, 0, At, B0); PG8_BAR; PG8_SCHED;
;             PG8_LDB(B1, 1, 1); PG8_STAGE(PG8_SB(1, 0), b3, voffB);
;             PG8_BAR; PG8_WAIT_L(0); PG8_MMA(0, 1, At, B1); PG8_BAR;
;             PG8_LDA(At, 1, 1); PG8_STAGE(PG8_SA(1, 0), a3, voffA);
	s_add_u32 s12, s14, 0x20000
	s_addc_u32 s13, s15, 0
	s_add_i32 s61, s56, s35
	v_lshl_add_u64 v[146:147], s[12:13], 0, v[132:133]
	s_mov_b32 m0, s61
	s_nop 0
	global_load_lds_dwordx4 v[146:147], off
	v_lshl_add_u64 v[146:147], s[12:13], 0, v[128:129]
	s_add_i32 m0, s61, 0x2000
	s_nop 0
	global_load_lds_dwordx4 v[146:147], off
	s_waitcnt vmcnt(6)
	s_barrier
	s_setprio 1
	v_mfma_f32_16x16x32_bf16 v[52:55], v[206:209], v[174:177], v[52:55]
	v_mfma_f32_16x16x32_bf16 v[48:51], v[214:217], v[174:177], v[48:51]
	v_mfma_f32_16x16x32_bf16 v[36:39], v[206:209], v[182:185], v[36:39]
	v_mfma_f32_16x16x32_bf16 v[32:35], v[214:217], v[182:185], v[32:35]
	v_mfma_f32_16x16x32_bf16 v[20:23], v[206:209], v[190:193], v[20:23]
	v_mfma_f32_16x16x32_bf16 v[16:19], v[214:217], v[190:193], v[16:19]
	v_mfma_f32_16x16x32_bf16 v[4:7], v[206:209], v[198:201], v[4:7]
	v_mfma_f32_16x16x32_bf16 v[0:3], v[214:217], v[198:201], v[0:3]
	v_mfma_f32_16x16x32_bf16 v[52:55], v[210:213], v[178:181], v[52:55]
	v_mfma_f32_16x16x32_bf16 v[48:51], v[218:221], v[178:181], v[48:51]
	v_mfma_f32_16x16x32_bf16 v[36:39], v[210:213], v[186:189], v[36:39]
	v_mfma_f32_16x16x32_bf16 v[32:35], v[218:221], v[186:189], v[32:35]
	v_mfma_f32_16x16x32_bf16 v[20:23], v[210:213], v[194:197], v[20:23]
	v_mfma_f32_16x16x32_bf16 v[16:19], v[218:221], v[194:197], v[16:19]
	v_mfma_f32_16x16x32_bf16 v[4:7], v[210:213], v[202:205], v[4:7]
	v_mfma_f32_16x16x32_bf16 v[0:3], v[218:221], v[202:205], v[0:3]
	s_setprio 0
	s_add_i32 s61, 0, 0x18000
	v_add_u32_e32 v169, s61, v155
	s_barrier
	ds_read_b128 v[146:149], v169
	ds_read_b128 v[150:153], v169 offset:1024
	ds_read_b128 v[160:163], v169 offset:2048
	ds_read_b128 v[170:173], v169 offset:3072
	s_add_u32 s12, s16, 0x110000
	s_addc_u32 s13, s17, 0
	s_mov_b32 m0, s41
	v_lshl_add_u64 v[206:207], s[12:13], 0, v[134:135]
	ds_read_b128 v[174:177], v158 offset:32768
	ds_read_b128 v[178:181], v158 offset:33792
	ds_read_b128 v[182:185], v158 offset:34816
	ds_read_b128 v[186:189], v158 offset:35840
	ds_read_b128 v[190:193], v158 offset:36864
	ds_read_b128 v[194:197], v158 offset:37888
	ds_read_b128 v[198:201], v158 offset:38912
	ds_read_b128 v[202:205], v158 offset:39936
	global_load_lds_dwordx4 v[206:207], off
	v_lshl_add_u64 v[206:207], s[12:13], 0, v[130:131]
	s_mov_b32 m0, s42
	s_nop 0
	global_load_lds_dwordx4 v[206:207], off
	s_waitcnt lgkmcnt(8)
	s_barrier
	s_waitcnt lgkmcnt(0)
	s_setprio 1
	s_waitcnt lgkmcnt(0)
	v_mfma_f32_16x16x32_bf16 v[124:127], v[146:149], v[174:177], v[124:127]
	v_mfma_f32_16x16x32_bf16 v[120:123], v[160:163], v[174:177], v[120:123]
	v_mfma_f32_16x16x32_bf16 v[108:111], v[146:149], v[182:185], v[108:111]
	v_mfma_f32_16x16x32_bf16 v[104:107], v[160:163], v[182:185], v[104:107]
	v_mfma_f32_16x16x32_bf16 v[92:95], v[146:149], v[190:193], v[92:95]
	v_mfma_f32_16x16x32_bf16 v[88:91], v[160:163], v[190:193], v[88:91]
	v_mfma_f32_16x16x32_bf16 v[76:79], v[146:149], v[198:201], v[76:79]
	v_mfma_f32_16x16x32_bf16 v[72:75], v[160:163], v[198:201], v[72:75]
	v_mfma_f32_16x16x32_bf16 v[124:127], v[150:153], v[178:181], v[124:127]
	v_mfma_f32_16x16x32_bf16 v[120:123], v[170:173], v[178:181], v[120:123]
	v_mfma_f32_16x16x32_bf16 v[108:111], v[150:153], v[186:189], v[108:111]
	v_mfma_f32_16x16x32_bf16 v[104:107], v[170:173], v[186:189], v[104:107]
	v_mfma_f32_16x16x32_bf16 v[92:95], v[150:153], v[194:197], v[92:95]
	v_mfma_f32_16x16x32_bf16 v[88:91], v[170:173], v[194:197], v[88:91]
	v_mfma_f32_16x16x32_bf16 v[76:79], v[150:153], v[202:205], v[76:79]
	v_mfma_f32_16x16x32_bf16 v[72:75], v[170:173], v[202:205], v[72:75]
	s_setprio 0
	s_barrier
	s_add_i32 s16, 0, 0x1c000
	s_add_i32 s12, s61, s35
	v_add_u32_e32 v169, s16, v155
	v_lshl_add_u64 v[164:165], v[164:165], 0, s[24:25]
	s_mov_b32 m0, s12
	ds_read_b128 v[206:209], v169
	ds_read_b128 v[210:213], v169 offset:1024
	ds_read_b128 v[214:217], v169 offset:2048
	ds_read_b128 v[218:221], v169 offset:3072
	global_load_lds_dwordx4 v[164:165], off
	v_lshl_add_u64 v[164:165], v[222:223], 0, s[24:25]
	s_add_i32 m0, s12, 0x2000
	s_nop 0
	global_load_lds_dwordx4 v[164:165], off
	s_barrier
	s_waitcnt lgkmcnt(0)
	s_setprio 1
	s_waitcnt lgkmcnt(0)
	v_mfma_f32_16x16x32_bf16 v[116:119], v[206:209], v[174:177], v[116:119]
	v_mfma_f32_16x16x32_bf16 v[112:115], v[214:217], v[174:177], v[112:115]
	v_mfma_f32_16x16x32_bf16 v[100:103], v[206:209], v[182:185], v[100:103]
	v_mfma_f32_16x16x32_bf16 v[96:99], v[214:217], v[182:185], v[96:99]
	v_mfma_f32_16x16x32_bf16 v[84:87], v[206:209], v[190:193], v[84:87]
	v_mfma_f32_16x16x32_bf16 v[80:83], v[214:217], v[190:193], v[80:83]
	v_mfma_f32_16x16x32_bf16 v[68:71], v[206:209], v[198:201], v[68:71]
	v_mfma_f32_16x16x32_bf16 v[64:67], v[214:217], v[198:201], v[64:67]
	v_mfma_f32_16x16x32_bf16 v[116:119], v[210:213], v[178:181], v[116:119]
	v_mfma_f32_16x16x32_bf16 v[112:115], v[218:221], v[178:181], v[112:115]
	v_mfma_f32_16x16x32_bf16 v[100:103], v[210:213], v[186:189], v[100:103]
	v_mfma_f32_16x16x32_bf16 v[96:99], v[218:221], v[186:189], v[96:99]
	v_mfma_f32_16x16x32_bf16 v[84:87], v[210:213], v[194:197], v[84:87]
	v_mfma_f32_16x16x32_bf16 v[80:83], v[218:221], v[194:197], v[80:83]
	v_mfma_f32_16x16x32_bf16 v[68:71], v[210:213], v[202:205], v[68:71]
	v_mfma_f32_16x16x32_bf16 v[64:67], v[218:221], v[202:205], v[64:67]
	s_setprio 0
	s_mov_b32 m0, s52
	v_lshl_add_u64 v[164:165], v[224:225], 0, s[24:25]
	s_barrier
	ds_read_b128 v[174:177], v158 offset:49152
	ds_read_b128 v[178:181], v158 offset:50176
	ds_read_b128 v[182:185], v158 offset:51200
	ds_read_b128 v[186:189], v158 offset:52224
	ds_read_b128 v[190:193], v158 offset:53248
	ds_read_b128 v[194:197], v158 offset:54272
	ds_read_b128 v[198:201], v158 offset:55296
	ds_read_b128 v[202:205], v158 offset:56320
	global_load_lds_dwordx4 v[164:165], off
	v_lshl_add_u64 v[164:165], v[226:227], 0, s[24:25]
	s_mov_b32 m0, s53
	s_nop 0
	global_load_lds_dwordx4 v[164:165], off
	s_barrier
; __device__ __forceinline__ float sigmoidf_(float x) { return 1.0f / (1.0f + __expf(-x)); }
; #define PG8_STAGE(bufoff, gbase, voff) do { _Pragma("unroll") for (int _i = 0; _i < 2; ++_i) \
;         __builtin_amdgcn_global_load_lds((const unsigned*)((const char*)(gbase) + (voff)[_i]), (LAS unsigned*)(lds + (bufoff) + ldsw + _i * 8192), 16, 0, 0); } while (0)
; #define PG8_MMA(ai, bj, At, Bt) do { __builtin_amdgcn_s_setprio(1); _Pragma("unroll") for (int m = 0; m < 4; ++m) _Pragma("unroll") for (int n = 0; n < 2; ++n) _Pragma("unroll") for (int k = 0; k < 2; ++k) \
;         acc[ai][bj][m][n] = __builtin_amdgcn_mfma_f32_16x16x32_bf16(Bt[n][k], At[m][k], acc[ai][bj][m][n], 0, 0, 0); __builtin_amdgcn_s_setprio(0); } while (0)
; #define PG8_WAIT_V(n) asm volatile("s_waitcnt vmcnt(" #n ")" ::: "memory")
; #define PG8_WAIT_L(n) asm volatile("s_waitcnt lgkmcnt(" #n ")" ::: "memory")
; #define PG8_BAR __builtin_amdgcn_s_barrier()
; #define PG8_SCHED __builtin_amdgcn_sched_barrier(0)
;     ...
;             PG8_BAR; PG8_WAIT_L(0); PG8_MMA(1, 0, At, B0); PG8_BAR; PG8_SCHED;
;             PG8_STAGE(PG8_SB(1, 1), b3 + hB, voffB);
;             PG8_WAIT_V(6); PG8_BAR; PG8_MMA(1, 1, At, B1); PG8_BAR;
;     __device__ __forceinline__ void operator()(const f32x4 (&acc)[2][2][4][2], const Unit& u, int wr, int wc, int fr, int fq) const {
;         const int row0 = u.pm * 256 + wr * 64 + fr, col0 = u.pn * 256 + wc * 32 + 8 * fq;
; #pragma unroll
;         for (int ai = 0; ai < 2; ++ai)
; #pragma unroll
;             for (int m = 0; m < 4; ++m) {
;                 bf16_t* rowp = z + (size_t)(row0 + ai * 128 + m * 16) * DIN + col0;
; #pragma unroll
;                 for (int bj = 0; bj < 2; ++bj) {
;                     const u32x4 gw = *(const u32x4*)(rowp + (MODE == 0 ? O_GB : O_GA) + bj * 128);
;                     f32x4 g0, g1; unpack8(gw, g0, g1);
;                     f32x4 v0, v1;
; #pragma unroll
;                     for (int j = 0; j < 4; ++j) { v0[j] = sigmoidf_(g0[j]) * acc[ai][bj][m][0][j]; v1[j] = sigmoidf_(g1[j]) * acc[ai][bj][m][1][j]; }
;                     if (MODE == 1) { const u32x4 mw = *(const u32x4*)(rowp + bj * 128); f32x4 m0, m1; unpack8(mw, m0, m1); v0 += m0; v1 += m1; }
;                     *(u32x4*)(rowp + bj * 128) = pack8(v0, v1); }
	s_waitcnt lgkmcnt(0)
	s_setprio 1
	s_waitcnt lgkmcnt(0)
	v_mfma_f32_16x16x32_bf16 v[60:63], v[146:149], v[174:177], v[60:63]
	v_mfma_f32_16x16x32_bf16 v[56:59], v[160:163], v[174:177], v[56:59]
	v_mfma_f32_16x16x32_bf16 v[44:47], v[146:149], v[182:185], v[44:47]
	v_mfma_f32_16x16x32_bf16 v[40:43], v[160:163], v[182:185], v[40:43]
	v_mfma_f32_16x16x32_bf16 v[28:31], v[146:149], v[190:193], v[28:31]
	v_mfma_f32_16x16x32_bf16 v[24:27], v[160:163], v[190:193], v[24:27]
	v_mfma_f32_16x16x32_bf16 v[12:15], v[146:149], v[198:201], v[12:15]
	v_mfma_f32_16x16x32_bf16 v[8:11], v[160:163], v[198:201], v[8:11]
	v_mfma_f32_16x16x32_bf16 v[60:63], v[150:153], v[178:181], v[60:63]
	v_mfma_f32_16x16x32_bf16 v[56:59], v[170:173], v[178:181], v[56:59]
	v_mfma_f32_16x16x32_bf16 v[44:47], v[150:153], v[186:189], v[44:47]
	v_mfma_f32_16x16x32_bf16 v[40:43], v[170:173], v[186:189], v[40:43]
	v_mfma_f32_16x16x32_bf16 v[28:31], v[150:153], v[194:197], v[28:31]
	v_mfma_f32_16x16x32_bf16 v[24:27], v[170:173], v[194:197], v[24:27]
	v_mfma_f32_16x16x32_bf16 v[12:15], v[150:153], v[202:205], v[12:15]
	v_mfma_f32_16x16x32_bf16 v[8:11], v[170:173], v[202:205], v[8:11]
	s_setprio 0
	s_barrier
	s_add_u32 s12, s14, 0x20080
	s_addc_u32 s13, s15, 0
	s_add_i32 s14, s16, s35
	v_lshl_add_u64 v[146:147], s[12:13], 0, v[132:133]
	s_mov_b32 m0, s14
	s_nop 0
	global_load_lds_dwordx4 v[146:147], off
	v_lshl_add_u64 v[146:147], s[12:13], 0, v[128:129]
	s_add_i32 m0, s14, 0x2000
	s_nop 0
	global_load_lds_dwordx4 v[146:147], off
	s_waitcnt vmcnt(6)
	s_barrier
	s_setprio 1
	v_mfma_f32_16x16x32_bf16 v[52:55], v[206:209], v[174:177], v[52:55]
	v_mfma_f32_16x16x32_bf16 v[48:51], v[214:217], v[174:177], v[48:51]
	v_mfma_f32_16x16x32_bf16 v[36:39], v[206:209], v[182:185], v[36:39]
	v_mfma_f32_16x16x32_bf16 v[32:35], v[214:217], v[182:185], v[32:35]
	v_mfma_f32_16x16x32_bf16 v[20:23], v[206:209], v[190:193], v[20:23]
	v_mfma_f32_16x16x32_bf16 v[16:19], v[214:217], v[190:193], v[16:19]
	v_mfma_f32_16x16x32_bf16 v[4:7], v[206:209], v[198:201], v[4:7]
	v_mfma_f32_16x16x32_bf16 v[0:3], v[214:217], v[198:201], v[0:3]
	v_mfma_f32_16x16x32_bf16 v[52:55], v[210:213], v[178:181], v[52:55]
	v_mfma_f32_16x16x32_bf16 v[48:51], v[218:221], v[178:181], v[48:51]
	v_mfma_f32_16x16x32_bf16 v[36:39], v[210:213], v[186:189], v[36:39]
	v_mfma_f32_16x16x32_bf16 v[32:35], v[218:221], v[186:189], v[32:35]
	v_mfma_f32_16x16x32_bf16 v[20:23], v[210:213], v[194:197], v[20:23]
	v_mfma_f32_16x16x32_bf16 v[16:19], v[218:221], v[194:197], v[16:19]
	v_mfma_f32_16x16x32_bf16 v[4:7], v[210:213], v[202:205], v[4:7]
	v_mfma_f32_16x16x32_bf16 v[0:3], v[218:221], v[202:205], v[0:3]
	s_setprio 0
	s_add_i32 s60, s60, 2
	s_add_u32 s44, s44, 0x100
	s_addc_u32 s45, s45, 0
	s_cmp_gt_u32 s60, 5
	s_mov_b64 s[12:13], s[10:11]
	s_barrier
	s_cbranch_scc0 .LBB0_1768
	v_lshl_or_b32 v148, s7, 8, v156
	v_lshl_add_u32 v160, s6, 8, v154
	v_ashrrev_i32_e32 v149, 31, v148
	v_mov_b64_e32 v[146:147], s[22:23]
	v_mad_i64_i32 v[150:151], s[6:7], v160, s57, v[146:147]
	v_lshlrev_b64 v[148:149], 1, v[148:149]
	v_lshl_add_u64 v[150:151], v[150:151], 0, v[148:149]
	v_add_co_u32_e32 v152, vcc, 0x1000, v150
	s_nop 1
	v_addc_co_u32_e32 v153, vcc, 0, v151, vcc
	v_subrev_u32_e32 v197, s22, v150
	v_add_u32_e32 v198, 0x1a00, v197
	global_load_dwordx4 v[200:203], v198, s[22:23]
	v_add_u32_e32 v198, 0x1b00, v197
	global_load_dwordx4 v[204:207], v198, s[22:23]
	v_add_u32_e32 v198, 0x23a00, v197
	global_load_dwordx4 v[208:211], v198, s[22:23]
	v_add_u32_e32 v198, 0x23b00, v197
	global_load_dwordx4 v[212:215], v198, s[22:23]
	v_add_u32_e32 v198, 0x45a00, v197
	global_load_dwordx4 v[216:219], v198, s[22:23]
	v_add_u32_e32 v198, 0x45b00, v197
	global_load_dwordx4 v[232:235], v198, s[22:23]
	v_add_u32_e32 v198, 0x67a00, v197
	global_load_dwordx4 v[236:239], v198, s[22:23]
	s_waitcnt vmcnt(6)
	v_mov_b32_e32 v162, v200
	v_mov_b32_e32 v163, v201
	v_mov_b32_e32 v164, v202
	v_mov_b32_e32 v165, v203
	v_add_u32_e32 v198, 0x67b00, v197
	global_load_dwordx4 v[200:203], v198, s[22:23]
	s_mov_b32 s100, 0xbfb8aa3b
	v_lshlrev_b32_e32 v242, 16, v162
	v_and_b32_e32 v243, 0xffff0000, v162
	v_lshlrev_b32_e32 v244, 16, v164
	v_and_b32_e32 v245, 0xffff0000, v164
	v_lshlrev_b32_e32 v246, 16, v163
	v_and_b32_e32 v247, 0xffff0000, v163
	v_lshlrev_b32_e32 v248, 16, v165
	v_and_b32_e32 v249, 0xffff0000, v165
	v_pk_mul_f32 v[242:243], v[242:243], s[100:101] op_sel_hi:[1,0]
	v_pk_mul_f32 v[244:245], v[244:245], s[100:101] op_sel_hi:[1,0]
	v_pk_mul_f32 v[246:247], v[246:247], s[100:101] op_sel_hi:[1,0]
	v_pk_mul_f32 v[248:249], v[248:249], s[100:101] op_sel_hi:[1,0]
	v_exp_f32_e32 v242, v242
	v_exp_f32_e32 v243, v243
	v_exp_f32_e32 v244, v244
	v_exp_f32_e32 v245, v245
	v_exp_f32_e32 v246, v246
	v_exp_f32_e32 v247, v247
	v_exp_f32_e32 v248, v248
	v_exp_f32_e32 v249, v249
	s_nop 0
	v_pk_add_f32 v[242:243], v[242:243], 1.0 op_sel_hi:[1,0]
	v_pk_add_f32 v[244:245], v[244:245], 1.0 op_sel_hi:[1,0]
	v_pk_add_f32 v[246:247], v[246:247], 1.0 op_sel_hi:[1,0]
	v_pk_add_f32 v[248:249], v[248:249], 1.0 op_sel_hi:[1,0]
	v_rcp_f32_e32 v250, v242
	v_rcp_f32_e32 v251, v243
	s_nop 0
	v_pk_fma_f32 v[252:253], v[242:243], v[250:251], 1.0 op_sel_hi:[1,1,0] neg_lo:[1,0,0] neg_hi:[1,0,0]
	v_pk_fma_f32 v[250:251], v[252:253], v[250:251], v[250:251]
	v_pk_fma_f32 v[252:253], v[242:243], v[250:251], 1.0 op_sel_hi:[1,1,0] neg_lo:[1,0,0] neg_hi:[1,0,0]
	v_pk_fma_f32 v[254:255], v[252:253], v[250:251], v[250:251]
	v_pk_fma_f32 v[252:253], v[242:243], v[254:255], 1.0 op_sel_hi:[1,1,0] neg_lo:[1,0,0] neg_hi:[1,0,0]
	v_pk_fma_f32 v[254:255], v[252:253], v[250:251], v[254:255]
	v_div_fixup_f32 v242, v254, v242, 1.0
; __device__ __forceinline__ u32x4 pack8(const f32x4 v0, const f32x4 v1) { u32x4 w; w.x = pk2(v0[0], v0[1]); w.y = pk2(v0[2], v0[3]); w.z = pk2(v1[0], v1[1]); w.w = pk2(v1[2], v1[3]); return w; }
; __device__ __forceinline__ void unpack8(const u32x4 w, f32x4& v0, f32x4& v1) { v0 = (f32x4){bflo(w.x), bfhi(w.x), bflo(w.y), bfhi(w.y)}; v1 = (f32x4){bflo(w.z), bfhi(w.z), bflo(w.w), bfhi(w.w)}; }
; __device__ __forceinline__ float sigmoidf_(float x) { return 1.0f / (1.0f + __expf(-x)); }
;     __device__ __forceinline__ void operator()(const f32x4 (&acc)[2][2][4][2], const Unit& u, int wr, int wc, int fr, int fq) const {
;     ...
;                 bf16_t* rowp = z + (size_t)(row0 + ai * 128 + m * 16) * DIN + col0;
; #pragma unroll
;                 for (int bj = 0; bj < 2; ++bj) {
;                     const u32x4 gw = *(const u32x4*)(rowp + (MODE == 0 ? O_GB : O_GA) + bj * 128);
;                     f32x4 g0, g1; unpack8(gw, g0, g1);
;                     f32x4 v0, v1;
; #pragma unroll
;                     for (int j = 0; j < 4; ++j) { v0[j] = sigmoidf_(g0[j]) * acc[ai][bj][m][0][j]; v1[j] = sigmoidf_(g1[j]) * acc[ai][bj][m][1][j]; }
;                     if (MODE == 1) { const u32x4 mw = *(const u32x4*)(rowp + bj * 128); f32x4 m0, m1; unpack8(mw, m0, m1); v0 += m0; v1 += m1; }
;                     *(u32x4*)(rowp + bj * 128) = pack8(v0, v1); }
	v_div_fixup_f32 v243, v255, v243, 1.0
	v_rcp_f32_e32 v250, v244
	v_rcp_f32_e32 v251, v245
	s_nop 0
	v_pk_fma_f32 v[252:253], v[244:245], v[250:251], 1.0 op_sel_hi:[1,1,0] neg_lo:[1,0,0] neg_hi:[1,0,0]
	v_pk_fma_f32 v[250:251], v[252:253], v[250:251], v[250:251]
	v_pk_fma_f32 v[252:253], v[244:245], v[250:251], 1.0 op_sel_hi:[1,1,0] neg_lo:[1,0,0] neg_hi:[1,0,0]
	v_pk_fma_f32 v[254:255], v[252:253], v[250:251], v[250:251]
	v_pk_fma_f32 v[252:253], v[244:245], v[254:255], 1.0 op_sel_hi:[1,1,0] neg_lo:[1,0,0] neg_hi:[1,0,0]
	v_pk_fma_f32 v[254:255], v[252:253], v[250:251], v[254:255]
	v_div_fixup_f32 v244, v254, v244, 1.0
	v_div_fixup_f32 v245, v255, v245, 1.0
	v_rcp_f32_e32 v250, v246
	v_rcp_f32_e32 v251, v247
	s_nop 0
	v_pk_fma_f32 v[252:253], v[246:247], v[250:251], 1.0 op_sel_hi:[1,1,0] neg_lo:[1,0,0] neg_hi:[1,0,0]
	v_pk_fma_f32 v[250:251], v[252:253], v[250:251], v[250:251]
	v_pk_fma_f32 v[252:253], v[246:247], v[250:251], 1.0 op_sel_hi:[1,1,0] neg_lo:[1,0,0] neg_hi:[1,0,0]
	v_pk_fma_f32 v[254:255], v[252:253], v[250:251], v[250:251]
	v_pk_fma_f32 v[252:253], v[246:247], v[254:255], 1.0 op_sel_hi:[1,1,0] neg_lo:[1,0,0] neg_hi:[1,0,0]
	v_pk_fma_f32 v[254:255], v[252:253], v[250:251], v[254:255]
	v_div_fixup_f32 v246, v254, v246, 1.0
	v_div_fixup_f32 v247, v255, v247, 1.0
	v_rcp_f32_e32 v250, v248
	v_rcp_f32_e32 v251, v249
	s_nop 0
	v_pk_fma_f32 v[252:253], v[248:249], v[250:251], 1.0 op_sel_hi:[1,1,0] neg_lo:[1,0,0] neg_hi:[1,0,0]
	v_pk_fma_f32 v[250:251], v[252:253], v[250:251], v[250:251]
	v_pk_fma_f32 v[252:253], v[248:249], v[250:251], 1.0 op_sel_hi:[1,1,0] neg_lo:[1,0,0] neg_hi:[1,0,0]
	v_pk_fma_f32 v[254:255], v[252:253], v[250:251], v[250:251]
	v_pk_fma_f32 v[252:253], v[248:249], v[254:255], 1.0 op_sel_hi:[1,1,0] neg_lo:[1,0,0] neg_hi:[1,0,0]
	v_pk_fma_f32 v[254:255], v[252:253], v[250:251], v[254:255]
	v_div_fixup_f32 v248, v254, v248, 1.0
	v_div_fixup_f32 v249, v255, v249, 1.0
	s_mov_b64 vcc, s[10:11]
	s_mov_b64 vcc, s[12:13]
	v_mul_f32_e32 v124, v124, v242
	s_mov_b64 vcc, s[14:15]
	v_mul_f32_e32 v161, v120, v244
	v_mul_f32_e32 v120, v125, v243
	v_mul_f32_e32 v125, v121, v245
	s_mov_b64 vcc, s[16:17]
	v_mul_f32_e32 v126, v126, v246
	v_mul_f32_e32 v162, v122, v248
	v_mul_f32_e32 v121, v127, v247
	v_mul_f32_e32 v123, v123, v249
	v_cvt_pk_bf16_f32 v120, v124, v120
	v_cvt_pk_bf16_f32 v121, v126, v121
	v_cvt_pk_bf16_f32 v122, v161, v125
	v_cvt_pk_bf16_f32 v123, v162, v123
	s_mov_b64 s[14:15], s[30:31]
	global_store_dwordx4 v[150:151], v[120:123], off
	s_mov_b64 s[12:13], s[28:29]
	s_waitcnt vmcnt(7)
	v_mov_b32_e32 v124, v204
	v_mov_b32_e32 v125, v205
	v_mov_b32_e32 v126, v206
	v_mov_b32_e32 v127, v207
	v_add_u32_e32 v198, 0x111a00, v197
	global_load_dwordx4 v[204:207], v198, s[22:23]
	s_mov_b32 s100, 0xbfb8aa3b
	v_lshlrev_b32_e32 v242, 16, v124
	v_and_b32_e32 v243, 0xffff0000, v124
	v_lshlrev_b32_e32 v244, 16, v126
	v_and_b32_e32 v245, 0xffff0000, v126
	v_lshlrev_b32_e32 v246, 16, v125
	v_and_b32_e32 v247, 0xffff0000, v125
	v_lshlrev_b32_e32 v248, 16, v127
	v_and_b32_e32 v249, 0xffff0000, v127
	v_pk_mul_f32 v[242:243], v[242:243], s[100:101] op_sel_hi:[1,0]
	v_pk_mul_f32 v[244:245], v[244:245], s[100:101] op_sel_hi:[1,0]
	v_pk_mul_f32 v[246:247], v[246:247], s[100:101] op_sel_hi:[1,0]
	v_pk_mul_f32 v[248:249], v[248:249], s[100:101] op_sel_hi:[1,0]
	v_exp_f32_e32 v242, v242
	v_exp_f32_e32 v243, v243
	v_exp_f32_e32 v244, v244
	v_exp_f32_e32 v245, v245
	v_exp_f32_e32 v246, v246
	v_exp_f32_e32 v247, v247
	v_exp_f32_e32 v248, v248
	v_exp_f32_e32 v249, v249
	s_nop 0
	v_pk_add_f32 v[242:243], v[242:243], 1.0 op_sel_hi:[1,0]
	v_pk_add_f32 v[244:245], v[244:245], 1.0 op_sel_hi:[1,0]
	v_pk_add_f32 v[246:247], v[246:247], 1.0 op_sel_hi:[1,0]
	v_pk_add_f32 v[248:249], v[248:249], 1.0 op_sel_hi:[1,0]
	v_rcp_f32_e32 v250, v242
	v_rcp_f32_e32 v251, v243
	s_nop 0
	v_pk_fma_f32 v[252:253], v[242:243], v[250:251], 1.0 op_sel_hi:[1,1,0] neg_lo:[1,0,0] neg_hi:[1,0,0]
	v_pk_fma_f32 v[250:251], v[252:253], v[250:251], v[250:251]
	v_pk_fma_f32 v[252:253], v[242:243], v[250:251], 1.0 op_sel_hi:[1,1,0] neg_lo:[1,0,0] neg_hi:[1,0,0]
	v_pk_fma_f32 v[254:255], v[252:253], v[250:251], v[250:251]
	v_pk_fma_f32 v[252:253], v[242:243], v[254:255], 1.0 op_sel_hi:[1,1,0] neg_lo:[1,0,0] neg_hi:[1,0,0]
	v_pk_fma_f32 v[254:255], v[252:253], v[250:251], v[254:255]
	v_div_fixup_f32 v242, v254, v242, 1.0
	v_div_fixup_f32 v243, v255, v243, 1.0
	v_rcp_f32_e32 v250, v244
	v_rcp_f32_e32 v251, v245
	s_nop 0
	v_pk_fma_f32 v[252:253], v[244:245], v[250:251], 1.0 op_sel_hi:[1,1,0] neg_lo:[1,0,0] neg_hi:[1,0,0]
	v_pk_fma_f32 v[250:251], v[252:253], v[250:251], v[250:251]
	v_pk_fma_f32 v[252:253], v[244:245], v[250:251], 1.0 op_sel_hi:[1,1,0] neg_lo:[1,0,0] neg_hi:[1,0,0]
	v_pk_fma_f32 v[254:255], v[252:253], v[250:251], v[250:251]
	v_pk_fma_f32 v[252:253], v[244:245], v[254:255], 1.0 op_sel_hi:[1,1,0] neg_lo:[1,0,0] neg_hi:[1,0,0]
	v_pk_fma_f32 v[254:255], v[252:253], v[250:251], v[254:255]
	v_div_fixup_f32 v244, v254, v244, 1.0
	v_div_fixup_f32 v245, v255, v245, 1.0
	v_rcp_f32_e32 v250, v246
	v_rcp_f32_e32 v251, v247
	s_nop 0
	v_pk_fma_f32 v[252:253], v[246:247], v[250:251], 1.0 op_sel_hi:[1,1,0] neg_lo:[1,0,0] neg_hi:[1,0,0]
	v_pk_fma_f32 v[250:251], v[252:253], v[250:251], v[250:251]
	v_pk_fma_f32 v[252:253], v[246:247], v[250:251], 1.0 op_sel_hi:[1,1,0] neg_lo:[1,0,0] neg_hi:[1,0,0]
	v_pk_fma_f32 v[254:255], v[252:253], v[250:251], v[250:251]
	v_pk_fma_f32 v[252:253], v[246:247], v[254:255], 1.0 op_sel_hi:[1,1,0] neg_lo:[1,0,0] neg_hi:[1,0,0]
	v_pk_fma_f32 v[254:255], v[252:253], v[250:251], v[254:255]
	v_div_fixup_f32 v246, v254, v246, 1.0
	v_div_fixup_f32 v247, v255, v247, 1.0
	v_rcp_f32_e32 v250, v248
	v_rcp_f32_e32 v251, v249
	s_nop 0
	v_pk_fma_f32 v[252:253], v[248:249], v[250:251], 1.0 op_sel_hi:[1,1,0] neg_lo:[1,0,0] neg_hi:[1,0,0]
	v_pk_fma_f32 v[250:251], v[252:253], v[250:251], v[250:251]
	v_pk_fma_f32 v[252:253], v[248:249], v[250:251], 1.0 op_sel_hi:[1,1,0] neg_lo:[1,0,0] neg_hi:[1,0,0]
	v_pk_fma_f32 v[254:255], v[252:253], v[250:251], v[250:251]
	v_pk_fma_f32 v[252:253], v[248:249], v[254:255], 1.0 op_sel_hi:[1,1,0] neg_lo:[1,0,0] neg_hi:[1,0,0]
	v_pk_fma_f32 v[254:255], v[252:253], v[250:251], v[254:255]
	v_div_fixup_f32 v248, v254, v248, 1.0
	v_div_fixup_f32 v249, v255, v249, 1.0
	s_mov_b64 vcc, s[10:11]
	v_pk_mul_f32 v[116:117], v[116:117], v[242:243]
	v_pk_mul_f32 v[112:113], v[112:113], v[244:245]
	v_pk_mul_f32 v[118:119], v[118:119], v[246:247]
	v_pk_mul_f32 v[120:121], v[114:115], v[248:249]
	v_cvt_pk_bf16_f32 v114, v116, v117
	v_cvt_pk_bf16_f32 v115, v118, v119
	v_cvt_pk_bf16_f32 v116, v112, v113
	v_or_b32_e32 v112, 16, v160
	v_mad_i64_i32 v[112:113], s[6:7], v112, s57, v[146:147]
	v_lshl_add_u64 v[112:113], v[112:113], 0, v[148:149]
	v_add_co_u32_e32 v122, vcc, s58, v112
	v_cvt_pk_bf16_f32 v117, v120, v121
	global_store_dwordx4 v[150:151], v[114:117], off offset:256
	s_nop 0
	v_addc_co_u32_e32 v123, vcc, 0, v113, vcc
	s_waitcnt vmcnt(8)
; __device__ __forceinline__ u32x4 pack8(const f32x4 v0, const f32x4 v1) { u32x4 w; w.x = pk2(v0[0], v0[1]); w.y = pk2(v0[2], v0[3]); w.z = pk2(v1[0], v1[1]); w.w = pk2(v1[2], v1[3]); return w; }
; __device__ __forceinline__ void unpack8(const u32x4 w, f32x4& v0, f32x4& v1) { v0 = (f32x4){bflo(w.x), bfhi(w.x), bflo(w.y), bfhi(w.y)}; v1 = (f32x4){bflo(w.z), bfhi(w.z), bflo(w.w), bfhi(w.w)}; }
; __device__ __forceinline__ float sigmoidf_(float x) { return 1.0f / (1.0f + __expf(-x)); }
;     __device__ __forceinline__ void operator()(const f32x4 (&acc)[2][2][4][2], const Unit& u, int wr, int wc, int fr, int fq) const {
;     ...
;                 bf16_t* rowp = z + (size_t)(row0 + ai * 128 + m * 16) * DIN + col0;
; #pragma unroll
;                 for (int bj = 0; bj < 2; ++bj) {
;                     const u32x4 gw = *(const u32x4*)(rowp + (MODE == 0 ? O_GB : O_GA) + bj * 128);
;                     f32x4 g0, g1; unpack8(gw, g0, g1);
;                     f32x4 v0, v1;
; #pragma unroll
;                     for (int j = 0; j < 4; ++j) { v0[j] = sigmoidf_(g0[j]) * acc[ai][bj][m][0][j]; v1[j] = sigmoidf_(g1[j]) * acc[ai][bj][m][1][j]; }
;                     if (MODE == 1) { const u32x4 mw = *(const u32x4*)(rowp + bj * 128); f32x4 m0, m1; unpack8(mw, m0, m1); v0 += m0; v1 += m1; }
;                     *(u32x4*)(rowp + bj * 128) = pack8(v0, v1); }
	v_mov_b32_e32 v118, v208
	v_mov_b32_e32 v119, v209
	v_mov_b32_e32 v120, v210
	v_mov_b32_e32 v121, v211
	v_add_u32_e32 v198, 0x111b00, v197
	global_load_dwordx4 v[208:211], v198, s[22:23]
	s_mov_b32 s100, 0xbfb8aa3b
	v_lshlrev_b32_e32 v242, 16, v118
	v_and_b32_e32 v243, 0xffff0000, v118
	v_lshlrev_b32_e32 v244, 16, v120
	v_and_b32_e32 v245, 0xffff0000, v120
	v_lshlrev_b32_e32 v246, 16, v119
	v_and_b32_e32 v247, 0xffff0000, v119
	v_lshlrev_b32_e32 v248, 16, v121
	v_and_b32_e32 v249, 0xffff0000, v121
	v_pk_mul_f32 v[242:243], v[242:243], s[100:101] op_sel_hi:[1,0]
	v_pk_mul_f32 v[244:245], v[244:245], s[100:101] op_sel_hi:[1,0]
	v_pk_mul_f32 v[246:247], v[246:247], s[100:101] op_sel_hi:[1,0]
	v_pk_mul_f32 v[248:249], v[248:249], s[100:101] op_sel_hi:[1,0]
	v_exp_f32_e32 v242, v242
	v_exp_f32_e32 v243, v243
	v_exp_f32_e32 v244, v244
	v_exp_f32_e32 v245, v245
	v_exp_f32_e32 v246, v246
	v_exp_f32_e32 v247, v247
	v_exp_f32_e32 v248, v248
	v_exp_f32_e32 v249, v249
	s_nop 0
	v_pk_add_f32 v[242:243], v[242:243], 1.0 op_sel_hi:[1,0]
	v_pk_add_f32 v[244:245], v[244:245], 1.0 op_sel_hi:[1,0]
	v_pk_add_f32 v[246:247], v[246:247], 1.0 op_sel_hi:[1,0]
	v_pk_add_f32 v[248:249], v[248:249], 1.0 op_sel_hi:[1,0]
	v_rcp_f32_e32 v250, v242
	v_rcp_f32_e32 v251, v243
	s_nop 0
	v_pk_fma_f32 v[252:253], v[242:243], v[250:251], 1.0 op_sel_hi:[1,1,0] neg_lo:[1,0,0] neg_hi:[1,0,0]
	v_pk_fma_f32 v[250:251], v[252:253], v[250:251], v[250:251]
	v_pk_fma_f32 v[252:253], v[242:243], v[250:251], 1.0 op_sel_hi:[1,1,0] neg_lo:[1,0,0] neg_hi:[1,0,0]
	v_pk_fma_f32 v[254:255], v[252:253], v[250:251], v[250:251]
	v_pk_fma_f32 v[252:253], v[242:243], v[254:255], 1.0 op_sel_hi:[1,1,0] neg_lo:[1,0,0] neg_hi:[1,0,0]
	v_pk_fma_f32 v[254:255], v[252:253], v[250:251], v[254:255]
	v_div_fixup_f32 v242, v254, v242, 1.0
	v_div_fixup_f32 v243, v255, v243, 1.0
	v_rcp_f32_e32 v250, v244
	v_rcp_f32_e32 v251, v245
	s_nop 0
	v_pk_fma_f32 v[252:253], v[244:245], v[250:251], 1.0 op_sel_hi:[1,1,0] neg_lo:[1,0,0] neg_hi:[1,0,0]
	v_pk_fma_f32 v[250:251], v[252:253], v[250:251], v[250:251]
	v_pk_fma_f32 v[252:253], v[244:245], v[250:251], 1.0 op_sel_hi:[1,1,0] neg_lo:[1,0,0] neg_hi:[1,0,0]
	v_pk_fma_f32 v[254:255], v[252:253], v[250:251], v[250:251]
	v_pk_fma_f32 v[252:253], v[244:245], v[254:255], 1.0 op_sel_hi:[1,1,0] neg_lo:[1,0,0] neg_hi:[1,0,0]
	v_pk_fma_f32 v[254:255], v[252:253], v[250:251], v[254:255]
	v_div_fixup_f32 v244, v254, v244, 1.0
	v_div_fixup_f32 v245, v255, v245, 1.0
	v_rcp_f32_e32 v250, v246
	v_rcp_f32_e32 v251, v247
	s_nop 0
	v_pk_fma_f32 v[252:253], v[246:247], v[250:251], 1.0 op_sel_hi:[1,1,0] neg_lo:[1,0,0] neg_hi:[1,0,0]
	v_pk_fma_f32 v[250:251], v[252:253], v[250:251], v[250:251]
	v_pk_fma_f32 v[252:253], v[246:247], v[250:251], 1.0 op_sel_hi:[1,1,0] neg_lo:[1,0,0] neg_hi:[1,0,0]
	v_pk_fma_f32 v[254:255], v[252:253], v[250:251], v[250:251]
	v_pk_fma_f32 v[252:253], v[246:247], v[254:255], 1.0 op_sel_hi:[1,1,0] neg_lo:[1,0,0] neg_hi:[1,0,0]
	v_pk_fma_f32 v[254:255], v[252:253], v[250:251], v[254:255]
	v_div_fixup_f32 v246, v254, v246, 1.0
	v_div_fixup_f32 v247, v255, v247, 1.0
	v_rcp_f32_e32 v250, v248
	v_rcp_f32_e32 v251, v249
	s_nop 0
	v_pk_fma_f32 v[252:253], v[248:249], v[250:251], 1.0 op_sel_hi:[1,1,0] neg_lo:[1,0,0] neg_hi:[1,0,0]
	v_pk_fma_f32 v[250:251], v[252:253], v[250:251], v[250:251]
	v_pk_fma_f32 v[252:253], v[248:249], v[250:251], 1.0 op_sel_hi:[1,1,0] neg_lo:[1,0,0] neg_hi:[1,0,0]
	v_pk_fma_f32 v[254:255], v[252:253], v[250:251], v[250:251]
	v_pk_fma_f32 v[252:253], v[248:249], v[254:255], 1.0 op_sel_hi:[1,1,0] neg_lo:[1,0,0] neg_hi:[1,0,0]
	v_pk_fma_f32 v[254:255], v[252:253], v[250:251], v[254:255]
	v_div_fixup_f32 v248, v254, v248, 1.0
	v_div_fixup_f32 v249, v255, v249, 1.0
	v_mul_f32_e32 v108, v108, v242
	v_mul_f32_e32 v114, v104, v244
	v_mul_f32_e32 v104, v109, v243
	v_mul_f32_e32 v109, v105, v245
	v_mul_f32_e32 v105, v110, v246
	v_mul_f32_e32 v110, v106, v248
	v_mul_f32_e32 v106, v111, v247
	v_mul_f32_e32 v107, v107, v249
	v_cvt_pk_bf16_f32 v104, v108, v104
	v_cvt_pk_bf16_f32 v105, v105, v106
	v_cvt_pk_bf16_f32 v106, v114, v109
	v_cvt_pk_bf16_f32 v107, v110, v107
	s_waitcnt vmcnt(8)
	v_mov_b32_e32 v108, v212
	v_mov_b32_e32 v109, v213
	v_mov_b32_e32 v110, v214
	v_mov_b32_e32 v111, v215
	v_add_u32_e32 v198, 0x133a00, v197
	global_load_dwordx4 v[212:215], v198, s[22:23]
	s_mov_b32 s100, 0xbfb8aa3b
	v_lshlrev_b32_e32 v242, 16, v108
	v_and_b32_e32 v243, 0xffff0000, v108
	v_lshlrev_b32_e32 v244, 16, v110
	v_and_b32_e32 v245, 0xffff0000, v110
	v_lshlrev_b32_e32 v246, 16, v109
	v_and_b32_e32 v247, 0xffff0000, v109
	v_lshlrev_b32_e32 v248, 16, v111
	v_and_b32_e32 v249, 0xffff0000, v111
	v_pk_mul_f32 v[242:243], v[242:243], s[100:101] op_sel_hi:[1,0]
	v_pk_mul_f32 v[244:245], v[244:245], s[100:101] op_sel_hi:[1,0]
	v_pk_mul_f32 v[246:247], v[246:247], s[100:101] op_sel_hi:[1,0]
	v_pk_mul_f32 v[248:249], v[248:249], s[100:101] op_sel_hi:[1,0]
	v_exp_f32_e32 v242, v242
	v_exp_f32_e32 v243, v243
	v_exp_f32_e32 v244, v244
	v_exp_f32_e32 v245, v245
	v_exp_f32_e32 v246, v246
	v_exp_f32_e32 v247, v247
	v_exp_f32_e32 v248, v248
	v_exp_f32_e32 v249, v249
	s_nop 0
	v_pk_add_f32 v[242:243], v[242:243], 1.0 op_sel_hi:[1,0]
	v_pk_add_f32 v[244:245], v[244:245], 1.0 op_sel_hi:[1,0]
	v_pk_add_f32 v[246:247], v[246:247], 1.0 op_sel_hi:[1,0]
	v_pk_add_f32 v[248:249], v[248:249], 1.0 op_sel_hi:[1,0]
	v_rcp_f32_e32 v250, v242
	v_rcp_f32_e32 v251, v243
	s_nop 0
	v_pk_fma_f32 v[252:253], v[242:243], v[250:251], 1.0 op_sel_hi:[1,1,0] neg_lo:[1,0,0] neg_hi:[1,0,0]
	v_pk_fma_f32 v[250:251], v[252:253], v[250:251], v[250:251]
	v_pk_fma_f32 v[252:253], v[242:243], v[250:251], 1.0 op_sel_hi:[1,1,0] neg_lo:[1,0,0] neg_hi:[1,0,0]
; __device__ __forceinline__ u32x4 pack8(const f32x4 v0, const f32x4 v1) { u32x4 w; w.x = pk2(v0[0], v0[1]); w.y = pk2(v0[2], v0[3]); w.z = pk2(v1[0], v1[1]); w.w = pk2(v1[2], v1[3]); return w; }
; __device__ __forceinline__ void unpack8(const u32x4 w, f32x4& v0, f32x4& v1) { v0 = (f32x4){bflo(w.x), bfhi(w.x), bflo(w.y), bfhi(w.y)}; v1 = (f32x4){bflo(w.z), bfhi(w.z), bflo(w.w), bfhi(w.w)}; }
; __device__ __forceinline__ float sigmoidf_(float x) { return 1.0f / (1.0f + __expf(-x)); }
;     __device__ __forceinline__ void operator()(const f32x4 (&acc)[2][2][4][2], const Unit& u, int wr, int wc, int fr, int fq) const {
;     ...
;         for (int ai = 0; ai < 2; ++ai)
; #pragma unroll
;             for (int m = 0; m < 4; ++m) {
;                 bf16_t* rowp = z + (size_t)(row0 + ai * 128 + m * 16) * DIN + col0;
; #pragma unroll
;                 for (int bj = 0; bj < 2; ++bj) {
;                     const u32x4 gw = *(const u32x4*)(rowp + (MODE == 0 ? O_GB : O_GA) + bj * 128);
;                     f32x4 g0, g1; unpack8(gw, g0, g1);
;                     f32x4 v0, v1;
; #pragma unroll
;                     for (int j = 0; j < 4; ++j) { v0[j] = sigmoidf_(g0[j]) * acc[ai][bj][m][0][j]; v1[j] = sigmoidf_(g1[j]) * acc[ai][bj][m][1][j]; }
;                     if (MODE == 1) { const u32x4 mw = *(const u32x4*)(rowp + bj * 128); f32x4 m0, m1; unpack8(mw, m0, m1); v0 += m0; v1 += m1; }
;                     *(u32x4*)(rowp + bj * 128) = pack8(v0, v1); }
	v_pk_fma_f32 v[254:255], v[252:253], v[250:251], v[250:251]
	v_pk_fma_f32 v[252:253], v[242:243], v[254:255], 1.0 op_sel_hi:[1,1,0] neg_lo:[1,0,0] neg_hi:[1,0,0]
	v_pk_fma_f32 v[254:255], v[252:253], v[250:251], v[254:255]
	v_div_fixup_f32 v242, v254, v242, 1.0
	v_div_fixup_f32 v243, v255, v243, 1.0
	v_rcp_f32_e32 v250, v244
	v_rcp_f32_e32 v251, v245
	s_nop 0
	v_pk_fma_f32 v[252:253], v[244:245], v[250:251], 1.0 op_sel_hi:[1,1,0] neg_lo:[1,0,0] neg_hi:[1,0,0]
	v_pk_fma_f32 v[250:251], v[252:253], v[250:251], v[250:251]
	v_pk_fma_f32 v[252:253], v[244:245], v[250:251], 1.0 op_sel_hi:[1,1,0] neg_lo:[1,0,0] neg_hi:[1,0,0]
	v_pk_fma_f32 v[254:255], v[252:253], v[250:251], v[250:251]
	v_pk_fma_f32 v[252:253], v[244:245], v[254:255], 1.0 op_sel_hi:[1,1,0] neg_lo:[1,0,0] neg_hi:[1,0,0]
	v_pk_fma_f32 v[254:255], v[252:253], v[250:251], v[254:255]
	v_div_fixup_f32 v244, v254, v244, 1.0
	v_div_fixup_f32 v245, v255, v245, 1.0
	v_rcp_f32_e32 v250, v246
	v_rcp_f32_e32 v251, v247
	s_nop 0
	v_pk_fma_f32 v[252:253], v[246:247], v[250:251], 1.0 op_sel_hi:[1,1,0] neg_lo:[1,0,0] neg_hi:[1,0,0]
	v_pk_fma_f32 v[250:251], v[252:253], v[250:251], v[250:251]
	v_pk_fma_f32 v[252:253], v[246:247], v[250:251], 1.0 op_sel_hi:[1,1,0] neg_lo:[1,0,0] neg_hi:[1,0,0]
	v_pk_fma_f32 v[254:255], v[252:253], v[250:251], v[250:251]
	v_pk_fma_f32 v[252:253], v[246:247], v[254:255], 1.0 op_sel_hi:[1,1,0] neg_lo:[1,0,0] neg_hi:[1,0,0]
	v_pk_fma_f32 v[254:255], v[252:253], v[250:251], v[254:255]
	v_div_fixup_f32 v246, v254, v246, 1.0
	v_div_fixup_f32 v247, v255, v247, 1.0
	v_rcp_f32_e32 v250, v248
	v_rcp_f32_e32 v251, v249
	s_nop 0
	v_pk_fma_f32 v[252:253], v[248:249], v[250:251], 1.0 op_sel_hi:[1,1,0] neg_lo:[1,0,0] neg_hi:[1,0,0]
	v_pk_fma_f32 v[250:251], v[252:253], v[250:251], v[250:251]
	v_pk_fma_f32 v[252:253], v[248:249], v[250:251], 1.0 op_sel_hi:[1,1,0] neg_lo:[1,0,0] neg_hi:[1,0,0]
	v_pk_fma_f32 v[254:255], v[252:253], v[250:251], v[250:251]
	v_pk_fma_f32 v[252:253], v[248:249], v[254:255], 1.0 op_sel_hi:[1,1,0] neg_lo:[1,0,0] neg_hi:[1,0,0]
	v_pk_fma_f32 v[254:255], v[252:253], v[250:251], v[254:255]
	v_div_fixup_f32 v248, v254, v248, 1.0
	v_div_fixup_f32 v249, v255, v249, 1.0
	global_store_dwordx4 v[112:113], v[104:107], off
	s_nop 0
	v_pk_mul_f32 v[100:101], v[100:101], v[242:243]
	v_pk_mul_f32 v[96:97], v[96:97], v[244:245]
	v_pk_mul_f32 v[102:103], v[102:103], v[246:247]
	v_pk_mul_f32 v[104:105], v[98:99], v[248:249]
	v_cvt_pk_bf16_f32 v98, v100, v101
	v_cvt_pk_bf16_f32 v99, v102, v103
	v_cvt_pk_bf16_f32 v100, v96, v97
	v_or_b32_e32 v96, 32, v160
	v_mad_i64_i32 v[96:97], s[6:7], v96, s57, v[146:147]
	v_lshl_add_u64 v[96:97], v[96:97], 0, v[148:149]
	v_add_co_u32_e32 v106, vcc, s58, v96
	v_cvt_pk_bf16_f32 v101, v104, v105
	global_store_dwordx4 v[112:113], v[98:101], off offset:256
	s_nop 0
	v_addc_co_u32_e32 v107, vcc, 0, v97, vcc
	s_waitcnt vmcnt(10)
	v_mov_b32_e32 v102, v216
	v_mov_b32_e32 v103, v217
	v_mov_b32_e32 v104, v218
	v_mov_b32_e32 v105, v219
	v_add_u32_e32 v198, 0x133b00, v197
	global_load_dwordx4 v[216:219], v198, s[22:23]
	s_mov_b32 s100, 0xbfb8aa3b
	v_lshlrev_b32_e32 v242, 16, v102
	v_and_b32_e32 v243, 0xffff0000, v102
	v_lshlrev_b32_e32 v244, 16, v104
	v_and_b32_e32 v245, 0xffff0000, v104
	v_lshlrev_b32_e32 v246, 16, v103
	v_and_b32_e32 v247, 0xffff0000, v103
	v_lshlrev_b32_e32 v248, 16, v105
	v_and_b32_e32 v249, 0xffff0000, v105
	v_pk_mul_f32 v[242:243], v[242:243], s[100:101] op_sel_hi:[1,0]
	v_pk_mul_f32 v[244:245], v[244:245], s[100:101] op_sel_hi:[1,0]
	v_pk_mul_f32 v[246:247], v[246:247], s[100:101] op_sel_hi:[1,0]
	v_pk_mul_f32 v[248:249], v[248:249], s[100:101] op_sel_hi:[1,0]
	v_exp_f32_e32 v242, v242
	v_exp_f32_e32 v243, v243
	v_exp_f32_e32 v244, v244
	v_exp_f32_e32 v245, v245
	v_exp_f32_e32 v246, v246
	v_exp_f32_e32 v247, v247
	v_exp_f32_e32 v248, v248
	v_exp_f32_e32 v249, v249
	s_nop 0
	v_pk_add_f32 v[242:243], v[242:243], 1.0 op_sel_hi:[1,0]
	v_pk_add_f32 v[244:245], v[244:245], 1.0 op_sel_hi:[1,0]
	v_pk_add_f32 v[246:247], v[246:247], 1.0 op_sel_hi:[1,0]
	v_pk_add_f32 v[248:249], v[248:249], 1.0 op_sel_hi:[1,0]
	v_rcp_f32_e32 v250, v242
	v_rcp_f32_e32 v251, v243
	s_nop 0
	v_pk_fma_f32 v[252:253], v[242:243], v[250:251], 1.0 op_sel_hi:[1,1,0] neg_lo:[1,0,0] neg_hi:[1,0,0]
	v_pk_fma_f32 v[250:251], v[252:253], v[250:251], v[250:251]
	v_pk_fma_f32 v[252:253], v[242:243], v[250:251], 1.0 op_sel_hi:[1,1,0] neg_lo:[1,0,0] neg_hi:[1,0,0]
	v_pk_fma_f32 v[254:255], v[252:253], v[250:251], v[250:251]
	v_pk_fma_f32 v[252:253], v[242:243], v[254:255], 1.0 op_sel_hi:[1,1,0] neg_lo:[1,0,0] neg_hi:[1,0,0]
	v_pk_fma_f32 v[254:255], v[252:253], v[250:251], v[254:255]
	v_div_fixup_f32 v242, v254, v242, 1.0
	v_div_fixup_f32 v243, v255, v243, 1.0
	v_rcp_f32_e32 v250, v244
	v_rcp_f32_e32 v251, v245
	s_nop 0
	v_pk_fma_f32 v[252:253], v[244:245], v[250:251], 1.0 op_sel_hi:[1,1,0] neg_lo:[1,0,0] neg_hi:[1,0,0]
	v_pk_fma_f32 v[250:251], v[252:253], v[250:251], v[250:251]
	v_pk_fma_f32 v[252:253], v[244:245], v[250:251], 1.0 op_sel_hi:[1,1,0] neg_lo:[1,0,0] neg_hi:[1,0,0]
	v_pk_fma_f32 v[254:255], v[252:253], v[250:251], v[250:251]
	v_pk_fma_f32 v[252:253], v[244:245], v[254:255], 1.0 op_sel_hi:[1,1,0] neg_lo:[1,0,0] neg_hi:[1,0,0]
	v_pk_fma_f32 v[254:255], v[252:253], v[250:251], v[254:255]
	v_div_fixup_f32 v244, v254, v244, 1.0
	v_div_fixup_f32 v245, v255, v245, 1.0
	v_rcp_f32_e32 v250, v246
	v_rcp_f32_e32 v251, v247
	s_nop 0
	v_pk_fma_f32 v[252:253], v[246:247], v[250:251], 1.0 op_sel_hi:[1,1,0] neg_lo:[1,0,0] neg_hi:[1,0,0]
	v_pk_fma_f32 v[250:251], v[252:253], v[250:251], v[250:251]
	v_pk_fma_f32 v[252:253], v[246:247], v[250:251], 1.0 op_sel_hi:[1,1,0] neg_lo:[1,0,0] neg_hi:[1,0,0]
	v_pk_fma_f32 v[254:255], v[252:253], v[250:251], v[250:251]
	v_pk_fma_f32 v[252:253], v[246:247], v[254:255], 1.0 op_sel_hi:[1,1,0] neg_lo:[1,0,0] neg_hi:[1,0,0]
	v_pk_fma_f32 v[254:255], v[252:253], v[250:251], v[254:255]
	v_div_fixup_f32 v246, v254, v246, 1.0
	v_div_fixup_f32 v247, v255, v247, 1.0
	v_rcp_f32_e32 v250, v248
	v_rcp_f32_e32 v251, v249
	s_nop 0
	v_pk_fma_f32 v[252:253], v[248:249], v[250:251], 1.0 op_sel_hi:[1,1,0] neg_lo:[1,0,0] neg_hi:[1,0,0]
	v_pk_fma_f32 v[250:251], v[252:253], v[250:251], v[250:251]
	v_pk_fma_f32 v[252:253], v[248:249], v[250:251], 1.0 op_sel_hi:[1,1,0] neg_lo:[1,0,0] neg_hi:[1,0,0]
	v_pk_fma_f32 v[254:255], v[252:253], v[250:251], v[250:251]
	v_pk_fma_f32 v[252:253], v[248:249], v[254:255], 1.0 op_sel_hi:[1,1,0] neg_lo:[1,0,0] neg_hi:[1,0,0]
	v_pk_fma_f32 v[254:255], v[252:253], v[250:251], v[254:255]
	v_div_fixup_f32 v248, v254, v248, 1.0
	v_div_fixup_f32 v249, v255, v249, 1.0
	v_mul_f32_e32 v92, v92, v242
	v_mul_f32_e32 v98, v88, v244
	v_mul_f32_e32 v88, v93, v243
	v_mul_f32_e32 v93, v89, v245
	v_mul_f32_e32 v89, v94, v246
	v_mul_f32_e32 v94, v90, v248
	v_mul_f32_e32 v90, v95, v247
	v_mul_f32_e32 v91, v91, v249
	v_cvt_pk_bf16_f32 v88, v92, v88
	v_cvt_pk_bf16_f32 v89, v89, v90
	v_cvt_pk_bf16_f32 v90, v98, v93
	v_cvt_pk_bf16_f32 v91, v94, v91
	s_waitcnt vmcnt(10)
; __device__ __forceinline__ u32x4 pack8(const f32x4 v0, const f32x4 v1) { u32x4 w; w.x = pk2(v0[0], v0[1]); w.y = pk2(v0[2], v0[3]); w.z = pk2(v1[0], v1[1]); w.w = pk2(v1[2], v1[3]); return w; }
; __device__ __forceinline__ void unpack8(const u32x4 w, f32x4& v0, f32x4& v1) { v0 = (f32x4){bflo(w.x), bfhi(w.x), bflo(w.y), bfhi(w.y)}; v1 = (f32x4){bflo(w.z), bfhi(w.z), bflo(w.w), bfhi(w.w)}; }
; __device__ __forceinline__ float sigmoidf_(float x) { return 1.0f / (1.0f + __expf(-x)); }
;     __device__ __forceinline__ void operator()(const f32x4 (&acc)[2][2][4][2], const Unit& u, int wr, int wc, int fr, int fq) const {
;     ...
;         for (int ai = 0; ai < 2; ++ai)
; #pragma unroll
;             for (int m = 0; m < 4; ++m) {
;                 bf16_t* rowp = z + (size_t)(row0 + ai * 128 + m * 16) * DIN + col0;
; #pragma unroll
;                 for (int bj = 0; bj < 2; ++bj) {
;                     const u32x4 gw = *(const u32x4*)(rowp + (MODE == 0 ? O_GB : O_GA) + bj * 128);
;                     f32x4 g0, g1; unpack8(gw, g0, g1);
;                     f32x4 v0, v1;
; #pragma unroll
;                     for (int j = 0; j < 4; ++j) { v0[j] = sigmoidf_(g0[j]) * acc[ai][bj][m][0][j]; v1[j] = sigmoidf_(g1[j]) * acc[ai][bj][m][1][j]; }
;                     if (MODE == 1) { const u32x4 mw = *(const u32x4*)(rowp + bj * 128); f32x4 m0, m1; unpack8(mw, m0, m1); v0 += m0; v1 += m1; }
;                     *(u32x4*)(rowp + bj * 128) = pack8(v0, v1); }
	v_mov_b32_e32 v92, v232
	v_mov_b32_e32 v93, v233
	v_mov_b32_e32 v94, v234
	v_mov_b32_e32 v95, v235
	v_add_u32_e32 v198, 0x155a00, v197
	global_load_dwordx4 v[232:235], v198, s[22:23]
	s_mov_b32 s100, 0xbfb8aa3b
	v_lshlrev_b32_e32 v242, 16, v92
	v_and_b32_e32 v243, 0xffff0000, v92
	v_lshlrev_b32_e32 v244, 16, v94
	v_and_b32_e32 v245, 0xffff0000, v94
	v_lshlrev_b32_e32 v246, 16, v93
	v_and_b32_e32 v247, 0xffff0000, v93
	v_lshlrev_b32_e32 v248, 16, v95
	v_and_b32_e32 v249, 0xffff0000, v95
	v_pk_mul_f32 v[242:243], v[242:243], s[100:101] op_sel_hi:[1,0]
	v_pk_mul_f32 v[244:245], v[244:245], s[100:101] op_sel_hi:[1,0]
	v_pk_mul_f32 v[246:247], v[246:247], s[100:101] op_sel_hi:[1,0]
	v_pk_mul_f32 v[248:249], v[248:249], s[100:101] op_sel_hi:[1,0]
	v_exp_f32_e32 v242, v242
	v_exp_f32_e32 v243, v243
	v_exp_f32_e32 v244, v244
	v_exp_f32_e32 v245, v245
	v_exp_f32_e32 v246, v246
	v_exp_f32_e32 v247, v247
	v_exp_f32_e32 v248, v248
	v_exp_f32_e32 v249, v249
	s_nop 0
	v_pk_add_f32 v[242:243], v[242:243], 1.0 op_sel_hi:[1,0]
	v_pk_add_f32 v[244:245], v[244:245], 1.0 op_sel_hi:[1,0]
	v_pk_add_f32 v[246:247], v[246:247], 1.0 op_sel_hi:[1,0]
	v_pk_add_f32 v[248:249], v[248:249], 1.0 op_sel_hi:[1,0]
	v_rcp_f32_e32 v250, v242
	v_rcp_f32_e32 v251, v243
	s_nop 0
	v_pk_fma_f32 v[252:253], v[242:243], v[250:251], 1.0 op_sel_hi:[1,1,0] neg_lo:[1,0,0] neg_hi:[1,0,0]
	v_pk_fma_f32 v[250:251], v[252:253], v[250:251], v[250:251]
	v_pk_fma_f32 v[252:253], v[242:243], v[250:251], 1.0 op_sel_hi:[1,1,0] neg_lo:[1,0,0] neg_hi:[1,0,0]
	v_pk_fma_f32 v[254:255], v[252:253], v[250:251], v[250:251]
	v_pk_fma_f32 v[252:253], v[242:243], v[254:255], 1.0 op_sel_hi:[1,1,0] neg_lo:[1,0,0] neg_hi:[1,0,0]
	v_pk_fma_f32 v[254:255], v[252:253], v[250:251], v[254:255]
	v_div_fixup_f32 v242, v254, v242, 1.0
	v_div_fixup_f32 v243, v255, v243, 1.0
	v_rcp_f32_e32 v250, v244
	v_rcp_f32_e32 v251, v245
	s_nop 0
	v_pk_fma_f32 v[252:253], v[244:245], v[250:251], 1.0 op_sel_hi:[1,1,0] neg_lo:[1,0,0] neg_hi:[1,0,0]
	v_pk_fma_f32 v[250:251], v[252:253], v[250:251], v[250:251]
	v_pk_fma_f32 v[252:253], v[244:245], v[250:251], 1.0 op_sel_hi:[1,1,0] neg_lo:[1,0,0] neg_hi:[1,0,0]
	v_pk_fma_f32 v[254:255], v[252:253], v[250:251], v[250:251]
	v_pk_fma_f32 v[252:253], v[244:245], v[254:255], 1.0 op_sel_hi:[1,1,0] neg_lo:[1,0,0] neg_hi:[1,0,0]
	v_pk_fma_f32 v[254:255], v[252:253], v[250:251], v[254:255]
	v_div_fixup_f32 v244, v254, v244, 1.0
	v_div_fixup_f32 v245, v255, v245, 1.0
	v_rcp_f32_e32 v250, v246
	v_rcp_f32_e32 v251, v247
	s_nop 0
	v_pk_fma_f32 v[252:253], v[246:247], v[250:251], 1.0 op_sel_hi:[1,1,0] neg_lo:[1,0,0] neg_hi:[1,0,0]
	v_pk_fma_f32 v[250:251], v[252:253], v[250:251], v[250:251]
	v_pk_fma_f32 v[252:253], v[246:247], v[250:251], 1.0 op_sel_hi:[1,1,0] neg_lo:[1,0,0] neg_hi:[1,0,0]
	v_pk_fma_f32 v[254:255], v[252:253], v[250:251], v[250:251]
	v_pk_fma_f32 v[252:253], v[246:247], v[254:255], 1.0 op_sel_hi:[1,1,0] neg_lo:[1,0,0] neg_hi:[1,0,0]
	v_pk_fma_f32 v[254:255], v[252:253], v[250:251], v[254:255]
	v_div_fixup_f32 v246, v254, v246, 1.0
	v_div_fixup_f32 v247, v255, v247, 1.0
	v_rcp_f32_e32 v250, v248
	v_rcp_f32_e32 v251, v249
	s_nop 0
	v_pk_fma_f32 v[252:253], v[248:249], v[250:251], 1.0 op_sel_hi:[1,1,0] neg_lo:[1,0,0] neg_hi:[1,0,0]
	v_pk_fma_f32 v[250:251], v[252:253], v[250:251], v[250:251]
	v_pk_fma_f32 v[252:253], v[248:249], v[250:251], 1.0 op_sel_hi:[1,1,0] neg_lo:[1,0,0] neg_hi:[1,0,0]
	v_pk_fma_f32 v[254:255], v[252:253], v[250:251], v[250:251]
	v_pk_fma_f32 v[252:253], v[248:249], v[254:255], 1.0 op_sel_hi:[1,1,0] neg_lo:[1,0,0] neg_hi:[1,0,0]
	v_pk_fma_f32 v[254:255], v[252:253], v[250:251], v[254:255]
	v_div_fixup_f32 v248, v254, v248, 1.0
	v_div_fixup_f32 v249, v255, v249, 1.0
	global_store_dwordx4 v[96:97], v[88:91], off
	s_nop 0
	v_pk_mul_f32 v[84:85], v[84:85], v[242:243]
	v_pk_mul_f32 v[80:81], v[80:81], v[244:245]
	v_pk_mul_f32 v[86:87], v[86:87], v[246:247]
	v_pk_mul_f32 v[88:89], v[82:83], v[248:249]
	v_cvt_pk_bf16_f32 v82, v84, v85
	v_cvt_pk_bf16_f32 v83, v86, v87
	v_cvt_pk_bf16_f32 v84, v80, v81
	v_or_b32_e32 v80, 48, v160
	v_mad_i64_i32 v[80:81], s[6:7], v80, s57, v[146:147]
	v_lshl_add_u64 v[80:81], v[80:81], 0, v[148:149]
	v_add_co_u32_e32 v90, vcc, s58, v80
	v_cvt_pk_bf16_f32 v85, v88, v89
	global_store_dwordx4 v[96:97], v[82:85], off offset:256
	s_nop 0
	v_addc_co_u32_e32 v91, vcc, 0, v81, vcc
	s_waitcnt vmcnt(12)
; __device__ __forceinline__ u32x4 pack8(const f32x4 v0, const f32x4 v1) { u32x4 w; w.x = pk2(v0[0], v0[1]); w.y = pk2(v0[2], v0[3]); w.z = pk2(v1[0], v1[1]); w.w = pk2(v1[2], v1[3]); return w; }
; __device__ __forceinline__ void unpack8(const u32x4 w, f32x4& v0, f32x4& v1) { v0 = (f32x4){bflo(w.x), bfhi(w.x), bflo(w.y), bfhi(w.y)}; v1 = (f32x4){bflo(w.z), bfhi(w.z), bflo(w.w), bfhi(w.w)}; }
; __device__ __forceinline__ float sigmoidf_(float x) { return 1.0f / (1.0f + __expf(-x)); }
;     __device__ __forceinline__ void operator()(const f32x4 (&acc)[2][2][4][2], const Unit& u, int wr, int wc, int fr, int fq) const {
;     ...
;         for (int ai = 0; ai < 2; ++ai)
; #pragma unroll
;             for (int m = 0; m < 4; ++m) {
;                 bf16_t* rowp = z + (size_t)(row0 + ai * 128 + m * 16) * DIN + col0;
; #pragma unroll
;                 for (int bj = 0; bj < 2; ++bj) {
;                     const u32x4 gw = *(const u32x4*)(rowp + (MODE == 0 ? O_GB : O_GA) + bj * 128);
;                     f32x4 g0, g1; unpack8(gw, g0, g1);
;                     f32x4 v0, v1;
; #pragma unroll
;                     for (int j = 0; j < 4; ++j) { v0[j] = sigmoidf_(g0[j]) * acc[ai][bj][m][0][j]; v1[j] = sigmoidf_(g1[j]) * acc[ai][bj][m][1][j]; }
;                     if (MODE == 1) { const u32x4 mw = *(const u32x4*)(rowp + bj * 128); f32x4 m0, m1; unpack8(mw, m0, m1); v0 += m0; v1 += m1; }
;                     *(u32x4*)(rowp + bj * 128) = pack8(v0, v1); }
	v_mov_b32_e32 v86, v236
	v_mov_b32_e32 v87, v237
	v_mov_b32_e32 v88, v238
	v_mov_b32_e32 v89, v239
	v_add_u32_e32 v198, 0x155b00, v197
	global_load_dwordx4 v[236:239], v198, s[22:23]
	s_mov_b32 s100, 0xbfb8aa3b
	v_lshlrev_b32_e32 v242, 16, v86
	v_and_b32_e32 v243, 0xffff0000, v86
	v_lshlrev_b32_e32 v244, 16, v88
	v_and_b32_e32 v245, 0xffff0000, v88
	v_lshlrev_b32_e32 v246, 16, v87
	v_and_b32_e32 v247, 0xffff0000, v87
	v_lshlrev_b32_e32 v248, 16, v89
	v_and_b32_e32 v249, 0xffff0000, v89
	v_pk_mul_f32 v[242:243], v[242:243], s[100:101] op_sel_hi:[1,0]
	v_pk_mul_f32 v[244:245], v[244:245], s[100:101] op_sel_hi:[1,0]
	v_pk_mul_f32 v[246:247], v[246:247], s[100:101] op_sel_hi:[1,0]
	v_pk_mul_f32 v[248:249], v[248:249], s[100:101] op_sel_hi:[1,0]
	v_exp_f32_e32 v242, v242
	v_exp_f32_e32 v243, v243
	v_exp_f32_e32 v244, v244
	v_exp_f32_e32 v245, v245
	v_exp_f32_e32 v246, v246
	v_exp_f32_e32 v247, v247
	v_exp_f32_e32 v248, v248
	v_exp_f32_e32 v249, v249
	s_nop 0
	v_pk_add_f32 v[242:243], v[242:243], 1.0 op_sel_hi:[1,0]
	v_pk_add_f32 v[244:245], v[244:245], 1.0 op_sel_hi:[1,0]
	v_pk_add_f32 v[246:247], v[246:247], 1.0 op_sel_hi:[1,0]
	v_pk_add_f32 v[248:249], v[248:249], 1.0 op_sel_hi:[1,0]
	v_rcp_f32_e32 v250, v242
	v_rcp_f32_e32 v251, v243
	s_nop 0
	v_pk_fma_f32 v[252:253], v[242:243], v[250:251], 1.0 op_sel_hi:[1,1,0] neg_lo:[1,0,0] neg_hi:[1,0,0]
	v_pk_fma_f32 v[250:251], v[252:253], v[250:251], v[250:251]
	v_pk_fma_f32 v[252:253], v[242:243], v[250:251], 1.0 op_sel_hi:[1,1,0] neg_lo:[1,0,0] neg_hi:[1,0,0]
	v_pk_fma_f32 v[254:255], v[252:253], v[250:251], v[250:251]
	v_pk_fma_f32 v[252:253], v[242:243], v[254:255], 1.0 op_sel_hi:[1,1,0] neg_lo:[1,0,0] neg_hi:[1,0,0]
	v_pk_fma_f32 v[254:255], v[252:253], v[250:251], v[254:255]
	v_div_fixup_f32 v242, v254, v242, 1.0
	v_div_fixup_f32 v243, v255, v243, 1.0
	v_rcp_f32_e32 v250, v244
	v_rcp_f32_e32 v251, v245
	s_nop 0
	v_pk_fma_f32 v[252:253], v[244:245], v[250:251], 1.0 op_sel_hi:[1,1,0] neg_lo:[1,0,0] neg_hi:[1,0,0]
	v_pk_fma_f32 v[250:251], v[252:253], v[250:251], v[250:251]
	v_pk_fma_f32 v[252:253], v[244:245], v[250:251], 1.0 op_sel_hi:[1,1,0] neg_lo:[1,0,0] neg_hi:[1,0,0]
	v_pk_fma_f32 v[254:255], v[252:253], v[250:251], v[250:251]
	v_pk_fma_f32 v[252:253], v[244:245], v[254:255], 1.0 op_sel_hi:[1,1,0] neg_lo:[1,0,0] neg_hi:[1,0,0]
	v_pk_fma_f32 v[254:255], v[252:253], v[250:251], v[254:255]
	v_div_fixup_f32 v244, v254, v244, 1.0
	v_div_fixup_f32 v245, v255, v245, 1.0
	v_rcp_f32_e32 v250, v246
	v_rcp_f32_e32 v251, v247
	s_nop 0
	v_pk_fma_f32 v[252:253], v[246:247], v[250:251], 1.0 op_sel_hi:[1,1,0] neg_lo:[1,0,0] neg_hi:[1,0,0]
	v_pk_fma_f32 v[250:251], v[252:253], v[250:251], v[250:251]
	v_pk_fma_f32 v[252:253], v[246:247], v[250:251], 1.0 op_sel_hi:[1,1,0] neg_lo:[1,0,0] neg_hi:[1,0,0]
	v_pk_fma_f32 v[254:255], v[252:253], v[250:251], v[250:251]
	v_pk_fma_f32 v[252:253], v[246:247], v[254:255], 1.0 op_sel_hi:[1,1,0] neg_lo:[1,0,0] neg_hi:[1,0,0]
	v_pk_fma_f32 v[254:255], v[252:253], v[250:251], v[254:255]
	v_div_fixup_f32 v246, v254, v246, 1.0
	v_div_fixup_f32 v247, v255, v247, 1.0
	v_rcp_f32_e32 v250, v248
	v_rcp_f32_e32 v251, v249
	s_nop 0
	v_pk_fma_f32 v[252:253], v[248:249], v[250:251], 1.0 op_sel_hi:[1,1,0] neg_lo:[1,0,0] neg_hi:[1,0,0]
	v_pk_fma_f32 v[250:251], v[252:253], v[250:251], v[250:251]
	v_pk_fma_f32 v[252:253], v[248:249], v[250:251], 1.0 op_sel_hi:[1,1,0] neg_lo:[1,0,0] neg_hi:[1,0,0]
	v_pk_fma_f32 v[254:255], v[252:253], v[250:251], v[250:251]
	v_pk_fma_f32 v[252:253], v[248:249], v[254:255], 1.0 op_sel_hi:[1,1,0] neg_lo:[1,0,0] neg_hi:[1,0,0]
	v_pk_fma_f32 v[254:255], v[252:253], v[250:251], v[254:255]
	v_div_fixup_f32 v248, v254, v248, 1.0
	v_div_fixup_f32 v249, v255, v249, 1.0
	v_mul_f32_e32 v76, v76, v242
	v_mul_f32_e32 v82, v72, v244
	v_mul_f32_e32 v72, v77, v243
	v_mul_f32_e32 v77, v73, v245
	v_mul_f32_e32 v73, v78, v246
	v_mul_f32_e32 v78, v74, v248
	v_mul_f32_e32 v74, v79, v247
	v_mul_f32_e32 v75, v75, v249
	v_cvt_pk_bf16_f32 v72, v76, v72
	v_cvt_pk_bf16_f32 v73, v73, v74
	v_cvt_pk_bf16_f32 v74, v82, v77
	v_cvt_pk_bf16_f32 v75, v78, v75
	s_waitcnt vmcnt(12)
	v_mov_b32_e32 v76, v200
	v_mov_b32_e32 v77, v201
	v_mov_b32_e32 v78, v202
	v_mov_b32_e32 v79, v203
	v_add_u32_e32 v198, 0x177a00, v197
	global_load_dwordx4 v[200:203], v198, s[22:23]
	s_mov_b32 s100, 0xbfb8aa3b
	v_lshlrev_b32_e32 v242, 16, v76
	v_and_b32_e32 v243, 0xffff0000, v76
	v_lshlrev_b32_e32 v244, 16, v78
	v_and_b32_e32 v245, 0xffff0000, v78
	v_lshlrev_b32_e32 v246, 16, v77
	v_and_b32_e32 v247, 0xffff0000, v77
	v_lshlrev_b32_e32 v248, 16, v79
	v_and_b32_e32 v249, 0xffff0000, v79
	v_pk_mul_f32 v[242:243], v[242:243], s[100:101] op_sel_hi:[1,0]
	v_pk_mul_f32 v[244:245], v[244:245], s[100:101] op_sel_hi:[1,0]
	v_pk_mul_f32 v[246:247], v[246:247], s[100:101] op_sel_hi:[1,0]
	v_pk_mul_f32 v[248:249], v[248:249], s[100:101] op_sel_hi:[1,0]
	v_exp_f32_e32 v242, v242
	v_exp_f32_e32 v243, v243
	v_exp_f32_e32 v244, v244
	v_exp_f32_e32 v245, v245
	v_exp_f32_e32 v246, v246
	v_exp_f32_e32 v247, v247
	v_exp_f32_e32 v248, v248
	v_exp_f32_e32 v249, v249
	s_nop 0
	v_pk_add_f32 v[242:243], v[242:243], 1.0 op_sel_hi:[1,0]
	v_pk_add_f32 v[244:245], v[244:245], 1.0 op_sel_hi:[1,0]
	v_pk_add_f32 v[246:247], v[246:247], 1.0 op_sel_hi:[1,0]
	v_pk_add_f32 v[248:249], v[248:249], 1.0 op_sel_hi:[1,0]
	v_rcp_f32_e32 v250, v242
	v_rcp_f32_e32 v251, v243
	s_nop 0
	v_pk_fma_f32 v[252:253], v[242:243], v[250:251], 1.0 op_sel_hi:[1,1,0] neg_lo:[1,0,0] neg_hi:[1,0,0]
	v_pk_fma_f32 v[250:251], v[252:253], v[250:251], v[250:251]
	v_pk_fma_f32 v[252:253], v[242:243], v[250:251], 1.0 op_sel_hi:[1,1,0] neg_lo:[1,0,0] neg_hi:[1,0,0]
; __device__ __forceinline__ u32x4 pack8(const f32x4 v0, const f32x4 v1) { u32x4 w; w.x = pk2(v0[0], v0[1]); w.y = pk2(v0[2], v0[3]); w.z = pk2(v1[0], v1[1]); w.w = pk2(v1[2], v1[3]); return w; }
; __device__ __forceinline__ void unpack8(const u32x4 w, f32x4& v0, f32x4& v1) { v0 = (f32x4){bflo(w.x), bfhi(w.x), bflo(w.y), bfhi(w.y)}; v1 = (f32x4){bflo(w.z), bfhi(w.z), bflo(w.w), bfhi(w.w)}; }
; __device__ __forceinline__ float sigmoidf_(float x) { return 1.0f / (1.0f + __expf(-x)); }
;     __device__ __forceinline__ void operator()(const f32x4 (&acc)[2][2][4][2], const Unit& u, int wr, int wc, int fr, int fq) const {
;     ...
;         for (int ai = 0; ai < 2; ++ai)
; #pragma unroll
;             for (int m = 0; m < 4; ++m) {
;                 bf16_t* rowp = z + (size_t)(row0 + ai * 128 + m * 16) * DIN + col0;
; #pragma unroll
;                 for (int bj = 0; bj < 2; ++bj) {
;                     const u32x4 gw = *(const u32x4*)(rowp + (MODE == 0 ? O_GB : O_GA) + bj * 128);
;                     f32x4 g0, g1; unpack8(gw, g0, g1);
;                     f32x4 v0, v1;
; #pragma unroll
;                     for (int j = 0; j < 4; ++j) { v0[j] = sigmoidf_(g0[j]) * acc[ai][bj][m][0][j]; v1[j] = sigmoidf_(g1[j]) * acc[ai][bj][m][1][j]; }
;                     if (MODE == 1) { const u32x4 mw = *(const u32x4*)(rowp + bj * 128); f32x4 m0, m1; unpack8(mw, m0, m1); v0 += m0; v1 += m1; }
;                     *(u32x4*)(rowp + bj * 128) = pack8(v0, v1); }
	v_pk_fma_f32 v[254:255], v[252:253], v[250:251], v[250:251]
	v_pk_fma_f32 v[252:253], v[242:243], v[254:255], 1.0 op_sel_hi:[1,1,0] neg_lo:[1,0,0] neg_hi:[1,0,0]
	v_pk_fma_f32 v[254:255], v[252:253], v[250:251], v[254:255]
	v_div_fixup_f32 v242, v254, v242, 1.0
	v_div_fixup_f32 v243, v255, v243, 1.0
	v_rcp_f32_e32 v250, v244
	v_rcp_f32_e32 v251, v245
	s_nop 0
	v_pk_fma_f32 v[252:253], v[244:245], v[250:251], 1.0 op_sel_hi:[1,1,0] neg_lo:[1,0,0] neg_hi:[1,0,0]
	v_pk_fma_f32 v[250:251], v[252:253], v[250:251], v[250:251]
	v_pk_fma_f32 v[252:253], v[244:245], v[250:251], 1.0 op_sel_hi:[1,1,0] neg_lo:[1,0,0] neg_hi:[1,0,0]
	v_pk_fma_f32 v[254:255], v[252:253], v[250:251], v[250:251]
	v_pk_fma_f32 v[252:253], v[244:245], v[254:255], 1.0 op_sel_hi:[1,1,0] neg_lo:[1,0,0] neg_hi:[1,0,0]
	v_pk_fma_f32 v[254:255], v[252:253], v[250:251], v[254:255]
	v_div_fixup_f32 v244, v254, v244, 1.0
	v_div_fixup_f32 v245, v255, v245, 1.0
	v_rcp_f32_e32 v250, v246
	v_rcp_f32_e32 v251, v247
	s_nop 0
	v_pk_fma_f32 v[252:253], v[246:247], v[250:251], 1.0 op_sel_hi:[1,1,0] neg_lo:[1,0,0] neg_hi:[1,0,0]
	v_pk_fma_f32 v[250:251], v[252:253], v[250:251], v[250:251]
	v_pk_fma_f32 v[252:253], v[246:247], v[250:251], 1.0 op_sel_hi:[1,1,0] neg_lo:[1,0,0] neg_hi:[1,0,0]
	v_pk_fma_f32 v[254:255], v[252:253], v[250:251], v[250:251]
	v_pk_fma_f32 v[252:253], v[246:247], v[254:255], 1.0 op_sel_hi:[1,1,0] neg_lo:[1,0,0] neg_hi:[1,0,0]
	v_pk_fma_f32 v[254:255], v[252:253], v[250:251], v[254:255]
	v_div_fixup_f32 v246, v254, v246, 1.0
	v_div_fixup_f32 v247, v255, v247, 1.0
	v_rcp_f32_e32 v250, v248
	v_rcp_f32_e32 v251, v249
	s_nop 0
	v_pk_fma_f32 v[252:253], v[248:249], v[250:251], 1.0 op_sel_hi:[1,1,0] neg_lo:[1,0,0] neg_hi:[1,0,0]
	v_pk_fma_f32 v[250:251], v[252:253], v[250:251], v[250:251]
	v_pk_fma_f32 v[252:253], v[248:249], v[250:251], 1.0 op_sel_hi:[1,1,0] neg_lo:[1,0,0] neg_hi:[1,0,0]
	v_pk_fma_f32 v[254:255], v[252:253], v[250:251], v[250:251]
	v_pk_fma_f32 v[252:253], v[248:249], v[254:255], 1.0 op_sel_hi:[1,1,0] neg_lo:[1,0,0] neg_hi:[1,0,0]
	v_pk_fma_f32 v[254:255], v[252:253], v[250:251], v[254:255]
	v_div_fixup_f32 v248, v254, v248, 1.0
	v_div_fixup_f32 v249, v255, v249, 1.0
	global_store_dwordx4 v[80:81], v[72:75], off
	s_nop 0
	v_pk_mul_f32 v[68:69], v[68:69], v[242:243]
	v_pk_mul_f32 v[64:65], v[64:65], v[244:245]
	v_pk_mul_f32 v[70:71], v[70:71], v[246:247]
	v_pk_mul_f32 v[72:73], v[66:67], v[248:249]
	v_cvt_pk_bf16_f32 v66, v68, v69
	v_cvt_pk_bf16_f32 v67, v70, v71
	v_cvt_pk_bf16_f32 v68, v64, v65
	v_add_u32_e32 v64, 0x80, v160
	v_mad_i64_i32 v[64:65], s[6:7], v64, s57, v[146:147]
	v_lshl_add_u64 v[64:65], v[64:65], 0, v[148:149]
	v_add_co_u32_e32 v74, vcc, s58, v64
	v_cvt_pk_bf16_f32 v69, v72, v73
	global_store_dwordx4 v[80:81], v[66:69], off offset:256
	s_nop 0
	v_addc_co_u32_e32 v75, vcc, 0, v65, vcc
	s_waitcnt vmcnt(13)
	v_mov_b32_e32 v70, v204
	v_mov_b32_e32 v71, v205
	v_mov_b32_e32 v72, v206
	v_mov_b32_e32 v73, v207
	v_add_u32_e32 v198, 0x177b00, v197
	global_load_dwordx4 v[204:207], v198, s[22:23]
	s_mov_b32 s100, 0xbfb8aa3b
	v_lshlrev_b32_e32 v242, 16, v70
	v_and_b32_e32 v243, 0xffff0000, v70
	v_lshlrev_b32_e32 v244, 16, v72
	v_and_b32_e32 v245, 0xffff0000, v72
	v_lshlrev_b32_e32 v246, 16, v71
	v_and_b32_e32 v247, 0xffff0000, v71
	v_lshlrev_b32_e32 v248, 16, v73
	v_and_b32_e32 v249, 0xffff0000, v73
	v_pk_mul_f32 v[242:243], v[242:243], s[100:101] op_sel_hi:[1,0]
	v_pk_mul_f32 v[244:245], v[244:245], s[100:101] op_sel_hi:[1,0]
	v_pk_mul_f32 v[246:247], v[246:247], s[100:101] op_sel_hi:[1,0]
	v_pk_mul_f32 v[248:249], v[248:249], s[100:101] op_sel_hi:[1,0]
	v_exp_f32_e32 v242, v242
	v_exp_f32_e32 v243, v243
	v_exp_f32_e32 v244, v244
	v_exp_f32_e32 v245, v245
	v_exp_f32_e32 v246, v246
	v_exp_f32_e32 v247, v247
	v_exp_f32_e32 v248, v248
	v_exp_f32_e32 v249, v249
	s_nop 0
	v_pk_add_f32 v[242:243], v[242:243], 1.0 op_sel_hi:[1,0]
	v_pk_add_f32 v[244:245], v[244:245], 1.0 op_sel_hi:[1,0]
	v_pk_add_f32 v[246:247], v[246:247], 1.0 op_sel_hi:[1,0]
	v_pk_add_f32 v[248:249], v[248:249], 1.0 op_sel_hi:[1,0]
	v_rcp_f32_e32 v250, v242
	v_rcp_f32_e32 v251, v243
	s_nop 0
	v_pk_fma_f32 v[252:253], v[242:243], v[250:251], 1.0 op_sel_hi:[1,1,0] neg_lo:[1,0,0] neg_hi:[1,0,0]
	v_pk_fma_f32 v[250:251], v[252:253], v[250:251], v[250:251]
	v_pk_fma_f32 v[252:253], v[242:243], v[250:251], 1.0 op_sel_hi:[1,1,0] neg_lo:[1,0,0] neg_hi:[1,0,0]
	v_pk_fma_f32 v[254:255], v[252:253], v[250:251], v[250:251]
	v_pk_fma_f32 v[252:253], v[242:243], v[254:255], 1.0 op_sel_hi:[1,1,0] neg_lo:[1,0,0] neg_hi:[1,0,0]
	v_pk_fma_f32 v[254:255], v[252:253], v[250:251], v[254:255]
	v_div_fixup_f32 v242, v254, v242, 1.0
	v_div_fixup_f32 v243, v255, v243, 1.0
	v_rcp_f32_e32 v250, v244
	v_rcp_f32_e32 v251, v245
	s_nop 0
	v_pk_fma_f32 v[252:253], v[244:245], v[250:251], 1.0 op_sel_hi:[1,1,0] neg_lo:[1,0,0] neg_hi:[1,0,0]
	v_pk_fma_f32 v[250:251], v[252:253], v[250:251], v[250:251]
	v_pk_fma_f32 v[252:253], v[244:245], v[250:251], 1.0 op_sel_hi:[1,1,0] neg_lo:[1,0,0] neg_hi:[1,0,0]
	v_pk_fma_f32 v[254:255], v[252:253], v[250:251], v[250:251]
	v_pk_fma_f32 v[252:253], v[244:245], v[254:255], 1.0 op_sel_hi:[1,1,0] neg_lo:[1,0,0] neg_hi:[1,0,0]
	v_pk_fma_f32 v[254:255], v[252:253], v[250:251], v[254:255]
	v_div_fixup_f32 v244, v254, v244, 1.0
	v_div_fixup_f32 v245, v255, v245, 1.0
	v_rcp_f32_e32 v250, v246
	v_rcp_f32_e32 v251, v247
	s_nop 0
	v_pk_fma_f32 v[252:253], v[246:247], v[250:251], 1.0 op_sel_hi:[1,1,0] neg_lo:[1,0,0] neg_hi:[1,0,0]
	v_pk_fma_f32 v[250:251], v[252:253], v[250:251], v[250:251]
	v_pk_fma_f32 v[252:253], v[246:247], v[250:251], 1.0 op_sel_hi:[1,1,0] neg_lo:[1,0,0] neg_hi:[1,0,0]
	v_pk_fma_f32 v[254:255], v[252:253], v[250:251], v[250:251]
	v_pk_fma_f32 v[252:253], v[246:247], v[254:255], 1.0 op_sel_hi:[1,1,0] neg_lo:[1,0,0] neg_hi:[1,0,0]
	v_pk_fma_f32 v[254:255], v[252:253], v[250:251], v[254:255]
	v_div_fixup_f32 v246, v254, v246, 1.0
	v_div_fixup_f32 v247, v255, v247, 1.0
	v_rcp_f32_e32 v250, v248
	v_rcp_f32_e32 v251, v249
	s_nop 0
	v_pk_fma_f32 v[252:253], v[248:249], v[250:251], 1.0 op_sel_hi:[1,1,0] neg_lo:[1,0,0] neg_hi:[1,0,0]
	v_pk_fma_f32 v[250:251], v[252:253], v[250:251], v[250:251]
	v_pk_fma_f32 v[252:253], v[248:249], v[250:251], 1.0 op_sel_hi:[1,1,0] neg_lo:[1,0,0] neg_hi:[1,0,0]
	v_pk_fma_f32 v[254:255], v[252:253], v[250:251], v[250:251]
	v_pk_fma_f32 v[252:253], v[248:249], v[254:255], 1.0 op_sel_hi:[1,1,0] neg_lo:[1,0,0] neg_hi:[1,0,0]
	v_pk_fma_f32 v[254:255], v[252:253], v[250:251], v[254:255]
	v_div_fixup_f32 v248, v254, v248, 1.0
	v_div_fixup_f32 v249, v255, v249, 1.0
	v_mul_f32_e32 v60, v60, v242
	v_mul_f32_e32 v66, v56, v244
	v_mul_f32_e32 v56, v61, v243
	v_mul_f32_e32 v61, v57, v245
	v_mul_f32_e32 v57, v62, v246
	v_mul_f32_e32 v62, v58, v248
	v_mul_f32_e32 v58, v63, v247
	v_mul_f32_e32 v59, v59, v249
	v_cvt_pk_bf16_f32 v56, v60, v56
	v_cvt_pk_bf16_f32 v57, v57, v58
	v_cvt_pk_bf16_f32 v58, v66, v61
	v_cvt_pk_bf16_f32 v59, v62, v59
	s_waitcnt vmcnt(12)
; __device__ __forceinline__ u32x4 pack8(const f32x4 v0, const f32x4 v1) { u32x4 w; w.x = pk2(v0[0], v0[1]); w.y = pk2(v0[2], v0[3]); w.z = pk2(v1[0], v1[1]); w.w = pk2(v1[2], v1[3]); return w; }
; __device__ __forceinline__ void unpack8(const u32x4 w, f32x4& v0, f32x4& v1) { v0 = (f32x4){bflo(w.x), bfhi(w.x), bflo(w.y), bfhi(w.y)}; v1 = (f32x4){bflo(w.z), bfhi(w.z), bflo(w.w), bfhi(w.w)}; }
; __device__ __forceinline__ float sigmoidf_(float x) { return 1.0f / (1.0f + __expf(-x)); }
;     __device__ __forceinline__ void operator()(const f32x4 (&acc)[2][2][4][2], const Unit& u, int wr, int wc, int fr, int fq) const {
;     ...
;         for (int ai = 0; ai < 2; ++ai)
; #pragma unroll
;             for (int m = 0; m < 4; ++m) {
;                 bf16_t* rowp = z + (size_t)(row0 + ai * 128 + m * 16) * DIN + col0;
; #pragma unroll
;                 for (int bj = 0; bj < 2; ++bj) {
;                     const u32x4 gw = *(const u32x4*)(rowp + (MODE == 0 ? O_GB : O_GA) + bj * 128);
;                     f32x4 g0, g1; unpack8(gw, g0, g1);
;                     f32x4 v0, v1;
; #pragma unroll
;                     for (int j = 0; j < 4; ++j) { v0[j] = sigmoidf_(g0[j]) * acc[ai][bj][m][0][j]; v1[j] = sigmoidf_(g1[j]) * acc[ai][bj][m][1][j]; }
;                     if (MODE == 1) { const u32x4 mw = *(const u32x4*)(rowp + bj * 128); f32x4 m0, m1; unpack8(mw, m0, m1); v0 += m0; v1 += m1; }
;                     *(u32x4*)(rowp + bj * 128) = pack8(v0, v1); }
	v_mov_b32_e32 v60, v208
	v_mov_b32_e32 v61, v209
	v_mov_b32_e32 v62, v210
	v_mov_b32_e32 v63, v211
	s_mov_b32 s100, 0xbfb8aa3b
	v_lshlrev_b32_e32 v242, 16, v60
	v_and_b32_e32 v243, 0xffff0000, v60
	v_lshlrev_b32_e32 v244, 16, v62
	v_and_b32_e32 v245, 0xffff0000, v62
	v_lshlrev_b32_e32 v246, 16, v61
	v_and_b32_e32 v247, 0xffff0000, v61
	v_lshlrev_b32_e32 v248, 16, v63
	v_and_b32_e32 v249, 0xffff0000, v63
	v_pk_mul_f32 v[242:243], v[242:243], s[100:101] op_sel_hi:[1,0]
	v_pk_mul_f32 v[244:245], v[244:245], s[100:101] op_sel_hi:[1,0]
	v_pk_mul_f32 v[246:247], v[246:247], s[100:101] op_sel_hi:[1,0]
	v_pk_mul_f32 v[248:249], v[248:249], s[100:101] op_sel_hi:[1,0]
	v_exp_f32_e32 v242, v242
	v_exp_f32_e32 v243, v243
	v_exp_f32_e32 v244, v244
	v_exp_f32_e32 v245, v245
	v_exp_f32_e32 v246, v246
	v_exp_f32_e32 v247, v247
	v_exp_f32_e32 v248, v248
	v_exp_f32_e32 v249, v249
	s_nop 0
	v_pk_add_f32 v[242:243], v[242:243], 1.0 op_sel_hi:[1,0]
	v_pk_add_f32 v[244:245], v[244:245], 1.0 op_sel_hi:[1,0]
	v_pk_add_f32 v[246:247], v[246:247], 1.0 op_sel_hi:[1,0]
	v_pk_add_f32 v[248:249], v[248:249], 1.0 op_sel_hi:[1,0]
	v_rcp_f32_e32 v250, v242
	v_rcp_f32_e32 v251, v243
	s_nop 0
	v_pk_fma_f32 v[252:253], v[242:243], v[250:251], 1.0 op_sel_hi:[1,1,0] neg_lo:[1,0,0] neg_hi:[1,0,0]
	v_pk_fma_f32 v[250:251], v[252:253], v[250:251], v[250:251]
	v_pk_fma_f32 v[252:253], v[242:243], v[250:251], 1.0 op_sel_hi:[1,1,0] neg_lo:[1,0,0] neg_hi:[1,0,0]
	v_pk_fma_f32 v[254:255], v[252:253], v[250:251], v[250:251]
	v_pk_fma_f32 v[252:253], v[242:243], v[254:255], 1.0 op_sel_hi:[1,1,0] neg_lo:[1,0,0] neg_hi:[1,0,0]
	v_pk_fma_f32 v[254:255], v[252:253], v[250:251], v[254:255]
	v_div_fixup_f32 v242, v254, v242, 1.0
	v_div_fixup_f32 v243, v255, v243, 1.0
	v_rcp_f32_e32 v250, v244
	v_rcp_f32_e32 v251, v245
	s_nop 0
	v_pk_fma_f32 v[252:253], v[244:245], v[250:251], 1.0 op_sel_hi:[1,1,0] neg_lo:[1,0,0] neg_hi:[1,0,0]
	v_pk_fma_f32 v[250:251], v[252:253], v[250:251], v[250:251]
	v_pk_fma_f32 v[252:253], v[244:245], v[250:251], 1.0 op_sel_hi:[1,1,0] neg_lo:[1,0,0] neg_hi:[1,0,0]
	v_pk_fma_f32 v[254:255], v[252:253], v[250:251], v[250:251]
	v_pk_fma_f32 v[252:253], v[244:245], v[254:255], 1.0 op_sel_hi:[1,1,0] neg_lo:[1,0,0] neg_hi:[1,0,0]
	v_pk_fma_f32 v[254:255], v[252:253], v[250:251], v[254:255]
	v_div_fixup_f32 v244, v254, v244, 1.0
	v_div_fixup_f32 v245, v255, v245, 1.0
	v_rcp_f32_e32 v250, v246
	v_rcp_f32_e32 v251, v247
	s_nop 0
	v_pk_fma_f32 v[252:253], v[246:247], v[250:251], 1.0 op_sel_hi:[1,1,0] neg_lo:[1,0,0] neg_hi:[1,0,0]
	v_pk_fma_f32 v[250:251], v[252:253], v[250:251], v[250:251]
	v_pk_fma_f32 v[252:253], v[246:247], v[250:251], 1.0 op_sel_hi:[1,1,0] neg_lo:[1,0,0] neg_hi:[1,0,0]
	v_pk_fma_f32 v[254:255], v[252:253], v[250:251], v[250:251]
	v_pk_fma_f32 v[252:253], v[246:247], v[254:255], 1.0 op_sel_hi:[1,1,0] neg_lo:[1,0,0] neg_hi:[1,0,0]
	v_pk_fma_f32 v[254:255], v[252:253], v[250:251], v[254:255]
	v_div_fixup_f32 v246, v254, v246, 1.0
	v_div_fixup_f32 v247, v255, v247, 1.0
	v_rcp_f32_e32 v250, v248
	v_rcp_f32_e32 v251, v249
	s_nop 0
	v_pk_fma_f32 v[252:253], v[248:249], v[250:251], 1.0 op_sel_hi:[1,1,0] neg_lo:[1,0,0] neg_hi:[1,0,0]
	v_pk_fma_f32 v[250:251], v[252:253], v[250:251], v[250:251]
	v_pk_fma_f32 v[252:253], v[248:249], v[250:251], 1.0 op_sel_hi:[1,1,0] neg_lo:[1,0,0] neg_hi:[1,0,0]
	v_pk_fma_f32 v[254:255], v[252:253], v[250:251], v[250:251]
	v_pk_fma_f32 v[252:253], v[248:249], v[254:255], 1.0 op_sel_hi:[1,1,0] neg_lo:[1,0,0] neg_hi:[1,0,0]
	v_pk_fma_f32 v[254:255], v[252:253], v[250:251], v[254:255]
	v_div_fixup_f32 v248, v254, v248, 1.0
	v_div_fixup_f32 v249, v255, v249, 1.0
	global_store_dwordx4 v[64:65], v[56:59], off
	s_nop 0
	v_pk_mul_f32 v[52:53], v[52:53], v[242:243]
	v_pk_mul_f32 v[48:49], v[48:49], v[244:245]
	v_pk_mul_f32 v[54:55], v[54:55], v[246:247]
	v_pk_mul_f32 v[56:57], v[50:51], v[248:249]
	v_cvt_pk_bf16_f32 v50, v52, v53
	v_cvt_pk_bf16_f32 v51, v54, v55
	v_cvt_pk_bf16_f32 v52, v48, v49
	v_add_u32_e32 v48, 0x90, v160
	v_mad_i64_i32 v[48:49], s[6:7], v48, s57, v[146:147]
	v_lshl_add_u64 v[48:49], v[48:49], 0, v[148:149]
	v_add_co_u32_e32 v58, vcc, s58, v48
	v_cvt_pk_bf16_f32 v53, v56, v57
	global_store_dwordx4 v[64:65], v[50:53], off offset:256
	s_nop 0
	v_addc_co_u32_e32 v59, vcc, 0, v49, vcc
	s_waitcnt vmcnt(13)
; __device__ __forceinline__ u32x4 pack8(const f32x4 v0, const f32x4 v1) { u32x4 w; w.x = pk2(v0[0], v0[1]); w.y = pk2(v0[2], v0[3]); w.z = pk2(v1[0], v1[1]); w.w = pk2(v1[2], v1[3]); return w; }
; __device__ __forceinline__ void unpack8(const u32x4 w, f32x4& v0, f32x4& v1) { v0 = (f32x4){bflo(w.x), bfhi(w.x), bflo(w.y), bfhi(w.y)}; v1 = (f32x4){bflo(w.z), bfhi(w.z), bflo(w.w), bfhi(w.w)}; }
; __device__ __forceinline__ float sigmoidf_(float x) { return 1.0f / (1.0f + __expf(-x)); }
;     __device__ __forceinline__ void operator()(const f32x4 (&acc)[2][2][4][2], const Unit& u, int wr, int wc, int fr, int fq) const {
;     ...
;         for (int ai = 0; ai < 2; ++ai)
; #pragma unroll
;             for (int m = 0; m < 4; ++m) {
;                 bf16_t* rowp = z + (size_t)(row0 + ai * 128 + m * 16) * DIN + col0;
; #pragma unroll
;                 for (int bj = 0; bj < 2; ++bj) {
;                     const u32x4 gw = *(const u32x4*)(rowp + (MODE == 0 ? O_GB : O_GA) + bj * 128);
;                     f32x4 g0, g1; unpack8(gw, g0, g1);
;                     f32x4 v0, v1;
; #pragma unroll
;                     for (int j = 0; j < 4; ++j) { v0[j] = sigmoidf_(g0[j]) * acc[ai][bj][m][0][j]; v1[j] = sigmoidf_(g1[j]) * acc[ai][bj][m][1][j]; }
;                     if (MODE == 1) { const u32x4 mw = *(const u32x4*)(rowp + bj * 128); f32x4 m0, m1; unpack8(mw, m0, m1); v0 += m0; v1 += m1; }
;                     *(u32x4*)(rowp + bj * 128) = pack8(v0, v1); }
	v_mov_b32_e32 v54, v212
	v_mov_b32_e32 v55, v213
	v_mov_b32_e32 v56, v214
	v_mov_b32_e32 v57, v215
	s_mov_b32 s100, 0xbfb8aa3b
	v_lshlrev_b32_e32 v242, 16, v54
	v_and_b32_e32 v243, 0xffff0000, v54
	v_lshlrev_b32_e32 v244, 16, v56
	v_and_b32_e32 v245, 0xffff0000, v56
	v_lshlrev_b32_e32 v246, 16, v55
	v_and_b32_e32 v247, 0xffff0000, v55
	v_lshlrev_b32_e32 v248, 16, v57
	v_and_b32_e32 v249, 0xffff0000, v57
	v_pk_mul_f32 v[242:243], v[242:243], s[100:101] op_sel_hi:[1,0]
	v_pk_mul_f32 v[244:245], v[244:245], s[100:101] op_sel_hi:[1,0]
	v_pk_mul_f32 v[246:247], v[246:247], s[100:101] op_sel_hi:[1,0]
	v_pk_mul_f32 v[248:249], v[248:249], s[100:101] op_sel_hi:[1,0]
	v_exp_f32_e32 v242, v242
	v_exp_f32_e32 v243, v243
	v_exp_f32_e32 v244, v244
	v_exp_f32_e32 v245, v245
	v_exp_f32_e32 v246, v246
	v_exp_f32_e32 v247, v247
	v_exp_f32_e32 v248, v248
	v_exp_f32_e32 v249, v249
	s_nop 0
	v_pk_add_f32 v[242:243], v[242:243], 1.0 op_sel_hi:[1,0]
	v_pk_add_f32 v[244:245], v[244:245], 1.0 op_sel_hi:[1,0]
	v_pk_add_f32 v[246:247], v[246:247], 1.0 op_sel_hi:[1,0]
	v_pk_add_f32 v[248:249], v[248:249], 1.0 op_sel_hi:[1,0]
	v_rcp_f32_e32 v250, v242
	v_rcp_f32_e32 v251, v243
	s_nop 0
	v_pk_fma_f32 v[252:253], v[242:243], v[250:251], 1.0 op_sel_hi:[1,1,0] neg_lo:[1,0,0] neg_hi:[1,0,0]
	v_pk_fma_f32 v[250:251], v[252:253], v[250:251], v[250:251]
	v_pk_fma_f32 v[252:253], v[242:243], v[250:251], 1.0 op_sel_hi:[1,1,0] neg_lo:[1,0,0] neg_hi:[1,0,0]
	v_pk_fma_f32 v[254:255], v[252:253], v[250:251], v[250:251]
	v_pk_fma_f32 v[252:253], v[242:243], v[254:255], 1.0 op_sel_hi:[1,1,0] neg_lo:[1,0,0] neg_hi:[1,0,0]
	v_pk_fma_f32 v[254:255], v[252:253], v[250:251], v[254:255]
	v_div_fixup_f32 v242, v254, v242, 1.0
	v_div_fixup_f32 v243, v255, v243, 1.0
	v_rcp_f32_e32 v250, v244
	v_rcp_f32_e32 v251, v245
	s_nop 0
	v_pk_fma_f32 v[252:253], v[244:245], v[250:251], 1.0 op_sel_hi:[1,1,0] neg_lo:[1,0,0] neg_hi:[1,0,0]
	v_pk_fma_f32 v[250:251], v[252:253], v[250:251], v[250:251]
	v_pk_fma_f32 v[252:253], v[244:245], v[250:251], 1.0 op_sel_hi:[1,1,0] neg_lo:[1,0,0] neg_hi:[1,0,0]
	v_pk_fma_f32 v[254:255], v[252:253], v[250:251], v[250:251]
	v_pk_fma_f32 v[252:253], v[244:245], v[254:255], 1.0 op_sel_hi:[1,1,0] neg_lo:[1,0,0] neg_hi:[1,0,0]
	v_pk_fma_f32 v[254:255], v[252:253], v[250:251], v[254:255]
	v_div_fixup_f32 v244, v254, v244, 1.0
	v_div_fixup_f32 v245, v255, v245, 1.0
	v_rcp_f32_e32 v250, v246
	v_rcp_f32_e32 v251, v247
	s_nop 0
	v_pk_fma_f32 v[252:253], v[246:247], v[250:251], 1.0 op_sel_hi:[1,1,0] neg_lo:[1,0,0] neg_hi:[1,0,0]
	v_pk_fma_f32 v[250:251], v[252:253], v[250:251], v[250:251]
	v_pk_fma_f32 v[252:253], v[246:247], v[250:251], 1.0 op_sel_hi:[1,1,0] neg_lo:[1,0,0] neg_hi:[1,0,0]
	v_pk_fma_f32 v[254:255], v[252:253], v[250:251], v[250:251]
	v_pk_fma_f32 v[252:253], v[246:247], v[254:255], 1.0 op_sel_hi:[1,1,0] neg_lo:[1,0,0] neg_hi:[1,0,0]
	v_pk_fma_f32 v[254:255], v[252:253], v[250:251], v[254:255]
	v_div_fixup_f32 v246, v254, v246, 1.0
	v_div_fixup_f32 v247, v255, v247, 1.0
	v_rcp_f32_e32 v250, v248
	v_rcp_f32_e32 v251, v249
	s_nop 0
	v_pk_fma_f32 v[252:253], v[248:249], v[250:251], 1.0 op_sel_hi:[1,1,0] neg_lo:[1,0,0] neg_hi:[1,0,0]
	v_pk_fma_f32 v[250:251], v[252:253], v[250:251], v[250:251]
	v_pk_fma_f32 v[252:253], v[248:249], v[250:251], 1.0 op_sel_hi:[1,1,0] neg_lo:[1,0,0] neg_hi:[1,0,0]
	v_pk_fma_f32 v[254:255], v[252:253], v[250:251], v[250:251]
	v_pk_fma_f32 v[252:253], v[248:249], v[254:255], 1.0 op_sel_hi:[1,1,0] neg_lo:[1,0,0] neg_hi:[1,0,0]
	v_pk_fma_f32 v[254:255], v[252:253], v[250:251], v[254:255]
	v_div_fixup_f32 v248, v254, v248, 1.0
	v_div_fixup_f32 v249, v255, v249, 1.0
	v_mul_f32_e32 v44, v44, v242
	v_mul_f32_e32 v50, v40, v244
	v_mul_f32_e32 v40, v45, v243
	v_mul_f32_e32 v45, v41, v245
	v_mul_f32_e32 v41, v46, v246
	v_mul_f32_e32 v46, v42, v248
	v_mul_f32_e32 v42, v47, v247
	v_mul_f32_e32 v43, v43, v249
	v_cvt_pk_bf16_f32 v40, v44, v40
	v_cvt_pk_bf16_f32 v41, v41, v42
	v_cvt_pk_bf16_f32 v42, v50, v45
	v_cvt_pk_bf16_f32 v43, v46, v43
	s_waitcnt vmcnt(10)
	v_mov_b32_e32 v44, v216
	v_mov_b32_e32 v45, v217
	v_mov_b32_e32 v46, v218
	v_mov_b32_e32 v47, v219
	s_mov_b32 s100, 0xbfb8aa3b
	v_lshlrev_b32_e32 v242, 16, v44
	v_and_b32_e32 v243, 0xffff0000, v44
	v_lshlrev_b32_e32 v244, 16, v46
	v_and_b32_e32 v245, 0xffff0000, v46
	v_lshlrev_b32_e32 v246, 16, v45
	v_and_b32_e32 v247, 0xffff0000, v45
	v_lshlrev_b32_e32 v248, 16, v47
	v_and_b32_e32 v249, 0xffff0000, v47
	v_pk_mul_f32 v[242:243], v[242:243], s[100:101] op_sel_hi:[1,0]
	v_pk_mul_f32 v[244:245], v[244:245], s[100:101] op_sel_hi:[1,0]
	v_pk_mul_f32 v[246:247], v[246:247], s[100:101] op_sel_hi:[1,0]
	v_pk_mul_f32 v[248:249], v[248:249], s[100:101] op_sel_hi:[1,0]
	v_exp_f32_e32 v242, v242
	v_exp_f32_e32 v243, v243
	v_exp_f32_e32 v244, v244
	v_exp_f32_e32 v245, v245
	v_exp_f32_e32 v246, v246
	v_exp_f32_e32 v247, v247
	v_exp_f32_e32 v248, v248
	v_exp_f32_e32 v249, v249
	s_nop 0
	v_pk_add_f32 v[242:243], v[242:243], 1.0 op_sel_hi:[1,0]
	v_pk_add_f32 v[244:245], v[244:245], 1.0 op_sel_hi:[1,0]
	v_pk_add_f32 v[246:247], v[246:247], 1.0 op_sel_hi:[1,0]
	v_pk_add_f32 v[248:249], v[248:249], 1.0 op_sel_hi:[1,0]
	v_rcp_f32_e32 v250, v242
	v_rcp_f32_e32 v251, v243
	s_nop 0
	v_pk_fma_f32 v[252:253], v[242:243], v[250:251], 1.0 op_sel_hi:[1,1,0] neg_lo:[1,0,0] neg_hi:[1,0,0]
	v_pk_fma_f32 v[250:251], v[252:253], v[250:251], v[250:251]
	v_pk_fma_f32 v[252:253], v[242:243], v[250:251], 1.0 op_sel_hi:[1,1,0] neg_lo:[1,0,0] neg_hi:[1,0,0]
	v_pk_fma_f32 v[254:255], v[252:253], v[250:251], v[250:251]
	v_pk_fma_f32 v[252:253], v[242:243], v[254:255], 1.0 op_sel_hi:[1,1,0] neg_lo:[1,0,0] neg_hi:[1,0,0]
; __device__ __forceinline__ u32x4 pack8(const f32x4 v0, const f32x4 v1) { u32x4 w; w.x = pk2(v0[0], v0[1]); w.y = pk2(v0[2], v0[3]); w.z = pk2(v1[0], v1[1]); w.w = pk2(v1[2], v1[3]); return w; }
; __device__ __forceinline__ void unpack8(const u32x4 w, f32x4& v0, f32x4& v1) { v0 = (f32x4){bflo(w.x), bfhi(w.x), bflo(w.y), bfhi(w.y)}; v1 = (f32x4){bflo(w.z), bfhi(w.z), bflo(w.w), bfhi(w.w)}; }
; __device__ __forceinline__ float sigmoidf_(float x) { return 1.0f / (1.0f + __expf(-x)); }
;     __device__ __forceinline__ void operator()(const f32x4 (&acc)[2][2][4][2], const Unit& u, int wr, int wc, int fr, int fq) const {
;     ...
;         for (int ai = 0; ai < 2; ++ai)
; #pragma unroll
;             for (int m = 0; m < 4; ++m) {
;                 bf16_t* rowp = z + (size_t)(row0 + ai * 128 + m * 16) * DIN + col0;
; #pragma unroll
;                 for (int bj = 0; bj < 2; ++bj) {
;                     const u32x4 gw = *(const u32x4*)(rowp + (MODE == 0 ? O_GB : O_GA) + bj * 128);
;                     f32x4 g0, g1; unpack8(gw, g0, g1);
;                     f32x4 v0, v1;
; #pragma unroll
;                     for (int j = 0; j < 4; ++j) { v0[j] = sigmoidf_(g0[j]) * acc[ai][bj][m][0][j]; v1[j] = sigmoidf_(g1[j]) * acc[ai][bj][m][1][j]; }
;                     if (MODE == 1) { const u32x4 mw = *(const u32x4*)(rowp + bj * 128); f32x4 m0, m1; unpack8(mw, m0, m1); v0 += m0; v1 += m1; }
;                     *(u32x4*)(rowp + bj * 128) = pack8(v0, v1); }
	v_pk_fma_f32 v[254:255], v[252:253], v[250:251], v[254:255]
	v_div_fixup_f32 v242, v254, v242, 1.0
	v_div_fixup_f32 v243, v255, v243, 1.0
	v_rcp_f32_e32 v250, v244
	v_rcp_f32_e32 v251, v245
	s_nop 0
	v_pk_fma_f32 v[252:253], v[244:245], v[250:251], 1.0 op_sel_hi:[1,1,0] neg_lo:[1,0,0] neg_hi:[1,0,0]
	v_pk_fma_f32 v[250:251], v[252:253], v[250:251], v[250:251]
	v_pk_fma_f32 v[252:253], v[244:245], v[250:251], 1.0 op_sel_hi:[1,1,0] neg_lo:[1,0,0] neg_hi:[1,0,0]
	v_pk_fma_f32 v[254:255], v[252:253], v[250:251], v[250:251]
	v_pk_fma_f32 v[252:253], v[244:245], v[254:255], 1.0 op_sel_hi:[1,1,0] neg_lo:[1,0,0] neg_hi:[1,0,0]
	v_pk_fma_f32 v[254:255], v[252:253], v[250:251], v[254:255]
	v_div_fixup_f32 v244, v254, v244, 1.0
	v_div_fixup_f32 v245, v255, v245, 1.0
	v_rcp_f32_e32 v250, v246
	v_rcp_f32_e32 v251, v247
	s_nop 0
	v_pk_fma_f32 v[252:253], v[246:247], v[250:251], 1.0 op_sel_hi:[1,1,0] neg_lo:[1,0,0] neg_hi:[1,0,0]
	v_pk_fma_f32 v[250:251], v[252:253], v[250:251], v[250:251]
	v_pk_fma_f32 v[252:253], v[246:247], v[250:251], 1.0 op_sel_hi:[1,1,0] neg_lo:[1,0,0] neg_hi:[1,0,0]
	v_pk_fma_f32 v[254:255], v[252:253], v[250:251], v[250:251]
	v_pk_fma_f32 v[252:253], v[246:247], v[254:255], 1.0 op_sel_hi:[1,1,0] neg_lo:[1,0,0] neg_hi:[1,0,0]
	v_pk_fma_f32 v[254:255], v[252:253], v[250:251], v[254:255]
	v_div_fixup_f32 v246, v254, v246, 1.0
	v_div_fixup_f32 v247, v255, v247, 1.0
	v_rcp_f32_e32 v250, v248
	v_rcp_f32_e32 v251, v249
	s_nop 0
	v_pk_fma_f32 v[252:253], v[248:249], v[250:251], 1.0 op_sel_hi:[1,1,0] neg_lo:[1,0,0] neg_hi:[1,0,0]
	v_pk_fma_f32 v[250:251], v[252:253], v[250:251], v[250:251]
	v_pk_fma_f32 v[252:253], v[248:249], v[250:251], 1.0 op_sel_hi:[1,1,0] neg_lo:[1,0,0] neg_hi:[1,0,0]
	v_pk_fma_f32 v[254:255], v[252:253], v[250:251], v[250:251]
	v_pk_fma_f32 v[252:253], v[248:249], v[254:255], 1.0 op_sel_hi:[1,1,0] neg_lo:[1,0,0] neg_hi:[1,0,0]
	v_pk_fma_f32 v[254:255], v[252:253], v[250:251], v[254:255]
	v_div_fixup_f32 v248, v254, v248, 1.0
	v_div_fixup_f32 v249, v255, v249, 1.0
	global_store_dwordx4 v[48:49], v[40:43], off
	s_nop 0
	v_pk_mul_f32 v[36:37], v[36:37], v[242:243]
	v_pk_mul_f32 v[32:33], v[32:33], v[244:245]
	v_pk_mul_f32 v[38:39], v[38:39], v[246:247]
	v_pk_mul_f32 v[40:41], v[34:35], v[248:249]
	v_cvt_pk_bf16_f32 v34, v36, v37
	v_cvt_pk_bf16_f32 v35, v38, v39
	v_cvt_pk_bf16_f32 v36, v32, v33
	v_add_u32_e32 v32, 0xa0, v160
	v_mad_i64_i32 v[32:33], s[6:7], v32, s57, v[146:147]
	v_lshl_add_u64 v[32:33], v[32:33], 0, v[148:149]
	v_add_co_u32_e32 v42, vcc, s58, v32
	v_cvt_pk_bf16_f32 v37, v40, v41
	global_store_dwordx4 v[48:49], v[34:37], off offset:256
	s_nop 0
	v_addc_co_u32_e32 v43, vcc, 0, v33, vcc
	s_waitcnt vmcnt(11)
	v_mov_b32_e32 v38, v232
	v_mov_b32_e32 v39, v233
	v_mov_b32_e32 v40, v234
	v_mov_b32_e32 v41, v235
	s_mov_b32 s100, 0xbfb8aa3b
	v_lshlrev_b32_e32 v242, 16, v38
	v_and_b32_e32 v243, 0xffff0000, v38
	v_lshlrev_b32_e32 v244, 16, v40
	v_and_b32_e32 v245, 0xffff0000, v40
	v_lshlrev_b32_e32 v246, 16, v39
	v_and_b32_e32 v247, 0xffff0000, v39
	v_lshlrev_b32_e32 v248, 16, v41
	v_and_b32_e32 v249, 0xffff0000, v41
	v_pk_mul_f32 v[242:243], v[242:243], s[100:101] op_sel_hi:[1,0]
	v_pk_mul_f32 v[244:245], v[244:245], s[100:101] op_sel_hi:[1,0]
	v_pk_mul_f32 v[246:247], v[246:247], s[100:101] op_sel_hi:[1,0]
	v_pk_mul_f32 v[248:249], v[248:249], s[100:101] op_sel_hi:[1,0]
	v_exp_f32_e32 v242, v242
	v_exp_f32_e32 v243, v243
	v_exp_f32_e32 v244, v244
	v_exp_f32_e32 v245, v245
	v_exp_f32_e32 v246, v246
	v_exp_f32_e32 v247, v247
	v_exp_f32_e32 v248, v248
	v_exp_f32_e32 v249, v249
	s_nop 0
	v_pk_add_f32 v[242:243], v[242:243], 1.0 op_sel_hi:[1,0]
	v_pk_add_f32 v[244:245], v[244:245], 1.0 op_sel_hi:[1,0]
	v_pk_add_f32 v[246:247], v[246:247], 1.0 op_sel_hi:[1,0]
	v_pk_add_f32 v[248:249], v[248:249], 1.0 op_sel_hi:[1,0]
	v_rcp_f32_e32 v250, v242
	v_rcp_f32_e32 v251, v243
	s_nop 0
	v_pk_fma_f32 v[252:253], v[242:243], v[250:251], 1.0 op_sel_hi:[1,1,0] neg_lo:[1,0,0] neg_hi:[1,0,0]
	v_pk_fma_f32 v[250:251], v[252:253], v[250:251], v[250:251]
	v_pk_fma_f32 v[252:253], v[242:243], v[250:251], 1.0 op_sel_hi:[1,1,0] neg_lo:[1,0,0] neg_hi:[1,0,0]
	v_pk_fma_f32 v[254:255], v[252:253], v[250:251], v[250:251]
	v_pk_fma_f32 v[252:253], v[242:243], v[254:255], 1.0 op_sel_hi:[1,1,0] neg_lo:[1,0,0] neg_hi:[1,0,0]
	v_pk_fma_f32 v[254:255], v[252:253], v[250:251], v[254:255]
	v_div_fixup_f32 v242, v254, v242, 1.0
	v_div_fixup_f32 v243, v255, v243, 1.0
	v_rcp_f32_e32 v250, v244
	v_rcp_f32_e32 v251, v245
	s_nop 0
	v_pk_fma_f32 v[252:253], v[244:245], v[250:251], 1.0 op_sel_hi:[1,1,0] neg_lo:[1,0,0] neg_hi:[1,0,0]
	v_pk_fma_f32 v[250:251], v[252:253], v[250:251], v[250:251]
	v_pk_fma_f32 v[252:253], v[244:245], v[250:251], 1.0 op_sel_hi:[1,1,0] neg_lo:[1,0,0] neg_hi:[1,0,0]
	v_pk_fma_f32 v[254:255], v[252:253], v[250:251], v[250:251]
	v_pk_fma_f32 v[252:253], v[244:245], v[254:255], 1.0 op_sel_hi:[1,1,0] neg_lo:[1,0,0] neg_hi:[1,0,0]
	v_pk_fma_f32 v[254:255], v[252:253], v[250:251], v[254:255]
	v_div_fixup_f32 v244, v254, v244, 1.0
	v_div_fixup_f32 v245, v255, v245, 1.0
	v_rcp_f32_e32 v250, v246
	v_rcp_f32_e32 v251, v247
	s_nop 0
	v_pk_fma_f32 v[252:253], v[246:247], v[250:251], 1.0 op_sel_hi:[1,1,0] neg_lo:[1,0,0] neg_hi:[1,0,0]
	v_pk_fma_f32 v[250:251], v[252:253], v[250:251], v[250:251]
	v_pk_fma_f32 v[252:253], v[246:247], v[250:251], 1.0 op_sel_hi:[1,1,0] neg_lo:[1,0,0] neg_hi:[1,0,0]
	v_pk_fma_f32 v[254:255], v[252:253], v[250:251], v[250:251]
	v_pk_fma_f32 v[252:253], v[246:247], v[254:255], 1.0 op_sel_hi:[1,1,0] neg_lo:[1,0,0] neg_hi:[1,0,0]
	v_pk_fma_f32 v[254:255], v[252:253], v[250:251], v[254:255]
	v_div_fixup_f32 v246, v254, v246, 1.0
	v_div_fixup_f32 v247, v255, v247, 1.0
	v_rcp_f32_e32 v250, v248
	v_rcp_f32_e32 v251, v249
	s_nop 0
	v_pk_fma_f32 v[252:253], v[248:249], v[250:251], 1.0 op_sel_hi:[1,1,0] neg_lo:[1,0,0] neg_hi:[1,0,0]
	v_pk_fma_f32 v[250:251], v[252:253], v[250:251], v[250:251]
	v_pk_fma_f32 v[252:253], v[248:249], v[250:251], 1.0 op_sel_hi:[1,1,0] neg_lo:[1,0,0] neg_hi:[1,0,0]
	v_pk_fma_f32 v[254:255], v[252:253], v[250:251], v[250:251]
	v_pk_fma_f32 v[252:253], v[248:249], v[254:255], 1.0 op_sel_hi:[1,1,0] neg_lo:[1,0,0] neg_hi:[1,0,0]
	v_pk_fma_f32 v[254:255], v[252:253], v[250:251], v[254:255]
	v_div_fixup_f32 v248, v254, v248, 1.0
	v_div_fixup_f32 v249, v255, v249, 1.0
	v_mul_f32_e32 v28, v28, v242
	v_mul_f32_e32 v34, v24, v244
	v_mul_f32_e32 v24, v29, v243
	v_mul_f32_e32 v29, v25, v245
	v_mul_f32_e32 v25, v30, v246
	v_mul_f32_e32 v30, v26, v248
	v_mul_f32_e32 v26, v31, v247
	v_mul_f32_e32 v27, v27, v249
	v_cvt_pk_bf16_f32 v24, v28, v24
	v_cvt_pk_bf16_f32 v25, v25, v26
	v_cvt_pk_bf16_f32 v26, v34, v29
	v_cvt_pk_bf16_f32 v27, v30, v27
	s_waitcnt vmcnt(8)
; __device__ __forceinline__ u32x4 pack8(const f32x4 v0, const f32x4 v1) { u32x4 w; w.x = pk2(v0[0], v0[1]); w.y = pk2(v0[2], v0[3]); w.z = pk2(v1[0], v1[1]); w.w = pk2(v1[2], v1[3]); return w; }
; __device__ __forceinline__ void unpack8(const u32x4 w, f32x4& v0, f32x4& v1) { v0 = (f32x4){bflo(w.x), bfhi(w.x), bflo(w.y), bfhi(w.y)}; v1 = (f32x4){bflo(w.z), bfhi(w.z), bflo(w.w), bfhi(w.w)}; }
; __device__ __forceinline__ float sigmoidf_(float x) { return 1.0f / (1.0f + __expf(-x)); }
;     __device__ __forceinline__ void operator()(const f32x4 (&acc)[2][2][4][2], const Unit& u, int wr, int wc, int fr, int fq) const {
;     ...
;         for (int ai = 0; ai < 2; ++ai)
; #pragma unroll
;             for (int m = 0; m < 4; ++m) {
;                 bf16_t* rowp = z + (size_t)(row0 + ai * 128 + m * 16) * DIN + col0;
; #pragma unroll
;                 for (int bj = 0; bj < 2; ++bj) {
;                     const u32x4 gw = *(const u32x4*)(rowp + (MODE == 0 ? O_GB : O_GA) + bj * 128);
;                     f32x4 g0, g1; unpack8(gw, g0, g1);
;                     f32x4 v0, v1;
; #pragma unroll
;                     for (int j = 0; j < 4; ++j) { v0[j] = sigmoidf_(g0[j]) * acc[ai][bj][m][0][j]; v1[j] = sigmoidf_(g1[j]) * acc[ai][bj][m][1][j]; }
;                     if (MODE == 1) { const u32x4 mw = *(const u32x4*)(rowp + bj * 128); f32x4 m0, m1; unpack8(mw, m0, m1); v0 += m0; v1 += m1; }
;                     *(u32x4*)(rowp + bj * 128) = pack8(v0, v1); }
	v_mov_b32_e32 v28, v236
	v_mov_b32_e32 v29, v237
	v_mov_b32_e32 v30, v238
	v_mov_b32_e32 v31, v239
	s_mov_b32 s100, 0xbfb8aa3b
	v_lshlrev_b32_e32 v242, 16, v28
	v_and_b32_e32 v243, 0xffff0000, v28
	v_lshlrev_b32_e32 v244, 16, v30
	v_and_b32_e32 v245, 0xffff0000, v30
	v_lshlrev_b32_e32 v246, 16, v29
	v_and_b32_e32 v247, 0xffff0000, v29
	v_lshlrev_b32_e32 v248, 16, v31
	v_and_b32_e32 v249, 0xffff0000, v31
	v_pk_mul_f32 v[242:243], v[242:243], s[100:101] op_sel_hi:[1,0]
	v_pk_mul_f32 v[244:245], v[244:245], s[100:101] op_sel_hi:[1,0]
	v_pk_mul_f32 v[246:247], v[246:247], s[100:101] op_sel_hi:[1,0]
	v_pk_mul_f32 v[248:249], v[248:249], s[100:101] op_sel_hi:[1,0]
	v_exp_f32_e32 v242, v242
	v_exp_f32_e32 v243, v243
	v_exp_f32_e32 v244, v244
	v_exp_f32_e32 v245, v245
	v_exp_f32_e32 v246, v246
	v_exp_f32_e32 v247, v247
	v_exp_f32_e32 v248, v248
	v_exp_f32_e32 v249, v249
	s_nop 0
	v_pk_add_f32 v[242:243], v[242:243], 1.0 op_sel_hi:[1,0]
	v_pk_add_f32 v[244:245], v[244:245], 1.0 op_sel_hi:[1,0]
	v_pk_add_f32 v[246:247], v[246:247], 1.0 op_sel_hi:[1,0]
	v_pk_add_f32 v[248:249], v[248:249], 1.0 op_sel_hi:[1,0]
	v_rcp_f32_e32 v250, v242
	v_rcp_f32_e32 v251, v243
	s_nop 0
	v_pk_fma_f32 v[252:253], v[242:243], v[250:251], 1.0 op_sel_hi:[1,1,0] neg_lo:[1,0,0] neg_hi:[1,0,0]
	v_pk_fma_f32 v[250:251], v[252:253], v[250:251], v[250:251]
	v_pk_fma_f32 v[252:253], v[242:243], v[250:251], 1.0 op_sel_hi:[1,1,0] neg_lo:[1,0,0] neg_hi:[1,0,0]
	v_pk_fma_f32 v[254:255], v[252:253], v[250:251], v[250:251]
	v_pk_fma_f32 v[252:253], v[242:243], v[254:255], 1.0 op_sel_hi:[1,1,0] neg_lo:[1,0,0] neg_hi:[1,0,0]
	v_pk_fma_f32 v[254:255], v[252:253], v[250:251], v[254:255]
	v_div_fixup_f32 v242, v254, v242, 1.0
	v_div_fixup_f32 v243, v255, v243, 1.0
	v_rcp_f32_e32 v250, v244
	v_rcp_f32_e32 v251, v245
	s_nop 0
	v_pk_fma_f32 v[252:253], v[244:245], v[250:251], 1.0 op_sel_hi:[1,1,0] neg_lo:[1,0,0] neg_hi:[1,0,0]
	v_pk_fma_f32 v[250:251], v[252:253], v[250:251], v[250:251]
	v_pk_fma_f32 v[252:253], v[244:245], v[250:251], 1.0 op_sel_hi:[1,1,0] neg_lo:[1,0,0] neg_hi:[1,0,0]
	v_pk_fma_f32 v[254:255], v[252:253], v[250:251], v[250:251]
	v_pk_fma_f32 v[252:253], v[244:245], v[254:255], 1.0 op_sel_hi:[1,1,0] neg_lo:[1,0,0] neg_hi:[1,0,0]
	v_pk_fma_f32 v[254:255], v[252:253], v[250:251], v[254:255]
	v_div_fixup_f32 v244, v254, v244, 1.0
	v_div_fixup_f32 v245, v255, v245, 1.0
	v_rcp_f32_e32 v250, v246
	v_rcp_f32_e32 v251, v247
	s_nop 0
	v_pk_fma_f32 v[252:253], v[246:247], v[250:251], 1.0 op_sel_hi:[1,1,0] neg_lo:[1,0,0] neg_hi:[1,0,0]
	v_pk_fma_f32 v[250:251], v[252:253], v[250:251], v[250:251]
	v_pk_fma_f32 v[252:253], v[246:247], v[250:251], 1.0 op_sel_hi:[1,1,0] neg_lo:[1,0,0] neg_hi:[1,0,0]
	v_pk_fma_f32 v[254:255], v[252:253], v[250:251], v[250:251]
	v_pk_fma_f32 v[252:253], v[246:247], v[254:255], 1.0 op_sel_hi:[1,1,0] neg_lo:[1,0,0] neg_hi:[1,0,0]
	v_pk_fma_f32 v[254:255], v[252:253], v[250:251], v[254:255]
	v_div_fixup_f32 v246, v254, v246, 1.0
	v_div_fixup_f32 v247, v255, v247, 1.0
	v_rcp_f32_e32 v250, v248
	v_rcp_f32_e32 v251, v249
	s_nop 0
	v_pk_fma_f32 v[252:253], v[248:249], v[250:251], 1.0 op_sel_hi:[1,1,0] neg_lo:[1,0,0] neg_hi:[1,0,0]
	v_pk_fma_f32 v[250:251], v[252:253], v[250:251], v[250:251]
	v_pk_fma_f32 v[252:253], v[248:249], v[250:251], 1.0 op_sel_hi:[1,1,0] neg_lo:[1,0,0] neg_hi:[1,0,0]
	v_pk_fma_f32 v[254:255], v[252:253], v[250:251], v[250:251]
	v_pk_fma_f32 v[252:253], v[248:249], v[254:255], 1.0 op_sel_hi:[1,1,0] neg_lo:[1,0,0] neg_hi:[1,0,0]
	v_pk_fma_f32 v[254:255], v[252:253], v[250:251], v[254:255]
	v_div_fixup_f32 v248, v254, v248, 1.0
	v_div_fixup_f32 v249, v255, v249, 1.0
	global_store_dwordx4 v[32:33], v[24:27], off
	s_nop 0
	v_pk_mul_f32 v[20:21], v[20:21], v[242:243]
	v_pk_mul_f32 v[16:17], v[16:17], v[244:245]
	v_pk_mul_f32 v[22:23], v[22:23], v[246:247]
	v_pk_mul_f32 v[24:25], v[18:19], v[248:249]
	v_cvt_pk_bf16_f32 v18, v20, v21
	v_cvt_pk_bf16_f32 v19, v22, v23
	v_cvt_pk_bf16_f32 v20, v16, v17
	v_add_u32_e32 v16, 0xb0, v160
	v_mad_i64_i32 v[16:17], s[6:7], v16, s57, v[146:147]
	v_lshl_add_u64 v[16:17], v[16:17], 0, v[148:149]
	v_add_co_u32_e32 v26, vcc, s58, v16
	v_cvt_pk_bf16_f32 v21, v24, v25
	global_store_dwordx4 v[32:33], v[18:21], off offset:256
	s_nop 0
	v_addc_co_u32_e32 v27, vcc, 0, v17, vcc
	s_waitcnt vmcnt(9)
; __device__ __forceinline__ u32x4 pack8(const f32x4 v0, const f32x4 v1) { u32x4 w; w.x = pk2(v0[0], v0[1]); w.y = pk2(v0[2], v0[3]); w.z = pk2(v1[0], v1[1]); w.w = pk2(v1[2], v1[3]); return w; }
; __device__ __forceinline__ void unpack8(const u32x4 w, f32x4& v0, f32x4& v1) { v0 = (f32x4){bflo(w.x), bfhi(w.x), bflo(w.y), bfhi(w.y)}; v1 = (f32x4){bflo(w.z), bfhi(w.z), bflo(w.w), bfhi(w.w)}; }
; __device__ __forceinline__ float sigmoidf_(float x) { return 1.0f / (1.0f + __expf(-x)); }
;     __device__ __forceinline__ void operator()(const f32x4 (&acc)[2][2][4][2], const Unit& u, int wr, int wc, int fr, int fq) const {
;     ...
;         for (int ai = 0; ai < 2; ++ai)
; #pragma unroll
;             for (int m = 0; m < 4; ++m) {
;                 bf16_t* rowp = z + (size_t)(row0 + ai * 128 + m * 16) * DIN + col0;
; #pragma unroll
;                 for (int bj = 0; bj < 2; ++bj) {
;                     const u32x4 gw = *(const u32x4*)(rowp + (MODE == 0 ? O_GB : O_GA) + bj * 128);
;                     f32x4 g0, g1; unpack8(gw, g0, g1);
;                     f32x4 v0, v1;
; #pragma unroll
;                     for (int j = 0; j < 4; ++j) { v0[j] = sigmoidf_(g0[j]) * acc[ai][bj][m][0][j]; v1[j] = sigmoidf_(g1[j]) * acc[ai][bj][m][1][j]; }
;                     if (MODE == 1) { const u32x4 mw = *(const u32x4*)(rowp + bj * 128); f32x4 m0, m1; unpack8(mw, m0, m1); v0 += m0; v1 += m1; }
;                     *(u32x4*)(rowp + bj * 128) = pack8(v0, v1); }
	v_mov_b32_e32 v22, v200
	v_mov_b32_e32 v23, v201
	v_mov_b32_e32 v24, v202
	v_mov_b32_e32 v25, v203
	s_mov_b32 s100, 0xbfb8aa3b
	v_lshlrev_b32_e32 v242, 16, v22
	v_and_b32_e32 v243, 0xffff0000, v22
	v_lshlrev_b32_e32 v244, 16, v24
	v_and_b32_e32 v245, 0xffff0000, v24
	v_lshlrev_b32_e32 v246, 16, v23
	v_and_b32_e32 v247, 0xffff0000, v23
	v_lshlrev_b32_e32 v248, 16, v25
	v_and_b32_e32 v249, 0xffff0000, v25
	v_pk_mul_f32 v[242:243], v[242:243], s[100:101] op_sel_hi:[1,0]
	v_pk_mul_f32 v[244:245], v[244:245], s[100:101] op_sel_hi:[1,0]
	v_pk_mul_f32 v[246:247], v[246:247], s[100:101] op_sel_hi:[1,0]
	v_pk_mul_f32 v[248:249], v[248:249], s[100:101] op_sel_hi:[1,0]
	v_exp_f32_e32 v242, v242
	v_exp_f32_e32 v243, v243
	v_exp_f32_e32 v244, v244
	v_exp_f32_e32 v245, v245
	v_exp_f32_e32 v246, v246
	v_exp_f32_e32 v247, v247
	v_exp_f32_e32 v248, v248
	v_exp_f32_e32 v249, v249
	s_nop 0
	v_pk_add_f32 v[242:243], v[242:243], 1.0 op_sel_hi:[1,0]
	v_pk_add_f32 v[244:245], v[244:245], 1.0 op_sel_hi:[1,0]
	v_pk_add_f32 v[246:247], v[246:247], 1.0 op_sel_hi:[1,0]
	v_pk_add_f32 v[248:249], v[248:249], 1.0 op_sel_hi:[1,0]
	v_rcp_f32_e32 v250, v242
	v_rcp_f32_e32 v251, v243
	s_nop 0
	v_pk_fma_f32 v[252:253], v[242:243], v[250:251], 1.0 op_sel_hi:[1,1,0] neg_lo:[1,0,0] neg_hi:[1,0,0]
	v_pk_fma_f32 v[250:251], v[252:253], v[250:251], v[250:251]
	v_pk_fma_f32 v[252:253], v[242:243], v[250:251], 1.0 op_sel_hi:[1,1,0] neg_lo:[1,0,0] neg_hi:[1,0,0]
	v_pk_fma_f32 v[254:255], v[252:253], v[250:251], v[250:251]
	v_pk_fma_f32 v[252:253], v[242:243], v[254:255], 1.0 op_sel_hi:[1,1,0] neg_lo:[1,0,0] neg_hi:[1,0,0]
	v_pk_fma_f32 v[254:255], v[252:253], v[250:251], v[254:255]
	v_div_fixup_f32 v242, v254, v242, 1.0
	v_div_fixup_f32 v243, v255, v243, 1.0
	v_rcp_f32_e32 v250, v244
	v_rcp_f32_e32 v251, v245
	s_nop 0
	v_pk_fma_f32 v[252:253], v[244:245], v[250:251], 1.0 op_sel_hi:[1,1,0] neg_lo:[1,0,0] neg_hi:[1,0,0]
	v_pk_fma_f32 v[250:251], v[252:253], v[250:251], v[250:251]
	v_pk_fma_f32 v[252:253], v[244:245], v[250:251], 1.0 op_sel_hi:[1,1,0] neg_lo:[1,0,0] neg_hi:[1,0,0]
	v_pk_fma_f32 v[254:255], v[252:253], v[250:251], v[250:251]
	v_pk_fma_f32 v[252:253], v[244:245], v[254:255], 1.0 op_sel_hi:[1,1,0] neg_lo:[1,0,0] neg_hi:[1,0,0]
	v_pk_fma_f32 v[254:255], v[252:253], v[250:251], v[254:255]
	v_div_fixup_f32 v244, v254, v244, 1.0
	v_div_fixup_f32 v245, v255, v245, 1.0
	v_rcp_f32_e32 v250, v246
	v_rcp_f32_e32 v251, v247
	s_nop 0
	v_pk_fma_f32 v[252:253], v[246:247], v[250:251], 1.0 op_sel_hi:[1,1,0] neg_lo:[1,0,0] neg_hi:[1,0,0]
	v_pk_fma_f32 v[250:251], v[252:253], v[250:251], v[250:251]
	v_pk_fma_f32 v[252:253], v[246:247], v[250:251], 1.0 op_sel_hi:[1,1,0] neg_lo:[1,0,0] neg_hi:[1,0,0]
	v_pk_fma_f32 v[254:255], v[252:253], v[250:251], v[250:251]
	v_pk_fma_f32 v[252:253], v[246:247], v[254:255], 1.0 op_sel_hi:[1,1,0] neg_lo:[1,0,0] neg_hi:[1,0,0]
	v_pk_fma_f32 v[254:255], v[252:253], v[250:251], v[254:255]
	v_div_fixup_f32 v246, v254, v246, 1.0
	v_div_fixup_f32 v247, v255, v247, 1.0
	v_rcp_f32_e32 v250, v248
	v_rcp_f32_e32 v251, v249
	s_nop 0
	v_pk_fma_f32 v[252:253], v[248:249], v[250:251], 1.0 op_sel_hi:[1,1,0] neg_lo:[1,0,0] neg_hi:[1,0,0]
	v_pk_fma_f32 v[250:251], v[252:253], v[250:251], v[250:251]
	v_pk_fma_f32 v[252:253], v[248:249], v[250:251], 1.0 op_sel_hi:[1,1,0] neg_lo:[1,0,0] neg_hi:[1,0,0]
	v_pk_fma_f32 v[254:255], v[252:253], v[250:251], v[250:251]
	v_pk_fma_f32 v[252:253], v[248:249], v[254:255], 1.0 op_sel_hi:[1,1,0] neg_lo:[1,0,0] neg_hi:[1,0,0]
	v_pk_fma_f32 v[254:255], v[252:253], v[250:251], v[254:255]
	v_div_fixup_f32 v248, v254, v248, 1.0
	v_div_fixup_f32 v249, v255, v249, 1.0
	v_mul_f32_e32 v12, v12, v242
	v_mul_f32_e32 v18, v8, v244
	v_mul_f32_e32 v8, v13, v243
	v_mul_f32_e32 v13, v9, v245
	v_mul_f32_e32 v9, v14, v246
	v_mul_f32_e32 v14, v10, v248
	v_mul_f32_e32 v10, v15, v247
	v_mul_f32_e32 v11, v11, v249
	v_cvt_pk_bf16_f32 v8, v12, v8
	v_cvt_pk_bf16_f32 v9, v9, v10
	v_cvt_pk_bf16_f32 v10, v18, v13
	v_cvt_pk_bf16_f32 v11, v14, v11
	s_waitcnt vmcnt(6)
; __device__ __forceinline__ u32x4 pack8(const f32x4 v0, const f32x4 v1) { u32x4 w; w.x = pk2(v0[0], v0[1]); w.y = pk2(v0[2], v0[3]); w.z = pk2(v1[0], v1[1]); w.w = pk2(v1[2], v1[3]); return w; }
; __device__ __forceinline__ void unpack8(const u32x4 w, f32x4& v0, f32x4& v1) { v0 = (f32x4){bflo(w.x), bfhi(w.x), bflo(w.y), bfhi(w.y)}; v1 = (f32x4){bflo(w.z), bfhi(w.z), bflo(w.w), bfhi(w.w)}; }
; __device__ __forceinline__ float sigmoidf_(float x) { return 1.0f / (1.0f + __expf(-x)); }
;     __device__ __forceinline__ void operator()(const f32x4 (&acc)[2][2][4][2], const Unit& u, int wr, int wc, int fr, int fq) const {
;     ...
;         for (int ai = 0; ai < 2; ++ai)
; #pragma unroll
;             for (int m = 0; m < 4; ++m) {
;                 bf16_t* rowp = z + (size_t)(row0 + ai * 128 + m * 16) * DIN + col0;
; #pragma unroll
;                 for (int bj = 0; bj < 2; ++bj) {
;                     const u32x4 gw = *(const u32x4*)(rowp + (MODE == 0 ? O_GB : O_GA) + bj * 128);
;                     f32x4 g0, g1; unpack8(gw, g0, g1);
;                     f32x4 v0, v1;
; #pragma unroll
;                     for (int j = 0; j < 4; ++j) { v0[j] = sigmoidf_(g0[j]) * acc[ai][bj][m][0][j]; v1[j] = sigmoidf_(g1[j]) * acc[ai][bj][m][1][j]; }
;                     if (MODE == 1) { const u32x4 mw = *(const u32x4*)(rowp + bj * 128); f32x4 m0, m1; unpack8(mw, m0, m1); v0 += m0; v1 += m1; }
;                     *(u32x4*)(rowp + bj * 128) = pack8(v0, v1); }
	v_mov_b32_e32 v12, v204
	v_mov_b32_e32 v13, v205
	v_mov_b32_e32 v14, v206
	v_mov_b32_e32 v15, v207
	s_mov_b32 s100, 0xbfb8aa3b
	v_lshlrev_b32_e32 v242, 16, v12
	v_and_b32_e32 v243, 0xffff0000, v12
	v_lshlrev_b32_e32 v244, 16, v14
	v_and_b32_e32 v245, 0xffff0000, v14
	v_lshlrev_b32_e32 v246, 16, v13
	v_and_b32_e32 v247, 0xffff0000, v13
	v_lshlrev_b32_e32 v248, 16, v15
	v_and_b32_e32 v249, 0xffff0000, v15
	v_pk_mul_f32 v[242:243], v[242:243], s[100:101] op_sel_hi:[1,0]
	v_pk_mul_f32 v[244:245], v[244:245], s[100:101] op_sel_hi:[1,0]
	v_pk_mul_f32 v[246:247], v[246:247], s[100:101] op_sel_hi:[1,0]
	v_pk_mul_f32 v[248:249], v[248:249], s[100:101] op_sel_hi:[1,0]
	v_exp_f32_e32 v242, v242
	v_exp_f32_e32 v243, v243
	v_exp_f32_e32 v244, v244
	v_exp_f32_e32 v245, v245
	v_exp_f32_e32 v246, v246
	v_exp_f32_e32 v247, v247
	v_exp_f32_e32 v248, v248
	v_exp_f32_e32 v249, v249
	s_nop 0
	v_pk_add_f32 v[242:243], v[242:243], 1.0 op_sel_hi:[1,0]
	v_pk_add_f32 v[244:245], v[244:245], 1.0 op_sel_hi:[1,0]
	v_pk_add_f32 v[246:247], v[246:247], 1.0 op_sel_hi:[1,0]
	v_pk_add_f32 v[248:249], v[248:249], 1.0 op_sel_hi:[1,0]
	v_rcp_f32_e32 v250, v242
	v_rcp_f32_e32 v251, v243
	s_nop 0
	v_pk_fma_f32 v[252:253], v[242:243], v[250:251], 1.0 op_sel_hi:[1,1,0] neg_lo:[1,0,0] neg_hi:[1,0,0]
	v_pk_fma_f32 v[250:251], v[252:253], v[250:251], v[250:251]
	v_pk_fma_f32 v[252:253], v[242:243], v[250:251], 1.0 op_sel_hi:[1,1,0] neg_lo:[1,0,0] neg_hi:[1,0,0]
	v_pk_fma_f32 v[254:255], v[252:253], v[250:251], v[250:251]
	v_pk_fma_f32 v[252:253], v[242:243], v[254:255], 1.0 op_sel_hi:[1,1,0] neg_lo:[1,0,0] neg_hi:[1,0,0]
	v_pk_fma_f32 v[254:255], v[252:253], v[250:251], v[254:255]
	v_div_fixup_f32 v242, v254, v242, 1.0
	v_div_fixup_f32 v243, v255, v243, 1.0
	v_rcp_f32_e32 v250, v244
	v_rcp_f32_e32 v251, v245
	s_nop 0
	v_pk_fma_f32 v[252:253], v[244:245], v[250:251], 1.0 op_sel_hi:[1,1,0] neg_lo:[1,0,0] neg_hi:[1,0,0]
	v_pk_fma_f32 v[250:251], v[252:253], v[250:251], v[250:251]
	v_pk_fma_f32 v[252:253], v[244:245], v[250:251], 1.0 op_sel_hi:[1,1,0] neg_lo:[1,0,0] neg_hi:[1,0,0]
	v_pk_fma_f32 v[254:255], v[252:253], v[250:251], v[250:251]
	v_pk_fma_f32 v[252:253], v[244:245], v[254:255], 1.0 op_sel_hi:[1,1,0] neg_lo:[1,0,0] neg_hi:[1,0,0]
	v_pk_fma_f32 v[254:255], v[252:253], v[250:251], v[254:255]
	v_div_fixup_f32 v244, v254, v244, 1.0
	v_div_fixup_f32 v245, v255, v245, 1.0
	v_rcp_f32_e32 v250, v246
	v_rcp_f32_e32 v251, v247
	s_nop 0
	v_pk_fma_f32 v[252:253], v[246:247], v[250:251], 1.0 op_sel_hi:[1,1,0] neg_lo:[1,0,0] neg_hi:[1,0,0]
	v_pk_fma_f32 v[250:251], v[252:253], v[250:251], v[250:251]
	v_pk_fma_f32 v[252:253], v[246:247], v[250:251], 1.0 op_sel_hi:[1,1,0] neg_lo:[1,0,0] neg_hi:[1,0,0]
	v_pk_fma_f32 v[254:255], v[252:253], v[250:251], v[250:251]
	v_pk_fma_f32 v[252:253], v[246:247], v[254:255], 1.0 op_sel_hi:[1,1,0] neg_lo:[1,0,0] neg_hi:[1,0,0]
	v_pk_fma_f32 v[254:255], v[252:253], v[250:251], v[254:255]
	v_div_fixup_f32 v246, v254, v246, 1.0
	v_div_fixup_f32 v247, v255, v247, 1.0
	v_rcp_f32_e32 v250, v248
	v_rcp_f32_e32 v251, v249
	s_nop 0
	v_pk_fma_f32 v[252:253], v[248:249], v[250:251], 1.0 op_sel_hi:[1,1,0] neg_lo:[1,0,0] neg_hi:[1,0,0]
	v_pk_fma_f32 v[250:251], v[252:253], v[250:251], v[250:251]
	v_pk_fma_f32 v[252:253], v[248:249], v[250:251], 1.0 op_sel_hi:[1,1,0] neg_lo:[1,0,0] neg_hi:[1,0,0]
	v_pk_fma_f32 v[254:255], v[252:253], v[250:251], v[250:251]
	v_pk_fma_f32 v[252:253], v[248:249], v[254:255], 1.0 op_sel_hi:[1,1,0] neg_lo:[1,0,0] neg_hi:[1,0,0]
	v_pk_fma_f32 v[254:255], v[252:253], v[250:251], v[254:255]
	v_div_fixup_f32 v248, v254, v248, 1.0
	v_div_fixup_f32 v249, v255, v249, 1.0
	global_store_dwordx4 v[16:17], v[8:11], off
	s_nop 0
	v_mul_f32_e32 v4, v4, v242
	v_mul_f32_e32 v8, v0, v244
	v_mul_f32_e32 v0, v5, v243
	v_mul_f32_e32 v5, v1, v245
	v_mul_f32_e32 v1, v6, v246
	v_mul_f32_e32 v6, v2, v248
	v_mul_f32_e32 v2, v7, v247
	v_mul_f32_e32 v3, v3, v249
	s_and_b64 vcc, exec, s[8:9]
	s_mov_b32 s7, s26
	s_mov_b32 s6, s59
	v_cvt_pk_bf16_f32 v0, v4, v0
	v_cvt_pk_bf16_f32 v1, v1, v2
	v_cvt_pk_bf16_f32 v2, v8, v5
	v_cvt_pk_bf16_f32 v3, v6, v3
	global_store_dwordx4 v[16:17], v[0:3], off offset:256
	s_cbranch_vccz .LBB0_1763
	s_waitcnt vmcnt(0)
	s_cmpk_gt_u32 s34, 0xff
	s_cbranch_scc1 .LBB0_1772
	s_barrier

; #define PG8_STAGE(bufoff, gbase, voff) do { _Pragma("unroll") for (int _i = 0; _i < 2; ++_i) \
;         __builtin_amdgcn_global_load_lds((const unsigned*)((const char*)(gbase) + (voff)[_i]), (LAS unsigned*)(lds + (bufoff) + ldsw + _i * 8192), 16, 0, 0); } while (0)
; #define PG8_LDA(dst, b, h) do { _Pragma("unroll") for (int m = 0; m < 4; ++m) _Pragma("unroll") for (int k = 0; k < 2; ++k) dst[m][k] = *(const LAS bf16x8*)(lds + PG8_SA(b, h) + aoff + m * 2048 + k * 1024); } while (0)
; #define PG8_LDB(dst, b, h) do { _Pragma("unroll") for (int n = 0; n < 2; ++n) _Pragma("unroll") for (int k = 0; k < 2; ++k) dst[n][k] = *(const LAS bf16x8*)(lds + PG8_SB(b, h) + boff + n * 2048 + k * 1024); } while (0)
; #define PG8_MMA(ai, bj, At, Bt) do { __builtin_amdgcn_s_setprio(1); _Pragma("unroll") for (int m = 0; m < 4; ++m) _Pragma("unroll") for (int n = 0; n < 2; ++n) _Pragma("unroll") for (int k = 0; k < 2; ++k) \
;         acc[ai][bj][m][n] = __builtin_amdgcn_mfma_f32_16x16x32_bf16(Bt[n][k], At[m][k], acc[ai][bj][m][n], 0, 0, 0); __builtin_amdgcn_s_setprio(0); } while (0)
; #define PG8_WAIT_V(n) asm volatile("s_waitcnt vmcnt(" #n ")" ::: "memory")
; #define PG8_WAIT_L(n) asm volatile("s_waitcnt lgkmcnt(" #n ")" ::: "memory")
; #define PG8_BAR __builtin_amdgcn_s_barrier()
; #define PG8_SCHED __builtin_amdgcn_sched_barrier(0)
;     ...
;             PG8_LDB(B0, 0, 0); PG8_SCHED; PG8_LDA(At, 0, 0); PG8_STAGE(PG8_SA(1, 1), a1 + hA, voffA);
;             PG8_WAIT_L(8); PG8_BAR; PG8_WAIT_L(0); PG8_MMA(0, 0, At, B0); PG8_BAR; PG8_SCHED;
;             PG8_LDB(B1, 0, 1); PG8_STAGE(PG8_SB(0, 0), b2, voffB);
;             PG8_BAR; PG8_WAIT_L(0); PG8_MMA(0, 1, At, B1); PG8_BAR;
;             PG8_LDA(At, 0, 1); PG8_STAGE(PG8_SA(0, 0), a2, voffA);
;             PG8_BAR; PG8_WAIT_L(0); PG8_MMA(1, 0, At, B0); PG8_BAR; PG8_SCHED;
;             PG8_STAGE(PG8_SB(0, 1), b2 + hB, voffB);
;             PG8_WAIT_V(6); PG8_BAR; PG8_MMA(1, 1, At, B1); PG8_BAR;
;             PG8_LDB(B0, 1, 0); PG8_SCHED; PG8_LDA(At, 1, 0); PG8_STAGE(PG8_SA(0, 1), a2 + hA, voffA);
.LBB0_1841:
	ds_read_b128 v[146:149], v159
	ds_read_b128 v[150:153], v159 offset:1024
	ds_read_b128 v[162:165], v159 offset:2048
	ds_read_b128 v[170:173], v159 offset:3072
	s_add_u32 s14, s12, 0xfffe0080
	s_addc_u32 s15, s13, -1
	s_cmp_eq_u32 s45, 4
	s_cselect_b32 s17, s7, s15
	s_cselect_b32 s16, s18, s14
	s_cselect_b32 s15, s19, s44
	s_cselect_b32 s14, s33, s39
	v_lshl_add_u64 v[154:155], s[12:13], 0, v[138:139]
	s_add_i32 m0, s62, 0xc000
	ds_read_b128 v[174:177], v160
	ds_read_b128 v[178:181], v160 offset:1024
	ds_read_b128 v[182:185], v160 offset:2048
	ds_read_b128 v[186:189], v160 offset:3072
	ds_read_b128 v[190:193], v160 offset:4096
	ds_read_b128 v[194:197], v160 offset:5120
	ds_read_b128 v[198:201], v160 offset:6144
	ds_read_b128 v[202:205], v160 offset:7168
	global_load_lds_dwordx4 v[154:155], off
	v_lshl_add_u64 v[154:155], s[12:13], 0, v[136:137]
	s_add_i32 m0, s62, 0xe000
	s_nop 0
	global_load_lds_dwordx4 v[154:155], off
	s_waitcnt lgkmcnt(8)
	s_barrier
	s_waitcnt lgkmcnt(0)
	s_setprio 1
	s_waitcnt lgkmcnt(0)
	v_mfma_f32_16x16x32_bf16 v[124:127], v[146:149], v[174:177], v[124:127]
	v_mfma_f32_16x16x32_bf16 v[120:123], v[162:165], v[174:177], v[120:123]
	v_mfma_f32_16x16x32_bf16 v[108:111], v[146:149], v[182:185], v[108:111]
	v_mfma_f32_16x16x32_bf16 v[104:107], v[162:165], v[182:185], v[104:107]
	v_mfma_f32_16x16x32_bf16 v[92:95], v[146:149], v[190:193], v[92:95]
	v_mfma_f32_16x16x32_bf16 v[88:91], v[162:165], v[190:193], v[88:91]
	v_mfma_f32_16x16x32_bf16 v[76:79], v[146:149], v[198:201], v[76:79]
	v_mfma_f32_16x16x32_bf16 v[72:75], v[162:165], v[198:201], v[72:75]
	v_mfma_f32_16x16x32_bf16 v[124:127], v[150:153], v[178:181], v[124:127]
	v_mfma_f32_16x16x32_bf16 v[120:123], v[170:173], v[178:181], v[120:123]
	v_mfma_f32_16x16x32_bf16 v[108:111], v[150:153], v[186:189], v[108:111]
	v_mfma_f32_16x16x32_bf16 v[104:107], v[170:173], v[186:189], v[104:107]
	v_mfma_f32_16x16x32_bf16 v[92:95], v[150:153], v[194:197], v[92:95]
	v_mfma_f32_16x16x32_bf16 v[88:91], v[170:173], v[194:197], v[88:91]
	v_mfma_f32_16x16x32_bf16 v[76:79], v[150:153], v[202:205], v[76:79]
	v_mfma_f32_16x16x32_bf16 v[72:75], v[170:173], v[202:205], v[72:75]
	s_setprio 0
	s_barrier
	s_add_i32 s55, s71, s61
	v_lshl_add_u64 v[154:155], s[14:15], 0, v[130:131]
	s_mov_b32 m0, s55
	ds_read_b128 v[206:209], v161
	ds_read_b128 v[210:213], v161 offset:1024
	ds_read_b128 v[214:217], v161 offset:2048
	ds_read_b128 v[218:221], v161 offset:3072
	global_load_lds_dwordx4 v[154:155], off
	v_lshl_add_u64 v[222:223], s[14:15], 0, v[134:135]
	s_add_i32 m0, s55, 0x2000
	s_nop 0
	global_load_lds_dwordx4 v[222:223], off
	s_barrier
	s_waitcnt lgkmcnt(0)
	s_setprio 1
	s_waitcnt lgkmcnt(0)
	v_mfma_f32_16x16x32_bf16 v[116:119], v[206:209], v[174:177], v[116:119]
	v_mfma_f32_16x16x32_bf16 v[112:115], v[214:217], v[174:177], v[112:115]
	v_mfma_f32_16x16x32_bf16 v[100:103], v[206:209], v[182:185], v[100:103]
	v_mfma_f32_16x16x32_bf16 v[96:99], v[214:217], v[182:185], v[96:99]
	v_mfma_f32_16x16x32_bf16 v[84:87], v[206:209], v[190:193], v[84:87]
	v_mfma_f32_16x16x32_bf16 v[80:83], v[214:217], v[190:193], v[80:83]
	v_mfma_f32_16x16x32_bf16 v[68:71], v[206:209], v[198:201], v[68:71]
	v_mfma_f32_16x16x32_bf16 v[64:67], v[214:217], v[198:201], v[64:67]
	v_mfma_f32_16x16x32_bf16 v[116:119], v[210:213], v[178:181], v[116:119]
	v_mfma_f32_16x16x32_bf16 v[112:115], v[218:221], v[178:181], v[112:115]
	v_mfma_f32_16x16x32_bf16 v[100:103], v[210:213], v[186:189], v[100:103]
	v_mfma_f32_16x16x32_bf16 v[96:99], v[218:221], v[186:189], v[96:99]
	v_mfma_f32_16x16x32_bf16 v[84:87], v[210:213], v[194:197], v[84:87]
	v_mfma_f32_16x16x32_bf16 v[80:83], v[218:221], v[194:197], v[80:83]
	v_mfma_f32_16x16x32_bf16 v[68:71], v[210:213], v[202:205], v[68:71]
	v_mfma_f32_16x16x32_bf16 v[64:67], v[218:221], v[202:205], v[64:67]
	s_setprio 0
	s_mov_b32 m0, s62
	v_lshl_add_u64 v[224:225], s[16:17], 0, v[128:129]
	s_barrier
	ds_read_b128 v[174:177], v160 offset:16384
	ds_read_b128 v[178:181], v160 offset:17408
	ds_read_b128 v[182:185], v160 offset:18432
	ds_read_b128 v[186:189], v160 offset:19456
	ds_read_b128 v[190:193], v160 offset:20480
	ds_read_b128 v[194:197], v160 offset:21504
	ds_read_b128 v[198:201], v160 offset:22528
	ds_read_b128 v[202:205], v160 offset:23552
	global_load_lds_dwordx4 v[224:225], off
	v_lshl_add_u64 v[226:227], s[16:17], 0, v[132:133]
	s_mov_b32 m0, s63
	s_nop 0
	global_load_lds_dwordx4 v[226:227], off
	s_barrier
	s_waitcnt lgkmcnt(0)
	s_setprio 1
	s_waitcnt lgkmcnt(0)
	v_mfma_f32_16x16x32_bf16 v[60:63], v[146:149], v[174:177], v[60:63]
	v_mfma_f32_16x16x32_bf16 v[56:59], v[162:165], v[174:177], v[56:59]
	v_mfma_f32_16x16x32_bf16 v[44:47], v[146:149], v[182:185], v[44:47]
	v_mfma_f32_16x16x32_bf16 v[40:43], v[162:165], v[182:185], v[40:43]
	v_mfma_f32_16x16x32_bf16 v[28:31], v[146:149], v[190:193], v[28:31]
	v_mfma_f32_16x16x32_bf16 v[24:27], v[162:165], v[190:193], v[24:27]
	v_mfma_f32_16x16x32_bf16 v[12:15], v[146:149], v[198:201], v[12:15]
	v_mfma_f32_16x16x32_bf16 v[8:11], v[162:165], v[198:201], v[8:11]
	v_mfma_f32_16x16x32_bf16 v[60:63], v[150:153], v[178:181], v[60:63]
	v_mfma_f32_16x16x32_bf16 v[56:59], v[170:173], v[178:181], v[56:59]
	v_mfma_f32_16x16x32_bf16 v[44:47], v[150:153], v[186:189], v[44:47]
	v_mfma_f32_16x16x32_bf16 v[40:43], v[170:173], v[186:189], v[40:43]
	v_mfma_f32_16x16x32_bf16 v[28:31], v[150:153], v[194:197], v[28:31]
	v_mfma_f32_16x16x32_bf16 v[24:27], v[170:173], v[194:197], v[24:27]
	v_mfma_f32_16x16x32_bf16 v[12:15], v[150:153], v[202:205], v[12:15]
	v_mfma_f32_16x16x32_bf16 v[8:11], v[170:173], v[202:205], v[8:11]
	s_setprio 0
	s_barrier
; #define PG8_STAGE(bufoff, gbase, voff) do { _Pragma("unroll") for (int _i = 0; _i < 2; ++_i) \
;         __builtin_amdgcn_global_load_lds((const unsigned*)((const char*)(gbase) + (voff)[_i]), (LAS unsigned*)(lds + (bufoff) + ldsw + _i * 8192), 16, 0, 0); } while (0)
; #define PG8_LDA(dst, b, h) do { _Pragma("unroll") for (int m = 0; m < 4; ++m) _Pragma("unroll") for (int k = 0; k < 2; ++k) dst[m][k] = *(const LAS bf16x8*)(lds + PG8_SA(b, h) + aoff + m * 2048 + k * 1024); } while (0)
; #define PG8_LDB(dst, b, h) do { _Pragma("unroll") for (int n = 0; n < 2; ++n) _Pragma("unroll") for (int k = 0; k < 2; ++k) dst[n][k] = *(const LAS bf16x8*)(lds + PG8_SB(b, h) + boff + n * 2048 + k * 1024); } while (0)
; #define PG8_MMA(ai, bj, At, Bt) do { __builtin_amdgcn_s_setprio(1); _Pragma("unroll") for (int m = 0; m < 4; ++m) _Pragma("unroll") for (int n = 0; n < 2; ++n) _Pragma("unroll") for (int k = 0; k < 2; ++k) \
;         acc[ai][bj][m][n] = __builtin_amdgcn_mfma_f32_16x16x32_bf16(Bt[n][k], At[m][k], acc[ai][bj][m][n], 0, 0, 0); __builtin_amdgcn_s_setprio(0); } while (0)
; #define PG8_WAIT_V(n) asm volatile("s_waitcnt vmcnt(" #n ")" ::: "memory")
; #define PG8_WAIT_L(n) asm volatile("s_waitcnt lgkmcnt(" #n ")" ::: "memory")
; #define PG8_BAR __builtin_amdgcn_s_barrier()
; #define PG8_SCHED __builtin_amdgcn_sched_barrier(0)
;     ...
;             PG8_WAIT_V(6); PG8_BAR; PG8_MMA(1, 1, At, B1); PG8_BAR;
;             PG8_LDB(B0, 1, 0); PG8_SCHED; PG8_LDA(At, 1, 0); PG8_STAGE(PG8_SA(0, 1), a2 + hA, voffA);
;             PG8_WAIT_L(8); PG8_BAR; PG8_WAIT_L(0); PG8_MMA(0, 0, At, B0); PG8_BAR; PG8_SCHED;
;             PG8_LDB(B1, 1, 1); PG8_STAGE(PG8_SB(1, 0), b3, voffB);
;             PG8_BAR; PG8_WAIT_L(0); PG8_MMA(0, 1, At, B1); PG8_BAR;
;             PG8_LDA(At, 1, 1); PG8_STAGE(PG8_SA(1, 0), a3, voffA);
;             PG8_BAR; PG8_WAIT_L(0); PG8_MMA(1, 0, At, B0); PG8_BAR; PG8_SCHED;
	s_add_u32 s76, s14, 0x20000
	s_addc_u32 s77, s15, 0
	s_add_i32 s55, s72, s61
	v_lshl_add_u64 v[146:147], s[76:77], 0, v[130:131]
	s_mov_b32 m0, s55
	s_nop 0
	global_load_lds_dwordx4 v[146:147], off
	v_lshl_add_u64 v[146:147], s[76:77], 0, v[134:135]
	s_add_i32 m0, s55, 0x2000
	s_nop 0
	global_load_lds_dwordx4 v[146:147], off
	s_waitcnt vmcnt(6)
	s_barrier
	s_setprio 1
	v_mfma_f32_16x16x32_bf16 v[52:55], v[206:209], v[174:177], v[52:55]
	v_mfma_f32_16x16x32_bf16 v[48:51], v[214:217], v[174:177], v[48:51]
	v_mfma_f32_16x16x32_bf16 v[36:39], v[206:209], v[182:185], v[36:39]
	v_mfma_f32_16x16x32_bf16 v[32:35], v[214:217], v[182:185], v[32:35]
	v_mfma_f32_16x16x32_bf16 v[20:23], v[206:209], v[190:193], v[20:23]
	v_mfma_f32_16x16x32_bf16 v[16:19], v[214:217], v[190:193], v[16:19]
	v_mfma_f32_16x16x32_bf16 v[4:7], v[206:209], v[198:201], v[4:7]
	v_mfma_f32_16x16x32_bf16 v[0:3], v[214:217], v[198:201], v[0:3]
	v_mfma_f32_16x16x32_bf16 v[52:55], v[210:213], v[178:181], v[52:55]
	v_mfma_f32_16x16x32_bf16 v[48:51], v[218:221], v[178:181], v[48:51]
	v_mfma_f32_16x16x32_bf16 v[36:39], v[210:213], v[186:189], v[36:39]
	v_mfma_f32_16x16x32_bf16 v[32:35], v[218:221], v[186:189], v[32:35]
	v_mfma_f32_16x16x32_bf16 v[20:23], v[210:213], v[194:197], v[20:23]
	v_mfma_f32_16x16x32_bf16 v[16:19], v[218:221], v[194:197], v[16:19]
	v_mfma_f32_16x16x32_bf16 v[4:7], v[210:213], v[202:205], v[4:7]
	v_mfma_f32_16x16x32_bf16 v[0:3], v[218:221], v[202:205], v[0:3]
	s_setprio 0
	s_add_i32 s55, 0, 0x18000
	v_add_u32_e32 v169, s55, v157
	s_barrier
	ds_read_b128 v[146:149], v169
	ds_read_b128 v[150:153], v169 offset:1024
	ds_read_b128 v[162:165], v169 offset:2048
	ds_read_b128 v[170:173], v169 offset:3072
	s_add_u32 s16, s16, 0x20000
	s_addc_u32 s17, s17, 0
	s_mov_b32 m0, s64
	v_lshl_add_u64 v[206:207], s[16:17], 0, v[128:129]
	ds_read_b128 v[174:177], v160 offset:32768
	ds_read_b128 v[178:181], v160 offset:33792
	ds_read_b128 v[182:185], v160 offset:34816
	ds_read_b128 v[186:189], v160 offset:35840
	ds_read_b128 v[190:193], v160 offset:36864
	ds_read_b128 v[194:197], v160 offset:37888
	ds_read_b128 v[198:201], v160 offset:38912
	ds_read_b128 v[202:205], v160 offset:39936
	global_load_lds_dwordx4 v[206:207], off
	v_lshl_add_u64 v[206:207], s[16:17], 0, v[132:133]
	s_mov_b32 m0, s65
	s_nop 0
	global_load_lds_dwordx4 v[206:207], off
	s_waitcnt lgkmcnt(8)
	s_barrier
	s_waitcnt lgkmcnt(0)
	s_setprio 1
	s_waitcnt lgkmcnt(0)
	v_mfma_f32_16x16x32_bf16 v[124:127], v[146:149], v[174:177], v[124:127]
	v_mfma_f32_16x16x32_bf16 v[120:123], v[162:165], v[174:177], v[120:123]
	v_mfma_f32_16x16x32_bf16 v[108:111], v[146:149], v[182:185], v[108:111]
	v_mfma_f32_16x16x32_bf16 v[104:107], v[162:165], v[182:185], v[104:107]
	v_mfma_f32_16x16x32_bf16 v[92:95], v[146:149], v[190:193], v[92:95]
	v_mfma_f32_16x16x32_bf16 v[88:91], v[162:165], v[190:193], v[88:91]
	v_mfma_f32_16x16x32_bf16 v[76:79], v[146:149], v[198:201], v[76:79]
	v_mfma_f32_16x16x32_bf16 v[72:75], v[162:165], v[198:201], v[72:75]
	v_mfma_f32_16x16x32_bf16 v[124:127], v[150:153], v[178:181], v[124:127]
	v_mfma_f32_16x16x32_bf16 v[120:123], v[170:173], v[178:181], v[120:123]
	v_mfma_f32_16x16x32_bf16 v[108:111], v[150:153], v[186:189], v[108:111]
	v_mfma_f32_16x16x32_bf16 v[104:107], v[170:173], v[186:189], v[104:107]
	v_mfma_f32_16x16x32_bf16 v[92:95], v[150:153], v[194:197], v[92:95]
	v_mfma_f32_16x16x32_bf16 v[88:91], v[170:173], v[194:197], v[88:91]
	v_mfma_f32_16x16x32_bf16 v[76:79], v[150:153], v[202:205], v[76:79]
	v_mfma_f32_16x16x32_bf16 v[72:75], v[170:173], v[202:205], v[72:75]
	s_setprio 0
	s_barrier
	s_add_i32 s16, 0, 0x1c000
	s_add_i32 s17, s55, s61
	v_add_u32_e32 v169, s16, v157
	v_lshl_add_u64 v[154:155], v[154:155], 0, s[40:41]
	s_mov_b32 m0, s17
	ds_read_b128 v[206:209], v169
	ds_read_b128 v[210:213], v169 offset:1024
	ds_read_b128 v[214:217], v169 offset:2048
	ds_read_b128 v[218:221], v169 offset:3072
	global_load_lds_dwordx4 v[154:155], off
	v_lshl_add_u64 v[154:155], v[222:223], 0, s[40:41]
	s_add_i32 m0, s17, 0x2000
	s_nop 0
	global_load_lds_dwordx4 v[154:155], off
	s_barrier
	s_waitcnt lgkmcnt(0)
	s_setprio 1
	s_waitcnt lgkmcnt(0)
	v_mfma_f32_16x16x32_bf16 v[116:119], v[206:209], v[174:177], v[116:119]
	v_mfma_f32_16x16x32_bf16 v[112:115], v[214:217], v[174:177], v[112:115]
	v_mfma_f32_16x16x32_bf16 v[100:103], v[206:209], v[182:185], v[100:103]
	v_mfma_f32_16x16x32_bf16 v[96:99], v[214:217], v[182:185], v[96:99]
	v_mfma_f32_16x16x32_bf16 v[84:87], v[206:209], v[190:193], v[84:87]
	v_mfma_f32_16x16x32_bf16 v[80:83], v[214:217], v[190:193], v[80:83]
	v_mfma_f32_16x16x32_bf16 v[68:71], v[206:209], v[198:201], v[68:71]
	v_mfma_f32_16x16x32_bf16 v[64:67], v[214:217], v[198:201], v[64:67]
	v_mfma_f32_16x16x32_bf16 v[116:119], v[210:213], v[178:181], v[116:119]
	v_mfma_f32_16x16x32_bf16 v[112:115], v[218:221], v[178:181], v[112:115]
	v_mfma_f32_16x16x32_bf16 v[100:103], v[210:213], v[186:189], v[100:103]
	v_mfma_f32_16x16x32_bf16 v[96:99], v[218:221], v[186:189], v[96:99]
	v_mfma_f32_16x16x32_bf16 v[84:87], v[210:213], v[194:197], v[84:87]
	v_mfma_f32_16x16x32_bf16 v[80:83], v[218:221], v[194:197], v[80:83]
	v_mfma_f32_16x16x32_bf16 v[68:71], v[210:213], v[202:205], v[68:71]
	v_mfma_f32_16x16x32_bf16 v[64:67], v[218:221], v[202:205], v[64:67]
	s_setprio 0
	s_mov_b32 m0, s67
	v_lshl_add_u64 v[154:155], v[224:225], 0, s[40:41]
	s_barrier
	ds_read_b128 v[174:177], v160 offset:49152
	ds_read_b128 v[178:181], v160 offset:50176
	ds_read_b128 v[182:185], v160 offset:51200
	ds_read_b128 v[186:189], v160 offset:52224
	ds_read_b128 v[190:193], v160 offset:53248
	ds_read_b128 v[194:197], v160 offset:54272
	ds_read_b128 v[198:201], v160 offset:55296
	ds_read_b128 v[202:205], v160 offset:56320
	global_load_lds_dwordx4 v[154:155], off
	v_lshl_add_u64 v[154:155], v[226:227], 0, s[40:41]
	s_mov_b32 m0, s68
	s_nop 0
	global_load_lds_dwordx4 v[154:155], off
	s_barrier
; #define PG8_STAGE(bufoff, gbase, voff) do { _Pragma("unroll") for (int _i = 0; _i < 2; ++_i) \
;         __builtin_amdgcn_global_load_lds((const unsigned*)((const char*)(gbase) + (voff)[_i]), (LAS unsigned*)(lds + (bufoff) + ldsw + _i * 8192), 16, 0, 0); } while (0)
; #define PG8_MMA(ai, bj, At, Bt) do { __builtin_amdgcn_s_setprio(1); _Pragma("unroll") for (int m = 0; m < 4; ++m) _Pragma("unroll") for (int n = 0; n < 2; ++n) _Pragma("unroll") for (int k = 0; k < 2; ++k) \
;         acc[ai][bj][m][n] = __builtin_amdgcn_mfma_f32_16x16x32_bf16(Bt[n][k], At[m][k], acc[ai][bj][m][n], 0, 0, 0); __builtin_amdgcn_s_setprio(0); } while (0)
; #define PG8_WAIT_V(n) asm volatile("s_waitcnt vmcnt(" #n ")" ::: "memory")
; #define PG8_WAIT_L(n) asm volatile("s_waitcnt lgkmcnt(" #n ")" ::: "memory")
; #define PG8_BAR __builtin_amdgcn_s_barrier()
; #define PG8_SCHED __builtin_amdgcn_sched_barrier(0)
; __device__ __forceinline__ void unpack8(const u32x4 w, f32x4& v0, f32x4& v1) { v0 = (f32x4){bflo(w.x), bfhi(w.x), bflo(w.y), bfhi(w.y)}; v1 = (f32x4){bflo(w.z), bfhi(w.z), bflo(w.w), bfhi(w.w)}; }
; __device__ __forceinline__ float sigmoidf_(float x) { return 1.0f / (1.0f + __expf(-x)); }
;     ...
;             PG8_BAR; PG8_WAIT_L(0); PG8_MMA(1, 0, At, B0); PG8_BAR; PG8_SCHED;
;             PG8_STAGE(PG8_SB(1, 1), b3 + hB, voffB);
;             PG8_WAIT_V(6); PG8_BAR; PG8_MMA(1, 1, At, B1); PG8_BAR;
;     __device__ __forceinline__ void operator()(const f32x4 (&acc)[2][2][4][2], const Unit& u, int wr, int wc, int fr, int fq) const {
;     ...
;         for (int ai = 0; ai < 2; ++ai)
; #pragma unroll
;             for (int m = 0; m < 4; ++m) {
;                 const int row = row0 + ai * 128 + m * 16;
;                 const bf16_t* rowp = z + (size_t)row * DIN + col0;
; #pragma unroll
;                 for (int bj = 0; bj < 2; ++bj) {
;                     const u32x4 gw = *(const u32x4*)(rowp + O_GA + bj * 128);
;                     f32x4 g0, g1; unpack8(gw, g0, g1);
;                     f32x4 v0, v1;
; #pragma unroll
;                     for (int j = 0; j < 4; ++j) { v0[j] = sigmoidf_(g0[j]) * acc[ai][bj][m][0][j]; v1[j] = sigmoidf_(g1[j]) * acc[ai][bj][m][1][j]; }
;                     const u32x4 mw = *(const u32x4*)(rowp + bj * 128); f32x4 m0, m1; unpack8(mw, m0, m1); v0 += m0; v1 += m1;
	s_waitcnt lgkmcnt(0)
	s_setprio 1
	s_waitcnt lgkmcnt(0)
	v_mfma_f32_16x16x32_bf16 v[60:63], v[146:149], v[174:177], v[60:63]
	v_mfma_f32_16x16x32_bf16 v[56:59], v[162:165], v[174:177], v[56:59]
	v_mfma_f32_16x16x32_bf16 v[44:47], v[146:149], v[182:185], v[44:47]
	v_mfma_f32_16x16x32_bf16 v[40:43], v[162:165], v[182:185], v[40:43]
	v_mfma_f32_16x16x32_bf16 v[28:31], v[146:149], v[190:193], v[28:31]
	v_mfma_f32_16x16x32_bf16 v[24:27], v[162:165], v[190:193], v[24:27]
	v_mfma_f32_16x16x32_bf16 v[12:15], v[146:149], v[198:201], v[12:15]
	v_mfma_f32_16x16x32_bf16 v[8:11], v[162:165], v[198:201], v[8:11]
	v_mfma_f32_16x16x32_bf16 v[60:63], v[150:153], v[178:181], v[60:63]
	v_mfma_f32_16x16x32_bf16 v[56:59], v[170:173], v[178:181], v[56:59]
	v_mfma_f32_16x16x32_bf16 v[44:47], v[150:153], v[186:189], v[44:47]
	v_mfma_f32_16x16x32_bf16 v[40:43], v[170:173], v[186:189], v[40:43]
	v_mfma_f32_16x16x32_bf16 v[28:31], v[150:153], v[194:197], v[28:31]
	v_mfma_f32_16x16x32_bf16 v[24:27], v[170:173], v[194:197], v[24:27]
	v_mfma_f32_16x16x32_bf16 v[12:15], v[150:153], v[202:205], v[12:15]
	v_mfma_f32_16x16x32_bf16 v[8:11], v[170:173], v[202:205], v[8:11]
	s_setprio 0
	s_barrier
	s_add_u32 s14, s14, 0x20080
	s_addc_u32 s15, s15, 0
	s_add_i32 s16, s16, s61
	v_lshl_add_u64 v[146:147], s[14:15], 0, v[130:131]
	s_mov_b32 m0, s16
	s_nop 0
	global_load_lds_dwordx4 v[146:147], off
	v_lshl_add_u64 v[146:147], s[14:15], 0, v[134:135]
	s_add_i32 m0, s16, 0x2000
	s_nop 0
	global_load_lds_dwordx4 v[146:147], off
	s_waitcnt vmcnt(6)
	s_barrier
	s_setprio 1
	v_mfma_f32_16x16x32_bf16 v[52:55], v[206:209], v[174:177], v[52:55]
	v_mfma_f32_16x16x32_bf16 v[48:51], v[214:217], v[174:177], v[48:51]
	v_mfma_f32_16x16x32_bf16 v[36:39], v[206:209], v[182:185], v[36:39]
	v_mfma_f32_16x16x32_bf16 v[32:35], v[214:217], v[182:185], v[32:35]
	v_mfma_f32_16x16x32_bf16 v[20:23], v[206:209], v[190:193], v[20:23]
	v_mfma_f32_16x16x32_bf16 v[16:19], v[214:217], v[190:193], v[16:19]
	v_mfma_f32_16x16x32_bf16 v[4:7], v[206:209], v[198:201], v[4:7]
	v_mfma_f32_16x16x32_bf16 v[0:3], v[214:217], v[198:201], v[0:3]
	v_mfma_f32_16x16x32_bf16 v[52:55], v[210:213], v[178:181], v[52:55]
	v_mfma_f32_16x16x32_bf16 v[48:51], v[218:221], v[178:181], v[48:51]
	v_mfma_f32_16x16x32_bf16 v[36:39], v[210:213], v[186:189], v[36:39]
	v_mfma_f32_16x16x32_bf16 v[32:35], v[218:221], v[186:189], v[32:35]
	v_mfma_f32_16x16x32_bf16 v[20:23], v[210:213], v[194:197], v[20:23]
	v_mfma_f32_16x16x32_bf16 v[16:19], v[218:221], v[194:197], v[16:19]
	v_mfma_f32_16x16x32_bf16 v[4:7], v[210:213], v[202:205], v[4:7]
	v_mfma_f32_16x16x32_bf16 v[0:3], v[218:221], v[202:205], v[0:3]
	s_setprio 0
	s_add_i32 s45, s45, 2
	s_add_u32 s39, s39, 0x100
	s_addc_u32 s44, s44, 0
	s_add_u32 s12, s12, 0x100
	s_addc_u32 s13, s13, 0
	s_cmp_gt_u32 s45, 5
	s_barrier
	s_cbranch_scc0 .LBB0_1841
	v_lshl_or_b32 v146, s6, 8, v158
	v_lshl_add_u32 v162, s75, 8, v156
	v_ashrrev_i32_e32 v147, 31, v146
	v_mad_i64_i32 v[154:155], s[6:7], v162, s73, 0
	v_lshl_add_u64 v[150:151], v[154:155], 1, s[36:37]
	v_lshlrev_b64 v[148:149], 1, v[146:147]
	v_lshl_add_u64 v[150:151], v[150:151], 0, v[148:149]
	v_add_co_u32_e32 v152, vcc, 0x1000, v150
	s_nop 1
	v_addc_co_u32_e32 v153, vcc, 0, v151, vcc
	v_subrev_u32_e32 v201, s36, v150
	v_add_u32_e32 v202, 0x1200, v201
	global_load_dwordx4 v[204:207], v202, s[36:37]
	v_add_u32_e32 v202, 0x0, v201
	global_load_dwordx4 v[208:211], v202, s[36:37]
	v_add_u32_e32 v202, 0x1300, v201
	global_load_dwordx4 v[212:215], v202, s[36:37]
	v_add_u32_e32 v202, 0x100, v201
	global_load_dwordx4 v[216:219], v202, s[36:37]
	v_add_u32_e32 v202, 0x23200, v201
	global_load_dwordx4 v[232:235], v202, s[36:37]
	v_add_u32_e32 v202, 0x22000, v201
	global_load_dwordx4 v[236:239], v202, s[36:37]
	s_waitcnt vmcnt(4)
	v_mov_b32_e32 v170, v204
	v_mov_b32_e32 v171, v205
	v_mov_b32_e32 v172, v206
	v_mov_b32_e32 v173, v207
	v_mov_b32_e32 v174, v208
	v_mov_b32_e32 v175, v209
	v_mov_b32_e32 v176, v210
	v_mov_b32_e32 v177, v211
	v_add_u32_e32 v202, 0x23300, v201
	global_load_dwordx4 v[204:207], v202, s[36:37]
	v_add_u32_e32 v202, 0x22100, v201
	global_load_dwordx4 v[208:211], v202, s[36:37]
	s_mov_b32 s100, 0xbfb8aa3b
	v_lshlrev_b32_e32 v242, 16, v170
	v_and_b32_e32 v243, 0xffff0000, v170
	v_lshlrev_b32_e32 v244, 16, v172
	v_and_b32_e32 v245, 0xffff0000, v172
	v_lshlrev_b32_e32 v246, 16, v173
	v_and_b32_e32 v247, 0xffff0000, v173
	v_lshlrev_b32_e32 v248, 16, v171
	v_and_b32_e32 v249, 0xffff0000, v171
	v_pk_mul_f32 v[242:243], v[242:243], s[100:101] op_sel_hi:[1,0]
	v_pk_mul_f32 v[244:245], v[244:245], s[100:101] op_sel_hi:[1,0]
	v_pk_mul_f32 v[246:247], v[246:247], s[100:101] op_sel_hi:[1,0]
	v_pk_mul_f32 v[248:249], v[248:249], s[100:101] op_sel_hi:[1,0]
	v_exp_f32_e32 v242, v242
	v_exp_f32_e32 v243, v243
	v_exp_f32_e32 v244, v244
	v_exp_f32_e32 v245, v245
	v_exp_f32_e32 v246, v246
	v_exp_f32_e32 v247, v247
	v_exp_f32_e32 v248, v248
	v_exp_f32_e32 v249, v249
	s_nop 0
	v_pk_add_f32 v[242:243], v[242:243], 1.0 op_sel_hi:[1,0]
	v_pk_add_f32 v[244:245], v[244:245], 1.0 op_sel_hi:[1,0]
	v_pk_add_f32 v[246:247], v[246:247], 1.0 op_sel_hi:[1,0]
	v_pk_add_f32 v[248:249], v[248:249], 1.0 op_sel_hi:[1,0]
	v_rcp_f32_e32 v250, v242
	v_rcp_f32_e32 v251, v243
	s_nop 0
	v_pk_fma_f32 v[252:253], v[242:243], v[250:251], 1.0 op_sel_hi:[1,1,0] neg_lo:[1,0,0] neg_hi:[1,0,0]
	v_pk_fma_f32 v[250:251], v[252:253], v[250:251], v[250:251]
	v_pk_fma_f32 v[252:253], v[242:243], v[250:251], 1.0 op_sel_hi:[1,1,0] neg_lo:[1,0,0] neg_hi:[1,0,0]
	v_pk_fma_f32 v[254:255], v[252:253], v[250:251], v[250:251]
	v_pk_fma_f32 v[252:253], v[242:243], v[254:255], 1.0 op_sel_hi:[1,1,0] neg_lo:[1,0,0] neg_hi:[1,0,0]
; __device__ __forceinline__ u32x4 pack8(const f32x4 v0, const f32x4 v1) { u32x4 w; w.x = pk2(v0[0], v0[1]); w.y = pk2(v0[2], v0[3]); w.z = pk2(v1[0], v1[1]); w.w = pk2(v1[2], v1[3]); return w; }
; __device__ __forceinline__ void unpack8(const u32x4 w, f32x4& v0, f32x4& v1) { v0 = (f32x4){bflo(w.x), bfhi(w.x), bflo(w.y), bfhi(w.y)}; v1 = (f32x4){bflo(w.z), bfhi(w.z), bflo(w.w), bfhi(w.w)}; }
; __device__ __forceinline__ float sigmoidf_(float x) { return 1.0f / (1.0f + __expf(-x)); }
;     __device__ __forceinline__ void operator()(const f32x4 (&acc)[2][2][4][2], const Unit& u, int wr, int wc, int fr, int fq) const {
;     ...
;         for (int ai = 0; ai < 2; ++ai)
; #pragma unroll
;             for (int m = 0; m < 4; ++m) {
;                 const int row = row0 + ai * 128 + m * 16;
;                 const bf16_t* rowp = z + (size_t)row * DIN + col0;
; #pragma unroll
;                 for (int bj = 0; bj < 2; ++bj) {
;                     const u32x4 gw = *(const u32x4*)(rowp + O_GA + bj * 128);
;                     f32x4 g0, g1; unpack8(gw, g0, g1);
;                     f32x4 v0, v1;
; #pragma unroll
;                     for (int j = 0; j < 4; ++j) { v0[j] = sigmoidf_(g0[j]) * acc[ai][bj][m][0][j]; v1[j] = sigmoidf_(g1[j]) * acc[ai][bj][m][1][j]; }
;                     const u32x4 mw = *(const u32x4*)(rowp + bj * 128); f32x4 m0, m1; unpack8(mw, m0, m1); v0 += m0; v1 += m1;
;                     __builtin_amdgcn_raw_buffer_store_b128(pack8(v0, v1), rsrc, (unsigned)(((size_t)row * DIN + col0 + bj * 128) * 2), 0, 16  ); }
	v_pk_fma_f32 v[254:255], v[252:253], v[250:251], v[254:255]
	v_div_fixup_f32 v242, v254, v242, 1.0
	v_div_fixup_f32 v243, v255, v243, 1.0
	v_rcp_f32_e32 v250, v244
	v_rcp_f32_e32 v251, v245
	s_nop 0
	v_pk_fma_f32 v[252:253], v[244:245], v[250:251], 1.0 op_sel_hi:[1,1,0] neg_lo:[1,0,0] neg_hi:[1,0,0]
	v_pk_fma_f32 v[250:251], v[252:253], v[250:251], v[250:251]
	v_pk_fma_f32 v[252:253], v[244:245], v[250:251], 1.0 op_sel_hi:[1,1,0] neg_lo:[1,0,0] neg_hi:[1,0,0]
	v_pk_fma_f32 v[254:255], v[252:253], v[250:251], v[250:251]
	v_pk_fma_f32 v[252:253], v[244:245], v[254:255], 1.0 op_sel_hi:[1,1,0] neg_lo:[1,0,0] neg_hi:[1,0,0]
	v_pk_fma_f32 v[254:255], v[252:253], v[250:251], v[254:255]
	v_div_fixup_f32 v244, v254, v244, 1.0
	v_div_fixup_f32 v245, v255, v245, 1.0
	v_rcp_f32_e32 v250, v246
	v_rcp_f32_e32 v251, v247
	s_nop 0
	v_pk_fma_f32 v[252:253], v[246:247], v[250:251], 1.0 op_sel_hi:[1,1,0] neg_lo:[1,0,0] neg_hi:[1,0,0]
	v_pk_fma_f32 v[250:251], v[252:253], v[250:251], v[250:251]
	v_pk_fma_f32 v[252:253], v[246:247], v[250:251], 1.0 op_sel_hi:[1,1,0] neg_lo:[1,0,0] neg_hi:[1,0,0]
	v_pk_fma_f32 v[254:255], v[252:253], v[250:251], v[250:251]
	v_pk_fma_f32 v[252:253], v[246:247], v[254:255], 1.0 op_sel_hi:[1,1,0] neg_lo:[1,0,0] neg_hi:[1,0,0]
	v_pk_fma_f32 v[254:255], v[252:253], v[250:251], v[254:255]
	v_div_fixup_f32 v246, v254, v246, 1.0
	v_div_fixup_f32 v247, v255, v247, 1.0
	v_rcp_f32_e32 v250, v248
	v_rcp_f32_e32 v251, v249
	s_nop 0
	v_pk_fma_f32 v[252:253], v[248:249], v[250:251], 1.0 op_sel_hi:[1,1,0] neg_lo:[1,0,0] neg_hi:[1,0,0]
	v_pk_fma_f32 v[250:251], v[252:253], v[250:251], v[250:251]
	v_pk_fma_f32 v[252:253], v[248:249], v[250:251], 1.0 op_sel_hi:[1,1,0] neg_lo:[1,0,0] neg_hi:[1,0,0]
	v_pk_fma_f32 v[254:255], v[252:253], v[250:251], v[250:251]
	v_pk_fma_f32 v[252:253], v[248:249], v[254:255], 1.0 op_sel_hi:[1,1,0] neg_lo:[1,0,0] neg_hi:[1,0,0]
	v_pk_fma_f32 v[254:255], v[252:253], v[250:251], v[254:255]
	v_div_fixup_f32 v248, v254, v248, 1.0
	v_div_fixup_f32 v249, v255, v249, 1.0
	s_mov_b64 vcc, s[12:13]
	s_mov_b64 vcc, s[14:15]
	s_mov_b64 vcc, s[16:17]
	s_mov_b64 vcc, s[18:19]
	v_and_b32_e32 v181, 0xffff0000, v174
	v_lshlrev_b32_e32 v182, 16, v176
	v_lshlrev_b32_e32 v180, 16, v174
	v_and_b32_e32 v183, 0xffff0000, v176
	v_lshlrev_b32_e32 v176, 16, v177
	v_and_b32_e32 v177, 0xffff0000, v177
	v_lshlrev_b32_e32 v174, 16, v175
	v_and_b32_e32 v175, 0xffff0000, v175
	v_pk_fma_f32 v[124:125], v[124:125], v[242:243], v[180:181]
	v_pk_fma_f32 v[164:165], v[122:123], v[246:247], v[176:177]
	v_pk_fma_f32 v[122:123], v[120:121], v[244:245], v[182:183]
	v_add_lshl_u32 v147, v146, v154, 1
	v_pk_fma_f32 v[126:127], v[126:127], v[248:249], v[174:175]
	v_cvt_pk_bf16_f32 v120, v124, v125
	s_nop 0
	v_cvt_pk_bf16_f32 v121, v126, v127
	v_cvt_pk_bf16_f32 v122, v122, v123
	v_cvt_pk_bf16_f32 v123, v164, v165
	buffer_store_dwordx4 v[120:123], v147, s[20:23], 0 offen sc1
	s_nop 0
	s_waitcnt vmcnt(5)
	v_mov_b32_e32 v120, v212
	v_mov_b32_e32 v121, v213
	v_mov_b32_e32 v122, v214
	v_mov_b32_e32 v123, v215
	v_mov_b32_e32 v124, v216
	v_mov_b32_e32 v125, v217
	v_mov_b32_e32 v126, v218
	v_mov_b32_e32 v127, v219
	v_add_u32_e32 v202, 0x45200, v201
	global_load_dwordx4 v[212:215], v202, s[36:37]
	v_add_u32_e32 v202, 0x44000, v201
	global_load_dwordx4 v[216:219], v202, s[36:37]
	s_mov_b32 s100, 0xbfb8aa3b
	v_lshlrev_b32_e32 v242, 16, v120
	v_and_b32_e32 v243, 0xffff0000, v120
	v_lshlrev_b32_e32 v244, 16, v122
	v_and_b32_e32 v245, 0xffff0000, v122
	v_lshlrev_b32_e32 v246, 16, v121
	v_and_b32_e32 v247, 0xffff0000, v121
	v_lshlrev_b32_e32 v248, 16, v123
	v_and_b32_e32 v249, 0xffff0000, v123
	v_pk_mul_f32 v[242:243], v[242:243], s[100:101] op_sel_hi:[1,0]
	v_pk_mul_f32 v[244:245], v[244:245], s[100:101] op_sel_hi:[1,0]
	v_pk_mul_f32 v[246:247], v[246:247], s[100:101] op_sel_hi:[1,0]
	v_pk_mul_f32 v[248:249], v[248:249], s[100:101] op_sel_hi:[1,0]
	v_exp_f32_e32 v242, v242
	v_exp_f32_e32 v243, v243
	v_exp_f32_e32 v244, v244
	v_exp_f32_e32 v245, v245
	v_exp_f32_e32 v246, v246
	v_exp_f32_e32 v247, v247
	v_exp_f32_e32 v248, v248
	v_exp_f32_e32 v249, v249
	s_nop 0
	v_pk_add_f32 v[242:243], v[242:243], 1.0 op_sel_hi:[1,0]
	v_pk_add_f32 v[244:245], v[244:245], 1.0 op_sel_hi:[1,0]
	v_pk_add_f32 v[246:247], v[246:247], 1.0 op_sel_hi:[1,0]
	v_pk_add_f32 v[248:249], v[248:249], 1.0 op_sel_hi:[1,0]
	v_rcp_f32_e32 v250, v242
	v_rcp_f32_e32 v251, v243
	s_nop 0
	v_pk_fma_f32 v[252:253], v[242:243], v[250:251], 1.0 op_sel_hi:[1,1,0] neg_lo:[1,0,0] neg_hi:[1,0,0]
	v_pk_fma_f32 v[250:251], v[252:253], v[250:251], v[250:251]
	v_pk_fma_f32 v[252:253], v[242:243], v[250:251], 1.0 op_sel_hi:[1,1,0] neg_lo:[1,0,0] neg_hi:[1,0,0]
	v_pk_fma_f32 v[254:255], v[252:253], v[250:251], v[250:251]
	v_pk_fma_f32 v[252:253], v[242:243], v[254:255], 1.0 op_sel_hi:[1,1,0] neg_lo:[1,0,0] neg_hi:[1,0,0]
	v_pk_fma_f32 v[254:255], v[252:253], v[250:251], v[254:255]
	v_div_fixup_f32 v242, v254, v242, 1.0
	v_div_fixup_f32 v243, v255, v243, 1.0
	v_rcp_f32_e32 v250, v244
	v_rcp_f32_e32 v251, v245
	s_nop 0
	v_pk_fma_f32 v[252:253], v[244:245], v[250:251], 1.0 op_sel_hi:[1,1,0] neg_lo:[1,0,0] neg_hi:[1,0,0]
	v_pk_fma_f32 v[250:251], v[252:253], v[250:251], v[250:251]
	v_pk_fma_f32 v[252:253], v[244:245], v[250:251], 1.0 op_sel_hi:[1,1,0] neg_lo:[1,0,0] neg_hi:[1,0,0]
	v_pk_fma_f32 v[254:255], v[252:253], v[250:251], v[250:251]
	v_pk_fma_f32 v[252:253], v[244:245], v[254:255], 1.0 op_sel_hi:[1,1,0] neg_lo:[1,0,0] neg_hi:[1,0,0]
	v_pk_fma_f32 v[254:255], v[252:253], v[250:251], v[254:255]
	v_div_fixup_f32 v244, v254, v244, 1.0
	v_div_fixup_f32 v245, v255, v245, 1.0
	v_rcp_f32_e32 v250, v246
	v_rcp_f32_e32 v251, v247
; __device__ __forceinline__ u32x4 pack8(const f32x4 v0, const f32x4 v1) { u32x4 w; w.x = pk2(v0[0], v0[1]); w.y = pk2(v0[2], v0[3]); w.z = pk2(v1[0], v1[1]); w.w = pk2(v1[2], v1[3]); return w; }
; __device__ __forceinline__ void unpack8(const u32x4 w, f32x4& v0, f32x4& v1) { v0 = (f32x4){bflo(w.x), bfhi(w.x), bflo(w.y), bfhi(w.y)}; v1 = (f32x4){bflo(w.z), bfhi(w.z), bflo(w.w), bfhi(w.w)}; }
; __device__ __forceinline__ float sigmoidf_(float x) { return 1.0f / (1.0f + __expf(-x)); }
;     __device__ __forceinline__ void operator()(const f32x4 (&acc)[2][2][4][2], const Unit& u, int wr, int wc, int fr, int fq) const {
;     ...
;         for (int ai = 0; ai < 2; ++ai)
; #pragma unroll
;             for (int m = 0; m < 4; ++m) {
;                 const int row = row0 + ai * 128 + m * 16;
;                 const bf16_t* rowp = z + (size_t)row * DIN + col0;
; #pragma unroll
;                 for (int bj = 0; bj < 2; ++bj) {
;                     const u32x4 gw = *(const u32x4*)(rowp + O_GA + bj * 128);
;                     f32x4 g0, g1; unpack8(gw, g0, g1);
;                     f32x4 v0, v1;
; #pragma unroll
;                     for (int j = 0; j < 4; ++j) { v0[j] = sigmoidf_(g0[j]) * acc[ai][bj][m][0][j]; v1[j] = sigmoidf_(g1[j]) * acc[ai][bj][m][1][j]; }
;                     const u32x4 mw = *(const u32x4*)(rowp + bj * 128); f32x4 m0, m1; unpack8(mw, m0, m1); v0 += m0; v1 += m1;
;                     __builtin_amdgcn_raw_buffer_store_b128(pack8(v0, v1), rsrc, (unsigned)(((size_t)row * DIN + col0 + bj * 128) * 2), 0, 16  ); }
	s_nop 0
	v_pk_fma_f32 v[252:253], v[246:247], v[250:251], 1.0 op_sel_hi:[1,1,0] neg_lo:[1,0,0] neg_hi:[1,0,0]
	v_pk_fma_f32 v[250:251], v[252:253], v[250:251], v[250:251]
	v_pk_fma_f32 v[252:253], v[246:247], v[250:251], 1.0 op_sel_hi:[1,1,0] neg_lo:[1,0,0] neg_hi:[1,0,0]
	v_pk_fma_f32 v[254:255], v[252:253], v[250:251], v[250:251]
	v_pk_fma_f32 v[252:253], v[246:247], v[254:255], 1.0 op_sel_hi:[1,1,0] neg_lo:[1,0,0] neg_hi:[1,0,0]
	v_pk_fma_f32 v[254:255], v[252:253], v[250:251], v[254:255]
	v_div_fixup_f32 v246, v254, v246, 1.0
	v_div_fixup_f32 v247, v255, v247, 1.0
	v_rcp_f32_e32 v250, v248
	v_rcp_f32_e32 v251, v249
	s_nop 0
	v_pk_fma_f32 v[252:253], v[248:249], v[250:251], 1.0 op_sel_hi:[1,1,0] neg_lo:[1,0,0] neg_hi:[1,0,0]
	v_pk_fma_f32 v[250:251], v[252:253], v[250:251], v[250:251]
	v_pk_fma_f32 v[252:253], v[248:249], v[250:251], 1.0 op_sel_hi:[1,1,0] neg_lo:[1,0,0] neg_hi:[1,0,0]
	v_pk_fma_f32 v[254:255], v[252:253], v[250:251], v[250:251]
	v_pk_fma_f32 v[252:253], v[248:249], v[254:255], 1.0 op_sel_hi:[1,1,0] neg_lo:[1,0,0] neg_hi:[1,0,0]
	v_pk_fma_f32 v[254:255], v[252:253], v[250:251], v[254:255]
	v_div_fixup_f32 v248, v254, v248, 1.0
	v_div_fixup_f32 v249, v255, v249, 1.0
	v_lshlrev_b32_e32 v154, 16, v124
	v_and_b32_e32 v155, 0xffff0000, v124
	v_lshlrev_b32_e32 v164, 16, v126
	v_and_b32_e32 v165, 0xffff0000, v126
	v_lshlrev_b32_e32 v126, 16, v127
	v_and_b32_e32 v127, 0xffff0000, v127
	v_lshlrev_b32_e32 v124, 16, v125
	v_and_b32_e32 v125, 0xffff0000, v125
	v_pk_fma_f32 v[116:117], v[116:117], v[242:243], v[154:155]
	v_pk_fma_f32 v[120:121], v[114:115], v[248:249], v[126:127]
	v_pk_fma_f32 v[114:115], v[112:113], v[244:245], v[164:165]
	v_cvt_pk_bf16_f32 v112, v116, v117
	v_pk_fma_f32 v[118:119], v[118:119], v[246:247], v[124:125]
	s_nop 0
	v_cvt_pk_bf16_f32 v113, v118, v119
	v_cvt_pk_bf16_f32 v114, v114, v115
	v_cvt_pk_bf16_f32 v115, v120, v121
	buffer_store_dwordx4 v[112:115], v147, s[20:23], 0 offen offset:256 sc1
	s_nop 1
	v_or_b32_e32 v112, 16, v162
	v_mad_i64_i32 v[114:115], s[6:7], v112, s73, 0
	v_lshl_add_u64 v[112:113], v[114:115], 1, s[36:37]
	v_lshl_add_u64 v[112:113], v[112:113], 0, v[148:149]
	v_add_co_u32_e32 v116, vcc, s74, v112
	s_nop 1
	v_addc_co_u32_e32 v117, vcc, 0, v113, vcc
	s_waitcnt vmcnt(6)
	v_mov_b32_e32 v118, v232
	v_mov_b32_e32 v119, v233
	v_mov_b32_e32 v120, v234
	v_mov_b32_e32 v121, v235
	v_mov_b32_e32 v122, v236
	v_mov_b32_e32 v123, v237
	v_mov_b32_e32 v124, v238
	v_mov_b32_e32 v125, v239
	v_add_u32_e32 v202, 0x45300, v201
	global_load_dwordx4 v[232:235], v202, s[36:37]
	v_add_u32_e32 v202, 0x44100, v201
	global_load_dwordx4 v[236:239], v202, s[36:37]
	s_mov_b32 s100, 0xbfb8aa3b
	v_lshlrev_b32_e32 v242, 16, v118
	v_and_b32_e32 v243, 0xffff0000, v118
	v_lshlrev_b32_e32 v244, 16, v120
	v_and_b32_e32 v245, 0xffff0000, v120
	v_lshlrev_b32_e32 v246, 16, v119
	v_and_b32_e32 v247, 0xffff0000, v119
	v_lshlrev_b32_e32 v248, 16, v121
	v_and_b32_e32 v249, 0xffff0000, v121
	v_pk_mul_f32 v[242:243], v[242:243], s[100:101] op_sel_hi:[1,0]
	v_pk_mul_f32 v[244:245], v[244:245], s[100:101] op_sel_hi:[1,0]
	v_pk_mul_f32 v[246:247], v[246:247], s[100:101] op_sel_hi:[1,0]
	v_pk_mul_f32 v[248:249], v[248:249], s[100:101] op_sel_hi:[1,0]
	v_exp_f32_e32 v242, v242
	v_exp_f32_e32 v243, v243
	v_exp_f32_e32 v244, v244
	v_exp_f32_e32 v245, v245
	v_exp_f32_e32 v246, v246
	v_exp_f32_e32 v247, v247
	v_exp_f32_e32 v248, v248
	v_exp_f32_e32 v249, v249
	s_nop 0
	v_pk_add_f32 v[242:243], v[242:243], 1.0 op_sel_hi:[1,0]
	v_pk_add_f32 v[244:245], v[244:245], 1.0 op_sel_hi:[1,0]
	v_pk_add_f32 v[246:247], v[246:247], 1.0 op_sel_hi:[1,0]
	v_pk_add_f32 v[248:249], v[248:249], 1.0 op_sel_hi:[1,0]
	v_rcp_f32_e32 v250, v242
	v_rcp_f32_e32 v251, v243
	s_nop 0
	v_pk_fma_f32 v[252:253], v[242:243], v[250:251], 1.0 op_sel_hi:[1,1,0] neg_lo:[1,0,0] neg_hi:[1,0,0]
	v_pk_fma_f32 v[250:251], v[252:253], v[250:251], v[250:251]
	v_pk_fma_f32 v[252:253], v[242:243], v[250:251], 1.0 op_sel_hi:[1,1,0] neg_lo:[1,0,0] neg_hi:[1,0,0]
	v_pk_fma_f32 v[254:255], v[252:253], v[250:251], v[250:251]
	v_pk_fma_f32 v[252:253], v[242:243], v[254:255], 1.0 op_sel_hi:[1,1,0] neg_lo:[1,0,0] neg_hi:[1,0,0]
	v_pk_fma_f32 v[254:255], v[252:253], v[250:251], v[254:255]
	v_div_fixup_f32 v242, v254, v242, 1.0
	v_div_fixup_f32 v243, v255, v243, 1.0
	v_rcp_f32_e32 v250, v244
	v_rcp_f32_e32 v251, v245
	s_nop 0
	v_pk_fma_f32 v[252:253], v[244:245], v[250:251], 1.0 op_sel_hi:[1,1,0] neg_lo:[1,0,0] neg_hi:[1,0,0]
	v_pk_fma_f32 v[250:251], v[252:253], v[250:251], v[250:251]
	v_pk_fma_f32 v[252:253], v[244:245], v[250:251], 1.0 op_sel_hi:[1,1,0] neg_lo:[1,0,0] neg_hi:[1,0,0]
	v_pk_fma_f32 v[254:255], v[252:253], v[250:251], v[250:251]
	v_pk_fma_f32 v[252:253], v[244:245], v[254:255], 1.0 op_sel_hi:[1,1,0] neg_lo:[1,0,0] neg_hi:[1,0,0]
	v_pk_fma_f32 v[254:255], v[252:253], v[250:251], v[254:255]
	v_div_fixup_f32 v244, v254, v244, 1.0
	v_div_fixup_f32 v245, v255, v245, 1.0
	v_rcp_f32_e32 v250, v246
	v_rcp_f32_e32 v251, v247
	s_nop 0
	v_pk_fma_f32 v[252:253], v[246:247], v[250:251], 1.0 op_sel_hi:[1,1,0] neg_lo:[1,0,0] neg_hi:[1,0,0]
	v_pk_fma_f32 v[250:251], v[252:253], v[250:251], v[250:251]
	v_pk_fma_f32 v[252:253], v[246:247], v[250:251], 1.0 op_sel_hi:[1,1,0] neg_lo:[1,0,0] neg_hi:[1,0,0]
	v_pk_fma_f32 v[254:255], v[252:253], v[250:251], v[250:251]
	v_pk_fma_f32 v[252:253], v[246:247], v[254:255], 1.0 op_sel_hi:[1,1,0] neg_lo:[1,0,0] neg_hi:[1,0,0]
	v_pk_fma_f32 v[254:255], v[252:253], v[250:251], v[254:255]
	v_div_fixup_f32 v246, v254, v246, 1.0
	v_div_fixup_f32 v247, v255, v247, 1.0
	v_rcp_f32_e32 v250, v248
	v_rcp_f32_e32 v251, v249
	s_nop 0
	v_pk_fma_f32 v[252:253], v[248:249], v[250:251], 1.0 op_sel_hi:[1,1,0] neg_lo:[1,0,0] neg_hi:[1,0,0]
	v_pk_fma_f32 v[250:251], v[252:253], v[250:251], v[250:251]
	v_pk_fma_f32 v[252:253], v[248:249], v[250:251], 1.0 op_sel_hi:[1,1,0] neg_lo:[1,0,0] neg_hi:[1,0,0]
	v_pk_fma_f32 v[254:255], v[252:253], v[250:251], v[250:251]
	v_pk_fma_f32 v[252:253], v[248:249], v[254:255], 1.0 op_sel_hi:[1,1,0] neg_lo:[1,0,0] neg_hi:[1,0,0]
	v_pk_fma_f32 v[254:255], v[252:253], v[250:251], v[254:255]
	v_div_fixup_f32 v248, v254, v248, 1.0
	v_div_fixup_f32 v249, v255, v249, 1.0
	v_and_b32_e32 v155, 0xffff0000, v124
	v_lshlrev_b32_e32 v152, 16, v122
	v_and_b32_e32 v153, 0xffff0000, v122
	v_lshlrev_b32_e32 v154, 16, v124
	v_lshlrev_b32_e32 v124, 16, v125
	v_and_b32_e32 v125, 0xffff0000, v125
	v_lshlrev_b32_e32 v122, 16, v123
	v_and_b32_e32 v123, 0xffff0000, v123
	v_pk_fma_f32 v[108:109], v[108:109], v[242:243], v[152:153]
	v_pk_fma_f32 v[118:119], v[106:107], v[248:249], v[124:125]
	v_pk_fma_f32 v[106:107], v[104:105], v[244:245], v[154:155]
	v_add_lshl_u32 v120, v146, v114, 1
	v_pk_fma_f32 v[110:111], v[110:111], v[246:247], v[122:123]
	v_cvt_pk_bf16_f32 v104, v108, v109
	s_nop 0
	v_cvt_pk_bf16_f32 v105, v110, v111
	v_cvt_pk_bf16_f32 v106, v106, v107
	v_cvt_pk_bf16_f32 v107, v118, v119
	buffer_store_dwordx4 v[104:107], v120, s[20:23], 0 offen sc1
	s_nop 0
	s_waitcnt vmcnt(7)
; __device__ __forceinline__ u32x4 pack8(const f32x4 v0, const f32x4 v1) { u32x4 w; w.x = pk2(v0[0], v0[1]); w.y = pk2(v0[2], v0[3]); w.z = pk2(v1[0], v1[1]); w.w = pk2(v1[2], v1[3]); return w; }
; __device__ __forceinline__ void unpack8(const u32x4 w, f32x4& v0, f32x4& v1) { v0 = (f32x4){bflo(w.x), bfhi(w.x), bflo(w.y), bfhi(w.y)}; v1 = (f32x4){bflo(w.z), bfhi(w.z), bflo(w.w), bfhi(w.w)}; }
; __device__ __forceinline__ float sigmoidf_(float x) { return 1.0f / (1.0f + __expf(-x)); }
;     __device__ __forceinline__ void operator()(const f32x4 (&acc)[2][2][4][2], const Unit& u, int wr, int wc, int fr, int fq) const {
;     ...
;         for (int ai = 0; ai < 2; ++ai)
; #pragma unroll
;             for (int m = 0; m < 4; ++m) {
;                 const int row = row0 + ai * 128 + m * 16;
;                 const bf16_t* rowp = z + (size_t)row * DIN + col0;
; #pragma unroll
;                 for (int bj = 0; bj < 2; ++bj) {
;                     const u32x4 gw = *(const u32x4*)(rowp + O_GA + bj * 128);
;                     f32x4 g0, g1; unpack8(gw, g0, g1);
;                     f32x4 v0, v1;
; #pragma unroll
;                     for (int j = 0; j < 4; ++j) { v0[j] = sigmoidf_(g0[j]) * acc[ai][bj][m][0][j]; v1[j] = sigmoidf_(g1[j]) * acc[ai][bj][m][1][j]; }
;                     const u32x4 mw = *(const u32x4*)(rowp + bj * 128); f32x4 m0, m1; unpack8(mw, m0, m1); v0 += m0; v1 += m1;
;                     __builtin_amdgcn_raw_buffer_store_b128(pack8(v0, v1), rsrc, (unsigned)(((size_t)row * DIN + col0 + bj * 128) * 2), 0, 16  ); }
	v_mov_b32_e32 v104, v204
	v_mov_b32_e32 v105, v205
	v_mov_b32_e32 v106, v206
	v_mov_b32_e32 v107, v207
	v_mov_b32_e32 v108, v208
	v_mov_b32_e32 v109, v209
	v_mov_b32_e32 v110, v210
	v_mov_b32_e32 v111, v211
	v_add_u32_e32 v202, 0x67200, v201
	global_load_dwordx4 v[204:207], v202, s[36:37]
	v_add_u32_e32 v202, 0x66000, v201
	global_load_dwordx4 v[208:211], v202, s[36:37]
	s_mov_b32 s100, 0xbfb8aa3b
	v_lshlrev_b32_e32 v242, 16, v106
	v_and_b32_e32 v243, 0xffff0000, v106
	v_lshlrev_b32_e32 v244, 16, v104
	v_and_b32_e32 v245, 0xffff0000, v104
	v_lshlrev_b32_e32 v246, 16, v105
	v_and_b32_e32 v247, 0xffff0000, v105
	v_lshlrev_b32_e32 v248, 16, v107
	v_and_b32_e32 v249, 0xffff0000, v107
	v_pk_mul_f32 v[242:243], v[242:243], s[100:101] op_sel_hi:[1,0]
	v_pk_mul_f32 v[244:245], v[244:245], s[100:101] op_sel_hi:[1,0]
	v_pk_mul_f32 v[246:247], v[246:247], s[100:101] op_sel_hi:[1,0]
	v_pk_mul_f32 v[248:249], v[248:249], s[100:101] op_sel_hi:[1,0]
	v_exp_f32_e32 v242, v242
	v_exp_f32_e32 v243, v243
	v_exp_f32_e32 v244, v244
	v_exp_f32_e32 v245, v245
	v_exp_f32_e32 v246, v246
	v_exp_f32_e32 v247, v247
	v_exp_f32_e32 v248, v248
	v_exp_f32_e32 v249, v249
	s_nop 0
	v_pk_add_f32 v[242:243], v[242:243], 1.0 op_sel_hi:[1,0]
	v_pk_add_f32 v[244:245], v[244:245], 1.0 op_sel_hi:[1,0]
	v_pk_add_f32 v[246:247], v[246:247], 1.0 op_sel_hi:[1,0]
	v_pk_add_f32 v[248:249], v[248:249], 1.0 op_sel_hi:[1,0]
	v_rcp_f32_e32 v250, v242
	v_rcp_f32_e32 v251, v243
	s_nop 0
	v_pk_fma_f32 v[252:253], v[242:243], v[250:251], 1.0 op_sel_hi:[1,1,0] neg_lo:[1,0,0] neg_hi:[1,0,0]
	v_pk_fma_f32 v[250:251], v[252:253], v[250:251], v[250:251]
	v_pk_fma_f32 v[252:253], v[242:243], v[250:251], 1.0 op_sel_hi:[1,1,0] neg_lo:[1,0,0] neg_hi:[1,0,0]
	v_pk_fma_f32 v[254:255], v[252:253], v[250:251], v[250:251]
	v_pk_fma_f32 v[252:253], v[242:243], v[254:255], 1.0 op_sel_hi:[1,1,0] neg_lo:[1,0,0] neg_hi:[1,0,0]
	v_pk_fma_f32 v[254:255], v[252:253], v[250:251], v[254:255]
	v_div_fixup_f32 v242, v254, v242, 1.0
	v_div_fixup_f32 v243, v255, v243, 1.0
	v_rcp_f32_e32 v250, v244
	v_rcp_f32_e32 v251, v245
	s_nop 0
	v_pk_fma_f32 v[252:253], v[244:245], v[250:251], 1.0 op_sel_hi:[1,1,0] neg_lo:[1,0,0] neg_hi:[1,0,0]
	v_pk_fma_f32 v[250:251], v[252:253], v[250:251], v[250:251]
	v_pk_fma_f32 v[252:253], v[244:245], v[250:251], 1.0 op_sel_hi:[1,1,0] neg_lo:[1,0,0] neg_hi:[1,0,0]
	v_pk_fma_f32 v[254:255], v[252:253], v[250:251], v[250:251]
	v_pk_fma_f32 v[252:253], v[244:245], v[254:255], 1.0 op_sel_hi:[1,1,0] neg_lo:[1,0,0] neg_hi:[1,0,0]
	v_pk_fma_f32 v[254:255], v[252:253], v[250:251], v[254:255]
	v_div_fixup_f32 v244, v254, v244, 1.0
	v_div_fixup_f32 v245, v255, v245, 1.0
	v_rcp_f32_e32 v250, v246
	v_rcp_f32_e32 v251, v247
	s_nop 0
	v_pk_fma_f32 v[252:253], v[246:247], v[250:251], 1.0 op_sel_hi:[1,1,0] neg_lo:[1,0,0] neg_hi:[1,0,0]
	v_pk_fma_f32 v[250:251], v[252:253], v[250:251], v[250:251]
	v_pk_fma_f32 v[252:253], v[246:247], v[250:251], 1.0 op_sel_hi:[1,1,0] neg_lo:[1,0,0] neg_hi:[1,0,0]
	v_pk_fma_f32 v[254:255], v[252:253], v[250:251], v[250:251]
	v_pk_fma_f32 v[252:253], v[246:247], v[254:255], 1.0 op_sel_hi:[1,1,0] neg_lo:[1,0,0] neg_hi:[1,0,0]
	v_pk_fma_f32 v[254:255], v[252:253], v[250:251], v[254:255]
	v_div_fixup_f32 v246, v254, v246, 1.0
	v_div_fixup_f32 v247, v255, v247, 1.0
	v_rcp_f32_e32 v250, v248
	v_rcp_f32_e32 v251, v249
	s_nop 0
	v_pk_fma_f32 v[252:253], v[248:249], v[250:251], 1.0 op_sel_hi:[1,1,0] neg_lo:[1,0,0] neg_hi:[1,0,0]
	v_pk_fma_f32 v[250:251], v[252:253], v[250:251], v[250:251]
	v_pk_fma_f32 v[252:253], v[248:249], v[250:251], 1.0 op_sel_hi:[1,1,0] neg_lo:[1,0,0] neg_hi:[1,0,0]
	v_pk_fma_f32 v[254:255], v[252:253], v[250:251], v[250:251]
	v_pk_fma_f32 v[252:253], v[248:249], v[254:255], 1.0 op_sel_hi:[1,1,0] neg_lo:[1,0,0] neg_hi:[1,0,0]
	v_pk_fma_f32 v[254:255], v[252:253], v[250:251], v[254:255]
	v_div_fixup_f32 v248, v254, v248, 1.0
	v_div_fixup_f32 v249, v255, v249, 1.0
	v_lshlrev_b32_e32 v116, 16, v108
	v_and_b32_e32 v117, 0xffff0000, v108
	v_lshlrev_b32_e32 v118, 16, v110
	v_and_b32_e32 v119, 0xffff0000, v110
	v_lshlrev_b32_e32 v110, 16, v111
	v_and_b32_e32 v111, 0xffff0000, v111
	v_lshlrev_b32_e32 v108, 16, v109
	v_and_b32_e32 v109, 0xffff0000, v109
	v_pk_fma_f32 v[100:101], v[100:101], v[244:245], v[116:117]
	v_pk_fma_f32 v[104:105], v[98:99], v[248:249], v[110:111]
	v_pk_fma_f32 v[98:99], v[96:97], v[242:243], v[118:119]
	v_cvt_pk_bf16_f32 v96, v100, v101
	v_pk_fma_f32 v[102:103], v[102:103], v[246:247], v[108:109]
	s_nop 0
	v_cvt_pk_bf16_f32 v97, v102, v103
	v_cvt_pk_bf16_f32 v98, v98, v99
	v_cvt_pk_bf16_f32 v99, v104, v105
	buffer_store_dwordx4 v[96:99], v120, s[20:23], 0 offen offset:256 sc1
	s_nop 1
	v_or_b32_e32 v96, 32, v162
	v_mad_i64_i32 v[98:99], s[6:7], v96, s73, 0
	v_lshl_add_u64 v[96:97], v[98:99], 1, s[36:37]
	v_lshl_add_u64 v[96:97], v[96:97], 0, v[148:149]
	v_add_co_u32_e32 v100, vcc, s74, v96
	s_nop 1
	v_addc_co_u32_e32 v101, vcc, 0, v97, vcc
	s_waitcnt vmcnt(7)
; __device__ __forceinline__ u32x4 pack8(const f32x4 v0, const f32x4 v1) { u32x4 w; w.x = pk2(v0[0], v0[1]); w.y = pk2(v0[2], v0[3]); w.z = pk2(v1[0], v1[1]); w.w = pk2(v1[2], v1[3]); return w; }
; __device__ __forceinline__ void unpack8(const u32x4 w, f32x4& v0, f32x4& v1) { v0 = (f32x4){bflo(w.x), bfhi(w.x), bflo(w.y), bfhi(w.y)}; v1 = (f32x4){bflo(w.z), bfhi(w.z), bflo(w.w), bfhi(w.w)}; }
; __device__ __forceinline__ float sigmoidf_(float x) { return 1.0f / (1.0f + __expf(-x)); }
;     __device__ __forceinline__ void operator()(const f32x4 (&acc)[2][2][4][2], const Unit& u, int wr, int wc, int fr, int fq) const {
;     ...
;         for (int ai = 0; ai < 2; ++ai)
; #pragma unroll
;             for (int m = 0; m < 4; ++m) {
;                 const int row = row0 + ai * 128 + m * 16;
;                 const bf16_t* rowp = z + (size_t)row * DIN + col0;
; #pragma unroll
;                 for (int bj = 0; bj < 2; ++bj) {
;                     const u32x4 gw = *(const u32x4*)(rowp + O_GA + bj * 128);
;                     f32x4 g0, g1; unpack8(gw, g0, g1);
;                     f32x4 v0, v1;
; #pragma unroll
;                     for (int j = 0; j < 4; ++j) { v0[j] = sigmoidf_(g0[j]) * acc[ai][bj][m][0][j]; v1[j] = sigmoidf_(g1[j]) * acc[ai][bj][m][1][j]; }
;                     const u32x4 mw = *(const u32x4*)(rowp + bj * 128); f32x4 m0, m1; unpack8(mw, m0, m1); v0 += m0; v1 += m1;
;                     __builtin_amdgcn_raw_buffer_store_b128(pack8(v0, v1), rsrc, (unsigned)(((size_t)row * DIN + col0 + bj * 128) * 2), 0, 16  ); }
	v_mov_b32_e32 v102, v212
	v_mov_b32_e32 v103, v213
	v_mov_b32_e32 v104, v214
	v_mov_b32_e32 v105, v215
	v_mov_b32_e32 v106, v216
	v_mov_b32_e32 v107, v217
	v_mov_b32_e32 v108, v218
	v_mov_b32_e32 v109, v219
	v_add_u32_e32 v202, 0x67300, v201
	global_load_dwordx4 v[212:215], v202, s[36:37]
	v_add_u32_e32 v202, 0x66100, v201
	global_load_dwordx4 v[216:219], v202, s[36:37]
	s_mov_b32 s100, 0xbfb8aa3b
	v_lshlrev_b32_e32 v242, 16, v102
	v_and_b32_e32 v243, 0xffff0000, v102
	v_lshlrev_b32_e32 v244, 16, v104
	v_and_b32_e32 v245, 0xffff0000, v104
	v_lshlrev_b32_e32 v246, 16, v103
	v_and_b32_e32 v247, 0xffff0000, v103
	v_lshlrev_b32_e32 v248, 16, v105
	v_and_b32_e32 v249, 0xffff0000, v105
	v_pk_mul_f32 v[242:243], v[242:243], s[100:101] op_sel_hi:[1,0]
	v_pk_mul_f32 v[244:245], v[244:245], s[100:101] op_sel_hi:[1,0]
	v_pk_mul_f32 v[246:247], v[246:247], s[100:101] op_sel_hi:[1,0]
	v_pk_mul_f32 v[248:249], v[248:249], s[100:101] op_sel_hi:[1,0]
	v_exp_f32_e32 v242, v242
	v_exp_f32_e32 v243, v243
	v_exp_f32_e32 v244, v244
	v_exp_f32_e32 v245, v245
	v_exp_f32_e32 v246, v246
	v_exp_f32_e32 v247, v247
	v_exp_f32_e32 v248, v248
	v_exp_f32_e32 v249, v249
	s_nop 0
	v_pk_add_f32 v[242:243], v[242:243], 1.0 op_sel_hi:[1,0]
	v_pk_add_f32 v[244:245], v[244:245], 1.0 op_sel_hi:[1,0]
	v_pk_add_f32 v[246:247], v[246:247], 1.0 op_sel_hi:[1,0]
	v_pk_add_f32 v[248:249], v[248:249], 1.0 op_sel_hi:[1,0]
	v_rcp_f32_e32 v250, v242
	v_rcp_f32_e32 v251, v243
	s_nop 0
	v_pk_fma_f32 v[252:253], v[242:243], v[250:251], 1.0 op_sel_hi:[1,1,0] neg_lo:[1,0,0] neg_hi:[1,0,0]
	v_pk_fma_f32 v[250:251], v[252:253], v[250:251], v[250:251]
	v_pk_fma_f32 v[252:253], v[242:243], v[250:251], 1.0 op_sel_hi:[1,1,0] neg_lo:[1,0,0] neg_hi:[1,0,0]
	v_pk_fma_f32 v[254:255], v[252:253], v[250:251], v[250:251]
	v_pk_fma_f32 v[252:253], v[242:243], v[254:255], 1.0 op_sel_hi:[1,1,0] neg_lo:[1,0,0] neg_hi:[1,0,0]
	v_pk_fma_f32 v[254:255], v[252:253], v[250:251], v[254:255]
	v_div_fixup_f32 v242, v254, v242, 1.0
	v_div_fixup_f32 v243, v255, v243, 1.0
	v_rcp_f32_e32 v250, v244
	v_rcp_f32_e32 v251, v245
	s_nop 0
	v_pk_fma_f32 v[252:253], v[244:245], v[250:251], 1.0 op_sel_hi:[1,1,0] neg_lo:[1,0,0] neg_hi:[1,0,0]
	v_pk_fma_f32 v[250:251], v[252:253], v[250:251], v[250:251]
	v_pk_fma_f32 v[252:253], v[244:245], v[250:251], 1.0 op_sel_hi:[1,1,0] neg_lo:[1,0,0] neg_hi:[1,0,0]
	v_pk_fma_f32 v[254:255], v[252:253], v[250:251], v[250:251]
	v_pk_fma_f32 v[252:253], v[244:245], v[254:255], 1.0 op_sel_hi:[1,1,0] neg_lo:[1,0,0] neg_hi:[1,0,0]
	v_pk_fma_f32 v[254:255], v[252:253], v[250:251], v[254:255]
	v_div_fixup_f32 v244, v254, v244, 1.0
	v_div_fixup_f32 v245, v255, v245, 1.0
	v_rcp_f32_e32 v250, v246
	v_rcp_f32_e32 v251, v247
	s_nop 0
	v_pk_fma_f32 v[252:253], v[246:247], v[250:251], 1.0 op_sel_hi:[1,1,0] neg_lo:[1,0,0] neg_hi:[1,0,0]
	v_pk_fma_f32 v[250:251], v[252:253], v[250:251], v[250:251]
	v_pk_fma_f32 v[252:253], v[246:247], v[250:251], 1.0 op_sel_hi:[1,1,0] neg_lo:[1,0,0] neg_hi:[1,0,0]
	v_pk_fma_f32 v[254:255], v[252:253], v[250:251], v[250:251]
	v_pk_fma_f32 v[252:253], v[246:247], v[254:255], 1.0 op_sel_hi:[1,1,0] neg_lo:[1,0,0] neg_hi:[1,0,0]
	v_pk_fma_f32 v[254:255], v[252:253], v[250:251], v[254:255]
	v_div_fixup_f32 v246, v254, v246, 1.0
	v_div_fixup_f32 v247, v255, v247, 1.0
	v_rcp_f32_e32 v250, v248
	v_rcp_f32_e32 v251, v249
	s_nop 0
	v_pk_fma_f32 v[252:253], v[248:249], v[250:251], 1.0 op_sel_hi:[1,1,0] neg_lo:[1,0,0] neg_hi:[1,0,0]
	v_pk_fma_f32 v[250:251], v[252:253], v[250:251], v[250:251]
	v_pk_fma_f32 v[252:253], v[248:249], v[250:251], 1.0 op_sel_hi:[1,1,0] neg_lo:[1,0,0] neg_hi:[1,0,0]
	v_pk_fma_f32 v[254:255], v[252:253], v[250:251], v[250:251]
	v_pk_fma_f32 v[252:253], v[248:249], v[254:255], 1.0 op_sel_hi:[1,1,0] neg_lo:[1,0,0] neg_hi:[1,0,0]
	v_pk_fma_f32 v[254:255], v[252:253], v[250:251], v[254:255]
	v_div_fixup_f32 v248, v254, v248, 1.0
	v_div_fixup_f32 v249, v255, v249, 1.0
	v_lshlrev_b32_e32 v114, 16, v106
	v_and_b32_e32 v115, 0xffff0000, v106
	v_lshlrev_b32_e32 v116, 16, v108
	v_and_b32_e32 v117, 0xffff0000, v108
	v_lshlrev_b32_e32 v108, 16, v109
	v_and_b32_e32 v109, 0xffff0000, v109
	v_lshlrev_b32_e32 v106, 16, v107
	v_and_b32_e32 v107, 0xffff0000, v107
	v_pk_fma_f32 v[92:93], v[92:93], v[242:243], v[114:115]
	v_pk_fma_f32 v[102:103], v[90:91], v[248:249], v[108:109]
	v_pk_fma_f32 v[90:91], v[88:89], v[244:245], v[116:117]
	v_add_lshl_u32 v104, v146, v98, 1
	v_pk_fma_f32 v[94:95], v[94:95], v[246:247], v[106:107]
	v_cvt_pk_bf16_f32 v88, v92, v93
	s_nop 0
	v_cvt_pk_bf16_f32 v89, v94, v95
	v_cvt_pk_bf16_f32 v90, v90, v91
	v_cvt_pk_bf16_f32 v91, v102, v103
	buffer_store_dwordx4 v[88:91], v104, s[20:23], 0 offen sc1
	s_nop 0
	s_waitcnt vmcnt(7)
; __device__ __forceinline__ u32x4 pack8(const f32x4 v0, const f32x4 v1) { u32x4 w; w.x = pk2(v0[0], v0[1]); w.y = pk2(v0[2], v0[3]); w.z = pk2(v1[0], v1[1]); w.w = pk2(v1[2], v1[3]); return w; }
; __device__ __forceinline__ void unpack8(const u32x4 w, f32x4& v0, f32x4& v1) { v0 = (f32x4){bflo(w.x), bfhi(w.x), bflo(w.y), bfhi(w.y)}; v1 = (f32x4){bflo(w.z), bfhi(w.z), bflo(w.w), bfhi(w.w)}; }
; __device__ __forceinline__ float sigmoidf_(float x) { return 1.0f / (1.0f + __expf(-x)); }
;     __device__ __forceinline__ void operator()(const f32x4 (&acc)[2][2][4][2], const Unit& u, int wr, int wc, int fr, int fq) const {
;     ...
;         for (int ai = 0; ai < 2; ++ai)
; #pragma unroll
;             for (int m = 0; m < 4; ++m) {
;                 const int row = row0 + ai * 128 + m * 16;
;                 const bf16_t* rowp = z + (size_t)row * DIN + col0;
; #pragma unroll
;                 for (int bj = 0; bj < 2; ++bj) {
;                     const u32x4 gw = *(const u32x4*)(rowp + O_GA + bj * 128);
;                     f32x4 g0, g1; unpack8(gw, g0, g1);
;                     f32x4 v0, v1;
; #pragma unroll
;                     for (int j = 0; j < 4; ++j) { v0[j] = sigmoidf_(g0[j]) * acc[ai][bj][m][0][j]; v1[j] = sigmoidf_(g1[j]) * acc[ai][bj][m][1][j]; }
;                     const u32x4 mw = *(const u32x4*)(rowp + bj * 128); f32x4 m0, m1; unpack8(mw, m0, m1); v0 += m0; v1 += m1;
;                     __builtin_amdgcn_raw_buffer_store_b128(pack8(v0, v1), rsrc, (unsigned)(((size_t)row * DIN + col0 + bj * 128) * 2), 0, 16  ); }
	v_mov_b32_e32 v88, v232
	v_mov_b32_e32 v89, v233
	v_mov_b32_e32 v90, v234
	v_mov_b32_e32 v91, v235
	v_mov_b32_e32 v92, v236
	v_mov_b32_e32 v93, v237
	v_mov_b32_e32 v94, v238
	v_mov_b32_e32 v95, v239
	v_add_u32_e32 v202, 0x111200, v201
	global_load_dwordx4 v[232:235], v202, s[36:37]
	v_add_u32_e32 v202, 0x110000, v201
	global_load_dwordx4 v[236:239], v202, s[36:37]
	s_mov_b32 s100, 0xbfb8aa3b
	v_lshlrev_b32_e32 v242, 16, v90
	v_and_b32_e32 v243, 0xffff0000, v90
	v_lshlrev_b32_e32 v244, 16, v88
	v_and_b32_e32 v245, 0xffff0000, v88
	v_lshlrev_b32_e32 v246, 16, v89
	v_and_b32_e32 v247, 0xffff0000, v89
	v_lshlrev_b32_e32 v248, 16, v91
	v_and_b32_e32 v249, 0xffff0000, v91
	v_pk_mul_f32 v[242:243], v[242:243], s[100:101] op_sel_hi:[1,0]
	v_pk_mul_f32 v[244:245], v[244:245], s[100:101] op_sel_hi:[1,0]
	v_pk_mul_f32 v[246:247], v[246:247], s[100:101] op_sel_hi:[1,0]
	v_pk_mul_f32 v[248:249], v[248:249], s[100:101] op_sel_hi:[1,0]
	v_exp_f32_e32 v242, v242
	v_exp_f32_e32 v243, v243
	v_exp_f32_e32 v244, v244
	v_exp_f32_e32 v245, v245
	v_exp_f32_e32 v246, v246
	v_exp_f32_e32 v247, v247
	v_exp_f32_e32 v248, v248
	v_exp_f32_e32 v249, v249
	s_nop 0
	v_pk_add_f32 v[242:243], v[242:243], 1.0 op_sel_hi:[1,0]
	v_pk_add_f32 v[244:245], v[244:245], 1.0 op_sel_hi:[1,0]
	v_pk_add_f32 v[246:247], v[246:247], 1.0 op_sel_hi:[1,0]
	v_pk_add_f32 v[248:249], v[248:249], 1.0 op_sel_hi:[1,0]
	v_rcp_f32_e32 v250, v242
	v_rcp_f32_e32 v251, v243
	s_nop 0
	v_pk_fma_f32 v[252:253], v[242:243], v[250:251], 1.0 op_sel_hi:[1,1,0] neg_lo:[1,0,0] neg_hi:[1,0,0]
	v_pk_fma_f32 v[250:251], v[252:253], v[250:251], v[250:251]
	v_pk_fma_f32 v[252:253], v[242:243], v[250:251], 1.0 op_sel_hi:[1,1,0] neg_lo:[1,0,0] neg_hi:[1,0,0]
	v_pk_fma_f32 v[254:255], v[252:253], v[250:251], v[250:251]
	v_pk_fma_f32 v[252:253], v[242:243], v[254:255], 1.0 op_sel_hi:[1,1,0] neg_lo:[1,0,0] neg_hi:[1,0,0]
	v_pk_fma_f32 v[254:255], v[252:253], v[250:251], v[254:255]
	v_div_fixup_f32 v242, v254, v242, 1.0
	v_div_fixup_f32 v243, v255, v243, 1.0
	v_rcp_f32_e32 v250, v244
	v_rcp_f32_e32 v251, v245
	s_nop 0
	v_pk_fma_f32 v[252:253], v[244:245], v[250:251], 1.0 op_sel_hi:[1,1,0] neg_lo:[1,0,0] neg_hi:[1,0,0]
	v_pk_fma_f32 v[250:251], v[252:253], v[250:251], v[250:251]
	v_pk_fma_f32 v[252:253], v[244:245], v[250:251], 1.0 op_sel_hi:[1,1,0] neg_lo:[1,0,0] neg_hi:[1,0,0]
	v_pk_fma_f32 v[254:255], v[252:253], v[250:251], v[250:251]
	v_pk_fma_f32 v[252:253], v[244:245], v[254:255], 1.0 op_sel_hi:[1,1,0] neg_lo:[1,0,0] neg_hi:[1,0,0]
	v_pk_fma_f32 v[254:255], v[252:253], v[250:251], v[254:255]
	v_div_fixup_f32 v244, v254, v244, 1.0
	v_div_fixup_f32 v245, v255, v245, 1.0
	v_rcp_f32_e32 v250, v246
	v_rcp_f32_e32 v251, v247
	s_nop 0
	v_pk_fma_f32 v[252:253], v[246:247], v[250:251], 1.0 op_sel_hi:[1,1,0] neg_lo:[1,0,0] neg_hi:[1,0,0]
	v_pk_fma_f32 v[250:251], v[252:253], v[250:251], v[250:251]
	v_pk_fma_f32 v[252:253], v[246:247], v[250:251], 1.0 op_sel_hi:[1,1,0] neg_lo:[1,0,0] neg_hi:[1,0,0]
	v_pk_fma_f32 v[254:255], v[252:253], v[250:251], v[250:251]
	v_pk_fma_f32 v[252:253], v[246:247], v[254:255], 1.0 op_sel_hi:[1,1,0] neg_lo:[1,0,0] neg_hi:[1,0,0]
	v_pk_fma_f32 v[254:255], v[252:253], v[250:251], v[254:255]
	v_div_fixup_f32 v246, v254, v246, 1.0
	v_div_fixup_f32 v247, v255, v247, 1.0
	v_rcp_f32_e32 v250, v248
	v_rcp_f32_e32 v251, v249
	s_nop 0
	v_pk_fma_f32 v[252:253], v[248:249], v[250:251], 1.0 op_sel_hi:[1,1,0] neg_lo:[1,0,0] neg_hi:[1,0,0]
	v_pk_fma_f32 v[250:251], v[252:253], v[250:251], v[250:251]
	v_pk_fma_f32 v[252:253], v[248:249], v[250:251], 1.0 op_sel_hi:[1,1,0] neg_lo:[1,0,0] neg_hi:[1,0,0]
	v_pk_fma_f32 v[254:255], v[252:253], v[250:251], v[250:251]
	v_pk_fma_f32 v[252:253], v[248:249], v[254:255], 1.0 op_sel_hi:[1,1,0] neg_lo:[1,0,0] neg_hi:[1,0,0]
	v_pk_fma_f32 v[254:255], v[252:253], v[250:251], v[254:255]
	v_div_fixup_f32 v248, v254, v248, 1.0
	v_div_fixup_f32 v249, v255, v249, 1.0
	v_lshlrev_b32_e32 v100, 16, v92
	v_and_b32_e32 v101, 0xffff0000, v92
	v_lshlrev_b32_e32 v102, 16, v94
	v_and_b32_e32 v103, 0xffff0000, v94
	v_lshlrev_b32_e32 v94, 16, v95
	v_and_b32_e32 v95, 0xffff0000, v95
	v_lshlrev_b32_e32 v92, 16, v93
	v_and_b32_e32 v93, 0xffff0000, v93
	v_pk_fma_f32 v[84:85], v[84:85], v[244:245], v[100:101]
	v_pk_fma_f32 v[88:89], v[82:83], v[248:249], v[94:95]
	v_pk_fma_f32 v[82:83], v[80:81], v[242:243], v[102:103]
	v_cvt_pk_bf16_f32 v80, v84, v85
	v_pk_fma_f32 v[86:87], v[86:87], v[246:247], v[92:93]
	s_nop 0
	v_cvt_pk_bf16_f32 v81, v86, v87
	v_cvt_pk_bf16_f32 v82, v82, v83
	v_cvt_pk_bf16_f32 v83, v88, v89
	buffer_store_dwordx4 v[80:83], v104, s[20:23], 0 offen offset:256 sc1
	s_nop 1
	v_or_b32_e32 v80, 48, v162
	v_mad_i64_i32 v[82:83], s[6:7], v80, s73, 0
	v_lshl_add_u64 v[80:81], v[82:83], 1, s[36:37]
	v_lshl_add_u64 v[80:81], v[80:81], 0, v[148:149]
	v_add_co_u32_e32 v84, vcc, s74, v80
	s_nop 1
	v_addc_co_u32_e32 v85, vcc, 0, v81, vcc
	s_waitcnt vmcnt(7)
; __device__ __forceinline__ float sigmoidf_(float x) { return 1.0f / (1.0f + __expf(-x)); }
; __device__ __forceinline__ u32x4 pack8(const f32x4 v0, const f32x4 v1) { u32x4 w; w.x = pk2(v0[0], v0[1]); w.y = pk2(v0[2], v0[3]); w.z = pk2(v1[0], v1[1]); w.w = pk2(v1[2], v1[3]); return w; }
; __device__ __forceinline__ void unpack8(const u32x4 w, f32x4& v0, f32x4& v1) { v0 = (f32x4){bflo(w.x), bfhi(w.x), bflo(w.y), bfhi(w.y)}; v1 = (f32x4){bflo(w.z), bfhi(w.z), bflo(w.w), bfhi(w.w)}; }
;     __device__ __forceinline__ void operator()(const f32x4 (&acc)[2][2][4][2], const Unit& u, int wr, int wc, int fr, int fq) const {
;     ...
;                 const int row = row0 + ai * 128 + m * 16;
;                 const bf16_t* rowp = z + (size_t)row * DIN + col0;
; #pragma unroll
;                 for (int bj = 0; bj < 2; ++bj) {
;                     const u32x4 gw = *(const u32x4*)(rowp + O_GA + bj * 128);
;                     f32x4 g0, g1; unpack8(gw, g0, g1);
;                     f32x4 v0, v1;
; #pragma unroll
;                     for (int j = 0; j < 4; ++j) { v0[j] = sigmoidf_(g0[j]) * acc[ai][bj][m][0][j]; v1[j] = sigmoidf_(g1[j]) * acc[ai][bj][m][1][j]; }
;                     const u32x4 mw = *(const u32x4*)(rowp + bj * 128); f32x4 m0, m1; unpack8(mw, m0, m1); v0 += m0; v1 += m1;
;                     __builtin_amdgcn_raw_buffer_store_b128(pack8(v0, v1), rsrc, (unsigned)(((size_t)row * DIN + col0 + bj * 128) * 2), 0, 16  ); }
	v_mov_b32_e32 v86, v204
	v_mov_b32_e32 v87, v205
	v_mov_b32_e32 v88, v206
	v_mov_b32_e32 v89, v207
	v_mov_b32_e32 v90, v208
	v_mov_b32_e32 v91, v209
	v_mov_b32_e32 v92, v210
	v_mov_b32_e32 v93, v211
	v_add_u32_e32 v202, 0x111300, v201
	global_load_dwordx4 v[204:207], v202, s[36:37]
	v_add_u32_e32 v202, 0x110100, v201
	global_load_dwordx4 v[208:211], v202, s[36:37]
	s_mov_b32 s100, 0xbfb8aa3b
	v_lshlrev_b32_e32 v242, 16, v86
	v_and_b32_e32 v243, 0xffff0000, v86
	v_lshlrev_b32_e32 v244, 16, v88
	v_and_b32_e32 v245, 0xffff0000, v88
	v_lshlrev_b32_e32 v246, 16, v87
	v_and_b32_e32 v247, 0xffff0000, v87
	v_lshlrev_b32_e32 v248, 16, v89
	v_and_b32_e32 v249, 0xffff0000, v89
	v_pk_mul_f32 v[242:243], v[242:243], s[100:101] op_sel_hi:[1,0]
	v_pk_mul_f32 v[244:245], v[244:245], s[100:101] op_sel_hi:[1,0]
	v_pk_mul_f32 v[246:247], v[246:247], s[100:101] op_sel_hi:[1,0]
	v_pk_mul_f32 v[248:249], v[248:249], s[100:101] op_sel_hi:[1,0]
	v_exp_f32_e32 v242, v242
	v_exp_f32_e32 v243, v243
	v_exp_f32_e32 v244, v244
	v_exp_f32_e32 v245, v245
	v_exp_f32_e32 v246, v246
	v_exp_f32_e32 v247, v247
	v_exp_f32_e32 v248, v248
	v_exp_f32_e32 v249, v249
	s_nop 0
	v_pk_add_f32 v[242:243], v[242:243], 1.0 op_sel_hi:[1,0]
	v_pk_add_f32 v[244:245], v[244:245], 1.0 op_sel_hi:[1,0]
	v_pk_add_f32 v[246:247], v[246:247], 1.0 op_sel_hi:[1,0]
	v_pk_add_f32 v[248:249], v[248:249], 1.0 op_sel_hi:[1,0]
	v_rcp_f32_e32 v250, v242
	v_rcp_f32_e32 v251, v243
	s_nop 0
	v_pk_fma_f32 v[252:253], v[242:243], v[250:251], 1.0 op_sel_hi:[1,1,0] neg_lo:[1,0,0] neg_hi:[1,0,0]
	v_pk_fma_f32 v[250:251], v[252:253], v[250:251], v[250:251]
	v_pk_fma_f32 v[252:253], v[242:243], v[250:251], 1.0 op_sel_hi:[1,1,0] neg_lo:[1,0,0] neg_hi:[1,0,0]
	v_pk_fma_f32 v[254:255], v[252:253], v[250:251], v[250:251]
	v_pk_fma_f32 v[252:253], v[242:243], v[254:255], 1.0 op_sel_hi:[1,1,0] neg_lo:[1,0,0] neg_hi:[1,0,0]
	v_pk_fma_f32 v[254:255], v[252:253], v[250:251], v[254:255]
	v_div_fixup_f32 v242, v254, v242, 1.0
	v_div_fixup_f32 v243, v255, v243, 1.0
	v_rcp_f32_e32 v250, v244
	v_rcp_f32_e32 v251, v245
	s_nop 0
	v_pk_fma_f32 v[252:253], v[244:245], v[250:251], 1.0 op_sel_hi:[1,1,0] neg_lo:[1,0,0] neg_hi:[1,0,0]
	v_pk_fma_f32 v[250:251], v[252:253], v[250:251], v[250:251]
	v_pk_fma_f32 v[252:253], v[244:245], v[250:251], 1.0 op_sel_hi:[1,1,0] neg_lo:[1,0,0] neg_hi:[1,0,0]
	v_pk_fma_f32 v[254:255], v[252:253], v[250:251], v[250:251]
	v_pk_fma_f32 v[252:253], v[244:245], v[254:255], 1.0 op_sel_hi:[1,1,0] neg_lo:[1,0,0] neg_hi:[1,0,0]
	v_pk_fma_f32 v[254:255], v[252:253], v[250:251], v[254:255]
	v_div_fixup_f32 v244, v254, v244, 1.0
	v_div_fixup_f32 v245, v255, v245, 1.0
	v_rcp_f32_e32 v250, v246
	v_rcp_f32_e32 v251, v247
	s_nop 0
	v_pk_fma_f32 v[252:253], v[246:247], v[250:251], 1.0 op_sel_hi:[1,1,0] neg_lo:[1,0,0] neg_hi:[1,0,0]
	v_pk_fma_f32 v[250:251], v[252:253], v[250:251], v[250:251]
	v_pk_fma_f32 v[252:253], v[246:247], v[250:251], 1.0 op_sel_hi:[1,1,0] neg_lo:[1,0,0] neg_hi:[1,0,0]
	v_pk_fma_f32 v[254:255], v[252:253], v[250:251], v[250:251]
	v_pk_fma_f32 v[252:253], v[246:247], v[254:255], 1.0 op_sel_hi:[1,1,0] neg_lo:[1,0,0] neg_hi:[1,0,0]
	v_pk_fma_f32 v[254:255], v[252:253], v[250:251], v[254:255]
	v_div_fixup_f32 v246, v254, v246, 1.0
	v_div_fixup_f32 v247, v255, v247, 1.0
	v_rcp_f32_e32 v250, v248
	v_rcp_f32_e32 v251, v249
	s_nop 0
	v_pk_fma_f32 v[252:253], v[248:249], v[250:251], 1.0 op_sel_hi:[1,1,0] neg_lo:[1,0,0] neg_hi:[1,0,0]
	v_pk_fma_f32 v[250:251], v[252:253], v[250:251], v[250:251]
	v_pk_fma_f32 v[252:253], v[248:249], v[250:251], 1.0 op_sel_hi:[1,1,0] neg_lo:[1,0,0] neg_hi:[1,0,0]
	v_pk_fma_f32 v[254:255], v[252:253], v[250:251], v[250:251]
	v_pk_fma_f32 v[252:253], v[248:249], v[254:255], 1.0 op_sel_hi:[1,1,0] neg_lo:[1,0,0] neg_hi:[1,0,0]
	v_pk_fma_f32 v[254:255], v[252:253], v[250:251], v[254:255]
	v_div_fixup_f32 v248, v254, v248, 1.0
	v_div_fixup_f32 v249, v255, v249, 1.0
	v_lshlrev_b32_e32 v98, 16, v90
	v_and_b32_e32 v99, 0xffff0000, v90
	v_lshlrev_b32_e32 v100, 16, v92
	v_and_b32_e32 v101, 0xffff0000, v92
	v_lshlrev_b32_e32 v92, 16, v93
	v_and_b32_e32 v93, 0xffff0000, v93
	v_lshlrev_b32_e32 v90, 16, v91
	v_and_b32_e32 v91, 0xffff0000, v91
	v_pk_fma_f32 v[76:77], v[76:77], v[242:243], v[98:99]
	v_pk_fma_f32 v[86:87], v[74:75], v[248:249], v[92:93]
	v_pk_fma_f32 v[74:75], v[72:73], v[244:245], v[100:101]
	v_add_lshl_u32 v88, v146, v82, 1
	v_pk_fma_f32 v[78:79], v[78:79], v[246:247], v[90:91]
	v_cvt_pk_bf16_f32 v72, v76, v77
	s_nop 0
	v_cvt_pk_bf16_f32 v73, v78, v79
	v_cvt_pk_bf16_f32 v74, v74, v75
	v_cvt_pk_bf16_f32 v75, v86, v87
	buffer_store_dwordx4 v[72:75], v88, s[20:23], 0 offen sc1
	s_nop 0
	s_waitcnt vmcnt(7)
; __device__ __forceinline__ float sigmoidf_(float x) { return 1.0f / (1.0f + __expf(-x)); }
; __device__ __forceinline__ u32x4 pack8(const f32x4 v0, const f32x4 v1) { u32x4 w; w.x = pk2(v0[0], v0[1]); w.y = pk2(v0[2], v0[3]); w.z = pk2(v1[0], v1[1]); w.w = pk2(v1[2], v1[3]); return w; }
; __device__ __forceinline__ void unpack8(const u32x4 w, f32x4& v0, f32x4& v1) { v0 = (f32x4){bflo(w.x), bfhi(w.x), bflo(w.y), bfhi(w.y)}; v1 = (f32x4){bflo(w.z), bfhi(w.z), bflo(w.w), bfhi(w.w)}; }
;     __device__ __forceinline__ void operator()(const f32x4 (&acc)[2][2][4][2], const Unit& u, int wr, int wc, int fr, int fq) const {
;     ...
;                 const int row = row0 + ai * 128 + m * 16;
;                 const bf16_t* rowp = z + (size_t)row * DIN + col0;
; #pragma unroll
;                 for (int bj = 0; bj < 2; ++bj) {
;                     const u32x4 gw = *(const u32x4*)(rowp + O_GA + bj * 128);
;                     f32x4 g0, g1; unpack8(gw, g0, g1);
;                     f32x4 v0, v1;
; #pragma unroll
;                     for (int j = 0; j < 4; ++j) { v0[j] = sigmoidf_(g0[j]) * acc[ai][bj][m][0][j]; v1[j] = sigmoidf_(g1[j]) * acc[ai][bj][m][1][j]; }
;                     const u32x4 mw = *(const u32x4*)(rowp + bj * 128); f32x4 m0, m1; unpack8(mw, m0, m1); v0 += m0; v1 += m1;
;                     __builtin_amdgcn_raw_buffer_store_b128(pack8(v0, v1), rsrc, (unsigned)(((size_t)row * DIN + col0 + bj * 128) * 2), 0, 16  ); }
	v_mov_b32_e32 v72, v212
	v_mov_b32_e32 v73, v213
	v_mov_b32_e32 v74, v214
	v_mov_b32_e32 v75, v215
	v_mov_b32_e32 v76, v216
	v_mov_b32_e32 v77, v217
	v_mov_b32_e32 v78, v218
	v_mov_b32_e32 v79, v219
	v_add_u32_e32 v202, 0x133200, v201
	global_load_dwordx4 v[212:215], v202, s[36:37]
	v_add_u32_e32 v202, 0x132000, v201
	global_load_dwordx4 v[216:219], v202, s[36:37]
	s_mov_b32 s100, 0xbfb8aa3b
	v_lshlrev_b32_e32 v242, 16, v74
	v_and_b32_e32 v243, 0xffff0000, v74
	v_lshlrev_b32_e32 v244, 16, v72
	v_and_b32_e32 v245, 0xffff0000, v72
	v_lshlrev_b32_e32 v246, 16, v73
	v_and_b32_e32 v247, 0xffff0000, v73
	v_lshlrev_b32_e32 v248, 16, v75
	v_and_b32_e32 v249, 0xffff0000, v75
	v_pk_mul_f32 v[242:243], v[242:243], s[100:101] op_sel_hi:[1,0]
	v_pk_mul_f32 v[244:245], v[244:245], s[100:101] op_sel_hi:[1,0]
	v_pk_mul_f32 v[246:247], v[246:247], s[100:101] op_sel_hi:[1,0]
	v_pk_mul_f32 v[248:249], v[248:249], s[100:101] op_sel_hi:[1,0]
	v_exp_f32_e32 v242, v242
	v_exp_f32_e32 v243, v243
	v_exp_f32_e32 v244, v244
	v_exp_f32_e32 v245, v245
	v_exp_f32_e32 v246, v246
	v_exp_f32_e32 v247, v247
	v_exp_f32_e32 v248, v248
	v_exp_f32_e32 v249, v249
	s_nop 0
	v_pk_add_f32 v[242:243], v[242:243], 1.0 op_sel_hi:[1,0]
	v_pk_add_f32 v[244:245], v[244:245], 1.0 op_sel_hi:[1,0]
	v_pk_add_f32 v[246:247], v[246:247], 1.0 op_sel_hi:[1,0]
	v_pk_add_f32 v[248:249], v[248:249], 1.0 op_sel_hi:[1,0]
	v_rcp_f32_e32 v250, v242
	v_rcp_f32_e32 v251, v243
	s_nop 0
	v_pk_fma_f32 v[252:253], v[242:243], v[250:251], 1.0 op_sel_hi:[1,1,0] neg_lo:[1,0,0] neg_hi:[1,0,0]
	v_pk_fma_f32 v[250:251], v[252:253], v[250:251], v[250:251]
	v_pk_fma_f32 v[252:253], v[242:243], v[250:251], 1.0 op_sel_hi:[1,1,0] neg_lo:[1,0,0] neg_hi:[1,0,0]
	v_pk_fma_f32 v[254:255], v[252:253], v[250:251], v[250:251]
	v_pk_fma_f32 v[252:253], v[242:243], v[254:255], 1.0 op_sel_hi:[1,1,0] neg_lo:[1,0,0] neg_hi:[1,0,0]
	v_pk_fma_f32 v[254:255], v[252:253], v[250:251], v[254:255]
	v_div_fixup_f32 v242, v254, v242, 1.0
	v_div_fixup_f32 v243, v255, v243, 1.0
	v_rcp_f32_e32 v250, v244
	v_rcp_f32_e32 v251, v245
	s_nop 0
	v_pk_fma_f32 v[252:253], v[244:245], v[250:251], 1.0 op_sel_hi:[1,1,0] neg_lo:[1,0,0] neg_hi:[1,0,0]
	v_pk_fma_f32 v[250:251], v[252:253], v[250:251], v[250:251]
	v_pk_fma_f32 v[252:253], v[244:245], v[250:251], 1.0 op_sel_hi:[1,1,0] neg_lo:[1,0,0] neg_hi:[1,0,0]
	v_pk_fma_f32 v[254:255], v[252:253], v[250:251], v[250:251]
	v_pk_fma_f32 v[252:253], v[244:245], v[254:255], 1.0 op_sel_hi:[1,1,0] neg_lo:[1,0,0] neg_hi:[1,0,0]
	v_pk_fma_f32 v[254:255], v[252:253], v[250:251], v[254:255]
	v_div_fixup_f32 v244, v254, v244, 1.0
	v_div_fixup_f32 v245, v255, v245, 1.0
	v_rcp_f32_e32 v250, v246
	v_rcp_f32_e32 v251, v247
	s_nop 0
	v_pk_fma_f32 v[252:253], v[246:247], v[250:251], 1.0 op_sel_hi:[1,1,0] neg_lo:[1,0,0] neg_hi:[1,0,0]
	v_pk_fma_f32 v[250:251], v[252:253], v[250:251], v[250:251]
	v_pk_fma_f32 v[252:253], v[246:247], v[250:251], 1.0 op_sel_hi:[1,1,0] neg_lo:[1,0,0] neg_hi:[1,0,0]
	v_pk_fma_f32 v[254:255], v[252:253], v[250:251], v[250:251]
	v_pk_fma_f32 v[252:253], v[246:247], v[254:255], 1.0 op_sel_hi:[1,1,0] neg_lo:[1,0,0] neg_hi:[1,0,0]
	v_pk_fma_f32 v[254:255], v[252:253], v[250:251], v[254:255]
	v_div_fixup_f32 v246, v254, v246, 1.0
	v_div_fixup_f32 v247, v255, v247, 1.0
	v_rcp_f32_e32 v250, v248
	v_rcp_f32_e32 v251, v249
	s_nop 0
	v_pk_fma_f32 v[252:253], v[248:249], v[250:251], 1.0 op_sel_hi:[1,1,0] neg_lo:[1,0,0] neg_hi:[1,0,0]
	v_pk_fma_f32 v[250:251], v[252:253], v[250:251], v[250:251]
	v_pk_fma_f32 v[252:253], v[248:249], v[250:251], 1.0 op_sel_hi:[1,1,0] neg_lo:[1,0,0] neg_hi:[1,0,0]
	v_pk_fma_f32 v[254:255], v[252:253], v[250:251], v[250:251]
	v_pk_fma_f32 v[252:253], v[248:249], v[254:255], 1.0 op_sel_hi:[1,1,0] neg_lo:[1,0,0] neg_hi:[1,0,0]
	v_pk_fma_f32 v[254:255], v[252:253], v[250:251], v[254:255]
	v_div_fixup_f32 v248, v254, v248, 1.0
	v_div_fixup_f32 v249, v255, v249, 1.0
	v_lshlrev_b32_e32 v84, 16, v76
	v_and_b32_e32 v85, 0xffff0000, v76
	v_lshlrev_b32_e32 v86, 16, v78
	v_and_b32_e32 v87, 0xffff0000, v78
	v_lshlrev_b32_e32 v78, 16, v79
	v_and_b32_e32 v79, 0xffff0000, v79
	v_lshlrev_b32_e32 v76, 16, v77
	v_and_b32_e32 v77, 0xffff0000, v77
	v_pk_fma_f32 v[68:69], v[68:69], v[244:245], v[84:85]
	v_pk_fma_f32 v[72:73], v[66:67], v[248:249], v[78:79]
	v_pk_fma_f32 v[66:67], v[64:65], v[242:243], v[86:87]
	v_cvt_pk_bf16_f32 v64, v68, v69
	v_pk_fma_f32 v[70:71], v[70:71], v[246:247], v[76:77]
	s_nop 0
	v_cvt_pk_bf16_f32 v65, v70, v71
	v_cvt_pk_bf16_f32 v66, v66, v67
	v_cvt_pk_bf16_f32 v67, v72, v73
	buffer_store_dwordx4 v[64:67], v88, s[20:23], 0 offen offset:256 sc1
	s_nop 1
	v_add_u32_e32 v64, 0x80, v162
	v_mad_i64_i32 v[66:67], s[6:7], v64, s73, 0
	v_lshl_add_u64 v[64:65], v[66:67], 1, s[36:37]
	v_lshl_add_u64 v[64:65], v[64:65], 0, v[148:149]
	v_add_co_u32_e32 v68, vcc, s74, v64
	s_nop 1
	v_addc_co_u32_e32 v69, vcc, 0, v65, vcc
	s_waitcnt vmcnt(7)
; __device__ __forceinline__ float sigmoidf_(float x) { return 1.0f / (1.0f + __expf(-x)); }
; __device__ __forceinline__ u32x4 pack8(const f32x4 v0, const f32x4 v1) { u32x4 w; w.x = pk2(v0[0], v0[1]); w.y = pk2(v0[2], v0[3]); w.z = pk2(v1[0], v1[1]); w.w = pk2(v1[2], v1[3]); return w; }
; __device__ __forceinline__ void unpack8(const u32x4 w, f32x4& v0, f32x4& v1) { v0 = (f32x4){bflo(w.x), bfhi(w.x), bflo(w.y), bfhi(w.y)}; v1 = (f32x4){bflo(w.z), bfhi(w.z), bflo(w.w), bfhi(w.w)}; }
;     __device__ __forceinline__ void operator()(const f32x4 (&acc)[2][2][4][2], const Unit& u, int wr, int wc, int fr, int fq) const {
;     ...
;                 const int row = row0 + ai * 128 + m * 16;
;                 const bf16_t* rowp = z + (size_t)row * DIN + col0;
; #pragma unroll
;                 for (int bj = 0; bj < 2; ++bj) {
;                     const u32x4 gw = *(const u32x4*)(rowp + O_GA + bj * 128);
;                     f32x4 g0, g1; unpack8(gw, g0, g1);
;                     f32x4 v0, v1;
; #pragma unroll
;                     for (int j = 0; j < 4; ++j) { v0[j] = sigmoidf_(g0[j]) * acc[ai][bj][m][0][j]; v1[j] = sigmoidf_(g1[j]) * acc[ai][bj][m][1][j]; }
;                     const u32x4 mw = *(const u32x4*)(rowp + bj * 128); f32x4 m0, m1; unpack8(mw, m0, m1); v0 += m0; v1 += m1;
;                     __builtin_amdgcn_raw_buffer_store_b128(pack8(v0, v1), rsrc, (unsigned)(((size_t)row * DIN + col0 + bj * 128) * 2), 0, 16  ); }
	v_mov_b32_e32 v70, v232
	v_mov_b32_e32 v71, v233
	v_mov_b32_e32 v72, v234
	v_mov_b32_e32 v73, v235
	v_mov_b32_e32 v74, v236
	v_mov_b32_e32 v75, v237
	v_mov_b32_e32 v76, v238
	v_mov_b32_e32 v77, v239
	v_add_u32_e32 v202, 0x133300, v201
	global_load_dwordx4 v[232:235], v202, s[36:37]
	v_add_u32_e32 v202, 0x132100, v201
	global_load_dwordx4 v[236:239], v202, s[36:37]
	s_mov_b32 s100, 0xbfb8aa3b
	v_lshlrev_b32_e32 v242, 16, v70
	v_and_b32_e32 v243, 0xffff0000, v70
	v_lshlrev_b32_e32 v244, 16, v72
	v_and_b32_e32 v245, 0xffff0000, v72
	v_lshlrev_b32_e32 v246, 16, v71
	v_and_b32_e32 v247, 0xffff0000, v71
	v_lshlrev_b32_e32 v248, 16, v73
	v_and_b32_e32 v249, 0xffff0000, v73
	v_pk_mul_f32 v[242:243], v[242:243], s[100:101] op_sel_hi:[1,0]
	v_pk_mul_f32 v[244:245], v[244:245], s[100:101] op_sel_hi:[1,0]
	v_pk_mul_f32 v[246:247], v[246:247], s[100:101] op_sel_hi:[1,0]
	v_pk_mul_f32 v[248:249], v[248:249], s[100:101] op_sel_hi:[1,0]
	v_exp_f32_e32 v242, v242
	v_exp_f32_e32 v243, v243
	v_exp_f32_e32 v244, v244
	v_exp_f32_e32 v245, v245
	v_exp_f32_e32 v246, v246
	v_exp_f32_e32 v247, v247
	v_exp_f32_e32 v248, v248
	v_exp_f32_e32 v249, v249
	s_nop 0
	v_pk_add_f32 v[242:243], v[242:243], 1.0 op_sel_hi:[1,0]
	v_pk_add_f32 v[244:245], v[244:245], 1.0 op_sel_hi:[1,0]
	v_pk_add_f32 v[246:247], v[246:247], 1.0 op_sel_hi:[1,0]
	v_pk_add_f32 v[248:249], v[248:249], 1.0 op_sel_hi:[1,0]
	v_rcp_f32_e32 v250, v242
	v_rcp_f32_e32 v251, v243
	s_nop 0
	v_pk_fma_f32 v[252:253], v[242:243], v[250:251], 1.0 op_sel_hi:[1,1,0] neg_lo:[1,0,0] neg_hi:[1,0,0]
	v_pk_fma_f32 v[250:251], v[252:253], v[250:251], v[250:251]
	v_pk_fma_f32 v[252:253], v[242:243], v[250:251], 1.0 op_sel_hi:[1,1,0] neg_lo:[1,0,0] neg_hi:[1,0,0]
	v_pk_fma_f32 v[254:255], v[252:253], v[250:251], v[250:251]
	v_pk_fma_f32 v[252:253], v[242:243], v[254:255], 1.0 op_sel_hi:[1,1,0] neg_lo:[1,0,0] neg_hi:[1,0,0]
	v_pk_fma_f32 v[254:255], v[252:253], v[250:251], v[254:255]
	v_div_fixup_f32 v242, v254, v242, 1.0
	v_div_fixup_f32 v243, v255, v243, 1.0
	v_rcp_f32_e32 v250, v244
	v_rcp_f32_e32 v251, v245
	s_nop 0
	v_pk_fma_f32 v[252:253], v[244:245], v[250:251], 1.0 op_sel_hi:[1,1,0] neg_lo:[1,0,0] neg_hi:[1,0,0]
	v_pk_fma_f32 v[250:251], v[252:253], v[250:251], v[250:251]
	v_pk_fma_f32 v[252:253], v[244:245], v[250:251], 1.0 op_sel_hi:[1,1,0] neg_lo:[1,0,0] neg_hi:[1,0,0]
	v_pk_fma_f32 v[254:255], v[252:253], v[250:251], v[250:251]
	v_pk_fma_f32 v[252:253], v[244:245], v[254:255], 1.0 op_sel_hi:[1,1,0] neg_lo:[1,0,0] neg_hi:[1,0,0]
	v_pk_fma_f32 v[254:255], v[252:253], v[250:251], v[254:255]
	v_div_fixup_f32 v244, v254, v244, 1.0
	v_div_fixup_f32 v245, v255, v245, 1.0
	v_rcp_f32_e32 v250, v246
	v_rcp_f32_e32 v251, v247
	s_nop 0
	v_pk_fma_f32 v[252:253], v[246:247], v[250:251], 1.0 op_sel_hi:[1,1,0] neg_lo:[1,0,0] neg_hi:[1,0,0]
	v_pk_fma_f32 v[250:251], v[252:253], v[250:251], v[250:251]
	v_pk_fma_f32 v[252:253], v[246:247], v[250:251], 1.0 op_sel_hi:[1,1,0] neg_lo:[1,0,0] neg_hi:[1,0,0]
	v_pk_fma_f32 v[254:255], v[252:253], v[250:251], v[250:251]
	v_pk_fma_f32 v[252:253], v[246:247], v[254:255], 1.0 op_sel_hi:[1,1,0] neg_lo:[1,0,0] neg_hi:[1,0,0]
	v_pk_fma_f32 v[254:255], v[252:253], v[250:251], v[254:255]
	v_div_fixup_f32 v246, v254, v246, 1.0
	v_div_fixup_f32 v247, v255, v247, 1.0
	v_rcp_f32_e32 v250, v248
	v_rcp_f32_e32 v251, v249
	s_nop 0
	v_pk_fma_f32 v[252:253], v[248:249], v[250:251], 1.0 op_sel_hi:[1,1,0] neg_lo:[1,0,0] neg_hi:[1,0,0]
	v_pk_fma_f32 v[250:251], v[252:253], v[250:251], v[250:251]
	v_pk_fma_f32 v[252:253], v[248:249], v[250:251], 1.0 op_sel_hi:[1,1,0] neg_lo:[1,0,0] neg_hi:[1,0,0]
	v_pk_fma_f32 v[254:255], v[252:253], v[250:251], v[250:251]
	v_pk_fma_f32 v[252:253], v[248:249], v[254:255], 1.0 op_sel_hi:[1,1,0] neg_lo:[1,0,0] neg_hi:[1,0,0]
	v_pk_fma_f32 v[254:255], v[252:253], v[250:251], v[254:255]
	v_div_fixup_f32 v248, v254, v248, 1.0
	v_div_fixup_f32 v249, v255, v249, 1.0
	v_lshlrev_b32_e32 v82, 16, v74
	v_and_b32_e32 v83, 0xffff0000, v74
	v_lshlrev_b32_e32 v84, 16, v76
	v_and_b32_e32 v85, 0xffff0000, v76
	v_lshlrev_b32_e32 v76, 16, v77
	v_and_b32_e32 v77, 0xffff0000, v77
	v_lshlrev_b32_e32 v74, 16, v75
	v_and_b32_e32 v75, 0xffff0000, v75
	v_pk_fma_f32 v[60:61], v[60:61], v[242:243], v[82:83]
	v_pk_fma_f32 v[70:71], v[58:59], v[248:249], v[76:77]
	v_pk_fma_f32 v[58:59], v[56:57], v[244:245], v[84:85]
	v_add_lshl_u32 v72, v146, v66, 1
	v_pk_fma_f32 v[62:63], v[62:63], v[246:247], v[74:75]
	v_cvt_pk_bf16_f32 v56, v60, v61
	s_nop 0
	v_cvt_pk_bf16_f32 v57, v62, v63
	v_cvt_pk_bf16_f32 v58, v58, v59
	v_cvt_pk_bf16_f32 v59, v70, v71
	buffer_store_dwordx4 v[56:59], v72, s[20:23], 0 offen sc1
	s_nop 0
	s_waitcnt vmcnt(7)
; __device__ __forceinline__ float sigmoidf_(float x) { return 1.0f / (1.0f + __expf(-x)); }
; __device__ __forceinline__ u32x4 pack8(const f32x4 v0, const f32x4 v1) { u32x4 w; w.x = pk2(v0[0], v0[1]); w.y = pk2(v0[2], v0[3]); w.z = pk2(v1[0], v1[1]); w.w = pk2(v1[2], v1[3]); return w; }
; __device__ __forceinline__ void unpack8(const u32x4 w, f32x4& v0, f32x4& v1) { v0 = (f32x4){bflo(w.x), bfhi(w.x), bflo(w.y), bfhi(w.y)}; v1 = (f32x4){bflo(w.z), bfhi(w.z), bflo(w.w), bfhi(w.w)}; }
;     __device__ __forceinline__ void operator()(const f32x4 (&acc)[2][2][4][2], const Unit& u, int wr, int wc, int fr, int fq) const {
;     ...
;                 const int row = row0 + ai * 128 + m * 16;
;                 const bf16_t* rowp = z + (size_t)row * DIN + col0;
; #pragma unroll
;                 for (int bj = 0; bj < 2; ++bj) {
;                     const u32x4 gw = *(const u32x4*)(rowp + O_GA + bj * 128);
;                     f32x4 g0, g1; unpack8(gw, g0, g1);
;                     f32x4 v0, v1;
; #pragma unroll
;                     for (int j = 0; j < 4; ++j) { v0[j] = sigmoidf_(g0[j]) * acc[ai][bj][m][0][j]; v1[j] = sigmoidf_(g1[j]) * acc[ai][bj][m][1][j]; }
;                     const u32x4 mw = *(const u32x4*)(rowp + bj * 128); f32x4 m0, m1; unpack8(mw, m0, m1); v0 += m0; v1 += m1;
;                     __builtin_amdgcn_raw_buffer_store_b128(pack8(v0, v1), rsrc, (unsigned)(((size_t)row * DIN + col0 + bj * 128) * 2), 0, 16  ); }
	v_mov_b32_e32 v56, v204
	v_mov_b32_e32 v57, v205
	v_mov_b32_e32 v58, v206
	v_mov_b32_e32 v59, v207
	v_mov_b32_e32 v60, v208
	v_mov_b32_e32 v61, v209
	v_mov_b32_e32 v62, v210
	v_mov_b32_e32 v63, v211
	v_add_u32_e32 v202, 0x155200, v201
	global_load_dwordx4 v[204:207], v202, s[36:37]
	v_add_u32_e32 v202, 0x154000, v201
	global_load_dwordx4 v[208:211], v202, s[36:37]
	s_mov_b32 s100, 0xbfb8aa3b
	v_lshlrev_b32_e32 v242, 16, v58
	v_and_b32_e32 v243, 0xffff0000, v58
	v_lshlrev_b32_e32 v244, 16, v56
	v_and_b32_e32 v245, 0xffff0000, v56
	v_lshlrev_b32_e32 v246, 16, v57
	v_and_b32_e32 v247, 0xffff0000, v57
	v_lshlrev_b32_e32 v248, 16, v59
	v_and_b32_e32 v249, 0xffff0000, v59
	v_pk_mul_f32 v[242:243], v[242:243], s[100:101] op_sel_hi:[1,0]
	v_pk_mul_f32 v[244:245], v[244:245], s[100:101] op_sel_hi:[1,0]
	v_pk_mul_f32 v[246:247], v[246:247], s[100:101] op_sel_hi:[1,0]
	v_pk_mul_f32 v[248:249], v[248:249], s[100:101] op_sel_hi:[1,0]
	v_exp_f32_e32 v242, v242
	v_exp_f32_e32 v243, v243
	v_exp_f32_e32 v244, v244
	v_exp_f32_e32 v245, v245
	v_exp_f32_e32 v246, v246
	v_exp_f32_e32 v247, v247
	v_exp_f32_e32 v248, v248
	v_exp_f32_e32 v249, v249
	s_nop 0
	v_pk_add_f32 v[242:243], v[242:243], 1.0 op_sel_hi:[1,0]
	v_pk_add_f32 v[244:245], v[244:245], 1.0 op_sel_hi:[1,0]
	v_pk_add_f32 v[246:247], v[246:247], 1.0 op_sel_hi:[1,0]
	v_pk_add_f32 v[248:249], v[248:249], 1.0 op_sel_hi:[1,0]
	v_rcp_f32_e32 v250, v242
	v_rcp_f32_e32 v251, v243
	s_nop 0
	v_pk_fma_f32 v[252:253], v[242:243], v[250:251], 1.0 op_sel_hi:[1,1,0] neg_lo:[1,0,0] neg_hi:[1,0,0]
	v_pk_fma_f32 v[250:251], v[252:253], v[250:251], v[250:251]
	v_pk_fma_f32 v[252:253], v[242:243], v[250:251], 1.0 op_sel_hi:[1,1,0] neg_lo:[1,0,0] neg_hi:[1,0,0]
	v_pk_fma_f32 v[254:255], v[252:253], v[250:251], v[250:251]
	v_pk_fma_f32 v[252:253], v[242:243], v[254:255], 1.0 op_sel_hi:[1,1,0] neg_lo:[1,0,0] neg_hi:[1,0,0]
	v_pk_fma_f32 v[254:255], v[252:253], v[250:251], v[254:255]
	v_div_fixup_f32 v242, v254, v242, 1.0
	v_div_fixup_f32 v243, v255, v243, 1.0
	v_rcp_f32_e32 v250, v244
	v_rcp_f32_e32 v251, v245
	s_nop 0
	v_pk_fma_f32 v[252:253], v[244:245], v[250:251], 1.0 op_sel_hi:[1,1,0] neg_lo:[1,0,0] neg_hi:[1,0,0]
	v_pk_fma_f32 v[250:251], v[252:253], v[250:251], v[250:251]
	v_pk_fma_f32 v[252:253], v[244:245], v[250:251], 1.0 op_sel_hi:[1,1,0] neg_lo:[1,0,0] neg_hi:[1,0,0]
	v_pk_fma_f32 v[254:255], v[252:253], v[250:251], v[250:251]
	v_pk_fma_f32 v[252:253], v[244:245], v[254:255], 1.0 op_sel_hi:[1,1,0] neg_lo:[1,0,0] neg_hi:[1,0,0]
	v_pk_fma_f32 v[254:255], v[252:253], v[250:251], v[254:255]
	v_div_fixup_f32 v244, v254, v244, 1.0
	v_div_fixup_f32 v245, v255, v245, 1.0
	v_rcp_f32_e32 v250, v246
	v_rcp_f32_e32 v251, v247
	s_nop 0
	v_pk_fma_f32 v[252:253], v[246:247], v[250:251], 1.0 op_sel_hi:[1,1,0] neg_lo:[1,0,0] neg_hi:[1,0,0]
	v_pk_fma_f32 v[250:251], v[252:253], v[250:251], v[250:251]
	v_pk_fma_f32 v[252:253], v[246:247], v[250:251], 1.0 op_sel_hi:[1,1,0] neg_lo:[1,0,0] neg_hi:[1,0,0]
	v_pk_fma_f32 v[254:255], v[252:253], v[250:251], v[250:251]
	v_pk_fma_f32 v[252:253], v[246:247], v[254:255], 1.0 op_sel_hi:[1,1,0] neg_lo:[1,0,0] neg_hi:[1,0,0]
	v_pk_fma_f32 v[254:255], v[252:253], v[250:251], v[254:255]
	v_div_fixup_f32 v246, v254, v246, 1.0
	v_div_fixup_f32 v247, v255, v247, 1.0
	v_rcp_f32_e32 v250, v248
	v_rcp_f32_e32 v251, v249
	s_nop 0
	v_pk_fma_f32 v[252:253], v[248:249], v[250:251], 1.0 op_sel_hi:[1,1,0] neg_lo:[1,0,0] neg_hi:[1,0,0]
	v_pk_fma_f32 v[250:251], v[252:253], v[250:251], v[250:251]
	v_pk_fma_f32 v[252:253], v[248:249], v[250:251], 1.0 op_sel_hi:[1,1,0] neg_lo:[1,0,0] neg_hi:[1,0,0]
	v_pk_fma_f32 v[254:255], v[252:253], v[250:251], v[250:251]
	v_pk_fma_f32 v[252:253], v[248:249], v[254:255], 1.0 op_sel_hi:[1,1,0] neg_lo:[1,0,0] neg_hi:[1,0,0]
	v_pk_fma_f32 v[254:255], v[252:253], v[250:251], v[254:255]
	v_div_fixup_f32 v248, v254, v248, 1.0
	v_div_fixup_f32 v249, v255, v249, 1.0
	v_lshlrev_b32_e32 v68, 16, v60
	v_and_b32_e32 v69, 0xffff0000, v60
	v_lshlrev_b32_e32 v70, 16, v62
	v_and_b32_e32 v71, 0xffff0000, v62
	v_lshlrev_b32_e32 v62, 16, v63
	v_and_b32_e32 v63, 0xffff0000, v63
	v_lshlrev_b32_e32 v60, 16, v61
	v_and_b32_e32 v61, 0xffff0000, v61
	v_pk_fma_f32 v[52:53], v[52:53], v[244:245], v[68:69]
	v_pk_fma_f32 v[56:57], v[50:51], v[248:249], v[62:63]
	v_pk_fma_f32 v[50:51], v[48:49], v[242:243], v[70:71]
	v_cvt_pk_bf16_f32 v48, v52, v53
	v_pk_fma_f32 v[54:55], v[54:55], v[246:247], v[60:61]
	s_nop 0
	v_cvt_pk_bf16_f32 v49, v54, v55
	v_cvt_pk_bf16_f32 v50, v50, v51
	v_cvt_pk_bf16_f32 v51, v56, v57
	buffer_store_dwordx4 v[48:51], v72, s[20:23], 0 offen offset:256 sc1
	s_nop 1
	v_add_u32_e32 v48, 0x90, v162
	v_mad_i64_i32 v[50:51], s[6:7], v48, s73, 0
	v_lshl_add_u64 v[48:49], v[50:51], 1, s[36:37]
	v_lshl_add_u64 v[48:49], v[48:49], 0, v[148:149]
	v_add_co_u32_e32 v52, vcc, s74, v48
	s_nop 1
	v_addc_co_u32_e32 v53, vcc, 0, v49, vcc
	s_waitcnt vmcnt(7)
; __device__ __forceinline__ float sigmoidf_(float x) { return 1.0f / (1.0f + __expf(-x)); }
; __device__ __forceinline__ u32x4 pack8(const f32x4 v0, const f32x4 v1) { u32x4 w; w.x = pk2(v0[0], v0[1]); w.y = pk2(v0[2], v0[3]); w.z = pk2(v1[0], v1[1]); w.w = pk2(v1[2], v1[3]); return w; }
; __device__ __forceinline__ void unpack8(const u32x4 w, f32x4& v0, f32x4& v1) { v0 = (f32x4){bflo(w.x), bfhi(w.x), bflo(w.y), bfhi(w.y)}; v1 = (f32x4){bflo(w.z), bfhi(w.z), bflo(w.w), bfhi(w.w)}; }
;     __device__ __forceinline__ void operator()(const f32x4 (&acc)[2][2][4][2], const Unit& u, int wr, int wc, int fr, int fq) const {
;     ...
;                 const int row = row0 + ai * 128 + m * 16;
;                 const bf16_t* rowp = z + (size_t)row * DIN + col0;
; #pragma unroll
;                 for (int bj = 0; bj < 2; ++bj) {
;                     const u32x4 gw = *(const u32x4*)(rowp + O_GA + bj * 128);
;                     f32x4 g0, g1; unpack8(gw, g0, g1);
;                     f32x4 v0, v1;
; #pragma unroll
;                     for (int j = 0; j < 4; ++j) { v0[j] = sigmoidf_(g0[j]) * acc[ai][bj][m][0][j]; v1[j] = sigmoidf_(g1[j]) * acc[ai][bj][m][1][j]; }
;                     const u32x4 mw = *(const u32x4*)(rowp + bj * 128); f32x4 m0, m1; unpack8(mw, m0, m1); v0 += m0; v1 += m1;
;                     __builtin_amdgcn_raw_buffer_store_b128(pack8(v0, v1), rsrc, (unsigned)(((size_t)row * DIN + col0 + bj * 128) * 2), 0, 16  ); }
	v_mov_b32_e32 v54, v212
	v_mov_b32_e32 v55, v213
	v_mov_b32_e32 v56, v214
	v_mov_b32_e32 v57, v215
	v_mov_b32_e32 v58, v216
	v_mov_b32_e32 v59, v217
	v_mov_b32_e32 v60, v218
	v_mov_b32_e32 v61, v219
	v_add_u32_e32 v202, 0x155300, v201
	global_load_dwordx4 v[212:215], v202, s[36:37]
	v_add_u32_e32 v202, 0x154100, v201
	global_load_dwordx4 v[216:219], v202, s[36:37]
	s_mov_b32 s100, 0xbfb8aa3b
	v_lshlrev_b32_e32 v242, 16, v54
	v_and_b32_e32 v243, 0xffff0000, v54
	v_lshlrev_b32_e32 v244, 16, v56
	v_and_b32_e32 v245, 0xffff0000, v56
	v_lshlrev_b32_e32 v246, 16, v55
	v_and_b32_e32 v247, 0xffff0000, v55
	v_lshlrev_b32_e32 v248, 16, v57
	v_and_b32_e32 v249, 0xffff0000, v57
	v_pk_mul_f32 v[242:243], v[242:243], s[100:101] op_sel_hi:[1,0]
	v_pk_mul_f32 v[244:245], v[244:245], s[100:101] op_sel_hi:[1,0]
	v_pk_mul_f32 v[246:247], v[246:247], s[100:101] op_sel_hi:[1,0]
	v_pk_mul_f32 v[248:249], v[248:249], s[100:101] op_sel_hi:[1,0]
	v_exp_f32_e32 v242, v242
	v_exp_f32_e32 v243, v243
	v_exp_f32_e32 v244, v244
	v_exp_f32_e32 v245, v245
	v_exp_f32_e32 v246, v246
	v_exp_f32_e32 v247, v247
	v_exp_f32_e32 v248, v248
	v_exp_f32_e32 v249, v249
	s_nop 0
	v_pk_add_f32 v[242:243], v[242:243], 1.0 op_sel_hi:[1,0]
	v_pk_add_f32 v[244:245], v[244:245], 1.0 op_sel_hi:[1,0]
	v_pk_add_f32 v[246:247], v[246:247], 1.0 op_sel_hi:[1,0]
	v_pk_add_f32 v[248:249], v[248:249], 1.0 op_sel_hi:[1,0]
	v_rcp_f32_e32 v250, v242
	v_rcp_f32_e32 v251, v243
	s_nop 0
	v_pk_fma_f32 v[252:253], v[242:243], v[250:251], 1.0 op_sel_hi:[1,1,0] neg_lo:[1,0,0] neg_hi:[1,0,0]
	v_pk_fma_f32 v[250:251], v[252:253], v[250:251], v[250:251]
	v_pk_fma_f32 v[252:253], v[242:243], v[250:251], 1.0 op_sel_hi:[1,1,0] neg_lo:[1,0,0] neg_hi:[1,0,0]
	v_pk_fma_f32 v[254:255], v[252:253], v[250:251], v[250:251]
	v_pk_fma_f32 v[252:253], v[242:243], v[254:255], 1.0 op_sel_hi:[1,1,0] neg_lo:[1,0,0] neg_hi:[1,0,0]
	v_pk_fma_f32 v[254:255], v[252:253], v[250:251], v[254:255]
	v_div_fixup_f32 v242, v254, v242, 1.0
	v_div_fixup_f32 v243, v255, v243, 1.0
	v_rcp_f32_e32 v250, v244
	v_rcp_f32_e32 v251, v245
	s_nop 0
	v_pk_fma_f32 v[252:253], v[244:245], v[250:251], 1.0 op_sel_hi:[1,1,0] neg_lo:[1,0,0] neg_hi:[1,0,0]
	v_pk_fma_f32 v[250:251], v[252:253], v[250:251], v[250:251]
	v_pk_fma_f32 v[252:253], v[244:245], v[250:251], 1.0 op_sel_hi:[1,1,0] neg_lo:[1,0,0] neg_hi:[1,0,0]
	v_pk_fma_f32 v[254:255], v[252:253], v[250:251], v[250:251]
	v_pk_fma_f32 v[252:253], v[244:245], v[254:255], 1.0 op_sel_hi:[1,1,0] neg_lo:[1,0,0] neg_hi:[1,0,0]
	v_pk_fma_f32 v[254:255], v[252:253], v[250:251], v[254:255]
	v_div_fixup_f32 v244, v254, v244, 1.0
	v_div_fixup_f32 v245, v255, v245, 1.0
	v_rcp_f32_e32 v250, v246
	v_rcp_f32_e32 v251, v247
	s_nop 0
	v_pk_fma_f32 v[252:253], v[246:247], v[250:251], 1.0 op_sel_hi:[1,1,0] neg_lo:[1,0,0] neg_hi:[1,0,0]
	v_pk_fma_f32 v[250:251], v[252:253], v[250:251], v[250:251]
	v_pk_fma_f32 v[252:253], v[246:247], v[250:251], 1.0 op_sel_hi:[1,1,0] neg_lo:[1,0,0] neg_hi:[1,0,0]
	v_pk_fma_f32 v[254:255], v[252:253], v[250:251], v[250:251]
	v_pk_fma_f32 v[252:253], v[246:247], v[254:255], 1.0 op_sel_hi:[1,1,0] neg_lo:[1,0,0] neg_hi:[1,0,0]
	v_pk_fma_f32 v[254:255], v[252:253], v[250:251], v[254:255]
	v_div_fixup_f32 v246, v254, v246, 1.0
	v_div_fixup_f32 v247, v255, v247, 1.0
	v_rcp_f32_e32 v250, v248
	v_rcp_f32_e32 v251, v249
	s_nop 0
	v_pk_fma_f32 v[252:253], v[248:249], v[250:251], 1.0 op_sel_hi:[1,1,0] neg_lo:[1,0,0] neg_hi:[1,0,0]
	v_pk_fma_f32 v[250:251], v[252:253], v[250:251], v[250:251]
	v_pk_fma_f32 v[252:253], v[248:249], v[250:251], 1.0 op_sel_hi:[1,1,0] neg_lo:[1,0,0] neg_hi:[1,0,0]
	v_pk_fma_f32 v[254:255], v[252:253], v[250:251], v[250:251]
	v_pk_fma_f32 v[252:253], v[248:249], v[254:255], 1.0 op_sel_hi:[1,1,0] neg_lo:[1,0,0] neg_hi:[1,0,0]
	v_pk_fma_f32 v[254:255], v[252:253], v[250:251], v[254:255]
	v_div_fixup_f32 v248, v254, v248, 1.0
	v_div_fixup_f32 v249, v255, v249, 1.0
	v_lshlrev_b32_e32 v66, 16, v58
	v_and_b32_e32 v67, 0xffff0000, v58
	v_lshlrev_b32_e32 v68, 16, v60
	v_and_b32_e32 v69, 0xffff0000, v60
	v_lshlrev_b32_e32 v60, 16, v61
	v_and_b32_e32 v61, 0xffff0000, v61
	v_lshlrev_b32_e32 v58, 16, v59
	v_and_b32_e32 v59, 0xffff0000, v59
	v_pk_fma_f32 v[44:45], v[44:45], v[242:243], v[66:67]
	v_pk_fma_f32 v[54:55], v[42:43], v[248:249], v[60:61]
	v_pk_fma_f32 v[42:43], v[40:41], v[244:245], v[68:69]
	v_add_lshl_u32 v56, v146, v50, 1
	v_pk_fma_f32 v[46:47], v[46:47], v[246:247], v[58:59]
	v_cvt_pk_bf16_f32 v40, v44, v45
	s_nop 0
	v_cvt_pk_bf16_f32 v41, v46, v47
	v_cvt_pk_bf16_f32 v42, v42, v43
	v_cvt_pk_bf16_f32 v43, v54, v55
	buffer_store_dwordx4 v[40:43], v56, s[20:23], 0 offen sc1
	s_nop 0
	s_waitcnt vmcnt(7)
; __device__ __forceinline__ float sigmoidf_(float x) { return 1.0f / (1.0f + __expf(-x)); }
; __device__ __forceinline__ u32x4 pack8(const f32x4 v0, const f32x4 v1) { u32x4 w; w.x = pk2(v0[0], v0[1]); w.y = pk2(v0[2], v0[3]); w.z = pk2(v1[0], v1[1]); w.w = pk2(v1[2], v1[3]); return w; }
; __device__ __forceinline__ void unpack8(const u32x4 w, f32x4& v0, f32x4& v1) { v0 = (f32x4){bflo(w.x), bfhi(w.x), bflo(w.y), bfhi(w.y)}; v1 = (f32x4){bflo(w.z), bfhi(w.z), bflo(w.w), bfhi(w.w)}; }
;     __device__ __forceinline__ void operator()(const f32x4 (&acc)[2][2][4][2], const Unit& u, int wr, int wc, int fr, int fq) const {
;     ...
;                 const int row = row0 + ai * 128 + m * 16;
;                 const bf16_t* rowp = z + (size_t)row * DIN + col0;
; #pragma unroll
;                 for (int bj = 0; bj < 2; ++bj) {
;                     const u32x4 gw = *(const u32x4*)(rowp + O_GA + bj * 128);
;                     f32x4 g0, g1; unpack8(gw, g0, g1);
;                     f32x4 v0, v1;
; #pragma unroll
;                     for (int j = 0; j < 4; ++j) { v0[j] = sigmoidf_(g0[j]) * acc[ai][bj][m][0][j]; v1[j] = sigmoidf_(g1[j]) * acc[ai][bj][m][1][j]; }
;                     const u32x4 mw = *(const u32x4*)(rowp + bj * 128); f32x4 m0, m1; unpack8(mw, m0, m1); v0 += m0; v1 += m1;
;                     __builtin_amdgcn_raw_buffer_store_b128(pack8(v0, v1), rsrc, (unsigned)(((size_t)row * DIN + col0 + bj * 128) * 2), 0, 16  ); }
	v_mov_b32_e32 v40, v232
	v_mov_b32_e32 v41, v233
	v_mov_b32_e32 v42, v234
	v_mov_b32_e32 v43, v235
	v_mov_b32_e32 v44, v236
	v_mov_b32_e32 v45, v237
	v_mov_b32_e32 v46, v238
	v_mov_b32_e32 v47, v239
	v_add_u32_e32 v202, 0x177200, v201
	global_load_dwordx4 v[232:235], v202, s[36:37]
	v_add_u32_e32 v202, 0x176000, v201
	global_load_dwordx4 v[236:239], v202, s[36:37]
	s_mov_b32 s100, 0xbfb8aa3b
	v_lshlrev_b32_e32 v242, 16, v42
	v_and_b32_e32 v243, 0xffff0000, v42
	v_lshlrev_b32_e32 v244, 16, v40
	v_and_b32_e32 v245, 0xffff0000, v40
	v_lshlrev_b32_e32 v246, 16, v41
	v_and_b32_e32 v247, 0xffff0000, v41
	v_lshlrev_b32_e32 v248, 16, v43
	v_and_b32_e32 v249, 0xffff0000, v43
	v_pk_mul_f32 v[242:243], v[242:243], s[100:101] op_sel_hi:[1,0]
	v_pk_mul_f32 v[244:245], v[244:245], s[100:101] op_sel_hi:[1,0]
	v_pk_mul_f32 v[246:247], v[246:247], s[100:101] op_sel_hi:[1,0]
	v_pk_mul_f32 v[248:249], v[248:249], s[100:101] op_sel_hi:[1,0]
	v_exp_f32_e32 v242, v242
	v_exp_f32_e32 v243, v243
	v_exp_f32_e32 v244, v244
	v_exp_f32_e32 v245, v245
	v_exp_f32_e32 v246, v246
	v_exp_f32_e32 v247, v247
	v_exp_f32_e32 v248, v248
	v_exp_f32_e32 v249, v249
	s_nop 0
	v_pk_add_f32 v[242:243], v[242:243], 1.0 op_sel_hi:[1,0]
	v_pk_add_f32 v[244:245], v[244:245], 1.0 op_sel_hi:[1,0]
	v_pk_add_f32 v[246:247], v[246:247], 1.0 op_sel_hi:[1,0]
	v_pk_add_f32 v[248:249], v[248:249], 1.0 op_sel_hi:[1,0]
	v_rcp_f32_e32 v250, v242
	v_rcp_f32_e32 v251, v243
	s_nop 0
	v_pk_fma_f32 v[252:253], v[242:243], v[250:251], 1.0 op_sel_hi:[1,1,0] neg_lo:[1,0,0] neg_hi:[1,0,0]
	v_pk_fma_f32 v[250:251], v[252:253], v[250:251], v[250:251]
	v_pk_fma_f32 v[252:253], v[242:243], v[250:251], 1.0 op_sel_hi:[1,1,0] neg_lo:[1,0,0] neg_hi:[1,0,0]
	v_pk_fma_f32 v[254:255], v[252:253], v[250:251], v[250:251]
	v_pk_fma_f32 v[252:253], v[242:243], v[254:255], 1.0 op_sel_hi:[1,1,0] neg_lo:[1,0,0] neg_hi:[1,0,0]
	v_pk_fma_f32 v[254:255], v[252:253], v[250:251], v[254:255]
	v_div_fixup_f32 v242, v254, v242, 1.0
	v_div_fixup_f32 v243, v255, v243, 1.0
	v_rcp_f32_e32 v250, v244
	v_rcp_f32_e32 v251, v245
	s_nop 0
	v_pk_fma_f32 v[252:253], v[244:245], v[250:251], 1.0 op_sel_hi:[1,1,0] neg_lo:[1,0,0] neg_hi:[1,0,0]
	v_pk_fma_f32 v[250:251], v[252:253], v[250:251], v[250:251]
	v_pk_fma_f32 v[252:253], v[244:245], v[250:251], 1.0 op_sel_hi:[1,1,0] neg_lo:[1,0,0] neg_hi:[1,0,0]
	v_pk_fma_f32 v[254:255], v[252:253], v[250:251], v[250:251]
	v_pk_fma_f32 v[252:253], v[244:245], v[254:255], 1.0 op_sel_hi:[1,1,0] neg_lo:[1,0,0] neg_hi:[1,0,0]
	v_pk_fma_f32 v[254:255], v[252:253], v[250:251], v[254:255]
	v_div_fixup_f32 v244, v254, v244, 1.0
	v_div_fixup_f32 v245, v255, v245, 1.0
	v_rcp_f32_e32 v250, v246
	v_rcp_f32_e32 v251, v247
	s_nop 0
	v_pk_fma_f32 v[252:253], v[246:247], v[250:251], 1.0 op_sel_hi:[1,1,0] neg_lo:[1,0,0] neg_hi:[1,0,0]
	v_pk_fma_f32 v[250:251], v[252:253], v[250:251], v[250:251]
	v_pk_fma_f32 v[252:253], v[246:247], v[250:251], 1.0 op_sel_hi:[1,1,0] neg_lo:[1,0,0] neg_hi:[1,0,0]
	v_pk_fma_f32 v[254:255], v[252:253], v[250:251], v[250:251]
	v_pk_fma_f32 v[252:253], v[246:247], v[254:255], 1.0 op_sel_hi:[1,1,0] neg_lo:[1,0,0] neg_hi:[1,0,0]
	v_pk_fma_f32 v[254:255], v[252:253], v[250:251], v[254:255]
	v_div_fixup_f32 v246, v254, v246, 1.0
	v_div_fixup_f32 v247, v255, v247, 1.0
	v_rcp_f32_e32 v250, v248
	v_rcp_f32_e32 v251, v249
	s_nop 0
	v_pk_fma_f32 v[252:253], v[248:249], v[250:251], 1.0 op_sel_hi:[1,1,0] neg_lo:[1,0,0] neg_hi:[1,0,0]
	v_pk_fma_f32 v[250:251], v[252:253], v[250:251], v[250:251]
	v_pk_fma_f32 v[252:253], v[248:249], v[250:251], 1.0 op_sel_hi:[1,1,0] neg_lo:[1,0,0] neg_hi:[1,0,0]
	v_pk_fma_f32 v[254:255], v[252:253], v[250:251], v[250:251]
	v_pk_fma_f32 v[252:253], v[248:249], v[254:255], 1.0 op_sel_hi:[1,1,0] neg_lo:[1,0,0] neg_hi:[1,0,0]
	v_pk_fma_f32 v[254:255], v[252:253], v[250:251], v[254:255]
	v_div_fixup_f32 v248, v254, v248, 1.0
	v_div_fixup_f32 v249, v255, v249, 1.0
	v_lshlrev_b32_e32 v52, 16, v44
	v_and_b32_e32 v53, 0xffff0000, v44
	v_lshlrev_b32_e32 v54, 16, v46
	v_and_b32_e32 v55, 0xffff0000, v46
	v_lshlrev_b32_e32 v46, 16, v47
	v_and_b32_e32 v47, 0xffff0000, v47
	v_lshlrev_b32_e32 v44, 16, v45
	v_and_b32_e32 v45, 0xffff0000, v45
	v_pk_fma_f32 v[36:37], v[36:37], v[244:245], v[52:53]
	v_pk_fma_f32 v[40:41], v[34:35], v[248:249], v[46:47]
	v_pk_fma_f32 v[34:35], v[32:33], v[242:243], v[54:55]
	v_cvt_pk_bf16_f32 v32, v36, v37
	v_pk_fma_f32 v[38:39], v[38:39], v[246:247], v[44:45]
	s_nop 0
	v_cvt_pk_bf16_f32 v33, v38, v39
	v_cvt_pk_bf16_f32 v34, v34, v35
	v_cvt_pk_bf16_f32 v35, v40, v41
	buffer_store_dwordx4 v[32:35], v56, s[20:23], 0 offen offset:256 sc1
	s_nop 1
	v_add_u32_e32 v32, 0xa0, v162
	v_mad_i64_i32 v[34:35], s[6:7], v32, s73, 0
	v_lshl_add_u64 v[32:33], v[34:35], 1, s[36:37]
	v_lshl_add_u64 v[32:33], v[32:33], 0, v[148:149]
	v_add_co_u32_e32 v36, vcc, s74, v32
	s_nop 1
	v_addc_co_u32_e32 v37, vcc, 0, v33, vcc
	s_waitcnt vmcnt(7)
; __device__ __forceinline__ float sigmoidf_(float x) { return 1.0f / (1.0f + __expf(-x)); }
; __device__ __forceinline__ u32x4 pack8(const f32x4 v0, const f32x4 v1) { u32x4 w; w.x = pk2(v0[0], v0[1]); w.y = pk2(v0[2], v0[3]); w.z = pk2(v1[0], v1[1]); w.w = pk2(v1[2], v1[3]); return w; }
; __device__ __forceinline__ void unpack8(const u32x4 w, f32x4& v0, f32x4& v1) { v0 = (f32x4){bflo(w.x), bfhi(w.x), bflo(w.y), bfhi(w.y)}; v1 = (f32x4){bflo(w.z), bfhi(w.z), bflo(w.w), bfhi(w.w)}; }
;     __device__ __forceinline__ void operator()(const f32x4 (&acc)[2][2][4][2], const Unit& u, int wr, int wc, int fr, int fq) const {
;     ...
;                 const int row = row0 + ai * 128 + m * 16;
;                 const bf16_t* rowp = z + (size_t)row * DIN + col0;
; #pragma unroll
;                 for (int bj = 0; bj < 2; ++bj) {
;                     const u32x4 gw = *(const u32x4*)(rowp + O_GA + bj * 128);
;                     f32x4 g0, g1; unpack8(gw, g0, g1);
;                     f32x4 v0, v1;
; #pragma unroll
;                     for (int j = 0; j < 4; ++j) { v0[j] = sigmoidf_(g0[j]) * acc[ai][bj][m][0][j]; v1[j] = sigmoidf_(g1[j]) * acc[ai][bj][m][1][j]; }
;                     const u32x4 mw = *(const u32x4*)(rowp + bj * 128); f32x4 m0, m1; unpack8(mw, m0, m1); v0 += m0; v1 += m1;
;                     __builtin_amdgcn_raw_buffer_store_b128(pack8(v0, v1), rsrc, (unsigned)(((size_t)row * DIN + col0 + bj * 128) * 2), 0, 16  ); }
	v_mov_b32_e32 v38, v204
	v_mov_b32_e32 v39, v205
	v_mov_b32_e32 v40, v206
	v_mov_b32_e32 v41, v207
	v_mov_b32_e32 v42, v208
	v_mov_b32_e32 v43, v209
	v_mov_b32_e32 v44, v210
	v_mov_b32_e32 v45, v211
	v_add_u32_e32 v202, 0x177300, v201
	global_load_dwordx4 v[204:207], v202, s[36:37]
	v_add_u32_e32 v202, 0x176100, v201
	global_load_dwordx4 v[208:211], v202, s[36:37]
	s_mov_b32 s100, 0xbfb8aa3b
	v_lshlrev_b32_e32 v242, 16, v38
	v_and_b32_e32 v243, 0xffff0000, v38
	v_lshlrev_b32_e32 v244, 16, v40
	v_and_b32_e32 v245, 0xffff0000, v40
	v_lshlrev_b32_e32 v246, 16, v39
	v_and_b32_e32 v247, 0xffff0000, v39
	v_lshlrev_b32_e32 v248, 16, v41
	v_and_b32_e32 v249, 0xffff0000, v41
	v_pk_mul_f32 v[242:243], v[242:243], s[100:101] op_sel_hi:[1,0]
	v_pk_mul_f32 v[244:245], v[244:245], s[100:101] op_sel_hi:[1,0]
	v_pk_mul_f32 v[246:247], v[246:247], s[100:101] op_sel_hi:[1,0]
	v_pk_mul_f32 v[248:249], v[248:249], s[100:101] op_sel_hi:[1,0]
	v_exp_f32_e32 v242, v242
	v_exp_f32_e32 v243, v243
	v_exp_f32_e32 v244, v244
	v_exp_f32_e32 v245, v245
	v_exp_f32_e32 v246, v246
	v_exp_f32_e32 v247, v247
	v_exp_f32_e32 v248, v248
	v_exp_f32_e32 v249, v249
	s_nop 0
	v_pk_add_f32 v[242:243], v[242:243], 1.0 op_sel_hi:[1,0]
	v_pk_add_f32 v[244:245], v[244:245], 1.0 op_sel_hi:[1,0]
	v_pk_add_f32 v[246:247], v[246:247], 1.0 op_sel_hi:[1,0]
	v_pk_add_f32 v[248:249], v[248:249], 1.0 op_sel_hi:[1,0]
	v_rcp_f32_e32 v250, v242
	v_rcp_f32_e32 v251, v243
	s_nop 0
	v_pk_fma_f32 v[252:253], v[242:243], v[250:251], 1.0 op_sel_hi:[1,1,0] neg_lo:[1,0,0] neg_hi:[1,0,0]
	v_pk_fma_f32 v[250:251], v[252:253], v[250:251], v[250:251]
	v_pk_fma_f32 v[252:253], v[242:243], v[250:251], 1.0 op_sel_hi:[1,1,0] neg_lo:[1,0,0] neg_hi:[1,0,0]
	v_pk_fma_f32 v[254:255], v[252:253], v[250:251], v[250:251]
	v_pk_fma_f32 v[252:253], v[242:243], v[254:255], 1.0 op_sel_hi:[1,1,0] neg_lo:[1,0,0] neg_hi:[1,0,0]
	v_pk_fma_f32 v[254:255], v[252:253], v[250:251], v[254:255]
	v_div_fixup_f32 v242, v254, v242, 1.0
	v_div_fixup_f32 v243, v255, v243, 1.0
	v_rcp_f32_e32 v250, v244
	v_rcp_f32_e32 v251, v245
	s_nop 0
	v_pk_fma_f32 v[252:253], v[244:245], v[250:251], 1.0 op_sel_hi:[1,1,0] neg_lo:[1,0,0] neg_hi:[1,0,0]
	v_pk_fma_f32 v[250:251], v[252:253], v[250:251], v[250:251]
	v_pk_fma_f32 v[252:253], v[244:245], v[250:251], 1.0 op_sel_hi:[1,1,0] neg_lo:[1,0,0] neg_hi:[1,0,0]
	v_pk_fma_f32 v[254:255], v[252:253], v[250:251], v[250:251]
	v_pk_fma_f32 v[252:253], v[244:245], v[254:255], 1.0 op_sel_hi:[1,1,0] neg_lo:[1,0,0] neg_hi:[1,0,0]
	v_pk_fma_f32 v[254:255], v[252:253], v[250:251], v[254:255]
	v_div_fixup_f32 v244, v254, v244, 1.0
	v_div_fixup_f32 v245, v255, v245, 1.0
	v_rcp_f32_e32 v250, v246
	v_rcp_f32_e32 v251, v247
	s_nop 0
	v_pk_fma_f32 v[252:253], v[246:247], v[250:251], 1.0 op_sel_hi:[1,1,0] neg_lo:[1,0,0] neg_hi:[1,0,0]
	v_pk_fma_f32 v[250:251], v[252:253], v[250:251], v[250:251]
	v_pk_fma_f32 v[252:253], v[246:247], v[250:251], 1.0 op_sel_hi:[1,1,0] neg_lo:[1,0,0] neg_hi:[1,0,0]
	v_pk_fma_f32 v[254:255], v[252:253], v[250:251], v[250:251]
	v_pk_fma_f32 v[252:253], v[246:247], v[254:255], 1.0 op_sel_hi:[1,1,0] neg_lo:[1,0,0] neg_hi:[1,0,0]
	v_pk_fma_f32 v[254:255], v[252:253], v[250:251], v[254:255]
	v_div_fixup_f32 v246, v254, v246, 1.0
	v_div_fixup_f32 v247, v255, v247, 1.0
	v_rcp_f32_e32 v250, v248
	v_rcp_f32_e32 v251, v249
	s_nop 0
	v_pk_fma_f32 v[252:253], v[248:249], v[250:251], 1.0 op_sel_hi:[1,1,0] neg_lo:[1,0,0] neg_hi:[1,0,0]
	v_pk_fma_f32 v[250:251], v[252:253], v[250:251], v[250:251]
	v_pk_fma_f32 v[252:253], v[248:249], v[250:251], 1.0 op_sel_hi:[1,1,0] neg_lo:[1,0,0] neg_hi:[1,0,0]
	v_pk_fma_f32 v[254:255], v[252:253], v[250:251], v[250:251]
	v_pk_fma_f32 v[252:253], v[248:249], v[254:255], 1.0 op_sel_hi:[1,1,0] neg_lo:[1,0,0] neg_hi:[1,0,0]
	v_pk_fma_f32 v[254:255], v[252:253], v[250:251], v[254:255]
	v_div_fixup_f32 v248, v254, v248, 1.0
	v_div_fixup_f32 v249, v255, v249, 1.0
	v_lshlrev_b32_e32 v50, 16, v42
	v_and_b32_e32 v51, 0xffff0000, v42
	v_lshlrev_b32_e32 v52, 16, v44
	v_and_b32_e32 v53, 0xffff0000, v44
	v_lshlrev_b32_e32 v44, 16, v45
	v_and_b32_e32 v45, 0xffff0000, v45
	v_lshlrev_b32_e32 v42, 16, v43
	v_and_b32_e32 v43, 0xffff0000, v43
	v_pk_fma_f32 v[28:29], v[28:29], v[242:243], v[50:51]
	v_pk_fma_f32 v[38:39], v[26:27], v[248:249], v[44:45]
	v_pk_fma_f32 v[26:27], v[24:25], v[244:245], v[52:53]
	v_add_lshl_u32 v40, v146, v34, 1
	v_pk_fma_f32 v[30:31], v[30:31], v[246:247], v[42:43]
	v_cvt_pk_bf16_f32 v24, v28, v29
	s_nop 0
	v_cvt_pk_bf16_f32 v25, v30, v31
	v_cvt_pk_bf16_f32 v26, v26, v27
	v_cvt_pk_bf16_f32 v27, v38, v39
	buffer_store_dwordx4 v[24:27], v40, s[20:23], 0 offen sc1
	s_nop 0
	s_waitcnt vmcnt(7)
; __device__ __forceinline__ float sigmoidf_(float x) { return 1.0f / (1.0f + __expf(-x)); }
; __device__ __forceinline__ u32x4 pack8(const f32x4 v0, const f32x4 v1) { u32x4 w; w.x = pk2(v0[0], v0[1]); w.y = pk2(v0[2], v0[3]); w.z = pk2(v1[0], v1[1]); w.w = pk2(v1[2], v1[3]); return w; }
; __device__ __forceinline__ void unpack8(const u32x4 w, f32x4& v0, f32x4& v1) { v0 = (f32x4){bflo(w.x), bfhi(w.x), bflo(w.y), bfhi(w.y)}; v1 = (f32x4){bflo(w.z), bfhi(w.z), bflo(w.w), bfhi(w.w)}; }
;     __device__ __forceinline__ void operator()(const f32x4 (&acc)[2][2][4][2], const Unit& u, int wr, int wc, int fr, int fq) const {
;     ...
;                 const int row = row0 + ai * 128 + m * 16;
;                 const bf16_t* rowp = z + (size_t)row * DIN + col0;
; #pragma unroll
;                 for (int bj = 0; bj < 2; ++bj) {
;                     const u32x4 gw = *(const u32x4*)(rowp + O_GA + bj * 128);
;                     f32x4 g0, g1; unpack8(gw, g0, g1);
;                     f32x4 v0, v1;
; #pragma unroll
;                     for (int j = 0; j < 4; ++j) { v0[j] = sigmoidf_(g0[j]) * acc[ai][bj][m][0][j]; v1[j] = sigmoidf_(g1[j]) * acc[ai][bj][m][1][j]; }
;                     const u32x4 mw = *(const u32x4*)(rowp + bj * 128); f32x4 m0, m1; unpack8(mw, m0, m1); v0 += m0; v1 += m1;
;                     __builtin_amdgcn_raw_buffer_store_b128(pack8(v0, v1), rsrc, (unsigned)(((size_t)row * DIN + col0 + bj * 128) * 2), 0, 16  ); }
	v_mov_b32_e32 v24, v212
	v_mov_b32_e32 v25, v213
	v_mov_b32_e32 v26, v214
	v_mov_b32_e32 v27, v215
	v_mov_b32_e32 v28, v216
	v_mov_b32_e32 v29, v217
	v_mov_b32_e32 v30, v218
	v_mov_b32_e32 v31, v219
	s_mov_b32 s100, 0xbfb8aa3b
	v_lshlrev_b32_e32 v242, 16, v26
	v_and_b32_e32 v243, 0xffff0000, v26
	v_lshlrev_b32_e32 v244, 16, v24
	v_and_b32_e32 v245, 0xffff0000, v24
	v_lshlrev_b32_e32 v246, 16, v25
	v_and_b32_e32 v247, 0xffff0000, v25
	v_lshlrev_b32_e32 v248, 16, v27
	v_and_b32_e32 v249, 0xffff0000, v27
	v_pk_mul_f32 v[242:243], v[242:243], s[100:101] op_sel_hi:[1,0]
	v_pk_mul_f32 v[244:245], v[244:245], s[100:101] op_sel_hi:[1,0]
	v_pk_mul_f32 v[246:247], v[246:247], s[100:101] op_sel_hi:[1,0]
	v_pk_mul_f32 v[248:249], v[248:249], s[100:101] op_sel_hi:[1,0]
	v_exp_f32_e32 v242, v242
	v_exp_f32_e32 v243, v243
	v_exp_f32_e32 v244, v244
	v_exp_f32_e32 v245, v245
	v_exp_f32_e32 v246, v246
	v_exp_f32_e32 v247, v247
	v_exp_f32_e32 v248, v248
	v_exp_f32_e32 v249, v249
	s_nop 0
	v_pk_add_f32 v[242:243], v[242:243], 1.0 op_sel_hi:[1,0]
	v_pk_add_f32 v[244:245], v[244:245], 1.0 op_sel_hi:[1,0]
	v_pk_add_f32 v[246:247], v[246:247], 1.0 op_sel_hi:[1,0]
	v_pk_add_f32 v[248:249], v[248:249], 1.0 op_sel_hi:[1,0]
	v_rcp_f32_e32 v250, v242
	v_rcp_f32_e32 v251, v243
	s_nop 0
	v_pk_fma_f32 v[252:253], v[242:243], v[250:251], 1.0 op_sel_hi:[1,1,0] neg_lo:[1,0,0] neg_hi:[1,0,0]
	v_pk_fma_f32 v[250:251], v[252:253], v[250:251], v[250:251]
	v_pk_fma_f32 v[252:253], v[242:243], v[250:251], 1.0 op_sel_hi:[1,1,0] neg_lo:[1,0,0] neg_hi:[1,0,0]
	v_pk_fma_f32 v[254:255], v[252:253], v[250:251], v[250:251]
	v_pk_fma_f32 v[252:253], v[242:243], v[254:255], 1.0 op_sel_hi:[1,1,0] neg_lo:[1,0,0] neg_hi:[1,0,0]
	v_pk_fma_f32 v[254:255], v[252:253], v[250:251], v[254:255]
	v_div_fixup_f32 v242, v254, v242, 1.0
	v_div_fixup_f32 v243, v255, v243, 1.0
	v_rcp_f32_e32 v250, v244
	v_rcp_f32_e32 v251, v245
	s_nop 0
	v_pk_fma_f32 v[252:253], v[244:245], v[250:251], 1.0 op_sel_hi:[1,1,0] neg_lo:[1,0,0] neg_hi:[1,0,0]
	v_pk_fma_f32 v[250:251], v[252:253], v[250:251], v[250:251]
	v_pk_fma_f32 v[252:253], v[244:245], v[250:251], 1.0 op_sel_hi:[1,1,0] neg_lo:[1,0,0] neg_hi:[1,0,0]
	v_pk_fma_f32 v[254:255], v[252:253], v[250:251], v[250:251]
	v_pk_fma_f32 v[252:253], v[244:245], v[254:255], 1.0 op_sel_hi:[1,1,0] neg_lo:[1,0,0] neg_hi:[1,0,0]
	v_pk_fma_f32 v[254:255], v[252:253], v[250:251], v[254:255]
	v_div_fixup_f32 v244, v254, v244, 1.0
	v_div_fixup_f32 v245, v255, v245, 1.0
	v_rcp_f32_e32 v250, v246
	v_rcp_f32_e32 v251, v247
	s_nop 0
	v_pk_fma_f32 v[252:253], v[246:247], v[250:251], 1.0 op_sel_hi:[1,1,0] neg_lo:[1,0,0] neg_hi:[1,0,0]
	v_pk_fma_f32 v[250:251], v[252:253], v[250:251], v[250:251]
	v_pk_fma_f32 v[252:253], v[246:247], v[250:251], 1.0 op_sel_hi:[1,1,0] neg_lo:[1,0,0] neg_hi:[1,0,0]
	v_pk_fma_f32 v[254:255], v[252:253], v[250:251], v[250:251]
	v_pk_fma_f32 v[252:253], v[246:247], v[254:255], 1.0 op_sel_hi:[1,1,0] neg_lo:[1,0,0] neg_hi:[1,0,0]
	v_pk_fma_f32 v[254:255], v[252:253], v[250:251], v[254:255]
	v_div_fixup_f32 v246, v254, v246, 1.0
	v_div_fixup_f32 v247, v255, v247, 1.0
	v_rcp_f32_e32 v250, v248
	v_rcp_f32_e32 v251, v249
	s_nop 0
	v_pk_fma_f32 v[252:253], v[248:249], v[250:251], 1.0 op_sel_hi:[1,1,0] neg_lo:[1,0,0] neg_hi:[1,0,0]
	v_pk_fma_f32 v[250:251], v[252:253], v[250:251], v[250:251]
	v_pk_fma_f32 v[252:253], v[248:249], v[250:251], 1.0 op_sel_hi:[1,1,0] neg_lo:[1,0,0] neg_hi:[1,0,0]
	v_pk_fma_f32 v[254:255], v[252:253], v[250:251], v[250:251]
	v_pk_fma_f32 v[252:253], v[248:249], v[254:255], 1.0 op_sel_hi:[1,1,0] neg_lo:[1,0,0] neg_hi:[1,0,0]
	v_pk_fma_f32 v[254:255], v[252:253], v[250:251], v[254:255]
	v_div_fixup_f32 v248, v254, v248, 1.0
	v_div_fixup_f32 v249, v255, v249, 1.0
	v_lshlrev_b32_e32 v36, 16, v28
	v_and_b32_e32 v37, 0xffff0000, v28
	v_lshlrev_b32_e32 v38, 16, v30
	v_and_b32_e32 v39, 0xffff0000, v30
	v_lshlrev_b32_e32 v30, 16, v31
	v_and_b32_e32 v31, 0xffff0000, v31
	v_lshlrev_b32_e32 v28, 16, v29
	v_and_b32_e32 v29, 0xffff0000, v29
	v_pk_fma_f32 v[20:21], v[20:21], v[244:245], v[36:37]
	v_pk_fma_f32 v[24:25], v[18:19], v[248:249], v[30:31]
	v_pk_fma_f32 v[18:19], v[16:17], v[242:243], v[38:39]
	v_cvt_pk_bf16_f32 v16, v20, v21
	v_pk_fma_f32 v[22:23], v[22:23], v[246:247], v[28:29]
	s_nop 0
	v_cvt_pk_bf16_f32 v17, v22, v23
	v_cvt_pk_bf16_f32 v18, v18, v19
	v_cvt_pk_bf16_f32 v19, v24, v25
	buffer_store_dwordx4 v[16:19], v40, s[20:23], 0 offen offset:256 sc1
	s_nop 1
	v_add_u32_e32 v16, 0xb0, v162
	v_mad_i64_i32 v[18:19], s[6:7], v16, s73, 0
	v_lshl_add_u64 v[16:17], v[18:19], 1, s[36:37]
	v_lshl_add_u64 v[16:17], v[16:17], 0, v[148:149]
	v_add_co_u32_e32 v20, vcc, s74, v16
	s_nop 1
	v_addc_co_u32_e32 v21, vcc, 0, v17, vcc
	s_waitcnt vmcnt(5)
; __device__ __forceinline__ float sigmoidf_(float x) { return 1.0f / (1.0f + __expf(-x)); }
; __device__ __forceinline__ u32x4 pack8(const f32x4 v0, const f32x4 v1) { u32x4 w; w.x = pk2(v0[0], v0[1]); w.y = pk2(v0[2], v0[3]); w.z = pk2(v1[0], v1[1]); w.w = pk2(v1[2], v1[3]); return w; }
; __device__ __forceinline__ void unpack8(const u32x4 w, f32x4& v0, f32x4& v1) { v0 = (f32x4){bflo(w.x), bfhi(w.x), bflo(w.y), bfhi(w.y)}; v1 = (f32x4){bflo(w.z), bfhi(w.z), bflo(w.w), bfhi(w.w)}; }
;     __device__ __forceinline__ void operator()(const f32x4 (&acc)[2][2][4][2], const Unit& u, int wr, int wc, int fr, int fq) const {
;     ...
;                 const int row = row0 + ai * 128 + m * 16;
;                 const bf16_t* rowp = z + (size_t)row * DIN + col0;
; #pragma unroll
;                 for (int bj = 0; bj < 2; ++bj) {
;                     const u32x4 gw = *(const u32x4*)(rowp + O_GA + bj * 128);
;                     f32x4 g0, g1; unpack8(gw, g0, g1);
;                     f32x4 v0, v1;
; #pragma unroll
;                     for (int j = 0; j < 4; ++j) { v0[j] = sigmoidf_(g0[j]) * acc[ai][bj][m][0][j]; v1[j] = sigmoidf_(g1[j]) * acc[ai][bj][m][1][j]; }
;                     const u32x4 mw = *(const u32x4*)(rowp + bj * 128); f32x4 m0, m1; unpack8(mw, m0, m1); v0 += m0; v1 += m1;
;                     __builtin_amdgcn_raw_buffer_store_b128(pack8(v0, v1), rsrc, (unsigned)(((size_t)row * DIN + col0 + bj * 128) * 2), 0, 16  ); }
	v_mov_b32_e32 v22, v232
	v_mov_b32_e32 v23, v233
	v_mov_b32_e32 v24, v234
	v_mov_b32_e32 v25, v235
	v_mov_b32_e32 v26, v236
	v_mov_b32_e32 v27, v237
	v_mov_b32_e32 v28, v238
	v_mov_b32_e32 v29, v239
	s_mov_b32 s100, 0xbfb8aa3b
	v_lshlrev_b32_e32 v242, 16, v22
	v_and_b32_e32 v243, 0xffff0000, v22
	v_lshlrev_b32_e32 v244, 16, v24
	v_and_b32_e32 v245, 0xffff0000, v24
	v_lshlrev_b32_e32 v246, 16, v23
	v_and_b32_e32 v247, 0xffff0000, v23
	v_lshlrev_b32_e32 v248, 16, v25
	v_and_b32_e32 v249, 0xffff0000, v25
	v_pk_mul_f32 v[242:243], v[242:243], s[100:101] op_sel_hi:[1,0]
	v_pk_mul_f32 v[244:245], v[244:245], s[100:101] op_sel_hi:[1,0]
	v_pk_mul_f32 v[246:247], v[246:247], s[100:101] op_sel_hi:[1,0]
	v_pk_mul_f32 v[248:249], v[248:249], s[100:101] op_sel_hi:[1,0]
	v_exp_f32_e32 v242, v242
	v_exp_f32_e32 v243, v243
	v_exp_f32_e32 v244, v244
	v_exp_f32_e32 v245, v245
	v_exp_f32_e32 v246, v246
	v_exp_f32_e32 v247, v247
	v_exp_f32_e32 v248, v248
	v_exp_f32_e32 v249, v249
	s_nop 0
	v_pk_add_f32 v[242:243], v[242:243], 1.0 op_sel_hi:[1,0]
	v_pk_add_f32 v[244:245], v[244:245], 1.0 op_sel_hi:[1,0]
	v_pk_add_f32 v[246:247], v[246:247], 1.0 op_sel_hi:[1,0]
	v_pk_add_f32 v[248:249], v[248:249], 1.0 op_sel_hi:[1,0]
	v_rcp_f32_e32 v250, v242
	v_rcp_f32_e32 v251, v243
	s_nop 0
	v_pk_fma_f32 v[252:253], v[242:243], v[250:251], 1.0 op_sel_hi:[1,1,0] neg_lo:[1,0,0] neg_hi:[1,0,0]
	v_pk_fma_f32 v[250:251], v[252:253], v[250:251], v[250:251]
	v_pk_fma_f32 v[252:253], v[242:243], v[250:251], 1.0 op_sel_hi:[1,1,0] neg_lo:[1,0,0] neg_hi:[1,0,0]
	v_pk_fma_f32 v[254:255], v[252:253], v[250:251], v[250:251]
	v_pk_fma_f32 v[252:253], v[242:243], v[254:255], 1.0 op_sel_hi:[1,1,0] neg_lo:[1,0,0] neg_hi:[1,0,0]
	v_pk_fma_f32 v[254:255], v[252:253], v[250:251], v[254:255]
	v_div_fixup_f32 v242, v254, v242, 1.0
	v_div_fixup_f32 v243, v255, v243, 1.0
	v_rcp_f32_e32 v250, v244
	v_rcp_f32_e32 v251, v245
	s_nop 0
	v_pk_fma_f32 v[252:253], v[244:245], v[250:251], 1.0 op_sel_hi:[1,1,0] neg_lo:[1,0,0] neg_hi:[1,0,0]
	v_pk_fma_f32 v[250:251], v[252:253], v[250:251], v[250:251]
	v_pk_fma_f32 v[252:253], v[244:245], v[250:251], 1.0 op_sel_hi:[1,1,0] neg_lo:[1,0,0] neg_hi:[1,0,0]
	v_pk_fma_f32 v[254:255], v[252:253], v[250:251], v[250:251]
	v_pk_fma_f32 v[252:253], v[244:245], v[254:255], 1.0 op_sel_hi:[1,1,0] neg_lo:[1,0,0] neg_hi:[1,0,0]
	v_pk_fma_f32 v[254:255], v[252:253], v[250:251], v[254:255]
	v_div_fixup_f32 v244, v254, v244, 1.0
	v_div_fixup_f32 v245, v255, v245, 1.0
	v_rcp_f32_e32 v250, v246
	v_rcp_f32_e32 v251, v247
	s_nop 0
	v_pk_fma_f32 v[252:253], v[246:247], v[250:251], 1.0 op_sel_hi:[1,1,0] neg_lo:[1,0,0] neg_hi:[1,0,0]
	v_pk_fma_f32 v[250:251], v[252:253], v[250:251], v[250:251]
	v_pk_fma_f32 v[252:253], v[246:247], v[250:251], 1.0 op_sel_hi:[1,1,0] neg_lo:[1,0,0] neg_hi:[1,0,0]
	v_pk_fma_f32 v[254:255], v[252:253], v[250:251], v[250:251]
	v_pk_fma_f32 v[252:253], v[246:247], v[254:255], 1.0 op_sel_hi:[1,1,0] neg_lo:[1,0,0] neg_hi:[1,0,0]
	v_pk_fma_f32 v[254:255], v[252:253], v[250:251], v[254:255]
	v_div_fixup_f32 v246, v254, v246, 1.0
	v_div_fixup_f32 v247, v255, v247, 1.0
	v_rcp_f32_e32 v250, v248
	v_rcp_f32_e32 v251, v249
	s_nop 0
	v_pk_fma_f32 v[252:253], v[248:249], v[250:251], 1.0 op_sel_hi:[1,1,0] neg_lo:[1,0,0] neg_hi:[1,0,0]
	v_pk_fma_f32 v[250:251], v[252:253], v[250:251], v[250:251]
	v_pk_fma_f32 v[252:253], v[248:249], v[250:251], 1.0 op_sel_hi:[1,1,0] neg_lo:[1,0,0] neg_hi:[1,0,0]
	v_pk_fma_f32 v[254:255], v[252:253], v[250:251], v[250:251]
	v_pk_fma_f32 v[252:253], v[248:249], v[254:255], 1.0 op_sel_hi:[1,1,0] neg_lo:[1,0,0] neg_hi:[1,0,0]
	v_pk_fma_f32 v[254:255], v[252:253], v[250:251], v[254:255]
	v_div_fixup_f32 v248, v254, v248, 1.0
	v_div_fixup_f32 v249, v255, v249, 1.0
	v_lshlrev_b32_e32 v34, 16, v26
	v_and_b32_e32 v35, 0xffff0000, v26
	v_lshlrev_b32_e32 v36, 16, v28
	v_and_b32_e32 v37, 0xffff0000, v28
	v_lshlrev_b32_e32 v28, 16, v29
	v_and_b32_e32 v29, 0xffff0000, v29
	v_lshlrev_b32_e32 v26, 16, v27
	v_and_b32_e32 v27, 0xffff0000, v27
	v_pk_fma_f32 v[12:13], v[12:13], v[242:243], v[34:35]
	v_pk_fma_f32 v[22:23], v[10:11], v[248:249], v[28:29]
	v_pk_fma_f32 v[10:11], v[8:9], v[244:245], v[36:37]
	v_add_lshl_u32 v24, v146, v18, 1
	v_pk_fma_f32 v[14:15], v[14:15], v[246:247], v[26:27]
	v_cvt_pk_bf16_f32 v8, v12, v13
	s_nop 0
	v_cvt_pk_bf16_f32 v9, v14, v15
	v_cvt_pk_bf16_f32 v10, v10, v11
	v_cvt_pk_bf16_f32 v11, v22, v23
	buffer_store_dwordx4 v[8:11], v24, s[20:23], 0 offen sc1
	s_nop 0
	s_waitcnt vmcnt(3)
; __device__ __forceinline__ float sigmoidf_(float x) { return 1.0f / (1.0f + __expf(-x)); }
; __device__ __forceinline__ u32x4 pack8(const f32x4 v0, const f32x4 v1) { u32x4 w; w.x = pk2(v0[0], v0[1]); w.y = pk2(v0[2], v0[3]); w.z = pk2(v1[0], v1[1]); w.w = pk2(v1[2], v1[3]); return w; }
; __device__ __forceinline__ void unpack8(const u32x4 w, f32x4& v0, f32x4& v1) { v0 = (f32x4){bflo(w.x), bfhi(w.x), bflo(w.y), bfhi(w.y)}; v1 = (f32x4){bflo(w.z), bfhi(w.z), bflo(w.w), bfhi(w.w)}; }
;     __device__ __forceinline__ void operator()(const f32x4 (&acc)[2][2][4][2], const Unit& u, int wr, int wc, int fr, int fq) const {
;     ...
;                 const int row = row0 + ai * 128 + m * 16;
;                 const bf16_t* rowp = z + (size_t)row * DIN + col0;
; #pragma unroll
;                 for (int bj = 0; bj < 2; ++bj) {
;                     const u32x4 gw = *(const u32x4*)(rowp + O_GA + bj * 128);
;                     f32x4 g0, g1; unpack8(gw, g0, g1);
;                     f32x4 v0, v1;
; #pragma unroll
;                     for (int j = 0; j < 4; ++j) { v0[j] = sigmoidf_(g0[j]) * acc[ai][bj][m][0][j]; v1[j] = sigmoidf_(g1[j]) * acc[ai][bj][m][1][j]; }
;                     const u32x4 mw = *(const u32x4*)(rowp + bj * 128); f32x4 m0, m1; unpack8(mw, m0, m1); v0 += m0; v1 += m1;
;                     __builtin_amdgcn_raw_buffer_store_b128(pack8(v0, v1), rsrc, (unsigned)(((size_t)row * DIN + col0 + bj * 128) * 2), 0, 16  ); }
;             }
;         asm volatile("s_waitcnt vmcnt(0)" ::: "memory");
;         if (fr == 0 && fq == 0) (void)__hip_atomic_fetch_add(ready + 64 * (pm_off + u.pm), 1u, __ATOMIC_RELAXED, __HIP_MEMORY_SCOPE_AGENT);
	v_mov_b32_e32 v8, v204
	v_mov_b32_e32 v9, v205
	v_mov_b32_e32 v10, v206
	v_mov_b32_e32 v11, v207
	v_mov_b32_e32 v12, v208
	v_mov_b32_e32 v13, v209
	v_mov_b32_e32 v14, v210
	v_mov_b32_e32 v15, v211
	s_mov_b32 s100, 0xbfb8aa3b
	v_lshlrev_b32_e32 v242, 16, v10
	v_and_b32_e32 v243, 0xffff0000, v10
	v_lshlrev_b32_e32 v244, 16, v8
	v_and_b32_e32 v245, 0xffff0000, v8
	v_lshlrev_b32_e32 v246, 16, v9
	v_and_b32_e32 v247, 0xffff0000, v9
	v_lshlrev_b32_e32 v248, 16, v11
	v_and_b32_e32 v249, 0xffff0000, v11
	v_pk_mul_f32 v[242:243], v[242:243], s[100:101] op_sel_hi:[1,0]
	v_pk_mul_f32 v[244:245], v[244:245], s[100:101] op_sel_hi:[1,0]
	v_pk_mul_f32 v[246:247], v[246:247], s[100:101] op_sel_hi:[1,0]
	v_pk_mul_f32 v[248:249], v[248:249], s[100:101] op_sel_hi:[1,0]
	v_exp_f32_e32 v242, v242
	v_exp_f32_e32 v243, v243
	v_exp_f32_e32 v244, v244
	v_exp_f32_e32 v245, v245
	v_exp_f32_e32 v246, v246
	v_exp_f32_e32 v247, v247
	v_exp_f32_e32 v248, v248
	v_exp_f32_e32 v249, v249
	s_nop 0
	v_pk_add_f32 v[242:243], v[242:243], 1.0 op_sel_hi:[1,0]
	v_pk_add_f32 v[244:245], v[244:245], 1.0 op_sel_hi:[1,0]
	v_pk_add_f32 v[246:247], v[246:247], 1.0 op_sel_hi:[1,0]
	v_pk_add_f32 v[248:249], v[248:249], 1.0 op_sel_hi:[1,0]
	v_rcp_f32_e32 v250, v242
	v_rcp_f32_e32 v251, v243
	s_nop 0
	v_pk_fma_f32 v[252:253], v[242:243], v[250:251], 1.0 op_sel_hi:[1,1,0] neg_lo:[1,0,0] neg_hi:[1,0,0]
	v_pk_fma_f32 v[250:251], v[252:253], v[250:251], v[250:251]
	v_pk_fma_f32 v[252:253], v[242:243], v[250:251], 1.0 op_sel_hi:[1,1,0] neg_lo:[1,0,0] neg_hi:[1,0,0]
	v_pk_fma_f32 v[254:255], v[252:253], v[250:251], v[250:251]
	v_pk_fma_f32 v[252:253], v[242:243], v[254:255], 1.0 op_sel_hi:[1,1,0] neg_lo:[1,0,0] neg_hi:[1,0,0]
	v_pk_fma_f32 v[254:255], v[252:253], v[250:251], v[254:255]
	v_div_fixup_f32 v242, v254, v242, 1.0
	v_div_fixup_f32 v243, v255, v243, 1.0
	v_rcp_f32_e32 v250, v244
	v_rcp_f32_e32 v251, v245
	s_nop 0
	v_pk_fma_f32 v[252:253], v[244:245], v[250:251], 1.0 op_sel_hi:[1,1,0] neg_lo:[1,0,0] neg_hi:[1,0,0]
	v_pk_fma_f32 v[250:251], v[252:253], v[250:251], v[250:251]
	v_pk_fma_f32 v[252:253], v[244:245], v[250:251], 1.0 op_sel_hi:[1,1,0] neg_lo:[1,0,0] neg_hi:[1,0,0]
	v_pk_fma_f32 v[254:255], v[252:253], v[250:251], v[250:251]
	v_pk_fma_f32 v[252:253], v[244:245], v[254:255], 1.0 op_sel_hi:[1,1,0] neg_lo:[1,0,0] neg_hi:[1,0,0]
	v_pk_fma_f32 v[254:255], v[252:253], v[250:251], v[254:255]
	v_div_fixup_f32 v244, v254, v244, 1.0
	v_div_fixup_f32 v245, v255, v245, 1.0
	v_rcp_f32_e32 v250, v246
	v_rcp_f32_e32 v251, v247
	s_nop 0
	v_pk_fma_f32 v[252:253], v[246:247], v[250:251], 1.0 op_sel_hi:[1,1,0] neg_lo:[1,0,0] neg_hi:[1,0,0]
	v_pk_fma_f32 v[250:251], v[252:253], v[250:251], v[250:251]
	v_pk_fma_f32 v[252:253], v[246:247], v[250:251], 1.0 op_sel_hi:[1,1,0] neg_lo:[1,0,0] neg_hi:[1,0,0]
	v_pk_fma_f32 v[254:255], v[252:253], v[250:251], v[250:251]
	v_pk_fma_f32 v[252:253], v[246:247], v[254:255], 1.0 op_sel_hi:[1,1,0] neg_lo:[1,0,0] neg_hi:[1,0,0]
	v_pk_fma_f32 v[254:255], v[252:253], v[250:251], v[254:255]
	v_div_fixup_f32 v246, v254, v246, 1.0
	v_div_fixup_f32 v247, v255, v247, 1.0
	v_rcp_f32_e32 v250, v248
	v_rcp_f32_e32 v251, v249
	s_nop 0
	v_pk_fma_f32 v[252:253], v[248:249], v[250:251], 1.0 op_sel_hi:[1,1,0] neg_lo:[1,0,0] neg_hi:[1,0,0]
	v_pk_fma_f32 v[250:251], v[252:253], v[250:251], v[250:251]
	v_pk_fma_f32 v[252:253], v[248:249], v[250:251], 1.0 op_sel_hi:[1,1,0] neg_lo:[1,0,0] neg_hi:[1,0,0]
	v_pk_fma_f32 v[254:255], v[252:253], v[250:251], v[250:251]
	v_pk_fma_f32 v[252:253], v[248:249], v[254:255], 1.0 op_sel_hi:[1,1,0] neg_lo:[1,0,0] neg_hi:[1,0,0]
	v_pk_fma_f32 v[254:255], v[252:253], v[250:251], v[254:255]
	v_div_fixup_f32 v248, v254, v248, 1.0
	v_div_fixup_f32 v249, v255, v249, 1.0
	v_lshlrev_b32_e32 v20, 16, v12
	v_and_b32_e32 v21, 0xffff0000, v12
	v_lshlrev_b32_e32 v22, 16, v14
	v_and_b32_e32 v23, 0xffff0000, v14
	v_lshlrev_b32_e32 v14, 16, v15
	v_and_b32_e32 v15, 0xffff0000, v15
	v_lshlrev_b32_e32 v12, 16, v13
	v_and_b32_e32 v13, 0xffff0000, v13
	v_pk_fma_f32 v[4:5], v[4:5], v[244:245], v[20:21]
	v_pk_fma_f32 v[8:9], v[2:3], v[248:249], v[14:15]
	v_pk_fma_f32 v[2:3], v[0:1], v[242:243], v[22:23]
	v_pk_fma_f32 v[6:7], v[6:7], v[246:247], v[12:13]
	v_cvt_pk_bf16_f32 v0, v4, v5
	s_nop 0
	v_cvt_pk_bf16_f32 v1, v6, v7
	v_cvt_pk_bf16_f32 v2, v2, v3
	v_cvt_pk_bf16_f32 v3, v8, v9
	buffer_store_dwordx4 v[0:3], v24, s[20:23], 0 offen offset:256 sc1
	s_waitcnt vmcnt(0)
	s_and_saveexec_b64 s[12:13], s[8:9]
	s_cbranch_execz .LBB0_1833
	s_mov_b64 s[14:15], exec
	v_mbcnt_lo_u32_b32 v0, s14, 0
	v_mbcnt_hi_u32_b32 v0, s15, v0
	v_cmp_eq_u32_e32 vcc, 0, v0
	s_and_b64 s[6:7], exec, vcc
	s_mov_b64 exec, s[6:7]
	s_cbranch_execz .LBB0_1833
	s_lshl_b32 s6, s75, 6
	s_ashr_i32 s7, s6, 31
	s_lshl_b64 s[6:7], s[6:7], 2
	s_add_u32 s6, s28, s6
	s_addc_u32 s7, s29, s7
	s_bcnt1_i32_b64 s14, s[14:15]
	v_mov_b32_e32 v0, s14
	global_atomic_add v131, v0, s[6:7]
	s_branch .LBB0_1833

; #define PG8_STAGE(bufoff, gbase, voff) do { _Pragma("unroll") for (int _i = 0; _i < 2; ++_i) \
;         __builtin_amdgcn_global_load_lds((const unsigned*)((const char*)(gbase) + (voff)[_i]), (LAS unsigned*)(lds + (bufoff) + ldsw + _i * 8192), 16, 0, 0); } while (0)
; #define PG8_LDA(dst, b, h) do { _Pragma("unroll") for (int m = 0; m < 4; ++m) _Pragma("unroll") for (int k = 0; k < 2; ++k) dst[m][k] = *(const LAS bf16x8*)(lds + PG8_SA(b, h) + aoff + m * 2048 + k * 1024); } while (0)
; #define PG8_LDB(dst, b, h) do { _Pragma("unroll") for (int n = 0; n < 2; ++n) _Pragma("unroll") for (int k = 0; k < 2; ++k) dst[n][k] = *(const LAS bf16x8*)(lds + PG8_SB(b, h) + boff + n * 2048 + k * 1024); } while (0)
; #define PG8_MMA(ai, bj, At, Bt) do { __builtin_amdgcn_s_setprio(1); _Pragma("unroll") for (int m = 0; m < 4; ++m) _Pragma("unroll") for (int n = 0; n < 2; ++n) _Pragma("unroll") for (int k = 0; k < 2; ++k) \
;         acc[ai][bj][m][n] = __builtin_amdgcn_mfma_f32_16x16x32_bf16(Bt[n][k], At[m][k], acc[ai][bj][m][n], 0, 0, 0); __builtin_amdgcn_s_setprio(0); } while (0)
; #define PG8_WAIT_V(n) asm volatile("s_waitcnt vmcnt(" #n ")" ::: "memory")
; #define PG8_WAIT_L(n) asm volatile("s_waitcnt lgkmcnt(" #n ")" ::: "memory")
; #define PG8_BAR __builtin_amdgcn_s_barrier()
; #define PG8_SCHED __builtin_amdgcn_sched_barrier(0)
;     ...
;             PG8_LDB(B0, 0, 0); PG8_SCHED; PG8_LDA(At, 0, 0); PG8_STAGE(PG8_SA(1, 1), a1 + hA, voffA);
;             PG8_WAIT_L(8); PG8_BAR; PG8_WAIT_L(0); PG8_MMA(0, 0, At, B0); PG8_BAR; PG8_SCHED;
;             PG8_LDB(B1, 0, 1); PG8_STAGE(PG8_SB(0, 0), b2, voffB);
;             PG8_BAR; PG8_WAIT_L(0); PG8_MMA(0, 1, At, B1); PG8_BAR;
;             PG8_LDA(At, 0, 1); PG8_STAGE(PG8_SA(0, 0), a2, voffA);
;             PG8_BAR; PG8_WAIT_L(0); PG8_MMA(1, 0, At, B0); PG8_BAR; PG8_SCHED;
;             PG8_STAGE(PG8_SB(0, 1), b2 + hB, voffB);
;             PG8_WAIT_V(6); PG8_BAR; PG8_MMA(1, 1, At, B1); PG8_BAR;
;             PG8_LDB(B0, 1, 0); PG8_SCHED; PG8_LDA(At, 1, 0); PG8_STAGE(PG8_SA(0, 1), a2 + hA, voffA);
;             PG8_WAIT_L(8); PG8_BAR; PG8_WAIT_L(0); PG8_MMA(0, 0, At, B0); PG8_BAR; PG8_SCHED;
.LBB0_1864:
	ds_read_b128 v[140:143], v155
	ds_read_b128 v[146:149], v155 offset:1024
	ds_read_b128 v[158:161], v155 offset:2048
	ds_read_b128 v[162:165], v155 offset:3072
	s_add_u32 s12, s10, 0xfffe0080
	s_addc_u32 s13, s11, -1
	s_cmp_eq_u32 s45, 4
	s_cselect_b32 s15, s7, s13
	s_cselect_b32 s14, s16, s12
	s_cselect_b32 s13, s17, s44
	s_cselect_b32 s12, s33, s37
	v_lshl_add_u64 v[150:151], s[10:11], 0, v[138:139]
	s_add_i32 m0, s62, 0xc000
	ds_read_b128 v[170:173], v156
	ds_read_b128 v[174:177], v156 offset:1024
	ds_read_b128 v[178:181], v156 offset:2048
	ds_read_b128 v[182:185], v156 offset:3072
	ds_read_b128 v[186:189], v156 offset:4096
	ds_read_b128 v[190:193], v156 offset:5120
	ds_read_b128 v[194:197], v156 offset:6144
	ds_read_b128 v[198:201], v156 offset:7168
	global_load_lds_dwordx4 v[150:151], off
	v_lshl_add_u64 v[150:151], s[10:11], 0, v[136:137]
	s_add_i32 m0, s62, 0xe000
	s_nop 0
	global_load_lds_dwordx4 v[150:151], off
	s_waitcnt lgkmcnt(8)
	s_barrier
	s_waitcnt lgkmcnt(0)
	s_setprio 1
	s_waitcnt lgkmcnt(0)
	v_mfma_f32_16x16x32_bf16 v[124:127], v[140:143], v[170:173], v[124:127]
	v_mfma_f32_16x16x32_bf16 v[120:123], v[158:161], v[170:173], v[120:123]
	v_mfma_f32_16x16x32_bf16 v[108:111], v[140:143], v[178:181], v[108:111]
	v_mfma_f32_16x16x32_bf16 v[104:107], v[158:161], v[178:181], v[104:107]
	v_mfma_f32_16x16x32_bf16 v[92:95], v[140:143], v[186:189], v[92:95]
	v_mfma_f32_16x16x32_bf16 v[88:91], v[158:161], v[186:189], v[88:91]
	v_mfma_f32_16x16x32_bf16 v[76:79], v[140:143], v[194:197], v[76:79]
	v_mfma_f32_16x16x32_bf16 v[72:75], v[158:161], v[194:197], v[72:75]
	v_mfma_f32_16x16x32_bf16 v[124:127], v[146:149], v[174:177], v[124:127]
	v_mfma_f32_16x16x32_bf16 v[120:123], v[162:165], v[174:177], v[120:123]
	v_mfma_f32_16x16x32_bf16 v[108:111], v[146:149], v[182:185], v[108:111]
	v_mfma_f32_16x16x32_bf16 v[104:107], v[162:165], v[182:185], v[104:107]
	v_mfma_f32_16x16x32_bf16 v[92:95], v[146:149], v[190:193], v[92:95]
	v_mfma_f32_16x16x32_bf16 v[88:91], v[162:165], v[190:193], v[88:91]
	v_mfma_f32_16x16x32_bf16 v[76:79], v[146:149], v[198:201], v[76:79]
	v_mfma_f32_16x16x32_bf16 v[72:75], v[162:165], v[198:201], v[72:75]
	s_setprio 0
	s_barrier
	s_add_i32 s53, s71, s61
	v_lshl_add_u64 v[150:151], s[12:13], 0, v[130:131]
	s_mov_b32 m0, s53
	ds_read_b128 v[202:205], v157
	ds_read_b128 v[206:209], v157 offset:1024
	ds_read_b128 v[210:213], v157 offset:2048
	ds_read_b128 v[214:217], v157 offset:3072
	global_load_lds_dwordx4 v[150:151], off
	v_lshl_add_u64 v[218:219], s[12:13], 0, v[134:135]
	s_add_i32 m0, s53, 0x2000
	s_nop 0
	global_load_lds_dwordx4 v[218:219], off
	s_barrier
	s_waitcnt lgkmcnt(0)
	s_setprio 1
	s_waitcnt lgkmcnt(0)
	v_mfma_f32_16x16x32_bf16 v[116:119], v[202:205], v[170:173], v[116:119]
	v_mfma_f32_16x16x32_bf16 v[112:115], v[210:213], v[170:173], v[112:115]
	v_mfma_f32_16x16x32_bf16 v[100:103], v[202:205], v[178:181], v[100:103]
	v_mfma_f32_16x16x32_bf16 v[96:99], v[210:213], v[178:181], v[96:99]
	v_mfma_f32_16x16x32_bf16 v[84:87], v[202:205], v[186:189], v[84:87]
	v_mfma_f32_16x16x32_bf16 v[80:83], v[210:213], v[186:189], v[80:83]
	v_mfma_f32_16x16x32_bf16 v[68:71], v[202:205], v[194:197], v[68:71]
	v_mfma_f32_16x16x32_bf16 v[64:67], v[210:213], v[194:197], v[64:67]
	v_mfma_f32_16x16x32_bf16 v[116:119], v[206:209], v[174:177], v[116:119]
	v_mfma_f32_16x16x32_bf16 v[112:115], v[214:217], v[174:177], v[112:115]
	v_mfma_f32_16x16x32_bf16 v[100:103], v[206:209], v[182:185], v[100:103]
	v_mfma_f32_16x16x32_bf16 v[96:99], v[214:217], v[182:185], v[96:99]
	v_mfma_f32_16x16x32_bf16 v[84:87], v[206:209], v[190:193], v[84:87]
	v_mfma_f32_16x16x32_bf16 v[80:83], v[214:217], v[190:193], v[80:83]
	v_mfma_f32_16x16x32_bf16 v[68:71], v[206:209], v[198:201], v[68:71]
	v_mfma_f32_16x16x32_bf16 v[64:67], v[214:217], v[198:201], v[64:67]
	s_setprio 0
	s_mov_b32 m0, s62
	v_lshl_add_u64 v[220:221], s[14:15], 0, v[128:129]
	s_barrier
	ds_read_b128 v[170:173], v156 offset:16384
	ds_read_b128 v[174:177], v156 offset:17408
	ds_read_b128 v[178:181], v156 offset:18432
	ds_read_b128 v[182:185], v156 offset:19456
	ds_read_b128 v[186:189], v156 offset:20480
	ds_read_b128 v[190:193], v156 offset:21504
	ds_read_b128 v[194:197], v156 offset:22528
	ds_read_b128 v[198:201], v156 offset:23552
	global_load_lds_dwordx4 v[220:221], off
	v_lshl_add_u64 v[222:223], s[14:15], 0, v[132:133]
	s_mov_b32 m0, s63
	s_nop 0
	global_load_lds_dwordx4 v[222:223], off
	s_barrier
	s_waitcnt lgkmcnt(0)
	s_setprio 1
	s_waitcnt lgkmcnt(0)
	v_mfma_f32_16x16x32_bf16 v[60:63], v[140:143], v[170:173], v[60:63]
	v_mfma_f32_16x16x32_bf16 v[56:59], v[158:161], v[170:173], v[56:59]
	v_mfma_f32_16x16x32_bf16 v[44:47], v[140:143], v[178:181], v[44:47]
	v_mfma_f32_16x16x32_bf16 v[40:43], v[158:161], v[178:181], v[40:43]
	v_mfma_f32_16x16x32_bf16 v[28:31], v[140:143], v[186:189], v[28:31]
	v_mfma_f32_16x16x32_bf16 v[24:27], v[158:161], v[186:189], v[24:27]
	v_mfma_f32_16x16x32_bf16 v[12:15], v[140:143], v[194:197], v[12:15]
	v_mfma_f32_16x16x32_bf16 v[8:11], v[158:161], v[194:197], v[8:11]
	v_mfma_f32_16x16x32_bf16 v[60:63], v[146:149], v[174:177], v[60:63]
	v_mfma_f32_16x16x32_bf16 v[56:59], v[162:165], v[174:177], v[56:59]
	v_mfma_f32_16x16x32_bf16 v[44:47], v[146:149], v[182:185], v[44:47]
	v_mfma_f32_16x16x32_bf16 v[40:43], v[162:165], v[182:185], v[40:43]
	v_mfma_f32_16x16x32_bf16 v[28:31], v[146:149], v[190:193], v[28:31]
	v_mfma_f32_16x16x32_bf16 v[24:27], v[162:165], v[190:193], v[24:27]
	v_mfma_f32_16x16x32_bf16 v[12:15], v[146:149], v[198:201], v[12:15]
	v_mfma_f32_16x16x32_bf16 v[8:11], v[162:165], v[198:201], v[8:11]
	s_setprio 0
	s_barrier
; #define PG8_STAGE(bufoff, gbase, voff) do { _Pragma("unroll") for (int _i = 0; _i < 2; ++_i) \
;         __builtin_amdgcn_global_load_lds((const unsigned*)((const char*)(gbase) + (voff)[_i]), (LAS unsigned*)(lds + (bufoff) + ldsw + _i * 8192), 16, 0, 0); } while (0)
; #define PG8_LDA(dst, b, h) do { _Pragma("unroll") for (int m = 0; m < 4; ++m) _Pragma("unroll") for (int k = 0; k < 2; ++k) dst[m][k] = *(const LAS bf16x8*)(lds + PG8_SA(b, h) + aoff + m * 2048 + k * 1024); } while (0)
; #define PG8_LDB(dst, b, h) do { _Pragma("unroll") for (int n = 0; n < 2; ++n) _Pragma("unroll") for (int k = 0; k < 2; ++k) dst[n][k] = *(const LAS bf16x8*)(lds + PG8_SB(b, h) + boff + n * 2048 + k * 1024); } while (0)
; #define PG8_MMA(ai, bj, At, Bt) do { __builtin_amdgcn_s_setprio(1); _Pragma("unroll") for (int m = 0; m < 4; ++m) _Pragma("unroll") for (int n = 0; n < 2; ++n) _Pragma("unroll") for (int k = 0; k < 2; ++k) \
;         acc[ai][bj][m][n] = __builtin_amdgcn_mfma_f32_16x16x32_bf16(Bt[n][k], At[m][k], acc[ai][bj][m][n], 0, 0, 0); __builtin_amdgcn_s_setprio(0); } while (0)
; #define PG8_WAIT_V(n) asm volatile("s_waitcnt vmcnt(" #n ")" ::: "memory")
; #define PG8_WAIT_L(n) asm volatile("s_waitcnt lgkmcnt(" #n ")" ::: "memory")
; #define PG8_BAR __builtin_amdgcn_s_barrier()
; #define PG8_SCHED __builtin_amdgcn_sched_barrier(0)
;     ...
;             PG8_STAGE(PG8_SB(0, 1), b2 + hB, voffB);
;             PG8_WAIT_V(6); PG8_BAR; PG8_MMA(1, 1, At, B1); PG8_BAR;
;             PG8_LDB(B0, 1, 0); PG8_SCHED; PG8_LDA(At, 1, 0); PG8_STAGE(PG8_SA(0, 1), a2 + hA, voffA);
;             PG8_WAIT_L(8); PG8_BAR; PG8_WAIT_L(0); PG8_MMA(0, 0, At, B0); PG8_BAR; PG8_SCHED;
;             PG8_LDB(B1, 1, 1); PG8_STAGE(PG8_SB(1, 0), b3, voffB);
;             PG8_BAR; PG8_WAIT_L(0); PG8_MMA(0, 1, At, B1); PG8_BAR;
;             PG8_LDA(At, 1, 1); PG8_STAGE(PG8_SA(1, 0), a3, voffA);
;             PG8_BAR; PG8_WAIT_L(0); PG8_MMA(1, 0, At, B0); PG8_BAR; PG8_SCHED;
	s_add_u32 s76, s12, 0x20000
	s_addc_u32 s77, s13, 0
	s_add_i32 s53, s72, s61
	v_lshl_add_u64 v[140:141], s[76:77], 0, v[130:131]
	s_mov_b32 m0, s53
	s_nop 0
	global_load_lds_dwordx4 v[140:141], off
	v_lshl_add_u64 v[140:141], s[76:77], 0, v[134:135]
	s_add_i32 m0, s53, 0x2000
	s_nop 0
	global_load_lds_dwordx4 v[140:141], off
	s_waitcnt vmcnt(6)
	s_barrier
	s_setprio 1
	v_mfma_f32_16x16x32_bf16 v[52:55], v[202:205], v[170:173], v[52:55]
	v_mfma_f32_16x16x32_bf16 v[48:51], v[210:213], v[170:173], v[48:51]
	v_mfma_f32_16x16x32_bf16 v[36:39], v[202:205], v[178:181], v[36:39]
	v_mfma_f32_16x16x32_bf16 v[32:35], v[210:213], v[178:181], v[32:35]
	v_mfma_f32_16x16x32_bf16 v[20:23], v[202:205], v[186:189], v[20:23]
	v_mfma_f32_16x16x32_bf16 v[16:19], v[210:213], v[186:189], v[16:19]
	v_mfma_f32_16x16x32_bf16 v[4:7], v[202:205], v[194:197], v[4:7]
	v_mfma_f32_16x16x32_bf16 v[0:3], v[210:213], v[194:197], v[0:3]
	v_mfma_f32_16x16x32_bf16 v[52:55], v[206:209], v[174:177], v[52:55]
	v_mfma_f32_16x16x32_bf16 v[48:51], v[214:217], v[174:177], v[48:51]
	v_mfma_f32_16x16x32_bf16 v[36:39], v[206:209], v[182:185], v[36:39]
	v_mfma_f32_16x16x32_bf16 v[32:35], v[214:217], v[182:185], v[32:35]
	v_mfma_f32_16x16x32_bf16 v[20:23], v[206:209], v[190:193], v[20:23]
	v_mfma_f32_16x16x32_bf16 v[16:19], v[214:217], v[190:193], v[16:19]
	v_mfma_f32_16x16x32_bf16 v[4:7], v[206:209], v[198:201], v[4:7]
	v_mfma_f32_16x16x32_bf16 v[0:3], v[214:217], v[198:201], v[0:3]
	s_setprio 0
	s_add_i32 s53, 0, 0x18000
	v_add_u32_e32 v162, s53, v153
	s_barrier
	ds_read_b128 v[140:143], v162
	ds_read_b128 v[146:149], v162 offset:1024
	ds_read_b128 v[158:161], v162 offset:2048
	ds_read_b128 v[162:165], v162 offset:3072
	s_add_u32 s14, s14, 0x20000
	s_addc_u32 s15, s15, 0
	s_mov_b32 m0, s64
	v_lshl_add_u64 v[202:203], s[14:15], 0, v[128:129]
	ds_read_b128 v[170:173], v156 offset:32768
	ds_read_b128 v[174:177], v156 offset:33792
	ds_read_b128 v[178:181], v156 offset:34816
	ds_read_b128 v[182:185], v156 offset:35840
	ds_read_b128 v[186:189], v156 offset:36864
	ds_read_b128 v[190:193], v156 offset:37888
	ds_read_b128 v[194:197], v156 offset:38912
	ds_read_b128 v[198:201], v156 offset:39936
	global_load_lds_dwordx4 v[202:203], off
	v_lshl_add_u64 v[202:203], s[14:15], 0, v[132:133]
	s_mov_b32 m0, s65
	s_nop 0
	global_load_lds_dwordx4 v[202:203], off
	s_waitcnt lgkmcnt(8)
	s_barrier
	s_waitcnt lgkmcnt(0)
	s_setprio 1
	s_waitcnt lgkmcnt(0)
	v_mfma_f32_16x16x32_bf16 v[124:127], v[140:143], v[170:173], v[124:127]
	v_mfma_f32_16x16x32_bf16 v[120:123], v[158:161], v[170:173], v[120:123]
	v_mfma_f32_16x16x32_bf16 v[108:111], v[140:143], v[178:181], v[108:111]
	v_mfma_f32_16x16x32_bf16 v[104:107], v[158:161], v[178:181], v[104:107]
	v_mfma_f32_16x16x32_bf16 v[92:95], v[140:143], v[186:189], v[92:95]
	v_mfma_f32_16x16x32_bf16 v[88:91], v[158:161], v[186:189], v[88:91]
	v_mfma_f32_16x16x32_bf16 v[76:79], v[140:143], v[194:197], v[76:79]
	v_mfma_f32_16x16x32_bf16 v[72:75], v[158:161], v[194:197], v[72:75]
	v_mfma_f32_16x16x32_bf16 v[124:127], v[146:149], v[174:177], v[124:127]
	v_mfma_f32_16x16x32_bf16 v[120:123], v[162:165], v[174:177], v[120:123]
	v_mfma_f32_16x16x32_bf16 v[108:111], v[146:149], v[182:185], v[108:111]
	v_mfma_f32_16x16x32_bf16 v[104:107], v[162:165], v[182:185], v[104:107]
	v_mfma_f32_16x16x32_bf16 v[92:95], v[146:149], v[190:193], v[92:95]
	v_mfma_f32_16x16x32_bf16 v[88:91], v[162:165], v[190:193], v[88:91]
	v_mfma_f32_16x16x32_bf16 v[76:79], v[146:149], v[198:201], v[76:79]
	v_mfma_f32_16x16x32_bf16 v[72:75], v[162:165], v[198:201], v[72:75]
	s_setprio 0
	s_barrier
	s_add_i32 s14, 0, 0x1c000
	s_add_i32 s15, s53, s61
	v_add_u32_e32 v169, s14, v153
	v_lshl_add_u64 v[150:151], v[150:151], 0, s[38:39]
	s_mov_b32 m0, s15
	ds_read_b128 v[202:205], v169
	ds_read_b128 v[206:209], v169 offset:1024
	ds_read_b128 v[210:213], v169 offset:2048
	ds_read_b128 v[214:217], v169 offset:3072
	global_load_lds_dwordx4 v[150:151], off
	v_lshl_add_u64 v[150:151], v[218:219], 0, s[38:39]
	s_add_i32 m0, s15, 0x2000
	s_nop 0
	global_load_lds_dwordx4 v[150:151], off
	s_barrier
	s_waitcnt lgkmcnt(0)
	s_setprio 1
	s_waitcnt lgkmcnt(0)
	v_mfma_f32_16x16x32_bf16 v[116:119], v[202:205], v[170:173], v[116:119]
	v_mfma_f32_16x16x32_bf16 v[112:115], v[210:213], v[170:173], v[112:115]
	v_mfma_f32_16x16x32_bf16 v[100:103], v[202:205], v[178:181], v[100:103]
	v_mfma_f32_16x16x32_bf16 v[96:99], v[210:213], v[178:181], v[96:99]
	v_mfma_f32_16x16x32_bf16 v[84:87], v[202:205], v[186:189], v[84:87]
	v_mfma_f32_16x16x32_bf16 v[80:83], v[210:213], v[186:189], v[80:83]
	v_mfma_f32_16x16x32_bf16 v[68:71], v[202:205], v[194:197], v[68:71]
	v_mfma_f32_16x16x32_bf16 v[64:67], v[210:213], v[194:197], v[64:67]
	v_mfma_f32_16x16x32_bf16 v[116:119], v[206:209], v[174:177], v[116:119]
	v_mfma_f32_16x16x32_bf16 v[112:115], v[214:217], v[174:177], v[112:115]
	v_mfma_f32_16x16x32_bf16 v[100:103], v[206:209], v[182:185], v[100:103]
	v_mfma_f32_16x16x32_bf16 v[96:99], v[214:217], v[182:185], v[96:99]
	v_mfma_f32_16x16x32_bf16 v[84:87], v[206:209], v[190:193], v[84:87]
	v_mfma_f32_16x16x32_bf16 v[80:83], v[214:217], v[190:193], v[80:83]
	v_mfma_f32_16x16x32_bf16 v[68:71], v[206:209], v[198:201], v[68:71]
	v_mfma_f32_16x16x32_bf16 v[64:67], v[214:217], v[198:201], v[64:67]
	s_setprio 0
	s_mov_b32 m0, s67
	v_lshl_add_u64 v[150:151], v[220:221], 0, s[38:39]
	s_barrier
	ds_read_b128 v[170:173], v156 offset:49152
	ds_read_b128 v[174:177], v156 offset:50176
	ds_read_b128 v[178:181], v156 offset:51200
	ds_read_b128 v[182:185], v156 offset:52224
	ds_read_b128 v[186:189], v156 offset:53248
	ds_read_b128 v[190:193], v156 offset:54272
	ds_read_b128 v[194:197], v156 offset:55296
	ds_read_b128 v[198:201], v156 offset:56320
	global_load_lds_dwordx4 v[150:151], off
	v_lshl_add_u64 v[150:151], v[222:223], 0, s[38:39]
	s_mov_b32 m0, s68
	s_nop 0
	global_load_lds_dwordx4 v[150:151], off
	s_barrier
; __device__ __forceinline__ float sigmoidf_(float x) { return 1.0f / (1.0f + __expf(-x)); }
; #define PG8_STAGE(bufoff, gbase, voff) do { _Pragma("unroll") for (int _i = 0; _i < 2; ++_i) \
;         __builtin_amdgcn_global_load_lds((const unsigned*)((const char*)(gbase) + (voff)[_i]), (LAS unsigned*)(lds + (bufoff) + ldsw + _i * 8192), 16, 0, 0); } while (0)
; #define PG8_LDA(dst, b, h) do { _Pragma("unroll") for (int m = 0; m < 4; ++m) _Pragma("unroll") for (int k = 0; k < 2; ++k) dst[m][k] = *(const LAS bf16x8*)(lds + PG8_SA(b, h) + aoff + m * 2048 + k * 1024); } while (0)
;     ...
;             PG8_WAIT_L(8); PG8_BAR; PG8_WAIT_L(0); PG8_MMA(0, 0, At, B0); PG8_BAR; PG8_SCHED;
;             PG8_LDB(B1, 1, 1); PG8_STAGE(PG8_SB(1, 0), b3, voffB);
;             PG8_BAR; PG8_WAIT_L(0); PG8_MMA(0, 1, At, B1); PG8_BAR;
;             PG8_LDA(At, 1, 1); PG8_STAGE(PG8_SA(1, 0), a3, voffA);
;             PG8_BAR; PG8_WAIT_L(0); PG8_MMA(1, 0, At, B0); PG8_BAR; PG8_SCHED;
;             PG8_STAGE(PG8_SB(1, 1), b3 + hB, voffB);
;             PG8_WAIT_V(6); PG8_BAR; PG8_MMA(1, 1, At, B1); PG8_BAR;
;     __device__ __forceinline__ void operator()(const f32x4 (&acc)[2][2][4][2], const Unit& u, int wr, int wc, int fr, int fq) const {
;         const __amdgpu_buffer_rsrc_t rsrc = __builtin_amdgcn_make_buffer_rsrc((void*)z, 0, T_ALL * DIN * 2, 0x00020000);
;         const int row0 = row_off + u.pm * 256 + wr * 64 + fr, col0 = u.pn * 256 + wc * 32 + 8 * fq;
; #pragma unroll
;         for (int ai = 0; ai < 2; ++ai)
; #pragma unroll
;             for (int m = 0; m < 4; ++m) {
;                 const int row = row0 + ai * 128 + m * 16;
;                 const bf16_t* rowp = z + (size_t)row * DIN + col0;
; #pragma unroll
;                 for (int bj = 0; bj < 2; ++bj) {
;                     const u32x4 gw = *(const u32x4*)(rowp + O_GA + bj * 128);
;                     f32x4 g0, g1; unpack8(gw, g0, g1);
;                     f32x4 v0, v1;
; #pragma unroll
;                     for (int j = 0; j < 4; ++j) { v0[j] = sigmoidf_(g0[j]) * acc[ai][bj][m][0][j]; v1[j] = sigmoidf_(g1[j]) * acc[ai][bj][m][1][j]; }
;                     const u32x4 mw = *(const u32x4*)(rowp + bj * 128); f32x4 m0, m1; unpack8(mw, m0, m1); v0 += m0; v1 += m1;
;                     __builtin_amdgcn_raw_buffer_store_b128(pack8(v0, v1), rsrc, (unsigned)(((size_t)row * DIN + col0 + bj * 128) * 2), 0, 16  ); }
	s_waitcnt lgkmcnt(0)
	s_setprio 1
	s_waitcnt lgkmcnt(0)
	v_mfma_f32_16x16x32_bf16 v[60:63], v[140:143], v[170:173], v[60:63]
	v_mfma_f32_16x16x32_bf16 v[56:59], v[158:161], v[170:173], v[56:59]
	v_mfma_f32_16x16x32_bf16 v[44:47], v[140:143], v[178:181], v[44:47]
	v_mfma_f32_16x16x32_bf16 v[40:43], v[158:161], v[178:181], v[40:43]
	v_mfma_f32_16x16x32_bf16 v[28:31], v[140:143], v[186:189], v[28:31]
	v_mfma_f32_16x16x32_bf16 v[24:27], v[158:161], v[186:189], v[24:27]
	v_mfma_f32_16x16x32_bf16 v[12:15], v[140:143], v[194:197], v[12:15]
	v_mfma_f32_16x16x32_bf16 v[8:11], v[158:161], v[194:197], v[8:11]
	v_mfma_f32_16x16x32_bf16 v[60:63], v[146:149], v[174:177], v[60:63]
	v_mfma_f32_16x16x32_bf16 v[56:59], v[162:165], v[174:177], v[56:59]
	v_mfma_f32_16x16x32_bf16 v[44:47], v[146:149], v[182:185], v[44:47]
	v_mfma_f32_16x16x32_bf16 v[40:43], v[162:165], v[182:185], v[40:43]
	v_mfma_f32_16x16x32_bf16 v[28:31], v[146:149], v[190:193], v[28:31]
	v_mfma_f32_16x16x32_bf16 v[24:27], v[162:165], v[190:193], v[24:27]
	v_mfma_f32_16x16x32_bf16 v[12:15], v[146:149], v[198:201], v[12:15]
	v_mfma_f32_16x16x32_bf16 v[8:11], v[162:165], v[198:201], v[8:11]
	s_setprio 0
	s_barrier
	s_add_u32 s12, s12, 0x20080
	s_addc_u32 s13, s13, 0
	s_add_i32 s14, s14, s61
	v_lshl_add_u64 v[140:141], s[12:13], 0, v[130:131]
	s_mov_b32 m0, s14
	s_nop 0
	global_load_lds_dwordx4 v[140:141], off
	v_lshl_add_u64 v[140:141], s[12:13], 0, v[134:135]
	s_add_i32 m0, s14, 0x2000
	s_nop 0
	global_load_lds_dwordx4 v[140:141], off
	s_waitcnt vmcnt(6)
	s_barrier
	s_setprio 1
	v_mfma_f32_16x16x32_bf16 v[52:55], v[202:205], v[170:173], v[52:55]
	v_mfma_f32_16x16x32_bf16 v[48:51], v[210:213], v[170:173], v[48:51]
	v_mfma_f32_16x16x32_bf16 v[36:39], v[202:205], v[178:181], v[36:39]
	v_mfma_f32_16x16x32_bf16 v[32:35], v[210:213], v[178:181], v[32:35]
	v_mfma_f32_16x16x32_bf16 v[20:23], v[202:205], v[186:189], v[20:23]
	v_mfma_f32_16x16x32_bf16 v[16:19], v[210:213], v[186:189], v[16:19]
	v_mfma_f32_16x16x32_bf16 v[4:7], v[202:205], v[194:197], v[4:7]
	v_mfma_f32_16x16x32_bf16 v[0:3], v[210:213], v[194:197], v[0:3]
	v_mfma_f32_16x16x32_bf16 v[52:55], v[206:209], v[174:177], v[52:55]
	v_mfma_f32_16x16x32_bf16 v[48:51], v[214:217], v[174:177], v[48:51]
	v_mfma_f32_16x16x32_bf16 v[36:39], v[206:209], v[182:185], v[36:39]
	v_mfma_f32_16x16x32_bf16 v[32:35], v[214:217], v[182:185], v[32:35]
	v_mfma_f32_16x16x32_bf16 v[20:23], v[206:209], v[190:193], v[20:23]
	v_mfma_f32_16x16x32_bf16 v[16:19], v[214:217], v[190:193], v[16:19]
	v_mfma_f32_16x16x32_bf16 v[4:7], v[206:209], v[198:201], v[4:7]
	v_mfma_f32_16x16x32_bf16 v[0:3], v[214:217], v[198:201], v[0:3]
	s_setprio 0
	s_add_i32 s45, s45, 2
	s_add_u32 s37, s37, 0x100
	s_addc_u32 s44, s44, 0
	s_add_u32 s10, s10, 0x100
	s_addc_u32 s11, s11, 0
	s_cmp_gt_u32 s45, 5
	s_barrier
	s_cbranch_scc0 .LBB0_1864
	v_lshl_add_u32 v158, s75, 8, v152
	v_lshl_or_b32 v140, s6, 8, v154
	v_add_u32_e32 v142, 0x4000, v158
	v_ashrrev_i32_e32 v141, 31, v140
	v_mad_i64_i32 v[150:151], s[6:7], v142, s73, 0
	v_lshl_add_u64 v[146:147], v[150:151], 1, s[34:35]
	v_lshlrev_b64 v[142:143], 1, v[140:141]
	v_lshl_add_u64 v[146:147], v[146:147], 0, v[142:143]
	v_add_co_u32_e32 v148, vcc, 0x1000, v146
	s_nop 1
	v_addc_co_u32_e32 v149, vcc, 0, v147, vcc
	v_subrev_u32_e32 v197, s34, v146
	v_add_u32_e32 v198, 0x1200, v197
	global_load_dwordx4 v[200:203], v198, s[34:35]
	v_add_u32_e32 v198, 0x0, v197
	global_load_dwordx4 v[204:207], v198, s[34:35]
	v_add_u32_e32 v198, 0x1300, v197
	global_load_dwordx4 v[208:211], v198, s[34:35]
	v_add_u32_e32 v198, 0x100, v197
	global_load_dwordx4 v[212:215], v198, s[34:35]
	v_add_u32_e32 v198, 0x23200, v197
	global_load_dwordx4 v[232:235], v198, s[34:35]
	v_add_u32_e32 v198, 0x22000, v197
	global_load_dwordx4 v[236:239], v198, s[34:35]
	s_waitcnt vmcnt(4)
	v_mov_b32_e32 v160, v200
	v_mov_b32_e32 v161, v201
	v_mov_b32_e32 v162, v202
	v_mov_b32_e32 v163, v203
	v_mov_b32_e32 v170, v204
	v_mov_b32_e32 v171, v205
	v_mov_b32_e32 v172, v206
	v_mov_b32_e32 v173, v207
	v_add_u32_e32 v198, 0x23300, v197
	global_load_dwordx4 v[200:203], v198, s[34:35]
	v_add_u32_e32 v198, 0x22100, v197
	global_load_dwordx4 v[204:207], v198, s[34:35]
	s_mov_b32 s100, 0xbfb8aa3b
	v_lshlrev_b32_e32 v242, 16, v160
	v_and_b32_e32 v243, 0xffff0000, v160
	v_lshlrev_b32_e32 v244, 16, v162
	v_and_b32_e32 v245, 0xffff0000, v162
	v_lshlrev_b32_e32 v246, 16, v161
	v_and_b32_e32 v247, 0xffff0000, v161
	v_lshlrev_b32_e32 v248, 16, v163
	v_and_b32_e32 v249, 0xffff0000, v163
	v_pk_mul_f32 v[242:243], v[242:243], s[100:101] op_sel_hi:[1,0]
	v_pk_mul_f32 v[244:245], v[244:245], s[100:101] op_sel_hi:[1,0]
	v_pk_mul_f32 v[246:247], v[246:247], s[100:101] op_sel_hi:[1,0]
	v_pk_mul_f32 v[248:249], v[248:249], s[100:101] op_sel_hi:[1,0]
	v_exp_f32_e32 v242, v242
	v_exp_f32_e32 v243, v243
	v_exp_f32_e32 v244, v244
	v_exp_f32_e32 v245, v245
	v_exp_f32_e32 v246, v246
	v_exp_f32_e32 v247, v247
	v_exp_f32_e32 v248, v248
	v_exp_f32_e32 v249, v249
	s_nop 0
	v_pk_add_f32 v[242:243], v[242:243], 1.0 op_sel_hi:[1,0]
	v_pk_add_f32 v[244:245], v[244:245], 1.0 op_sel_hi:[1,0]
	v_pk_add_f32 v[246:247], v[246:247], 1.0 op_sel_hi:[1,0]
	v_pk_add_f32 v[248:249], v[248:249], 1.0 op_sel_hi:[1,0]
	v_rcp_f32_e32 v250, v242
	v_rcp_f32_e32 v251, v243
	s_nop 0
	v_pk_fma_f32 v[252:253], v[242:243], v[250:251], 1.0 op_sel_hi:[1,1,0] neg_lo:[1,0,0] neg_hi:[1,0,0]
	v_pk_fma_f32 v[250:251], v[252:253], v[250:251], v[250:251]
	v_pk_fma_f32 v[252:253], v[242:243], v[250:251], 1.0 op_sel_hi:[1,1,0] neg_lo:[1,0,0] neg_hi:[1,0,0]
	v_pk_fma_f32 v[254:255], v[252:253], v[250:251], v[250:251]
; __device__ __forceinline__ float sigmoidf_(float x) { return 1.0f / (1.0f + __expf(-x)); }
; __device__ __forceinline__ u32x4 pack8(const f32x4 v0, const f32x4 v1) { u32x4 w; w.x = pk2(v0[0], v0[1]); w.y = pk2(v0[2], v0[3]); w.z = pk2(v1[0], v1[1]); w.w = pk2(v1[2], v1[3]); return w; }
; __device__ __forceinline__ void unpack8(const u32x4 w, f32x4& v0, f32x4& v1) { v0 = (f32x4){bflo(w.x), bfhi(w.x), bflo(w.y), bfhi(w.y)}; v1 = (f32x4){bflo(w.z), bfhi(w.z), bflo(w.w), bfhi(w.w)}; }
;     __device__ __forceinline__ void operator()(const f32x4 (&acc)[2][2][4][2], const Unit& u, int wr, int wc, int fr, int fq) const {
;     ...
;                 const int row = row0 + ai * 128 + m * 16;
;                 const bf16_t* rowp = z + (size_t)row * DIN + col0;
; #pragma unroll
;                 for (int bj = 0; bj < 2; ++bj) {
;                     const u32x4 gw = *(const u32x4*)(rowp + O_GA + bj * 128);
;                     f32x4 g0, g1; unpack8(gw, g0, g1);
;                     f32x4 v0, v1;
; #pragma unroll
;                     for (int j = 0; j < 4; ++j) { v0[j] = sigmoidf_(g0[j]) * acc[ai][bj][m][0][j]; v1[j] = sigmoidf_(g1[j]) * acc[ai][bj][m][1][j]; }
;                     const u32x4 mw = *(const u32x4*)(rowp + bj * 128); f32x4 m0, m1; unpack8(mw, m0, m1); v0 += m0; v1 += m1;
;                     __builtin_amdgcn_raw_buffer_store_b128(pack8(v0, v1), rsrc, (unsigned)(((size_t)row * DIN + col0 + bj * 128) * 2), 0, 16  ); }
	v_pk_fma_f32 v[252:253], v[242:243], v[254:255], 1.0 op_sel_hi:[1,1,0] neg_lo:[1,0,0] neg_hi:[1,0,0]
	v_pk_fma_f32 v[254:255], v[252:253], v[250:251], v[254:255]
	v_div_fixup_f32 v242, v254, v242, 1.0
	v_div_fixup_f32 v243, v255, v243, 1.0
	v_rcp_f32_e32 v250, v244
	v_rcp_f32_e32 v251, v245
	s_nop 0
	v_pk_fma_f32 v[252:253], v[244:245], v[250:251], 1.0 op_sel_hi:[1,1,0] neg_lo:[1,0,0] neg_hi:[1,0,0]
	v_pk_fma_f32 v[250:251], v[252:253], v[250:251], v[250:251]
	v_pk_fma_f32 v[252:253], v[244:245], v[250:251], 1.0 op_sel_hi:[1,1,0] neg_lo:[1,0,0] neg_hi:[1,0,0]
	v_pk_fma_f32 v[254:255], v[252:253], v[250:251], v[250:251]
	v_pk_fma_f32 v[252:253], v[244:245], v[254:255], 1.0 op_sel_hi:[1,1,0] neg_lo:[1,0,0] neg_hi:[1,0,0]
	v_pk_fma_f32 v[254:255], v[252:253], v[250:251], v[254:255]
	v_div_fixup_f32 v244, v254, v244, 1.0
	v_div_fixup_f32 v245, v255, v245, 1.0
	v_rcp_f32_e32 v250, v246
	v_rcp_f32_e32 v251, v247
	s_nop 0
	v_pk_fma_f32 v[252:253], v[246:247], v[250:251], 1.0 op_sel_hi:[1,1,0] neg_lo:[1,0,0] neg_hi:[1,0,0]
	v_pk_fma_f32 v[250:251], v[252:253], v[250:251], v[250:251]
	v_pk_fma_f32 v[252:253], v[246:247], v[250:251], 1.0 op_sel_hi:[1,1,0] neg_lo:[1,0,0] neg_hi:[1,0,0]
	v_pk_fma_f32 v[254:255], v[252:253], v[250:251], v[250:251]
	v_pk_fma_f32 v[252:253], v[246:247], v[254:255], 1.0 op_sel_hi:[1,1,0] neg_lo:[1,0,0] neg_hi:[1,0,0]
	v_pk_fma_f32 v[254:255], v[252:253], v[250:251], v[254:255]
	v_div_fixup_f32 v246, v254, v246, 1.0
	v_div_fixup_f32 v247, v255, v247, 1.0
	v_rcp_f32_e32 v250, v248
	v_rcp_f32_e32 v251, v249
	s_nop 0
	v_pk_fma_f32 v[252:253], v[248:249], v[250:251], 1.0 op_sel_hi:[1,1,0] neg_lo:[1,0,0] neg_hi:[1,0,0]
	v_pk_fma_f32 v[250:251], v[252:253], v[250:251], v[250:251]
	v_pk_fma_f32 v[252:253], v[248:249], v[250:251], 1.0 op_sel_hi:[1,1,0] neg_lo:[1,0,0] neg_hi:[1,0,0]
	v_pk_fma_f32 v[254:255], v[252:253], v[250:251], v[250:251]
	v_pk_fma_f32 v[252:253], v[248:249], v[254:255], 1.0 op_sel_hi:[1,1,0] neg_lo:[1,0,0] neg_hi:[1,0,0]
	v_pk_fma_f32 v[254:255], v[252:253], v[250:251], v[254:255]
	v_div_fixup_f32 v248, v254, v248, 1.0
	v_div_fixup_f32 v249, v255, v249, 1.0
	s_mov_b64 vcc, s[10:11]
	s_mov_b64 vcc, s[12:13]
	s_mov_b64 vcc, s[14:15]
	s_mov_b64 vcc, s[16:17]
	v_and_b32_e32 v177, 0xffff0000, v170
	v_lshlrev_b32_e32 v178, 16, v172
	v_lshlrev_b32_e32 v176, 16, v170
	v_and_b32_e32 v179, 0xffff0000, v172
	v_lshlrev_b32_e32 v172, 16, v173
	v_and_b32_e32 v173, 0xffff0000, v173
	v_lshlrev_b32_e32 v170, 16, v171
	v_and_b32_e32 v171, 0xffff0000, v171
	v_pk_fma_f32 v[124:125], v[124:125], v[242:243], v[176:177]
	v_pk_fma_f32 v[160:161], v[122:123], v[248:249], v[172:173]
	v_pk_fma_f32 v[122:123], v[120:121], v[244:245], v[178:179]
	v_add_lshl_u32 v141, v140, v150, 1
	v_pk_fma_f32 v[126:127], v[126:127], v[246:247], v[170:171]
	v_cvt_pk_bf16_f32 v120, v124, v125
	s_nop 0
	v_cvt_pk_bf16_f32 v121, v126, v127
	v_cvt_pk_bf16_f32 v122, v122, v123
	v_cvt_pk_bf16_f32 v123, v160, v161
	buffer_store_dwordx4 v[120:123], v141, s[20:23], 0 offen sc1
	s_nop 0
	s_waitcnt vmcnt(5)
	v_mov_b32_e32 v120, v208
	v_mov_b32_e32 v121, v209
	v_mov_b32_e32 v122, v210
	v_mov_b32_e32 v123, v211
	v_mov_b32_e32 v124, v212
	v_mov_b32_e32 v125, v213
	v_mov_b32_e32 v126, v214
	v_mov_b32_e32 v127, v215
	v_add_u32_e32 v198, 0x45200, v197
	global_load_dwordx4 v[208:211], v198, s[34:35]
	v_add_u32_e32 v198, 0x44000, v197
	global_load_dwordx4 v[212:215], v198, s[34:35]
	s_mov_b32 s100, 0xbfb8aa3b
	v_lshlrev_b32_e32 v242, 16, v120
	v_and_b32_e32 v243, 0xffff0000, v120
	v_lshlrev_b32_e32 v244, 16, v122
	v_and_b32_e32 v245, 0xffff0000, v122
	v_lshlrev_b32_e32 v246, 16, v121
	v_and_b32_e32 v247, 0xffff0000, v121
	v_lshlrev_b32_e32 v248, 16, v123
	v_and_b32_e32 v249, 0xffff0000, v123
	v_pk_mul_f32 v[242:243], v[242:243], s[100:101] op_sel_hi:[1,0]
	v_pk_mul_f32 v[244:245], v[244:245], s[100:101] op_sel_hi:[1,0]
	v_pk_mul_f32 v[246:247], v[246:247], s[100:101] op_sel_hi:[1,0]
	v_pk_mul_f32 v[248:249], v[248:249], s[100:101] op_sel_hi:[1,0]
	v_exp_f32_e32 v242, v242
	v_exp_f32_e32 v243, v243
	v_exp_f32_e32 v244, v244
	v_exp_f32_e32 v245, v245
	v_exp_f32_e32 v246, v246
	v_exp_f32_e32 v247, v247
	v_exp_f32_e32 v248, v248
	v_exp_f32_e32 v249, v249
	s_nop 0
	v_pk_add_f32 v[242:243], v[242:243], 1.0 op_sel_hi:[1,0]
	v_pk_add_f32 v[244:245], v[244:245], 1.0 op_sel_hi:[1,0]
	v_pk_add_f32 v[246:247], v[246:247], 1.0 op_sel_hi:[1,0]
	v_pk_add_f32 v[248:249], v[248:249], 1.0 op_sel_hi:[1,0]
	v_rcp_f32_e32 v250, v242
	v_rcp_f32_e32 v251, v243
	s_nop 0
	v_pk_fma_f32 v[252:253], v[242:243], v[250:251], 1.0 op_sel_hi:[1,1,0] neg_lo:[1,0,0] neg_hi:[1,0,0]
	v_pk_fma_f32 v[250:251], v[252:253], v[250:251], v[250:251]
	v_pk_fma_f32 v[252:253], v[242:243], v[250:251], 1.0 op_sel_hi:[1,1,0] neg_lo:[1,0,0] neg_hi:[1,0,0]
	v_pk_fma_f32 v[254:255], v[252:253], v[250:251], v[250:251]
	v_pk_fma_f32 v[252:253], v[242:243], v[254:255], 1.0 op_sel_hi:[1,1,0] neg_lo:[1,0,0] neg_hi:[1,0,0]
	v_pk_fma_f32 v[254:255], v[252:253], v[250:251], v[254:255]
	v_div_fixup_f32 v242, v254, v242, 1.0
	v_div_fixup_f32 v243, v255, v243, 1.0
	v_rcp_f32_e32 v250, v244
	v_rcp_f32_e32 v251, v245
	s_nop 0
	v_pk_fma_f32 v[252:253], v[244:245], v[250:251], 1.0 op_sel_hi:[1,1,0] neg_lo:[1,0,0] neg_hi:[1,0,0]
	v_pk_fma_f32 v[250:251], v[252:253], v[250:251], v[250:251]
	v_pk_fma_f32 v[252:253], v[244:245], v[250:251], 1.0 op_sel_hi:[1,1,0] neg_lo:[1,0,0] neg_hi:[1,0,0]
	v_pk_fma_f32 v[254:255], v[252:253], v[250:251], v[250:251]
	v_pk_fma_f32 v[252:253], v[244:245], v[254:255], 1.0 op_sel_hi:[1,1,0] neg_lo:[1,0,0] neg_hi:[1,0,0]
	v_pk_fma_f32 v[254:255], v[252:253], v[250:251], v[254:255]
	v_div_fixup_f32 v244, v254, v244, 1.0
; __device__ __forceinline__ float sigmoidf_(float x) { return 1.0f / (1.0f + __expf(-x)); }
; __device__ __forceinline__ u32x4 pack8(const f32x4 v0, const f32x4 v1) { u32x4 w; w.x = pk2(v0[0], v0[1]); w.y = pk2(v0[2], v0[3]); w.z = pk2(v1[0], v1[1]); w.w = pk2(v1[2], v1[3]); return w; }
; __device__ __forceinline__ void unpack8(const u32x4 w, f32x4& v0, f32x4& v1) { v0 = (f32x4){bflo(w.x), bfhi(w.x), bflo(w.y), bfhi(w.y)}; v1 = (f32x4){bflo(w.z), bfhi(w.z), bflo(w.w), bfhi(w.w)}; }
;     __device__ __forceinline__ void operator()(const f32x4 (&acc)[2][2][4][2], const Unit& u, int wr, int wc, int fr, int fq) const {
;     ...
;                 const int row = row0 + ai * 128 + m * 16;
;                 const bf16_t* rowp = z + (size_t)row * DIN + col0;
; #pragma unroll
;                 for (int bj = 0; bj < 2; ++bj) {
;                     const u32x4 gw = *(const u32x4*)(rowp + O_GA + bj * 128);
;                     f32x4 g0, g1; unpack8(gw, g0, g1);
;                     f32x4 v0, v1;
; #pragma unroll
;                     for (int j = 0; j < 4; ++j) { v0[j] = sigmoidf_(g0[j]) * acc[ai][bj][m][0][j]; v1[j] = sigmoidf_(g1[j]) * acc[ai][bj][m][1][j]; }
;                     const u32x4 mw = *(const u32x4*)(rowp + bj * 128); f32x4 m0, m1; unpack8(mw, m0, m1); v0 += m0; v1 += m1;
;                     __builtin_amdgcn_raw_buffer_store_b128(pack8(v0, v1), rsrc, (unsigned)(((size_t)row * DIN + col0 + bj * 128) * 2), 0, 16  ); }
	v_div_fixup_f32 v245, v255, v245, 1.0
	v_rcp_f32_e32 v250, v246
	v_rcp_f32_e32 v251, v247
	s_nop 0
	v_pk_fma_f32 v[252:253], v[246:247], v[250:251], 1.0 op_sel_hi:[1,1,0] neg_lo:[1,0,0] neg_hi:[1,0,0]
	v_pk_fma_f32 v[250:251], v[252:253], v[250:251], v[250:251]
	v_pk_fma_f32 v[252:253], v[246:247], v[250:251], 1.0 op_sel_hi:[1,1,0] neg_lo:[1,0,0] neg_hi:[1,0,0]
	v_pk_fma_f32 v[254:255], v[252:253], v[250:251], v[250:251]
	v_pk_fma_f32 v[252:253], v[246:247], v[254:255], 1.0 op_sel_hi:[1,1,0] neg_lo:[1,0,0] neg_hi:[1,0,0]
	v_pk_fma_f32 v[254:255], v[252:253], v[250:251], v[254:255]
	v_div_fixup_f32 v246, v254, v246, 1.0
	v_div_fixup_f32 v247, v255, v247, 1.0
	v_rcp_f32_e32 v250, v248
	v_rcp_f32_e32 v251, v249
	s_nop 0
	v_pk_fma_f32 v[252:253], v[248:249], v[250:251], 1.0 op_sel_hi:[1,1,0] neg_lo:[1,0,0] neg_hi:[1,0,0]
	v_pk_fma_f32 v[250:251], v[252:253], v[250:251], v[250:251]
	v_pk_fma_f32 v[252:253], v[248:249], v[250:251], 1.0 op_sel_hi:[1,1,0] neg_lo:[1,0,0] neg_hi:[1,0,0]
	v_pk_fma_f32 v[254:255], v[252:253], v[250:251], v[250:251]
	v_pk_fma_f32 v[252:253], v[248:249], v[254:255], 1.0 op_sel_hi:[1,1,0] neg_lo:[1,0,0] neg_hi:[1,0,0]
	v_pk_fma_f32 v[254:255], v[252:253], v[250:251], v[254:255]
	v_div_fixup_f32 v248, v254, v248, 1.0
	v_div_fixup_f32 v249, v255, v249, 1.0
	v_lshlrev_b32_e32 v150, 16, v124
	v_and_b32_e32 v151, 0xffff0000, v124
	v_lshlrev_b32_e32 v160, 16, v126
	v_and_b32_e32 v161, 0xffff0000, v126
	v_lshlrev_b32_e32 v126, 16, v127
	v_and_b32_e32 v127, 0xffff0000, v127
	v_lshlrev_b32_e32 v124, 16, v125
	v_and_b32_e32 v125, 0xffff0000, v125
	v_pk_fma_f32 v[116:117], v[116:117], v[242:243], v[150:151]
	v_pk_fma_f32 v[120:121], v[114:115], v[248:249], v[126:127]
	v_pk_fma_f32 v[114:115], v[112:113], v[244:245], v[160:161]
	v_cvt_pk_bf16_f32 v112, v116, v117
	v_pk_fma_f32 v[118:119], v[118:119], v[246:247], v[124:125]
	s_nop 0
	v_cvt_pk_bf16_f32 v113, v118, v119
	v_cvt_pk_bf16_f32 v114, v114, v115
	v_cvt_pk_bf16_f32 v115, v120, v121
	buffer_store_dwordx4 v[112:115], v141, s[20:23], 0 offen offset:256 sc1
	s_nop 1
	v_add_u32_e32 v112, 0x4010, v158
	v_mad_i64_i32 v[114:115], s[6:7], v112, s73, 0
	v_lshl_add_u64 v[112:113], v[114:115], 1, s[34:35]
	v_lshl_add_u64 v[112:113], v[112:113], 0, v[142:143]
	v_add_co_u32_e32 v116, vcc, s74, v112
	s_nop 1
	v_addc_co_u32_e32 v117, vcc, 0, v113, vcc
	s_waitcnt vmcnt(6)
	v_mov_b32_e32 v118, v232
	v_mov_b32_e32 v119, v233
	v_mov_b32_e32 v120, v234
	v_mov_b32_e32 v121, v235
	v_mov_b32_e32 v122, v236
	v_mov_b32_e32 v123, v237
	v_mov_b32_e32 v124, v238
	v_mov_b32_e32 v125, v239
	v_add_u32_e32 v198, 0x45300, v197
	global_load_dwordx4 v[232:235], v198, s[34:35]
	v_add_u32_e32 v198, 0x44100, v197
	global_load_dwordx4 v[236:239], v198, s[34:35]
	s_mov_b32 s100, 0xbfb8aa3b
	v_lshlrev_b32_e32 v242, 16, v118
	v_and_b32_e32 v243, 0xffff0000, v118
	v_lshlrev_b32_e32 v244, 16, v120
	v_and_b32_e32 v245, 0xffff0000, v120
	v_lshlrev_b32_e32 v246, 16, v119
	v_and_b32_e32 v247, 0xffff0000, v119
	v_lshlrev_b32_e32 v248, 16, v121
	v_and_b32_e32 v249, 0xffff0000, v121
	v_pk_mul_f32 v[242:243], v[242:243], s[100:101] op_sel_hi:[1,0]
	v_pk_mul_f32 v[244:245], v[244:245], s[100:101] op_sel_hi:[1,0]
	v_pk_mul_f32 v[246:247], v[246:247], s[100:101] op_sel_hi:[1,0]
	v_pk_mul_f32 v[248:249], v[248:249], s[100:101] op_sel_hi:[1,0]
	v_exp_f32_e32 v242, v242
	v_exp_f32_e32 v243, v243
	v_exp_f32_e32 v244, v244
	v_exp_f32_e32 v245, v245
	v_exp_f32_e32 v246, v246
	v_exp_f32_e32 v247, v247
	v_exp_f32_e32 v248, v248
	v_exp_f32_e32 v249, v249
	s_nop 0
	v_pk_add_f32 v[242:243], v[242:243], 1.0 op_sel_hi:[1,0]
	v_pk_add_f32 v[244:245], v[244:245], 1.0 op_sel_hi:[1,0]
	v_pk_add_f32 v[246:247], v[246:247], 1.0 op_sel_hi:[1,0]
	v_pk_add_f32 v[248:249], v[248:249], 1.0 op_sel_hi:[1,0]
	v_rcp_f32_e32 v250, v242
	v_rcp_f32_e32 v251, v243
	s_nop 0
	v_pk_fma_f32 v[252:253], v[242:243], v[250:251], 1.0 op_sel_hi:[1,1,0] neg_lo:[1,0,0] neg_hi:[1,0,0]
	v_pk_fma_f32 v[250:251], v[252:253], v[250:251], v[250:251]
	v_pk_fma_f32 v[252:253], v[242:243], v[250:251], 1.0 op_sel_hi:[1,1,0] neg_lo:[1,0,0] neg_hi:[1,0,0]
	v_pk_fma_f32 v[254:255], v[252:253], v[250:251], v[250:251]
	v_pk_fma_f32 v[252:253], v[242:243], v[254:255], 1.0 op_sel_hi:[1,1,0] neg_lo:[1,0,0] neg_hi:[1,0,0]
	v_pk_fma_f32 v[254:255], v[252:253], v[250:251], v[254:255]
	v_div_fixup_f32 v242, v254, v242, 1.0
	v_div_fixup_f32 v243, v255, v243, 1.0
	v_rcp_f32_e32 v250, v244
	v_rcp_f32_e32 v251, v245
	s_nop 0
	v_pk_fma_f32 v[252:253], v[244:245], v[250:251], 1.0 op_sel_hi:[1,1,0] neg_lo:[1,0,0] neg_hi:[1,0,0]
	v_pk_fma_f32 v[250:251], v[252:253], v[250:251], v[250:251]
	v_pk_fma_f32 v[252:253], v[244:245], v[250:251], 1.0 op_sel_hi:[1,1,0] neg_lo:[1,0,0] neg_hi:[1,0,0]
	v_pk_fma_f32 v[254:255], v[252:253], v[250:251], v[250:251]
	v_pk_fma_f32 v[252:253], v[244:245], v[254:255], 1.0 op_sel_hi:[1,1,0] neg_lo:[1,0,0] neg_hi:[1,0,0]
	v_pk_fma_f32 v[254:255], v[252:253], v[250:251], v[254:255]
	v_div_fixup_f32 v244, v254, v244, 1.0
	v_div_fixup_f32 v245, v255, v245, 1.0
	v_rcp_f32_e32 v250, v246
	v_rcp_f32_e32 v251, v247
	s_nop 0
	v_pk_fma_f32 v[252:253], v[246:247], v[250:251], 1.0 op_sel_hi:[1,1,0] neg_lo:[1,0,0] neg_hi:[1,0,0]
	v_pk_fma_f32 v[250:251], v[252:253], v[250:251], v[250:251]
	v_pk_fma_f32 v[252:253], v[246:247], v[250:251], 1.0 op_sel_hi:[1,1,0] neg_lo:[1,0,0] neg_hi:[1,0,0]
	v_pk_fma_f32 v[254:255], v[252:253], v[250:251], v[250:251]
	v_pk_fma_f32 v[252:253], v[246:247], v[254:255], 1.0 op_sel_hi:[1,1,0] neg_lo:[1,0,0] neg_hi:[1,0,0]
	v_pk_fma_f32 v[254:255], v[252:253], v[250:251], v[254:255]
	v_div_fixup_f32 v246, v254, v246, 1.0
	v_div_fixup_f32 v247, v255, v247, 1.0
; __device__ __forceinline__ float sigmoidf_(float x) { return 1.0f / (1.0f + __expf(-x)); }
; __device__ __forceinline__ u32x4 pack8(const f32x4 v0, const f32x4 v1) { u32x4 w; w.x = pk2(v0[0], v0[1]); w.y = pk2(v0[2], v0[3]); w.z = pk2(v1[0], v1[1]); w.w = pk2(v1[2], v1[3]); return w; }
; __device__ __forceinline__ void unpack8(const u32x4 w, f32x4& v0, f32x4& v1) { v0 = (f32x4){bflo(w.x), bfhi(w.x), bflo(w.y), bfhi(w.y)}; v1 = (f32x4){bflo(w.z), bfhi(w.z), bflo(w.w), bfhi(w.w)}; }
;     __device__ __forceinline__ void operator()(const f32x4 (&acc)[2][2][4][2], const Unit& u, int wr, int wc, int fr, int fq) const {
;     ...
;                 const int row = row0 + ai * 128 + m * 16;
;                 const bf16_t* rowp = z + (size_t)row * DIN + col0;
; #pragma unroll
;                 for (int bj = 0; bj < 2; ++bj) {
;                     const u32x4 gw = *(const u32x4*)(rowp + O_GA + bj * 128);
;                     f32x4 g0, g1; unpack8(gw, g0, g1);
;                     f32x4 v0, v1;
; #pragma unroll
;                     for (int j = 0; j < 4; ++j) { v0[j] = sigmoidf_(g0[j]) * acc[ai][bj][m][0][j]; v1[j] = sigmoidf_(g1[j]) * acc[ai][bj][m][1][j]; }
;                     const u32x4 mw = *(const u32x4*)(rowp + bj * 128); f32x4 m0, m1; unpack8(mw, m0, m1); v0 += m0; v1 += m1;
;                     __builtin_amdgcn_raw_buffer_store_b128(pack8(v0, v1), rsrc, (unsigned)(((size_t)row * DIN + col0 + bj * 128) * 2), 0, 16  ); }
	v_rcp_f32_e32 v250, v248
	v_rcp_f32_e32 v251, v249
	s_nop 0
	v_pk_fma_f32 v[252:253], v[248:249], v[250:251], 1.0 op_sel_hi:[1,1,0] neg_lo:[1,0,0] neg_hi:[1,0,0]
	v_pk_fma_f32 v[250:251], v[252:253], v[250:251], v[250:251]
	v_pk_fma_f32 v[252:253], v[248:249], v[250:251], 1.0 op_sel_hi:[1,1,0] neg_lo:[1,0,0] neg_hi:[1,0,0]
	v_pk_fma_f32 v[254:255], v[252:253], v[250:251], v[250:251]
	v_pk_fma_f32 v[252:253], v[248:249], v[254:255], 1.0 op_sel_hi:[1,1,0] neg_lo:[1,0,0] neg_hi:[1,0,0]
	v_pk_fma_f32 v[254:255], v[252:253], v[250:251], v[254:255]
	v_div_fixup_f32 v248, v254, v248, 1.0
	v_div_fixup_f32 v249, v255, v249, 1.0
	v_and_b32_e32 v151, 0xffff0000, v124
	v_lshlrev_b32_e32 v148, 16, v122
	v_and_b32_e32 v149, 0xffff0000, v122
	v_lshlrev_b32_e32 v150, 16, v124
	v_lshlrev_b32_e32 v124, 16, v125
	v_and_b32_e32 v125, 0xffff0000, v125
	v_lshlrev_b32_e32 v122, 16, v123
	v_and_b32_e32 v123, 0xffff0000, v123
	v_pk_fma_f32 v[108:109], v[108:109], v[242:243], v[148:149]
	v_pk_fma_f32 v[118:119], v[106:107], v[248:249], v[124:125]
	v_pk_fma_f32 v[106:107], v[104:105], v[244:245], v[150:151]
	v_add_lshl_u32 v120, v140, v114, 1
	v_pk_fma_f32 v[110:111], v[110:111], v[246:247], v[122:123]
	v_cvt_pk_bf16_f32 v104, v108, v109
	s_nop 0
	v_cvt_pk_bf16_f32 v105, v110, v111
	v_cvt_pk_bf16_f32 v106, v106, v107
	v_cvt_pk_bf16_f32 v107, v118, v119
	buffer_store_dwordx4 v[104:107], v120, s[20:23], 0 offen sc1
	s_nop 0
	s_waitcnt vmcnt(7)
	v_mov_b32_e32 v104, v200
	v_mov_b32_e32 v105, v201
	v_mov_b32_e32 v106, v202
	v_mov_b32_e32 v107, v203
	v_mov_b32_e32 v108, v204
	v_mov_b32_e32 v109, v205
	v_mov_b32_e32 v110, v206
	v_mov_b32_e32 v111, v207
	v_add_u32_e32 v198, 0x67200, v197
	global_load_dwordx4 v[200:203], v198, s[34:35]
	v_add_u32_e32 v198, 0x66000, v197
	global_load_dwordx4 v[204:207], v198, s[34:35]
	s_mov_b32 s100, 0xbfb8aa3b
	v_lshlrev_b32_e32 v242, 16, v106
	v_and_b32_e32 v243, 0xffff0000, v106
	v_lshlrev_b32_e32 v244, 16, v104
	v_and_b32_e32 v245, 0xffff0000, v104
	v_lshlrev_b32_e32 v246, 16, v105
	v_and_b32_e32 v247, 0xffff0000, v105
	v_lshlrev_b32_e32 v248, 16, v107
	v_and_b32_e32 v249, 0xffff0000, v107
	v_pk_mul_f32 v[242:243], v[242:243], s[100:101] op_sel_hi:[1,0]
	v_pk_mul_f32 v[244:245], v[244:245], s[100:101] op_sel_hi:[1,0]
	v_pk_mul_f32 v[246:247], v[246:247], s[100:101] op_sel_hi:[1,0]
	v_pk_mul_f32 v[248:249], v[248:249], s[100:101] op_sel_hi:[1,0]
	v_exp_f32_e32 v242, v242
	v_exp_f32_e32 v243, v243
	v_exp_f32_e32 v244, v244
	v_exp_f32_e32 v245, v245
	v_exp_f32_e32 v246, v246
	v_exp_f32_e32 v247, v247
	v_exp_f32_e32 v248, v248
	v_exp_f32_e32 v249, v249
	s_nop 0
	v_pk_add_f32 v[242:243], v[242:243], 1.0 op_sel_hi:[1,0]
	v_pk_add_f32 v[244:245], v[244:245], 1.0 op_sel_hi:[1,0]
	v_pk_add_f32 v[246:247], v[246:247], 1.0 op_sel_hi:[1,0]
	v_pk_add_f32 v[248:249], v[248:249], 1.0 op_sel_hi:[1,0]
	v_rcp_f32_e32 v250, v242
	v_rcp_f32_e32 v251, v243
	s_nop 0
	v_pk_fma_f32 v[252:253], v[242:243], v[250:251], 1.0 op_sel_hi:[1,1,0] neg_lo:[1,0,0] neg_hi:[1,0,0]
	v_pk_fma_f32 v[250:251], v[252:253], v[250:251], v[250:251]
	v_pk_fma_f32 v[252:253], v[242:243], v[250:251], 1.0 op_sel_hi:[1,1,0] neg_lo:[1,0,0] neg_hi:[1,0,0]
	v_pk_fma_f32 v[254:255], v[252:253], v[250:251], v[250:251]
	v_pk_fma_f32 v[252:253], v[242:243], v[254:255], 1.0 op_sel_hi:[1,1,0] neg_lo:[1,0,0] neg_hi:[1,0,0]
	v_pk_fma_f32 v[254:255], v[252:253], v[250:251], v[254:255]
	v_div_fixup_f32 v242, v254, v242, 1.0
	v_div_fixup_f32 v243, v255, v243, 1.0
	v_rcp_f32_e32 v250, v244
	v_rcp_f32_e32 v251, v245
	s_nop 0
	v_pk_fma_f32 v[252:253], v[244:245], v[250:251], 1.0 op_sel_hi:[1,1,0] neg_lo:[1,0,0] neg_hi:[1,0,0]
	v_pk_fma_f32 v[250:251], v[252:253], v[250:251], v[250:251]
	v_pk_fma_f32 v[252:253], v[244:245], v[250:251], 1.0 op_sel_hi:[1,1,0] neg_lo:[1,0,0] neg_hi:[1,0,0]
	v_pk_fma_f32 v[254:255], v[252:253], v[250:251], v[250:251]
	v_pk_fma_f32 v[252:253], v[244:245], v[254:255], 1.0 op_sel_hi:[1,1,0] neg_lo:[1,0,0] neg_hi:[1,0,0]
	v_pk_fma_f32 v[254:255], v[252:253], v[250:251], v[254:255]
	v_div_fixup_f32 v244, v254, v244, 1.0
	v_div_fixup_f32 v245, v255, v245, 1.0
	v_rcp_f32_e32 v250, v246
	v_rcp_f32_e32 v251, v247
	s_nop 0
	v_pk_fma_f32 v[252:253], v[246:247], v[250:251], 1.0 op_sel_hi:[1,1,0] neg_lo:[1,0,0] neg_hi:[1,0,0]
	v_pk_fma_f32 v[250:251], v[252:253], v[250:251], v[250:251]
	v_pk_fma_f32 v[252:253], v[246:247], v[250:251], 1.0 op_sel_hi:[1,1,0] neg_lo:[1,0,0] neg_hi:[1,0,0]
	v_pk_fma_f32 v[254:255], v[252:253], v[250:251], v[250:251]
	v_pk_fma_f32 v[252:253], v[246:247], v[254:255], 1.0 op_sel_hi:[1,1,0] neg_lo:[1,0,0] neg_hi:[1,0,0]
	v_pk_fma_f32 v[254:255], v[252:253], v[250:251], v[254:255]
	v_div_fixup_f32 v246, v254, v246, 1.0
	v_div_fixup_f32 v247, v255, v247, 1.0
	v_rcp_f32_e32 v250, v248
	v_rcp_f32_e32 v251, v249
	s_nop 0
	v_pk_fma_f32 v[252:253], v[248:249], v[250:251], 1.0 op_sel_hi:[1,1,0] neg_lo:[1,0,0] neg_hi:[1,0,0]
	v_pk_fma_f32 v[250:251], v[252:253], v[250:251], v[250:251]
	v_pk_fma_f32 v[252:253], v[248:249], v[250:251], 1.0 op_sel_hi:[1,1,0] neg_lo:[1,0,0] neg_hi:[1,0,0]
	v_pk_fma_f32 v[254:255], v[252:253], v[250:251], v[250:251]
	v_pk_fma_f32 v[252:253], v[248:249], v[254:255], 1.0 op_sel_hi:[1,1,0] neg_lo:[1,0,0] neg_hi:[1,0,0]
	v_pk_fma_f32 v[254:255], v[252:253], v[250:251], v[254:255]
	v_div_fixup_f32 v248, v254, v248, 1.0
	v_div_fixup_f32 v249, v255, v249, 1.0
	v_lshlrev_b32_e32 v116, 16, v108
	v_and_b32_e32 v117, 0xffff0000, v108
	v_lshlrev_b32_e32 v118, 16, v110
	v_and_b32_e32 v119, 0xffff0000, v110
	v_lshlrev_b32_e32 v110, 16, v111
	v_and_b32_e32 v111, 0xffff0000, v111
	v_lshlrev_b32_e32 v108, 16, v109
	v_and_b32_e32 v109, 0xffff0000, v109
	v_pk_fma_f32 v[100:101], v[100:101], v[244:245], v[116:117]
	v_pk_fma_f32 v[104:105], v[98:99], v[248:249], v[110:111]
	v_pk_fma_f32 v[98:99], v[96:97], v[242:243], v[118:119]
	v_cvt_pk_bf16_f32 v96, v100, v101
	v_pk_fma_f32 v[102:103], v[102:103], v[246:247], v[108:109]
	s_nop 0
	v_cvt_pk_bf16_f32 v97, v102, v103
	v_cvt_pk_bf16_f32 v98, v98, v99
	v_cvt_pk_bf16_f32 v99, v104, v105
	buffer_store_dwordx4 v[96:99], v120, s[20:23], 0 offen offset:256 sc1
	s_nop 1
	v_add_u32_e32 v96, 0x4020, v158
	v_mad_i64_i32 v[98:99], s[6:7], v96, s73, 0
	v_lshl_add_u64 v[96:97], v[98:99], 1, s[34:35]
	v_lshl_add_u64 v[96:97], v[96:97], 0, v[142:143]
	v_add_co_u32_e32 v100, vcc, s74, v96
	s_nop 1
	v_addc_co_u32_e32 v101, vcc, 0, v97, vcc
	s_waitcnt vmcnt(7)
; __device__ __forceinline__ float sigmoidf_(float x) { return 1.0f / (1.0f + __expf(-x)); }
; __device__ __forceinline__ u32x4 pack8(const f32x4 v0, const f32x4 v1) { u32x4 w; w.x = pk2(v0[0], v0[1]); w.y = pk2(v0[2], v0[3]); w.z = pk2(v1[0], v1[1]); w.w = pk2(v1[2], v1[3]); return w; }
; __device__ __forceinline__ void unpack8(const u32x4 w, f32x4& v0, f32x4& v1) { v0 = (f32x4){bflo(w.x), bfhi(w.x), bflo(w.y), bfhi(w.y)}; v1 = (f32x4){bflo(w.z), bfhi(w.z), bflo(w.w), bfhi(w.w)}; }
;     __device__ __forceinline__ void operator()(const f32x4 (&acc)[2][2][4][2], const Unit& u, int wr, int wc, int fr, int fq) const {
;     ...
;                 const int row = row0 + ai * 128 + m * 16;
;                 const bf16_t* rowp = z + (size_t)row * DIN + col0;
; #pragma unroll
;                 for (int bj = 0; bj < 2; ++bj) {
;                     const u32x4 gw = *(const u32x4*)(rowp + O_GA + bj * 128);
;                     f32x4 g0, g1; unpack8(gw, g0, g1);
;                     f32x4 v0, v1;
; #pragma unroll
;                     for (int j = 0; j < 4; ++j) { v0[j] = sigmoidf_(g0[j]) * acc[ai][bj][m][0][j]; v1[j] = sigmoidf_(g1[j]) * acc[ai][bj][m][1][j]; }
;                     const u32x4 mw = *(const u32x4*)(rowp + bj * 128); f32x4 m0, m1; unpack8(mw, m0, m1); v0 += m0; v1 += m1;
;                     __builtin_amdgcn_raw_buffer_store_b128(pack8(v0, v1), rsrc, (unsigned)(((size_t)row * DIN + col0 + bj * 128) * 2), 0, 16  ); }
	v_mov_b32_e32 v102, v208
	v_mov_b32_e32 v103, v209
	v_mov_b32_e32 v104, v210
	v_mov_b32_e32 v105, v211
	v_mov_b32_e32 v106, v212
	v_mov_b32_e32 v107, v213
	v_mov_b32_e32 v108, v214
	v_mov_b32_e32 v109, v215
	v_add_u32_e32 v198, 0x67300, v197
	global_load_dwordx4 v[208:211], v198, s[34:35]
	v_add_u32_e32 v198, 0x66100, v197
	global_load_dwordx4 v[212:215], v198, s[34:35]
	s_mov_b32 s100, 0xbfb8aa3b
	v_lshlrev_b32_e32 v242, 16, v102
	v_and_b32_e32 v243, 0xffff0000, v102
	v_lshlrev_b32_e32 v244, 16, v104
	v_and_b32_e32 v245, 0xffff0000, v104
	v_lshlrev_b32_e32 v246, 16, v103
	v_and_b32_e32 v247, 0xffff0000, v103
	v_lshlrev_b32_e32 v248, 16, v105
	v_and_b32_e32 v249, 0xffff0000, v105
	v_pk_mul_f32 v[242:243], v[242:243], s[100:101] op_sel_hi:[1,0]
	v_pk_mul_f32 v[244:245], v[244:245], s[100:101] op_sel_hi:[1,0]
	v_pk_mul_f32 v[246:247], v[246:247], s[100:101] op_sel_hi:[1,0]
	v_pk_mul_f32 v[248:249], v[248:249], s[100:101] op_sel_hi:[1,0]
	v_exp_f32_e32 v242, v242
	v_exp_f32_e32 v243, v243
	v_exp_f32_e32 v244, v244
	v_exp_f32_e32 v245, v245
	v_exp_f32_e32 v246, v246
	v_exp_f32_e32 v247, v247
	v_exp_f32_e32 v248, v248
	v_exp_f32_e32 v249, v249
	s_nop 0
	v_pk_add_f32 v[242:243], v[242:243], 1.0 op_sel_hi:[1,0]
	v_pk_add_f32 v[244:245], v[244:245], 1.0 op_sel_hi:[1,0]
	v_pk_add_f32 v[246:247], v[246:247], 1.0 op_sel_hi:[1,0]
	v_pk_add_f32 v[248:249], v[248:249], 1.0 op_sel_hi:[1,0]
	v_rcp_f32_e32 v250, v242
	v_rcp_f32_e32 v251, v243
	s_nop 0
	v_pk_fma_f32 v[252:253], v[242:243], v[250:251], 1.0 op_sel_hi:[1,1,0] neg_lo:[1,0,0] neg_hi:[1,0,0]
	v_pk_fma_f32 v[250:251], v[252:253], v[250:251], v[250:251]
	v_pk_fma_f32 v[252:253], v[242:243], v[250:251], 1.0 op_sel_hi:[1,1,0] neg_lo:[1,0,0] neg_hi:[1,0,0]
	v_pk_fma_f32 v[254:255], v[252:253], v[250:251], v[250:251]
	v_pk_fma_f32 v[252:253], v[242:243], v[254:255], 1.0 op_sel_hi:[1,1,0] neg_lo:[1,0,0] neg_hi:[1,0,0]
	v_pk_fma_f32 v[254:255], v[252:253], v[250:251], v[254:255]
	v_div_fixup_f32 v242, v254, v242, 1.0
	v_div_fixup_f32 v243, v255, v243, 1.0
	v_rcp_f32_e32 v250, v244
	v_rcp_f32_e32 v251, v245
	s_nop 0
	v_pk_fma_f32 v[252:253], v[244:245], v[250:251], 1.0 op_sel_hi:[1,1,0] neg_lo:[1,0,0] neg_hi:[1,0,0]
	v_pk_fma_f32 v[250:251], v[252:253], v[250:251], v[250:251]
	v_pk_fma_f32 v[252:253], v[244:245], v[250:251], 1.0 op_sel_hi:[1,1,0] neg_lo:[1,0,0] neg_hi:[1,0,0]
	v_pk_fma_f32 v[254:255], v[252:253], v[250:251], v[250:251]
	v_pk_fma_f32 v[252:253], v[244:245], v[254:255], 1.0 op_sel_hi:[1,1,0] neg_lo:[1,0,0] neg_hi:[1,0,0]
	v_pk_fma_f32 v[254:255], v[252:253], v[250:251], v[254:255]
	v_div_fixup_f32 v244, v254, v244, 1.0
	v_div_fixup_f32 v245, v255, v245, 1.0
	v_rcp_f32_e32 v250, v246
	v_rcp_f32_e32 v251, v247
	s_nop 0
	v_pk_fma_f32 v[252:253], v[246:247], v[250:251], 1.0 op_sel_hi:[1,1,0] neg_lo:[1,0,0] neg_hi:[1,0,0]
	v_pk_fma_f32 v[250:251], v[252:253], v[250:251], v[250:251]
	v_pk_fma_f32 v[252:253], v[246:247], v[250:251], 1.0 op_sel_hi:[1,1,0] neg_lo:[1,0,0] neg_hi:[1,0,0]
	v_pk_fma_f32 v[254:255], v[252:253], v[250:251], v[250:251]
	v_pk_fma_f32 v[252:253], v[246:247], v[254:255], 1.0 op_sel_hi:[1,1,0] neg_lo:[1,0,0] neg_hi:[1,0,0]
	v_pk_fma_f32 v[254:255], v[252:253], v[250:251], v[254:255]
	v_div_fixup_f32 v246, v254, v246, 1.0
	v_div_fixup_f32 v247, v255, v247, 1.0
	v_rcp_f32_e32 v250, v248
	v_rcp_f32_e32 v251, v249
	s_nop 0
	v_pk_fma_f32 v[252:253], v[248:249], v[250:251], 1.0 op_sel_hi:[1,1,0] neg_lo:[1,0,0] neg_hi:[1,0,0]
	v_pk_fma_f32 v[250:251], v[252:253], v[250:251], v[250:251]
	v_pk_fma_f32 v[252:253], v[248:249], v[250:251], 1.0 op_sel_hi:[1,1,0] neg_lo:[1,0,0] neg_hi:[1,0,0]
	v_pk_fma_f32 v[254:255], v[252:253], v[250:251], v[250:251]
	v_pk_fma_f32 v[252:253], v[248:249], v[254:255], 1.0 op_sel_hi:[1,1,0] neg_lo:[1,0,0] neg_hi:[1,0,0]
	v_pk_fma_f32 v[254:255], v[252:253], v[250:251], v[254:255]
	v_div_fixup_f32 v248, v254, v248, 1.0
	v_div_fixup_f32 v249, v255, v249, 1.0
	v_lshlrev_b32_e32 v114, 16, v106
	v_and_b32_e32 v115, 0xffff0000, v106
	v_lshlrev_b32_e32 v116, 16, v108
	v_and_b32_e32 v117, 0xffff0000, v108
	v_lshlrev_b32_e32 v108, 16, v109
	v_and_b32_e32 v109, 0xffff0000, v109
	v_lshlrev_b32_e32 v106, 16, v107
	v_and_b32_e32 v107, 0xffff0000, v107
	v_pk_fma_f32 v[92:93], v[92:93], v[242:243], v[114:115]
	v_pk_fma_f32 v[102:103], v[90:91], v[248:249], v[108:109]
	v_pk_fma_f32 v[90:91], v[88:89], v[244:245], v[116:117]
	v_add_lshl_u32 v104, v140, v98, 1
	v_pk_fma_f32 v[94:95], v[94:95], v[246:247], v[106:107]
	v_cvt_pk_bf16_f32 v88, v92, v93
	s_nop 0
	v_cvt_pk_bf16_f32 v89, v94, v95
	v_cvt_pk_bf16_f32 v90, v90, v91
	v_cvt_pk_bf16_f32 v91, v102, v103
	buffer_store_dwordx4 v[88:91], v104, s[20:23], 0 offen sc1
	s_nop 0
	s_waitcnt vmcnt(7)
; __device__ __forceinline__ float sigmoidf_(float x) { return 1.0f / (1.0f + __expf(-x)); }
; __device__ __forceinline__ u32x4 pack8(const f32x4 v0, const f32x4 v1) { u32x4 w; w.x = pk2(v0[0], v0[1]); w.y = pk2(v0[2], v0[3]); w.z = pk2(v1[0], v1[1]); w.w = pk2(v1[2], v1[3]); return w; }
; __device__ __forceinline__ void unpack8(const u32x4 w, f32x4& v0, f32x4& v1) { v0 = (f32x4){bflo(w.x), bfhi(w.x), bflo(w.y), bfhi(w.y)}; v1 = (f32x4){bflo(w.z), bfhi(w.z), bflo(w.w), bfhi(w.w)}; }
;     __device__ __forceinline__ void operator()(const f32x4 (&acc)[2][2][4][2], const Unit& u, int wr, int wc, int fr, int fq) const {
;     ...
;                 const int row = row0 + ai * 128 + m * 16;
;                 const bf16_t* rowp = z + (size_t)row * DIN + col0;
; #pragma unroll
;                 for (int bj = 0; bj < 2; ++bj) {
;                     const u32x4 gw = *(const u32x4*)(rowp + O_GA + bj * 128);
;                     f32x4 g0, g1; unpack8(gw, g0, g1);
;                     f32x4 v0, v1;
; #pragma unroll
;                     for (int j = 0; j < 4; ++j) { v0[j] = sigmoidf_(g0[j]) * acc[ai][bj][m][0][j]; v1[j] = sigmoidf_(g1[j]) * acc[ai][bj][m][1][j]; }
;                     const u32x4 mw = *(const u32x4*)(rowp + bj * 128); f32x4 m0, m1; unpack8(mw, m0, m1); v0 += m0; v1 += m1;
;                     __builtin_amdgcn_raw_buffer_store_b128(pack8(v0, v1), rsrc, (unsigned)(((size_t)row * DIN + col0 + bj * 128) * 2), 0, 16  ); }
	v_mov_b32_e32 v88, v232
	v_mov_b32_e32 v89, v233
	v_mov_b32_e32 v90, v234
	v_mov_b32_e32 v91, v235
	v_mov_b32_e32 v92, v236
	v_mov_b32_e32 v93, v237
	v_mov_b32_e32 v94, v238
	v_mov_b32_e32 v95, v239
	v_add_u32_e32 v198, 0x111200, v197
	global_load_dwordx4 v[232:235], v198, s[34:35]
	v_add_u32_e32 v198, 0x110000, v197
	global_load_dwordx4 v[236:239], v198, s[34:35]
	s_mov_b32 s100, 0xbfb8aa3b
	v_lshlrev_b32_e32 v242, 16, v90
	v_and_b32_e32 v243, 0xffff0000, v90
	v_lshlrev_b32_e32 v244, 16, v88
	v_and_b32_e32 v245, 0xffff0000, v88
	v_lshlrev_b32_e32 v246, 16, v89
	v_and_b32_e32 v247, 0xffff0000, v89
	v_lshlrev_b32_e32 v248, 16, v91
	v_and_b32_e32 v249, 0xffff0000, v91
	v_pk_mul_f32 v[242:243], v[242:243], s[100:101] op_sel_hi:[1,0]
	v_pk_mul_f32 v[244:245], v[244:245], s[100:101] op_sel_hi:[1,0]
	v_pk_mul_f32 v[246:247], v[246:247], s[100:101] op_sel_hi:[1,0]
	v_pk_mul_f32 v[248:249], v[248:249], s[100:101] op_sel_hi:[1,0]
	v_exp_f32_e32 v242, v242
	v_exp_f32_e32 v243, v243
	v_exp_f32_e32 v244, v244
	v_exp_f32_e32 v245, v245
	v_exp_f32_e32 v246, v246
	v_exp_f32_e32 v247, v247
	v_exp_f32_e32 v248, v248
	v_exp_f32_e32 v249, v249
	s_nop 0
	v_pk_add_f32 v[242:243], v[242:243], 1.0 op_sel_hi:[1,0]
	v_pk_add_f32 v[244:245], v[244:245], 1.0 op_sel_hi:[1,0]
	v_pk_add_f32 v[246:247], v[246:247], 1.0 op_sel_hi:[1,0]
	v_pk_add_f32 v[248:249], v[248:249], 1.0 op_sel_hi:[1,0]
	v_rcp_f32_e32 v250, v242
	v_rcp_f32_e32 v251, v243
	s_nop 0
	v_pk_fma_f32 v[252:253], v[242:243], v[250:251], 1.0 op_sel_hi:[1,1,0] neg_lo:[1,0,0] neg_hi:[1,0,0]
	v_pk_fma_f32 v[250:251], v[252:253], v[250:251], v[250:251]
	v_pk_fma_f32 v[252:253], v[242:243], v[250:251], 1.0 op_sel_hi:[1,1,0] neg_lo:[1,0,0] neg_hi:[1,0,0]
	v_pk_fma_f32 v[254:255], v[252:253], v[250:251], v[250:251]
	v_pk_fma_f32 v[252:253], v[242:243], v[254:255], 1.0 op_sel_hi:[1,1,0] neg_lo:[1,0,0] neg_hi:[1,0,0]
	v_pk_fma_f32 v[254:255], v[252:253], v[250:251], v[254:255]
	v_div_fixup_f32 v242, v254, v242, 1.0
	v_div_fixup_f32 v243, v255, v243, 1.0
	v_rcp_f32_e32 v250, v244
	v_rcp_f32_e32 v251, v245
	s_nop 0
	v_pk_fma_f32 v[252:253], v[244:245], v[250:251], 1.0 op_sel_hi:[1,1,0] neg_lo:[1,0,0] neg_hi:[1,0,0]
	v_pk_fma_f32 v[250:251], v[252:253], v[250:251], v[250:251]
	v_pk_fma_f32 v[252:253], v[244:245], v[250:251], 1.0 op_sel_hi:[1,1,0] neg_lo:[1,0,0] neg_hi:[1,0,0]
	v_pk_fma_f32 v[254:255], v[252:253], v[250:251], v[250:251]
	v_pk_fma_f32 v[252:253], v[244:245], v[254:255], 1.0 op_sel_hi:[1,1,0] neg_lo:[1,0,0] neg_hi:[1,0,0]
	v_pk_fma_f32 v[254:255], v[252:253], v[250:251], v[254:255]
	v_div_fixup_f32 v244, v254, v244, 1.0
	v_div_fixup_f32 v245, v255, v245, 1.0
	v_rcp_f32_e32 v250, v246
	v_rcp_f32_e32 v251, v247
	s_nop 0
	v_pk_fma_f32 v[252:253], v[246:247], v[250:251], 1.0 op_sel_hi:[1,1,0] neg_lo:[1,0,0] neg_hi:[1,0,0]
	v_pk_fma_f32 v[250:251], v[252:253], v[250:251], v[250:251]
	v_pk_fma_f32 v[252:253], v[246:247], v[250:251], 1.0 op_sel_hi:[1,1,0] neg_lo:[1,0,0] neg_hi:[1,0,0]
	v_pk_fma_f32 v[254:255], v[252:253], v[250:251], v[250:251]
	v_pk_fma_f32 v[252:253], v[246:247], v[254:255], 1.0 op_sel_hi:[1,1,0] neg_lo:[1,0,0] neg_hi:[1,0,0]
	v_pk_fma_f32 v[254:255], v[252:253], v[250:251], v[254:255]
	v_div_fixup_f32 v246, v254, v246, 1.0
	v_div_fixup_f32 v247, v255, v247, 1.0
	v_rcp_f32_e32 v250, v248
	v_rcp_f32_e32 v251, v249
	s_nop 0
	v_pk_fma_f32 v[252:253], v[248:249], v[250:251], 1.0 op_sel_hi:[1,1,0] neg_lo:[1,0,0] neg_hi:[1,0,0]
	v_pk_fma_f32 v[250:251], v[252:253], v[250:251], v[250:251]
	v_pk_fma_f32 v[252:253], v[248:249], v[250:251], 1.0 op_sel_hi:[1,1,0] neg_lo:[1,0,0] neg_hi:[1,0,0]
	v_pk_fma_f32 v[254:255], v[252:253], v[250:251], v[250:251]
	v_pk_fma_f32 v[252:253], v[248:249], v[254:255], 1.0 op_sel_hi:[1,1,0] neg_lo:[1,0,0] neg_hi:[1,0,0]
	v_pk_fma_f32 v[254:255], v[252:253], v[250:251], v[254:255]
	v_div_fixup_f32 v248, v254, v248, 1.0
	v_div_fixup_f32 v249, v255, v249, 1.0
	v_lshlrev_b32_e32 v100, 16, v92
	v_and_b32_e32 v101, 0xffff0000, v92
	v_lshlrev_b32_e32 v102, 16, v94
	v_and_b32_e32 v103, 0xffff0000, v94
	v_lshlrev_b32_e32 v94, 16, v95
	v_and_b32_e32 v95, 0xffff0000, v95
	v_lshlrev_b32_e32 v92, 16, v93
	v_and_b32_e32 v93, 0xffff0000, v93
	v_pk_fma_f32 v[84:85], v[84:85], v[244:245], v[100:101]
	v_pk_fma_f32 v[88:89], v[82:83], v[248:249], v[94:95]
	v_pk_fma_f32 v[82:83], v[80:81], v[242:243], v[102:103]
	v_cvt_pk_bf16_f32 v80, v84, v85
	v_pk_fma_f32 v[86:87], v[86:87], v[246:247], v[92:93]
	s_nop 0
	v_cvt_pk_bf16_f32 v81, v86, v87
	v_cvt_pk_bf16_f32 v82, v82, v83
	v_cvt_pk_bf16_f32 v83, v88, v89
	buffer_store_dwordx4 v[80:83], v104, s[20:23], 0 offen offset:256 sc1
	s_nop 1
	v_add_u32_e32 v80, 0x4030, v158
	v_mad_i64_i32 v[82:83], s[6:7], v80, s73, 0
	v_lshl_add_u64 v[80:81], v[82:83], 1, s[34:35]
	v_lshl_add_u64 v[80:81], v[80:81], 0, v[142:143]
	v_add_co_u32_e32 v84, vcc, s74, v80
	s_nop 1
	v_addc_co_u32_e32 v85, vcc, 0, v81, vcc
	s_waitcnt vmcnt(7)
; __device__ __forceinline__ float sigmoidf_(float x) { return 1.0f / (1.0f + __expf(-x)); }
; __device__ __forceinline__ u32x4 pack8(const f32x4 v0, const f32x4 v1) { u32x4 w; w.x = pk2(v0[0], v0[1]); w.y = pk2(v0[2], v0[3]); w.z = pk2(v1[0], v1[1]); w.w = pk2(v1[2], v1[3]); return w; }
; __device__ __forceinline__ void unpack8(const u32x4 w, f32x4& v0, f32x4& v1) { v0 = (f32x4){bflo(w.x), bfhi(w.x), bflo(w.y), bfhi(w.y)}; v1 = (f32x4){bflo(w.z), bfhi(w.z), bflo(w.w), bfhi(w.w)}; }
;     __device__ __forceinline__ void operator()(const f32x4 (&acc)[2][2][4][2], const Unit& u, int wr, int wc, int fr, int fq) const {
;     ...
;                 const int row = row0 + ai * 128 + m * 16;
;                 const bf16_t* rowp = z + (size_t)row * DIN + col0;
; #pragma unroll
;                 for (int bj = 0; bj < 2; ++bj) {
;                     const u32x4 gw = *(const u32x4*)(rowp + O_GA + bj * 128);
;                     f32x4 g0, g1; unpack8(gw, g0, g1);
;                     f32x4 v0, v1;
; #pragma unroll
;                     for (int j = 0; j < 4; ++j) { v0[j] = sigmoidf_(g0[j]) * acc[ai][bj][m][0][j]; v1[j] = sigmoidf_(g1[j]) * acc[ai][bj][m][1][j]; }
;                     const u32x4 mw = *(const u32x4*)(rowp + bj * 128); f32x4 m0, m1; unpack8(mw, m0, m1); v0 += m0; v1 += m1;
;                     __builtin_amdgcn_raw_buffer_store_b128(pack8(v0, v1), rsrc, (unsigned)(((size_t)row * DIN + col0 + bj * 128) * 2), 0, 16  ); }
	v_mov_b32_e32 v86, v200
	v_mov_b32_e32 v87, v201
	v_mov_b32_e32 v88, v202
	v_mov_b32_e32 v89, v203
	v_mov_b32_e32 v90, v204
	v_mov_b32_e32 v91, v205
	v_mov_b32_e32 v92, v206
	v_mov_b32_e32 v93, v207
	v_add_u32_e32 v198, 0x111300, v197
	global_load_dwordx4 v[200:203], v198, s[34:35]
	v_add_u32_e32 v198, 0x110100, v197
	global_load_dwordx4 v[204:207], v198, s[34:35]
	s_mov_b32 s100, 0xbfb8aa3b
	v_lshlrev_b32_e32 v242, 16, v86
	v_and_b32_e32 v243, 0xffff0000, v86
	v_lshlrev_b32_e32 v244, 16, v88
	v_and_b32_e32 v245, 0xffff0000, v88
	v_lshlrev_b32_e32 v246, 16, v87
	v_and_b32_e32 v247, 0xffff0000, v87
	v_lshlrev_b32_e32 v248, 16, v89
	v_and_b32_e32 v249, 0xffff0000, v89
	v_pk_mul_f32 v[242:243], v[242:243], s[100:101] op_sel_hi:[1,0]
	v_pk_mul_f32 v[244:245], v[244:245], s[100:101] op_sel_hi:[1,0]
	v_pk_mul_f32 v[246:247], v[246:247], s[100:101] op_sel_hi:[1,0]
	v_pk_mul_f32 v[248:249], v[248:249], s[100:101] op_sel_hi:[1,0]
	v_exp_f32_e32 v242, v242
	v_exp_f32_e32 v243, v243
	v_exp_f32_e32 v244, v244
	v_exp_f32_e32 v245, v245
	v_exp_f32_e32 v246, v246
	v_exp_f32_e32 v247, v247
	v_exp_f32_e32 v248, v248
	v_exp_f32_e32 v249, v249
	s_nop 0
	v_pk_add_f32 v[242:243], v[242:243], 1.0 op_sel_hi:[1,0]
	v_pk_add_f32 v[244:245], v[244:245], 1.0 op_sel_hi:[1,0]
	v_pk_add_f32 v[246:247], v[246:247], 1.0 op_sel_hi:[1,0]
	v_pk_add_f32 v[248:249], v[248:249], 1.0 op_sel_hi:[1,0]
	v_rcp_f32_e32 v250, v242
	v_rcp_f32_e32 v251, v243
	s_nop 0
	v_pk_fma_f32 v[252:253], v[242:243], v[250:251], 1.0 op_sel_hi:[1,1,0] neg_lo:[1,0,0] neg_hi:[1,0,0]
	v_pk_fma_f32 v[250:251], v[252:253], v[250:251], v[250:251]
	v_pk_fma_f32 v[252:253], v[242:243], v[250:251], 1.0 op_sel_hi:[1,1,0] neg_lo:[1,0,0] neg_hi:[1,0,0]
	v_pk_fma_f32 v[254:255], v[252:253], v[250:251], v[250:251]
	v_pk_fma_f32 v[252:253], v[242:243], v[254:255], 1.0 op_sel_hi:[1,1,0] neg_lo:[1,0,0] neg_hi:[1,0,0]
	v_pk_fma_f32 v[254:255], v[252:253], v[250:251], v[254:255]
	v_div_fixup_f32 v242, v254, v242, 1.0
	v_div_fixup_f32 v243, v255, v243, 1.0
	v_rcp_f32_e32 v250, v244
	v_rcp_f32_e32 v251, v245
	s_nop 0
	v_pk_fma_f32 v[252:253], v[244:245], v[250:251], 1.0 op_sel_hi:[1,1,0] neg_lo:[1,0,0] neg_hi:[1,0,0]
	v_pk_fma_f32 v[250:251], v[252:253], v[250:251], v[250:251]
	v_pk_fma_f32 v[252:253], v[244:245], v[250:251], 1.0 op_sel_hi:[1,1,0] neg_lo:[1,0,0] neg_hi:[1,0,0]
	v_pk_fma_f32 v[254:255], v[252:253], v[250:251], v[250:251]
	v_pk_fma_f32 v[252:253], v[244:245], v[254:255], 1.0 op_sel_hi:[1,1,0] neg_lo:[1,0,0] neg_hi:[1,0,0]
	v_pk_fma_f32 v[254:255], v[252:253], v[250:251], v[254:255]
	v_div_fixup_f32 v244, v254, v244, 1.0
	v_div_fixup_f32 v245, v255, v245, 1.0
	v_rcp_f32_e32 v250, v246
	v_rcp_f32_e32 v251, v247
	s_nop 0
	v_pk_fma_f32 v[252:253], v[246:247], v[250:251], 1.0 op_sel_hi:[1,1,0] neg_lo:[1,0,0] neg_hi:[1,0,0]
	v_pk_fma_f32 v[250:251], v[252:253], v[250:251], v[250:251]
	v_pk_fma_f32 v[252:253], v[246:247], v[250:251], 1.0 op_sel_hi:[1,1,0] neg_lo:[1,0,0] neg_hi:[1,0,0]
	v_pk_fma_f32 v[254:255], v[252:253], v[250:251], v[250:251]
	v_pk_fma_f32 v[252:253], v[246:247], v[254:255], 1.0 op_sel_hi:[1,1,0] neg_lo:[1,0,0] neg_hi:[1,0,0]
	v_pk_fma_f32 v[254:255], v[252:253], v[250:251], v[254:255]
	v_div_fixup_f32 v246, v254, v246, 1.0
	v_div_fixup_f32 v247, v255, v247, 1.0
	v_rcp_f32_e32 v250, v248
	v_rcp_f32_e32 v251, v249
	s_nop 0
	v_pk_fma_f32 v[252:253], v[248:249], v[250:251], 1.0 op_sel_hi:[1,1,0] neg_lo:[1,0,0] neg_hi:[1,0,0]
	v_pk_fma_f32 v[250:251], v[252:253], v[250:251], v[250:251]
	v_pk_fma_f32 v[252:253], v[248:249], v[250:251], 1.0 op_sel_hi:[1,1,0] neg_lo:[1,0,0] neg_hi:[1,0,0]
	v_pk_fma_f32 v[254:255], v[252:253], v[250:251], v[250:251]
	v_pk_fma_f32 v[252:253], v[248:249], v[254:255], 1.0 op_sel_hi:[1,1,0] neg_lo:[1,0,0] neg_hi:[1,0,0]
	v_pk_fma_f32 v[254:255], v[252:253], v[250:251], v[254:255]
	v_div_fixup_f32 v248, v254, v248, 1.0
	v_div_fixup_f32 v249, v255, v249, 1.0
	v_lshlrev_b32_e32 v98, 16, v90
	v_and_b32_e32 v99, 0xffff0000, v90
	v_lshlrev_b32_e32 v100, 16, v92
	v_and_b32_e32 v101, 0xffff0000, v92
	v_lshlrev_b32_e32 v92, 16, v93
	v_and_b32_e32 v93, 0xffff0000, v93
	v_lshlrev_b32_e32 v90, 16, v91
	v_and_b32_e32 v91, 0xffff0000, v91
	v_pk_fma_f32 v[76:77], v[76:77], v[242:243], v[98:99]
	v_pk_fma_f32 v[86:87], v[74:75], v[248:249], v[92:93]
	v_pk_fma_f32 v[74:75], v[72:73], v[244:245], v[100:101]
	v_add_lshl_u32 v88, v140, v82, 1
	v_pk_fma_f32 v[78:79], v[78:79], v[246:247], v[90:91]
	v_cvt_pk_bf16_f32 v72, v76, v77
	s_nop 0
	v_cvt_pk_bf16_f32 v73, v78, v79
	v_cvt_pk_bf16_f32 v74, v74, v75
	v_cvt_pk_bf16_f32 v75, v86, v87
	buffer_store_dwordx4 v[72:75], v88, s[20:23], 0 offen sc1
	s_nop 0
	s_waitcnt vmcnt(7)
; __device__ __forceinline__ float sigmoidf_(float x) { return 1.0f / (1.0f + __expf(-x)); }
; __device__ __forceinline__ u32x4 pack8(const f32x4 v0, const f32x4 v1) { u32x4 w; w.x = pk2(v0[0], v0[1]); w.y = pk2(v0[2], v0[3]); w.z = pk2(v1[0], v1[1]); w.w = pk2(v1[2], v1[3]); return w; }
; __device__ __forceinline__ void unpack8(const u32x4 w, f32x4& v0, f32x4& v1) { v0 = (f32x4){bflo(w.x), bfhi(w.x), bflo(w.y), bfhi(w.y)}; v1 = (f32x4){bflo(w.z), bfhi(w.z), bflo(w.w), bfhi(w.w)}; }
;     __device__ __forceinline__ void operator()(const f32x4 (&acc)[2][2][4][2], const Unit& u, int wr, int wc, int fr, int fq) const {
;     ...
;                 const int row = row0 + ai * 128 + m * 16;
;                 const bf16_t* rowp = z + (size_t)row * DIN + col0;
; #pragma unroll
;                 for (int bj = 0; bj < 2; ++bj) {
;                     const u32x4 gw = *(const u32x4*)(rowp + O_GA + bj * 128);
;                     f32x4 g0, g1; unpack8(gw, g0, g1);
;                     f32x4 v0, v1;
; #pragma unroll
;                     for (int j = 0; j < 4; ++j) { v0[j] = sigmoidf_(g0[j]) * acc[ai][bj][m][0][j]; v1[j] = sigmoidf_(g1[j]) * acc[ai][bj][m][1][j]; }
;                     const u32x4 mw = *(const u32x4*)(rowp + bj * 128); f32x4 m0, m1; unpack8(mw, m0, m1); v0 += m0; v1 += m1;
;                     __builtin_amdgcn_raw_buffer_store_b128(pack8(v0, v1), rsrc, (unsigned)(((size_t)row * DIN + col0 + bj * 128) * 2), 0, 16  ); }
	v_mov_b32_e32 v72, v208
	v_mov_b32_e32 v73, v209
	v_mov_b32_e32 v74, v210
	v_mov_b32_e32 v75, v211
	v_mov_b32_e32 v76, v212
	v_mov_b32_e32 v77, v213
	v_mov_b32_e32 v78, v214
	v_mov_b32_e32 v79, v215
	v_add_u32_e32 v198, 0x133200, v197
	global_load_dwordx4 v[208:211], v198, s[34:35]
	v_add_u32_e32 v198, 0x132000, v197
	global_load_dwordx4 v[212:215], v198, s[34:35]
	s_mov_b32 s100, 0xbfb8aa3b
	v_lshlrev_b32_e32 v242, 16, v74
	v_and_b32_e32 v243, 0xffff0000, v74
	v_lshlrev_b32_e32 v244, 16, v72
	v_and_b32_e32 v245, 0xffff0000, v72
	v_lshlrev_b32_e32 v246, 16, v73
	v_and_b32_e32 v247, 0xffff0000, v73
	v_lshlrev_b32_e32 v248, 16, v75
	v_and_b32_e32 v249, 0xffff0000, v75
	v_pk_mul_f32 v[242:243], v[242:243], s[100:101] op_sel_hi:[1,0]
	v_pk_mul_f32 v[244:245], v[244:245], s[100:101] op_sel_hi:[1,0]
	v_pk_mul_f32 v[246:247], v[246:247], s[100:101] op_sel_hi:[1,0]
	v_pk_mul_f32 v[248:249], v[248:249], s[100:101] op_sel_hi:[1,0]
	v_exp_f32_e32 v242, v242
	v_exp_f32_e32 v243, v243
	v_exp_f32_e32 v244, v244
	v_exp_f32_e32 v245, v245
	v_exp_f32_e32 v246, v246
	v_exp_f32_e32 v247, v247
	v_exp_f32_e32 v248, v248
	v_exp_f32_e32 v249, v249
	s_nop 0
	v_pk_add_f32 v[242:243], v[242:243], 1.0 op_sel_hi:[1,0]
	v_pk_add_f32 v[244:245], v[244:245], 1.0 op_sel_hi:[1,0]
	v_pk_add_f32 v[246:247], v[246:247], 1.0 op_sel_hi:[1,0]
	v_pk_add_f32 v[248:249], v[248:249], 1.0 op_sel_hi:[1,0]
	v_rcp_f32_e32 v250, v242
	v_rcp_f32_e32 v251, v243
	s_nop 0
	v_pk_fma_f32 v[252:253], v[242:243], v[250:251], 1.0 op_sel_hi:[1,1,0] neg_lo:[1,0,0] neg_hi:[1,0,0]
	v_pk_fma_f32 v[250:251], v[252:253], v[250:251], v[250:251]
	v_pk_fma_f32 v[252:253], v[242:243], v[250:251], 1.0 op_sel_hi:[1,1,0] neg_lo:[1,0,0] neg_hi:[1,0,0]
	v_pk_fma_f32 v[254:255], v[252:253], v[250:251], v[250:251]
	v_pk_fma_f32 v[252:253], v[242:243], v[254:255], 1.0 op_sel_hi:[1,1,0] neg_lo:[1,0,0] neg_hi:[1,0,0]
	v_pk_fma_f32 v[254:255], v[252:253], v[250:251], v[254:255]
	v_div_fixup_f32 v242, v254, v242, 1.0
	v_div_fixup_f32 v243, v255, v243, 1.0
	v_rcp_f32_e32 v250, v244
	v_rcp_f32_e32 v251, v245
	s_nop 0
	v_pk_fma_f32 v[252:253], v[244:245], v[250:251], 1.0 op_sel_hi:[1,1,0] neg_lo:[1,0,0] neg_hi:[1,0,0]
	v_pk_fma_f32 v[250:251], v[252:253], v[250:251], v[250:251]
	v_pk_fma_f32 v[252:253], v[244:245], v[250:251], 1.0 op_sel_hi:[1,1,0] neg_lo:[1,0,0] neg_hi:[1,0,0]
	v_pk_fma_f32 v[254:255], v[252:253], v[250:251], v[250:251]
	v_pk_fma_f32 v[252:253], v[244:245], v[254:255], 1.0 op_sel_hi:[1,1,0] neg_lo:[1,0,0] neg_hi:[1,0,0]
	v_pk_fma_f32 v[254:255], v[252:253], v[250:251], v[254:255]
	v_div_fixup_f32 v244, v254, v244, 1.0
	v_div_fixup_f32 v245, v255, v245, 1.0
	v_rcp_f32_e32 v250, v246
	v_rcp_f32_e32 v251, v247
	s_nop 0
	v_pk_fma_f32 v[252:253], v[246:247], v[250:251], 1.0 op_sel_hi:[1,1,0] neg_lo:[1,0,0] neg_hi:[1,0,0]
	v_pk_fma_f32 v[250:251], v[252:253], v[250:251], v[250:251]
	v_pk_fma_f32 v[252:253], v[246:247], v[250:251], 1.0 op_sel_hi:[1,1,0] neg_lo:[1,0,0] neg_hi:[1,0,0]
	v_pk_fma_f32 v[254:255], v[252:253], v[250:251], v[250:251]
	v_pk_fma_f32 v[252:253], v[246:247], v[254:255], 1.0 op_sel_hi:[1,1,0] neg_lo:[1,0,0] neg_hi:[1,0,0]
	v_pk_fma_f32 v[254:255], v[252:253], v[250:251], v[254:255]
	v_div_fixup_f32 v246, v254, v246, 1.0
	v_div_fixup_f32 v247, v255, v247, 1.0
	v_rcp_f32_e32 v250, v248
	v_rcp_f32_e32 v251, v249
	s_nop 0
	v_pk_fma_f32 v[252:253], v[248:249], v[250:251], 1.0 op_sel_hi:[1,1,0] neg_lo:[1,0,0] neg_hi:[1,0,0]
	v_pk_fma_f32 v[250:251], v[252:253], v[250:251], v[250:251]
	v_pk_fma_f32 v[252:253], v[248:249], v[250:251], 1.0 op_sel_hi:[1,1,0] neg_lo:[1,0,0] neg_hi:[1,0,0]
	v_pk_fma_f32 v[254:255], v[252:253], v[250:251], v[250:251]
	v_pk_fma_f32 v[252:253], v[248:249], v[254:255], 1.0 op_sel_hi:[1,1,0] neg_lo:[1,0,0] neg_hi:[1,0,0]
	v_pk_fma_f32 v[254:255], v[252:253], v[250:251], v[254:255]
	v_div_fixup_f32 v248, v254, v248, 1.0
	v_div_fixup_f32 v249, v255, v249, 1.0
	v_lshlrev_b32_e32 v84, 16, v76
	v_and_b32_e32 v85, 0xffff0000, v76
	v_lshlrev_b32_e32 v86, 16, v78
	v_and_b32_e32 v87, 0xffff0000, v78
	v_lshlrev_b32_e32 v78, 16, v79
	v_and_b32_e32 v79, 0xffff0000, v79
	v_lshlrev_b32_e32 v76, 16, v77
	v_and_b32_e32 v77, 0xffff0000, v77
	v_pk_fma_f32 v[68:69], v[68:69], v[244:245], v[84:85]
	v_pk_fma_f32 v[72:73], v[66:67], v[248:249], v[78:79]
	v_pk_fma_f32 v[66:67], v[64:65], v[242:243], v[86:87]
	v_cvt_pk_bf16_f32 v64, v68, v69
	v_pk_fma_f32 v[70:71], v[70:71], v[246:247], v[76:77]
	s_nop 0
	v_cvt_pk_bf16_f32 v65, v70, v71
	v_cvt_pk_bf16_f32 v66, v66, v67
	v_cvt_pk_bf16_f32 v67, v72, v73
	buffer_store_dwordx4 v[64:67], v88, s[20:23], 0 offen offset:256 sc1
	s_nop 1
	v_add_u32_e32 v64, 0x4080, v158
	v_mad_i64_i32 v[66:67], s[6:7], v64, s73, 0
	v_lshl_add_u64 v[64:65], v[66:67], 1, s[34:35]
	v_lshl_add_u64 v[64:65], v[64:65], 0, v[142:143]
	v_add_co_u32_e32 v68, vcc, s74, v64
	s_nop 1
	v_addc_co_u32_e32 v69, vcc, 0, v65, vcc
	s_waitcnt vmcnt(7)
; __device__ __forceinline__ float sigmoidf_(float x) { return 1.0f / (1.0f + __expf(-x)); }
; __device__ __forceinline__ u32x4 pack8(const f32x4 v0, const f32x4 v1) { u32x4 w; w.x = pk2(v0[0], v0[1]); w.y = pk2(v0[2], v0[3]); w.z = pk2(v1[0], v1[1]); w.w = pk2(v1[2], v1[3]); return w; }
; __device__ __forceinline__ void unpack8(const u32x4 w, f32x4& v0, f32x4& v1) { v0 = (f32x4){bflo(w.x), bfhi(w.x), bflo(w.y), bfhi(w.y)}; v1 = (f32x4){bflo(w.z), bfhi(w.z), bflo(w.w), bfhi(w.w)}; }
;     __device__ __forceinline__ void operator()(const f32x4 (&acc)[2][2][4][2], const Unit& u, int wr, int wc, int fr, int fq) const {
;     ...
;                 const int row = row0 + ai * 128 + m * 16;
;                 const bf16_t* rowp = z + (size_t)row * DIN + col0;
; #pragma unroll
;                 for (int bj = 0; bj < 2; ++bj) {
;                     const u32x4 gw = *(const u32x4*)(rowp + O_GA + bj * 128);
;                     f32x4 g0, g1; unpack8(gw, g0, g1);
;                     f32x4 v0, v1;
; #pragma unroll
;                     for (int j = 0; j < 4; ++j) { v0[j] = sigmoidf_(g0[j]) * acc[ai][bj][m][0][j]; v1[j] = sigmoidf_(g1[j]) * acc[ai][bj][m][1][j]; }
;                     const u32x4 mw = *(const u32x4*)(rowp + bj * 128); f32x4 m0, m1; unpack8(mw, m0, m1); v0 += m0; v1 += m1;
;                     __builtin_amdgcn_raw_buffer_store_b128(pack8(v0, v1), rsrc, (unsigned)(((size_t)row * DIN + col0 + bj * 128) * 2), 0, 16  ); }
	v_mov_b32_e32 v70, v232
	v_mov_b32_e32 v71, v233
	v_mov_b32_e32 v72, v234
	v_mov_b32_e32 v73, v235
	v_mov_b32_e32 v74, v236
	v_mov_b32_e32 v75, v237
	v_mov_b32_e32 v76, v238
	v_mov_b32_e32 v77, v239
	v_add_u32_e32 v198, 0x133300, v197
	global_load_dwordx4 v[232:235], v198, s[34:35]
	v_add_u32_e32 v198, 0x132100, v197
	global_load_dwordx4 v[236:239], v198, s[34:35]
	s_mov_b32 s100, 0xbfb8aa3b
	v_lshlrev_b32_e32 v242, 16, v70
	v_and_b32_e32 v243, 0xffff0000, v70
	v_lshlrev_b32_e32 v244, 16, v72
	v_and_b32_e32 v245, 0xffff0000, v72
	v_lshlrev_b32_e32 v246, 16, v71
	v_and_b32_e32 v247, 0xffff0000, v71
	v_lshlrev_b32_e32 v248, 16, v73
	v_and_b32_e32 v249, 0xffff0000, v73
	v_pk_mul_f32 v[242:243], v[242:243], s[100:101] op_sel_hi:[1,0]
	v_pk_mul_f32 v[244:245], v[244:245], s[100:101] op_sel_hi:[1,0]
	v_pk_mul_f32 v[246:247], v[246:247], s[100:101] op_sel_hi:[1,0]
	v_pk_mul_f32 v[248:249], v[248:249], s[100:101] op_sel_hi:[1,0]
	v_exp_f32_e32 v242, v242
	v_exp_f32_e32 v243, v243
	v_exp_f32_e32 v244, v244
	v_exp_f32_e32 v245, v245
	v_exp_f32_e32 v246, v246
	v_exp_f32_e32 v247, v247
	v_exp_f32_e32 v248, v248
	v_exp_f32_e32 v249, v249
	s_nop 0
	v_pk_add_f32 v[242:243], v[242:243], 1.0 op_sel_hi:[1,0]
	v_pk_add_f32 v[244:245], v[244:245], 1.0 op_sel_hi:[1,0]
	v_pk_add_f32 v[246:247], v[246:247], 1.0 op_sel_hi:[1,0]
	v_pk_add_f32 v[248:249], v[248:249], 1.0 op_sel_hi:[1,0]
	v_rcp_f32_e32 v250, v242
	v_rcp_f32_e32 v251, v243
	s_nop 0
	v_pk_fma_f32 v[252:253], v[242:243], v[250:251], 1.0 op_sel_hi:[1,1,0] neg_lo:[1,0,0] neg_hi:[1,0,0]
	v_pk_fma_f32 v[250:251], v[252:253], v[250:251], v[250:251]
	v_pk_fma_f32 v[252:253], v[242:243], v[250:251], 1.0 op_sel_hi:[1,1,0] neg_lo:[1,0,0] neg_hi:[1,0,0]
	v_pk_fma_f32 v[254:255], v[252:253], v[250:251], v[250:251]
	v_pk_fma_f32 v[252:253], v[242:243], v[254:255], 1.0 op_sel_hi:[1,1,0] neg_lo:[1,0,0] neg_hi:[1,0,0]
	v_pk_fma_f32 v[254:255], v[252:253], v[250:251], v[254:255]
	v_div_fixup_f32 v242, v254, v242, 1.0
	v_div_fixup_f32 v243, v255, v243, 1.0
	v_rcp_f32_e32 v250, v244
	v_rcp_f32_e32 v251, v245
	s_nop 0
	v_pk_fma_f32 v[252:253], v[244:245], v[250:251], 1.0 op_sel_hi:[1,1,0] neg_lo:[1,0,0] neg_hi:[1,0,0]
	v_pk_fma_f32 v[250:251], v[252:253], v[250:251], v[250:251]
	v_pk_fma_f32 v[252:253], v[244:245], v[250:251], 1.0 op_sel_hi:[1,1,0] neg_lo:[1,0,0] neg_hi:[1,0,0]
	v_pk_fma_f32 v[254:255], v[252:253], v[250:251], v[250:251]
	v_pk_fma_f32 v[252:253], v[244:245], v[254:255], 1.0 op_sel_hi:[1,1,0] neg_lo:[1,0,0] neg_hi:[1,0,0]
	v_pk_fma_f32 v[254:255], v[252:253], v[250:251], v[254:255]
	v_div_fixup_f32 v244, v254, v244, 1.0
	v_div_fixup_f32 v245, v255, v245, 1.0
	v_rcp_f32_e32 v250, v246
	v_rcp_f32_e32 v251, v247
	s_nop 0
	v_pk_fma_f32 v[252:253], v[246:247], v[250:251], 1.0 op_sel_hi:[1,1,0] neg_lo:[1,0,0] neg_hi:[1,0,0]
	v_pk_fma_f32 v[250:251], v[252:253], v[250:251], v[250:251]
	v_pk_fma_f32 v[252:253], v[246:247], v[250:251], 1.0 op_sel_hi:[1,1,0] neg_lo:[1,0,0] neg_hi:[1,0,0]
	v_pk_fma_f32 v[254:255], v[252:253], v[250:251], v[250:251]
	v_pk_fma_f32 v[252:253], v[246:247], v[254:255], 1.0 op_sel_hi:[1,1,0] neg_lo:[1,0,0] neg_hi:[1,0,0]
	v_pk_fma_f32 v[254:255], v[252:253], v[250:251], v[254:255]
	v_div_fixup_f32 v246, v254, v246, 1.0
	v_div_fixup_f32 v247, v255, v247, 1.0
	v_rcp_f32_e32 v250, v248
	v_rcp_f32_e32 v251, v249
	s_nop 0
	v_pk_fma_f32 v[252:253], v[248:249], v[250:251], 1.0 op_sel_hi:[1,1,0] neg_lo:[1,0,0] neg_hi:[1,0,0]
	v_pk_fma_f32 v[250:251], v[252:253], v[250:251], v[250:251]
	v_pk_fma_f32 v[252:253], v[248:249], v[250:251], 1.0 op_sel_hi:[1,1,0] neg_lo:[1,0,0] neg_hi:[1,0,0]
	v_pk_fma_f32 v[254:255], v[252:253], v[250:251], v[250:251]
	v_pk_fma_f32 v[252:253], v[248:249], v[254:255], 1.0 op_sel_hi:[1,1,0] neg_lo:[1,0,0] neg_hi:[1,0,0]
	v_pk_fma_f32 v[254:255], v[252:253], v[250:251], v[254:255]
	v_div_fixup_f32 v248, v254, v248, 1.0
	v_div_fixup_f32 v249, v255, v249, 1.0
	v_lshlrev_b32_e32 v82, 16, v74
	v_and_b32_e32 v83, 0xffff0000, v74
	v_lshlrev_b32_e32 v84, 16, v76
	v_and_b32_e32 v85, 0xffff0000, v76
	v_lshlrev_b32_e32 v76, 16, v77
	v_and_b32_e32 v77, 0xffff0000, v77
	v_lshlrev_b32_e32 v74, 16, v75
	v_and_b32_e32 v75, 0xffff0000, v75
	v_pk_fma_f32 v[60:61], v[60:61], v[242:243], v[82:83]
	v_pk_fma_f32 v[70:71], v[58:59], v[248:249], v[76:77]
	v_pk_fma_f32 v[58:59], v[56:57], v[244:245], v[84:85]
	v_add_lshl_u32 v72, v140, v66, 1
	v_pk_fma_f32 v[62:63], v[62:63], v[246:247], v[74:75]
	v_cvt_pk_bf16_f32 v56, v60, v61
	s_nop 0
	v_cvt_pk_bf16_f32 v57, v62, v63
	v_cvt_pk_bf16_f32 v58, v58, v59
	v_cvt_pk_bf16_f32 v59, v70, v71
	buffer_store_dwordx4 v[56:59], v72, s[20:23], 0 offen sc1
	s_nop 0
	s_waitcnt vmcnt(7)
; __device__ __forceinline__ float sigmoidf_(float x) { return 1.0f / (1.0f + __expf(-x)); }
; __device__ __forceinline__ u32x4 pack8(const f32x4 v0, const f32x4 v1) { u32x4 w; w.x = pk2(v0[0], v0[1]); w.y = pk2(v0[2], v0[3]); w.z = pk2(v1[0], v1[1]); w.w = pk2(v1[2], v1[3]); return w; }
; __device__ __forceinline__ void unpack8(const u32x4 w, f32x4& v0, f32x4& v1) { v0 = (f32x4){bflo(w.x), bfhi(w.x), bflo(w.y), bfhi(w.y)}; v1 = (f32x4){bflo(w.z), bfhi(w.z), bflo(w.w), bfhi(w.w)}; }
;     __device__ __forceinline__ void operator()(const f32x4 (&acc)[2][2][4][2], const Unit& u, int wr, int wc, int fr, int fq) const {
;     ...
;                 const int row = row0 + ai * 128 + m * 16;
;                 const bf16_t* rowp = z + (size_t)row * DIN + col0;
; #pragma unroll
;                 for (int bj = 0; bj < 2; ++bj) {
;                     const u32x4 gw = *(const u32x4*)(rowp + O_GA + bj * 128);
;                     f32x4 g0, g1; unpack8(gw, g0, g1);
;                     f32x4 v0, v1;
; #pragma unroll
;                     for (int j = 0; j < 4; ++j) { v0[j] = sigmoidf_(g0[j]) * acc[ai][bj][m][0][j]; v1[j] = sigmoidf_(g1[j]) * acc[ai][bj][m][1][j]; }
;                     const u32x4 mw = *(const u32x4*)(rowp + bj * 128); f32x4 m0, m1; unpack8(mw, m0, m1); v0 += m0; v1 += m1;
;                     __builtin_amdgcn_raw_buffer_store_b128(pack8(v0, v1), rsrc, (unsigned)(((size_t)row * DIN + col0 + bj * 128) * 2), 0, 16  ); }
	v_mov_b32_e32 v56, v200
	v_mov_b32_e32 v57, v201
	v_mov_b32_e32 v58, v202
	v_mov_b32_e32 v59, v203
	v_mov_b32_e32 v60, v204
	v_mov_b32_e32 v61, v205
	v_mov_b32_e32 v62, v206
	v_mov_b32_e32 v63, v207
	v_add_u32_e32 v198, 0x155200, v197
	global_load_dwordx4 v[200:203], v198, s[34:35]
	v_add_u32_e32 v198, 0x154000, v197
	global_load_dwordx4 v[204:207], v198, s[34:35]
	s_mov_b32 s100, 0xbfb8aa3b
	v_lshlrev_b32_e32 v242, 16, v58
	v_and_b32_e32 v243, 0xffff0000, v58
	v_lshlrev_b32_e32 v244, 16, v56
	v_and_b32_e32 v245, 0xffff0000, v56
	v_lshlrev_b32_e32 v246, 16, v57
	v_and_b32_e32 v247, 0xffff0000, v57
	v_lshlrev_b32_e32 v248, 16, v59
	v_and_b32_e32 v249, 0xffff0000, v59
	v_pk_mul_f32 v[242:243], v[242:243], s[100:101] op_sel_hi:[1,0]
	v_pk_mul_f32 v[244:245], v[244:245], s[100:101] op_sel_hi:[1,0]
	v_pk_mul_f32 v[246:247], v[246:247], s[100:101] op_sel_hi:[1,0]
	v_pk_mul_f32 v[248:249], v[248:249], s[100:101] op_sel_hi:[1,0]
	v_exp_f32_e32 v242, v242
	v_exp_f32_e32 v243, v243
	v_exp_f32_e32 v244, v244
	v_exp_f32_e32 v245, v245
	v_exp_f32_e32 v246, v246
	v_exp_f32_e32 v247, v247
	v_exp_f32_e32 v248, v248
	v_exp_f32_e32 v249, v249
	s_nop 0
	v_pk_add_f32 v[242:243], v[242:243], 1.0 op_sel_hi:[1,0]
	v_pk_add_f32 v[244:245], v[244:245], 1.0 op_sel_hi:[1,0]
	v_pk_add_f32 v[246:247], v[246:247], 1.0 op_sel_hi:[1,0]
	v_pk_add_f32 v[248:249], v[248:249], 1.0 op_sel_hi:[1,0]
	v_rcp_f32_e32 v250, v242
	v_rcp_f32_e32 v251, v243
	s_nop 0
	v_pk_fma_f32 v[252:253], v[242:243], v[250:251], 1.0 op_sel_hi:[1,1,0] neg_lo:[1,0,0] neg_hi:[1,0,0]
	v_pk_fma_f32 v[250:251], v[252:253], v[250:251], v[250:251]
	v_pk_fma_f32 v[252:253], v[242:243], v[250:251], 1.0 op_sel_hi:[1,1,0] neg_lo:[1,0,0] neg_hi:[1,0,0]
	v_pk_fma_f32 v[254:255], v[252:253], v[250:251], v[250:251]
	v_pk_fma_f32 v[252:253], v[242:243], v[254:255], 1.0 op_sel_hi:[1,1,0] neg_lo:[1,0,0] neg_hi:[1,0,0]
	v_pk_fma_f32 v[254:255], v[252:253], v[250:251], v[254:255]
	v_div_fixup_f32 v242, v254, v242, 1.0
	v_div_fixup_f32 v243, v255, v243, 1.0
	v_rcp_f32_e32 v250, v244
	v_rcp_f32_e32 v251, v245
	s_nop 0
	v_pk_fma_f32 v[252:253], v[244:245], v[250:251], 1.0 op_sel_hi:[1,1,0] neg_lo:[1,0,0] neg_hi:[1,0,0]
	v_pk_fma_f32 v[250:251], v[252:253], v[250:251], v[250:251]
	v_pk_fma_f32 v[252:253], v[244:245], v[250:251], 1.0 op_sel_hi:[1,1,0] neg_lo:[1,0,0] neg_hi:[1,0,0]
	v_pk_fma_f32 v[254:255], v[252:253], v[250:251], v[250:251]
	v_pk_fma_f32 v[252:253], v[244:245], v[254:255], 1.0 op_sel_hi:[1,1,0] neg_lo:[1,0,0] neg_hi:[1,0,0]
	v_pk_fma_f32 v[254:255], v[252:253], v[250:251], v[254:255]
	v_div_fixup_f32 v244, v254, v244, 1.0
	v_div_fixup_f32 v245, v255, v245, 1.0
	v_rcp_f32_e32 v250, v246
	v_rcp_f32_e32 v251, v247
	s_nop 0
	v_pk_fma_f32 v[252:253], v[246:247], v[250:251], 1.0 op_sel_hi:[1,1,0] neg_lo:[1,0,0] neg_hi:[1,0,0]
	v_pk_fma_f32 v[250:251], v[252:253], v[250:251], v[250:251]
	v_pk_fma_f32 v[252:253], v[246:247], v[250:251], 1.0 op_sel_hi:[1,1,0] neg_lo:[1,0,0] neg_hi:[1,0,0]
	v_pk_fma_f32 v[254:255], v[252:253], v[250:251], v[250:251]
	v_pk_fma_f32 v[252:253], v[246:247], v[254:255], 1.0 op_sel_hi:[1,1,0] neg_lo:[1,0,0] neg_hi:[1,0,0]
	v_pk_fma_f32 v[254:255], v[252:253], v[250:251], v[254:255]
	v_div_fixup_f32 v246, v254, v246, 1.0
	v_div_fixup_f32 v247, v255, v247, 1.0
	v_rcp_f32_e32 v250, v248
	v_rcp_f32_e32 v251, v249
	s_nop 0
	v_pk_fma_f32 v[252:253], v[248:249], v[250:251], 1.0 op_sel_hi:[1,1,0] neg_lo:[1,0,0] neg_hi:[1,0,0]
	v_pk_fma_f32 v[250:251], v[252:253], v[250:251], v[250:251]
	v_pk_fma_f32 v[252:253], v[248:249], v[250:251], 1.0 op_sel_hi:[1,1,0] neg_lo:[1,0,0] neg_hi:[1,0,0]
	v_pk_fma_f32 v[254:255], v[252:253], v[250:251], v[250:251]
	v_pk_fma_f32 v[252:253], v[248:249], v[254:255], 1.0 op_sel_hi:[1,1,0] neg_lo:[1,0,0] neg_hi:[1,0,0]
	v_pk_fma_f32 v[254:255], v[252:253], v[250:251], v[254:255]
	v_div_fixup_f32 v248, v254, v248, 1.0
	v_div_fixup_f32 v249, v255, v249, 1.0
	v_lshlrev_b32_e32 v68, 16, v60
	v_and_b32_e32 v69, 0xffff0000, v60
	v_lshlrev_b32_e32 v70, 16, v62
	v_and_b32_e32 v71, 0xffff0000, v62
	v_lshlrev_b32_e32 v62, 16, v63
	v_and_b32_e32 v63, 0xffff0000, v63
	v_lshlrev_b32_e32 v60, 16, v61
	v_and_b32_e32 v61, 0xffff0000, v61
	v_pk_fma_f32 v[52:53], v[52:53], v[244:245], v[68:69]
	v_pk_fma_f32 v[56:57], v[50:51], v[248:249], v[62:63]
	v_pk_fma_f32 v[50:51], v[48:49], v[242:243], v[70:71]
	v_cvt_pk_bf16_f32 v48, v52, v53
	v_pk_fma_f32 v[54:55], v[54:55], v[246:247], v[60:61]
	s_nop 0
	v_cvt_pk_bf16_f32 v49, v54, v55
	v_cvt_pk_bf16_f32 v50, v50, v51
	v_cvt_pk_bf16_f32 v51, v56, v57
	buffer_store_dwordx4 v[48:51], v72, s[20:23], 0 offen offset:256 sc1
	s_nop 1
	v_add_u32_e32 v48, 0x4090, v158
	v_mad_i64_i32 v[50:51], s[6:7], v48, s73, 0
	v_lshl_add_u64 v[48:49], v[50:51], 1, s[34:35]
	v_lshl_add_u64 v[48:49], v[48:49], 0, v[142:143]
	v_add_co_u32_e32 v52, vcc, s74, v48
	s_nop 1
	v_addc_co_u32_e32 v53, vcc, 0, v49, vcc
	s_waitcnt vmcnt(7)
; __device__ __forceinline__ float sigmoidf_(float x) { return 1.0f / (1.0f + __expf(-x)); }
; __device__ __forceinline__ u32x4 pack8(const f32x4 v0, const f32x4 v1) { u32x4 w; w.x = pk2(v0[0], v0[1]); w.y = pk2(v0[2], v0[3]); w.z = pk2(v1[0], v1[1]); w.w = pk2(v1[2], v1[3]); return w; }
; __device__ __forceinline__ void unpack8(const u32x4 w, f32x4& v0, f32x4& v1) { v0 = (f32x4){bflo(w.x), bfhi(w.x), bflo(w.y), bfhi(w.y)}; v1 = (f32x4){bflo(w.z), bfhi(w.z), bflo(w.w), bfhi(w.w)}; }
;     __device__ __forceinline__ void operator()(const f32x4 (&acc)[2][2][4][2], const Unit& u, int wr, int wc, int fr, int fq) const {
;     ...
;                 const int row = row0 + ai * 128 + m * 16;
;                 const bf16_t* rowp = z + (size_t)row * DIN + col0;
; #pragma unroll
;                 for (int bj = 0; bj < 2; ++bj) {
;                     const u32x4 gw = *(const u32x4*)(rowp + O_GA + bj * 128);
;                     f32x4 g0, g1; unpack8(gw, g0, g1);
;                     f32x4 v0, v1;
; #pragma unroll
;                     for (int j = 0; j < 4; ++j) { v0[j] = sigmoidf_(g0[j]) * acc[ai][bj][m][0][j]; v1[j] = sigmoidf_(g1[j]) * acc[ai][bj][m][1][j]; }
;                     const u32x4 mw = *(const u32x4*)(rowp + bj * 128); f32x4 m0, m1; unpack8(mw, m0, m1); v0 += m0; v1 += m1;
;                     __builtin_amdgcn_raw_buffer_store_b128(pack8(v0, v1), rsrc, (unsigned)(((size_t)row * DIN + col0 + bj * 128) * 2), 0, 16  ); }
	v_mov_b32_e32 v54, v208
	v_mov_b32_e32 v55, v209
	v_mov_b32_e32 v56, v210
	v_mov_b32_e32 v57, v211
	v_mov_b32_e32 v58, v212
	v_mov_b32_e32 v59, v213
	v_mov_b32_e32 v60, v214
	v_mov_b32_e32 v61, v215
	v_add_u32_e32 v198, 0x155300, v197
	global_load_dwordx4 v[208:211], v198, s[34:35]
	v_add_u32_e32 v198, 0x154100, v197
	global_load_dwordx4 v[212:215], v198, s[34:35]
	s_mov_b32 s100, 0xbfb8aa3b
	v_lshlrev_b32_e32 v242, 16, v54
	v_and_b32_e32 v243, 0xffff0000, v54
	v_lshlrev_b32_e32 v244, 16, v56
	v_and_b32_e32 v245, 0xffff0000, v56
	v_lshlrev_b32_e32 v246, 16, v55
	v_and_b32_e32 v247, 0xffff0000, v55
	v_lshlrev_b32_e32 v248, 16, v57
	v_and_b32_e32 v249, 0xffff0000, v57
	v_pk_mul_f32 v[242:243], v[242:243], s[100:101] op_sel_hi:[1,0]
	v_pk_mul_f32 v[244:245], v[244:245], s[100:101] op_sel_hi:[1,0]
	v_pk_mul_f32 v[246:247], v[246:247], s[100:101] op_sel_hi:[1,0]
	v_pk_mul_f32 v[248:249], v[248:249], s[100:101] op_sel_hi:[1,0]
	v_exp_f32_e32 v242, v242
	v_exp_f32_e32 v243, v243
	v_exp_f32_e32 v244, v244
	v_exp_f32_e32 v245, v245
	v_exp_f32_e32 v246, v246
	v_exp_f32_e32 v247, v247
	v_exp_f32_e32 v248, v248
	v_exp_f32_e32 v249, v249
	s_nop 0
	v_pk_add_f32 v[242:243], v[242:243], 1.0 op_sel_hi:[1,0]
	v_pk_add_f32 v[244:245], v[244:245], 1.0 op_sel_hi:[1,0]
	v_pk_add_f32 v[246:247], v[246:247], 1.0 op_sel_hi:[1,0]
	v_pk_add_f32 v[248:249], v[248:249], 1.0 op_sel_hi:[1,0]
	v_rcp_f32_e32 v250, v242
	v_rcp_f32_e32 v251, v243
	s_nop 0
	v_pk_fma_f32 v[252:253], v[242:243], v[250:251], 1.0 op_sel_hi:[1,1,0] neg_lo:[1,0,0] neg_hi:[1,0,0]
	v_pk_fma_f32 v[250:251], v[252:253], v[250:251], v[250:251]
	v_pk_fma_f32 v[252:253], v[242:243], v[250:251], 1.0 op_sel_hi:[1,1,0] neg_lo:[1,0,0] neg_hi:[1,0,0]
	v_pk_fma_f32 v[254:255], v[252:253], v[250:251], v[250:251]
	v_pk_fma_f32 v[252:253], v[242:243], v[254:255], 1.0 op_sel_hi:[1,1,0] neg_lo:[1,0,0] neg_hi:[1,0,0]
	v_pk_fma_f32 v[254:255], v[252:253], v[250:251], v[254:255]
	v_div_fixup_f32 v242, v254, v242, 1.0
	v_div_fixup_f32 v243, v255, v243, 1.0
	v_rcp_f32_e32 v250, v244
	v_rcp_f32_e32 v251, v245
	s_nop 0
	v_pk_fma_f32 v[252:253], v[244:245], v[250:251], 1.0 op_sel_hi:[1,1,0] neg_lo:[1,0,0] neg_hi:[1,0,0]
	v_pk_fma_f32 v[250:251], v[252:253], v[250:251], v[250:251]
	v_pk_fma_f32 v[252:253], v[244:245], v[250:251], 1.0 op_sel_hi:[1,1,0] neg_lo:[1,0,0] neg_hi:[1,0,0]
	v_pk_fma_f32 v[254:255], v[252:253], v[250:251], v[250:251]
	v_pk_fma_f32 v[252:253], v[244:245], v[254:255], 1.0 op_sel_hi:[1,1,0] neg_lo:[1,0,0] neg_hi:[1,0,0]
	v_pk_fma_f32 v[254:255], v[252:253], v[250:251], v[254:255]
	v_div_fixup_f32 v244, v254, v244, 1.0
	v_div_fixup_f32 v245, v255, v245, 1.0
	v_rcp_f32_e32 v250, v246
	v_rcp_f32_e32 v251, v247
	s_nop 0
	v_pk_fma_f32 v[252:253], v[246:247], v[250:251], 1.0 op_sel_hi:[1,1,0] neg_lo:[1,0,0] neg_hi:[1,0,0]
	v_pk_fma_f32 v[250:251], v[252:253], v[250:251], v[250:251]
	v_pk_fma_f32 v[252:253], v[246:247], v[250:251], 1.0 op_sel_hi:[1,1,0] neg_lo:[1,0,0] neg_hi:[1,0,0]
	v_pk_fma_f32 v[254:255], v[252:253], v[250:251], v[250:251]
	v_pk_fma_f32 v[252:253], v[246:247], v[254:255], 1.0 op_sel_hi:[1,1,0] neg_lo:[1,0,0] neg_hi:[1,0,0]
	v_pk_fma_f32 v[254:255], v[252:253], v[250:251], v[254:255]
	v_div_fixup_f32 v246, v254, v246, 1.0
	v_div_fixup_f32 v247, v255, v247, 1.0
	v_rcp_f32_e32 v250, v248
	v_rcp_f32_e32 v251, v249
	s_nop 0
	v_pk_fma_f32 v[252:253], v[248:249], v[250:251], 1.0 op_sel_hi:[1,1,0] neg_lo:[1,0,0] neg_hi:[1,0,0]
	v_pk_fma_f32 v[250:251], v[252:253], v[250:251], v[250:251]
	v_pk_fma_f32 v[252:253], v[248:249], v[250:251], 1.0 op_sel_hi:[1,1,0] neg_lo:[1,0,0] neg_hi:[1,0,0]
	v_pk_fma_f32 v[254:255], v[252:253], v[250:251], v[250:251]
	v_pk_fma_f32 v[252:253], v[248:249], v[254:255], 1.0 op_sel_hi:[1,1,0] neg_lo:[1,0,0] neg_hi:[1,0,0]
	v_pk_fma_f32 v[254:255], v[252:253], v[250:251], v[254:255]
	v_div_fixup_f32 v248, v254, v248, 1.0
	v_div_fixup_f32 v249, v255, v249, 1.0
	v_lshlrev_b32_e32 v66, 16, v58
	v_and_b32_e32 v67, 0xffff0000, v58
	v_lshlrev_b32_e32 v68, 16, v60
	v_and_b32_e32 v69, 0xffff0000, v60
	v_lshlrev_b32_e32 v60, 16, v61
	v_and_b32_e32 v61, 0xffff0000, v61
	v_lshlrev_b32_e32 v58, 16, v59
	v_and_b32_e32 v59, 0xffff0000, v59
	v_pk_fma_f32 v[44:45], v[44:45], v[242:243], v[66:67]
	v_pk_fma_f32 v[54:55], v[42:43], v[248:249], v[60:61]
	v_pk_fma_f32 v[42:43], v[40:41], v[244:245], v[68:69]
	v_add_lshl_u32 v56, v140, v50, 1
	v_pk_fma_f32 v[46:47], v[46:47], v[246:247], v[58:59]
	v_cvt_pk_bf16_f32 v40, v44, v45
	s_nop 0
	v_cvt_pk_bf16_f32 v41, v46, v47
	v_cvt_pk_bf16_f32 v42, v42, v43
	v_cvt_pk_bf16_f32 v43, v54, v55
	buffer_store_dwordx4 v[40:43], v56, s[20:23], 0 offen sc1
	s_nop 0
	s_waitcnt vmcnt(7)
; __device__ __forceinline__ float sigmoidf_(float x) { return 1.0f / (1.0f + __expf(-x)); }
; __device__ __forceinline__ u32x4 pack8(const f32x4 v0, const f32x4 v1) { u32x4 w; w.x = pk2(v0[0], v0[1]); w.y = pk2(v0[2], v0[3]); w.z = pk2(v1[0], v1[1]); w.w = pk2(v1[2], v1[3]); return w; }
; __device__ __forceinline__ void unpack8(const u32x4 w, f32x4& v0, f32x4& v1) { v0 = (f32x4){bflo(w.x), bfhi(w.x), bflo(w.y), bfhi(w.y)}; v1 = (f32x4){bflo(w.z), bfhi(w.z), bflo(w.w), bfhi(w.w)}; }
;     __device__ __forceinline__ void operator()(const f32x4 (&acc)[2][2][4][2], const Unit& u, int wr, int wc, int fr, int fq) const {
;     ...
;                 const int row = row0 + ai * 128 + m * 16;
;                 const bf16_t* rowp = z + (size_t)row * DIN + col0;
; #pragma unroll
;                 for (int bj = 0; bj < 2; ++bj) {
;                     const u32x4 gw = *(const u32x4*)(rowp + O_GA + bj * 128);
;                     f32x4 g0, g1; unpack8(gw, g0, g1);
;                     f32x4 v0, v1;
; #pragma unroll
;                     for (int j = 0; j < 4; ++j) { v0[j] = sigmoidf_(g0[j]) * acc[ai][bj][m][0][j]; v1[j] = sigmoidf_(g1[j]) * acc[ai][bj][m][1][j]; }
;                     const u32x4 mw = *(const u32x4*)(rowp + bj * 128); f32x4 m0, m1; unpack8(mw, m0, m1); v0 += m0; v1 += m1;
;                     __builtin_amdgcn_raw_buffer_store_b128(pack8(v0, v1), rsrc, (unsigned)(((size_t)row * DIN + col0 + bj * 128) * 2), 0, 16  ); }
	v_mov_b32_e32 v40, v232
	v_mov_b32_e32 v41, v233
	v_mov_b32_e32 v42, v234
	v_mov_b32_e32 v43, v235
	v_mov_b32_e32 v44, v236
	v_mov_b32_e32 v45, v237
	v_mov_b32_e32 v46, v238
	v_mov_b32_e32 v47, v239
	v_add_u32_e32 v198, 0x177200, v197
	global_load_dwordx4 v[232:235], v198, s[34:35]
	v_add_u32_e32 v198, 0x176000, v197
	global_load_dwordx4 v[236:239], v198, s[34:35]
	s_mov_b32 s100, 0xbfb8aa3b
	v_lshlrev_b32_e32 v242, 16, v42
	v_and_b32_e32 v243, 0xffff0000, v42
	v_lshlrev_b32_e32 v244, 16, v40
	v_and_b32_e32 v245, 0xffff0000, v40
	v_lshlrev_b32_e32 v246, 16, v41
	v_and_b32_e32 v247, 0xffff0000, v41
	v_lshlrev_b32_e32 v248, 16, v43
	v_and_b32_e32 v249, 0xffff0000, v43
	v_pk_mul_f32 v[242:243], v[242:243], s[100:101] op_sel_hi:[1,0]
	v_pk_mul_f32 v[244:245], v[244:245], s[100:101] op_sel_hi:[1,0]
	v_pk_mul_f32 v[246:247], v[246:247], s[100:101] op_sel_hi:[1,0]
	v_pk_mul_f32 v[248:249], v[248:249], s[100:101] op_sel_hi:[1,0]
	v_exp_f32_e32 v242, v242
	v_exp_f32_e32 v243, v243
	v_exp_f32_e32 v244, v244
	v_exp_f32_e32 v245, v245
	v_exp_f32_e32 v246, v246
	v_exp_f32_e32 v247, v247
	v_exp_f32_e32 v248, v248
	v_exp_f32_e32 v249, v249
	s_nop 0
	v_pk_add_f32 v[242:243], v[242:243], 1.0 op_sel_hi:[1,0]
	v_pk_add_f32 v[244:245], v[244:245], 1.0 op_sel_hi:[1,0]
	v_pk_add_f32 v[246:247], v[246:247], 1.0 op_sel_hi:[1,0]
	v_pk_add_f32 v[248:249], v[248:249], 1.0 op_sel_hi:[1,0]
	v_rcp_f32_e32 v250, v242
	v_rcp_f32_e32 v251, v243
	s_nop 0
	v_pk_fma_f32 v[252:253], v[242:243], v[250:251], 1.0 op_sel_hi:[1,1,0] neg_lo:[1,0,0] neg_hi:[1,0,0]
	v_pk_fma_f32 v[250:251], v[252:253], v[250:251], v[250:251]
	v_pk_fma_f32 v[252:253], v[242:243], v[250:251], 1.0 op_sel_hi:[1,1,0] neg_lo:[1,0,0] neg_hi:[1,0,0]
	v_pk_fma_f32 v[254:255], v[252:253], v[250:251], v[250:251]
	v_pk_fma_f32 v[252:253], v[242:243], v[254:255], 1.0 op_sel_hi:[1,1,0] neg_lo:[1,0,0] neg_hi:[1,0,0]
	v_pk_fma_f32 v[254:255], v[252:253], v[250:251], v[254:255]
	v_div_fixup_f32 v242, v254, v242, 1.0
	v_div_fixup_f32 v243, v255, v243, 1.0
	v_rcp_f32_e32 v250, v244
	v_rcp_f32_e32 v251, v245
	s_nop 0
	v_pk_fma_f32 v[252:253], v[244:245], v[250:251], 1.0 op_sel_hi:[1,1,0] neg_lo:[1,0,0] neg_hi:[1,0,0]
	v_pk_fma_f32 v[250:251], v[252:253], v[250:251], v[250:251]
	v_pk_fma_f32 v[252:253], v[244:245], v[250:251], 1.0 op_sel_hi:[1,1,0] neg_lo:[1,0,0] neg_hi:[1,0,0]
	v_pk_fma_f32 v[254:255], v[252:253], v[250:251], v[250:251]
	v_pk_fma_f32 v[252:253], v[244:245], v[254:255], 1.0 op_sel_hi:[1,1,0] neg_lo:[1,0,0] neg_hi:[1,0,0]
	v_pk_fma_f32 v[254:255], v[252:253], v[250:251], v[254:255]
	v_div_fixup_f32 v244, v254, v244, 1.0
	v_div_fixup_f32 v245, v255, v245, 1.0
	v_rcp_f32_e32 v250, v246
	v_rcp_f32_e32 v251, v247
	s_nop 0
	v_pk_fma_f32 v[252:253], v[246:247], v[250:251], 1.0 op_sel_hi:[1,1,0] neg_lo:[1,0,0] neg_hi:[1,0,0]
	v_pk_fma_f32 v[250:251], v[252:253], v[250:251], v[250:251]
	v_pk_fma_f32 v[252:253], v[246:247], v[250:251], 1.0 op_sel_hi:[1,1,0] neg_lo:[1,0,0] neg_hi:[1,0,0]
	v_pk_fma_f32 v[254:255], v[252:253], v[250:251], v[250:251]
	v_pk_fma_f32 v[252:253], v[246:247], v[254:255], 1.0 op_sel_hi:[1,1,0] neg_lo:[1,0,0] neg_hi:[1,0,0]
	v_pk_fma_f32 v[254:255], v[252:253], v[250:251], v[254:255]
	v_div_fixup_f32 v246, v254, v246, 1.0
	v_div_fixup_f32 v247, v255, v247, 1.0
	v_rcp_f32_e32 v250, v248
	v_rcp_f32_e32 v251, v249
	s_nop 0
	v_pk_fma_f32 v[252:253], v[248:249], v[250:251], 1.0 op_sel_hi:[1,1,0] neg_lo:[1,0,0] neg_hi:[1,0,0]
	v_pk_fma_f32 v[250:251], v[252:253], v[250:251], v[250:251]
	v_pk_fma_f32 v[252:253], v[248:249], v[250:251], 1.0 op_sel_hi:[1,1,0] neg_lo:[1,0,0] neg_hi:[1,0,0]
	v_pk_fma_f32 v[254:255], v[252:253], v[250:251], v[250:251]
	v_pk_fma_f32 v[252:253], v[248:249], v[254:255], 1.0 op_sel_hi:[1,1,0] neg_lo:[1,0,0] neg_hi:[1,0,0]
	v_pk_fma_f32 v[254:255], v[252:253], v[250:251], v[254:255]
	v_div_fixup_f32 v248, v254, v248, 1.0
	v_div_fixup_f32 v249, v255, v249, 1.0
	v_lshlrev_b32_e32 v52, 16, v44
	v_and_b32_e32 v53, 0xffff0000, v44
	v_lshlrev_b32_e32 v54, 16, v46
	v_and_b32_e32 v55, 0xffff0000, v46
	v_lshlrev_b32_e32 v46, 16, v47
	v_and_b32_e32 v47, 0xffff0000, v47
	v_lshlrev_b32_e32 v44, 16, v45
	v_and_b32_e32 v45, 0xffff0000, v45
	v_pk_fma_f32 v[36:37], v[36:37], v[244:245], v[52:53]
	v_pk_fma_f32 v[40:41], v[34:35], v[248:249], v[46:47]
	v_pk_fma_f32 v[34:35], v[32:33], v[242:243], v[54:55]
	v_cvt_pk_bf16_f32 v32, v36, v37
	v_pk_fma_f32 v[38:39], v[38:39], v[246:247], v[44:45]
	s_nop 0
	v_cvt_pk_bf16_f32 v33, v38, v39
	v_cvt_pk_bf16_f32 v34, v34, v35
	v_cvt_pk_bf16_f32 v35, v40, v41
	buffer_store_dwordx4 v[32:35], v56, s[20:23], 0 offen offset:256 sc1
	s_nop 1
	v_add_u32_e32 v32, 0x40a0, v158
	v_mad_i64_i32 v[34:35], s[6:7], v32, s73, 0
	v_lshl_add_u64 v[32:33], v[34:35], 1, s[34:35]
	v_lshl_add_u64 v[32:33], v[32:33], 0, v[142:143]
	v_add_co_u32_e32 v36, vcc, s74, v32
	s_nop 1
	v_addc_co_u32_e32 v37, vcc, 0, v33, vcc
	s_waitcnt vmcnt(7)
; __device__ __forceinline__ float sigmoidf_(float x) { return 1.0f / (1.0f + __expf(-x)); }
; __device__ __forceinline__ u32x4 pack8(const f32x4 v0, const f32x4 v1) { u32x4 w; w.x = pk2(v0[0], v0[1]); w.y = pk2(v0[2], v0[3]); w.z = pk2(v1[0], v1[1]); w.w = pk2(v1[2], v1[3]); return w; }
; __device__ __forceinline__ void unpack8(const u32x4 w, f32x4& v0, f32x4& v1) { v0 = (f32x4){bflo(w.x), bfhi(w.x), bflo(w.y), bfhi(w.y)}; v1 = (f32x4){bflo(w.z), bfhi(w.z), bflo(w.w), bfhi(w.w)}; }
;     __device__ __forceinline__ void operator()(const f32x4 (&acc)[2][2][4][2], const Unit& u, int wr, int wc, int fr, int fq) const {
;     ...
;                 const int row = row0 + ai * 128 + m * 16;
;                 const bf16_t* rowp = z + (size_t)row * DIN + col0;
; #pragma unroll
;                 for (int bj = 0; bj < 2; ++bj) {
;                     const u32x4 gw = *(const u32x4*)(rowp + O_GA + bj * 128);
;                     f32x4 g0, g1; unpack8(gw, g0, g1);
;                     f32x4 v0, v1;
; #pragma unroll
;                     for (int j = 0; j < 4; ++j) { v0[j] = sigmoidf_(g0[j]) * acc[ai][bj][m][0][j]; v1[j] = sigmoidf_(g1[j]) * acc[ai][bj][m][1][j]; }
;                     const u32x4 mw = *(const u32x4*)(rowp + bj * 128); f32x4 m0, m1; unpack8(mw, m0, m1); v0 += m0; v1 += m1;
;                     __builtin_amdgcn_raw_buffer_store_b128(pack8(v0, v1), rsrc, (unsigned)(((size_t)row * DIN + col0 + bj * 128) * 2), 0, 16  ); }
	v_mov_b32_e32 v38, v200
	v_mov_b32_e32 v39, v201
	v_mov_b32_e32 v40, v202
	v_mov_b32_e32 v41, v203
	v_mov_b32_e32 v42, v204
	v_mov_b32_e32 v43, v205
	v_mov_b32_e32 v44, v206
	v_mov_b32_e32 v45, v207
	v_add_u32_e32 v198, 0x177300, v197
	global_load_dwordx4 v[200:203], v198, s[34:35]
	v_add_u32_e32 v198, 0x176100, v197
	global_load_dwordx4 v[204:207], v198, s[34:35]
	s_mov_b32 s100, 0xbfb8aa3b
	v_lshlrev_b32_e32 v242, 16, v38
	v_and_b32_e32 v243, 0xffff0000, v38
	v_lshlrev_b32_e32 v244, 16, v40
	v_and_b32_e32 v245, 0xffff0000, v40
	v_lshlrev_b32_e32 v246, 16, v39
	v_and_b32_e32 v247, 0xffff0000, v39
	v_lshlrev_b32_e32 v248, 16, v41
	v_and_b32_e32 v249, 0xffff0000, v41
	v_pk_mul_f32 v[242:243], v[242:243], s[100:101] op_sel_hi:[1,0]
	v_pk_mul_f32 v[244:245], v[244:245], s[100:101] op_sel_hi:[1,0]
	v_pk_mul_f32 v[246:247], v[246:247], s[100:101] op_sel_hi:[1,0]
	v_pk_mul_f32 v[248:249], v[248:249], s[100:101] op_sel_hi:[1,0]
	v_exp_f32_e32 v242, v242
	v_exp_f32_e32 v243, v243
	v_exp_f32_e32 v244, v244
	v_exp_f32_e32 v245, v245
	v_exp_f32_e32 v246, v246
	v_exp_f32_e32 v247, v247
	v_exp_f32_e32 v248, v248
	v_exp_f32_e32 v249, v249
	s_nop 0
	v_pk_add_f32 v[242:243], v[242:243], 1.0 op_sel_hi:[1,0]
	v_pk_add_f32 v[244:245], v[244:245], 1.0 op_sel_hi:[1,0]
	v_pk_add_f32 v[246:247], v[246:247], 1.0 op_sel_hi:[1,0]
	v_pk_add_f32 v[248:249], v[248:249], 1.0 op_sel_hi:[1,0]
	v_rcp_f32_e32 v250, v242
	v_rcp_f32_e32 v251, v243
	s_nop 0
	v_pk_fma_f32 v[252:253], v[242:243], v[250:251], 1.0 op_sel_hi:[1,1,0] neg_lo:[1,0,0] neg_hi:[1,0,0]
	v_pk_fma_f32 v[250:251], v[252:253], v[250:251], v[250:251]
	v_pk_fma_f32 v[252:253], v[242:243], v[250:251], 1.0 op_sel_hi:[1,1,0] neg_lo:[1,0,0] neg_hi:[1,0,0]
	v_pk_fma_f32 v[254:255], v[252:253], v[250:251], v[250:251]
	v_pk_fma_f32 v[252:253], v[242:243], v[254:255], 1.0 op_sel_hi:[1,1,0] neg_lo:[1,0,0] neg_hi:[1,0,0]
	v_pk_fma_f32 v[254:255], v[252:253], v[250:251], v[254:255]
	v_div_fixup_f32 v242, v254, v242, 1.0
	v_div_fixup_f32 v243, v255, v243, 1.0
	v_rcp_f32_e32 v250, v244
	v_rcp_f32_e32 v251, v245
	s_nop 0
	v_pk_fma_f32 v[252:253], v[244:245], v[250:251], 1.0 op_sel_hi:[1,1,0] neg_lo:[1,0,0] neg_hi:[1,0,0]
	v_pk_fma_f32 v[250:251], v[252:253], v[250:251], v[250:251]
	v_pk_fma_f32 v[252:253], v[244:245], v[250:251], 1.0 op_sel_hi:[1,1,0] neg_lo:[1,0,0] neg_hi:[1,0,0]
	v_pk_fma_f32 v[254:255], v[252:253], v[250:251], v[250:251]
	v_pk_fma_f32 v[252:253], v[244:245], v[254:255], 1.0 op_sel_hi:[1,1,0] neg_lo:[1,0,0] neg_hi:[1,0,0]
	v_pk_fma_f32 v[254:255], v[252:253], v[250:251], v[254:255]
	v_div_fixup_f32 v244, v254, v244, 1.0
	v_div_fixup_f32 v245, v255, v245, 1.0
	v_rcp_f32_e32 v250, v246
	v_rcp_f32_e32 v251, v247
	s_nop 0
	v_pk_fma_f32 v[252:253], v[246:247], v[250:251], 1.0 op_sel_hi:[1,1,0] neg_lo:[1,0,0] neg_hi:[1,0,0]
	v_pk_fma_f32 v[250:251], v[252:253], v[250:251], v[250:251]
	v_pk_fma_f32 v[252:253], v[246:247], v[250:251], 1.0 op_sel_hi:[1,1,0] neg_lo:[1,0,0] neg_hi:[1,0,0]
	v_pk_fma_f32 v[254:255], v[252:253], v[250:251], v[250:251]
	v_pk_fma_f32 v[252:253], v[246:247], v[254:255], 1.0 op_sel_hi:[1,1,0] neg_lo:[1,0,0] neg_hi:[1,0,0]
	v_pk_fma_f32 v[254:255], v[252:253], v[250:251], v[254:255]
	v_div_fixup_f32 v246, v254, v246, 1.0
	v_div_fixup_f32 v247, v255, v247, 1.0
	v_rcp_f32_e32 v250, v248
	v_rcp_f32_e32 v251, v249
	s_nop 0
	v_pk_fma_f32 v[252:253], v[248:249], v[250:251], 1.0 op_sel_hi:[1,1,0] neg_lo:[1,0,0] neg_hi:[1,0,0]
	v_pk_fma_f32 v[250:251], v[252:253], v[250:251], v[250:251]
	v_pk_fma_f32 v[252:253], v[248:249], v[250:251], 1.0 op_sel_hi:[1,1,0] neg_lo:[1,0,0] neg_hi:[1,0,0]
	v_pk_fma_f32 v[254:255], v[252:253], v[250:251], v[250:251]
	v_pk_fma_f32 v[252:253], v[248:249], v[254:255], 1.0 op_sel_hi:[1,1,0] neg_lo:[1,0,0] neg_hi:[1,0,0]
	v_pk_fma_f32 v[254:255], v[252:253], v[250:251], v[254:255]
	v_div_fixup_f32 v248, v254, v248, 1.0
	v_div_fixup_f32 v249, v255, v249, 1.0
	v_lshlrev_b32_e32 v50, 16, v42
	v_and_b32_e32 v51, 0xffff0000, v42
	v_lshlrev_b32_e32 v52, 16, v44
	v_and_b32_e32 v53, 0xffff0000, v44
	v_lshlrev_b32_e32 v44, 16, v45
	v_and_b32_e32 v45, 0xffff0000, v45
	v_lshlrev_b32_e32 v42, 16, v43
	v_and_b32_e32 v43, 0xffff0000, v43
	v_pk_fma_f32 v[28:29], v[28:29], v[242:243], v[50:51]
	v_pk_fma_f32 v[38:39], v[26:27], v[248:249], v[44:45]
	v_pk_fma_f32 v[26:27], v[24:25], v[244:245], v[52:53]
	v_add_lshl_u32 v40, v140, v34, 1
	v_pk_fma_f32 v[30:31], v[30:31], v[246:247], v[42:43]
	v_cvt_pk_bf16_f32 v24, v28, v29
	s_nop 0
	v_cvt_pk_bf16_f32 v25, v30, v31
	v_cvt_pk_bf16_f32 v26, v26, v27
	v_cvt_pk_bf16_f32 v27, v38, v39
	buffer_store_dwordx4 v[24:27], v40, s[20:23], 0 offen sc1
	s_nop 0
	s_waitcnt vmcnt(7)
; __device__ __forceinline__ float sigmoidf_(float x) { return 1.0f / (1.0f + __expf(-x)); }
; __device__ __forceinline__ u32x4 pack8(const f32x4 v0, const f32x4 v1) { u32x4 w; w.x = pk2(v0[0], v0[1]); w.y = pk2(v0[2], v0[3]); w.z = pk2(v1[0], v1[1]); w.w = pk2(v1[2], v1[3]); return w; }
; __device__ __forceinline__ void unpack8(const u32x4 w, f32x4& v0, f32x4& v1) { v0 = (f32x4){bflo(w.x), bfhi(w.x), bflo(w.y), bfhi(w.y)}; v1 = (f32x4){bflo(w.z), bfhi(w.z), bflo(w.w), bfhi(w.w)}; }
;     __device__ __forceinline__ void operator()(const f32x4 (&acc)[2][2][4][2], const Unit& u, int wr, int wc, int fr, int fq) const {
;     ...
;                 const int row = row0 + ai * 128 + m * 16;
;                 const bf16_t* rowp = z + (size_t)row * DIN + col0;
; #pragma unroll
;                 for (int bj = 0; bj < 2; ++bj) {
;                     const u32x4 gw = *(const u32x4*)(rowp + O_GA + bj * 128);
;                     f32x4 g0, g1; unpack8(gw, g0, g1);
;                     f32x4 v0, v1;
; #pragma unroll
;                     for (int j = 0; j < 4; ++j) { v0[j] = sigmoidf_(g0[j]) * acc[ai][bj][m][0][j]; v1[j] = sigmoidf_(g1[j]) * acc[ai][bj][m][1][j]; }
;                     const u32x4 mw = *(const u32x4*)(rowp + bj * 128); f32x4 m0, m1; unpack8(mw, m0, m1); v0 += m0; v1 += m1;
;                     __builtin_amdgcn_raw_buffer_store_b128(pack8(v0, v1), rsrc, (unsigned)(((size_t)row * DIN + col0 + bj * 128) * 2), 0, 16  ); }
	v_mov_b32_e32 v24, v208
	v_mov_b32_e32 v25, v209
	v_mov_b32_e32 v26, v210
	v_mov_b32_e32 v27, v211
	v_mov_b32_e32 v28, v212
	v_mov_b32_e32 v29, v213
	v_mov_b32_e32 v30, v214
	v_mov_b32_e32 v31, v215
	s_mov_b32 s100, 0xbfb8aa3b
	v_lshlrev_b32_e32 v242, 16, v26
	v_and_b32_e32 v243, 0xffff0000, v26
	v_lshlrev_b32_e32 v244, 16, v24
	v_and_b32_e32 v245, 0xffff0000, v24
	v_lshlrev_b32_e32 v246, 16, v25
	v_and_b32_e32 v247, 0xffff0000, v25
	v_lshlrev_b32_e32 v248, 16, v27
	v_and_b32_e32 v249, 0xffff0000, v27
	v_pk_mul_f32 v[242:243], v[242:243], s[100:101] op_sel_hi:[1,0]
	v_pk_mul_f32 v[244:245], v[244:245], s[100:101] op_sel_hi:[1,0]
	v_pk_mul_f32 v[246:247], v[246:247], s[100:101] op_sel_hi:[1,0]
	v_pk_mul_f32 v[248:249], v[248:249], s[100:101] op_sel_hi:[1,0]
	v_exp_f32_e32 v242, v242
	v_exp_f32_e32 v243, v243
	v_exp_f32_e32 v244, v244
	v_exp_f32_e32 v245, v245
	v_exp_f32_e32 v246, v246
	v_exp_f32_e32 v247, v247
	v_exp_f32_e32 v248, v248
	v_exp_f32_e32 v249, v249
	s_nop 0
	v_pk_add_f32 v[242:243], v[242:243], 1.0 op_sel_hi:[1,0]
	v_pk_add_f32 v[244:245], v[244:245], 1.0 op_sel_hi:[1,0]
	v_pk_add_f32 v[246:247], v[246:247], 1.0 op_sel_hi:[1,0]
	v_pk_add_f32 v[248:249], v[248:249], 1.0 op_sel_hi:[1,0]
	v_rcp_f32_e32 v250, v242
	v_rcp_f32_e32 v251, v243
	s_nop 0
	v_pk_fma_f32 v[252:253], v[242:243], v[250:251], 1.0 op_sel_hi:[1,1,0] neg_lo:[1,0,0] neg_hi:[1,0,0]
	v_pk_fma_f32 v[250:251], v[252:253], v[250:251], v[250:251]
	v_pk_fma_f32 v[252:253], v[242:243], v[250:251], 1.0 op_sel_hi:[1,1,0] neg_lo:[1,0,0] neg_hi:[1,0,0]
	v_pk_fma_f32 v[254:255], v[252:253], v[250:251], v[250:251]
	v_pk_fma_f32 v[252:253], v[242:243], v[254:255], 1.0 op_sel_hi:[1,1,0] neg_lo:[1,0,0] neg_hi:[1,0,0]
	v_pk_fma_f32 v[254:255], v[252:253], v[250:251], v[254:255]
	v_div_fixup_f32 v242, v254, v242, 1.0
	v_div_fixup_f32 v243, v255, v243, 1.0
	v_rcp_f32_e32 v250, v244
	v_rcp_f32_e32 v251, v245
	s_nop 0
	v_pk_fma_f32 v[252:253], v[244:245], v[250:251], 1.0 op_sel_hi:[1,1,0] neg_lo:[1,0,0] neg_hi:[1,0,0]
	v_pk_fma_f32 v[250:251], v[252:253], v[250:251], v[250:251]
	v_pk_fma_f32 v[252:253], v[244:245], v[250:251], 1.0 op_sel_hi:[1,1,0] neg_lo:[1,0,0] neg_hi:[1,0,0]
	v_pk_fma_f32 v[254:255], v[252:253], v[250:251], v[250:251]
	v_pk_fma_f32 v[252:253], v[244:245], v[254:255], 1.0 op_sel_hi:[1,1,0] neg_lo:[1,0,0] neg_hi:[1,0,0]
	v_pk_fma_f32 v[254:255], v[252:253], v[250:251], v[254:255]
	v_div_fixup_f32 v244, v254, v244, 1.0
	v_div_fixup_f32 v245, v255, v245, 1.0
	v_rcp_f32_e32 v250, v246
	v_rcp_f32_e32 v251, v247
	s_nop 0
	v_pk_fma_f32 v[252:253], v[246:247], v[250:251], 1.0 op_sel_hi:[1,1,0] neg_lo:[1,0,0] neg_hi:[1,0,0]
	v_pk_fma_f32 v[250:251], v[252:253], v[250:251], v[250:251]
	v_pk_fma_f32 v[252:253], v[246:247], v[250:251], 1.0 op_sel_hi:[1,1,0] neg_lo:[1,0,0] neg_hi:[1,0,0]
	v_pk_fma_f32 v[254:255], v[252:253], v[250:251], v[250:251]
	v_pk_fma_f32 v[252:253], v[246:247], v[254:255], 1.0 op_sel_hi:[1,1,0] neg_lo:[1,0,0] neg_hi:[1,0,0]
	v_pk_fma_f32 v[254:255], v[252:253], v[250:251], v[254:255]
	v_div_fixup_f32 v246, v254, v246, 1.0
	v_div_fixup_f32 v247, v255, v247, 1.0
	v_rcp_f32_e32 v250, v248
	v_rcp_f32_e32 v251, v249
	s_nop 0
	v_pk_fma_f32 v[252:253], v[248:249], v[250:251], 1.0 op_sel_hi:[1,1,0] neg_lo:[1,0,0] neg_hi:[1,0,0]
	v_pk_fma_f32 v[250:251], v[252:253], v[250:251], v[250:251]
	v_pk_fma_f32 v[252:253], v[248:249], v[250:251], 1.0 op_sel_hi:[1,1,0] neg_lo:[1,0,0] neg_hi:[1,0,0]
	v_pk_fma_f32 v[254:255], v[252:253], v[250:251], v[250:251]
	v_pk_fma_f32 v[252:253], v[248:249], v[254:255], 1.0 op_sel_hi:[1,1,0] neg_lo:[1,0,0] neg_hi:[1,0,0]
	v_pk_fma_f32 v[254:255], v[252:253], v[250:251], v[254:255]
	v_div_fixup_f32 v248, v254, v248, 1.0
	v_div_fixup_f32 v249, v255, v249, 1.0
	v_lshlrev_b32_e32 v36, 16, v28
	v_and_b32_e32 v37, 0xffff0000, v28
	v_lshlrev_b32_e32 v38, 16, v30
	v_and_b32_e32 v39, 0xffff0000, v30
	v_lshlrev_b32_e32 v30, 16, v31
	v_and_b32_e32 v31, 0xffff0000, v31
	v_lshlrev_b32_e32 v28, 16, v29
	v_and_b32_e32 v29, 0xffff0000, v29
	v_pk_fma_f32 v[20:21], v[20:21], v[244:245], v[36:37]
	v_pk_fma_f32 v[24:25], v[18:19], v[248:249], v[30:31]
	v_pk_fma_f32 v[18:19], v[16:17], v[242:243], v[38:39]
	v_cvt_pk_bf16_f32 v16, v20, v21
	v_pk_fma_f32 v[22:23], v[22:23], v[246:247], v[28:29]
	s_nop 0
	v_cvt_pk_bf16_f32 v17, v22, v23
	v_cvt_pk_bf16_f32 v18, v18, v19
	v_cvt_pk_bf16_f32 v19, v24, v25
	buffer_store_dwordx4 v[16:19], v40, s[20:23], 0 offen offset:256 sc1
	s_nop 1
	v_add_u32_e32 v16, 0x40b0, v158
	v_mad_i64_i32 v[18:19], s[6:7], v16, s73, 0
	v_lshl_add_u64 v[16:17], v[18:19], 1, s[34:35]
	v_lshl_add_u64 v[16:17], v[16:17], 0, v[142:143]
	v_add_co_u32_e32 v20, vcc, s74, v16
	s_nop 1
	v_addc_co_u32_e32 v21, vcc, 0, v17, vcc
	s_waitcnt vmcnt(5)
; __device__ __forceinline__ float sigmoidf_(float x) { return 1.0f / (1.0f + __expf(-x)); }
; __device__ __forceinline__ u32x4 pack8(const f32x4 v0, const f32x4 v1) { u32x4 w; w.x = pk2(v0[0], v0[1]); w.y = pk2(v0[2], v0[3]); w.z = pk2(v1[0], v1[1]); w.w = pk2(v1[2], v1[3]); return w; }
; __device__ __forceinline__ void unpack8(const u32x4 w, f32x4& v0, f32x4& v1) { v0 = (f32x4){bflo(w.x), bfhi(w.x), bflo(w.y), bfhi(w.y)}; v1 = (f32x4){bflo(w.z), bfhi(w.z), bflo(w.w), bfhi(w.w)}; }
;     __device__ __forceinline__ void operator()(const f32x4 (&acc)[2][2][4][2], const Unit& u, int wr, int wc, int fr, int fq) const {
;     ...
;                 const int row = row0 + ai * 128 + m * 16;
;                 const bf16_t* rowp = z + (size_t)row * DIN + col0;
; #pragma unroll
;                 for (int bj = 0; bj < 2; ++bj) {
;                     const u32x4 gw = *(const u32x4*)(rowp + O_GA + bj * 128);
;                     f32x4 g0, g1; unpack8(gw, g0, g1);
;                     f32x4 v0, v1;
; #pragma unroll
;                     for (int j = 0; j < 4; ++j) { v0[j] = sigmoidf_(g0[j]) * acc[ai][bj][m][0][j]; v1[j] = sigmoidf_(g1[j]) * acc[ai][bj][m][1][j]; }
;                     const u32x4 mw = *(const u32x4*)(rowp + bj * 128); f32x4 m0, m1; unpack8(mw, m0, m1); v0 += m0; v1 += m1;
;                     __builtin_amdgcn_raw_buffer_store_b128(pack8(v0, v1), rsrc, (unsigned)(((size_t)row * DIN + col0 + bj * 128) * 2), 0, 16  ); }
	v_mov_b32_e32 v22, v232
	v_mov_b32_e32 v23, v233
	v_mov_b32_e32 v24, v234
	v_mov_b32_e32 v25, v235
	v_mov_b32_e32 v26, v236
	v_mov_b32_e32 v27, v237
	v_mov_b32_e32 v28, v238
	v_mov_b32_e32 v29, v239
	s_mov_b32 s100, 0xbfb8aa3b
	v_lshlrev_b32_e32 v242, 16, v22
	v_and_b32_e32 v243, 0xffff0000, v22
	v_lshlrev_b32_e32 v244, 16, v24
	v_and_b32_e32 v245, 0xffff0000, v24
	v_lshlrev_b32_e32 v246, 16, v23
	v_and_b32_e32 v247, 0xffff0000, v23
	v_lshlrev_b32_e32 v248, 16, v25
	v_and_b32_e32 v249, 0xffff0000, v25
	v_pk_mul_f32 v[242:243], v[242:243], s[100:101] op_sel_hi:[1,0]
	v_pk_mul_f32 v[244:245], v[244:245], s[100:101] op_sel_hi:[1,0]
	v_pk_mul_f32 v[246:247], v[246:247], s[100:101] op_sel_hi:[1,0]
	v_pk_mul_f32 v[248:249], v[248:249], s[100:101] op_sel_hi:[1,0]
	v_exp_f32_e32 v242, v242
	v_exp_f32_e32 v243, v243
	v_exp_f32_e32 v244, v244
	v_exp_f32_e32 v245, v245
	v_exp_f32_e32 v246, v246
	v_exp_f32_e32 v247, v247
	v_exp_f32_e32 v248, v248
	v_exp_f32_e32 v249, v249
	s_nop 0
	v_pk_add_f32 v[242:243], v[242:243], 1.0 op_sel_hi:[1,0]
	v_pk_add_f32 v[244:245], v[244:245], 1.0 op_sel_hi:[1,0]
	v_pk_add_f32 v[246:247], v[246:247], 1.0 op_sel_hi:[1,0]
	v_pk_add_f32 v[248:249], v[248:249], 1.0 op_sel_hi:[1,0]
	v_rcp_f32_e32 v250, v242
	v_rcp_f32_e32 v251, v243
	s_nop 0
	v_pk_fma_f32 v[252:253], v[242:243], v[250:251], 1.0 op_sel_hi:[1,1,0] neg_lo:[1,0,0] neg_hi:[1,0,0]
	v_pk_fma_f32 v[250:251], v[252:253], v[250:251], v[250:251]
	v_pk_fma_f32 v[252:253], v[242:243], v[250:251], 1.0 op_sel_hi:[1,1,0] neg_lo:[1,0,0] neg_hi:[1,0,0]
	v_pk_fma_f32 v[254:255], v[252:253], v[250:251], v[250:251]
	v_pk_fma_f32 v[252:253], v[242:243], v[254:255], 1.0 op_sel_hi:[1,1,0] neg_lo:[1,0,0] neg_hi:[1,0,0]
	v_pk_fma_f32 v[254:255], v[252:253], v[250:251], v[254:255]
	v_div_fixup_f32 v242, v254, v242, 1.0
	v_div_fixup_f32 v243, v255, v243, 1.0
	v_rcp_f32_e32 v250, v244
	v_rcp_f32_e32 v251, v245
	s_nop 0
	v_pk_fma_f32 v[252:253], v[244:245], v[250:251], 1.0 op_sel_hi:[1,1,0] neg_lo:[1,0,0] neg_hi:[1,0,0]
	v_pk_fma_f32 v[250:251], v[252:253], v[250:251], v[250:251]
	v_pk_fma_f32 v[252:253], v[244:245], v[250:251], 1.0 op_sel_hi:[1,1,0] neg_lo:[1,0,0] neg_hi:[1,0,0]
	v_pk_fma_f32 v[254:255], v[252:253], v[250:251], v[250:251]
	v_pk_fma_f32 v[252:253], v[244:245], v[254:255], 1.0 op_sel_hi:[1,1,0] neg_lo:[1,0,0] neg_hi:[1,0,0]
	v_pk_fma_f32 v[254:255], v[252:253], v[250:251], v[254:255]
	v_div_fixup_f32 v244, v254, v244, 1.0
	v_div_fixup_f32 v245, v255, v245, 1.0
	v_rcp_f32_e32 v250, v246
	v_rcp_f32_e32 v251, v247
	s_nop 0
	v_pk_fma_f32 v[252:253], v[246:247], v[250:251], 1.0 op_sel_hi:[1,1,0] neg_lo:[1,0,0] neg_hi:[1,0,0]
	v_pk_fma_f32 v[250:251], v[252:253], v[250:251], v[250:251]
	v_pk_fma_f32 v[252:253], v[246:247], v[250:251], 1.0 op_sel_hi:[1,1,0] neg_lo:[1,0,0] neg_hi:[1,0,0]
	v_pk_fma_f32 v[254:255], v[252:253], v[250:251], v[250:251]
	v_pk_fma_f32 v[252:253], v[246:247], v[254:255], 1.0 op_sel_hi:[1,1,0] neg_lo:[1,0,0] neg_hi:[1,0,0]
	v_pk_fma_f32 v[254:255], v[252:253], v[250:251], v[254:255]
	v_div_fixup_f32 v246, v254, v246, 1.0
	v_div_fixup_f32 v247, v255, v247, 1.0
	v_rcp_f32_e32 v250, v248
	v_rcp_f32_e32 v251, v249
	s_nop 0
	v_pk_fma_f32 v[252:253], v[248:249], v[250:251], 1.0 op_sel_hi:[1,1,0] neg_lo:[1,0,0] neg_hi:[1,0,0]
	v_pk_fma_f32 v[250:251], v[252:253], v[250:251], v[250:251]
	v_pk_fma_f32 v[252:253], v[248:249], v[250:251], 1.0 op_sel_hi:[1,1,0] neg_lo:[1,0,0] neg_hi:[1,0,0]
	v_pk_fma_f32 v[254:255], v[252:253], v[250:251], v[250:251]
	v_pk_fma_f32 v[252:253], v[248:249], v[254:255], 1.0 op_sel_hi:[1,1,0] neg_lo:[1,0,0] neg_hi:[1,0,0]
	v_pk_fma_f32 v[254:255], v[252:253], v[250:251], v[254:255]
	v_div_fixup_f32 v248, v254, v248, 1.0
	v_div_fixup_f32 v249, v255, v249, 1.0
	v_lshlrev_b32_e32 v34, 16, v26
	v_and_b32_e32 v35, 0xffff0000, v26
	v_lshlrev_b32_e32 v36, 16, v28
	v_and_b32_e32 v37, 0xffff0000, v28
	v_lshlrev_b32_e32 v28, 16, v29
	v_and_b32_e32 v29, 0xffff0000, v29
	v_lshlrev_b32_e32 v26, 16, v27
	v_and_b32_e32 v27, 0xffff0000, v27
	v_pk_fma_f32 v[12:13], v[12:13], v[242:243], v[34:35]
	v_pk_fma_f32 v[22:23], v[10:11], v[248:249], v[28:29]
	v_pk_fma_f32 v[10:11], v[8:9], v[244:245], v[36:37]
	v_add_lshl_u32 v24, v140, v18, 1
	v_pk_fma_f32 v[14:15], v[14:15], v[246:247], v[26:27]
	v_cvt_pk_bf16_f32 v8, v12, v13
	s_nop 0
	v_cvt_pk_bf16_f32 v9, v14, v15
	v_cvt_pk_bf16_f32 v10, v10, v11
	v_cvt_pk_bf16_f32 v11, v22, v23
	buffer_store_dwordx4 v[8:11], v24, s[20:23], 0 offen sc1
	s_nop 0
	s_waitcnt vmcnt(3)
; __device__ __forceinline__ float sigmoidf_(float x) { return 1.0f / (1.0f + __expf(-x)); }
; __device__ __forceinline__ u32x4 pack8(const f32x4 v0, const f32x4 v1) { u32x4 w; w.x = pk2(v0[0], v0[1]); w.y = pk2(v0[2], v0[3]); w.z = pk2(v1[0], v1[1]); w.w = pk2(v1[2], v1[3]); return w; }
; __device__ __forceinline__ void unpack8(const u32x4 w, f32x4& v0, f32x4& v1) { v0 = (f32x4){bflo(w.x), bfhi(w.x), bflo(w.y), bfhi(w.y)}; v1 = (f32x4){bflo(w.z), bfhi(w.z), bflo(w.w), bfhi(w.w)}; }
;     __device__ __forceinline__ void operator()(const f32x4 (&acc)[2][2][4][2], const Unit& u, int wr, int wc, int fr, int fq) const {
;     ...
;                 const int row = row0 + ai * 128 + m * 16;
;                 const bf16_t* rowp = z + (size_t)row * DIN + col0;
; #pragma unroll
;                 for (int bj = 0; bj < 2; ++bj) {
;                     const u32x4 gw = *(const u32x4*)(rowp + O_GA + bj * 128);
;                     f32x4 g0, g1; unpack8(gw, g0, g1);
;                     f32x4 v0, v1;
; #pragma unroll
;                     for (int j = 0; j < 4; ++j) { v0[j] = sigmoidf_(g0[j]) * acc[ai][bj][m][0][j]; v1[j] = sigmoidf_(g1[j]) * acc[ai][bj][m][1][j]; }
;                     const u32x4 mw = *(const u32x4*)(rowp + bj * 128); f32x4 m0, m1; unpack8(mw, m0, m1); v0 += m0; v1 += m1;
;                     __builtin_amdgcn_raw_buffer_store_b128(pack8(v0, v1), rsrc, (unsigned)(((size_t)row * DIN + col0 + bj * 128) * 2), 0, 16  ); }
;             }
;         asm volatile("s_waitcnt vmcnt(0)" ::: "memory");
;         if (fr == 0 && fq == 0) (void)__hip_atomic_fetch_add(ready + 64 * (pm_off + u.pm), 1u, __ATOMIC_RELAXED, __HIP_MEMORY_SCOPE_AGENT);
	v_mov_b32_e32 v8, v200
	v_mov_b32_e32 v9, v201
	v_mov_b32_e32 v10, v202
	v_mov_b32_e32 v11, v203
	v_mov_b32_e32 v12, v204
	v_mov_b32_e32 v13, v205
	v_mov_b32_e32 v14, v206
	v_mov_b32_e32 v15, v207
	s_mov_b32 s100, 0xbfb8aa3b
	v_lshlrev_b32_e32 v242, 16, v10
	v_and_b32_e32 v243, 0xffff0000, v10
	v_lshlrev_b32_e32 v244, 16, v8
	v_and_b32_e32 v245, 0xffff0000, v8
	v_lshlrev_b32_e32 v246, 16, v9
	v_and_b32_e32 v247, 0xffff0000, v9
	v_lshlrev_b32_e32 v248, 16, v11
	v_and_b32_e32 v249, 0xffff0000, v11
	v_pk_mul_f32 v[242:243], v[242:243], s[100:101] op_sel_hi:[1,0]
	v_pk_mul_f32 v[244:245], v[244:245], s[100:101] op_sel_hi:[1,0]
	v_pk_mul_f32 v[246:247], v[246:247], s[100:101] op_sel_hi:[1,0]
	v_pk_mul_f32 v[248:249], v[248:249], s[100:101] op_sel_hi:[1,0]
	v_exp_f32_e32 v242, v242
	v_exp_f32_e32 v243, v243
	v_exp_f32_e32 v244, v244
	v_exp_f32_e32 v245, v245
	v_exp_f32_e32 v246, v246
	v_exp_f32_e32 v247, v247
	v_exp_f32_e32 v248, v248
	v_exp_f32_e32 v249, v249
	s_nop 0
	v_pk_add_f32 v[242:243], v[242:243], 1.0 op_sel_hi:[1,0]
	v_pk_add_f32 v[244:245], v[244:245], 1.0 op_sel_hi:[1,0]
	v_pk_add_f32 v[246:247], v[246:247], 1.0 op_sel_hi:[1,0]
	v_pk_add_f32 v[248:249], v[248:249], 1.0 op_sel_hi:[1,0]
	v_rcp_f32_e32 v250, v242
	v_rcp_f32_e32 v251, v243
	s_nop 0
	v_pk_fma_f32 v[252:253], v[242:243], v[250:251], 1.0 op_sel_hi:[1,1,0] neg_lo:[1,0,0] neg_hi:[1,0,0]
	v_pk_fma_f32 v[250:251], v[252:253], v[250:251], v[250:251]
	v_pk_fma_f32 v[252:253], v[242:243], v[250:251], 1.0 op_sel_hi:[1,1,0] neg_lo:[1,0,0] neg_hi:[1,0,0]
	v_pk_fma_f32 v[254:255], v[252:253], v[250:251], v[250:251]
	v_pk_fma_f32 v[252:253], v[242:243], v[254:255], 1.0 op_sel_hi:[1,1,0] neg_lo:[1,0,0] neg_hi:[1,0,0]
	v_pk_fma_f32 v[254:255], v[252:253], v[250:251], v[254:255]
	v_div_fixup_f32 v242, v254, v242, 1.0
	v_div_fixup_f32 v243, v255, v243, 1.0
	v_rcp_f32_e32 v250, v244
	v_rcp_f32_e32 v251, v245
	s_nop 0
	v_pk_fma_f32 v[252:253], v[244:245], v[250:251], 1.0 op_sel_hi:[1,1,0] neg_lo:[1,0,0] neg_hi:[1,0,0]
	v_pk_fma_f32 v[250:251], v[252:253], v[250:251], v[250:251]
	v_pk_fma_f32 v[252:253], v[244:245], v[250:251], 1.0 op_sel_hi:[1,1,0] neg_lo:[1,0,0] neg_hi:[1,0,0]
	v_pk_fma_f32 v[254:255], v[252:253], v[250:251], v[250:251]
	v_pk_fma_f32 v[252:253], v[244:245], v[254:255], 1.0 op_sel_hi:[1,1,0] neg_lo:[1,0,0] neg_hi:[1,0,0]
	v_pk_fma_f32 v[254:255], v[252:253], v[250:251], v[254:255]
	v_div_fixup_f32 v244, v254, v244, 1.0
	v_div_fixup_f32 v245, v255, v245, 1.0
	v_rcp_f32_e32 v250, v246
	v_rcp_f32_e32 v251, v247
	s_nop 0
	v_pk_fma_f32 v[252:253], v[246:247], v[250:251], 1.0 op_sel_hi:[1,1,0] neg_lo:[1,0,0] neg_hi:[1,0,0]
	v_pk_fma_f32 v[250:251], v[252:253], v[250:251], v[250:251]
	v_pk_fma_f32 v[252:253], v[246:247], v[250:251], 1.0 op_sel_hi:[1,1,0] neg_lo:[1,0,0] neg_hi:[1,0,0]
	v_pk_fma_f32 v[254:255], v[252:253], v[250:251], v[250:251]
	v_pk_fma_f32 v[252:253], v[246:247], v[254:255], 1.0 op_sel_hi:[1,1,0] neg_lo:[1,0,0] neg_hi:[1,0,0]
	v_pk_fma_f32 v[254:255], v[252:253], v[250:251], v[254:255]
	v_div_fixup_f32 v246, v254, v246, 1.0
	v_div_fixup_f32 v247, v255, v247, 1.0
	v_rcp_f32_e32 v250, v248
	v_rcp_f32_e32 v251, v249
	s_nop 0
	v_pk_fma_f32 v[252:253], v[248:249], v[250:251], 1.0 op_sel_hi:[1,1,0] neg_lo:[1,0,0] neg_hi:[1,0,0]
	v_pk_fma_f32 v[250:251], v[252:253], v[250:251], v[250:251]
	v_pk_fma_f32 v[252:253], v[248:249], v[250:251], 1.0 op_sel_hi:[1,1,0] neg_lo:[1,0,0] neg_hi:[1,0,0]
	v_pk_fma_f32 v[254:255], v[252:253], v[250:251], v[250:251]
	v_pk_fma_f32 v[252:253], v[248:249], v[254:255], 1.0 op_sel_hi:[1,1,0] neg_lo:[1,0,0] neg_hi:[1,0,0]
	v_pk_fma_f32 v[254:255], v[252:253], v[250:251], v[254:255]
	v_div_fixup_f32 v248, v254, v248, 1.0
	v_div_fixup_f32 v249, v255, v249, 1.0
	v_lshlrev_b32_e32 v20, 16, v12
	v_and_b32_e32 v21, 0xffff0000, v12
	v_lshlrev_b32_e32 v22, 16, v14
	v_and_b32_e32 v23, 0xffff0000, v14
	v_lshlrev_b32_e32 v14, 16, v15
	v_and_b32_e32 v15, 0xffff0000, v15
	v_lshlrev_b32_e32 v12, 16, v13
	v_and_b32_e32 v13, 0xffff0000, v13
	v_pk_fma_f32 v[4:5], v[4:5], v[244:245], v[20:21]
	v_pk_fma_f32 v[8:9], v[2:3], v[248:249], v[14:15]
	v_pk_fma_f32 v[2:3], v[0:1], v[242:243], v[22:23]
	v_pk_fma_f32 v[6:7], v[6:7], v[246:247], v[12:13]
	v_cvt_pk_bf16_f32 v0, v4, v5
	s_nop 0
	v_cvt_pk_bf16_f32 v1, v6, v7
	v_cvt_pk_bf16_f32 v2, v2, v3
	v_cvt_pk_bf16_f32 v3, v8, v9
	buffer_store_dwordx4 v[0:3], v24, s[20:23], 0 offen offset:256 sc1
	s_waitcnt vmcnt(0)
	s_and_saveexec_b64 s[10:11], s[8:9]
	s_cbranch_execz .LBB0_1856
	s_mov_b64 s[12:13], exec
	v_mbcnt_lo_u32_b32 v0, s12, 0
	v_mbcnt_hi_u32_b32 v0, s13, v0
	v_cmp_eq_u32_e32 vcc, 0, v0
	s_and_b64 s[6:7], exec, vcc
	s_mov_b64 exec, s[6:7]
	s_cbranch_execz .LBB0_1856
	s_lshl_b32 s6, s75, 6
	s_addk_i32 s6, 0x1000
	s_ashr_i32 s7, s6, 31
	s_lshl_b64 s[6:7], s[6:7], 2
	s_add_u32 s6, s28, s6
	s_addc_u32 s7, s29, s7
	s_bcnt1_i32_b64 s12, s[12:13]
	v_mov_b32_e32 v0, s12
	global_atomic_add v131, v0, s[6:7]
	s_branch .LBB0_1856
